# v14: v13 plus removal of the GEMM per-slot s_setprio flips (A/B experiment)
# speedup vs baseline: 1.0177x; 1.0054x over previous
.LBB0_278:
	ds_read_b128 v[130:133], v158
	ds_read_b128 v[134:137], v158 offset:1024
	ds_read_b128 v[162:165], v158 offset:2048
	ds_read_b128 v[166:169], v158 offset:3072
	s_add_u32 s0, s30, 0xfffc0080
	s_addc_u32 s1, s31, -1
	s_cmp_eq_u32 s60, 12
	s_cselect_b32 s37, s23, s1
	s_cselect_b32 s36, s56, s0
	s_cselect_b32 s35, s21, s59
	s_cselect_b32 s34, s57, s58
	v_lshl_add_u64 v[154:155], s[30:31], 0, v[148:149]
	s_add_i32 m0, s29, 0xc000
	ds_read_b128 v[170:173], v159
	ds_read_b128 v[174:177], v159 offset:1024
	ds_read_b128 v[178:181], v159 offset:2048
	ds_read_b128 v[182:185], v159 offset:3072
	ds_read_b128 v[186:189], v159 offset:4096
	ds_read_b128 v[190:193], v159 offset:5120
	ds_read_b128 v[194:197], v159 offset:6144
	ds_read_b128 v[198:201], v159 offset:7168
	global_load_lds_dwordx4 v[154:155], off
	v_lshl_add_u64 v[154:155], s[30:31], 0, v[146:147]
	s_add_i32 m0, s29, 0xe000
	s_nop 0
	global_load_lds_dwordx4 v[154:155], off
	s_waitcnt lgkmcnt(8)
	s_waitcnt vmcnt(10)
	s_barrier
	s_waitcnt lgkmcnt(0)
	s_waitcnt lgkmcnt(0)
	v_mfma_f32_16x16x32_bf16 v[126:129], v[130:133], v[170:173], v[126:129]
	v_mfma_f32_16x16x32_bf16 v[122:125], v[162:165], v[170:173], v[122:125]
	v_mfma_f32_16x16x32_bf16 v[118:121], v[130:133], v[178:181], v[118:121]
	v_mfma_f32_16x16x32_bf16 v[110:113], v[162:165], v[178:181], v[110:113]
	v_mfma_f32_16x16x32_bf16 v[102:105], v[130:133], v[186:189], v[102:105]
	v_mfma_f32_16x16x32_bf16 v[94:97], v[162:165], v[186:189], v[94:97]
	v_mfma_f32_16x16x32_bf16 v[86:89], v[130:133], v[194:197], v[86:89]
	v_mfma_f32_16x16x32_bf16 v[78:81], v[162:165], v[194:197], v[78:81]
	v_mfma_f32_16x16x32_bf16 v[126:129], v[134:137], v[174:177], v[126:129]
	v_mfma_f32_16x16x32_bf16 v[122:125], v[166:169], v[174:177], v[122:125]
	v_mfma_f32_16x16x32_bf16 v[118:121], v[134:137], v[182:185], v[118:121]
	v_mfma_f32_16x16x32_bf16 v[110:113], v[166:169], v[182:185], v[110:113]
	v_mfma_f32_16x16x32_bf16 v[102:105], v[134:137], v[190:193], v[102:105]
	v_mfma_f32_16x16x32_bf16 v[94:97], v[166:169], v[190:193], v[94:97]
	v_mfma_f32_16x16x32_bf16 v[86:89], v[134:137], v[198:201], v[86:89]
	v_mfma_f32_16x16x32_bf16 v[78:81], v[166:169], v[198:201], v[78:81]
	s_barrier
	s_add_i32 s0, s52, s41
	v_lshl_add_u64 v[154:155], s[34:35], 0, v[142:143]
	s_mov_b32 m0, s0
	ds_read_b128 v[202:205], v160
	ds_read_b128 v[206:209], v160 offset:1024
	ds_read_b128 v[210:213], v160 offset:2048
	ds_read_b128 v[214:217], v160 offset:3072
	global_load_lds_dwordx4 v[154:155], off
	v_lshl_add_u64 v[218:219], s[34:35], 0, v[138:139]
	s_add_i32 m0, s0, 0x2000
	s_nop 0
	global_load_lds_dwordx4 v[218:219], off
	s_waitcnt vmcnt(10)
	s_barrier
	s_waitcnt lgkmcnt(0)
	s_waitcnt lgkmcnt(0)
	v_mfma_f32_16x16x32_bf16 v[114:117], v[202:205], v[170:173], v[114:117]
	v_mfma_f32_16x16x32_bf16 v[106:109], v[210:213], v[170:173], v[106:109]
	v_mfma_f32_16x16x32_bf16 v[98:101], v[202:205], v[178:181], v[98:101]
	v_mfma_f32_16x16x32_bf16 v[90:93], v[210:213], v[178:181], v[90:93]
	v_mfma_f32_16x16x32_bf16 v[82:85], v[202:205], v[186:189], v[82:85]
	v_mfma_f32_16x16x32_bf16 v[74:77], v[210:213], v[186:189], v[74:77]
	v_mfma_f32_16x16x32_bf16 v[70:73], v[202:205], v[194:197], v[70:73]
	v_mfma_f32_16x16x32_bf16 v[66:69], v[210:213], v[194:197], v[66:69]
	v_mfma_f32_16x16x32_bf16 v[114:117], v[206:209], v[174:177], v[114:117]
	v_mfma_f32_16x16x32_bf16 v[106:109], v[214:217], v[174:177], v[106:109]
	v_mfma_f32_16x16x32_bf16 v[98:101], v[206:209], v[182:185], v[98:101]
	v_mfma_f32_16x16x32_bf16 v[90:93], v[214:217], v[182:185], v[90:93]
	v_mfma_f32_16x16x32_bf16 v[82:85], v[206:209], v[190:193], v[82:85]
	v_mfma_f32_16x16x32_bf16 v[74:77], v[214:217], v[190:193], v[74:77]
	v_mfma_f32_16x16x32_bf16 v[70:73], v[206:209], v[198:201], v[70:73]
	v_mfma_f32_16x16x32_bf16 v[66:69], v[214:217], v[198:201], v[66:69]
	s_mov_b32 m0, s29
	v_lshl_add_u64 v[220:221], s[36:37], 0, v[144:145]
	s_barrier
	ds_read_b128 v[170:173], v159 offset:16384
	ds_read_b128 v[174:177], v159 offset:17408
	ds_read_b128 v[178:181], v159 offset:18432
	ds_read_b128 v[182:185], v159 offset:19456
	ds_read_b128 v[186:189], v159 offset:20480
	ds_read_b128 v[190:193], v159 offset:21504
	ds_read_b128 v[194:197], v159 offset:22528
	ds_read_b128 v[198:201], v159 offset:23552
	global_load_lds_dwordx4 v[220:221], off
	v_lshl_add_u64 v[222:223], s[36:37], 0, v[140:141]
	s_mov_b32 m0, s43
	s_nop 0
	global_load_lds_dwordx4 v[222:223], off
	s_waitcnt vmcnt(10)
	s_barrier
	s_waitcnt lgkmcnt(0)
	s_waitcnt lgkmcnt(0)
	v_mfma_f32_16x16x32_bf16 v[62:65], v[130:133], v[170:173], v[62:65]
	v_mfma_f32_16x16x32_bf16 v[58:61], v[162:165], v[170:173], v[58:61]
	v_mfma_f32_16x16x32_bf16 v[54:57], v[130:133], v[178:181], v[54:57]
	v_mfma_f32_16x16x32_bf16 v[46:49], v[162:165], v[178:181], v[46:49]
	v_mfma_f32_16x16x32_bf16 v[38:41], v[130:133], v[186:189], v[38:41]
	v_mfma_f32_16x16x32_bf16 v[30:33], v[162:165], v[186:189], v[30:33]
	v_mfma_f32_16x16x32_bf16 v[22:25], v[130:133], v[194:197], v[22:25]
	v_mfma_f32_16x16x32_bf16 v[14:17], v[162:165], v[194:197], v[14:17]
	v_mfma_f32_16x16x32_bf16 v[62:65], v[134:137], v[174:177], v[62:65]
	v_mfma_f32_16x16x32_bf16 v[58:61], v[166:169], v[174:177], v[58:61]
	v_mfma_f32_16x16x32_bf16 v[54:57], v[134:137], v[182:185], v[54:57]
	v_mfma_f32_16x16x32_bf16 v[46:49], v[166:169], v[182:185], v[46:49]
	v_mfma_f32_16x16x32_bf16 v[38:41], v[134:137], v[190:193], v[38:41]
	v_mfma_f32_16x16x32_bf16 v[30:33], v[166:169], v[190:193], v[30:33]
	v_mfma_f32_16x16x32_bf16 v[22:25], v[134:137], v[198:201], v[22:25]
	v_mfma_f32_16x16x32_bf16 v[14:17], v[166:169], v[198:201], v[14:17]
	s_barrier
	s_add_u32 s0, s34, 0x40000
	s_addc_u32 s1, s35, 0
	s_add_i32 s61, s53, s41
	v_lshl_add_u64 v[130:131], s[0:1], 0, v[142:143]
	s_mov_b32 m0, s61
	s_nop 0
	global_load_lds_dwordx4 v[130:131], off
	v_lshl_add_u64 v[130:131], s[0:1], 0, v[138:139]
	s_add_i32 m0, s61, 0x2000
	s_nop 0
	global_load_lds_dwordx4 v[130:131], off
	s_waitcnt vmcnt(10)
	s_barrier
	v_mfma_f32_16x16x32_bf16 v[50:53], v[202:205], v[170:173], v[50:53]
	v_mfma_f32_16x16x32_bf16 v[42:45], v[210:213], v[170:173], v[42:45]
	v_mfma_f32_16x16x32_bf16 v[34:37], v[202:205], v[178:181], v[34:37]
	v_mfma_f32_16x16x32_bf16 v[26:29], v[210:213], v[178:181], v[26:29]
	v_mfma_f32_16x16x32_bf16 v[18:21], v[202:205], v[186:189], v[18:21]
	v_mfma_f32_16x16x32_bf16 v[10:13], v[210:213], v[186:189], v[10:13]
	v_mfma_f32_16x16x32_bf16 v[6:9], v[202:205], v[194:197], v[6:9]
	v_mfma_f32_16x16x32_bf16 v[2:5], v[210:213], v[194:197], v[2:5]
	v_mfma_f32_16x16x32_bf16 v[50:53], v[206:209], v[174:177], v[50:53]
	v_mfma_f32_16x16x32_bf16 v[42:45], v[214:217], v[174:177], v[42:45]
	v_mfma_f32_16x16x32_bf16 v[34:37], v[206:209], v[182:185], v[34:37]
	v_mfma_f32_16x16x32_bf16 v[26:29], v[214:217], v[182:185], v[26:29]
	v_mfma_f32_16x16x32_bf16 v[18:21], v[206:209], v[190:193], v[18:21]
	v_mfma_f32_16x16x32_bf16 v[10:13], v[214:217], v[190:193], v[10:13]
	v_mfma_f32_16x16x32_bf16 v[6:9], v[206:209], v[198:201], v[6:9]
	v_mfma_f32_16x16x32_bf16 v[2:5], v[214:217], v[198:201], v[2:5]
	s_add_i32 s61, 0, 0x18000
	v_add_u32_e32 v166, s61, v157
	s_barrier
	ds_read_b128 v[130:133], v166
	ds_read_b128 v[134:137], v166 offset:1024
	ds_read_b128 v[162:165], v166 offset:2048
	ds_read_b128 v[166:169], v166 offset:3072
	s_add_u32 s0, s36, 0x40000
	s_addc_u32 s1, s37, 0
	s_mov_b32 m0, s44
	v_lshl_add_u64 v[202:203], s[0:1], 0, v[144:145]
	ds_read_b128 v[170:173], v159 offset:32768
	ds_read_b128 v[174:177], v159 offset:33792
	ds_read_b128 v[178:181], v159 offset:34816
	ds_read_b128 v[182:185], v159 offset:35840
	ds_read_b128 v[186:189], v159 offset:36864
	ds_read_b128 v[190:193], v159 offset:37888
	ds_read_b128 v[194:197], v159 offset:38912
	ds_read_b128 v[198:201], v159 offset:39936
	global_load_lds_dwordx4 v[202:203], off
	v_lshl_add_u64 v[202:203], s[0:1], 0, v[140:141]
	s_mov_b32 m0, s45
	s_nop 0
	global_load_lds_dwordx4 v[202:203], off
	s_waitcnt lgkmcnt(8)
	s_waitcnt vmcnt(10)
	s_barrier
	s_waitcnt lgkmcnt(0)
	s_waitcnt lgkmcnt(0)
	v_mfma_f32_16x16x32_bf16 v[126:129], v[130:133], v[170:173], v[126:129]
	v_mfma_f32_16x16x32_bf16 v[122:125], v[162:165], v[170:173], v[122:125]
	v_mfma_f32_16x16x32_bf16 v[118:121], v[130:133], v[178:181], v[118:121]
	v_mfma_f32_16x16x32_bf16 v[110:113], v[162:165], v[178:181], v[110:113]
	v_mfma_f32_16x16x32_bf16 v[102:105], v[130:133], v[186:189], v[102:105]
	v_mfma_f32_16x16x32_bf16 v[94:97], v[162:165], v[186:189], v[94:97]
	v_mfma_f32_16x16x32_bf16 v[86:89], v[130:133], v[194:197], v[86:89]
	v_mfma_f32_16x16x32_bf16 v[78:81], v[162:165], v[194:197], v[78:81]
	v_mfma_f32_16x16x32_bf16 v[126:129], v[134:137], v[174:177], v[126:129]
	v_mfma_f32_16x16x32_bf16 v[122:125], v[166:169], v[174:177], v[122:125]
	v_mfma_f32_16x16x32_bf16 v[118:121], v[134:137], v[182:185], v[118:121]
	v_mfma_f32_16x16x32_bf16 v[110:113], v[166:169], v[182:185], v[110:113]
	v_mfma_f32_16x16x32_bf16 v[102:105], v[134:137], v[190:193], v[102:105]
	v_mfma_f32_16x16x32_bf16 v[94:97], v[166:169], v[190:193], v[94:97]
	v_mfma_f32_16x16x32_bf16 v[86:89], v[134:137], v[198:201], v[86:89]
	v_mfma_f32_16x16x32_bf16 v[78:81], v[166:169], v[198:201], v[78:81]
	s_barrier
	s_add_i32 s36, 0, 0x1c000
	s_add_i32 s0, s61, s41
	v_add_u32_e32 v214, s36, v157
	v_lshl_add_u64 v[154:155], v[154:155], 0, s[16:17]
	s_mov_b32 m0, s0
	ds_read_b128 v[202:205], v214
	ds_read_b128 v[206:209], v214 offset:1024
	ds_read_b128 v[210:213], v214 offset:2048
	ds_read_b128 v[214:217], v214 offset:3072
	global_load_lds_dwordx4 v[154:155], off
	v_lshl_add_u64 v[154:155], v[218:219], 0, s[16:17]
	s_add_i32 m0, s0, 0x2000
	s_nop 0
	global_load_lds_dwordx4 v[154:155], off
	s_waitcnt vmcnt(10)
	s_barrier
	s_waitcnt lgkmcnt(0)
	s_waitcnt lgkmcnt(0)
	v_mfma_f32_16x16x32_bf16 v[114:117], v[202:205], v[170:173], v[114:117]
	v_mfma_f32_16x16x32_bf16 v[106:109], v[210:213], v[170:173], v[106:109]
	v_mfma_f32_16x16x32_bf16 v[98:101], v[202:205], v[178:181], v[98:101]
	v_mfma_f32_16x16x32_bf16 v[90:93], v[210:213], v[178:181], v[90:93]
	v_mfma_f32_16x16x32_bf16 v[82:85], v[202:205], v[186:189], v[82:85]
	v_mfma_f32_16x16x32_bf16 v[74:77], v[210:213], v[186:189], v[74:77]
	v_mfma_f32_16x16x32_bf16 v[70:73], v[202:205], v[194:197], v[70:73]
	v_mfma_f32_16x16x32_bf16 v[66:69], v[210:213], v[194:197], v[66:69]
	v_mfma_f32_16x16x32_bf16 v[114:117], v[206:209], v[174:177], v[114:117]
	v_mfma_f32_16x16x32_bf16 v[106:109], v[214:217], v[174:177], v[106:109]
	v_mfma_f32_16x16x32_bf16 v[98:101], v[206:209], v[182:185], v[98:101]
	v_mfma_f32_16x16x32_bf16 v[90:93], v[214:217], v[182:185], v[90:93]
	v_mfma_f32_16x16x32_bf16 v[82:85], v[206:209], v[190:193], v[82:85]
	v_mfma_f32_16x16x32_bf16 v[74:77], v[214:217], v[190:193], v[74:77]
	v_mfma_f32_16x16x32_bf16 v[70:73], v[206:209], v[198:201], v[70:73]
	v_mfma_f32_16x16x32_bf16 v[66:69], v[214:217], v[198:201], v[66:69]
	s_mov_b32 m0, s49
	v_lshl_add_u64 v[154:155], v[220:221], 0, s[16:17]
	s_barrier
	ds_read_b128 v[170:173], v159 offset:49152
	ds_read_b128 v[174:177], v159 offset:50176
	ds_read_b128 v[178:181], v159 offset:51200
	ds_read_b128 v[182:185], v159 offset:52224
	ds_read_b128 v[186:189], v159 offset:53248
	ds_read_b128 v[190:193], v159 offset:54272
	ds_read_b128 v[194:197], v159 offset:55296
	ds_read_b128 v[198:201], v159 offset:56320
	global_load_lds_dwordx4 v[154:155], off
	v_lshl_add_u64 v[154:155], v[222:223], 0, s[16:17]
	s_mov_b32 m0, s51
	s_nop 0
	global_load_lds_dwordx4 v[154:155], off
	s_waitcnt vmcnt(10)
	s_barrier
	s_waitcnt lgkmcnt(0)
	s_waitcnt lgkmcnt(0)
	v_mfma_f32_16x16x32_bf16 v[62:65], v[130:133], v[170:173], v[62:65]
	v_mfma_f32_16x16x32_bf16 v[58:61], v[162:165], v[170:173], v[58:61]
	v_mfma_f32_16x16x32_bf16 v[54:57], v[130:133], v[178:181], v[54:57]
	v_mfma_f32_16x16x32_bf16 v[46:49], v[162:165], v[178:181], v[46:49]
	v_mfma_f32_16x16x32_bf16 v[38:41], v[130:133], v[186:189], v[38:41]
	v_mfma_f32_16x16x32_bf16 v[30:33], v[162:165], v[186:189], v[30:33]
	v_mfma_f32_16x16x32_bf16 v[22:25], v[130:133], v[194:197], v[22:25]
	v_mfma_f32_16x16x32_bf16 v[14:17], v[162:165], v[194:197], v[14:17]
	v_mfma_f32_16x16x32_bf16 v[62:65], v[134:137], v[174:177], v[62:65]
	v_mfma_f32_16x16x32_bf16 v[58:61], v[166:169], v[174:177], v[58:61]
	v_mfma_f32_16x16x32_bf16 v[54:57], v[134:137], v[182:185], v[54:57]
	v_mfma_f32_16x16x32_bf16 v[46:49], v[166:169], v[182:185], v[46:49]
	v_mfma_f32_16x16x32_bf16 v[38:41], v[134:137], v[190:193], v[38:41]
	v_mfma_f32_16x16x32_bf16 v[30:33], v[166:169], v[190:193], v[30:33]
	v_mfma_f32_16x16x32_bf16 v[22:25], v[134:137], v[198:201], v[22:25]
	v_mfma_f32_16x16x32_bf16 v[14:17], v[166:169], v[198:201], v[14:17]
	s_barrier
	s_add_u32 s0, s34, 0x40080
	s_addc_u32 s1, s35, 0
	s_add_i32 s34, s36, s41
	v_lshl_add_u64 v[130:131], s[0:1], 0, v[142:143]
	s_mov_b32 m0, s34
	s_nop 0
	global_load_lds_dwordx4 v[130:131], off
	v_lshl_add_u64 v[130:131], s[0:1], 0, v[138:139]
	s_add_i32 m0, s34, 0x2000
	s_nop 0
	global_load_lds_dwordx4 v[130:131], off
	s_waitcnt vmcnt(10)
	s_barrier
	v_mfma_f32_16x16x32_bf16 v[50:53], v[202:205], v[170:173], v[50:53]
	v_mfma_f32_16x16x32_bf16 v[42:45], v[210:213], v[170:173], v[42:45]
	v_mfma_f32_16x16x32_bf16 v[34:37], v[202:205], v[178:181], v[34:37]
	v_mfma_f32_16x16x32_bf16 v[26:29], v[210:213], v[178:181], v[26:29]
	v_mfma_f32_16x16x32_bf16 v[18:21], v[202:205], v[186:189], v[18:21]
	v_mfma_f32_16x16x32_bf16 v[10:13], v[210:213], v[186:189], v[10:13]
	v_mfma_f32_16x16x32_bf16 v[6:9], v[202:205], v[194:197], v[6:9]
	v_mfma_f32_16x16x32_bf16 v[2:5], v[210:213], v[194:197], v[2:5]
	v_mfma_f32_16x16x32_bf16 v[50:53], v[206:209], v[174:177], v[50:53]
	v_mfma_f32_16x16x32_bf16 v[42:45], v[214:217], v[174:177], v[42:45]
	v_mfma_f32_16x16x32_bf16 v[34:37], v[206:209], v[182:185], v[34:37]
	v_mfma_f32_16x16x32_bf16 v[26:29], v[214:217], v[182:185], v[26:29]
	v_mfma_f32_16x16x32_bf16 v[18:21], v[206:209], v[190:193], v[18:21]
	v_mfma_f32_16x16x32_bf16 v[10:13], v[214:217], v[190:193], v[10:13]
	v_mfma_f32_16x16x32_bf16 v[6:9], v[206:209], v[198:201], v[6:9]
	v_mfma_f32_16x16x32_bf16 v[2:5], v[214:217], v[198:201], v[2:5]
	s_add_i32 s60, s60, 2
	s_add_u32 s58, s58, 0x100
	s_addc_u32 s59, s59, 0
	s_add_u32 s30, s30, 0x100
	s_addc_u32 s31, s31, 0
	s_cmp_gt_u32 s60, 13
	s_barrier
	s_cbranch_scc0 .LBB0_278
	v_mov_b32_e32 v162, v1
	v_mov_b32_e32 v163, v156
	s_cmp_gt_i32 s55, 11
	s_mov_b64 s[30:31], -1
	s_cbranch_scc0 .LBB0_286
	s_cmp_eq_u32 s55, 12
	s_cselect_b64 s[0:1], -1, 0
	s_and_b64 s[0:1], s[0:1], s[18:19]
	v_cmp_gt_i32_e32 vcc, 2, v163
	s_and_b64 s[0:1], s[0:1], vcc
	s_and_saveexec_b64 s[30:31], s[0:1]
	s_cbranch_execz .LBB0_285
	v_lshlrev_b32_e32 v154, 3, v163
	s_andn2_b64 vcc, exec, s[12:13]
	v_ashrrev_i32_e32 v155, 31, v154
	s_cbranch_vccnz .LBB0_283
	v_lshl_add_u64 v[134:135], v[154:155], 2, s[8:9]
	global_load_dwordx4 v[130:133], v[134:135], off
	s_nop 0
	global_load_dwordx4 v[134:137], v[134:135], off offset:16
	s_branch .LBB0_284

.LBB0_434:
	ds_read_b128 v[146:149], v152
	ds_read_b128 v[156:159], v152 offset:1024
	ds_read_b128 v[160:163], v152 offset:2048
	ds_read_b128 v[164:167], v152 offset:3072
	s_add_u32 s0, s36, 0xfffc0080
	s_addc_u32 s1, s37, -1
	s_cmp_eq_u32 s69, 12
	s_cselect_b32 s41, s60, s1
	s_cselect_b32 s40, s61, s0
	s_cselect_b32 s39, s62, s67
	s_cselect_b32 s38, s63, s66
	s_mov_b32 m0, s50
	v_lshl_add_u64 v[200:201], s[36:37], 0, v[144:145]
	ds_read_b128 v[168:171], v153
	ds_read_b128 v[172:175], v153 offset:1024
	ds_read_b128 v[176:179], v153 offset:2048
	ds_read_b128 v[180:183], v153 offset:3072
	ds_read_b128 v[184:187], v153 offset:4096
	ds_read_b128 v[188:191], v153 offset:5120
	ds_read_b128 v[192:195], v153 offset:6144
	ds_read_b128 v[196:199], v153 offset:7168
	global_load_lds_dwordx4 v[200:201], off
	v_lshl_add_u64 v[200:201], s[36:37], 0, v[142:143]
	s_mov_b32 m0, s51
	s_nop 0
	global_load_lds_dwordx4 v[200:201], off
	s_waitcnt lgkmcnt(8)
	s_waitcnt vmcnt(10)
	s_barrier
	s_waitcnt lgkmcnt(0)
	s_waitcnt lgkmcnt(0)
	v_mfma_f32_16x16x32_bf16 v[126:129], v[146:149], v[168:171], v[126:129]
	v_mfma_f32_16x16x32_bf16 v[122:125], v[160:163], v[168:171], v[122:125]
	v_mfma_f32_16x16x32_bf16 v[114:117], v[146:149], v[176:179], v[114:117]
	v_mfma_f32_16x16x32_bf16 v[106:109], v[160:163], v[176:179], v[106:109]
	v_mfma_f32_16x16x32_bf16 v[98:101], v[146:149], v[184:187], v[98:101]
	v_mfma_f32_16x16x32_bf16 v[90:93], v[160:163], v[184:187], v[90:93]
	v_mfma_f32_16x16x32_bf16 v[82:85], v[146:149], v[192:195], v[82:85]
	v_mfma_f32_16x16x32_bf16 v[74:77], v[160:163], v[192:195], v[74:77]
	v_mfma_f32_16x16x32_bf16 v[126:129], v[156:159], v[172:175], v[126:129]
	v_mfma_f32_16x16x32_bf16 v[122:125], v[164:167], v[172:175], v[122:125]
	v_mfma_f32_16x16x32_bf16 v[114:117], v[156:159], v[180:183], v[114:117]
	v_mfma_f32_16x16x32_bf16 v[106:109], v[164:167], v[180:183], v[106:109]
	v_mfma_f32_16x16x32_bf16 v[98:101], v[156:159], v[188:191], v[98:101]
	v_mfma_f32_16x16x32_bf16 v[90:93], v[164:167], v[188:191], v[90:93]
	v_mfma_f32_16x16x32_bf16 v[82:85], v[156:159], v[196:199], v[82:85]
	v_mfma_f32_16x16x32_bf16 v[74:77], v[164:167], v[196:199], v[74:77]
	s_barrier
	s_mov_b32 m0, s52
	v_lshl_add_u64 v[216:217], s[38:39], 0, v[138:139]
	ds_read_b128 v[200:203], v154
	ds_read_b128 v[204:207], v154 offset:1024
	ds_read_b128 v[208:211], v154 offset:2048
	ds_read_b128 v[212:215], v154 offset:3072
	global_load_lds_dwordx4 v[216:217], off
	v_lshl_add_u64 v[218:219], s[38:39], 0, v[134:135]
	s_mov_b32 m0, s53
	s_nop 0
	global_load_lds_dwordx4 v[218:219], off
	s_waitcnt vmcnt(10)
	s_barrier
	s_waitcnt lgkmcnt(0)
	s_waitcnt lgkmcnt(0)
	v_mfma_f32_16x16x32_bf16 v[118:121], v[200:203], v[168:171], v[118:121]
	v_mfma_f32_16x16x32_bf16 v[110:113], v[208:211], v[168:171], v[110:113]
	v_mfma_f32_16x16x32_bf16 v[102:105], v[200:203], v[176:179], v[102:105]
	v_mfma_f32_16x16x32_bf16 v[94:97], v[208:211], v[176:179], v[94:97]
	v_mfma_f32_16x16x32_bf16 v[86:89], v[200:203], v[184:187], v[86:89]
	v_mfma_f32_16x16x32_bf16 v[78:81], v[208:211], v[184:187], v[78:81]
	v_mfma_f32_16x16x32_bf16 v[70:73], v[200:203], v[192:195], v[70:73]
	v_mfma_f32_16x16x32_bf16 v[66:69], v[208:211], v[192:195], v[66:69]
	v_mfma_f32_16x16x32_bf16 v[118:121], v[204:207], v[172:175], v[118:121]
	v_mfma_f32_16x16x32_bf16 v[110:113], v[212:215], v[172:175], v[110:113]
	v_mfma_f32_16x16x32_bf16 v[102:105], v[204:207], v[180:183], v[102:105]
	v_mfma_f32_16x16x32_bf16 v[94:97], v[212:215], v[180:183], v[94:97]
	v_mfma_f32_16x16x32_bf16 v[86:89], v[204:207], v[188:191], v[86:89]
	v_mfma_f32_16x16x32_bf16 v[78:81], v[212:215], v[188:191], v[78:81]
	v_mfma_f32_16x16x32_bf16 v[70:73], v[204:207], v[196:199], v[70:73]
	v_mfma_f32_16x16x32_bf16 v[66:69], v[212:215], v[196:199], v[66:69]
	s_mov_b32 m0, s6
	v_lshl_add_u64 v[220:221], s[40:41], 0, v[140:141]
	s_barrier
	ds_read_b128 v[168:171], v153 offset:16384
	ds_read_b128 v[172:175], v153 offset:17408
	ds_read_b128 v[176:179], v153 offset:18432
	ds_read_b128 v[180:183], v153 offset:19456
	ds_read_b128 v[184:187], v153 offset:20480
	ds_read_b128 v[188:191], v153 offset:21504
	ds_read_b128 v[192:195], v153 offset:22528
	ds_read_b128 v[196:199], v153 offset:23552
	global_load_lds_dwordx4 v[220:221], off
	v_lshl_add_u64 v[222:223], s[40:41], 0, v[136:137]
	s_mov_b32 m0, s7
	s_nop 0
	global_load_lds_dwordx4 v[222:223], off
	s_waitcnt vmcnt(10)
	s_barrier
	s_waitcnt lgkmcnt(0)
	s_waitcnt lgkmcnt(0)
	v_mfma_f32_16x16x32_bf16 v[62:65], v[146:149], v[168:171], v[62:65]
	v_mfma_f32_16x16x32_bf16 v[58:61], v[160:163], v[168:171], v[58:61]
	v_mfma_f32_16x16x32_bf16 v[50:53], v[146:149], v[176:179], v[50:53]
	v_mfma_f32_16x16x32_bf16 v[42:45], v[160:163], v[176:179], v[42:45]
	v_mfma_f32_16x16x32_bf16 v[34:37], v[146:149], v[184:187], v[34:37]
	v_mfma_f32_16x16x32_bf16 v[26:29], v[160:163], v[184:187], v[26:29]
	v_mfma_f32_16x16x32_bf16 v[18:21], v[146:149], v[192:195], v[18:21]
	v_mfma_f32_16x16x32_bf16 v[10:13], v[160:163], v[192:195], v[10:13]
	v_mfma_f32_16x16x32_bf16 v[62:65], v[156:159], v[172:175], v[62:65]
	v_mfma_f32_16x16x32_bf16 v[58:61], v[164:167], v[172:175], v[58:61]
	v_mfma_f32_16x16x32_bf16 v[50:53], v[156:159], v[180:183], v[50:53]
	v_mfma_f32_16x16x32_bf16 v[42:45], v[164:167], v[180:183], v[42:45]
	v_mfma_f32_16x16x32_bf16 v[34:37], v[156:159], v[188:191], v[34:37]
	v_mfma_f32_16x16x32_bf16 v[26:29], v[164:167], v[188:191], v[26:29]
	v_mfma_f32_16x16x32_bf16 v[18:21], v[156:159], v[196:199], v[18:21]
	v_mfma_f32_16x16x32_bf16 v[10:13], v[164:167], v[196:199], v[10:13]
	s_barrier
	s_add_u32 s0, s38, 0x40000
	s_addc_u32 s1, s39, 0
	s_mov_b32 m0, s54
	v_lshl_add_u64 v[146:147], s[0:1], 0, v[138:139]
	global_load_lds_dwordx4 v[146:147], off
	v_lshl_add_u64 v[146:147], s[0:1], 0, v[134:135]
	s_add_i32 m0, s54, 0x2000
	s_nop 0
	global_load_lds_dwordx4 v[146:147], off
	s_waitcnt vmcnt(10)
	s_barrier
	v_mfma_f32_16x16x32_bf16 v[54:57], v[200:203], v[168:171], v[54:57]
	v_mfma_f32_16x16x32_bf16 v[46:49], v[208:211], v[168:171], v[46:49]
	v_mfma_f32_16x16x32_bf16 v[38:41], v[200:203], v[176:179], v[38:41]
	v_mfma_f32_16x16x32_bf16 v[30:33], v[208:211], v[176:179], v[30:33]
	v_mfma_f32_16x16x32_bf16 v[22:25], v[200:203], v[184:187], v[22:25]
	v_mfma_f32_16x16x32_bf16 v[14:17], v[208:211], v[184:187], v[14:17]
	v_mfma_f32_16x16x32_bf16 v[6:9], v[200:203], v[192:195], v[6:9]
	v_mfma_f32_16x16x32_bf16 v[2:5], v[208:211], v[192:195], v[2:5]
	v_mfma_f32_16x16x32_bf16 v[54:57], v[204:207], v[172:175], v[54:57]
	v_mfma_f32_16x16x32_bf16 v[46:49], v[212:215], v[172:175], v[46:49]
	v_mfma_f32_16x16x32_bf16 v[38:41], v[204:207], v[180:183], v[38:41]
	v_mfma_f32_16x16x32_bf16 v[30:33], v[212:215], v[180:183], v[30:33]
	v_mfma_f32_16x16x32_bf16 v[22:25], v[204:207], v[188:191], v[22:25]
	v_mfma_f32_16x16x32_bf16 v[14:17], v[212:215], v[188:191], v[14:17]
	v_mfma_f32_16x16x32_bf16 v[6:9], v[204:207], v[196:199], v[6:9]
	v_mfma_f32_16x16x32_bf16 v[2:5], v[212:215], v[196:199], v[2:5]
	s_add_i32 s70, 0, 0x18000
	v_add_u32_e32 v155, s70, v151
	s_barrier
	ds_read_b128 v[146:149], v155
	ds_read_b128 v[156:159], v155 offset:1024
	ds_read_b128 v[160:163], v155 offset:2048
	ds_read_b128 v[164:167], v155 offset:3072
	s_add_u32 s0, s40, 0x40000
	s_addc_u32 s1, s41, 0
	s_mov_b32 m0, s29
	v_lshl_add_u64 v[200:201], s[0:1], 0, v[140:141]
	ds_read_b128 v[168:171], v153 offset:32768
	ds_read_b128 v[172:175], v153 offset:33792
	ds_read_b128 v[176:179], v153 offset:34816
	ds_read_b128 v[180:183], v153 offset:35840
	ds_read_b128 v[184:187], v153 offset:36864
	ds_read_b128 v[188:191], v153 offset:37888
	ds_read_b128 v[192:195], v153 offset:38912
	ds_read_b128 v[196:199], v153 offset:39936
	global_load_lds_dwordx4 v[200:201], off
	v_lshl_add_u64 v[200:201], s[0:1], 0, v[136:137]
	s_mov_b32 m0, s42
	s_nop 0
	global_load_lds_dwordx4 v[200:201], off
	s_waitcnt lgkmcnt(8)
	s_waitcnt vmcnt(10)
	s_barrier
	s_waitcnt lgkmcnt(0)
	s_waitcnt lgkmcnt(0)
	v_mfma_f32_16x16x32_bf16 v[126:129], v[146:149], v[168:171], v[126:129]
	v_mfma_f32_16x16x32_bf16 v[122:125], v[160:163], v[168:171], v[122:125]
	v_mfma_f32_16x16x32_bf16 v[114:117], v[146:149], v[176:179], v[114:117]
	v_mfma_f32_16x16x32_bf16 v[106:109], v[160:163], v[176:179], v[106:109]
	v_mfma_f32_16x16x32_bf16 v[98:101], v[146:149], v[184:187], v[98:101]
	v_mfma_f32_16x16x32_bf16 v[90:93], v[160:163], v[184:187], v[90:93]
	v_mfma_f32_16x16x32_bf16 v[82:85], v[146:149], v[192:195], v[82:85]
	v_mfma_f32_16x16x32_bf16 v[74:77], v[160:163], v[192:195], v[74:77]
	v_mfma_f32_16x16x32_bf16 v[126:129], v[156:159], v[172:175], v[126:129]
	v_mfma_f32_16x16x32_bf16 v[122:125], v[164:167], v[172:175], v[122:125]
	v_mfma_f32_16x16x32_bf16 v[114:117], v[156:159], v[180:183], v[114:117]
	v_mfma_f32_16x16x32_bf16 v[106:109], v[164:167], v[180:183], v[106:109]
	v_mfma_f32_16x16x32_bf16 v[98:101], v[156:159], v[188:191], v[98:101]
	v_mfma_f32_16x16x32_bf16 v[90:93], v[164:167], v[188:191], v[90:93]
	v_mfma_f32_16x16x32_bf16 v[82:85], v[156:159], v[196:199], v[82:85]
	v_mfma_f32_16x16x32_bf16 v[74:77], v[164:167], v[196:199], v[74:77]
	s_barrier
	s_add_i32 s40, 0, 0x1c000
	s_add_i32 s0, s70, s5
	v_add_u32_e32 v155, s40, v151
	v_lshl_add_u64 v[216:217], v[216:217], 0, s[26:27]
	s_mov_b32 m0, s0
	ds_read_b128 v[200:203], v155
	ds_read_b128 v[204:207], v155 offset:1024
	ds_read_b128 v[208:211], v155 offset:2048
	ds_read_b128 v[212:215], v155 offset:3072
	global_load_lds_dwordx4 v[216:217], off
	v_lshl_add_u64 v[216:217], v[218:219], 0, s[26:27]
	s_add_i32 m0, s0, 0x2000
	s_nop 0
	global_load_lds_dwordx4 v[216:217], off
	s_waitcnt vmcnt(10)
	s_barrier
	s_waitcnt lgkmcnt(0)
	s_waitcnt lgkmcnt(0)
	v_mfma_f32_16x16x32_bf16 v[118:121], v[200:203], v[168:171], v[118:121]
	v_mfma_f32_16x16x32_bf16 v[110:113], v[208:211], v[168:171], v[110:113]
	v_mfma_f32_16x16x32_bf16 v[102:105], v[200:203], v[176:179], v[102:105]
	v_mfma_f32_16x16x32_bf16 v[94:97], v[208:211], v[176:179], v[94:97]
	v_mfma_f32_16x16x32_bf16 v[86:89], v[200:203], v[184:187], v[86:89]
	v_mfma_f32_16x16x32_bf16 v[78:81], v[208:211], v[184:187], v[78:81]
	v_mfma_f32_16x16x32_bf16 v[70:73], v[200:203], v[192:195], v[70:73]
	v_mfma_f32_16x16x32_bf16 v[66:69], v[208:211], v[192:195], v[66:69]
	v_mfma_f32_16x16x32_bf16 v[118:121], v[204:207], v[172:175], v[118:121]
	v_mfma_f32_16x16x32_bf16 v[110:113], v[212:215], v[172:175], v[110:113]
	v_mfma_f32_16x16x32_bf16 v[102:105], v[204:207], v[180:183], v[102:105]
	v_mfma_f32_16x16x32_bf16 v[94:97], v[212:215], v[180:183], v[94:97]
	v_mfma_f32_16x16x32_bf16 v[86:89], v[204:207], v[188:191], v[86:89]
	v_mfma_f32_16x16x32_bf16 v[78:81], v[212:215], v[188:191], v[78:81]
	v_mfma_f32_16x16x32_bf16 v[70:73], v[204:207], v[196:199], v[70:73]
	v_mfma_f32_16x16x32_bf16 v[66:69], v[212:215], v[196:199], v[66:69]
	s_mov_b32 m0, s46
	v_lshl_add_u64 v[216:217], v[220:221], 0, s[26:27]
	s_barrier
	ds_read_b128 v[168:171], v153 offset:49152
	ds_read_b128 v[172:175], v153 offset:50176
	ds_read_b128 v[176:179], v153 offset:51200
	ds_read_b128 v[180:183], v153 offset:52224
	ds_read_b128 v[184:187], v153 offset:53248
	ds_read_b128 v[188:191], v153 offset:54272
	ds_read_b128 v[192:195], v153 offset:55296
	ds_read_b128 v[196:199], v153 offset:56320
	global_load_lds_dwordx4 v[216:217], off
	v_lshl_add_u64 v[216:217], v[222:223], 0, s[26:27]
	s_mov_b32 m0, s47
	s_nop 0
	global_load_lds_dwordx4 v[216:217], off
	s_waitcnt vmcnt(10)
	s_barrier
	s_waitcnt lgkmcnt(0)
	s_waitcnt lgkmcnt(0)
	v_mfma_f32_16x16x32_bf16 v[62:65], v[146:149], v[168:171], v[62:65]
	v_mfma_f32_16x16x32_bf16 v[58:61], v[160:163], v[168:171], v[58:61]
	v_mfma_f32_16x16x32_bf16 v[50:53], v[146:149], v[176:179], v[50:53]
	v_mfma_f32_16x16x32_bf16 v[42:45], v[160:163], v[176:179], v[42:45]
	v_mfma_f32_16x16x32_bf16 v[34:37], v[146:149], v[184:187], v[34:37]
	v_mfma_f32_16x16x32_bf16 v[26:29], v[160:163], v[184:187], v[26:29]
	v_mfma_f32_16x16x32_bf16 v[18:21], v[146:149], v[192:195], v[18:21]
	v_mfma_f32_16x16x32_bf16 v[10:13], v[160:163], v[192:195], v[10:13]
	v_mfma_f32_16x16x32_bf16 v[62:65], v[156:159], v[172:175], v[62:65]
	v_mfma_f32_16x16x32_bf16 v[58:61], v[164:167], v[172:175], v[58:61]
	v_mfma_f32_16x16x32_bf16 v[50:53], v[156:159], v[180:183], v[50:53]
	v_mfma_f32_16x16x32_bf16 v[42:45], v[164:167], v[180:183], v[42:45]
	v_mfma_f32_16x16x32_bf16 v[34:37], v[156:159], v[188:191], v[34:37]
	v_mfma_f32_16x16x32_bf16 v[26:29], v[164:167], v[188:191], v[26:29]
	v_mfma_f32_16x16x32_bf16 v[18:21], v[156:159], v[196:199], v[18:21]
	v_mfma_f32_16x16x32_bf16 v[10:13], v[164:167], v[196:199], v[10:13]
	s_barrier
	s_add_u32 s0, s38, 0x40080
	s_addc_u32 s1, s39, 0
	s_add_i32 s38, s40, s5
	v_lshl_add_u64 v[146:147], s[0:1], 0, v[138:139]
	s_mov_b32 m0, s38
	s_nop 0
	global_load_lds_dwordx4 v[146:147], off
	v_lshl_add_u64 v[146:147], s[0:1], 0, v[134:135]
	s_add_i32 m0, s38, 0x2000
	s_nop 0
	global_load_lds_dwordx4 v[146:147], off
	s_waitcnt vmcnt(10)
	s_barrier
	v_mfma_f32_16x16x32_bf16 v[54:57], v[200:203], v[168:171], v[54:57]
	v_mfma_f32_16x16x32_bf16 v[46:49], v[208:211], v[168:171], v[46:49]
	v_mfma_f32_16x16x32_bf16 v[38:41], v[200:203], v[176:179], v[38:41]
	v_mfma_f32_16x16x32_bf16 v[30:33], v[208:211], v[176:179], v[30:33]
	v_mfma_f32_16x16x32_bf16 v[22:25], v[200:203], v[184:187], v[22:25]
	v_mfma_f32_16x16x32_bf16 v[14:17], v[208:211], v[184:187], v[14:17]
	v_mfma_f32_16x16x32_bf16 v[6:9], v[200:203], v[192:195], v[6:9]
	v_mfma_f32_16x16x32_bf16 v[2:5], v[208:211], v[192:195], v[2:5]
	v_mfma_f32_16x16x32_bf16 v[54:57], v[204:207], v[172:175], v[54:57]
	v_mfma_f32_16x16x32_bf16 v[46:49], v[212:215], v[172:175], v[46:49]
	v_mfma_f32_16x16x32_bf16 v[38:41], v[204:207], v[180:183], v[38:41]
	v_mfma_f32_16x16x32_bf16 v[30:33], v[212:215], v[180:183], v[30:33]
	v_mfma_f32_16x16x32_bf16 v[22:25], v[204:207], v[188:191], v[22:25]
	v_mfma_f32_16x16x32_bf16 v[14:17], v[212:215], v[188:191], v[14:17]
	v_mfma_f32_16x16x32_bf16 v[6:9], v[204:207], v[196:199], v[6:9]
	v_mfma_f32_16x16x32_bf16 v[2:5], v[212:215], v[196:199], v[2:5]
	s_add_i32 s69, s69, 2
	s_add_u32 s66, s66, 0x100
	s_addc_u32 s67, s67, 0
	s_add_u32 s36, s36, 0x100
	s_addc_u32 s37, s37, 0
	s_cmp_gt_u32 s69, 13
	s_barrier
	s_cbranch_scc0 .LBB0_434
	v_mov_b32_e32 v147, v131
	v_mov_b32_e32 v146, v133
	s_lshl_b32 s0, s58, 8
	s_or_b32 s0, s0, s45
	v_lshl_add_u32 v146, v146, 3, s0
	s_lshl_b32 s0, s59, 8
	s_add_i32 s0, s0, s44
	v_add_u32_e32 v155, s0, v147
	v_mov_b32_e32 v148, v155
	v_ashrrev_i32_e32 v147, 31, v146
	v_ashrrev_i32_e32 v149, 31, v148
	v_lshlrev_b64 v[148:149], 10, v[148:149]
	v_lshl_add_u64 v[148:149], v[148:149], 0, v[146:147]
	v_lshlrev_b64 v[148:149], 1, v[148:149]
	v_lshl_add_u64 v[176:177], s[10:11], 0, v[148:149]
	flat_load_dwordx4 v[156:159], v[176:177]
	flat_load_dwordx4 v[160:163], v[176:177] offset:256
	v_add_co_u32_e32 v168, vcc, s49, v176
	v_lshl_add_u64 v[148:149], s[12:13], 0, v[148:149]
	s_nop 0
	v_addc_co_u32_e32 v169, vcc, 0, v177, vcc
	flat_load_dwordx4 v[164:167], v[168:169]
	s_nop 0
	flat_load_dwordx4 v[168:171], v[168:169] offset:256
	v_add_co_u32_e32 v178, vcc, s43, v176
	s_mov_b32 s58, s57
	s_nop 0
	v_addc_co_u32_e32 v179, vcc, 0, v177, vcc
	flat_load_dwordx4 v[172:175], v[178:179]
	v_add_co_u32_e32 v184, vcc, s48, v176
	s_mov_b32 s59, s56
	s_nop 0
	v_addc_co_u32_e32 v185, vcc, 0, v177, vcc
	flat_load_dwordx4 v[176:179], v[178:179] offset:256
	s_nop 0
	flat_load_dwordx4 v[180:183], v[184:185]
	s_nop 0
	flat_load_dwordx4 v[184:187], v[184:185] offset:256
	v_add_co_u32_e32 v188, vcc, s49, v148
	s_waitcnt vmcnt(0) lgkmcnt(0)
	v_lshlrev_b32_e32 v190, 16, v156
	v_and_b32_e32 v191, 0xffff0000, v156
	v_lshlrev_b32_e32 v156, 16, v157
	v_and_b32_e32 v157, 0xffff0000, v157
	v_lshlrev_b32_e32 v192, 16, v158
	v_and_b32_e32 v193, 0xffff0000, v158
	v_lshlrev_b32_e32 v194, 16, v160
	v_and_b32_e32 v195, 0xffff0000, v160
	v_lshlrev_b32_e32 v160, 16, v161
	v_and_b32_e32 v161, 0xffff0000, v161
	v_lshlrev_b32_e32 v196, 16, v162
	v_and_b32_e32 v197, 0xffff0000, v162
	v_lshlrev_b32_e32 v162, 16, v163
	v_and_b32_e32 v163, 0xffff0000, v163
	v_lshlrev_b32_e32 v158, 16, v159
	v_and_b32_e32 v159, 0xffff0000, v159
	v_pk_fma_f32 v[128:129], v[156:157], s[28:29], v[128:129] op_sel_hi:[1,0,1]
	v_pk_fma_f32 v[122:123], v[192:193], s[28:29], v[122:123] op_sel_hi:[1,0,1]
	v_pk_fma_f32 v[120:121], v[160:161], s[28:29], v[120:121] op_sel_hi:[1,0,1]
	v_pk_fma_f32 v[156:157], v[162:163], s[28:29], v[112:113] op_sel_hi:[1,0,1]
	v_lshlrev_b32_e32 v160, 16, v164
	v_and_b32_e32 v161, 0xffff0000, v164
	v_lshlrev_b32_e32 v162, 16, v165
	v_and_b32_e32 v163, 0xffff0000, v165
	v_lshlrev_b32_e32 v164, 16, v166
	v_and_b32_e32 v165, 0xffff0000, v166
	v_lshlrev_b32_e32 v166, 16, v167
	v_and_b32_e32 v167, 0xffff0000, v167
	v_pk_fma_f32 v[126:127], v[190:191], s[28:29], v[126:127] op_sel_hi:[1,0,1]
	v_pk_fma_f32 v[124:125], v[158:159], s[28:29], v[124:125] op_sel_hi:[1,0,1]
	v_cvt_pk_bf16_f32 v112, v122, v123
	v_pk_fma_f32 v[116:117], v[162:163], s[28:29], v[116:117] op_sel_hi:[1,0,1]
	v_pk_fma_f32 v[114:115], v[160:161], s[28:29], v[114:115] op_sel_hi:[1,0,1]
	v_pk_fma_f32 v[122:123], v[166:167], s[28:29], v[108:109] op_sel_hi:[1,0,1]
	v_pk_fma_f32 v[108:109], v[164:165], s[28:29], v[106:107] op_sel_hi:[1,0,1]
	v_addc_co_u32_e32 v189, vcc, 0, v149, vcc
	v_pk_fma_f32 v[118:119], v[194:195], s[28:29], v[118:119] op_sel_hi:[1,0,1]
	v_pk_fma_f32 v[158:159], v[196:197], s[28:29], v[110:111] op_sel_hi:[1,0,1]
	v_cvt_pk_bf16_f32 v110, v126, v127
	v_cvt_pk_bf16_f32 v111, v128, v129
	v_cvt_pk_bf16_f32 v113, v124, v125
	v_cvt_pk_bf16_f32 v106, v114, v115
	v_cvt_pk_bf16_f32 v107, v116, v117
	v_cvt_pk_bf16_f32 v108, v108, v109
	v_cvt_pk_bf16_f32 v109, v122, v123
	v_lshlrev_b32_e32 v190, 16, v168
	v_cvt_pk_bf16_f32 v118, v118, v119
	v_cvt_pk_bf16_f32 v119, v120, v121
	v_cvt_pk_bf16_f32 v120, v158, v159
	v_cvt_pk_bf16_f32 v121, v156, v157
	flat_store_dwordx4 v[148:149], v[110:113]
	flat_store_dwordx4 v[148:149], v[118:121] offset:256
	flat_store_dwordx4 v[188:189], v[106:109]
	v_and_b32_e32 v191, 0xffff0000, v168
	v_lshlrev_b32_e32 v110, 16, v171
	v_lshlrev_b32_e32 v106, 16, v169
	v_and_b32_e32 v107, 0xffff0000, v169
	v_lshlrev_b32_e32 v108, 16, v170
	v_and_b32_e32 v109, 0xffff0000, v170
	v_and_b32_e32 v111, 0xffff0000, v171
	v_pk_fma_f32 v[104:105], v[106:107], s[28:29], v[104:105] op_sel_hi:[1,0,1]
	v_pk_fma_f32 v[102:103], v[190:191], s[28:29], v[102:103] op_sel_hi:[1,0,1]
	v_pk_fma_f32 v[106:107], v[110:111], s[28:29], v[96:97] op_sel_hi:[1,0,1]
	v_pk_fma_f32 v[96:97], v[108:109], s[28:29], v[94:95] op_sel_hi:[1,0,1]
	v_cvt_pk_bf16_f32 v94, v102, v103
	v_cvt_pk_bf16_f32 v95, v104, v105
	v_cvt_pk_bf16_f32 v96, v96, v97
	v_cvt_pk_bf16_f32 v97, v106, v107
	flat_store_dwordx4 v[188:189], v[94:97] offset:256
	v_lshlrev_b32_e32 v102, 16, v174
	v_and_b32_e32 v103, 0xffff0000, v174
	v_lshlrev_b32_e32 v94, 16, v172
	v_and_b32_e32 v95, 0xffff0000, v172
	v_lshlrev_b32_e32 v96, 16, v173
	v_and_b32_e32 v97, 0xffff0000, v173
	v_lshlrev_b32_e32 v104, 16, v175
	v_and_b32_e32 v105, 0xffff0000, v175
	v_pk_fma_f32 v[94:95], v[94:95], s[28:29], v[98:99] op_sel_hi:[1,0,1]
	v_pk_fma_f32 v[96:97], v[96:97], s[28:29], v[100:101] op_sel_hi:[1,0,1]
	v_pk_fma_f32 v[98:99], v[104:105], s[28:29], v[92:93] op_sel_hi:[1,0,1]
	v_pk_fma_f32 v[92:93], v[102:103], s[28:29], v[90:91] op_sel_hi:[1,0,1]
	v_cvt_pk_bf16_f32 v90, v94, v95
	v_add_co_u32_e32 v94, vcc, s43, v148
	v_cvt_pk_bf16_f32 v91, v96, v97
	v_cvt_pk_bf16_f32 v92, v92, v93
	v_cvt_pk_bf16_f32 v93, v98, v99
	v_addc_co_u32_e32 v95, vcc, 0, v149, vcc
	flat_store_dwordx4 v[94:95], v[90:93]
	v_lshlrev_b32_e32 v96, 16, v178
	v_and_b32_e32 v97, 0xffff0000, v178
	v_lshlrev_b32_e32 v90, 16, v176
	v_and_b32_e32 v91, 0xffff0000, v176
	v_lshlrev_b32_e32 v92, 16, v177
	v_and_b32_e32 v93, 0xffff0000, v177
	v_lshlrev_b32_e32 v98, 16, v179
	v_and_b32_e32 v99, 0xffff0000, v179
	v_pk_fma_f32 v[88:89], v[92:93], s[28:29], v[88:89] op_sel_hi:[1,0,1]
	v_pk_fma_f32 v[86:87], v[90:91], s[28:29], v[86:87] op_sel_hi:[1,0,1]
	v_pk_fma_f32 v[90:91], v[98:99], s[28:29], v[80:81] op_sel_hi:[1,0,1]
	v_pk_fma_f32 v[80:81], v[96:97], s[28:29], v[78:79] op_sel_hi:[1,0,1]
	v_cvt_pk_bf16_f32 v78, v86, v87
	v_cvt_pk_bf16_f32 v79, v88, v89
	v_cvt_pk_bf16_f32 v80, v80, v81
	v_cvt_pk_bf16_f32 v81, v90, v91
	flat_store_dwordx4 v[94:95], v[78:81] offset:256
	v_lshlrev_b32_e32 v86, 16, v182
	v_and_b32_e32 v87, 0xffff0000, v182
	v_lshlrev_b32_e32 v78, 16, v180
	v_and_b32_e32 v79, 0xffff0000, v180
	v_lshlrev_b32_e32 v80, 16, v181
	v_and_b32_e32 v81, 0xffff0000, v181
	v_lshlrev_b32_e32 v88, 16, v183
	v_and_b32_e32 v89, 0xffff0000, v183
	v_pk_fma_f32 v[78:79], v[78:79], s[28:29], v[82:83] op_sel_hi:[1,0,1]
	v_pk_fma_f32 v[80:81], v[80:81], s[28:29], v[84:85] op_sel_hi:[1,0,1]
	v_pk_fma_f32 v[82:83], v[88:89], s[28:29], v[76:77] op_sel_hi:[1,0,1]
	v_pk_fma_f32 v[76:77], v[86:87], s[28:29], v[74:75] op_sel_hi:[1,0,1]
	v_cvt_pk_bf16_f32 v74, v78, v79
	v_add_co_u32_e32 v78, vcc, s48, v148
	v_cvt_pk_bf16_f32 v75, v80, v81
	v_cvt_pk_bf16_f32 v76, v76, v77
	v_cvt_pk_bf16_f32 v77, v82, v83
	v_addc_co_u32_e32 v79, vcc, 0, v149, vcc
	flat_store_dwordx4 v[78:79], v[74:77]
	v_lshlrev_b32_e32 v80, 16, v186
	v_and_b32_e32 v81, 0xffff0000, v186
	v_lshlrev_b32_e32 v74, 16, v184
	v_and_b32_e32 v75, 0xffff0000, v184
	v_lshlrev_b32_e32 v76, 16, v185
	v_and_b32_e32 v77, 0xffff0000, v185
	v_lshlrev_b32_e32 v82, 16, v187
	v_and_b32_e32 v83, 0xffff0000, v187
	v_pk_fma_f32 v[72:73], v[76:77], s[28:29], v[72:73] op_sel_hi:[1,0,1]
	v_pk_fma_f32 v[70:71], v[74:75], s[28:29], v[70:71] op_sel_hi:[1,0,1]
	v_pk_fma_f32 v[74:75], v[82:83], s[28:29], v[68:69] op_sel_hi:[1,0,1]
	v_pk_fma_f32 v[68:69], v[80:81], s[28:29], v[66:67] op_sel_hi:[1,0,1]
	v_cvt_pk_bf16_f32 v66, v70, v71
	v_cvt_pk_bf16_f32 v67, v72, v73
	v_cvt_pk_bf16_f32 v68, v68, v69
	v_cvt_pk_bf16_f32 v69, v74, v75
	flat_store_dwordx4 v[78:79], v[66:69] offset:256
	s_nop 1
	v_add_u32_e32 v66, 0x80, v155
	s_nop 0
	v_ashrrev_i32_e32 v67, 31, v66
	v_lshlrev_b64 v[66:67], 10, v[66:67]
	v_lshl_add_u64 v[66:67], v[66:67], 0, v[146:147]
	v_lshlrev_b64 v[98:99], 1, v[66:67]
	v_lshl_add_u64 v[90:91], s[10:11], 0, v[98:99]
	flat_load_dwordx4 v[66:69], v[90:91]
	flat_load_dwordx4 v[70:73], v[90:91] offset:256
	v_add_co_u32_e32 v78, vcc, s49, v90
	s_waitcnt vmcnt(0) lgkmcnt(0)
	v_lshlrev_b32_e32 v100, 16, v66
	v_addc_co_u32_e32 v79, vcc, 0, v91, vcc
	flat_load_dwordx4 v[74:77], v[78:79]
	s_nop 0
	flat_load_dwordx4 v[78:81], v[78:79] offset:256
	v_add_co_u32_e32 v86, vcc, s43, v90
	v_and_b32_e32 v101, 0xffff0000, v66
	s_nop 0
	v_addc_co_u32_e32 v87, vcc, 0, v91, vcc
	flat_load_dwordx4 v[82:85], v[86:87]
	s_nop 0
	flat_load_dwordx4 v[86:89], v[86:87] offset:256
	v_add_co_u32_e32 v94, vcc, s48, v90
	v_lshlrev_b32_e32 v66, 16, v67
	s_nop 0
	v_addc_co_u32_e32 v95, vcc, 0, v91, vcc
	flat_load_dwordx4 v[90:93], v[94:95]
	s_nop 0
	flat_load_dwordx4 v[94:97], v[94:95] offset:256
	v_and_b32_e32 v67, 0xffff0000, v67
	v_lshlrev_b32_e32 v102, 16, v68
	v_and_b32_e32 v103, 0xffff0000, v68
	v_lshlrev_b32_e32 v68, 16, v69
	v_and_b32_e32 v69, 0xffff0000, v69
	v_pk_fma_f32 v[64:65], v[66:67], s[28:29], v[64:65] op_sel_hi:[1,0,1]
	v_pk_fma_f32 v[62:63], v[100:101], s[28:29], v[62:63] op_sel_hi:[1,0,1]
	v_pk_fma_f32 v[66:67], v[68:69], s[28:29], v[60:61] op_sel_hi:[1,0,1]
	v_pk_fma_f32 v[60:61], v[102:103], s[28:29], v[58:59] op_sel_hi:[1,0,1]
	v_cvt_pk_bf16_f32 v58, v62, v63
	v_cvt_pk_bf16_f32 v59, v64, v65
	v_cvt_pk_bf16_f32 v60, v60, v61
	v_cvt_pk_bf16_f32 v61, v66, v67
	v_lshl_add_u64 v[62:63], s[12:13], 0, v[98:99]
	flat_store_dwordx4 v[62:63], v[58:61]
	v_lshlrev_b32_e32 v64, 16, v72
	v_and_b32_e32 v65, 0xffff0000, v72
	v_lshlrev_b32_e32 v58, 16, v70
	v_and_b32_e32 v59, 0xffff0000, v70
	v_lshlrev_b32_e32 v60, 16, v71
	v_and_b32_e32 v61, 0xffff0000, v71
	v_lshlrev_b32_e32 v66, 16, v73
	v_and_b32_e32 v67, 0xffff0000, v73
	v_pk_fma_f32 v[56:57], v[60:61], s[28:29], v[56:57] op_sel_hi:[1,0,1]
	v_pk_fma_f32 v[54:55], v[58:59], s[28:29], v[54:55] op_sel_hi:[1,0,1]
	v_pk_fma_f32 v[58:59], v[66:67], s[28:29], v[48:49] op_sel_hi:[1,0,1]
	v_pk_fma_f32 v[48:49], v[64:65], s[28:29], v[46:47] op_sel_hi:[1,0,1]
	v_cvt_pk_bf16_f32 v46, v54, v55
	v_cvt_pk_bf16_f32 v47, v56, v57
	v_cvt_pk_bf16_f32 v48, v48, v49
	v_cvt_pk_bf16_f32 v49, v58, v59
	flat_store_dwordx4 v[62:63], v[46:49] offset:256
	s_waitcnt vmcnt(0) lgkmcnt(0)
	v_lshlrev_b32_e32 v54, 16, v76
	v_lshlrev_b32_e32 v46, 16, v74
	v_and_b32_e32 v47, 0xffff0000, v74
	v_lshlrev_b32_e32 v48, 16, v75
	v_and_b32_e32 v49, 0xffff0000, v75
	v_and_b32_e32 v55, 0xffff0000, v76
	v_lshlrev_b32_e32 v56, 16, v77
	v_and_b32_e32 v57, 0xffff0000, v77
	v_pk_fma_f32 v[46:47], v[46:47], s[28:29], v[50:51] op_sel_hi:[1,0,1]
	v_pk_fma_f32 v[48:49], v[48:49], s[28:29], v[52:53] op_sel_hi:[1,0,1]
	v_pk_fma_f32 v[50:51], v[56:57], s[28:29], v[44:45] op_sel_hi:[1,0,1]
	v_pk_fma_f32 v[44:45], v[54:55], s[28:29], v[42:43] op_sel_hi:[1,0,1]
	v_cvt_pk_bf16_f32 v42, v46, v47
	v_add_co_u32_e32 v46, vcc, s49, v62
	v_cvt_pk_bf16_f32 v43, v48, v49
	v_cvt_pk_bf16_f32 v44, v44, v45
	v_cvt_pk_bf16_f32 v45, v50, v51
	v_addc_co_u32_e32 v47, vcc, 0, v63, vcc
	flat_store_dwordx4 v[46:47], v[42:45]
	v_lshlrev_b32_e32 v48, 16, v80
	v_and_b32_e32 v49, 0xffff0000, v80
	v_lshlrev_b32_e32 v42, 16, v78
	v_and_b32_e32 v43, 0xffff0000, v78
	v_lshlrev_b32_e32 v44, 16, v79
	v_and_b32_e32 v45, 0xffff0000, v79
	v_lshlrev_b32_e32 v50, 16, v81
	v_and_b32_e32 v51, 0xffff0000, v81
	v_pk_fma_f32 v[40:41], v[44:45], s[28:29], v[40:41] op_sel_hi:[1,0,1]
	v_pk_fma_f32 v[38:39], v[42:43], s[28:29], v[38:39] op_sel_hi:[1,0,1]
	v_pk_fma_f32 v[42:43], v[50:51], s[28:29], v[32:33] op_sel_hi:[1,0,1]
	v_pk_fma_f32 v[32:33], v[48:49], s[28:29], v[30:31] op_sel_hi:[1,0,1]
	v_cvt_pk_bf16_f32 v30, v38, v39
	v_cvt_pk_bf16_f32 v31, v40, v41
	v_cvt_pk_bf16_f32 v32, v32, v33
	v_cvt_pk_bf16_f32 v33, v42, v43
	flat_store_dwordx4 v[46:47], v[30:33] offset:256
	v_lshlrev_b32_e32 v38, 16, v84
	v_and_b32_e32 v39, 0xffff0000, v84
	v_lshlrev_b32_e32 v30, 16, v82
	v_and_b32_e32 v31, 0xffff0000, v82
	v_lshlrev_b32_e32 v32, 16, v83
	v_and_b32_e32 v33, 0xffff0000, v83
	v_lshlrev_b32_e32 v40, 16, v85
	v_and_b32_e32 v41, 0xffff0000, v85
	v_pk_fma_f32 v[30:31], v[30:31], s[28:29], v[34:35] op_sel_hi:[1,0,1]
	v_pk_fma_f32 v[32:33], v[32:33], s[28:29], v[36:37] op_sel_hi:[1,0,1]
	v_pk_fma_f32 v[34:35], v[40:41], s[28:29], v[28:29] op_sel_hi:[1,0,1]
	v_pk_fma_f32 v[28:29], v[38:39], s[28:29], v[26:27] op_sel_hi:[1,0,1]
	v_cvt_pk_bf16_f32 v26, v30, v31
	v_add_co_u32_e32 v30, vcc, s43, v62
	v_cvt_pk_bf16_f32 v27, v32, v33
	v_cvt_pk_bf16_f32 v28, v28, v29
	v_cvt_pk_bf16_f32 v29, v34, v35
	v_addc_co_u32_e32 v31, vcc, 0, v63, vcc
	flat_store_dwordx4 v[30:31], v[26:29]
	v_lshlrev_b32_e32 v32, 16, v88
	v_and_b32_e32 v33, 0xffff0000, v88
	v_lshlrev_b32_e32 v26, 16, v86
	v_and_b32_e32 v27, 0xffff0000, v86
	v_lshlrev_b32_e32 v28, 16, v87
	v_and_b32_e32 v29, 0xffff0000, v87
	v_lshlrev_b32_e32 v34, 16, v89
	v_and_b32_e32 v35, 0xffff0000, v89
	v_pk_fma_f32 v[24:25], v[28:29], s[28:29], v[24:25] op_sel_hi:[1,0,1]
	v_pk_fma_f32 v[22:23], v[26:27], s[28:29], v[22:23] op_sel_hi:[1,0,1]
	v_pk_fma_f32 v[26:27], v[34:35], s[28:29], v[16:17] op_sel_hi:[1,0,1]
	v_pk_fma_f32 v[16:17], v[32:33], s[28:29], v[14:15] op_sel_hi:[1,0,1]
	v_cvt_pk_bf16_f32 v14, v22, v23
	v_cvt_pk_bf16_f32 v15, v24, v25
	v_cvt_pk_bf16_f32 v16, v16, v17
	v_cvt_pk_bf16_f32 v17, v26, v27
	flat_store_dwordx4 v[30:31], v[14:17] offset:256
	v_lshlrev_b32_e32 v22, 16, v92
	v_and_b32_e32 v23, 0xffff0000, v92
	v_lshlrev_b32_e32 v14, 16, v90
	v_and_b32_e32 v15, 0xffff0000, v90
	v_lshlrev_b32_e32 v16, 16, v91
	v_and_b32_e32 v17, 0xffff0000, v91
	v_lshlrev_b32_e32 v24, 16, v93
	v_and_b32_e32 v25, 0xffff0000, v93
	v_pk_fma_f32 v[14:15], v[14:15], s[28:29], v[18:19] op_sel_hi:[1,0,1]
	v_pk_fma_f32 v[16:17], v[16:17], s[28:29], v[20:21] op_sel_hi:[1,0,1]
	v_pk_fma_f32 v[18:19], v[24:25], s[28:29], v[12:13] op_sel_hi:[1,0,1]
	v_pk_fma_f32 v[12:13], v[22:23], s[28:29], v[10:11] op_sel_hi:[1,0,1]
	v_cvt_pk_bf16_f32 v10, v14, v15
	v_add_co_u32_e32 v14, vcc, s48, v62
	v_cvt_pk_bf16_f32 v11, v16, v17
	v_cvt_pk_bf16_f32 v12, v12, v13
	v_cvt_pk_bf16_f32 v13, v18, v19
	v_addc_co_u32_e32 v15, vcc, 0, v63, vcc
	flat_store_dwordx4 v[14:15], v[10:13]
	v_lshlrev_b32_e32 v16, 16, v96
	v_and_b32_e32 v17, 0xffff0000, v96
	v_lshlrev_b32_e32 v10, 16, v94
	v_and_b32_e32 v11, 0xffff0000, v94
	v_lshlrev_b32_e32 v12, 16, v95
	v_and_b32_e32 v13, 0xffff0000, v95
	v_lshlrev_b32_e32 v18, 16, v97
	v_and_b32_e32 v19, 0xffff0000, v97
	v_pk_fma_f32 v[8:9], v[12:13], s[28:29], v[8:9] op_sel_hi:[1,0,1]
	v_pk_fma_f32 v[6:7], v[10:11], s[28:29], v[6:7] op_sel_hi:[1,0,1]
	v_pk_fma_f32 v[10:11], v[18:19], s[28:29], v[4:5] op_sel_hi:[1,0,1]
	v_pk_fma_f32 v[4:5], v[16:17], s[28:29], v[2:3] op_sel_hi:[1,0,1]
	v_cvt_pk_bf16_f32 v2, v6, v7
	v_cvt_pk_bf16_f32 v3, v8, v9
	v_cvt_pk_bf16_f32 v4, v4, v5
	v_cvt_pk_bf16_f32 v5, v10, v11
	s_and_b64 vcc, exec, s[30:31]
	flat_store_dwordx4 v[14:15], v[2:5] offset:256
	s_cbranch_vccz .LBB0_433
	s_waitcnt vmcnt(0)
	s_cmpk_gt_u32 s4, 0xff
	s_cbranch_scc1 .LBB0_438
	s_barrier

.LBB0_688:
	s_add_u32 s10, s34, 0x100
	s_addc_u32 s11, s35, 0
	s_add_u32 s30, s29, s34
	s_addc_u32 s31, s55, s35
	s_cmpk_eq_i32 s34, 0x300
	s_cselect_b64 vcc, -1, 0
	s_and_b64 s[0:1], vcc, exec
	s_cselect_b32 s1, 0, s10
	s_cselect_b32 s0, 0, s11
	s_cselect_b32 s30, s27, s30
	s_cselect_b32 s31, s25, s31
	s_add_u32 s36, s14, s1
	s_addc_u32 s37, s15, s0
	s_add_i32 s1, 0, 0x10000
	v_add_u32_e32 v14, s1, v197
	ds_read_b128 v[2:5], v14
	ds_read_b128 v[6:9], v14 offset:1024
	ds_read_b128 v[10:13], v14 offset:2048
	ds_read_b128 v[14:17], v14 offset:3072
	v_cndmask_b32_e32 v162, v168, v171, vcc
	v_cndmask_b32_e32 v184, v170, v198, vcc
	v_cndmask_b32_e32 v175, v172, v199, vcc
	v_cndmask_b32_e32 v173, v174, v200, vcc
	v_lshl_add_u64 v[18:19], v[178:179], 0, s[34:35]
	s_add_i32 m0, s45, 0xc000
	ds_read_b128 v[202:205], v169
	ds_read_b128 v[206:209], v169 offset:1024
	ds_read_b128 v[210:213], v169 offset:2048
	ds_read_b128 v[214:217], v169 offset:3072
	ds_read_b128 v[218:221], v169 offset:4096
	ds_read_b128 v[222:225], v169 offset:5120
	ds_read_b128 v[226:229], v169 offset:6144
	ds_read_b128 v[230:233], v169 offset:7168
	global_load_lds_dwordx4 v[18:19], off
	v_lshl_add_u64 v[18:19], v[176:177], 0, s[34:35]
	s_add_i32 m0, s45, 0xe000
	s_nop 0
	global_load_lds_dwordx4 v[18:19], off
	s_waitcnt lgkmcnt(8)
	s_waitcnt vmcnt(10)
	s_barrier
	s_waitcnt lgkmcnt(0)
	s_waitcnt lgkmcnt(0)
	v_mfma_scale_f32_16x16x128_f8f6f4 v[158:161], v[2:9], v[202:209], v[158:161], v188, v188 op_sel_hi:[0,0,0]
	v_mfma_scale_f32_16x16x128_f8f6f4 v[150:153], v[10:17], v[202:209], v[150:153], v188, v188 op_sel_hi:[0,0,0]
	v_mfma_scale_f32_16x16x128_f8f6f4 v[142:145], v[2:9], v[210:217], v[142:145], v188, v188 op_sel_hi:[0,0,0]
	v_mfma_scale_f32_16x16x128_f8f6f4 v[134:137], v[10:17], v[210:217], v[134:137], v188, v188 op_sel_hi:[0,0,0]
	v_mfma_scale_f32_16x16x128_f8f6f4 v[126:129], v[2:9], v[218:225], v[126:129], v188, v188 op_sel_hi:[0,0,0]
	v_mfma_scale_f32_16x16x128_f8f6f4 v[118:121], v[10:17], v[218:225], v[118:121], v188, v188 op_sel_hi:[0,0,0]
	v_mfma_scale_f32_16x16x128_f8f6f4 v[110:113], v[2:9], v[226:233], v[110:113], v188, v188 op_sel_hi:[0,0,0]
	v_mfma_scale_f32_16x16x128_f8f6f4 v[102:105], v[10:17], v[226:233], v[102:105], v188, v188 op_sel_hi:[0,0,0]
	s_barrier
	s_add_i32 s0, 0, 0x14000
	s_add_i32 s1, s1, s43
	v_add_u32_e32 v30, s0, v197
	v_lshl_add_u64 v[180:181], s[30:31], 0, v[164:165]
	s_mov_b32 m0, s1
	ds_read_b128 v[18:21], v30
	ds_read_b128 v[22:25], v30 offset:1024
	ds_read_b128 v[26:29], v30 offset:2048
	ds_read_b128 v[30:33], v30 offset:3072
	global_load_lds_dwordx4 v[180:181], off
	v_lshl_add_u64 v[182:183], s[30:31], 0, v[166:167]
	s_add_i32 m0, s1, 0x2000
	s_nop 0
	global_load_lds_dwordx4 v[182:183], off
	s_waitcnt vmcnt(10)
	s_barrier
	s_waitcnt lgkmcnt(0)
	s_waitcnt lgkmcnt(0)
	v_mfma_scale_f32_16x16x128_f8f6f4 v[154:157], v[18:25], v[202:209], v[154:157], v188, v188 op_sel_hi:[0,0,0]
	v_mfma_scale_f32_16x16x128_f8f6f4 v[146:149], v[26:33], v[202:209], v[146:149], v188, v188 op_sel_hi:[0,0,0]
	v_mfma_scale_f32_16x16x128_f8f6f4 v[138:141], v[18:25], v[210:217], v[138:141], v188, v188 op_sel_hi:[0,0,0]
	v_mfma_scale_f32_16x16x128_f8f6f4 v[130:133], v[26:33], v[210:217], v[130:133], v188, v188 op_sel_hi:[0,0,0]
	v_mfma_scale_f32_16x16x128_f8f6f4 v[122:125], v[18:25], v[218:225], v[122:125], v188, v188 op_sel_hi:[0,0,0]
	v_mfma_scale_f32_16x16x128_f8f6f4 v[114:117], v[26:33], v[218:225], v[114:117], v188, v188 op_sel_hi:[0,0,0]
	v_mfma_scale_f32_16x16x128_f8f6f4 v[106:109], v[18:25], v[226:233], v[106:109], v188, v188 op_sel_hi:[0,0,0]
	v_mfma_scale_f32_16x16x128_f8f6f4 v[98:101], v[26:33], v[226:233], v[98:101], v188, v188 op_sel_hi:[0,0,0]
	s_mov_b32 m0, s45
	s_barrier
	ds_read_b128 v[202:205], v169 offset:16384
	ds_read_b128 v[206:209], v169 offset:17408
	ds_read_b128 v[210:213], v169 offset:18432
	ds_read_b128 v[214:217], v169 offset:19456
	ds_read_b128 v[218:221], v169 offset:20480
	ds_read_b128 v[222:225], v169 offset:21504
	ds_read_b128 v[226:229], v169 offset:22528
	ds_read_b128 v[230:233], v169 offset:23552
	global_load_lds_dwordx4 v162, s[36:37]
	s_mov_b32 m0, s46
	v_mov_b32_e32 v185, v163
	global_load_lds_dwordx4 v184, s[36:37]
	s_waitcnt vmcnt(10)
	s_barrier
	s_waitcnt lgkmcnt(0)
	v_lshl_add_u64 v[186:187], s[36:37], 0, v[162:163]
	v_lshl_add_u64 v[184:185], s[36:37], 0, v[184:185]
	s_waitcnt lgkmcnt(0)
	v_mfma_scale_f32_16x16x128_f8f6f4 v[94:97], v[2:9], v[202:209], v[94:97], v188, v188 op_sel_hi:[0,0,0]
	v_mfma_scale_f32_16x16x128_f8f6f4 v[86:89], v[10:17], v[202:209], v[86:89], v188, v188 op_sel_hi:[0,0,0]
	v_mfma_scale_f32_16x16x128_f8f6f4 v[78:81], v[2:9], v[210:217], v[78:81], v188, v188 op_sel_hi:[0,0,0]
	v_mfma_scale_f32_16x16x128_f8f6f4 v[70:73], v[10:17], v[210:217], v[70:73], v188, v188 op_sel_hi:[0,0,0]
	v_mfma_scale_f32_16x16x128_f8f6f4 v[62:65], v[2:9], v[218:225], v[62:65], v188, v188 op_sel_hi:[0,0,0]
	v_mfma_scale_f32_16x16x128_f8f6f4 v[54:57], v[10:17], v[218:225], v[54:57], v188, v188 op_sel_hi:[0,0,0]
	v_mfma_scale_f32_16x16x128_f8f6f4 v[46:49], v[2:9], v[226:233], v[46:49], v188, v188 op_sel_hi:[0,0,0]
	v_mfma_scale_f32_16x16x128_f8f6f4 v[38:41], v[10:17], v[226:233], v[38:41], v188, v188 op_sel_hi:[0,0,0]
	s_barrier
	s_add_u32 s34, s30, 0x20000
	s_addc_u32 s35, s31, 0
	s_add_i32 s0, s0, s43
	v_lshl_add_u64 v[2:3], s[34:35], 0, v[164:165]
	s_mov_b32 m0, s0
	s_nop 0
	global_load_lds_dwordx4 v[2:3], off
	v_lshl_add_u64 v[2:3], s[34:35], 0, v[166:167]
	s_add_i32 m0, s0, 0x2000
	s_nop 0
	global_load_lds_dwordx4 v[2:3], off
	s_waitcnt vmcnt(10)
	s_barrier
	v_mfma_scale_f32_16x16x128_f8f6f4 v[90:93], v[18:25], v[202:209], v[90:93], v188, v188 op_sel_hi:[0,0,0]
	v_mfma_scale_f32_16x16x128_f8f6f4 v[82:85], v[26:33], v[202:209], v[82:85], v188, v188 op_sel_hi:[0,0,0]
	v_mfma_scale_f32_16x16x128_f8f6f4 v[74:77], v[18:25], v[210:217], v[74:77], v188, v188 op_sel_hi:[0,0,0]
	v_mfma_scale_f32_16x16x128_f8f6f4 v[66:69], v[26:33], v[210:217], v[66:69], v188, v188 op_sel_hi:[0,0,0]
	v_mfma_scale_f32_16x16x128_f8f6f4 v[58:61], v[18:25], v[218:225], v[58:61], v188, v188 op_sel_hi:[0,0,0]
	v_mfma_scale_f32_16x16x128_f8f6f4 v[50:53], v[26:33], v[218:225], v[50:53], v188, v188 op_sel_hi:[0,0,0]
	v_mfma_scale_f32_16x16x128_f8f6f4 v[42:45], v[18:25], v[226:233], v[42:45], v188, v188 op_sel_hi:[0,0,0]
	v_mfma_scale_f32_16x16x128_f8f6f4 v[34:37], v[26:33], v[226:233], v[34:37], v188, v188 op_sel_hi:[0,0,0]
	s_add_i32 s0, 0, 0x18000
	v_add_u32_e32 v14, s0, v197
	s_barrier
	ds_read_b128 v[2:5], v14
	ds_read_b128 v[6:9], v14 offset:1024
	ds_read_b128 v[10:13], v14 offset:2048
	ds_read_b128 v[14:17], v14 offset:3072
	s_mov_b32 m0, s47
	ds_read_b128 v[18:21], v169 offset:32768
	ds_read_b128 v[22:25], v169 offset:33792
	ds_read_b128 v[26:29], v169 offset:34816
	ds_read_b128 v[30:33], v169 offset:35840
	ds_read_b128 v[202:205], v169 offset:36864
	ds_read_b128 v[206:209], v169 offset:37888
	ds_read_b128 v[210:213], v169 offset:38912
	ds_read_b128 v[214:217], v169 offset:39936
	global_load_lds_dwordx4 v175, s[36:37]
	s_mov_b32 m0, s48
	s_nop 0
	global_load_lds_dwordx4 v173, s[36:37]
	s_waitcnt lgkmcnt(8)
	s_waitcnt vmcnt(10)
	s_barrier
	s_waitcnt lgkmcnt(0)
	s_waitcnt lgkmcnt(0)
	v_mfma_scale_f32_16x16x128_f8f6f4 v[158:161], v[2:9], v[18:25], v[158:161], v188, v188 op_sel_hi:[0,0,0]
	v_mfma_scale_f32_16x16x128_f8f6f4 v[150:153], v[10:17], v[18:25], v[150:153], v188, v188 op_sel_hi:[0,0,0]
	v_mfma_scale_f32_16x16x128_f8f6f4 v[142:145], v[2:9], v[26:33], v[142:145], v188, v188 op_sel_hi:[0,0,0]
	v_mfma_scale_f32_16x16x128_f8f6f4 v[134:137], v[10:17], v[26:33], v[134:137], v188, v188 op_sel_hi:[0,0,0]
	v_mfma_scale_f32_16x16x128_f8f6f4 v[126:129], v[2:9], v[202:209], v[126:129], v188, v188 op_sel_hi:[0,0,0]
	v_mfma_scale_f32_16x16x128_f8f6f4 v[118:121], v[10:17], v[202:209], v[118:121], v188, v188 op_sel_hi:[0,0,0]
	v_mfma_scale_f32_16x16x128_f8f6f4 v[110:113], v[2:9], v[210:217], v[110:113], v188, v188 op_sel_hi:[0,0,0]
	v_mfma_scale_f32_16x16x128_f8f6f4 v[102:105], v[10:17], v[210:217], v[102:105], v188, v188 op_sel_hi:[0,0,0]
	s_barrier
	s_add_i32 s34, 0, 0x1c000
	s_add_i32 s0, s0, s43
	v_add_u32_e32 v162, s34, v197
	v_lshl_add_u64 v[180:181], v[180:181], 0, s[20:21]
	s_mov_b32 m0, s0
	ds_read_b128 v[218:221], v162
	ds_read_b128 v[222:225], v162 offset:1024
	ds_read_b128 v[226:229], v162 offset:2048
	ds_read_b128 v[230:233], v162 offset:3072
	global_load_lds_dwordx4 v[180:181], off
	v_lshl_add_u64 v[180:181], v[182:183], 0, s[20:21]
	s_add_i32 m0, s0, 0x2000
	s_nop 0
	global_load_lds_dwordx4 v[180:181], off
	s_waitcnt vmcnt(10)
	s_barrier
	s_waitcnt lgkmcnt(0)
	s_waitcnt lgkmcnt(0)
	v_mfma_scale_f32_16x16x128_f8f6f4 v[154:157], v[218:225], v[18:25], v[154:157], v188, v188 op_sel_hi:[0,0,0]
	v_mfma_scale_f32_16x16x128_f8f6f4 v[146:149], v[226:233], v[18:25], v[146:149], v188, v188 op_sel_hi:[0,0,0]
	v_mfma_scale_f32_16x16x128_f8f6f4 v[138:141], v[218:225], v[26:33], v[138:141], v188, v188 op_sel_hi:[0,0,0]
	v_mfma_scale_f32_16x16x128_f8f6f4 v[130:133], v[226:233], v[26:33], v[130:133], v188, v188 op_sel_hi:[0,0,0]
	v_mfma_scale_f32_16x16x128_f8f6f4 v[122:125], v[218:225], v[202:209], v[122:125], v188, v188 op_sel_hi:[0,0,0]
	v_mfma_scale_f32_16x16x128_f8f6f4 v[114:117], v[226:233], v[202:209], v[114:117], v188, v188 op_sel_hi:[0,0,0]
	v_mfma_scale_f32_16x16x128_f8f6f4 v[106:109], v[218:225], v[210:217], v[106:109], v188, v188 op_sel_hi:[0,0,0]
	v_mfma_scale_f32_16x16x128_f8f6f4 v[98:101], v[226:233], v[210:217], v[98:101], v188, v188 op_sel_hi:[0,0,0]
	s_mov_b32 m0, s51
	v_lshl_add_u64 v[180:181], v[186:187], 0, s[20:21]
	s_barrier
	ds_read_b128 v[18:21], v169 offset:49152
	ds_read_b128 v[22:25], v169 offset:50176
	ds_read_b128 v[26:29], v169 offset:51200
	ds_read_b128 v[30:33], v169 offset:52224
	ds_read_b128 v[202:205], v169 offset:53248
	ds_read_b128 v[206:209], v169 offset:54272
	ds_read_b128 v[210:213], v169 offset:55296
	ds_read_b128 v[214:217], v169 offset:56320
	global_load_lds_dwordx4 v[180:181], off
	v_lshl_add_u64 v[180:181], v[184:185], 0, s[20:21]
	s_mov_b32 m0, s52
	s_nop 0
	global_load_lds_dwordx4 v[180:181], off
	s_waitcnt vmcnt(10)
	s_barrier
	s_waitcnt lgkmcnt(0)
	s_waitcnt lgkmcnt(0)
	v_mfma_scale_f32_16x16x128_f8f6f4 v[94:97], v[2:9], v[18:25], v[94:97], v188, v188 op_sel_hi:[0,0,0]
	v_mfma_scale_f32_16x16x128_f8f6f4 v[86:89], v[10:17], v[18:25], v[86:89], v188, v188 op_sel_hi:[0,0,0]
	v_mfma_scale_f32_16x16x128_f8f6f4 v[78:81], v[2:9], v[26:33], v[78:81], v188, v188 op_sel_hi:[0,0,0]
	v_mfma_scale_f32_16x16x128_f8f6f4 v[70:73], v[10:17], v[26:33], v[70:73], v188, v188 op_sel_hi:[0,0,0]
	v_mfma_scale_f32_16x16x128_f8f6f4 v[62:65], v[2:9], v[202:209], v[62:65], v188, v188 op_sel_hi:[0,0,0]
	v_mfma_scale_f32_16x16x128_f8f6f4 v[54:57], v[10:17], v[202:209], v[54:57], v188, v188 op_sel_hi:[0,0,0]
	v_mfma_scale_f32_16x16x128_f8f6f4 v[46:49], v[2:9], v[210:217], v[46:49], v188, v188 op_sel_hi:[0,0,0]
	v_mfma_scale_f32_16x16x128_f8f6f4 v[38:41], v[10:17], v[210:217], v[38:41], v188, v188 op_sel_hi:[0,0,0]
	s_barrier
	s_add_u32 s0, s30, 0x20080
	s_addc_u32 s1, s31, 0
	s_add_i32 s30, s34, s43
	v_lshl_add_u64 v[2:3], s[0:1], 0, v[164:165]
	s_mov_b32 m0, s30
	s_nop 0
	global_load_lds_dwordx4 v[2:3], off
	v_lshl_add_u64 v[2:3], s[0:1], 0, v[166:167]
	s_add_i32 m0, s30, 0x2000
	s_nop 0
	global_load_lds_dwordx4 v[2:3], off
	s_waitcnt vmcnt(10)
	s_barrier
	v_mfma_scale_f32_16x16x128_f8f6f4 v[90:93], v[218:225], v[18:25], v[90:93], v188, v188 op_sel_hi:[0,0,0]
	v_mfma_scale_f32_16x16x128_f8f6f4 v[82:85], v[226:233], v[18:25], v[82:85], v188, v188 op_sel_hi:[0,0,0]
	v_mfma_scale_f32_16x16x128_f8f6f4 v[74:77], v[218:225], v[26:33], v[74:77], v188, v188 op_sel_hi:[0,0,0]
	v_mfma_scale_f32_16x16x128_f8f6f4 v[66:69], v[226:233], v[26:33], v[66:69], v188, v188 op_sel_hi:[0,0,0]
	v_mfma_scale_f32_16x16x128_f8f6f4 v[58:61], v[218:225], v[202:209], v[58:61], v188, v188 op_sel_hi:[0,0,0]
	v_mfma_scale_f32_16x16x128_f8f6f4 v[50:53], v[226:233], v[202:209], v[50:53], v188, v188 op_sel_hi:[0,0,0]
	v_mfma_scale_f32_16x16x128_f8f6f4 v[42:45], v[218:225], v[210:217], v[42:45], v188, v188 op_sel_hi:[0,0,0]
	v_mfma_scale_f32_16x16x128_f8f6f4 v[34:37], v[226:233], v[210:217], v[34:37], v188, v188 op_sel_hi:[0,0,0]
	s_add_i32 s56, s56, 2
	s_cmp_gt_u32 s56, 5
	s_mov_b64 s[34:35], s[10:11]
	s_barrier
	s_cbranch_scc0 .LBB0_688
	v_mul_f32_e32 v5, 0x3c800000, v158
	v_mul_f32_e32 v6, 0xbfb8aa3b, v5
	v_exp_f32_e32 v6, v6
	s_ashr_i32 s29, s28, 31
	s_ashr_i32 s27, s26, 31
	s_lshl_b64 s[10:11], s[28:29], 18
	v_add_f32_e32 v6, 1.0, v6
	v_rcp_f32_e32 v6, v6
	s_lshl_b64 s[26:27], s[26:27], 15
	v_mov_b32_e32 v3, v195
	s_add_u32 s0, s6, s10
	v_mul_f32_e32 v5, v5, v6
	v_mul_f32_e32 v6, 0x3c800000, v159
	v_mul_f32_e32 v7, 0xbfb8aa3b, v6
	v_exp_f32_e32 v7, v7
	v_mul_f32_e32 v5, v5, v154
	v_mul_f32_e32 v5, 0x3e000000, v5
	v_med3_f32 v5, v5, s40, v190
	v_add_f32_e32 v7, 1.0, v7
	v_rcp_f32_e32 v7, v7
	s_nop 15
	s_nop 15
	v_mov_b32_e32 v2, v196
	v_mul_f32_e32 v6, v6, v7
	v_mul_f32_e32 v7, 0x3c800000, v160
	v_mul_f32_e32 v8, 0xbfb8aa3b, v7
	v_exp_f32_e32 v8, v8
	v_mul_f32_e32 v6, v6, v155
	v_mul_f32_e32 v6, 0x3e000000, v6
	v_add_u32_e32 v4, s49, v3
	v_add_f32_e32 v8, 1.0, v8
	v_rcp_f32_e32 v8, v8
	s_addc_u32 s1, s7, s11
	s_add_u32 s10, s0, s26
	v_mul_f32_e32 v7, v7, v8
	v_mul_f32_e32 v8, 0x3c800000, v161
	v_mul_f32_e32 v9, 0xbfb8aa3b, v8
	v_exp_f32_e32 v9, v9
	v_mul_f32_e32 v7, v7, v156
	v_mul_f32_e32 v7, 0x3e000000, v7
	v_lshl_add_u32 v2, v2, 3, s50
	v_add_f32_e32 v9, 1.0, v9
	v_rcp_f32_e32 v9, v9
	s_addc_u32 s11, s1, s27
	v_ashrrev_i32_e32 v3, 31, v2
	s_and_b64 vcc, exec, s[8:9]
	v_mul_f32_e32 v8, v8, v9
	v_mul_f32_e32 v9, 0x3c800000, v150
	v_mul_f32_e32 v10, 0xbfb8aa3b, v9
	v_exp_f32_e32 v10, v10
	v_mul_f32_e32 v8, v8, v157
	v_mul_f32_e32 v8, 0x3e000000, v8
	v_mov_b32_e32 v174, v200
	v_add_f32_e32 v10, 1.0, v10
	v_rcp_f32_e32 v10, v10
	v_mov_b32_e32 v172, v199
	v_mov_b32_e32 v170, v198
	v_mov_b32_e32 v168, v171
	v_mul_f32_e32 v9, v9, v10
	v_mul_f32_e32 v10, 0x3c800000, v151
	v_mul_f32_e32 v11, 0xbfb8aa3b, v10
	v_exp_f32_e32 v11, v11
	v_mul_f32_e32 v9, v9, v146
	v_mul_f32_e32 v9, 0x3e000000, v9
	s_mov_b32 s26, s24
	v_add_f32_e32 v11, 1.0, v11
	v_rcp_f32_e32 v11, v11
	s_mov_b32 s28, s54
	s_mov_b64 s[30:31], s[12:13]
	v_mul_f32_e32 v10, v10, v11
	v_mul_f32_e32 v11, 0x3c800000, v152
	v_mul_f32_e32 v12, 0xbfb8aa3b, v11
	v_exp_f32_e32 v12, v12
	v_mul_f32_e32 v10, v10, v147
	v_mul_f32_e32 v10, 0x3e000000, v10
	v_add_f32_e32 v12, 1.0, v12
	v_rcp_f32_e32 v12, v12
	s_nop 0
	v_mul_f32_e32 v11, v11, v12
	v_mul_f32_e32 v12, 0x3c800000, v153
	v_mul_f32_e32 v13, 0xbfb8aa3b, v12
	v_exp_f32_e32 v13, v13
	v_mul_f32_e32 v11, v11, v148
	v_mul_f32_e32 v11, 0x3e000000, v11
	v_add_f32_e32 v13, 1.0, v13
	v_rcp_f32_e32 v13, v13
	s_nop 0
	v_mul_f32_e32 v12, v12, v13
	v_med3_f32 v13, v6, s40, v190
	v_mov_b32_e32 v6, v163
	v_cvt_pk_fp8_f32 v6, v5, v13
	v_med3_f32 v5, v7, s40, v190
	v_med3_f32 v7, v8, s40, v190
	v_med3_f32 v8, v10, s40, v190
	v_cvt_pk_fp8_f32 v6, v5, v7 op_sel:[0,0,1]
	v_med3_f32 v5, v9, s40, v190
	v_mov_b32_e32 v7, v163
	v_cvt_pk_fp8_f32 v7, v5, v8
	v_mul_f32_e32 v12, v12, v149
	v_mul_f32_e32 v12, 0x3e000000, v12
	v_med3_f32 v5, v11, s40, v190
	v_med3_f32 v8, v12, s40, v190
	v_cvt_pk_fp8_f32 v7, v5, v8 op_sel:[0,0,1]
	v_ashrrev_i32_e32 v5, 31, v4
	v_lshlrev_b64 v[8:9], 7, v[4:5]
	v_lshl_add_u64 v[8:9], s[10:11], 0, v[8:9]
	v_lshl_add_u64 v[8:9], v[8:9], 0, v[2:3]
	v_mul_f32_e32 v5, 0x3c800000, v142
	flat_store_dwordx2 v[8:9], v[6:7]
	v_mul_f32_e32 v6, 0xbfb8aa3b, v5
	v_exp_f32_e32 v6, v6
	s_nop 0
	v_add_f32_e32 v6, 1.0, v6
	v_rcp_f32_e32 v6, v6
	s_nop 0
	v_mul_f32_e32 v5, v5, v6
	v_mul_f32_e32 v6, 0x3c800000, v143
	v_mul_f32_e32 v7, 0xbfb8aa3b, v6
	v_exp_f32_e32 v7, v7
	v_mul_f32_e32 v5, v5, v138
	v_mul_f32_e32 v5, 0x3e000000, v5
	v_med3_f32 v5, v5, s40, v190
	v_add_f32_e32 v7, 1.0, v7
	v_rcp_f32_e32 v7, v7
	s_nop 0
	v_mul_f32_e32 v6, v6, v7
	v_mul_f32_e32 v6, v6, v139
	v_mul_f32_e32 v7, 0x3e000000, v6
	v_mul_f32_e32 v6, 0x3c800000, v144
	v_mul_f32_e32 v8, 0xbfb8aa3b, v6
	v_exp_f32_e32 v8, v8
	v_med3_f32 v7, v7, s40, v190
	v_add_f32_e32 v8, 1.0, v8
	v_rcp_f32_e32 v8, v8
	s_nop 0
	v_mul_f32_e32 v6, v6, v8
	v_mul_f32_e32 v6, v6, v140
	v_mul_f32_e32 v9, 0x3e000000, v6
	v_mul_f32_e32 v6, 0x3c800000, v145
	v_mul_f32_e32 v8, 0xbfb8aa3b, v6
	v_exp_f32_e32 v8, v8
	s_nop 0
	v_add_f32_e32 v8, 1.0, v8
	v_rcp_f32_e32 v8, v8
	s_nop 0
	v_mul_f32_e32 v6, v6, v8
	v_mul_f32_e32 v6, v6, v141
	v_mul_f32_e32 v10, 0x3e000000, v6
	v_mul_f32_e32 v6, 0x3c800000, v134
	v_mul_f32_e32 v8, 0xbfb8aa3b, v6
	v_exp_f32_e32 v8, v8
	s_nop 0
	v_add_f32_e32 v8, 1.0, v8
	v_rcp_f32_e32 v8, v8
	s_nop 0
	v_mul_f32_e32 v6, v6, v8
	v_mul_f32_e32 v6, v6, v130
	v_mul_f32_e32 v11, 0x3e000000, v6
	v_mul_f32_e32 v6, 0x3c800000, v135
	v_mul_f32_e32 v8, 0xbfb8aa3b, v6
	v_exp_f32_e32 v8, v8
	s_nop 0
	v_add_f32_e32 v8, 1.0, v8
	v_rcp_f32_e32 v8, v8
	s_nop 0
	v_mul_f32_e32 v6, v6, v8
	v_mul_f32_e32 v6, v6, v131
	v_mul_f32_e32 v12, 0x3e000000, v6
	v_mul_f32_e32 v6, 0x3c800000, v136
	v_mul_f32_e32 v8, 0xbfb8aa3b, v6
	v_exp_f32_e32 v8, v8
	s_nop 0
	v_add_f32_e32 v8, 1.0, v8
	v_rcp_f32_e32 v8, v8
	s_nop 0
	v_mul_f32_e32 v6, v6, v8
	v_mul_f32_e32 v6, v6, v132
	v_mul_f32_e32 v13, 0x3e000000, v6
	v_mul_f32_e32 v6, 0x3c800000, v137
	v_mul_f32_e32 v8, 0xbfb8aa3b, v6
	v_exp_f32_e32 v8, v8
	s_nop 0
	v_add_f32_e32 v8, 1.0, v8
	v_rcp_f32_e32 v8, v8
	s_nop 0
	v_mul_f32_e32 v6, v6, v8
	v_mov_b32_e32 v8, v163
	v_cvt_pk_fp8_f32 v8, v5, v7
	v_med3_f32 v5, v9, s40, v190
	v_med3_f32 v7, v10, s40, v190
	v_mov_b32_e32 v9, v163
	v_cvt_pk_fp8_f32 v8, v5, v7 op_sel:[0,0,1]
	v_med3_f32 v5, v11, s40, v190
	v_med3_f32 v7, v12, s40, v190
	v_cvt_pk_fp8_f32 v9, v5, v7
	v_mul_f32_e32 v6, v6, v133
	v_mul_f32_e32 v14, 0x3e000000, v6
	v_add_u32_e32 v6, 16, v4
	v_med3_f32 v5, v13, s40, v190
	v_med3_f32 v7, v14, s40, v190
	v_cvt_pk_fp8_f32 v9, v5, v7 op_sel:[0,0,1]
	v_ashrrev_i32_e32 v7, 31, v6
	v_lshlrev_b64 v[6:7], 7, v[6:7]
	v_lshl_add_u64 v[6:7], s[10:11], 0, v[6:7]
	v_lshl_add_u64 v[6:7], v[6:7], 0, v[2:3]
	v_mul_f32_e32 v5, 0x3c800000, v126
	flat_store_dwordx2 v[6:7], v[8:9]
	v_mul_f32_e32 v6, 0xbfb8aa3b, v5
	v_exp_f32_e32 v6, v6
	s_nop 0
	v_add_f32_e32 v6, 1.0, v6
	v_rcp_f32_e32 v6, v6
	s_nop 0
	v_mul_f32_e32 v5, v5, v6
	v_mul_f32_e32 v6, 0x3c800000, v127
	v_mul_f32_e32 v7, 0xbfb8aa3b, v6
	v_exp_f32_e32 v7, v7
	v_mul_f32_e32 v5, v5, v122
	v_mul_f32_e32 v5, 0x3e000000, v5
	v_med3_f32 v5, v5, s40, v190
	v_add_f32_e32 v7, 1.0, v7
	v_rcp_f32_e32 v7, v7
	s_nop 0
	v_mul_f32_e32 v6, v6, v7
	v_mul_f32_e32 v6, v6, v123
	v_mul_f32_e32 v7, 0x3e000000, v6
	v_mul_f32_e32 v6, 0x3c800000, v128
	v_mul_f32_e32 v8, 0xbfb8aa3b, v6
	v_exp_f32_e32 v8, v8
	v_med3_f32 v7, v7, s40, v190
	v_add_f32_e32 v8, 1.0, v8
	v_rcp_f32_e32 v8, v8
	s_nop 0
	v_mul_f32_e32 v6, v6, v8
	v_mul_f32_e32 v6, v6, v124
	v_mul_f32_e32 v9, 0x3e000000, v6
	v_mul_f32_e32 v6, 0x3c800000, v129
	v_mul_f32_e32 v8, 0xbfb8aa3b, v6
	v_exp_f32_e32 v8, v8
	s_nop 0
	v_add_f32_e32 v8, 1.0, v8
	v_rcp_f32_e32 v8, v8
	s_nop 0
	v_mul_f32_e32 v6, v6, v8
	v_mul_f32_e32 v6, v6, v125
	v_mul_f32_e32 v10, 0x3e000000, v6
	v_mul_f32_e32 v6, 0x3c800000, v118
	v_mul_f32_e32 v8, 0xbfb8aa3b, v6
	v_exp_f32_e32 v8, v8
	s_nop 0
	v_add_f32_e32 v8, 1.0, v8
	v_rcp_f32_e32 v8, v8
	s_nop 0
	v_mul_f32_e32 v6, v6, v8
	v_mul_f32_e32 v6, v6, v114
	v_mul_f32_e32 v11, 0x3e000000, v6
	v_mul_f32_e32 v6, 0x3c800000, v119
	v_mul_f32_e32 v8, 0xbfb8aa3b, v6
	v_exp_f32_e32 v8, v8
	s_nop 0
	v_add_f32_e32 v8, 1.0, v8
	v_rcp_f32_e32 v8, v8
	s_nop 0
	v_mul_f32_e32 v6, v6, v8
	v_mul_f32_e32 v6, v6, v115
	v_mul_f32_e32 v12, 0x3e000000, v6
	v_mul_f32_e32 v6, 0x3c800000, v120
	v_mul_f32_e32 v8, 0xbfb8aa3b, v6
	v_exp_f32_e32 v8, v8
	s_nop 0
	v_add_f32_e32 v8, 1.0, v8
	v_rcp_f32_e32 v8, v8
	s_nop 0
	v_mul_f32_e32 v6, v6, v8
	v_mul_f32_e32 v6, v6, v116
	v_mul_f32_e32 v13, 0x3e000000, v6
	v_mul_f32_e32 v6, 0x3c800000, v121
	v_mul_f32_e32 v8, 0xbfb8aa3b, v6
	v_exp_f32_e32 v8, v8
	s_nop 0
	v_add_f32_e32 v8, 1.0, v8
	v_rcp_f32_e32 v8, v8
	s_nop 0
	v_mul_f32_e32 v6, v6, v8
	v_mov_b32_e32 v8, v163
	v_cvt_pk_fp8_f32 v8, v5, v7
	v_med3_f32 v5, v9, s40, v190
	v_med3_f32 v7, v10, s40, v190
	v_mov_b32_e32 v9, v163
	v_cvt_pk_fp8_f32 v8, v5, v7 op_sel:[0,0,1]
	v_med3_f32 v5, v11, s40, v190
	v_med3_f32 v7, v12, s40, v190
	v_cvt_pk_fp8_f32 v9, v5, v7
	v_mul_f32_e32 v6, v6, v117
	v_mul_f32_e32 v14, 0x3e000000, v6
	v_add_u32_e32 v6, 32, v4
	v_med3_f32 v5, v13, s40, v190
	v_med3_f32 v7, v14, s40, v190
	v_cvt_pk_fp8_f32 v9, v5, v7 op_sel:[0,0,1]
	v_ashrrev_i32_e32 v7, 31, v6
	v_lshlrev_b64 v[6:7], 7, v[6:7]
	v_lshl_add_u64 v[6:7], s[10:11], 0, v[6:7]
	v_lshl_add_u64 v[6:7], v[6:7], 0, v[2:3]
	v_mul_f32_e32 v5, 0x3c800000, v110
	flat_store_dwordx2 v[6:7], v[8:9]
	v_mul_f32_e32 v6, 0xbfb8aa3b, v5
	v_exp_f32_e32 v6, v6
	s_nop 0
	v_add_f32_e32 v6, 1.0, v6
	v_rcp_f32_e32 v6, v6
	s_nop 0
	v_mul_f32_e32 v5, v5, v6
	v_mul_f32_e32 v6, 0x3c800000, v111
	v_mul_f32_e32 v7, 0xbfb8aa3b, v6
	v_exp_f32_e32 v7, v7
	v_mul_f32_e32 v5, v5, v106
	v_mul_f32_e32 v5, 0x3e000000, v5
	v_med3_f32 v5, v5, s40, v190
	v_add_f32_e32 v7, 1.0, v7
	v_rcp_f32_e32 v7, v7
	s_nop 0
	v_mul_f32_e32 v6, v6, v7
	v_mul_f32_e32 v6, v6, v107
	v_mul_f32_e32 v7, 0x3e000000, v6
	v_mul_f32_e32 v6, 0x3c800000, v112
	v_mul_f32_e32 v8, 0xbfb8aa3b, v6
	v_exp_f32_e32 v8, v8
	v_med3_f32 v7, v7, s40, v190
	v_add_f32_e32 v8, 1.0, v8
	v_rcp_f32_e32 v8, v8
	s_nop 0
	v_mul_f32_e32 v6, v6, v8
	v_mul_f32_e32 v6, v6, v108
	v_mul_f32_e32 v9, 0x3e000000, v6
	v_mul_f32_e32 v6, 0x3c800000, v113
	v_mul_f32_e32 v8, 0xbfb8aa3b, v6
	v_exp_f32_e32 v8, v8
	s_nop 0
	v_add_f32_e32 v8, 1.0, v8
	v_rcp_f32_e32 v8, v8
	s_nop 0
	v_mul_f32_e32 v6, v6, v8
	v_mul_f32_e32 v6, v6, v109
	v_mul_f32_e32 v10, 0x3e000000, v6
	v_mul_f32_e32 v6, 0x3c800000, v102
	v_mul_f32_e32 v8, 0xbfb8aa3b, v6
	v_exp_f32_e32 v8, v8
	s_nop 0
	v_add_f32_e32 v8, 1.0, v8
	v_rcp_f32_e32 v8, v8
	s_nop 0
	v_mul_f32_e32 v6, v6, v8
	v_mul_f32_e32 v6, v6, v98
	v_mul_f32_e32 v11, 0x3e000000, v6
	v_mul_f32_e32 v6, 0x3c800000, v103
	v_mul_f32_e32 v8, 0xbfb8aa3b, v6
	v_exp_f32_e32 v8, v8
	s_nop 0
	v_add_f32_e32 v8, 1.0, v8
	v_rcp_f32_e32 v8, v8
	s_nop 0
	v_mul_f32_e32 v6, v6, v8
	v_mul_f32_e32 v6, v6, v99
	v_mul_f32_e32 v12, 0x3e000000, v6
	v_mul_f32_e32 v6, 0x3c800000, v104
	v_mul_f32_e32 v8, 0xbfb8aa3b, v6
	v_exp_f32_e32 v8, v8
	s_nop 0
	v_add_f32_e32 v8, 1.0, v8
	v_rcp_f32_e32 v8, v8
	s_nop 0
	v_mul_f32_e32 v6, v6, v8
	v_mul_f32_e32 v6, v6, v100
	v_mul_f32_e32 v13, 0x3e000000, v6
	v_mul_f32_e32 v6, 0x3c800000, v105
	v_mul_f32_e32 v8, 0xbfb8aa3b, v6
	v_exp_f32_e32 v8, v8
	s_nop 0
	v_add_f32_e32 v8, 1.0, v8
	v_rcp_f32_e32 v8, v8
	s_nop 0
	v_mul_f32_e32 v6, v6, v8
	v_mov_b32_e32 v8, v163
	v_cvt_pk_fp8_f32 v8, v5, v7
	v_med3_f32 v5, v9, s40, v190
	v_med3_f32 v7, v10, s40, v190
	v_mov_b32_e32 v9, v163
	v_cvt_pk_fp8_f32 v8, v5, v7 op_sel:[0,0,1]
	v_med3_f32 v5, v11, s40, v190
	v_med3_f32 v7, v12, s40, v190
	v_cvt_pk_fp8_f32 v9, v5, v7
	v_mul_f32_e32 v6, v6, v101
	v_mul_f32_e32 v14, 0x3e000000, v6
	v_add_u32_e32 v6, 48, v4
	v_med3_f32 v5, v13, s40, v190
	v_med3_f32 v7, v14, s40, v190
	v_cvt_pk_fp8_f32 v9, v5, v7 op_sel:[0,0,1]
	v_ashrrev_i32_e32 v7, 31, v6
	v_lshlrev_b64 v[6:7], 7, v[6:7]
	v_lshl_add_u64 v[6:7], s[10:11], 0, v[6:7]
	v_lshl_add_u64 v[6:7], v[6:7], 0, v[2:3]
	v_mul_f32_e32 v5, 0x3c800000, v94
	flat_store_dwordx2 v[6:7], v[8:9]
	v_mul_f32_e32 v7, 0xbfb8aa3b, v5
	v_exp_f32_e32 v7, v7
	v_add_u32_e32 v6, 0x80, v4
	v_add_f32_e32 v7, 1.0, v7
	v_rcp_f32_e32 v7, v7
	s_nop 0
	v_mul_f32_e32 v5, v5, v7
	v_mul_f32_e32 v7, 0x3c800000, v95
	v_mul_f32_e32 v8, 0xbfb8aa3b, v7
	v_exp_f32_e32 v8, v8
	v_mul_f32_e32 v5, v5, v90
	v_mul_f32_e32 v5, 0x3e000000, v5
	v_med3_f32 v5, v5, s40, v190
	v_add_f32_e32 v8, 1.0, v8
	v_rcp_f32_e32 v8, v8
	s_nop 0
	v_mul_f32_e32 v7, v7, v8
	v_mul_f32_e32 v8, 0x3c800000, v96
	v_mul_f32_e32 v9, 0xbfb8aa3b, v8
	v_exp_f32_e32 v9, v9
	v_mul_f32_e32 v7, v7, v91
	v_mul_f32_e32 v7, 0x3e000000, v7
	v_med3_f32 v7, v7, s40, v190
	v_add_f32_e32 v9, 1.0, v9
	v_rcp_f32_e32 v9, v9
	s_nop 0
	v_mul_f32_e32 v8, v8, v9
	v_mul_f32_e32 v8, v8, v92
	v_mul_f32_e32 v9, 0x3e000000, v8
	v_mul_f32_e32 v8, 0x3c800000, v97
	v_mul_f32_e32 v10, 0xbfb8aa3b, v8
	v_exp_f32_e32 v10, v10
	s_nop 0
	v_add_f32_e32 v10, 1.0, v10
	v_rcp_f32_e32 v10, v10
	s_nop 0
	v_mul_f32_e32 v8, v8, v10
	v_mul_f32_e32 v8, v8, v93
	v_mul_f32_e32 v10, 0x3e000000, v8
	v_mul_f32_e32 v8, 0x3c800000, v86
	v_mul_f32_e32 v11, 0xbfb8aa3b, v8
	v_exp_f32_e32 v11, v11
	s_nop 0
	v_add_f32_e32 v11, 1.0, v11
	v_rcp_f32_e32 v11, v11
	s_nop 0
	v_mul_f32_e32 v8, v8, v11
	v_mul_f32_e32 v8, v8, v82
	v_mul_f32_e32 v11, 0x3e000000, v8
	v_mul_f32_e32 v8, 0x3c800000, v87
	v_mul_f32_e32 v12, 0xbfb8aa3b, v8
	v_exp_f32_e32 v12, v12
	s_nop 0
	v_add_f32_e32 v12, 1.0, v12
	v_rcp_f32_e32 v12, v12
	s_nop 0
	v_mul_f32_e32 v8, v8, v12
	v_mul_f32_e32 v8, v8, v83
	v_mul_f32_e32 v12, 0x3e000000, v8
	v_mul_f32_e32 v8, 0x3c800000, v88
	v_mul_f32_e32 v13, 0xbfb8aa3b, v8
	v_exp_f32_e32 v13, v13
	s_nop 0
	v_add_f32_e32 v13, 1.0, v13
	v_rcp_f32_e32 v13, v13
	s_nop 0
	v_mul_f32_e32 v8, v8, v13
	v_mul_f32_e32 v8, v8, v84
	v_mul_f32_e32 v13, 0x3e000000, v8
	v_mul_f32_e32 v8, 0x3c800000, v89
	v_mul_f32_e32 v14, 0xbfb8aa3b, v8
	v_exp_f32_e32 v14, v14
	s_nop 0
	v_add_f32_e32 v14, 1.0, v14
	v_rcp_f32_e32 v14, v14
	s_nop 0
	v_mul_f32_e32 v8, v8, v14
	v_mul_f32_e32 v8, v8, v85
	v_mul_f32_e32 v14, 0x3e000000, v8
	v_mov_b32_e32 v8, v163
	v_cvt_pk_fp8_f32 v8, v5, v7
	v_med3_f32 v5, v9, s40, v190
	v_med3_f32 v7, v10, s40, v190
	v_mov_b32_e32 v9, v163
	v_cvt_pk_fp8_f32 v8, v5, v7 op_sel:[0,0,1]
	v_med3_f32 v5, v11, s40, v190
	v_med3_f32 v7, v12, s40, v190
	v_cvt_pk_fp8_f32 v9, v5, v7
	v_med3_f32 v5, v13, s40, v190
	v_med3_f32 v7, v14, s40, v190
	v_cvt_pk_fp8_f32 v9, v5, v7 op_sel:[0,0,1]
	v_ashrrev_i32_e32 v7, 31, v6
	v_lshlrev_b64 v[6:7], 7, v[6:7]
	v_lshl_add_u64 v[6:7], s[10:11], 0, v[6:7]
	v_lshl_add_u64 v[6:7], v[6:7], 0, v[2:3]
	v_mul_f32_e32 v5, 0x3c800000, v78
	flat_store_dwordx2 v[6:7], v[8:9]
	v_mul_f32_e32 v6, 0xbfb8aa3b, v5
	v_exp_f32_e32 v6, v6
	s_nop 0
	v_add_f32_e32 v6, 1.0, v6
	v_rcp_f32_e32 v6, v6
	s_nop 0
	v_mul_f32_e32 v5, v5, v6
	v_mul_f32_e32 v6, 0x3c800000, v79
	v_mul_f32_e32 v7, 0xbfb8aa3b, v6
	v_exp_f32_e32 v7, v7
	v_mul_f32_e32 v5, v5, v74
	v_mul_f32_e32 v5, 0x3e000000, v5
	v_med3_f32 v5, v5, s40, v190
	v_add_f32_e32 v7, 1.0, v7
	v_rcp_f32_e32 v7, v7
	s_nop 0
	v_mul_f32_e32 v6, v6, v7
	v_mul_f32_e32 v6, v6, v75
	v_mul_f32_e32 v7, 0x3e000000, v6
	v_mul_f32_e32 v6, 0x3c800000, v80
	v_mul_f32_e32 v8, 0xbfb8aa3b, v6
	v_exp_f32_e32 v8, v8
	v_med3_f32 v7, v7, s40, v190
	v_add_f32_e32 v8, 1.0, v8
	v_rcp_f32_e32 v8, v8
	s_nop 0
	v_mul_f32_e32 v6, v6, v8
	v_mul_f32_e32 v6, v6, v76
	v_mul_f32_e32 v9, 0x3e000000, v6
	v_mul_f32_e32 v6, 0x3c800000, v81
	v_mul_f32_e32 v8, 0xbfb8aa3b, v6
	v_exp_f32_e32 v8, v8
	s_nop 0
	v_add_f32_e32 v8, 1.0, v8
	v_rcp_f32_e32 v8, v8
	s_nop 0
	v_mul_f32_e32 v6, v6, v8
	v_mul_f32_e32 v6, v6, v77
	v_mul_f32_e32 v10, 0x3e000000, v6
	v_mul_f32_e32 v6, 0x3c800000, v70
	v_mul_f32_e32 v8, 0xbfb8aa3b, v6
	v_exp_f32_e32 v8, v8
	s_nop 0
	v_add_f32_e32 v8, 1.0, v8
	v_rcp_f32_e32 v8, v8
	s_nop 0
	v_mul_f32_e32 v6, v6, v8
	v_mul_f32_e32 v6, v6, v66
	v_mul_f32_e32 v11, 0x3e000000, v6
	v_mul_f32_e32 v6, 0x3c800000, v71
	v_mul_f32_e32 v8, 0xbfb8aa3b, v6
	v_exp_f32_e32 v8, v8
	s_nop 0
	v_add_f32_e32 v8, 1.0, v8
	v_rcp_f32_e32 v8, v8
	s_nop 0
	v_mul_f32_e32 v6, v6, v8
	v_mul_f32_e32 v6, v6, v67
	v_mul_f32_e32 v12, 0x3e000000, v6
	v_mul_f32_e32 v6, 0x3c800000, v72
	v_mul_f32_e32 v8, 0xbfb8aa3b, v6
	v_exp_f32_e32 v8, v8
	s_nop 0
	v_add_f32_e32 v8, 1.0, v8
	v_rcp_f32_e32 v8, v8
	s_nop 0
	v_mul_f32_e32 v6, v6, v8
	v_mul_f32_e32 v6, v6, v68
	v_mul_f32_e32 v13, 0x3e000000, v6
	v_mul_f32_e32 v6, 0x3c800000, v73
	v_mul_f32_e32 v8, 0xbfb8aa3b, v6
	v_exp_f32_e32 v8, v8
	s_nop 0
	v_add_f32_e32 v8, 1.0, v8
	v_rcp_f32_e32 v8, v8
	s_nop 0
	v_mul_f32_e32 v6, v6, v8
	v_mov_b32_e32 v8, v163
	v_cvt_pk_fp8_f32 v8, v5, v7
	v_med3_f32 v5, v9, s40, v190
	v_med3_f32 v7, v10, s40, v190
	v_mov_b32_e32 v9, v163
	v_cvt_pk_fp8_f32 v8, v5, v7 op_sel:[0,0,1]
	v_med3_f32 v5, v11, s40, v190
	v_med3_f32 v7, v12, s40, v190
	v_cvt_pk_fp8_f32 v9, v5, v7
	v_mul_f32_e32 v6, v6, v69
	v_mul_f32_e32 v14, 0x3e000000, v6
	v_add_u32_e32 v6, 0x90, v4
	v_med3_f32 v5, v13, s40, v190
	v_med3_f32 v7, v14, s40, v190
	v_cvt_pk_fp8_f32 v9, v5, v7 op_sel:[0,0,1]
	v_ashrrev_i32_e32 v7, 31, v6
	v_lshlrev_b64 v[6:7], 7, v[6:7]
	v_lshl_add_u64 v[6:7], s[10:11], 0, v[6:7]
	v_lshl_add_u64 v[6:7], v[6:7], 0, v[2:3]
	v_mul_f32_e32 v5, 0x3c800000, v62
	flat_store_dwordx2 v[6:7], v[8:9]
	v_mul_f32_e32 v6, 0xbfb8aa3b, v5
	v_exp_f32_e32 v6, v6
	s_nop 0
	v_add_f32_e32 v6, 1.0, v6
	v_rcp_f32_e32 v6, v6
	s_nop 0
	v_mul_f32_e32 v5, v5, v6
	v_mul_f32_e32 v6, 0x3c800000, v63
	v_mul_f32_e32 v7, 0xbfb8aa3b, v6
	v_exp_f32_e32 v7, v7
	v_mul_f32_e32 v5, v5, v58
	v_mul_f32_e32 v5, 0x3e000000, v5
	v_med3_f32 v5, v5, s40, v190
	v_add_f32_e32 v7, 1.0, v7
	v_rcp_f32_e32 v7, v7
	s_nop 0
	v_mul_f32_e32 v6, v6, v7
	v_mul_f32_e32 v6, v6, v59
	v_mul_f32_e32 v7, 0x3e000000, v6
	v_mul_f32_e32 v6, 0x3c800000, v64
	v_mul_f32_e32 v8, 0xbfb8aa3b, v6
	v_exp_f32_e32 v8, v8
	v_med3_f32 v7, v7, s40, v190
	v_add_f32_e32 v8, 1.0, v8
	v_rcp_f32_e32 v8, v8
	s_nop 0
	v_mul_f32_e32 v6, v6, v8
	v_mul_f32_e32 v6, v6, v60
	v_mul_f32_e32 v9, 0x3e000000, v6
	v_mul_f32_e32 v6, 0x3c800000, v65
	v_mul_f32_e32 v8, 0xbfb8aa3b, v6
	v_exp_f32_e32 v8, v8
	s_nop 0
	v_add_f32_e32 v8, 1.0, v8
	v_rcp_f32_e32 v8, v8
	s_nop 0
	v_mul_f32_e32 v6, v6, v8
	v_mul_f32_e32 v6, v6, v61
	v_mul_f32_e32 v10, 0x3e000000, v6
	v_mul_f32_e32 v6, 0x3c800000, v54
	v_mul_f32_e32 v8, 0xbfb8aa3b, v6
	v_exp_f32_e32 v8, v8
	s_nop 0
	v_add_f32_e32 v8, 1.0, v8
	v_rcp_f32_e32 v8, v8
	s_nop 0
	v_mul_f32_e32 v6, v6, v8
	v_mul_f32_e32 v6, v6, v50
	v_mul_f32_e32 v11, 0x3e000000, v6
	v_mul_f32_e32 v6, 0x3c800000, v55
	v_mul_f32_e32 v8, 0xbfb8aa3b, v6
	v_exp_f32_e32 v8, v8
	s_nop 0
	v_add_f32_e32 v8, 1.0, v8
	v_rcp_f32_e32 v8, v8
	s_nop 0
	v_mul_f32_e32 v6, v6, v8
	v_mul_f32_e32 v6, v6, v51
	v_mul_f32_e32 v12, 0x3e000000, v6
	v_mul_f32_e32 v6, 0x3c800000, v56
	v_mul_f32_e32 v8, 0xbfb8aa3b, v6
	v_exp_f32_e32 v8, v8
	s_nop 0
	v_add_f32_e32 v8, 1.0, v8
	v_rcp_f32_e32 v8, v8
	s_nop 0
	v_mul_f32_e32 v6, v6, v8
	v_mul_f32_e32 v6, v6, v52
	v_mul_f32_e32 v13, 0x3e000000, v6
	v_mul_f32_e32 v6, 0x3c800000, v57
	v_mul_f32_e32 v8, 0xbfb8aa3b, v6
	v_exp_f32_e32 v8, v8
	s_nop 0
	v_add_f32_e32 v8, 1.0, v8
	v_rcp_f32_e32 v8, v8
	s_nop 0
	v_mul_f32_e32 v6, v6, v8
	v_mov_b32_e32 v8, v163
	v_cvt_pk_fp8_f32 v8, v5, v7
	v_med3_f32 v5, v9, s40, v190
	v_med3_f32 v7, v10, s40, v190
	v_mov_b32_e32 v9, v163
	v_cvt_pk_fp8_f32 v8, v5, v7 op_sel:[0,0,1]
	v_med3_f32 v5, v11, s40, v190
	v_med3_f32 v7, v12, s40, v190
	v_cvt_pk_fp8_f32 v9, v5, v7
	v_mul_f32_e32 v6, v6, v53
	v_mul_f32_e32 v14, 0x3e000000, v6
	v_add_u32_e32 v6, 0xa0, v4
	v_med3_f32 v5, v13, s40, v190
	v_med3_f32 v7, v14, s40, v190
	v_cvt_pk_fp8_f32 v9, v5, v7 op_sel:[0,0,1]
	v_ashrrev_i32_e32 v7, 31, v6
	v_lshlrev_b64 v[6:7], 7, v[6:7]
	v_lshl_add_u64 v[6:7], s[10:11], 0, v[6:7]
	v_lshl_add_u64 v[6:7], v[6:7], 0, v[2:3]
	v_mul_f32_e32 v5, 0x3c800000, v46
	flat_store_dwordx2 v[6:7], v[8:9]
	v_mul_f32_e32 v6, 0xbfb8aa3b, v5
	v_exp_f32_e32 v6, v6
	v_add_u32_e32 v4, 0xb0, v4
	v_add_f32_e32 v6, 1.0, v6
	v_rcp_f32_e32 v6, v6
	s_nop 0
	v_mul_f32_e32 v5, v5, v6
	v_mul_f32_e32 v6, 0x3c800000, v47
	v_mul_f32_e32 v7, 0xbfb8aa3b, v6
	v_exp_f32_e32 v7, v7
	v_mul_f32_e32 v5, v5, v42
	v_mul_f32_e32 v5, 0x3e000000, v5
	v_med3_f32 v5, v5, s40, v190
	v_add_f32_e32 v7, 1.0, v7
	v_rcp_f32_e32 v7, v7
	s_nop 0
	v_mul_f32_e32 v6, v6, v7
	v_mul_f32_e32 v7, 0x3c800000, v48
	v_mul_f32_e32 v8, 0xbfb8aa3b, v7
	v_exp_f32_e32 v8, v8
	v_mul_f32_e32 v6, v6, v43
	v_mul_f32_e32 v6, 0x3e000000, v6
	v_add_f32_e32 v8, 1.0, v8
	v_rcp_f32_e32 v8, v8
	s_nop 0
	v_mul_f32_e32 v7, v7, v8
	v_mul_f32_e32 v8, 0x3c800000, v49
	v_mul_f32_e32 v9, 0xbfb8aa3b, v8
	v_exp_f32_e32 v9, v9
	v_mul_f32_e32 v7, v7, v44
	v_mul_f32_e32 v7, 0x3e000000, v7
	v_add_f32_e32 v9, 1.0, v9
	v_rcp_f32_e32 v9, v9
	s_nop 0
	v_mul_f32_e32 v8, v8, v9
	v_mul_f32_e32 v9, 0x3c800000, v38
	v_mul_f32_e32 v10, 0xbfb8aa3b, v9
	v_exp_f32_e32 v10, v10
	v_mul_f32_e32 v8, v8, v45
	v_mul_f32_e32 v8, 0x3e000000, v8
	v_add_f32_e32 v10, 1.0, v10
	v_rcp_f32_e32 v10, v10
	s_nop 0
	v_mul_f32_e32 v9, v9, v10
	v_mul_f32_e32 v10, 0x3c800000, v39
	v_mul_f32_e32 v11, 0xbfb8aa3b, v10
	v_exp_f32_e32 v11, v11
	v_mul_f32_e32 v9, v9, v34
	v_mul_f32_e32 v9, 0x3e000000, v9
	v_add_f32_e32 v11, 1.0, v11
	v_rcp_f32_e32 v11, v11
	s_nop 0
	v_mul_f32_e32 v10, v10, v11
	v_mul_f32_e32 v11, 0x3c800000, v40
	v_mul_f32_e32 v12, 0xbfb8aa3b, v11
	v_exp_f32_e32 v12, v12
	v_mul_f32_e32 v10, v10, v35
	v_mul_f32_e32 v10, 0x3e000000, v10
	v_add_f32_e32 v12, 1.0, v12
	v_rcp_f32_e32 v12, v12
	s_nop 0
	v_mul_f32_e32 v11, v11, v12
	v_mul_f32_e32 v12, 0x3c800000, v41
	v_mul_f32_e32 v13, 0xbfb8aa3b, v12
	v_exp_f32_e32 v13, v13
	v_mul_f32_e32 v11, v11, v36
	v_mul_f32_e32 v11, 0x3e000000, v11
	v_add_f32_e32 v13, 1.0, v13
	v_rcp_f32_e32 v13, v13
	s_nop 0
	v_mul_f32_e32 v12, v12, v13
	v_med3_f32 v13, v6, s40, v190
	v_mov_b32_e32 v6, v163
	v_cvt_pk_fp8_f32 v6, v5, v13
	v_med3_f32 v5, v7, s40, v190
	v_med3_f32 v7, v8, s40, v190
	v_med3_f32 v8, v10, s40, v190
	v_cvt_pk_fp8_f32 v6, v5, v7 op_sel:[0,0,1]
	v_med3_f32 v5, v9, s40, v190
	v_mov_b32_e32 v7, v163
	v_cvt_pk_fp8_f32 v7, v5, v8
	v_mul_f32_e32 v12, v12, v37
	v_mul_f32_e32 v12, 0x3e000000, v12
	v_med3_f32 v5, v11, s40, v190
	v_med3_f32 v8, v12, s40, v190
	v_cvt_pk_fp8_f32 v7, v5, v8 op_sel:[0,0,1]
	v_ashrrev_i32_e32 v5, 31, v4
	v_lshlrev_b64 v[4:5], 7, v[4:5]
	v_lshl_add_u64 v[4:5], s[10:11], 0, v[4:5]
	v_lshl_add_u64 v[2:3], v[4:5], 0, v[2:3]
	flat_store_dwordx2 v[2:3], v[6:7]
	s_cbranch_vccz .LBB0_677
	s_waitcnt vmcnt(0)
	s_cmpk_gt_u32 s42, 0xff
	s_cbranch_scc1 .LBB0_623
	s_barrier
	s_branch .LBB0_623

.LBB0_755:
	ds_read_b128 v[2:5], v169
	ds_read_b128 v[6:9], v169 offset:1024
	ds_read_b128 v[10:13], v169 offset:2048
	ds_read_b128 v[14:17], v169 offset:3072
	s_add_u32 s0, s26, 0x4000
	s_addc_u32 s1, s27, 0
	s_cmp_eq_u32 s53, 4
	s_cselect_b32 s34, s49, s0
	s_cselect_b32 s35, s19, s1
	s_cselect_b32 s28, s50, s51
	s_cselect_b32 s29, s17, s52
	s_add_u32 s30, s34, 0x8000
	s_addc_u32 s31, s35, 0
	v_lshl_add_u64 v[162:163], s[26:27], 0, v[156:157]
	s_add_i32 m0, s25, 0xc000
	ds_read_b128 v[174:177], v170
	ds_read_b128 v[178:181], v170 offset:1024
	ds_read_b128 v[182:185], v170 offset:2048
	ds_read_b128 v[186:189], v170 offset:3072
	ds_read_b128 v[190:193], v170 offset:4096
	ds_read_b128 v[194:197], v170 offset:5120
	ds_read_b128 v[198:201], v170 offset:6144
	ds_read_b128 v[202:205], v170 offset:7168
	global_load_lds_dwordx4 v[162:163], off
	v_lshl_add_u64 v[162:163], s[26:27], 0, v[154:155]
	s_add_i32 m0, s25, 0xe000
	s_nop 0
	global_load_lds_dwordx4 v[162:163], off
	s_waitcnt lgkmcnt(8)
	s_waitcnt vmcnt(10)
	s_barrier
	s_waitcnt lgkmcnt(0)
	s_waitcnt lgkmcnt(0)
	v_mfma_scale_f32_16x16x128_f8f6f4 v[142:145], v[2:9], v[174:181], v[142:145], v171, v171 op_sel_hi:[0,0,0]
	v_mfma_scale_f32_16x16x128_f8f6f4 v[138:141], v[10:17], v[174:181], v[138:141], v171, v171 op_sel_hi:[0,0,0]
	v_mfma_scale_f32_16x16x128_f8f6f4 v[126:129], v[2:9], v[182:189], v[126:129], v171, v171 op_sel_hi:[0,0,0]
	v_mfma_scale_f32_16x16x128_f8f6f4 v[122:125], v[10:17], v[182:189], v[122:125], v171, v171 op_sel_hi:[0,0,0]
	v_mfma_scale_f32_16x16x128_f8f6f4 v[110:113], v[2:9], v[190:197], v[110:113], v171, v171 op_sel_hi:[0,0,0]
	v_mfma_scale_f32_16x16x128_f8f6f4 v[106:109], v[10:17], v[190:197], v[106:109], v171, v171 op_sel_hi:[0,0,0]
	v_mfma_scale_f32_16x16x128_f8f6f4 v[94:97], v[2:9], v[198:205], v[94:97], v171, v171 op_sel_hi:[0,0,0]
	v_mfma_scale_f32_16x16x128_f8f6f4 v[90:93], v[10:17], v[198:205], v[90:93], v171, v171 op_sel_hi:[0,0,0]
	s_barrier
	s_add_i32 s0, s45, s36
	v_lshl_add_u64 v[162:163], s[28:29], 0, v[150:151]
	s_mov_b32 m0, s0
	ds_read_b128 v[206:209], v172
	ds_read_b128 v[210:213], v172 offset:1024
	ds_read_b128 v[214:217], v172 offset:2048
	ds_read_b128 v[218:221], v172 offset:3072
	global_load_lds_dwordx4 v[162:163], off
	v_lshl_add_u64 v[164:165], s[28:29], 0, v[146:147]
	s_add_i32 m0, s0, 0x2000
	s_nop 0
	global_load_lds_dwordx4 v[164:165], off
	s_waitcnt vmcnt(10)
	s_barrier
	s_waitcnt lgkmcnt(0)
	s_waitcnt lgkmcnt(0)
	v_mfma_scale_f32_16x16x128_f8f6f4 v[134:137], v[206:213], v[174:181], v[134:137], v171, v171 op_sel_hi:[0,0,0]
	v_mfma_scale_f32_16x16x128_f8f6f4 v[130:133], v[214:221], v[174:181], v[130:133], v171, v171 op_sel_hi:[0,0,0]
	v_mfma_scale_f32_16x16x128_f8f6f4 v[118:121], v[206:213], v[182:189], v[118:121], v171, v171 op_sel_hi:[0,0,0]
	v_mfma_scale_f32_16x16x128_f8f6f4 v[114:117], v[214:221], v[182:189], v[114:117], v171, v171 op_sel_hi:[0,0,0]
	v_mfma_scale_f32_16x16x128_f8f6f4 v[102:105], v[206:213], v[190:197], v[102:105], v171, v171 op_sel_hi:[0,0,0]
	v_mfma_scale_f32_16x16x128_f8f6f4 v[98:101], v[214:221], v[190:197], v[98:101], v171, v171 op_sel_hi:[0,0,0]
	v_mfma_scale_f32_16x16x128_f8f6f4 v[86:89], v[206:213], v[198:205], v[86:89], v171, v171 op_sel_hi:[0,0,0]
	v_mfma_scale_f32_16x16x128_f8f6f4 v[82:85], v[214:221], v[198:205], v[82:85], v171, v171 op_sel_hi:[0,0,0]
	s_mov_b32 m0, s25
	v_lshl_add_u64 v[222:223], s[34:35], 0, v[152:153]
	s_barrier
	ds_read_b128 v[174:177], v170 offset:16384
	ds_read_b128 v[178:181], v170 offset:17408
	ds_read_b128 v[182:185], v170 offset:18432
	ds_read_b128 v[186:189], v170 offset:19456
	ds_read_b128 v[190:193], v170 offset:20480
	ds_read_b128 v[194:197], v170 offset:21504
	ds_read_b128 v[198:201], v170 offset:22528
	ds_read_b128 v[202:205], v170 offset:23552
	global_load_lds_dwordx4 v[222:223], off
	v_lshl_add_u64 v[222:223], s[34:35], 0, v[148:149]
	s_mov_b32 m0, s37
	s_nop 0
	global_load_lds_dwordx4 v[222:223], off
	s_waitcnt vmcnt(10)
	s_barrier
	s_waitcnt lgkmcnt(0)
	s_waitcnt lgkmcnt(0)
	v_mfma_scale_f32_16x16x128_f8f6f4 v[78:81], v[2:9], v[174:181], v[78:81], v171, v171 op_sel_hi:[0,0,0]
	v_mfma_scale_f32_16x16x128_f8f6f4 v[74:77], v[10:17], v[174:181], v[74:77], v171, v171 op_sel_hi:[0,0,0]
	v_mfma_scale_f32_16x16x128_f8f6f4 v[62:65], v[2:9], v[182:189], v[62:65], v171, v171 op_sel_hi:[0,0,0]
	v_mfma_scale_f32_16x16x128_f8f6f4 v[58:61], v[10:17], v[182:189], v[58:61], v171, v171 op_sel_hi:[0,0,0]
	v_mfma_scale_f32_16x16x128_f8f6f4 v[46:49], v[2:9], v[190:197], v[46:49], v171, v171 op_sel_hi:[0,0,0]
	v_mfma_scale_f32_16x16x128_f8f6f4 v[42:45], v[10:17], v[190:197], v[42:45], v171, v171 op_sel_hi:[0,0,0]
	v_mfma_scale_f32_16x16x128_f8f6f4 v[30:33], v[2:9], v[198:205], v[30:33], v171, v171 op_sel_hi:[0,0,0]
	v_mfma_scale_f32_16x16x128_f8f6f4 v[26:29], v[10:17], v[198:205], v[26:29], v171, v171 op_sel_hi:[0,0,0]
	s_barrier
	s_add_u32 s0, s28, 0x20000
	s_addc_u32 s1, s29, 0
	s_add_i32 s54, s46, s36
	v_lshl_add_u64 v[2:3], s[0:1], 0, v[150:151]
	s_mov_b32 m0, s54
	s_nop 0
	global_load_lds_dwordx4 v[2:3], off
	v_lshl_add_u64 v[2:3], s[0:1], 0, v[146:147]
	s_add_i32 m0, s54, 0x2000
	s_nop 0
	global_load_lds_dwordx4 v[2:3], off
	s_waitcnt vmcnt(10)
	s_barrier
	v_mfma_scale_f32_16x16x128_f8f6f4 v[70:73], v[206:213], v[174:181], v[70:73], v171, v171 op_sel_hi:[0,0,0]
	v_mfma_scale_f32_16x16x128_f8f6f4 v[66:69], v[214:221], v[174:181], v[66:69], v171, v171 op_sel_hi:[0,0,0]
	v_mfma_scale_f32_16x16x128_f8f6f4 v[54:57], v[206:213], v[182:189], v[54:57], v171, v171 op_sel_hi:[0,0,0]
	v_mfma_scale_f32_16x16x128_f8f6f4 v[50:53], v[214:221], v[182:189], v[50:53], v171, v171 op_sel_hi:[0,0,0]
	v_mfma_scale_f32_16x16x128_f8f6f4 v[38:41], v[206:213], v[190:197], v[38:41], v171, v171 op_sel_hi:[0,0,0]
	v_mfma_scale_f32_16x16x128_f8f6f4 v[34:37], v[214:221], v[190:197], v[34:37], v171, v171 op_sel_hi:[0,0,0]
	v_mfma_scale_f32_16x16x128_f8f6f4 v[22:25], v[206:213], v[198:205], v[22:25], v171, v171 op_sel_hi:[0,0,0]
	v_mfma_scale_f32_16x16x128_f8f6f4 v[18:21], v[214:221], v[198:205], v[18:21], v171, v171 op_sel_hi:[0,0,0]
	s_add_i32 s54, 0, 0x18000
	v_add_u32_e32 v14, s54, v168
	s_barrier
	ds_read_b128 v[2:5], v14
	ds_read_b128 v[6:9], v14 offset:1024
	ds_read_b128 v[10:13], v14 offset:2048
	ds_read_b128 v[14:17], v14 offset:3072
	s_add_u32 s0, s34, 0x4000
	s_addc_u32 s1, s35, 0
	s_mov_b32 m0, s38
	v_lshl_add_u64 v[206:207], s[0:1], 0, v[152:153]
	ds_read_b128 v[174:177], v170 offset:32768
	ds_read_b128 v[178:181], v170 offset:33792
	ds_read_b128 v[182:185], v170 offset:34816
	ds_read_b128 v[186:189], v170 offset:35840
	ds_read_b128 v[190:193], v170 offset:36864
	ds_read_b128 v[194:197], v170 offset:37888
	ds_read_b128 v[198:201], v170 offset:38912
	ds_read_b128 v[202:205], v170 offset:39936
	global_load_lds_dwordx4 v[206:207], off
	v_lshl_add_u64 v[206:207], s[0:1], 0, v[148:149]
	s_mov_b32 m0, s39
	s_nop 0
	global_load_lds_dwordx4 v[206:207], off
	s_waitcnt lgkmcnt(8)
	s_waitcnt vmcnt(10)
	s_barrier
	s_waitcnt lgkmcnt(0)
	s_waitcnt lgkmcnt(0)
	v_mfma_scale_f32_16x16x128_f8f6f4 v[142:145], v[2:9], v[174:181], v[142:145], v171, v171 op_sel_hi:[0,0,0]
	v_mfma_scale_f32_16x16x128_f8f6f4 v[138:141], v[10:17], v[174:181], v[138:141], v171, v171 op_sel_hi:[0,0,0]
	v_mfma_scale_f32_16x16x128_f8f6f4 v[126:129], v[2:9], v[182:189], v[126:129], v171, v171 op_sel_hi:[0,0,0]
	v_mfma_scale_f32_16x16x128_f8f6f4 v[122:125], v[10:17], v[182:189], v[122:125], v171, v171 op_sel_hi:[0,0,0]
	v_mfma_scale_f32_16x16x128_f8f6f4 v[110:113], v[2:9], v[190:197], v[110:113], v171, v171 op_sel_hi:[0,0,0]
	v_mfma_scale_f32_16x16x128_f8f6f4 v[106:109], v[10:17], v[190:197], v[106:109], v171, v171 op_sel_hi:[0,0,0]
	v_mfma_scale_f32_16x16x128_f8f6f4 v[94:97], v[2:9], v[198:205], v[94:97], v171, v171 op_sel_hi:[0,0,0]
	v_mfma_scale_f32_16x16x128_f8f6f4 v[90:93], v[10:17], v[198:205], v[90:93], v171, v171 op_sel_hi:[0,0,0]
	s_barrier
	s_add_i32 s34, 0, 0x1c000
	s_add_i32 s0, s54, s36
	v_add_u32_e32 v218, s34, v168
	v_lshl_add_u64 v[162:163], v[162:163], 0, s[12:13]
	s_mov_b32 m0, s0
	ds_read_b128 v[206:209], v218
	ds_read_b128 v[210:213], v218 offset:1024
	ds_read_b128 v[214:217], v218 offset:2048
	ds_read_b128 v[218:221], v218 offset:3072
	global_load_lds_dwordx4 v[162:163], off
	v_lshl_add_u64 v[162:163], v[164:165], 0, s[12:13]
	s_add_i32 m0, s0, 0x2000
	s_nop 0
	global_load_lds_dwordx4 v[162:163], off
	s_waitcnt vmcnt(10)
	s_barrier
	s_waitcnt lgkmcnt(0)
	s_waitcnt lgkmcnt(0)
	v_mfma_scale_f32_16x16x128_f8f6f4 v[134:137], v[206:213], v[174:181], v[134:137], v171, v171 op_sel_hi:[0,0,0]
	v_mfma_scale_f32_16x16x128_f8f6f4 v[130:133], v[214:221], v[174:181], v[130:133], v171, v171 op_sel_hi:[0,0,0]
	v_mfma_scale_f32_16x16x128_f8f6f4 v[118:121], v[206:213], v[182:189], v[118:121], v171, v171 op_sel_hi:[0,0,0]
	v_mfma_scale_f32_16x16x128_f8f6f4 v[114:117], v[214:221], v[182:189], v[114:117], v171, v171 op_sel_hi:[0,0,0]
	v_mfma_scale_f32_16x16x128_f8f6f4 v[102:105], v[206:213], v[190:197], v[102:105], v171, v171 op_sel_hi:[0,0,0]
	v_mfma_scale_f32_16x16x128_f8f6f4 v[98:101], v[214:221], v[190:197], v[98:101], v171, v171 op_sel_hi:[0,0,0]
	v_mfma_scale_f32_16x16x128_f8f6f4 v[86:89], v[206:213], v[198:205], v[86:89], v171, v171 op_sel_hi:[0,0,0]
	v_mfma_scale_f32_16x16x128_f8f6f4 v[82:85], v[214:221], v[198:205], v[82:85], v171, v171 op_sel_hi:[0,0,0]
	s_mov_b32 m0, s43
	v_lshl_add_u64 v[162:163], s[30:31], 0, v[152:153]
	s_barrier
	ds_read_b128 v[174:177], v170 offset:49152
	ds_read_b128 v[178:181], v170 offset:50176
	ds_read_b128 v[182:185], v170 offset:51200
	ds_read_b128 v[186:189], v170 offset:52224
	ds_read_b128 v[190:193], v170 offset:53248
	ds_read_b128 v[194:197], v170 offset:54272
	ds_read_b128 v[198:201], v170 offset:55296
	ds_read_b128 v[202:205], v170 offset:56320
	global_load_lds_dwordx4 v[162:163], off
	v_lshl_add_u64 v[162:163], s[30:31], 0, v[148:149]
	s_mov_b32 m0, s44
	s_nop 0
	global_load_lds_dwordx4 v[162:163], off
	s_waitcnt vmcnt(10)
	s_barrier
	s_waitcnt lgkmcnt(0)
	s_waitcnt lgkmcnt(0)
	v_mfma_scale_f32_16x16x128_f8f6f4 v[78:81], v[2:9], v[174:181], v[78:81], v171, v171 op_sel_hi:[0,0,0]
	v_mfma_scale_f32_16x16x128_f8f6f4 v[74:77], v[10:17], v[174:181], v[74:77], v171, v171 op_sel_hi:[0,0,0]
	v_mfma_scale_f32_16x16x128_f8f6f4 v[62:65], v[2:9], v[182:189], v[62:65], v171, v171 op_sel_hi:[0,0,0]
	v_mfma_scale_f32_16x16x128_f8f6f4 v[58:61], v[10:17], v[182:189], v[58:61], v171, v171 op_sel_hi:[0,0,0]
	v_mfma_scale_f32_16x16x128_f8f6f4 v[46:49], v[2:9], v[190:197], v[46:49], v171, v171 op_sel_hi:[0,0,0]
	v_mfma_scale_f32_16x16x128_f8f6f4 v[42:45], v[10:17], v[190:197], v[42:45], v171, v171 op_sel_hi:[0,0,0]
	v_mfma_scale_f32_16x16x128_f8f6f4 v[30:33], v[2:9], v[198:205], v[30:33], v171, v171 op_sel_hi:[0,0,0]
	v_mfma_scale_f32_16x16x128_f8f6f4 v[26:29], v[10:17], v[198:205], v[26:29], v171, v171 op_sel_hi:[0,0,0]
	s_barrier
	s_add_u32 s0, s28, 0x20080
	s_addc_u32 s1, s29, 0
	s_add_i32 s28, s34, s36
	v_lshl_add_u64 v[2:3], s[0:1], 0, v[150:151]
	s_mov_b32 m0, s28
	s_nop 0
	global_load_lds_dwordx4 v[2:3], off
	v_lshl_add_u64 v[2:3], s[0:1], 0, v[146:147]
	s_add_i32 m0, s28, 0x2000
	s_nop 0
	global_load_lds_dwordx4 v[2:3], off
	s_waitcnt vmcnt(10)
	s_barrier
	v_mfma_scale_f32_16x16x128_f8f6f4 v[70:73], v[206:213], v[174:181], v[70:73], v171, v171 op_sel_hi:[0,0,0]
	v_mfma_scale_f32_16x16x128_f8f6f4 v[66:69], v[214:221], v[174:181], v[66:69], v171, v171 op_sel_hi:[0,0,0]
	v_mfma_scale_f32_16x16x128_f8f6f4 v[54:57], v[206:213], v[182:189], v[54:57], v171, v171 op_sel_hi:[0,0,0]
	v_mfma_scale_f32_16x16x128_f8f6f4 v[50:53], v[214:221], v[182:189], v[50:53], v171, v171 op_sel_hi:[0,0,0]
	v_mfma_scale_f32_16x16x128_f8f6f4 v[38:41], v[206:213], v[190:197], v[38:41], v171, v171 op_sel_hi:[0,0,0]
	v_mfma_scale_f32_16x16x128_f8f6f4 v[34:37], v[214:221], v[190:197], v[34:37], v171, v171 op_sel_hi:[0,0,0]
	v_mfma_scale_f32_16x16x128_f8f6f4 v[22:25], v[206:213], v[198:205], v[22:25], v171, v171 op_sel_hi:[0,0,0]
	v_mfma_scale_f32_16x16x128_f8f6f4 v[18:21], v[214:221], v[198:205], v[18:21], v171, v171 op_sel_hi:[0,0,0]
	s_add_i32 s53, s53, 2
	s_add_u32 s51, s51, 0x100
	s_addc_u32 s52, s52, 0
	s_add_u32 s26, s26, 0x10000
	s_addc_u32 s27, s27, 0
	s_cmp_gt_u32 s53, 5
	s_barrier
	s_cbranch_scc0 .LBB0_755
	v_pk_mul_f32 v[10:11], v[142:143], s[14:15] op_sel_hi:[1,0]
	v_pk_mul_f32 v[8:9], v[144:145], s[14:15] op_sel_hi:[1,0]
	v_med3_f32 v5, v10, s47, v173
	v_med3_f32 v11, v11, s47, v173
	v_mov_b32_e32 v10, 0
	v_cvt_pk_fp8_f32 v10, v5, v11
	v_mov_b32_e32 v3, v166
	v_mov_b32_e32 v2, v167
	s_lshl_b32 s0, s48, 8
	v_pk_mul_f32 v[14:15], v[138:139], s[14:15] op_sel_hi:[1,0]
	v_med3_f32 v5, v8, s47, v173
	v_med3_f32 v8, v9, s47, v173
	s_nop 15
	s_nop 15
	s_or_b32 s0, s0, s42
	v_cvt_pk_fp8_f32 v10, v5, v8 op_sel:[0,0,1]
	v_med3_f32 v5, v14, s47, v173
	v_med3_f32 v8, v15, s47, v173
	v_mov_b32_e32 v11, 0
	v_lshl_add_u32 v2, v2, 3, s0
	s_lshl_b32 s0, s24, 8
	v_cvt_pk_fp8_f32 v11, v5, v8
	s_add_i32 s0, s0, s41
	v_add_u32_e32 v4, s0, v3
	v_pk_mul_f32 v[12:13], v[140:141], s[14:15] op_sel_hi:[1,0]
	v_mov_b32_e32 v6, v4
	v_med3_f32 v5, v12, s47, v173
	v_med3_f32 v8, v13, s47, v173
	v_cvt_pk_fp8_f32 v11, v5, v8 op_sel:[0,0,1]
	v_ashrrev_i32_e32 v7, 31, v6
	v_lshlrev_b64 v[6:7], 10, v[6:7]
	v_ashrrev_i32_e32 v3, 31, v2
	v_lshl_add_u64 v[6:7], s[10:11], 0, v[6:7]
	v_lshl_add_u64 v[6:7], v[6:7], 0, v[2:3]
	flat_store_dwordx2 v[6:7], v[10:11]
	v_pk_mul_f32 v[10:11], v[134:135], s[14:15] op_sel_hi:[1,0]
	v_pk_mul_f32 v[8:9], v[136:137], s[14:15] op_sel_hi:[1,0]
	v_med3_f32 v5, v10, s47, v173
	v_med3_f32 v11, v11, s47, v173
	v_mov_b32_e32 v10, 0
	v_cvt_pk_fp8_f32 v10, v5, v11
	v_pk_mul_f32 v[14:15], v[130:131], s[14:15] op_sel_hi:[1,0]
	v_med3_f32 v5, v8, s47, v173
	v_med3_f32 v8, v9, s47, v173
	v_cvt_pk_fp8_f32 v10, v5, v8 op_sel:[0,0,1]
	v_med3_f32 v5, v14, s47, v173
	v_med3_f32 v8, v15, s47, v173
	v_mov_b32_e32 v11, 0
	v_cvt_pk_fp8_f32 v11, v5, v8
	v_pk_mul_f32 v[12:13], v[132:133], s[14:15] op_sel_hi:[1,0]
	v_pk_mul_f32 v[14:15], v[122:123], s[14:15] op_sel_hi:[1,0]
	v_med3_f32 v5, v12, s47, v173
	v_med3_f32 v8, v13, s47, v173
	v_cvt_pk_fp8_f32 v11, v5, v8 op_sel:[0,0,1]
	v_pk_mul_f32 v[8:9], v[128:129], s[14:15] op_sel_hi:[1,0]
	v_pk_mul_f32 v[12:13], v[124:125], s[14:15] op_sel_hi:[1,0]
	s_and_b64 vcc, exec, s[8:9]
	flat_store_dwordx2 v[6:7], v[10:11] offset:128
	v_pk_mul_f32 v[10:11], v[126:127], s[14:15] op_sel_hi:[1,0]
	v_add_u32_e32 v6, 16, v4
	v_med3_f32 v5, v10, s47, v173
	v_med3_f32 v11, v11, s47, v173
	v_mov_b32_e32 v10, 0
	v_cvt_pk_fp8_f32 v10, v5, v11
	v_med3_f32 v5, v8, s47, v173
	v_med3_f32 v8, v9, s47, v173
	v_mov_b32_e32 v11, 0
	v_cvt_pk_fp8_f32 v10, v5, v8 op_sel:[0,0,1]
	v_med3_f32 v5, v14, s47, v173
	v_med3_f32 v8, v15, s47, v173
	v_cvt_pk_fp8_f32 v11, v5, v8
	v_med3_f32 v5, v12, s47, v173
	v_med3_f32 v8, v13, s47, v173
	v_cvt_pk_fp8_f32 v11, v5, v8 op_sel:[0,0,1]
	v_ashrrev_i32_e32 v7, 31, v6
	v_lshlrev_b64 v[6:7], 10, v[6:7]
	v_lshl_add_u64 v[6:7], s[10:11], 0, v[6:7]
	v_lshl_add_u64 v[6:7], v[6:7], 0, v[2:3]
	flat_store_dwordx2 v[6:7], v[10:11]
	v_pk_mul_f32 v[10:11], v[118:119], s[14:15] op_sel_hi:[1,0]
	v_pk_mul_f32 v[8:9], v[120:121], s[14:15] op_sel_hi:[1,0]
	v_med3_f32 v5, v10, s47, v173
	v_med3_f32 v11, v11, s47, v173
	v_mov_b32_e32 v10, 0
	v_cvt_pk_fp8_f32 v10, v5, v11
	v_pk_mul_f32 v[14:15], v[114:115], s[14:15] op_sel_hi:[1,0]
	v_med3_f32 v5, v8, s47, v173
	v_med3_f32 v8, v9, s47, v173
	v_cvt_pk_fp8_f32 v10, v5, v8 op_sel:[0,0,1]
	v_med3_f32 v5, v14, s47, v173
	v_med3_f32 v8, v15, s47, v173
	v_mov_b32_e32 v11, 0
	v_cvt_pk_fp8_f32 v11, v5, v8
	v_pk_mul_f32 v[12:13], v[116:117], s[14:15] op_sel_hi:[1,0]
	v_pk_mul_f32 v[14:15], v[106:107], s[14:15] op_sel_hi:[1,0]
	v_med3_f32 v5, v12, s47, v173
	v_med3_f32 v8, v13, s47, v173
	v_cvt_pk_fp8_f32 v11, v5, v8 op_sel:[0,0,1]
	v_pk_mul_f32 v[8:9], v[112:113], s[14:15] op_sel_hi:[1,0]
	v_pk_mul_f32 v[12:13], v[108:109], s[14:15] op_sel_hi:[1,0]
	s_mov_b32 s48, s16
	flat_store_dwordx2 v[6:7], v[10:11] offset:128
	v_pk_mul_f32 v[10:11], v[110:111], s[14:15] op_sel_hi:[1,0]
	v_add_u32_e32 v6, 32, v4
	v_med3_f32 v5, v10, s47, v173
	v_med3_f32 v11, v11, s47, v173
	v_mov_b32_e32 v10, 0
	v_cvt_pk_fp8_f32 v10, v5, v11
	v_med3_f32 v5, v8, s47, v173
	v_med3_f32 v8, v9, s47, v173
	v_mov_b32_e32 v11, 0
	v_cvt_pk_fp8_f32 v10, v5, v8 op_sel:[0,0,1]
	v_med3_f32 v5, v14, s47, v173
	v_med3_f32 v8, v15, s47, v173
	v_cvt_pk_fp8_f32 v11, v5, v8
	v_med3_f32 v5, v12, s47, v173
	v_med3_f32 v8, v13, s47, v173
	v_cvt_pk_fp8_f32 v11, v5, v8 op_sel:[0,0,1]
	v_ashrrev_i32_e32 v7, 31, v6
	v_lshlrev_b64 v[6:7], 10, v[6:7]
	v_lshl_add_u64 v[6:7], s[10:11], 0, v[6:7]
	v_lshl_add_u64 v[6:7], v[6:7], 0, v[2:3]
	flat_store_dwordx2 v[6:7], v[10:11]
	v_pk_mul_f32 v[10:11], v[102:103], s[14:15] op_sel_hi:[1,0]
	v_pk_mul_f32 v[8:9], v[104:105], s[14:15] op_sel_hi:[1,0]
	v_med3_f32 v5, v10, s47, v173
	v_med3_f32 v11, v11, s47, v173
	v_mov_b32_e32 v10, 0
	v_cvt_pk_fp8_f32 v10, v5, v11
	v_pk_mul_f32 v[14:15], v[98:99], s[14:15] op_sel_hi:[1,0]
	v_med3_f32 v5, v8, s47, v173
	v_med3_f32 v8, v9, s47, v173
	v_cvt_pk_fp8_f32 v10, v5, v8 op_sel:[0,0,1]
	v_med3_f32 v5, v14, s47, v173
	v_med3_f32 v8, v15, s47, v173
	v_mov_b32_e32 v11, 0
	v_cvt_pk_fp8_f32 v11, v5, v8
	v_pk_mul_f32 v[12:13], v[100:101], s[14:15] op_sel_hi:[1,0]
	v_pk_mul_f32 v[14:15], v[90:91], s[14:15] op_sel_hi:[1,0]
	v_med3_f32 v5, v12, s47, v173
	v_med3_f32 v8, v13, s47, v173
	v_cvt_pk_fp8_f32 v11, v5, v8 op_sel:[0,0,1]
	v_pk_mul_f32 v[8:9], v[96:97], s[14:15] op_sel_hi:[1,0]
	v_pk_mul_f32 v[12:13], v[92:93], s[14:15] op_sel_hi:[1,0]
	s_mov_b32 s24, s18
	flat_store_dwordx2 v[6:7], v[10:11] offset:128
	v_pk_mul_f32 v[10:11], v[94:95], s[14:15] op_sel_hi:[1,0]
	v_add_u32_e32 v6, 48, v4
	v_med3_f32 v5, v10, s47, v173
	v_med3_f32 v11, v11, s47, v173
	v_mov_b32_e32 v10, 0
	v_cvt_pk_fp8_f32 v10, v5, v11
	v_med3_f32 v5, v8, s47, v173
	v_med3_f32 v8, v9, s47, v173
	v_mov_b32_e32 v11, 0
	v_cvt_pk_fp8_f32 v10, v5, v8 op_sel:[0,0,1]
	v_med3_f32 v5, v14, s47, v173
	v_med3_f32 v8, v15, s47, v173
	v_cvt_pk_fp8_f32 v11, v5, v8
	v_med3_f32 v5, v12, s47, v173
	v_med3_f32 v8, v13, s47, v173
	v_cvt_pk_fp8_f32 v11, v5, v8 op_sel:[0,0,1]
	v_ashrrev_i32_e32 v7, 31, v6
	v_lshlrev_b64 v[6:7], 10, v[6:7]
	v_lshl_add_u64 v[6:7], s[10:11], 0, v[6:7]
	v_lshl_add_u64 v[6:7], v[6:7], 0, v[2:3]
	flat_store_dwordx2 v[6:7], v[10:11]
	v_pk_mul_f32 v[10:11], v[86:87], s[14:15] op_sel_hi:[1,0]
	v_pk_mul_f32 v[8:9], v[88:89], s[14:15] op_sel_hi:[1,0]
	v_med3_f32 v5, v10, s47, v173
	v_med3_f32 v11, v11, s47, v173
	v_mov_b32_e32 v10, 0
	v_cvt_pk_fp8_f32 v10, v5, v11
	v_pk_mul_f32 v[14:15], v[82:83], s[14:15] op_sel_hi:[1,0]
	v_med3_f32 v5, v8, s47, v173
	v_med3_f32 v8, v9, s47, v173
	v_cvt_pk_fp8_f32 v10, v5, v8 op_sel:[0,0,1]
	v_med3_f32 v5, v14, s47, v173
	v_med3_f32 v8, v15, s47, v173
	v_mov_b32_e32 v11, 0
	v_cvt_pk_fp8_f32 v11, v5, v8
	v_pk_mul_f32 v[12:13], v[84:85], s[14:15] op_sel_hi:[1,0]
	v_pk_mul_f32 v[14:15], v[74:75], s[14:15] op_sel_hi:[1,0]
	v_med3_f32 v5, v12, s47, v173
	v_med3_f32 v8, v13, s47, v173
	v_cvt_pk_fp8_f32 v11, v5, v8 op_sel:[0,0,1]
	v_pk_mul_f32 v[8:9], v[80:81], s[14:15] op_sel_hi:[1,0]
	v_pk_mul_f32 v[12:13], v[76:77], s[14:15] op_sel_hi:[1,0]
	s_mov_b64 s[26:27], s[22:23]
	flat_store_dwordx2 v[6:7], v[10:11] offset:128
	v_pk_mul_f32 v[10:11], v[78:79], s[14:15] op_sel_hi:[1,0]
	v_add_u32_e32 v6, 0x80, v4
	v_med3_f32 v5, v10, s47, v173
	v_med3_f32 v11, v11, s47, v173
	v_mov_b32_e32 v10, 0
	v_cvt_pk_fp8_f32 v10, v5, v11
	v_med3_f32 v5, v8, s47, v173
	v_med3_f32 v8, v9, s47, v173
	v_mov_b32_e32 v11, 0
	v_cvt_pk_fp8_f32 v10, v5, v8 op_sel:[0,0,1]
	v_med3_f32 v5, v14, s47, v173
	v_med3_f32 v8, v15, s47, v173
	v_cvt_pk_fp8_f32 v11, v5, v8
	v_med3_f32 v5, v12, s47, v173
	v_med3_f32 v8, v13, s47, v173
	v_cvt_pk_fp8_f32 v11, v5, v8 op_sel:[0,0,1]
	v_ashrrev_i32_e32 v7, 31, v6
	v_lshlrev_b64 v[6:7], 10, v[6:7]
	v_lshl_add_u64 v[6:7], s[10:11], 0, v[6:7]
	v_lshl_add_u64 v[6:7], v[6:7], 0, v[2:3]
	flat_store_dwordx2 v[6:7], v[10:11]
	v_pk_mul_f32 v[10:11], v[70:71], s[14:15] op_sel_hi:[1,0]
	v_pk_mul_f32 v[8:9], v[72:73], s[14:15] op_sel_hi:[1,0]
	v_med3_f32 v5, v10, s47, v173
	v_med3_f32 v11, v11, s47, v173
	v_mov_b32_e32 v10, 0
	v_cvt_pk_fp8_f32 v10, v5, v11
	v_pk_mul_f32 v[14:15], v[66:67], s[14:15] op_sel_hi:[1,0]
	v_med3_f32 v5, v8, s47, v173
	v_med3_f32 v8, v9, s47, v173
	v_cvt_pk_fp8_f32 v10, v5, v8 op_sel:[0,0,1]
	v_med3_f32 v5, v14, s47, v173
	v_med3_f32 v8, v15, s47, v173
	v_mov_b32_e32 v11, 0
	v_cvt_pk_fp8_f32 v11, v5, v8
	v_pk_mul_f32 v[12:13], v[68:69], s[14:15] op_sel_hi:[1,0]
	v_pk_mul_f32 v[14:15], v[58:59], s[14:15] op_sel_hi:[1,0]
	v_med3_f32 v5, v12, s47, v173
	v_med3_f32 v8, v13, s47, v173
	v_cvt_pk_fp8_f32 v11, v5, v8 op_sel:[0,0,1]
	v_pk_mul_f32 v[8:9], v[64:65], s[14:15] op_sel_hi:[1,0]
	v_pk_mul_f32 v[12:13], v[60:61], s[14:15] op_sel_hi:[1,0]
	s_mov_b64 s[28:29], s[20:21]
	flat_store_dwordx2 v[6:7], v[10:11] offset:128
	v_pk_mul_f32 v[10:11], v[62:63], s[14:15] op_sel_hi:[1,0]
	v_add_u32_e32 v6, 0x90, v4
	v_med3_f32 v5, v10, s47, v173
	v_med3_f32 v11, v11, s47, v173
	v_mov_b32_e32 v10, 0
	v_cvt_pk_fp8_f32 v10, v5, v11
	v_med3_f32 v5, v8, s47, v173
	v_med3_f32 v8, v9, s47, v173
	v_mov_b32_e32 v11, 0
	v_cvt_pk_fp8_f32 v10, v5, v8 op_sel:[0,0,1]
	v_med3_f32 v5, v14, s47, v173
	v_med3_f32 v8, v15, s47, v173
	v_cvt_pk_fp8_f32 v11, v5, v8
	v_med3_f32 v5, v12, s47, v173
	v_med3_f32 v8, v13, s47, v173
	v_cvt_pk_fp8_f32 v11, v5, v8 op_sel:[0,0,1]
	v_ashrrev_i32_e32 v7, 31, v6
	v_lshlrev_b64 v[6:7], 10, v[6:7]
	v_lshl_add_u64 v[6:7], s[10:11], 0, v[6:7]
	v_lshl_add_u64 v[6:7], v[6:7], 0, v[2:3]
	flat_store_dwordx2 v[6:7], v[10:11]
	v_pk_mul_f32 v[10:11], v[54:55], s[14:15] op_sel_hi:[1,0]
	v_pk_mul_f32 v[8:9], v[56:57], s[14:15] op_sel_hi:[1,0]
	v_med3_f32 v5, v10, s47, v173
	v_med3_f32 v11, v11, s47, v173
	v_mov_b32_e32 v10, 0
	v_cvt_pk_fp8_f32 v10, v5, v11
	v_pk_mul_f32 v[14:15], v[50:51], s[14:15] op_sel_hi:[1,0]
	v_med3_f32 v5, v8, s47, v173
	v_med3_f32 v8, v9, s47, v173
	v_cvt_pk_fp8_f32 v10, v5, v8 op_sel:[0,0,1]
	v_med3_f32 v5, v14, s47, v173
	v_med3_f32 v8, v15, s47, v173
	v_mov_b32_e32 v11, 0
	v_cvt_pk_fp8_f32 v11, v5, v8
	v_pk_mul_f32 v[12:13], v[52:53], s[14:15] op_sel_hi:[1,0]
	v_pk_mul_f32 v[14:15], v[42:43], s[14:15] op_sel_hi:[1,0]
	v_med3_f32 v5, v12, s47, v173
	v_med3_f32 v8, v13, s47, v173
	v_cvt_pk_fp8_f32 v11, v5, v8 op_sel:[0,0,1]
	v_pk_mul_f32 v[8:9], v[48:49], s[14:15] op_sel_hi:[1,0]
	v_pk_mul_f32 v[12:13], v[44:45], s[14:15] op_sel_hi:[1,0]
	flat_store_dwordx2 v[6:7], v[10:11] offset:128
	v_pk_mul_f32 v[10:11], v[46:47], s[14:15] op_sel_hi:[1,0]
	v_add_u32_e32 v6, 0xa0, v4
	v_med3_f32 v5, v10, s47, v173
	v_med3_f32 v11, v11, s47, v173
	v_mov_b32_e32 v10, 0
	v_cvt_pk_fp8_f32 v10, v5, v11
	v_med3_f32 v5, v8, s47, v173
	v_med3_f32 v8, v9, s47, v173
	v_mov_b32_e32 v11, 0
	v_cvt_pk_fp8_f32 v10, v5, v8 op_sel:[0,0,1]
	v_med3_f32 v5, v14, s47, v173
	v_med3_f32 v8, v15, s47, v173
	v_cvt_pk_fp8_f32 v11, v5, v8
	v_med3_f32 v5, v12, s47, v173
	v_med3_f32 v8, v13, s47, v173
	v_cvt_pk_fp8_f32 v11, v5, v8 op_sel:[0,0,1]
	v_ashrrev_i32_e32 v7, 31, v6
	v_lshlrev_b64 v[6:7], 10, v[6:7]
	v_lshl_add_u64 v[6:7], s[10:11], 0, v[6:7]
	v_lshl_add_u64 v[6:7], v[6:7], 0, v[2:3]
	flat_store_dwordx2 v[6:7], v[10:11]
	v_pk_mul_f32 v[10:11], v[38:39], s[14:15] op_sel_hi:[1,0]
	v_pk_mul_f32 v[8:9], v[40:41], s[14:15] op_sel_hi:[1,0]
	v_med3_f32 v5, v10, s47, v173
	v_med3_f32 v11, v11, s47, v173
	v_mov_b32_e32 v10, 0
	v_cvt_pk_fp8_f32 v10, v5, v11
	v_pk_mul_f32 v[14:15], v[34:35], s[14:15] op_sel_hi:[1,0]
	v_med3_f32 v5, v8, s47, v173
	v_med3_f32 v8, v9, s47, v173
	v_cvt_pk_fp8_f32 v10, v5, v8 op_sel:[0,0,1]
	v_med3_f32 v5, v14, s47, v173
	v_med3_f32 v8, v15, s47, v173
	v_mov_b32_e32 v11, 0
	v_cvt_pk_fp8_f32 v11, v5, v8
	v_pk_mul_f32 v[12:13], v[36:37], s[14:15] op_sel_hi:[1,0]
	v_add_u32_e32 v4, 0xb0, v4
	v_med3_f32 v5, v12, s47, v173
	v_med3_f32 v8, v13, s47, v173
	v_cvt_pk_fp8_f32 v11, v5, v8 op_sel:[0,0,1]
	v_pk_mul_f32 v[8:9], v[28:29], s[14:15] op_sel_hi:[1,0]
	flat_store_dwordx2 v[6:7], v[10:11] offset:128
	v_pk_mul_f32 v[6:7], v[30:31], s[14:15] op_sel_hi:[1,0]
	v_pk_mul_f32 v[10:11], v[26:27], s[14:15] op_sel_hi:[1,0]
	v_ashrrev_i32_e32 v5, 31, v4
	v_med3_f32 v12, v6, s47, v173
	v_med3_f32 v7, v7, s47, v173
	v_mov_b32_e32 v6, 0
	v_lshlrev_b64 v[4:5], 10, v[4:5]
	v_cvt_pk_fp8_f32 v6, v12, v7
	v_lshl_add_u64 v[4:5], s[10:11], 0, v[4:5]
	v_lshl_add_u64 v[2:3], v[4:5], 0, v[2:3]
	v_pk_mul_f32 v[4:5], v[32:33], s[14:15] op_sel_hi:[1,0]
	v_mov_b32_e32 v7, 0
	v_med3_f32 v4, v4, s47, v173
	v_med3_f32 v5, v5, s47, v173
	v_cvt_pk_fp8_f32 v6, v4, v5 op_sel:[0,0,1]
	v_med3_f32 v4, v10, s47, v173
	v_med3_f32 v5, v11, s47, v173
	v_cvt_pk_fp8_f32 v7, v4, v5
	v_med3_f32 v4, v8, s47, v173
	v_med3_f32 v5, v9, s47, v173
	v_pk_mul_f32 v[10:11], v[18:19], s[14:15] op_sel_hi:[1,0]
	v_cvt_pk_fp8_f32 v7, v4, v5 op_sel:[0,0,1]
	v_pk_mul_f32 v[4:5], v[24:25], s[14:15] op_sel_hi:[1,0]
	v_pk_mul_f32 v[8:9], v[20:21], s[14:15] op_sel_hi:[1,0]
	v_med3_f32 v4, v4, s47, v173
	flat_store_dwordx2 v[2:3], v[6:7]
	v_pk_mul_f32 v[6:7], v[22:23], s[14:15] op_sel_hi:[1,0]
	v_med3_f32 v5, v5, s47, v173
	v_med3_f32 v12, v6, s47, v173
	v_med3_f32 v7, v7, s47, v173
	v_mov_b32_e32 v6, 0
	v_cvt_pk_fp8_f32 v6, v12, v7
	v_mov_b32_e32 v7, 0
	v_cvt_pk_fp8_f32 v6, v4, v5 op_sel:[0,0,1]
	v_med3_f32 v4, v10, s47, v173
	v_med3_f32 v5, v11, s47, v173
	v_cvt_pk_fp8_f32 v7, v4, v5
	v_med3_f32 v4, v8, s47, v173
	v_med3_f32 v5, v9, s47, v173
	v_cvt_pk_fp8_f32 v7, v4, v5 op_sel:[0,0,1]
	flat_store_dwordx2 v[2:3], v[6:7] offset:128
	s_cbranch_vccz .LBB0_748
	s_waitcnt vmcnt(0)
	s_cmpk_gt_u32 s4, 0xff
	s_cbranch_scc1 .LBB0_759
	s_barrier

.LBB0_895:
	ds_read_b128 v[156:159], v152
	ds_read_b128 v[160:163], v152 offset:1024
	ds_read_b128 v[164:167], v152 offset:2048
	ds_read_b128 v[168:171], v152 offset:3072
	s_add_u32 s0, s30, 0xfffc0080
	s_addc_u32 s1, s31, -1
	s_cmp_eq_u32 s55, 12
	s_cselect_b32 s37, s23, s1
	s_cselect_b32 s36, s51, s0
	s_cselect_b32 s35, s21, s54
	s_cselect_b32 s34, s52, s53
	v_lshl_add_u64 v[148:149], s[30:31], 0, v[140:141]
	s_add_i32 m0, s25, 0xc000
	ds_read_b128 v[172:175], v153
	ds_read_b128 v[176:179], v153 offset:1024
	ds_read_b128 v[180:183], v153 offset:2048
	ds_read_b128 v[184:187], v153 offset:3072
	ds_read_b128 v[188:191], v153 offset:4096
	ds_read_b128 v[192:195], v153 offset:5120
	ds_read_b128 v[196:199], v153 offset:6144
	ds_read_b128 v[200:203], v153 offset:7168
	global_load_lds_dwordx4 v[148:149], off
	v_lshl_add_u64 v[148:149], s[30:31], 0, v[138:139]
	s_add_i32 m0, s25, 0xe000
	s_nop 0
	global_load_lds_dwordx4 v[148:149], off
	s_waitcnt lgkmcnt(8)
	s_waitcnt vmcnt(10)
	s_barrier
	s_waitcnt lgkmcnt(0)
	s_waitcnt lgkmcnt(0)
	v_mfma_f32_16x16x32_bf16 v[126:129], v[156:159], v[172:175], v[126:129]
	v_mfma_f32_16x16x32_bf16 v[122:125], v[164:167], v[172:175], v[122:125]
	v_mfma_f32_16x16x32_bf16 v[118:121], v[156:159], v[180:183], v[118:121]
	v_mfma_f32_16x16x32_bf16 v[110:113], v[164:167], v[180:183], v[110:113]
	v_mfma_f32_16x16x32_bf16 v[102:105], v[156:159], v[188:191], v[102:105]
	v_mfma_f32_16x16x32_bf16 v[94:97], v[164:167], v[188:191], v[94:97]
	v_mfma_f32_16x16x32_bf16 v[86:89], v[156:159], v[196:199], v[86:89]
	v_mfma_f32_16x16x32_bf16 v[78:81], v[164:167], v[196:199], v[78:81]
	v_mfma_f32_16x16x32_bf16 v[126:129], v[160:163], v[176:179], v[126:129]
	v_mfma_f32_16x16x32_bf16 v[122:125], v[168:171], v[176:179], v[122:125]
	v_mfma_f32_16x16x32_bf16 v[118:121], v[160:163], v[184:187], v[118:121]
	v_mfma_f32_16x16x32_bf16 v[110:113], v[168:171], v[184:187], v[110:113]
	v_mfma_f32_16x16x32_bf16 v[102:105], v[160:163], v[192:195], v[102:105]
	v_mfma_f32_16x16x32_bf16 v[94:97], v[168:171], v[192:195], v[94:97]
	v_mfma_f32_16x16x32_bf16 v[86:89], v[160:163], v[200:203], v[86:89]
	v_mfma_f32_16x16x32_bf16 v[78:81], v[168:171], v[200:203], v[78:81]
	s_barrier
	s_add_i32 s0, s47, s11
	v_lshl_add_u64 v[148:149], s[34:35], 0, v[134:135]
	s_mov_b32 m0, s0
	ds_read_b128 v[204:207], v154
	ds_read_b128 v[208:211], v154 offset:1024
	ds_read_b128 v[212:215], v154 offset:2048
	ds_read_b128 v[216:219], v154 offset:3072
	global_load_lds_dwordx4 v[148:149], off
	v_lshl_add_u64 v[220:221], s[34:35], 0, v[130:131]
	s_add_i32 m0, s0, 0x2000
	s_nop 0
	global_load_lds_dwordx4 v[220:221], off
	s_waitcnt vmcnt(10)
	s_barrier
	s_waitcnt lgkmcnt(0)
	s_waitcnt lgkmcnt(0)
	v_mfma_f32_16x16x32_bf16 v[114:117], v[204:207], v[172:175], v[114:117]
	v_mfma_f32_16x16x32_bf16 v[106:109], v[212:215], v[172:175], v[106:109]
	v_mfma_f32_16x16x32_bf16 v[98:101], v[204:207], v[180:183], v[98:101]
	v_mfma_f32_16x16x32_bf16 v[90:93], v[212:215], v[180:183], v[90:93]
	v_mfma_f32_16x16x32_bf16 v[82:85], v[204:207], v[188:191], v[82:85]
	v_mfma_f32_16x16x32_bf16 v[74:77], v[212:215], v[188:191], v[74:77]
	v_mfma_f32_16x16x32_bf16 v[70:73], v[204:207], v[196:199], v[70:73]
	v_mfma_f32_16x16x32_bf16 v[66:69], v[212:215], v[196:199], v[66:69]
	v_mfma_f32_16x16x32_bf16 v[114:117], v[208:211], v[176:179], v[114:117]
	v_mfma_f32_16x16x32_bf16 v[106:109], v[216:219], v[176:179], v[106:109]
	v_mfma_f32_16x16x32_bf16 v[98:101], v[208:211], v[184:187], v[98:101]
	v_mfma_f32_16x16x32_bf16 v[90:93], v[216:219], v[184:187], v[90:93]
	v_mfma_f32_16x16x32_bf16 v[82:85], v[208:211], v[192:195], v[82:85]
	v_mfma_f32_16x16x32_bf16 v[74:77], v[216:219], v[192:195], v[74:77]
	v_mfma_f32_16x16x32_bf16 v[70:73], v[208:211], v[200:203], v[70:73]
	v_mfma_f32_16x16x32_bf16 v[66:69], v[216:219], v[200:203], v[66:69]
	s_mov_b32 m0, s25
	v_lshl_add_u64 v[222:223], s[36:37], 0, v[136:137]
	s_barrier
	ds_read_b128 v[172:175], v153 offset:16384
	ds_read_b128 v[176:179], v153 offset:17408
	ds_read_b128 v[180:183], v153 offset:18432
	ds_read_b128 v[184:187], v153 offset:19456
	ds_read_b128 v[188:191], v153 offset:20480
	ds_read_b128 v[192:195], v153 offset:21504
	ds_read_b128 v[196:199], v153 offset:22528
	ds_read_b128 v[200:203], v153 offset:23552
	global_load_lds_dwordx4 v[222:223], off
	v_lshl_add_u64 v[224:225], s[36:37], 0, v[132:133]
	s_mov_b32 m0, s39
	s_nop 0
	global_load_lds_dwordx4 v[224:225], off
	s_waitcnt vmcnt(10)
	s_barrier
	s_waitcnt lgkmcnt(0)
	s_waitcnt lgkmcnt(0)
	v_mfma_f32_16x16x32_bf16 v[62:65], v[156:159], v[172:175], v[62:65]
	v_mfma_f32_16x16x32_bf16 v[58:61], v[164:167], v[172:175], v[58:61]
	v_mfma_f32_16x16x32_bf16 v[54:57], v[156:159], v[180:183], v[54:57]
	v_mfma_f32_16x16x32_bf16 v[46:49], v[164:167], v[180:183], v[46:49]
	v_mfma_f32_16x16x32_bf16 v[38:41], v[156:159], v[188:191], v[38:41]
	v_mfma_f32_16x16x32_bf16 v[30:33], v[164:167], v[188:191], v[30:33]
	v_mfma_f32_16x16x32_bf16 v[22:25], v[156:159], v[196:199], v[22:25]
	v_mfma_f32_16x16x32_bf16 v[14:17], v[164:167], v[196:199], v[14:17]
	v_mfma_f32_16x16x32_bf16 v[62:65], v[160:163], v[176:179], v[62:65]
	v_mfma_f32_16x16x32_bf16 v[58:61], v[168:171], v[176:179], v[58:61]
	v_mfma_f32_16x16x32_bf16 v[54:57], v[160:163], v[184:187], v[54:57]
	v_mfma_f32_16x16x32_bf16 v[46:49], v[168:171], v[184:187], v[46:49]
	v_mfma_f32_16x16x32_bf16 v[38:41], v[160:163], v[192:195], v[38:41]
	v_mfma_f32_16x16x32_bf16 v[30:33], v[168:171], v[192:195], v[30:33]
	v_mfma_f32_16x16x32_bf16 v[22:25], v[160:163], v[200:203], v[22:25]
	v_mfma_f32_16x16x32_bf16 v[14:17], v[168:171], v[200:203], v[14:17]
	s_barrier
	s_add_u32 s0, s34, 0x40000
	s_addc_u32 s1, s35, 0
	s_add_i32 s56, s48, s11
	v_lshl_add_u64 v[156:157], s[0:1], 0, v[134:135]
	s_mov_b32 m0, s56
	s_nop 0
	global_load_lds_dwordx4 v[156:157], off
	v_lshl_add_u64 v[156:157], s[0:1], 0, v[130:131]
	s_add_i32 m0, s56, 0x2000
	s_nop 0
	global_load_lds_dwordx4 v[156:157], off
	s_waitcnt vmcnt(10)
	s_barrier
	v_mfma_f32_16x16x32_bf16 v[50:53], v[204:207], v[172:175], v[50:53]
	v_mfma_f32_16x16x32_bf16 v[42:45], v[212:215], v[172:175], v[42:45]
	v_mfma_f32_16x16x32_bf16 v[34:37], v[204:207], v[180:183], v[34:37]
	v_mfma_f32_16x16x32_bf16 v[26:29], v[212:215], v[180:183], v[26:29]
	v_mfma_f32_16x16x32_bf16 v[18:21], v[204:207], v[188:191], v[18:21]
	v_mfma_f32_16x16x32_bf16 v[10:13], v[212:215], v[188:191], v[10:13]
	v_mfma_f32_16x16x32_bf16 v[6:9], v[204:207], v[196:199], v[6:9]
	v_mfma_f32_16x16x32_bf16 v[2:5], v[212:215], v[196:199], v[2:5]
	v_mfma_f32_16x16x32_bf16 v[50:53], v[208:211], v[176:179], v[50:53]
	v_mfma_f32_16x16x32_bf16 v[42:45], v[216:219], v[176:179], v[42:45]
	v_mfma_f32_16x16x32_bf16 v[34:37], v[208:211], v[184:187], v[34:37]
	v_mfma_f32_16x16x32_bf16 v[26:29], v[216:219], v[184:187], v[26:29]
	v_mfma_f32_16x16x32_bf16 v[18:21], v[208:211], v[192:195], v[18:21]
	v_mfma_f32_16x16x32_bf16 v[10:13], v[216:219], v[192:195], v[10:13]
	v_mfma_f32_16x16x32_bf16 v[6:9], v[208:211], v[200:203], v[6:9]
	v_mfma_f32_16x16x32_bf16 v[2:5], v[216:219], v[200:203], v[2:5]
	s_add_i32 s56, 0, 0x18000
	v_add_u32_e32 v146, s56, v151
	s_barrier
	ds_read_b128 v[156:159], v146
	ds_read_b128 v[160:163], v146 offset:1024
	ds_read_b128 v[164:167], v146 offset:2048
	ds_read_b128 v[168:171], v146 offset:3072
	s_add_u32 s0, s36, 0x40000
	s_addc_u32 s1, s37, 0
	s_mov_b32 m0, s40
	v_lshl_add_u64 v[204:205], s[0:1], 0, v[136:137]
	ds_read_b128 v[172:175], v153 offset:32768
	ds_read_b128 v[176:179], v153 offset:33792
	ds_read_b128 v[180:183], v153 offset:34816
	ds_read_b128 v[184:187], v153 offset:35840
	ds_read_b128 v[188:191], v153 offset:36864
	ds_read_b128 v[192:195], v153 offset:37888
	ds_read_b128 v[196:199], v153 offset:38912
	ds_read_b128 v[200:203], v153 offset:39936
	global_load_lds_dwordx4 v[204:205], off
	v_lshl_add_u64 v[204:205], s[0:1], 0, v[132:133]
	s_mov_b32 m0, s41
	s_nop 0
	global_load_lds_dwordx4 v[204:205], off
	s_waitcnt lgkmcnt(8)
	s_waitcnt vmcnt(10)
	s_barrier
	s_waitcnt lgkmcnt(0)
	s_waitcnt lgkmcnt(0)
	v_mfma_f32_16x16x32_bf16 v[126:129], v[156:159], v[172:175], v[126:129]
	v_mfma_f32_16x16x32_bf16 v[122:125], v[164:167], v[172:175], v[122:125]
	v_mfma_f32_16x16x32_bf16 v[118:121], v[156:159], v[180:183], v[118:121]
	v_mfma_f32_16x16x32_bf16 v[110:113], v[164:167], v[180:183], v[110:113]
	v_mfma_f32_16x16x32_bf16 v[102:105], v[156:159], v[188:191], v[102:105]
	v_mfma_f32_16x16x32_bf16 v[94:97], v[164:167], v[188:191], v[94:97]
	v_mfma_f32_16x16x32_bf16 v[86:89], v[156:159], v[196:199], v[86:89]
	v_mfma_f32_16x16x32_bf16 v[78:81], v[164:167], v[196:199], v[78:81]
	v_mfma_f32_16x16x32_bf16 v[126:129], v[160:163], v[176:179], v[126:129]
	v_mfma_f32_16x16x32_bf16 v[122:125], v[168:171], v[176:179], v[122:125]
	v_mfma_f32_16x16x32_bf16 v[118:121], v[160:163], v[184:187], v[118:121]
	v_mfma_f32_16x16x32_bf16 v[110:113], v[168:171], v[184:187], v[110:113]
	v_mfma_f32_16x16x32_bf16 v[102:105], v[160:163], v[192:195], v[102:105]
	v_mfma_f32_16x16x32_bf16 v[94:97], v[168:171], v[192:195], v[94:97]
	v_mfma_f32_16x16x32_bf16 v[86:89], v[160:163], v[200:203], v[86:89]
	v_mfma_f32_16x16x32_bf16 v[78:81], v[168:171], v[200:203], v[78:81]
	s_barrier
	s_add_i32 s36, 0, 0x1c000
	s_add_i32 s0, s56, s11
	v_add_u32_e32 v146, s36, v151
	v_lshl_add_u64 v[148:149], v[148:149], 0, s[16:17]
	s_mov_b32 m0, s0
	ds_read_b128 v[204:207], v146
	ds_read_b128 v[208:211], v146 offset:1024
	ds_read_b128 v[212:215], v146 offset:2048
	ds_read_b128 v[216:219], v146 offset:3072
	global_load_lds_dwordx4 v[148:149], off
	v_lshl_add_u64 v[148:149], v[220:221], 0, s[16:17]
	s_add_i32 m0, s0, 0x2000
	s_nop 0
	global_load_lds_dwordx4 v[148:149], off
	s_waitcnt vmcnt(10)
	s_barrier
	s_waitcnt lgkmcnt(0)
	s_waitcnt lgkmcnt(0)
	v_mfma_f32_16x16x32_bf16 v[114:117], v[204:207], v[172:175], v[114:117]
	v_mfma_f32_16x16x32_bf16 v[106:109], v[212:215], v[172:175], v[106:109]
	v_mfma_f32_16x16x32_bf16 v[98:101], v[204:207], v[180:183], v[98:101]
	v_mfma_f32_16x16x32_bf16 v[90:93], v[212:215], v[180:183], v[90:93]
	v_mfma_f32_16x16x32_bf16 v[82:85], v[204:207], v[188:191], v[82:85]
	v_mfma_f32_16x16x32_bf16 v[74:77], v[212:215], v[188:191], v[74:77]
	v_mfma_f32_16x16x32_bf16 v[70:73], v[204:207], v[196:199], v[70:73]
	v_mfma_f32_16x16x32_bf16 v[66:69], v[212:215], v[196:199], v[66:69]
	v_mfma_f32_16x16x32_bf16 v[114:117], v[208:211], v[176:179], v[114:117]
	v_mfma_f32_16x16x32_bf16 v[106:109], v[216:219], v[176:179], v[106:109]
	v_mfma_f32_16x16x32_bf16 v[98:101], v[208:211], v[184:187], v[98:101]
	v_mfma_f32_16x16x32_bf16 v[90:93], v[216:219], v[184:187], v[90:93]
	v_mfma_f32_16x16x32_bf16 v[82:85], v[208:211], v[192:195], v[82:85]
	v_mfma_f32_16x16x32_bf16 v[74:77], v[216:219], v[192:195], v[74:77]
	v_mfma_f32_16x16x32_bf16 v[70:73], v[208:211], v[200:203], v[70:73]
	v_mfma_f32_16x16x32_bf16 v[66:69], v[216:219], v[200:203], v[66:69]
	s_mov_b32 m0, s45
	v_lshl_add_u64 v[148:149], v[222:223], 0, s[16:17]
	s_barrier
	ds_read_b128 v[172:175], v153 offset:49152
	ds_read_b128 v[176:179], v153 offset:50176
	ds_read_b128 v[180:183], v153 offset:51200
	ds_read_b128 v[184:187], v153 offset:52224
	ds_read_b128 v[188:191], v153 offset:53248
	ds_read_b128 v[192:195], v153 offset:54272
	ds_read_b128 v[196:199], v153 offset:55296
	ds_read_b128 v[200:203], v153 offset:56320
	global_load_lds_dwordx4 v[148:149], off
	v_lshl_add_u64 v[148:149], v[224:225], 0, s[16:17]
	s_mov_b32 m0, s46
	s_nop 0
	global_load_lds_dwordx4 v[148:149], off
	s_waitcnt vmcnt(10)
	s_barrier
	s_waitcnt lgkmcnt(0)
	s_waitcnt lgkmcnt(0)
	v_mfma_f32_16x16x32_bf16 v[62:65], v[156:159], v[172:175], v[62:65]
	v_mfma_f32_16x16x32_bf16 v[58:61], v[164:167], v[172:175], v[58:61]
	v_mfma_f32_16x16x32_bf16 v[54:57], v[156:159], v[180:183], v[54:57]
	v_mfma_f32_16x16x32_bf16 v[46:49], v[164:167], v[180:183], v[46:49]
	v_mfma_f32_16x16x32_bf16 v[38:41], v[156:159], v[188:191], v[38:41]
	v_mfma_f32_16x16x32_bf16 v[30:33], v[164:167], v[188:191], v[30:33]
	v_mfma_f32_16x16x32_bf16 v[22:25], v[156:159], v[196:199], v[22:25]
	v_mfma_f32_16x16x32_bf16 v[14:17], v[164:167], v[196:199], v[14:17]
	v_mfma_f32_16x16x32_bf16 v[62:65], v[160:163], v[176:179], v[62:65]
	v_mfma_f32_16x16x32_bf16 v[58:61], v[168:171], v[176:179], v[58:61]
	v_mfma_f32_16x16x32_bf16 v[54:57], v[160:163], v[184:187], v[54:57]
	v_mfma_f32_16x16x32_bf16 v[46:49], v[168:171], v[184:187], v[46:49]
	v_mfma_f32_16x16x32_bf16 v[38:41], v[160:163], v[192:195], v[38:41]
	v_mfma_f32_16x16x32_bf16 v[30:33], v[168:171], v[192:195], v[30:33]
	v_mfma_f32_16x16x32_bf16 v[22:25], v[160:163], v[200:203], v[22:25]
	v_mfma_f32_16x16x32_bf16 v[14:17], v[168:171], v[200:203], v[14:17]
	s_barrier
	s_add_u32 s0, s34, 0x40080
	s_addc_u32 s1, s35, 0
	s_add_i32 s34, s36, s11
	v_lshl_add_u64 v[148:149], s[0:1], 0, v[134:135]
	s_mov_b32 m0, s34
	s_nop 0
	global_load_lds_dwordx4 v[148:149], off
	v_lshl_add_u64 v[148:149], s[0:1], 0, v[130:131]
	s_add_i32 m0, s34, 0x2000
	s_nop 0
	global_load_lds_dwordx4 v[148:149], off
	s_waitcnt vmcnt(10)
	s_barrier
	v_mfma_f32_16x16x32_bf16 v[50:53], v[204:207], v[172:175], v[50:53]
	v_mfma_f32_16x16x32_bf16 v[42:45], v[212:215], v[172:175], v[42:45]
	v_mfma_f32_16x16x32_bf16 v[34:37], v[204:207], v[180:183], v[34:37]
	v_mfma_f32_16x16x32_bf16 v[26:29], v[212:215], v[180:183], v[26:29]
	v_mfma_f32_16x16x32_bf16 v[18:21], v[204:207], v[188:191], v[18:21]
	v_mfma_f32_16x16x32_bf16 v[10:13], v[212:215], v[188:191], v[10:13]
	v_mfma_f32_16x16x32_bf16 v[6:9], v[204:207], v[196:199], v[6:9]
	v_mfma_f32_16x16x32_bf16 v[2:5], v[212:215], v[196:199], v[2:5]
	v_mfma_f32_16x16x32_bf16 v[50:53], v[208:211], v[176:179], v[50:53]
	v_mfma_f32_16x16x32_bf16 v[42:45], v[216:219], v[176:179], v[42:45]
	v_mfma_f32_16x16x32_bf16 v[34:37], v[208:211], v[184:187], v[34:37]
	v_mfma_f32_16x16x32_bf16 v[26:29], v[216:219], v[184:187], v[26:29]
	v_mfma_f32_16x16x32_bf16 v[18:21], v[208:211], v[192:195], v[18:21]
	v_mfma_f32_16x16x32_bf16 v[10:13], v[216:219], v[192:195], v[10:13]
	v_mfma_f32_16x16x32_bf16 v[6:9], v[208:211], v[200:203], v[6:9]
	v_mfma_f32_16x16x32_bf16 v[2:5], v[216:219], v[200:203], v[2:5]
	s_add_i32 s55, s55, 2
	s_add_u32 s53, s53, 0x100
	s_addc_u32 s54, s54, 0
	s_add_u32 s30, s30, 0x100
	s_addc_u32 s31, s31, 0
	s_cmp_gt_u32 s55, 13
	s_barrier
	s_cbranch_scc0 .LBB0_895
	v_mov_b32_e32 v156, v147
	v_mov_b32_e32 v146, v150
	s_cmp_gt_i32 s50, 11
	s_mov_b64 s[30:31], -1
	s_cbranch_scc0 .LBB0_900
	s_cmp_eq_u32 s50, 12
	s_cselect_b64 s[0:1], -1, 0
	s_and_b64 s[0:1], s[0:1], s[18:19]
	v_cmp_gt_i32_e32 vcc, 4, v146
	s_and_b64 s[0:1], s[0:1], vcc
	s_and_saveexec_b64 s[30:31], s[0:1]
	s_cbranch_execz .LBB0_899
	s_lshl_b32 s0, s24, 8
	s_add_i32 s0, s0, s43
	v_add_u32_e32 v157, s0, v156
	v_mov_b32_e32 v158, v157
	v_lshlrev_b32_e32 v148, 3, v146
	v_ashrrev_i32_e32 v149, 31, v148
	v_ashrrev_i32_e32 v159, 31, v158
	v_lshlrev_b64 v[158:159], 7, v[158:159]
	v_lshl_add_u64 v[158:159], s[14:15], 0, v[158:159]
	v_lshlrev_b64 v[148:149], 2, v[148:149]
	v_lshl_add_u64 v[162:163], v[158:159], 0, v[148:149]
	v_pk_add_f32 v[160:161], v[128:129], 0 op_sel_hi:[1,0]
	v_pk_add_f32 v[158:159], v[126:127], 0 op_sel_hi:[1,0]
	flat_store_dwordx4 v[162:163], v[158:161]
	s_nop 1
	v_pk_add_f32 v[160:161], v[124:125], 0 op_sel_hi:[1,0]
	v_pk_add_f32 v[158:159], v[122:123], 0 op_sel_hi:[1,0]
	flat_store_dwordx4 v[162:163], v[158:161] offset:16
	s_nop 1
	v_add_u32_e32 v158, 16, v157
	v_pk_add_f32 v[160:161], v[120:121], 0 op_sel_hi:[1,0]
	v_ashrrev_i32_e32 v159, 31, v158
	v_lshlrev_b64 v[158:159], 7, v[158:159]
	v_lshl_add_u64 v[158:159], s[14:15], 0, v[158:159]
	v_lshl_add_u64 v[162:163], v[158:159], 0, v[148:149]
	v_pk_add_f32 v[158:159], v[118:119], 0 op_sel_hi:[1,0]
	flat_store_dwordx4 v[162:163], v[158:161]
	s_nop 1
	v_pk_add_f32 v[160:161], v[112:113], 0 op_sel_hi:[1,0]
	v_pk_add_f32 v[158:159], v[110:111], 0 op_sel_hi:[1,0]
	flat_store_dwordx4 v[162:163], v[158:161] offset:16
	s_nop 1
	v_add_u32_e32 v158, 32, v157
	v_pk_add_f32 v[160:161], v[104:105], 0 op_sel_hi:[1,0]
	v_ashrrev_i32_e32 v159, 31, v158
	v_lshlrev_b64 v[158:159], 7, v[158:159]
	v_lshl_add_u64 v[158:159], s[14:15], 0, v[158:159]
	v_lshl_add_u64 v[162:163], v[158:159], 0, v[148:149]
	v_pk_add_f32 v[158:159], v[102:103], 0 op_sel_hi:[1,0]
	flat_store_dwordx4 v[162:163], v[158:161]
	s_nop 1
	v_pk_add_f32 v[160:161], v[96:97], 0 op_sel_hi:[1,0]
	v_pk_add_f32 v[158:159], v[94:95], 0 op_sel_hi:[1,0]
	flat_store_dwordx4 v[162:163], v[158:161] offset:16
	s_nop 1
	v_add_u32_e32 v158, 48, v157
	v_pk_add_f32 v[160:161], v[88:89], 0 op_sel_hi:[1,0]
	v_ashrrev_i32_e32 v159, 31, v158
	v_lshlrev_b64 v[158:159], 7, v[158:159]
	v_lshl_add_u64 v[158:159], s[14:15], 0, v[158:159]
	v_lshl_add_u64 v[162:163], v[158:159], 0, v[148:149]
	v_pk_add_f32 v[158:159], v[86:87], 0 op_sel_hi:[1,0]
	flat_store_dwordx4 v[162:163], v[158:161]
	s_nop 1
	v_pk_add_f32 v[160:161], v[80:81], 0 op_sel_hi:[1,0]
	v_pk_add_f32 v[158:159], v[78:79], 0 op_sel_hi:[1,0]
	flat_store_dwordx4 v[162:163], v[158:161] offset:16
	s_nop 1
	v_add_u32_e32 v158, 0x80, v157
	v_pk_add_f32 v[160:161], v[64:65], 0 op_sel_hi:[1,0]
	v_ashrrev_i32_e32 v159, 31, v158
	v_lshlrev_b64 v[158:159], 7, v[158:159]
	v_lshl_add_u64 v[158:159], s[14:15], 0, v[158:159]
	v_lshl_add_u64 v[162:163], v[158:159], 0, v[148:149]
	v_pk_add_f32 v[158:159], v[62:63], 0 op_sel_hi:[1,0]
	flat_store_dwordx4 v[162:163], v[158:161]
	s_nop 1
	v_pk_add_f32 v[160:161], v[60:61], 0 op_sel_hi:[1,0]
	v_pk_add_f32 v[158:159], v[58:59], 0 op_sel_hi:[1,0]
	flat_store_dwordx4 v[162:163], v[158:161] offset:16
	s_nop 1
	v_add_u32_e32 v158, 0x90, v157
	v_pk_add_f32 v[160:161], v[56:57], 0 op_sel_hi:[1,0]
	v_ashrrev_i32_e32 v159, 31, v158
	v_lshlrev_b64 v[158:159], 7, v[158:159]
	v_lshl_add_u64 v[158:159], s[14:15], 0, v[158:159]
	v_lshl_add_u64 v[162:163], v[158:159], 0, v[148:149]
	v_pk_add_f32 v[158:159], v[54:55], 0 op_sel_hi:[1,0]
	flat_store_dwordx4 v[162:163], v[158:161]
	s_nop 1
	v_pk_add_f32 v[160:161], v[48:49], 0 op_sel_hi:[1,0]
	v_pk_add_f32 v[158:159], v[46:47], 0 op_sel_hi:[1,0]
	flat_store_dwordx4 v[162:163], v[158:161] offset:16
	s_nop 1
	v_add_u32_e32 v158, 0xa0, v157
	v_pk_add_f32 v[160:161], v[40:41], 0 op_sel_hi:[1,0]
	v_ashrrev_i32_e32 v159, 31, v158
	v_lshlrev_b64 v[158:159], 7, v[158:159]
	v_lshl_add_u64 v[158:159], s[14:15], 0, v[158:159]
	v_lshl_add_u64 v[162:163], v[158:159], 0, v[148:149]
	v_pk_add_f32 v[158:159], v[38:39], 0 op_sel_hi:[1,0]
	flat_store_dwordx4 v[162:163], v[158:161]
	s_nop 1
	v_pk_add_f32 v[160:161], v[32:33], 0 op_sel_hi:[1,0]
	v_pk_add_f32 v[158:159], v[30:31], 0 op_sel_hi:[1,0]
	flat_store_dwordx4 v[162:163], v[158:161] offset:16
	s_nop 1
	v_add_u32_e32 v158, 0xb0, v157
	v_pk_add_f32 v[160:161], v[24:25], 0 op_sel_hi:[1,0]
	v_ashrrev_i32_e32 v159, 31, v158
	v_lshlrev_b64 v[158:159], 7, v[158:159]
	v_lshl_add_u64 v[158:159], s[14:15], 0, v[158:159]
	v_lshl_add_u64 v[148:149], v[158:159], 0, v[148:149]
	v_pk_add_f32 v[158:159], v[22:23], 0 op_sel_hi:[1,0]
	flat_store_dwordx4 v[148:149], v[158:161]
	s_nop 1
	v_pk_add_f32 v[160:161], v[16:17], 0 op_sel_hi:[1,0]
	v_pk_add_f32 v[158:159], v[14:15], 0 op_sel_hi:[1,0]
	flat_store_dwordx4 v[148:149], v[158:161] offset:16

.LBB0_1047:
	ds_read_b128 v[130:133], v170
	ds_read_b128 v[134:137], v170 offset:1024
	ds_read_b128 v[138:141], v170 offset:2048
	ds_read_b128 v[142:145], v170 offset:3072
	s_add_u32 s0, s38, 0xfffc0080
	s_addc_u32 s1, s39, -1
	s_cmp_eq_u32 s69, 12
	s_cselect_b32 s43, s60, s1
	s_cselect_b32 s42, s61, s0
	s_cselect_b32 s41, s62, s65
	s_cselect_b32 s40, s63, s64
	s_mov_b32 m0, s50
	v_lshl_add_u64 v[166:167], s[38:39], 0, v[164:165]
	ds_read_b128 v[146:149], v171
	ds_read_b128 v[174:177], v171 offset:1024
	ds_read_b128 v[178:181], v171 offset:2048
	ds_read_b128 v[182:185], v171 offset:3072
	ds_read_b128 v[186:189], v171 offset:4096
	ds_read_b128 v[190:193], v171 offset:5120
	ds_read_b128 v[194:197], v171 offset:6144
	ds_read_b128 v[198:201], v171 offset:7168
	global_load_lds_dwordx4 v[166:167], off
	v_lshl_add_u64 v[166:167], s[38:39], 0, v[162:163]
	s_mov_b32 m0, s51
	s_nop 0
	global_load_lds_dwordx4 v[166:167], off
	s_waitcnt lgkmcnt(8)
	s_waitcnt vmcnt(10)
	s_barrier
	s_waitcnt lgkmcnt(0)
	s_waitcnt lgkmcnt(0)
	v_mfma_f32_16x16x32_bf16 v[126:129], v[130:133], v[146:149], v[126:129]
	v_mfma_f32_16x16x32_bf16 v[122:125], v[138:141], v[146:149], v[122:125]
	v_mfma_f32_16x16x32_bf16 v[118:121], v[130:133], v[178:181], v[118:121]
	v_mfma_f32_16x16x32_bf16 v[110:113], v[138:141], v[178:181], v[110:113]
	v_mfma_f32_16x16x32_bf16 v[98:101], v[130:133], v[186:189], v[98:101]
	v_mfma_f32_16x16x32_bf16 v[90:93], v[138:141], v[186:189], v[90:93]
	v_mfma_f32_16x16x32_bf16 v[82:85], v[130:133], v[194:197], v[82:85]
	v_mfma_f32_16x16x32_bf16 v[74:77], v[138:141], v[194:197], v[74:77]
	v_mfma_f32_16x16x32_bf16 v[126:129], v[134:137], v[174:177], v[126:129]
	v_mfma_f32_16x16x32_bf16 v[122:125], v[142:145], v[174:177], v[122:125]
	v_mfma_f32_16x16x32_bf16 v[118:121], v[134:137], v[182:185], v[118:121]
	v_mfma_f32_16x16x32_bf16 v[110:113], v[142:145], v[182:185], v[110:113]
	v_mfma_f32_16x16x32_bf16 v[98:101], v[134:137], v[190:193], v[98:101]
	v_mfma_f32_16x16x32_bf16 v[90:93], v[142:145], v[190:193], v[90:93]
	v_mfma_f32_16x16x32_bf16 v[82:85], v[134:137], v[198:201], v[82:85]
	v_mfma_f32_16x16x32_bf16 v[74:77], v[142:145], v[198:201], v[74:77]
	s_barrier
	s_mov_b32 m0, s52
	v_lshl_add_u64 v[166:167], s[40:41], 0, v[158:159]
	ds_read_b128 v[202:205], v172
	ds_read_b128 v[206:209], v172 offset:1024
	ds_read_b128 v[210:213], v172 offset:2048
	ds_read_b128 v[214:217], v172 offset:3072
	global_load_lds_dwordx4 v[166:167], off
	v_lshl_add_u64 v[218:219], s[40:41], 0, v[154:155]
	s_mov_b32 m0, s53
	s_nop 0
	global_load_lds_dwordx4 v[218:219], off
	s_waitcnt vmcnt(10)
	s_barrier
	s_waitcnt lgkmcnt(0)
	s_waitcnt lgkmcnt(0)
	v_mfma_f32_16x16x32_bf16 v[114:117], v[202:205], v[146:149], v[114:117]
	v_mfma_f32_16x16x32_bf16 v[106:109], v[210:213], v[146:149], v[106:109]
	v_mfma_f32_16x16x32_bf16 v[102:105], v[202:205], v[178:181], v[102:105]
	v_mfma_f32_16x16x32_bf16 v[94:97], v[210:213], v[178:181], v[94:97]
	v_mfma_f32_16x16x32_bf16 v[86:89], v[202:205], v[186:189], v[86:89]
	v_mfma_f32_16x16x32_bf16 v[78:81], v[210:213], v[186:189], v[78:81]
	v_mfma_f32_16x16x32_bf16 v[70:73], v[202:205], v[194:197], v[70:73]
	v_mfma_f32_16x16x32_bf16 v[66:69], v[210:213], v[194:197], v[66:69]
	v_mfma_f32_16x16x32_bf16 v[114:117], v[206:209], v[174:177], v[114:117]
	v_mfma_f32_16x16x32_bf16 v[106:109], v[214:217], v[174:177], v[106:109]
	v_mfma_f32_16x16x32_bf16 v[102:105], v[206:209], v[182:185], v[102:105]
	v_mfma_f32_16x16x32_bf16 v[94:97], v[214:217], v[182:185], v[94:97]
	v_mfma_f32_16x16x32_bf16 v[86:89], v[206:209], v[190:193], v[86:89]
	v_mfma_f32_16x16x32_bf16 v[78:81], v[214:217], v[190:193], v[78:81]
	v_mfma_f32_16x16x32_bf16 v[70:73], v[206:209], v[198:201], v[70:73]
	v_mfma_f32_16x16x32_bf16 v[66:69], v[214:217], v[198:201], v[66:69]
	s_mov_b32 m0, s6
	v_lshl_add_u64 v[220:221], s[42:43], 0, v[160:161]
	s_barrier
	ds_read_b128 v[146:149], v171 offset:16384
	ds_read_b128 v[174:177], v171 offset:17408
	ds_read_b128 v[178:181], v171 offset:18432
	ds_read_b128 v[182:185], v171 offset:19456
	ds_read_b128 v[186:189], v171 offset:20480
	ds_read_b128 v[190:193], v171 offset:21504
	ds_read_b128 v[194:197], v171 offset:22528
	ds_read_b128 v[198:201], v171 offset:23552
	global_load_lds_dwordx4 v[220:221], off
	v_lshl_add_u64 v[222:223], s[42:43], 0, v[156:157]
	s_mov_b32 m0, s7
	s_nop 0
	global_load_lds_dwordx4 v[222:223], off
	s_waitcnt vmcnt(10)
	s_barrier
	s_waitcnt lgkmcnt(0)
	s_waitcnt lgkmcnt(0)
	v_mfma_f32_16x16x32_bf16 v[62:65], v[130:133], v[146:149], v[62:65]
	v_mfma_f32_16x16x32_bf16 v[58:61], v[138:141], v[146:149], v[58:61]
	v_mfma_f32_16x16x32_bf16 v[50:53], v[130:133], v[178:181], v[50:53]
	v_mfma_f32_16x16x32_bf16 v[42:45], v[138:141], v[178:181], v[42:45]
	v_mfma_f32_16x16x32_bf16 v[34:37], v[130:133], v[186:189], v[34:37]
	v_mfma_f32_16x16x32_bf16 v[26:29], v[138:141], v[186:189], v[26:29]
	v_mfma_f32_16x16x32_bf16 v[18:21], v[130:133], v[194:197], v[18:21]
	v_mfma_f32_16x16x32_bf16 v[10:13], v[138:141], v[194:197], v[10:13]
	v_mfma_f32_16x16x32_bf16 v[62:65], v[134:137], v[174:177], v[62:65]
	v_mfma_f32_16x16x32_bf16 v[58:61], v[142:145], v[174:177], v[58:61]
	v_mfma_f32_16x16x32_bf16 v[50:53], v[134:137], v[182:185], v[50:53]
	v_mfma_f32_16x16x32_bf16 v[42:45], v[142:145], v[182:185], v[42:45]
	v_mfma_f32_16x16x32_bf16 v[34:37], v[134:137], v[190:193], v[34:37]
	v_mfma_f32_16x16x32_bf16 v[26:29], v[142:145], v[190:193], v[26:29]
	v_mfma_f32_16x16x32_bf16 v[18:21], v[134:137], v[198:201], v[18:21]
	v_mfma_f32_16x16x32_bf16 v[10:13], v[142:145], v[198:201], v[10:13]
	s_barrier
	s_add_u32 s0, s40, 0x40000
	s_addc_u32 s1, s41, 0
	s_mov_b32 m0, s54
	v_lshl_add_u64 v[130:131], s[0:1], 0, v[158:159]
	global_load_lds_dwordx4 v[130:131], off
	v_lshl_add_u64 v[130:131], s[0:1], 0, v[154:155]
	s_add_i32 m0, s54, 0x2000
	s_nop 0
	global_load_lds_dwordx4 v[130:131], off
	s_waitcnt vmcnt(10)
	s_barrier
	v_mfma_f32_16x16x32_bf16 v[54:57], v[202:205], v[146:149], v[54:57]
	v_mfma_f32_16x16x32_bf16 v[46:49], v[210:213], v[146:149], v[46:49]
	v_mfma_f32_16x16x32_bf16 v[38:41], v[202:205], v[178:181], v[38:41]
	v_mfma_f32_16x16x32_bf16 v[30:33], v[210:213], v[178:181], v[30:33]
	v_mfma_f32_16x16x32_bf16 v[22:25], v[202:205], v[186:189], v[22:25]
	v_mfma_f32_16x16x32_bf16 v[14:17], v[210:213], v[186:189], v[14:17]
	v_mfma_f32_16x16x32_bf16 v[6:9], v[202:205], v[194:197], v[6:9]
	v_mfma_f32_16x16x32_bf16 v[2:5], v[210:213], v[194:197], v[2:5]
	v_mfma_f32_16x16x32_bf16 v[54:57], v[206:209], v[174:177], v[54:57]
	v_mfma_f32_16x16x32_bf16 v[46:49], v[214:217], v[174:177], v[46:49]
	v_mfma_f32_16x16x32_bf16 v[38:41], v[206:209], v[182:185], v[38:41]
	v_mfma_f32_16x16x32_bf16 v[30:33], v[214:217], v[182:185], v[30:33]
	v_mfma_f32_16x16x32_bf16 v[22:25], v[206:209], v[190:193], v[22:25]
	v_mfma_f32_16x16x32_bf16 v[14:17], v[214:217], v[190:193], v[14:17]
	v_mfma_f32_16x16x32_bf16 v[6:9], v[206:209], v[198:201], v[6:9]
	v_mfma_f32_16x16x32_bf16 v[2:5], v[214:217], v[198:201], v[2:5]
	s_add_i32 s70, 0, 0x18000
	v_add_u32_e32 v142, s70, v169
	s_barrier
	ds_read_b128 v[130:133], v142
	ds_read_b128 v[134:137], v142 offset:1024
	ds_read_b128 v[138:141], v142 offset:2048
	ds_read_b128 v[142:145], v142 offset:3072
	s_add_u32 s0, s42, 0x40000
	s_addc_u32 s1, s43, 0
	s_mov_b32 m0, s10
	v_lshl_add_u64 v[202:203], s[0:1], 0, v[160:161]
	ds_read_b128 v[146:149], v171 offset:32768
	ds_read_b128 v[174:177], v171 offset:33792
	ds_read_b128 v[178:181], v171 offset:34816
	ds_read_b128 v[182:185], v171 offset:35840
	ds_read_b128 v[186:189], v171 offset:36864
	ds_read_b128 v[190:193], v171 offset:37888
	ds_read_b128 v[194:197], v171 offset:38912
	ds_read_b128 v[198:201], v171 offset:39936
	global_load_lds_dwordx4 v[202:203], off
	v_lshl_add_u64 v[202:203], s[0:1], 0, v[156:157]
	s_mov_b32 m0, s11
	s_nop 0
	global_load_lds_dwordx4 v[202:203], off
	s_waitcnt lgkmcnt(8)
	s_waitcnt vmcnt(10)
	s_barrier
	s_waitcnt lgkmcnt(0)
	s_waitcnt lgkmcnt(0)
	v_mfma_f32_16x16x32_bf16 v[126:129], v[130:133], v[146:149], v[126:129]
	v_mfma_f32_16x16x32_bf16 v[122:125], v[138:141], v[146:149], v[122:125]
	v_mfma_f32_16x16x32_bf16 v[118:121], v[130:133], v[178:181], v[118:121]
	v_mfma_f32_16x16x32_bf16 v[110:113], v[138:141], v[178:181], v[110:113]
	v_mfma_f32_16x16x32_bf16 v[98:101], v[130:133], v[186:189], v[98:101]
	v_mfma_f32_16x16x32_bf16 v[90:93], v[138:141], v[186:189], v[90:93]
	v_mfma_f32_16x16x32_bf16 v[82:85], v[130:133], v[194:197], v[82:85]
	v_mfma_f32_16x16x32_bf16 v[74:77], v[138:141], v[194:197], v[74:77]
	v_mfma_f32_16x16x32_bf16 v[126:129], v[134:137], v[174:177], v[126:129]
	v_mfma_f32_16x16x32_bf16 v[122:125], v[142:145], v[174:177], v[122:125]
	v_mfma_f32_16x16x32_bf16 v[118:121], v[134:137], v[182:185], v[118:121]
	v_mfma_f32_16x16x32_bf16 v[110:113], v[142:145], v[182:185], v[110:113]
	v_mfma_f32_16x16x32_bf16 v[98:101], v[134:137], v[190:193], v[98:101]
	v_mfma_f32_16x16x32_bf16 v[90:93], v[142:145], v[190:193], v[90:93]
	v_mfma_f32_16x16x32_bf16 v[82:85], v[134:137], v[198:201], v[82:85]
	v_mfma_f32_16x16x32_bf16 v[74:77], v[142:145], v[198:201], v[74:77]
	s_barrier
	s_add_i32 s42, 0, 0x1c000
	s_add_i32 s0, s70, s5
	v_add_u32_e32 v173, s42, v169
	v_lshl_add_u64 v[166:167], v[166:167], 0, s[28:29]
	s_mov_b32 m0, s0
	ds_read_b128 v[202:205], v173
	ds_read_b128 v[206:209], v173 offset:1024
	ds_read_b128 v[210:213], v173 offset:2048
	ds_read_b128 v[214:217], v173 offset:3072
	global_load_lds_dwordx4 v[166:167], off
	v_lshl_add_u64 v[166:167], v[218:219], 0, s[28:29]
	s_add_i32 m0, s0, 0x2000
	s_nop 0
	global_load_lds_dwordx4 v[166:167], off
	s_waitcnt vmcnt(10)
	s_barrier
	s_waitcnt lgkmcnt(0)
	s_waitcnt lgkmcnt(0)
	v_mfma_f32_16x16x32_bf16 v[114:117], v[202:205], v[146:149], v[114:117]
	v_mfma_f32_16x16x32_bf16 v[106:109], v[210:213], v[146:149], v[106:109]
	v_mfma_f32_16x16x32_bf16 v[102:105], v[202:205], v[178:181], v[102:105]
	v_mfma_f32_16x16x32_bf16 v[94:97], v[210:213], v[178:181], v[94:97]
	v_mfma_f32_16x16x32_bf16 v[86:89], v[202:205], v[186:189], v[86:89]
	v_mfma_f32_16x16x32_bf16 v[78:81], v[210:213], v[186:189], v[78:81]
	v_mfma_f32_16x16x32_bf16 v[70:73], v[202:205], v[194:197], v[70:73]
	v_mfma_f32_16x16x32_bf16 v[66:69], v[210:213], v[194:197], v[66:69]
	v_mfma_f32_16x16x32_bf16 v[114:117], v[206:209], v[174:177], v[114:117]
	v_mfma_f32_16x16x32_bf16 v[106:109], v[214:217], v[174:177], v[106:109]
	v_mfma_f32_16x16x32_bf16 v[102:105], v[206:209], v[182:185], v[102:105]
	v_mfma_f32_16x16x32_bf16 v[94:97], v[214:217], v[182:185], v[94:97]
	v_mfma_f32_16x16x32_bf16 v[86:89], v[206:209], v[190:193], v[86:89]
	v_mfma_f32_16x16x32_bf16 v[78:81], v[214:217], v[190:193], v[78:81]
	v_mfma_f32_16x16x32_bf16 v[70:73], v[206:209], v[198:201], v[70:73]
	v_mfma_f32_16x16x32_bf16 v[66:69], v[214:217], v[198:201], v[66:69]
	s_mov_b32 m0, s48
	v_lshl_add_u64 v[166:167], v[220:221], 0, s[28:29]
	s_barrier
	ds_read_b128 v[146:149], v171 offset:49152
	ds_read_b128 v[174:177], v171 offset:50176
	ds_read_b128 v[178:181], v171 offset:51200
	ds_read_b128 v[182:185], v171 offset:52224
	ds_read_b128 v[186:189], v171 offset:53248
	ds_read_b128 v[190:193], v171 offset:54272
	ds_read_b128 v[194:197], v171 offset:55296
	ds_read_b128 v[198:201], v171 offset:56320
	global_load_lds_dwordx4 v[166:167], off
	v_lshl_add_u64 v[166:167], v[222:223], 0, s[28:29]
	s_mov_b32 m0, s49
	s_nop 0
	global_load_lds_dwordx4 v[166:167], off
	s_waitcnt vmcnt(10)
	s_barrier
	s_waitcnt lgkmcnt(0)
	s_waitcnt lgkmcnt(0)
	v_mfma_f32_16x16x32_bf16 v[62:65], v[130:133], v[146:149], v[62:65]
	v_mfma_f32_16x16x32_bf16 v[58:61], v[138:141], v[146:149], v[58:61]
	v_mfma_f32_16x16x32_bf16 v[50:53], v[130:133], v[178:181], v[50:53]
	v_mfma_f32_16x16x32_bf16 v[42:45], v[138:141], v[178:181], v[42:45]
	v_mfma_f32_16x16x32_bf16 v[34:37], v[130:133], v[186:189], v[34:37]
	v_mfma_f32_16x16x32_bf16 v[26:29], v[138:141], v[186:189], v[26:29]
	v_mfma_f32_16x16x32_bf16 v[18:21], v[130:133], v[194:197], v[18:21]
	v_mfma_f32_16x16x32_bf16 v[10:13], v[138:141], v[194:197], v[10:13]
	v_mfma_f32_16x16x32_bf16 v[62:65], v[134:137], v[174:177], v[62:65]
	v_mfma_f32_16x16x32_bf16 v[58:61], v[142:145], v[174:177], v[58:61]
	v_mfma_f32_16x16x32_bf16 v[50:53], v[134:137], v[182:185], v[50:53]
	v_mfma_f32_16x16x32_bf16 v[42:45], v[142:145], v[182:185], v[42:45]
	v_mfma_f32_16x16x32_bf16 v[34:37], v[134:137], v[190:193], v[34:37]
	v_mfma_f32_16x16x32_bf16 v[26:29], v[142:145], v[190:193], v[26:29]
	v_mfma_f32_16x16x32_bf16 v[18:21], v[134:137], v[198:201], v[18:21]
	v_mfma_f32_16x16x32_bf16 v[10:13], v[142:145], v[198:201], v[10:13]
	s_barrier
	s_add_u32 s0, s40, 0x40080
	s_addc_u32 s1, s41, 0
	s_add_i32 s40, s42, s5
	v_lshl_add_u64 v[130:131], s[0:1], 0, v[158:159]
	s_mov_b32 m0, s40
	s_nop 0
	global_load_lds_dwordx4 v[130:131], off
	v_lshl_add_u64 v[130:131], s[0:1], 0, v[154:155]
	s_add_i32 m0, s40, 0x2000
	s_nop 0
	global_load_lds_dwordx4 v[130:131], off
	s_waitcnt vmcnt(10)
	s_barrier
	v_mfma_f32_16x16x32_bf16 v[54:57], v[202:205], v[146:149], v[54:57]
	v_mfma_f32_16x16x32_bf16 v[46:49], v[210:213], v[146:149], v[46:49]
	v_mfma_f32_16x16x32_bf16 v[38:41], v[202:205], v[178:181], v[38:41]
	v_mfma_f32_16x16x32_bf16 v[30:33], v[210:213], v[178:181], v[30:33]
	v_mfma_f32_16x16x32_bf16 v[22:25], v[202:205], v[186:189], v[22:25]
	v_mfma_f32_16x16x32_bf16 v[14:17], v[210:213], v[186:189], v[14:17]
	v_mfma_f32_16x16x32_bf16 v[6:9], v[202:205], v[194:197], v[6:9]
	v_mfma_f32_16x16x32_bf16 v[2:5], v[210:213], v[194:197], v[2:5]
	v_mfma_f32_16x16x32_bf16 v[54:57], v[206:209], v[174:177], v[54:57]
	v_mfma_f32_16x16x32_bf16 v[46:49], v[214:217], v[174:177], v[46:49]
	v_mfma_f32_16x16x32_bf16 v[38:41], v[206:209], v[182:185], v[38:41]
	v_mfma_f32_16x16x32_bf16 v[30:33], v[214:217], v[182:185], v[30:33]
	v_mfma_f32_16x16x32_bf16 v[22:25], v[206:209], v[190:193], v[22:25]
	v_mfma_f32_16x16x32_bf16 v[14:17], v[214:217], v[190:193], v[14:17]
	v_mfma_f32_16x16x32_bf16 v[6:9], v[206:209], v[198:201], v[6:9]
	v_mfma_f32_16x16x32_bf16 v[2:5], v[214:217], v[198:201], v[2:5]
	s_add_i32 s69, s69, 2
	s_add_u32 s64, s64, 0x100
	s_addc_u32 s65, s65, 0
	s_add_u32 s38, s38, 0x100
	s_addc_u32 s39, s39, 0
	s_cmp_gt_u32 s69, 13
	s_barrier
	s_cbranch_scc0 .LBB0_1047
	s_lshl_b32 s0, s58, 8
	v_mov_b32_e32 v130, v151
	v_mov_b32_e32 v131, v153
	s_or_b32 s0, s0, s45
	s_mov_b32 s58, s57
	v_lshl_add_u32 v166, v131, 3, s0
	s_lshl_b32 s0, s59, 8
	s_add_i32 s0, s0, s44
	v_add_u32_e32 v173, s0, v130
	v_mov_b32_e32 v130, v173
	v_ashrrev_i32_e32 v167, 31, v166
	v_ashrrev_i32_e32 v131, 31, v130
	v_lshlrev_b64 v[130:131], 10, v[130:131]
	v_lshl_add_u64 v[130:131], v[130:131], 0, v[166:167]
	v_lshlrev_b64 v[186:187], 1, v[130:131]
	v_lshl_add_u64 v[130:131], s[12:13], 0, v[186:187]
	flat_load_dwordx4 v[174:177], v[130:131]
	flat_load_dwordx4 v[178:181], v[130:131] offset:256
	v_add_co_u32_e32 v132, vcc, s47, v130
	s_mov_b32 s59, s56
	s_nop 0
	v_addc_co_u32_e32 v133, vcc, 0, v131, vcc
	flat_load_dwordx4 v[182:185], v[132:133]
	flat_load_dwordx4 v[146:149], v[132:133] offset:256
	v_add_co_u32_e32 v132, vcc, s31, v130
	s_waitcnt vmcnt(0) lgkmcnt(0)
	v_lshlrev_b32_e32 v188, 16, v174
	v_addc_co_u32_e32 v133, vcc, 0, v131, vcc
	flat_load_dwordx4 v[142:145], v[132:133]
	flat_load_dwordx4 v[138:141], v[132:133] offset:256
	v_add_co_u32_e32 v130, vcc, s46, v130
	v_and_b32_e32 v189, 0xffff0000, v174
	s_nop 0
	v_addc_co_u32_e32 v131, vcc, 0, v131, vcc
	flat_load_dwordx4 v[134:137], v[130:131]
	s_nop 0
	flat_load_dwordx4 v[130:133], v[130:131] offset:256
	v_lshlrev_b32_e32 v174, 16, v175
	v_and_b32_e32 v175, 0xffff0000, v175
	v_lshlrev_b32_e32 v190, 16, v176
	v_and_b32_e32 v191, 0xffff0000, v176
	v_lshlrev_b32_e32 v176, 16, v177
	v_and_b32_e32 v177, 0xffff0000, v177
	v_pk_fma_f32 v[128:129], v[174:175], s[30:31], v[128:129] op_sel_hi:[1,0,1]
	v_pk_fma_f32 v[126:127], v[188:189], s[30:31], v[126:127] op_sel_hi:[1,0,1]
	v_pk_fma_f32 v[174:175], v[176:177], s[30:31], v[124:125] op_sel_hi:[1,0,1]
	v_pk_fma_f32 v[122:123], v[190:191], s[30:31], v[122:123] op_sel_hi:[1,0,1]
	v_cvt_pk_bf16_f32 v124, v126, v127
	v_cvt_pk_bf16_f32 v125, v128, v129
	v_cvt_pk_bf16_f32 v126, v122, v123
	v_cvt_pk_bf16_f32 v127, v174, v175
	v_lshl_add_u64 v[122:123], s[24:25], 0, v[186:187]
	flat_store_dwordx4 v[122:123], v[124:127]
	v_lshlrev_b32_e32 v128, 16, v180
	v_and_b32_e32 v129, 0xffff0000, v180
	v_lshlrev_b32_e32 v124, 16, v178
	v_and_b32_e32 v125, 0xffff0000, v178
	v_lshlrev_b32_e32 v126, 16, v179
	v_and_b32_e32 v127, 0xffff0000, v179
	v_lshlrev_b32_e32 v174, 16, v181
	v_and_b32_e32 v175, 0xffff0000, v181
	v_pk_fma_f32 v[116:117], v[126:127], s[30:31], v[116:117] op_sel_hi:[1,0,1]
	v_pk_fma_f32 v[114:115], v[124:125], s[30:31], v[114:115] op_sel_hi:[1,0,1]
	v_pk_fma_f32 v[124:125], v[174:175], s[30:31], v[108:109] op_sel_hi:[1,0,1]
	v_pk_fma_f32 v[108:109], v[128:129], s[30:31], v[106:107] op_sel_hi:[1,0,1]
	v_cvt_pk_bf16_f32 v106, v114, v115
	v_cvt_pk_bf16_f32 v107, v116, v117
	v_cvt_pk_bf16_f32 v108, v108, v109
	v_cvt_pk_bf16_f32 v109, v124, v125
	flat_store_dwordx4 v[122:123], v[106:109] offset:256
	v_lshlrev_b32_e32 v114, 16, v184
	v_and_b32_e32 v115, 0xffff0000, v184
	v_lshlrev_b32_e32 v106, 16, v182
	v_and_b32_e32 v107, 0xffff0000, v182
	v_lshlrev_b32_e32 v108, 16, v183
	v_and_b32_e32 v109, 0xffff0000, v183
	v_lshlrev_b32_e32 v116, 16, v185
	v_and_b32_e32 v117, 0xffff0000, v185
	v_pk_fma_f32 v[108:109], v[108:109], s[30:31], v[120:121] op_sel_hi:[1,0,1]
	v_pk_fma_f32 v[106:107], v[106:107], s[30:31], v[118:119] op_sel_hi:[1,0,1]
	v_pk_fma_f32 v[110:111], v[114:115], s[30:31], v[110:111] op_sel_hi:[1,0,1]
	v_pk_fma_f32 v[112:113], v[116:117], s[30:31], v[112:113] op_sel_hi:[1,0,1]
	v_cvt_pk_bf16_f32 v106, v106, v107
	v_cvt_pk_bf16_f32 v107, v108, v109
	v_cvt_pk_bf16_f32 v108, v110, v111
	v_add_co_u32_e32 v110, vcc, s47, v122
	v_cvt_pk_bf16_f32 v109, v112, v113
	s_nop 0
	v_addc_co_u32_e32 v111, vcc, 0, v123, vcc
	flat_store_dwordx4 v[110:111], v[106:109]
	v_lshlrev_b32_e32 v112, 16, v148
	v_and_b32_e32 v113, 0xffff0000, v148
	v_lshlrev_b32_e32 v106, 16, v146
	v_and_b32_e32 v107, 0xffff0000, v146
	v_lshlrev_b32_e32 v108, 16, v147
	v_and_b32_e32 v109, 0xffff0000, v147
	v_lshlrev_b32_e32 v114, 16, v149
	v_and_b32_e32 v115, 0xffff0000, v149
	v_pk_fma_f32 v[104:105], v[108:109], s[30:31], v[104:105] op_sel_hi:[1,0,1]
	v_pk_fma_f32 v[102:103], v[106:107], s[30:31], v[102:103] op_sel_hi:[1,0,1]
	v_pk_fma_f32 v[106:107], v[114:115], s[30:31], v[96:97] op_sel_hi:[1,0,1]
	v_pk_fma_f32 v[96:97], v[112:113], s[30:31], v[94:95] op_sel_hi:[1,0,1]
	v_cvt_pk_bf16_f32 v94, v102, v103
	v_cvt_pk_bf16_f32 v95, v104, v105
	v_cvt_pk_bf16_f32 v96, v96, v97
	v_cvt_pk_bf16_f32 v97, v106, v107
	flat_store_dwordx4 v[110:111], v[94:97] offset:256
	s_waitcnt vmcnt(0) lgkmcnt(0)
	v_lshlrev_b32_e32 v102, 16, v144
	v_lshlrev_b32_e32 v94, 16, v142
	v_and_b32_e32 v95, 0xffff0000, v142
	v_lshlrev_b32_e32 v96, 16, v143
	v_and_b32_e32 v97, 0xffff0000, v143
	v_and_b32_e32 v103, 0xffff0000, v144
	v_lshlrev_b32_e32 v104, 16, v145
	v_and_b32_e32 v105, 0xffff0000, v145
	v_pk_fma_f32 v[94:95], v[94:95], s[30:31], v[98:99] op_sel_hi:[1,0,1]
	v_pk_fma_f32 v[96:97], v[96:97], s[30:31], v[100:101] op_sel_hi:[1,0,1]
	v_pk_fma_f32 v[98:99], v[104:105], s[30:31], v[92:93] op_sel_hi:[1,0,1]
	v_pk_fma_f32 v[92:93], v[102:103], s[30:31], v[90:91] op_sel_hi:[1,0,1]
	v_cvt_pk_bf16_f32 v90, v94, v95
	v_add_co_u32_e32 v94, vcc, s31, v122
	v_cvt_pk_bf16_f32 v91, v96, v97
	v_cvt_pk_bf16_f32 v92, v92, v93
	v_cvt_pk_bf16_f32 v93, v98, v99
	v_addc_co_u32_e32 v95, vcc, 0, v123, vcc
	flat_store_dwordx4 v[94:95], v[90:93]
	v_lshlrev_b32_e32 v96, 16, v140
	v_and_b32_e32 v97, 0xffff0000, v140
	v_lshlrev_b32_e32 v90, 16, v138
	v_and_b32_e32 v91, 0xffff0000, v138
	v_lshlrev_b32_e32 v92, 16, v139
	v_and_b32_e32 v93, 0xffff0000, v139
	v_lshlrev_b32_e32 v98, 16, v141
	v_and_b32_e32 v99, 0xffff0000, v141
	v_pk_fma_f32 v[88:89], v[92:93], s[30:31], v[88:89] op_sel_hi:[1,0,1]
	v_pk_fma_f32 v[86:87], v[90:91], s[30:31], v[86:87] op_sel_hi:[1,0,1]
	v_pk_fma_f32 v[90:91], v[98:99], s[30:31], v[80:81] op_sel_hi:[1,0,1]
	v_pk_fma_f32 v[80:81], v[96:97], s[30:31], v[78:79] op_sel_hi:[1,0,1]
	v_cvt_pk_bf16_f32 v78, v86, v87
	v_cvt_pk_bf16_f32 v79, v88, v89
	v_cvt_pk_bf16_f32 v80, v80, v81
	v_cvt_pk_bf16_f32 v81, v90, v91
	flat_store_dwordx4 v[94:95], v[78:81] offset:256
	v_lshlrev_b32_e32 v86, 16, v136
	v_and_b32_e32 v87, 0xffff0000, v136
	v_lshlrev_b32_e32 v78, 16, v134
	v_and_b32_e32 v79, 0xffff0000, v134
	v_lshlrev_b32_e32 v80, 16, v135
	v_and_b32_e32 v81, 0xffff0000, v135
	v_lshlrev_b32_e32 v88, 16, v137
	v_and_b32_e32 v89, 0xffff0000, v137
	v_pk_fma_f32 v[78:79], v[78:79], s[30:31], v[82:83] op_sel_hi:[1,0,1]
	v_pk_fma_f32 v[80:81], v[80:81], s[30:31], v[84:85] op_sel_hi:[1,0,1]
	v_pk_fma_f32 v[82:83], v[88:89], s[30:31], v[76:77] op_sel_hi:[1,0,1]
	v_pk_fma_f32 v[76:77], v[86:87], s[30:31], v[74:75] op_sel_hi:[1,0,1]
	v_cvt_pk_bf16_f32 v74, v78, v79
	v_add_co_u32_e32 v78, vcc, s46, v122
	v_cvt_pk_bf16_f32 v75, v80, v81
	v_cvt_pk_bf16_f32 v76, v76, v77
	v_cvt_pk_bf16_f32 v77, v82, v83
	v_addc_co_u32_e32 v79, vcc, 0, v123, vcc
	flat_store_dwordx4 v[78:79], v[74:77]
	v_lshlrev_b32_e32 v80, 16, v132
	v_and_b32_e32 v81, 0xffff0000, v132
	v_lshlrev_b32_e32 v74, 16, v130
	v_and_b32_e32 v75, 0xffff0000, v130
	v_lshlrev_b32_e32 v76, 16, v131
	v_and_b32_e32 v77, 0xffff0000, v131
	v_lshlrev_b32_e32 v82, 16, v133
	v_and_b32_e32 v83, 0xffff0000, v133
	v_pk_fma_f32 v[72:73], v[76:77], s[30:31], v[72:73] op_sel_hi:[1,0,1]
	v_pk_fma_f32 v[70:71], v[74:75], s[30:31], v[70:71] op_sel_hi:[1,0,1]
	v_pk_fma_f32 v[74:75], v[82:83], s[30:31], v[68:69] op_sel_hi:[1,0,1]
	v_pk_fma_f32 v[68:69], v[80:81], s[30:31], v[66:67] op_sel_hi:[1,0,1]
	v_cvt_pk_bf16_f32 v66, v70, v71
	v_cvt_pk_bf16_f32 v67, v72, v73
	v_cvt_pk_bf16_f32 v68, v68, v69
	v_cvt_pk_bf16_f32 v69, v74, v75
	flat_store_dwordx4 v[78:79], v[66:69] offset:256
	s_nop 1
	v_add_u32_e32 v66, 0x80, v173
	s_nop 0
	v_ashrrev_i32_e32 v67, 31, v66
	v_lshlrev_b64 v[66:67], 10, v[66:67]
	v_lshl_add_u64 v[66:67], v[66:67], 0, v[166:167]
	v_lshlrev_b64 v[98:99], 1, v[66:67]
	v_lshl_add_u64 v[90:91], s[12:13], 0, v[98:99]
	flat_load_dwordx4 v[66:69], v[90:91]
	flat_load_dwordx4 v[70:73], v[90:91] offset:256
	v_add_co_u32_e32 v78, vcc, s47, v90
	s_waitcnt vmcnt(0) lgkmcnt(0)
	v_lshlrev_b32_e32 v100, 16, v66
	v_addc_co_u32_e32 v79, vcc, 0, v91, vcc
	flat_load_dwordx4 v[74:77], v[78:79]
	s_nop 0
	flat_load_dwordx4 v[78:81], v[78:79] offset:256
	v_add_co_u32_e32 v86, vcc, s31, v90
	v_and_b32_e32 v101, 0xffff0000, v66
	s_nop 0
	v_addc_co_u32_e32 v87, vcc, 0, v91, vcc
	flat_load_dwordx4 v[82:85], v[86:87]
	s_nop 0
	flat_load_dwordx4 v[86:89], v[86:87] offset:256
	v_add_co_u32_e32 v94, vcc, s46, v90
	v_lshlrev_b32_e32 v66, 16, v67
	s_nop 0
	v_addc_co_u32_e32 v95, vcc, 0, v91, vcc
	flat_load_dwordx4 v[90:93], v[94:95]
	s_nop 0
	flat_load_dwordx4 v[94:97], v[94:95] offset:256
	v_and_b32_e32 v67, 0xffff0000, v67
	v_lshlrev_b32_e32 v102, 16, v68
	v_and_b32_e32 v103, 0xffff0000, v68
	v_lshlrev_b32_e32 v68, 16, v69
	v_and_b32_e32 v69, 0xffff0000, v69
	v_pk_fma_f32 v[64:65], v[66:67], s[30:31], v[64:65] op_sel_hi:[1,0,1]
	v_pk_fma_f32 v[62:63], v[100:101], s[30:31], v[62:63] op_sel_hi:[1,0,1]
	v_pk_fma_f32 v[66:67], v[68:69], s[30:31], v[60:61] op_sel_hi:[1,0,1]
	v_pk_fma_f32 v[60:61], v[102:103], s[30:31], v[58:59] op_sel_hi:[1,0,1]
	v_cvt_pk_bf16_f32 v58, v62, v63
	v_cvt_pk_bf16_f32 v59, v64, v65
	v_cvt_pk_bf16_f32 v60, v60, v61
	v_cvt_pk_bf16_f32 v61, v66, v67
	v_lshl_add_u64 v[62:63], s[24:25], 0, v[98:99]
	flat_store_dwordx4 v[62:63], v[58:61]
	v_lshlrev_b32_e32 v64, 16, v72
	v_and_b32_e32 v65, 0xffff0000, v72
	v_lshlrev_b32_e32 v58, 16, v70
	v_and_b32_e32 v59, 0xffff0000, v70
	v_lshlrev_b32_e32 v60, 16, v71
	v_and_b32_e32 v61, 0xffff0000, v71
	v_lshlrev_b32_e32 v66, 16, v73
	v_and_b32_e32 v67, 0xffff0000, v73
	v_pk_fma_f32 v[56:57], v[60:61], s[30:31], v[56:57] op_sel_hi:[1,0,1]
	v_pk_fma_f32 v[54:55], v[58:59], s[30:31], v[54:55] op_sel_hi:[1,0,1]
	v_pk_fma_f32 v[58:59], v[66:67], s[30:31], v[48:49] op_sel_hi:[1,0,1]
	v_pk_fma_f32 v[48:49], v[64:65], s[30:31], v[46:47] op_sel_hi:[1,0,1]
	v_cvt_pk_bf16_f32 v46, v54, v55
	v_cvt_pk_bf16_f32 v47, v56, v57
	v_cvt_pk_bf16_f32 v48, v48, v49
	v_cvt_pk_bf16_f32 v49, v58, v59
	flat_store_dwordx4 v[62:63], v[46:49] offset:256
	s_waitcnt vmcnt(0) lgkmcnt(0)
	v_lshlrev_b32_e32 v54, 16, v76
	v_lshlrev_b32_e32 v46, 16, v74
	v_and_b32_e32 v47, 0xffff0000, v74
	v_lshlrev_b32_e32 v48, 16, v75
	v_and_b32_e32 v49, 0xffff0000, v75
	v_and_b32_e32 v55, 0xffff0000, v76
	v_lshlrev_b32_e32 v56, 16, v77
	v_and_b32_e32 v57, 0xffff0000, v77
	v_pk_fma_f32 v[46:47], v[46:47], s[30:31], v[50:51] op_sel_hi:[1,0,1]
	v_pk_fma_f32 v[48:49], v[48:49], s[30:31], v[52:53] op_sel_hi:[1,0,1]
	v_pk_fma_f32 v[50:51], v[56:57], s[30:31], v[44:45] op_sel_hi:[1,0,1]
	v_pk_fma_f32 v[44:45], v[54:55], s[30:31], v[42:43] op_sel_hi:[1,0,1]
	v_cvt_pk_bf16_f32 v42, v46, v47
	v_add_co_u32_e32 v46, vcc, s47, v62
	v_cvt_pk_bf16_f32 v43, v48, v49
	v_cvt_pk_bf16_f32 v44, v44, v45
	v_cvt_pk_bf16_f32 v45, v50, v51
	v_addc_co_u32_e32 v47, vcc, 0, v63, vcc
	flat_store_dwordx4 v[46:47], v[42:45]
	v_lshlrev_b32_e32 v48, 16, v80
	v_and_b32_e32 v49, 0xffff0000, v80
	v_lshlrev_b32_e32 v42, 16, v78
	v_and_b32_e32 v43, 0xffff0000, v78
	v_lshlrev_b32_e32 v44, 16, v79
	v_and_b32_e32 v45, 0xffff0000, v79
	v_lshlrev_b32_e32 v50, 16, v81
	v_and_b32_e32 v51, 0xffff0000, v81
	v_pk_fma_f32 v[40:41], v[44:45], s[30:31], v[40:41] op_sel_hi:[1,0,1]
	v_pk_fma_f32 v[38:39], v[42:43], s[30:31], v[38:39] op_sel_hi:[1,0,1]
	v_pk_fma_f32 v[42:43], v[50:51], s[30:31], v[32:33] op_sel_hi:[1,0,1]
	v_pk_fma_f32 v[32:33], v[48:49], s[30:31], v[30:31] op_sel_hi:[1,0,1]
	v_cvt_pk_bf16_f32 v30, v38, v39
	v_cvt_pk_bf16_f32 v31, v40, v41
	v_cvt_pk_bf16_f32 v32, v32, v33
	v_cvt_pk_bf16_f32 v33, v42, v43
	flat_store_dwordx4 v[46:47], v[30:33] offset:256
	v_lshlrev_b32_e32 v38, 16, v84
	v_and_b32_e32 v39, 0xffff0000, v84
	v_lshlrev_b32_e32 v30, 16, v82
	v_and_b32_e32 v31, 0xffff0000, v82
	v_lshlrev_b32_e32 v32, 16, v83
	v_and_b32_e32 v33, 0xffff0000, v83
	v_lshlrev_b32_e32 v40, 16, v85
	v_and_b32_e32 v41, 0xffff0000, v85
	v_pk_fma_f32 v[30:31], v[30:31], s[30:31], v[34:35] op_sel_hi:[1,0,1]
	v_pk_fma_f32 v[32:33], v[32:33], s[30:31], v[36:37] op_sel_hi:[1,0,1]
	v_pk_fma_f32 v[34:35], v[40:41], s[30:31], v[28:29] op_sel_hi:[1,0,1]
	v_pk_fma_f32 v[28:29], v[38:39], s[30:31], v[26:27] op_sel_hi:[1,0,1]
	v_cvt_pk_bf16_f32 v26, v30, v31
	v_add_co_u32_e32 v30, vcc, s31, v62
	v_cvt_pk_bf16_f32 v27, v32, v33
	v_cvt_pk_bf16_f32 v28, v28, v29
	v_cvt_pk_bf16_f32 v29, v34, v35
	v_addc_co_u32_e32 v31, vcc, 0, v63, vcc
	flat_store_dwordx4 v[30:31], v[26:29]
	v_lshlrev_b32_e32 v32, 16, v88
	v_and_b32_e32 v33, 0xffff0000, v88
	v_lshlrev_b32_e32 v26, 16, v86
	v_and_b32_e32 v27, 0xffff0000, v86
	v_lshlrev_b32_e32 v28, 16, v87
	v_and_b32_e32 v29, 0xffff0000, v87
	v_lshlrev_b32_e32 v34, 16, v89
	v_and_b32_e32 v35, 0xffff0000, v89
	v_pk_fma_f32 v[24:25], v[28:29], s[30:31], v[24:25] op_sel_hi:[1,0,1]
	v_pk_fma_f32 v[22:23], v[26:27], s[30:31], v[22:23] op_sel_hi:[1,0,1]
	v_pk_fma_f32 v[26:27], v[34:35], s[30:31], v[16:17] op_sel_hi:[1,0,1]
	v_pk_fma_f32 v[16:17], v[32:33], s[30:31], v[14:15] op_sel_hi:[1,0,1]
	v_cvt_pk_bf16_f32 v14, v22, v23
	v_cvt_pk_bf16_f32 v15, v24, v25
	v_cvt_pk_bf16_f32 v16, v16, v17
	v_cvt_pk_bf16_f32 v17, v26, v27
	flat_store_dwordx4 v[30:31], v[14:17] offset:256
	v_lshlrev_b32_e32 v22, 16, v92
	v_and_b32_e32 v23, 0xffff0000, v92
	v_lshlrev_b32_e32 v14, 16, v90
	v_and_b32_e32 v15, 0xffff0000, v90
	v_lshlrev_b32_e32 v16, 16, v91
	v_and_b32_e32 v17, 0xffff0000, v91
	v_lshlrev_b32_e32 v24, 16, v93
	v_and_b32_e32 v25, 0xffff0000, v93
	v_pk_fma_f32 v[14:15], v[14:15], s[30:31], v[18:19] op_sel_hi:[1,0,1]
	v_pk_fma_f32 v[16:17], v[16:17], s[30:31], v[20:21] op_sel_hi:[1,0,1]
	v_pk_fma_f32 v[18:19], v[24:25], s[30:31], v[12:13] op_sel_hi:[1,0,1]
	v_pk_fma_f32 v[12:13], v[22:23], s[30:31], v[10:11] op_sel_hi:[1,0,1]
	v_cvt_pk_bf16_f32 v10, v14, v15
	v_add_co_u32_e32 v14, vcc, s46, v62
	v_cvt_pk_bf16_f32 v11, v16, v17
	v_cvt_pk_bf16_f32 v12, v12, v13
	v_cvt_pk_bf16_f32 v13, v18, v19
	v_addc_co_u32_e32 v15, vcc, 0, v63, vcc
	flat_store_dwordx4 v[14:15], v[10:13]
	v_lshlrev_b32_e32 v16, 16, v96
	v_and_b32_e32 v17, 0xffff0000, v96
	v_lshlrev_b32_e32 v10, 16, v94
	v_and_b32_e32 v11, 0xffff0000, v94
	v_lshlrev_b32_e32 v12, 16, v95
	v_and_b32_e32 v13, 0xffff0000, v95
	v_lshlrev_b32_e32 v18, 16, v97
	v_and_b32_e32 v19, 0xffff0000, v97
	v_pk_fma_f32 v[8:9], v[12:13], s[30:31], v[8:9] op_sel_hi:[1,0,1]
	v_pk_fma_f32 v[6:7], v[10:11], s[30:31], v[6:7] op_sel_hi:[1,0,1]
	v_pk_fma_f32 v[10:11], v[18:19], s[30:31], v[4:5] op_sel_hi:[1,0,1]
	v_pk_fma_f32 v[4:5], v[16:17], s[30:31], v[2:3] op_sel_hi:[1,0,1]
	v_cvt_pk_bf16_f32 v2, v6, v7
	v_cvt_pk_bf16_f32 v3, v8, v9
	v_cvt_pk_bf16_f32 v4, v4, v5
	v_cvt_pk_bf16_f32 v5, v10, v11
	s_and_b64 vcc, exec, s[34:35]
	flat_store_dwordx4 v[14:15], v[2:5] offset:256
	s_cbranch_vccz .LBB0_1046
	s_waitcnt vmcnt(0)
	s_cmpk_gt_u32 s4, 0xff
	s_cbranch_scc1 .LBB0_1051
	s_barrier

.LBB0_1302:
	s_add_u32 s12, s36, 0x100
	s_addc_u32 s13, s37, 0
	s_add_u32 s34, s31, s36
	s_addc_u32 s35, s55, s37
	s_cmpk_eq_i32 s36, 0x300
	s_cselect_b64 vcc, -1, 0
	s_and_b64 s[0:1], vcc, exec
	s_cselect_b32 s1, 0, s12
	s_cselect_b32 s0, 0, s13
	s_cselect_b32 s34, s29, s34
	s_cselect_b32 s35, s27, s35
	s_add_u32 s38, s16, s1
	s_addc_u32 s39, s17, s0
	s_add_i32 s1, 0, 0x10000
	v_add_u32_e32 v14, s1, v197
	ds_read_b128 v[2:5], v14
	ds_read_b128 v[6:9], v14 offset:1024
	ds_read_b128 v[10:13], v14 offset:2048
	ds_read_b128 v[14:17], v14 offset:3072
	v_cndmask_b32_e32 v162, v168, v171, vcc
	v_cndmask_b32_e32 v184, v170, v198, vcc
	v_cndmask_b32_e32 v175, v172, v199, vcc
	v_cndmask_b32_e32 v173, v174, v200, vcc
	v_lshl_add_u64 v[18:19], v[178:179], 0, s[36:37]
	s_add_i32 m0, s45, 0xc000
	ds_read_b128 v[202:205], v169
	ds_read_b128 v[206:209], v169 offset:1024
	ds_read_b128 v[210:213], v169 offset:2048
	ds_read_b128 v[214:217], v169 offset:3072
	ds_read_b128 v[218:221], v169 offset:4096
	ds_read_b128 v[222:225], v169 offset:5120
	ds_read_b128 v[226:229], v169 offset:6144
	ds_read_b128 v[230:233], v169 offset:7168
	global_load_lds_dwordx4 v[18:19], off
	v_lshl_add_u64 v[18:19], v[176:177], 0, s[36:37]
	s_add_i32 m0, s45, 0xe000
	s_nop 0
	global_load_lds_dwordx4 v[18:19], off
	s_waitcnt lgkmcnt(8)
	s_waitcnt vmcnt(10)
	s_barrier
	s_waitcnt lgkmcnt(0)
	s_waitcnt lgkmcnt(0)
	v_mfma_scale_f32_16x16x128_f8f6f4 v[158:161], v[2:9], v[202:209], v[158:161], v188, v188 op_sel_hi:[0,0,0]
	v_mfma_scale_f32_16x16x128_f8f6f4 v[150:153], v[10:17], v[202:209], v[150:153], v188, v188 op_sel_hi:[0,0,0]
	v_mfma_scale_f32_16x16x128_f8f6f4 v[142:145], v[2:9], v[210:217], v[142:145], v188, v188 op_sel_hi:[0,0,0]
	v_mfma_scale_f32_16x16x128_f8f6f4 v[134:137], v[10:17], v[210:217], v[134:137], v188, v188 op_sel_hi:[0,0,0]
	v_mfma_scale_f32_16x16x128_f8f6f4 v[126:129], v[2:9], v[218:225], v[126:129], v188, v188 op_sel_hi:[0,0,0]
	v_mfma_scale_f32_16x16x128_f8f6f4 v[118:121], v[10:17], v[218:225], v[118:121], v188, v188 op_sel_hi:[0,0,0]
	v_mfma_scale_f32_16x16x128_f8f6f4 v[110:113], v[2:9], v[226:233], v[110:113], v188, v188 op_sel_hi:[0,0,0]
	v_mfma_scale_f32_16x16x128_f8f6f4 v[102:105], v[10:17], v[226:233], v[102:105], v188, v188 op_sel_hi:[0,0,0]
	s_barrier
	s_add_i32 s0, 0, 0x14000
	s_add_i32 s1, s1, s43
	v_add_u32_e32 v30, s0, v197
	v_lshl_add_u64 v[180:181], s[34:35], 0, v[164:165]
	s_mov_b32 m0, s1
	ds_read_b128 v[18:21], v30
	ds_read_b128 v[22:25], v30 offset:1024
	ds_read_b128 v[26:29], v30 offset:2048
	ds_read_b128 v[30:33], v30 offset:3072
	global_load_lds_dwordx4 v[180:181], off
	v_lshl_add_u64 v[182:183], s[34:35], 0, v[166:167]
	s_add_i32 m0, s1, 0x2000
	s_nop 0
	global_load_lds_dwordx4 v[182:183], off
	s_waitcnt vmcnt(10)
	s_barrier
	s_waitcnt lgkmcnt(0)
	s_waitcnt lgkmcnt(0)
	v_mfma_scale_f32_16x16x128_f8f6f4 v[154:157], v[18:25], v[202:209], v[154:157], v188, v188 op_sel_hi:[0,0,0]
	v_mfma_scale_f32_16x16x128_f8f6f4 v[146:149], v[26:33], v[202:209], v[146:149], v188, v188 op_sel_hi:[0,0,0]
	v_mfma_scale_f32_16x16x128_f8f6f4 v[138:141], v[18:25], v[210:217], v[138:141], v188, v188 op_sel_hi:[0,0,0]
	v_mfma_scale_f32_16x16x128_f8f6f4 v[130:133], v[26:33], v[210:217], v[130:133], v188, v188 op_sel_hi:[0,0,0]
	v_mfma_scale_f32_16x16x128_f8f6f4 v[122:125], v[18:25], v[218:225], v[122:125], v188, v188 op_sel_hi:[0,0,0]
	v_mfma_scale_f32_16x16x128_f8f6f4 v[114:117], v[26:33], v[218:225], v[114:117], v188, v188 op_sel_hi:[0,0,0]
	v_mfma_scale_f32_16x16x128_f8f6f4 v[106:109], v[18:25], v[226:233], v[106:109], v188, v188 op_sel_hi:[0,0,0]
	v_mfma_scale_f32_16x16x128_f8f6f4 v[98:101], v[26:33], v[226:233], v[98:101], v188, v188 op_sel_hi:[0,0,0]
	s_mov_b32 m0, s45
	s_barrier
	ds_read_b128 v[202:205], v169 offset:16384
	ds_read_b128 v[206:209], v169 offset:17408
	ds_read_b128 v[210:213], v169 offset:18432
	ds_read_b128 v[214:217], v169 offset:19456
	ds_read_b128 v[218:221], v169 offset:20480
	ds_read_b128 v[222:225], v169 offset:21504
	ds_read_b128 v[226:229], v169 offset:22528
	ds_read_b128 v[230:233], v169 offset:23552
	global_load_lds_dwordx4 v162, s[38:39]
	s_mov_b32 m0, s46
	v_mov_b32_e32 v185, v163
	global_load_lds_dwordx4 v184, s[38:39]
	s_waitcnt vmcnt(10)
	s_barrier
	s_waitcnt lgkmcnt(0)
	v_lshl_add_u64 v[186:187], s[38:39], 0, v[162:163]
	v_lshl_add_u64 v[184:185], s[38:39], 0, v[184:185]
	s_waitcnt lgkmcnt(0)
	v_mfma_scale_f32_16x16x128_f8f6f4 v[94:97], v[2:9], v[202:209], v[94:97], v188, v188 op_sel_hi:[0,0,0]
	v_mfma_scale_f32_16x16x128_f8f6f4 v[86:89], v[10:17], v[202:209], v[86:89], v188, v188 op_sel_hi:[0,0,0]
	v_mfma_scale_f32_16x16x128_f8f6f4 v[78:81], v[2:9], v[210:217], v[78:81], v188, v188 op_sel_hi:[0,0,0]
	v_mfma_scale_f32_16x16x128_f8f6f4 v[70:73], v[10:17], v[210:217], v[70:73], v188, v188 op_sel_hi:[0,0,0]
	v_mfma_scale_f32_16x16x128_f8f6f4 v[62:65], v[2:9], v[218:225], v[62:65], v188, v188 op_sel_hi:[0,0,0]
	v_mfma_scale_f32_16x16x128_f8f6f4 v[54:57], v[10:17], v[218:225], v[54:57], v188, v188 op_sel_hi:[0,0,0]
	v_mfma_scale_f32_16x16x128_f8f6f4 v[46:49], v[2:9], v[226:233], v[46:49], v188, v188 op_sel_hi:[0,0,0]
	v_mfma_scale_f32_16x16x128_f8f6f4 v[38:41], v[10:17], v[226:233], v[38:41], v188, v188 op_sel_hi:[0,0,0]
	s_barrier
	s_add_u32 s36, s34, 0x20000
	s_addc_u32 s37, s35, 0
	s_add_i32 s0, s0, s43
	v_lshl_add_u64 v[2:3], s[36:37], 0, v[164:165]
	s_mov_b32 m0, s0
	s_nop 0
	global_load_lds_dwordx4 v[2:3], off
	v_lshl_add_u64 v[2:3], s[36:37], 0, v[166:167]
	s_add_i32 m0, s0, 0x2000
	s_nop 0
	global_load_lds_dwordx4 v[2:3], off
	s_waitcnt vmcnt(10)
	s_barrier
	v_mfma_scale_f32_16x16x128_f8f6f4 v[90:93], v[18:25], v[202:209], v[90:93], v188, v188 op_sel_hi:[0,0,0]
	v_mfma_scale_f32_16x16x128_f8f6f4 v[82:85], v[26:33], v[202:209], v[82:85], v188, v188 op_sel_hi:[0,0,0]
	v_mfma_scale_f32_16x16x128_f8f6f4 v[74:77], v[18:25], v[210:217], v[74:77], v188, v188 op_sel_hi:[0,0,0]
	v_mfma_scale_f32_16x16x128_f8f6f4 v[66:69], v[26:33], v[210:217], v[66:69], v188, v188 op_sel_hi:[0,0,0]
	v_mfma_scale_f32_16x16x128_f8f6f4 v[58:61], v[18:25], v[218:225], v[58:61], v188, v188 op_sel_hi:[0,0,0]
	v_mfma_scale_f32_16x16x128_f8f6f4 v[50:53], v[26:33], v[218:225], v[50:53], v188, v188 op_sel_hi:[0,0,0]
	v_mfma_scale_f32_16x16x128_f8f6f4 v[42:45], v[18:25], v[226:233], v[42:45], v188, v188 op_sel_hi:[0,0,0]
	v_mfma_scale_f32_16x16x128_f8f6f4 v[34:37], v[26:33], v[226:233], v[34:37], v188, v188 op_sel_hi:[0,0,0]
	s_add_i32 s0, 0, 0x18000
	v_add_u32_e32 v14, s0, v197
	s_barrier
	ds_read_b128 v[2:5], v14
	ds_read_b128 v[6:9], v14 offset:1024
	ds_read_b128 v[10:13], v14 offset:2048
	ds_read_b128 v[14:17], v14 offset:3072
	s_mov_b32 m0, s47
	ds_read_b128 v[18:21], v169 offset:32768
	ds_read_b128 v[22:25], v169 offset:33792
	ds_read_b128 v[26:29], v169 offset:34816
	ds_read_b128 v[30:33], v169 offset:35840
	ds_read_b128 v[202:205], v169 offset:36864
	ds_read_b128 v[206:209], v169 offset:37888
	ds_read_b128 v[210:213], v169 offset:38912
	ds_read_b128 v[214:217], v169 offset:39936
	global_load_lds_dwordx4 v175, s[38:39]
	s_mov_b32 m0, s48
	s_nop 0
	global_load_lds_dwordx4 v173, s[38:39]
	s_waitcnt lgkmcnt(8)
	s_waitcnt vmcnt(10)
	s_barrier
	s_waitcnt lgkmcnt(0)
	s_waitcnt lgkmcnt(0)
	v_mfma_scale_f32_16x16x128_f8f6f4 v[158:161], v[2:9], v[18:25], v[158:161], v188, v188 op_sel_hi:[0,0,0]
	v_mfma_scale_f32_16x16x128_f8f6f4 v[150:153], v[10:17], v[18:25], v[150:153], v188, v188 op_sel_hi:[0,0,0]
	v_mfma_scale_f32_16x16x128_f8f6f4 v[142:145], v[2:9], v[26:33], v[142:145], v188, v188 op_sel_hi:[0,0,0]
	v_mfma_scale_f32_16x16x128_f8f6f4 v[134:137], v[10:17], v[26:33], v[134:137], v188, v188 op_sel_hi:[0,0,0]
	v_mfma_scale_f32_16x16x128_f8f6f4 v[126:129], v[2:9], v[202:209], v[126:129], v188, v188 op_sel_hi:[0,0,0]
	v_mfma_scale_f32_16x16x128_f8f6f4 v[118:121], v[10:17], v[202:209], v[118:121], v188, v188 op_sel_hi:[0,0,0]
	v_mfma_scale_f32_16x16x128_f8f6f4 v[110:113], v[2:9], v[210:217], v[110:113], v188, v188 op_sel_hi:[0,0,0]
	v_mfma_scale_f32_16x16x128_f8f6f4 v[102:105], v[10:17], v[210:217], v[102:105], v188, v188 op_sel_hi:[0,0,0]
	s_barrier
	s_add_i32 s36, 0, 0x1c000
	s_add_i32 s0, s0, s43
	v_add_u32_e32 v162, s36, v197
	v_lshl_add_u64 v[180:181], v[180:181], 0, s[22:23]
	s_mov_b32 m0, s0
	ds_read_b128 v[218:221], v162
	ds_read_b128 v[222:225], v162 offset:1024
	ds_read_b128 v[226:229], v162 offset:2048
	ds_read_b128 v[230:233], v162 offset:3072
	global_load_lds_dwordx4 v[180:181], off
	v_lshl_add_u64 v[180:181], v[182:183], 0, s[22:23]
	s_add_i32 m0, s0, 0x2000
	s_nop 0
	global_load_lds_dwordx4 v[180:181], off
	s_waitcnt vmcnt(10)
	s_barrier
	s_waitcnt lgkmcnt(0)
	s_waitcnt lgkmcnt(0)
	v_mfma_scale_f32_16x16x128_f8f6f4 v[154:157], v[218:225], v[18:25], v[154:157], v188, v188 op_sel_hi:[0,0,0]
	v_mfma_scale_f32_16x16x128_f8f6f4 v[146:149], v[226:233], v[18:25], v[146:149], v188, v188 op_sel_hi:[0,0,0]
	v_mfma_scale_f32_16x16x128_f8f6f4 v[138:141], v[218:225], v[26:33], v[138:141], v188, v188 op_sel_hi:[0,0,0]
	v_mfma_scale_f32_16x16x128_f8f6f4 v[130:133], v[226:233], v[26:33], v[130:133], v188, v188 op_sel_hi:[0,0,0]
	v_mfma_scale_f32_16x16x128_f8f6f4 v[122:125], v[218:225], v[202:209], v[122:125], v188, v188 op_sel_hi:[0,0,0]
	v_mfma_scale_f32_16x16x128_f8f6f4 v[114:117], v[226:233], v[202:209], v[114:117], v188, v188 op_sel_hi:[0,0,0]
	v_mfma_scale_f32_16x16x128_f8f6f4 v[106:109], v[218:225], v[210:217], v[106:109], v188, v188 op_sel_hi:[0,0,0]
	v_mfma_scale_f32_16x16x128_f8f6f4 v[98:101], v[226:233], v[210:217], v[98:101], v188, v188 op_sel_hi:[0,0,0]
	s_mov_b32 m0, s51
	v_lshl_add_u64 v[180:181], v[186:187], 0, s[22:23]
	s_barrier
	ds_read_b128 v[18:21], v169 offset:49152
	ds_read_b128 v[22:25], v169 offset:50176
	ds_read_b128 v[26:29], v169 offset:51200
	ds_read_b128 v[30:33], v169 offset:52224
	ds_read_b128 v[202:205], v169 offset:53248
	ds_read_b128 v[206:209], v169 offset:54272
	ds_read_b128 v[210:213], v169 offset:55296
	ds_read_b128 v[214:217], v169 offset:56320
	global_load_lds_dwordx4 v[180:181], off
	v_lshl_add_u64 v[180:181], v[184:185], 0, s[22:23]
	s_mov_b32 m0, s52
	s_nop 0
	global_load_lds_dwordx4 v[180:181], off
	s_waitcnt vmcnt(10)
	s_barrier
	s_waitcnt lgkmcnt(0)
	s_waitcnt lgkmcnt(0)
	v_mfma_scale_f32_16x16x128_f8f6f4 v[94:97], v[2:9], v[18:25], v[94:97], v188, v188 op_sel_hi:[0,0,0]
	v_mfma_scale_f32_16x16x128_f8f6f4 v[86:89], v[10:17], v[18:25], v[86:89], v188, v188 op_sel_hi:[0,0,0]
	v_mfma_scale_f32_16x16x128_f8f6f4 v[78:81], v[2:9], v[26:33], v[78:81], v188, v188 op_sel_hi:[0,0,0]
	v_mfma_scale_f32_16x16x128_f8f6f4 v[70:73], v[10:17], v[26:33], v[70:73], v188, v188 op_sel_hi:[0,0,0]
	v_mfma_scale_f32_16x16x128_f8f6f4 v[62:65], v[2:9], v[202:209], v[62:65], v188, v188 op_sel_hi:[0,0,0]
	v_mfma_scale_f32_16x16x128_f8f6f4 v[54:57], v[10:17], v[202:209], v[54:57], v188, v188 op_sel_hi:[0,0,0]
	v_mfma_scale_f32_16x16x128_f8f6f4 v[46:49], v[2:9], v[210:217], v[46:49], v188, v188 op_sel_hi:[0,0,0]
	v_mfma_scale_f32_16x16x128_f8f6f4 v[38:41], v[10:17], v[210:217], v[38:41], v188, v188 op_sel_hi:[0,0,0]
	s_barrier
	s_add_u32 s0, s34, 0x20080
	s_addc_u32 s1, s35, 0
	s_add_i32 s34, s36, s43
	v_lshl_add_u64 v[2:3], s[0:1], 0, v[164:165]
	s_mov_b32 m0, s34
	s_nop 0
	global_load_lds_dwordx4 v[2:3], off
	v_lshl_add_u64 v[2:3], s[0:1], 0, v[166:167]
	s_add_i32 m0, s34, 0x2000
	s_nop 0
	global_load_lds_dwordx4 v[2:3], off
	s_waitcnt vmcnt(10)
	s_barrier
	v_mfma_scale_f32_16x16x128_f8f6f4 v[90:93], v[218:225], v[18:25], v[90:93], v188, v188 op_sel_hi:[0,0,0]
	v_mfma_scale_f32_16x16x128_f8f6f4 v[82:85], v[226:233], v[18:25], v[82:85], v188, v188 op_sel_hi:[0,0,0]
	v_mfma_scale_f32_16x16x128_f8f6f4 v[74:77], v[218:225], v[26:33], v[74:77], v188, v188 op_sel_hi:[0,0,0]
	v_mfma_scale_f32_16x16x128_f8f6f4 v[66:69], v[226:233], v[26:33], v[66:69], v188, v188 op_sel_hi:[0,0,0]
	v_mfma_scale_f32_16x16x128_f8f6f4 v[58:61], v[218:225], v[202:209], v[58:61], v188, v188 op_sel_hi:[0,0,0]
	v_mfma_scale_f32_16x16x128_f8f6f4 v[50:53], v[226:233], v[202:209], v[50:53], v188, v188 op_sel_hi:[0,0,0]
	v_mfma_scale_f32_16x16x128_f8f6f4 v[42:45], v[218:225], v[210:217], v[42:45], v188, v188 op_sel_hi:[0,0,0]
	v_mfma_scale_f32_16x16x128_f8f6f4 v[34:37], v[226:233], v[210:217], v[34:37], v188, v188 op_sel_hi:[0,0,0]
	s_add_i32 s56, s56, 2
	s_cmp_gt_u32 s56, 5
	s_mov_b64 s[36:37], s[12:13]
	s_barrier
	s_cbranch_scc0 .LBB0_1302
	v_mul_f32_e32 v5, 0x3c800000, v158
	v_mul_f32_e32 v6, 0xbfb8aa3b, v5
	v_exp_f32_e32 v6, v6
	s_ashr_i32 s31, s30, 31
	s_ashr_i32 s29, s28, 31
	s_lshl_b64 s[12:13], s[30:31], 18
	v_add_f32_e32 v6, 1.0, v6
	v_rcp_f32_e32 v6, v6
	s_lshl_b64 s[28:29], s[28:29], 15
	v_mov_b32_e32 v3, v195
	s_add_u32 s0, s6, s12
	v_mul_f32_e32 v5, v5, v6
	v_mul_f32_e32 v6, 0x3c800000, v159
	v_mul_f32_e32 v7, 0xbfb8aa3b, v6
	v_exp_f32_e32 v7, v7
	v_mul_f32_e32 v5, v5, v154
	v_mul_f32_e32 v5, 0x3e000000, v5
	v_med3_f32 v5, v5, s40, v190
	v_add_f32_e32 v7, 1.0, v7
	v_rcp_f32_e32 v7, v7
	s_nop 15
	s_nop 15
	v_mov_b32_e32 v2, v196
	v_mul_f32_e32 v6, v6, v7
	v_mul_f32_e32 v7, 0x3c800000, v160
	v_mul_f32_e32 v8, 0xbfb8aa3b, v7
	v_exp_f32_e32 v8, v8
	v_mul_f32_e32 v6, v6, v155
	v_mul_f32_e32 v6, 0x3e000000, v6
	v_add_u32_e32 v4, s49, v3
	v_add_f32_e32 v8, 1.0, v8
	v_rcp_f32_e32 v8, v8
	s_addc_u32 s1, s7, s13
	s_add_u32 s12, s0, s28
	v_mul_f32_e32 v7, v7, v8
	v_mul_f32_e32 v8, 0x3c800000, v161
	v_mul_f32_e32 v9, 0xbfb8aa3b, v8
	v_exp_f32_e32 v9, v9
	v_mul_f32_e32 v7, v7, v156
	v_mul_f32_e32 v7, 0x3e000000, v7
	v_lshl_add_u32 v2, v2, 3, s50
	v_add_f32_e32 v9, 1.0, v9
	v_rcp_f32_e32 v9, v9
	s_addc_u32 s13, s1, s29
	v_ashrrev_i32_e32 v3, 31, v2
	s_and_b64 vcc, exec, s[8:9]
	v_mul_f32_e32 v8, v8, v9
	v_mul_f32_e32 v9, 0x3c800000, v150
	v_mul_f32_e32 v10, 0xbfb8aa3b, v9
	v_exp_f32_e32 v10, v10
	v_mul_f32_e32 v8, v8, v157
	v_mul_f32_e32 v8, 0x3e000000, v8
	v_mov_b32_e32 v174, v200
	v_add_f32_e32 v10, 1.0, v10
	v_rcp_f32_e32 v10, v10
	v_mov_b32_e32 v172, v199
	v_mov_b32_e32 v170, v198
	v_mov_b32_e32 v168, v171
	v_mul_f32_e32 v9, v9, v10
	v_mul_f32_e32 v10, 0x3c800000, v151
	v_mul_f32_e32 v11, 0xbfb8aa3b, v10
	v_exp_f32_e32 v11, v11
	v_mul_f32_e32 v9, v9, v146
	v_mul_f32_e32 v9, 0x3e000000, v9
	s_mov_b32 s28, s26
	v_add_f32_e32 v11, 1.0, v11
	v_rcp_f32_e32 v11, v11
	s_mov_b32 s30, s54
	s_mov_b64 s[34:35], s[14:15]
	v_mul_f32_e32 v10, v10, v11
	v_mul_f32_e32 v11, 0x3c800000, v152
	v_mul_f32_e32 v12, 0xbfb8aa3b, v11
	v_exp_f32_e32 v12, v12
	v_mul_f32_e32 v10, v10, v147
	v_mul_f32_e32 v10, 0x3e000000, v10
	v_add_f32_e32 v12, 1.0, v12
	v_rcp_f32_e32 v12, v12
	s_nop 0
	v_mul_f32_e32 v11, v11, v12
	v_mul_f32_e32 v12, 0x3c800000, v153
	v_mul_f32_e32 v13, 0xbfb8aa3b, v12
	v_exp_f32_e32 v13, v13
	v_mul_f32_e32 v11, v11, v148
	v_mul_f32_e32 v11, 0x3e000000, v11
	v_add_f32_e32 v13, 1.0, v13
	v_rcp_f32_e32 v13, v13
	s_nop 0
	v_mul_f32_e32 v12, v12, v13
	v_med3_f32 v13, v6, s40, v190
	v_mov_b32_e32 v6, v163
	v_cvt_pk_fp8_f32 v6, v5, v13
	v_med3_f32 v5, v7, s40, v190
	v_med3_f32 v7, v8, s40, v190
	v_med3_f32 v8, v10, s40, v190
	v_cvt_pk_fp8_f32 v6, v5, v7 op_sel:[0,0,1]
	v_med3_f32 v5, v9, s40, v190
	v_mov_b32_e32 v7, v163
	v_cvt_pk_fp8_f32 v7, v5, v8
	v_mul_f32_e32 v12, v12, v149
	v_mul_f32_e32 v12, 0x3e000000, v12
	v_med3_f32 v5, v11, s40, v190
	v_med3_f32 v8, v12, s40, v190
	v_cvt_pk_fp8_f32 v7, v5, v8 op_sel:[0,0,1]
	v_ashrrev_i32_e32 v5, 31, v4
	v_lshlrev_b64 v[8:9], 7, v[4:5]
	v_lshl_add_u64 v[8:9], s[12:13], 0, v[8:9]
	v_lshl_add_u64 v[8:9], v[8:9], 0, v[2:3]
	v_mul_f32_e32 v5, 0x3c800000, v142
	flat_store_dwordx2 v[8:9], v[6:7]
	v_mul_f32_e32 v6, 0xbfb8aa3b, v5
	v_exp_f32_e32 v6, v6
	s_nop 0
	v_add_f32_e32 v6, 1.0, v6
	v_rcp_f32_e32 v6, v6
	s_nop 0
	v_mul_f32_e32 v5, v5, v6
	v_mul_f32_e32 v6, 0x3c800000, v143
	v_mul_f32_e32 v7, 0xbfb8aa3b, v6
	v_exp_f32_e32 v7, v7
	v_mul_f32_e32 v5, v5, v138
	v_mul_f32_e32 v5, 0x3e000000, v5
	v_med3_f32 v5, v5, s40, v190
	v_add_f32_e32 v7, 1.0, v7
	v_rcp_f32_e32 v7, v7
	s_nop 0
	v_mul_f32_e32 v6, v6, v7
	v_mul_f32_e32 v6, v6, v139
	v_mul_f32_e32 v7, 0x3e000000, v6
	v_mul_f32_e32 v6, 0x3c800000, v144
	v_mul_f32_e32 v8, 0xbfb8aa3b, v6
	v_exp_f32_e32 v8, v8
	v_med3_f32 v7, v7, s40, v190
	v_add_f32_e32 v8, 1.0, v8
	v_rcp_f32_e32 v8, v8
	s_nop 0
	v_mul_f32_e32 v6, v6, v8
	v_mul_f32_e32 v6, v6, v140
	v_mul_f32_e32 v9, 0x3e000000, v6
	v_mul_f32_e32 v6, 0x3c800000, v145
	v_mul_f32_e32 v8, 0xbfb8aa3b, v6
	v_exp_f32_e32 v8, v8
	s_nop 0
	v_add_f32_e32 v8, 1.0, v8
	v_rcp_f32_e32 v8, v8
	s_nop 0
	v_mul_f32_e32 v6, v6, v8
	v_mul_f32_e32 v6, v6, v141
	v_mul_f32_e32 v10, 0x3e000000, v6
	v_mul_f32_e32 v6, 0x3c800000, v134
	v_mul_f32_e32 v8, 0xbfb8aa3b, v6
	v_exp_f32_e32 v8, v8
	s_nop 0
	v_add_f32_e32 v8, 1.0, v8
	v_rcp_f32_e32 v8, v8
	s_nop 0
	v_mul_f32_e32 v6, v6, v8
	v_mul_f32_e32 v6, v6, v130
	v_mul_f32_e32 v11, 0x3e000000, v6
	v_mul_f32_e32 v6, 0x3c800000, v135
	v_mul_f32_e32 v8, 0xbfb8aa3b, v6
	v_exp_f32_e32 v8, v8
	s_nop 0
	v_add_f32_e32 v8, 1.0, v8
	v_rcp_f32_e32 v8, v8
	s_nop 0
	v_mul_f32_e32 v6, v6, v8
	v_mul_f32_e32 v6, v6, v131
	v_mul_f32_e32 v12, 0x3e000000, v6
	v_mul_f32_e32 v6, 0x3c800000, v136
	v_mul_f32_e32 v8, 0xbfb8aa3b, v6
	v_exp_f32_e32 v8, v8
	s_nop 0
	v_add_f32_e32 v8, 1.0, v8
	v_rcp_f32_e32 v8, v8
	s_nop 0
	v_mul_f32_e32 v6, v6, v8
	v_mul_f32_e32 v6, v6, v132
	v_mul_f32_e32 v13, 0x3e000000, v6
	v_mul_f32_e32 v6, 0x3c800000, v137
	v_mul_f32_e32 v8, 0xbfb8aa3b, v6
	v_exp_f32_e32 v8, v8
	s_nop 0
	v_add_f32_e32 v8, 1.0, v8
	v_rcp_f32_e32 v8, v8
	s_nop 0
	v_mul_f32_e32 v6, v6, v8
	v_mov_b32_e32 v8, v163
	v_cvt_pk_fp8_f32 v8, v5, v7
	v_med3_f32 v5, v9, s40, v190
	v_med3_f32 v7, v10, s40, v190
	v_mov_b32_e32 v9, v163
	v_cvt_pk_fp8_f32 v8, v5, v7 op_sel:[0,0,1]
	v_med3_f32 v5, v11, s40, v190
	v_med3_f32 v7, v12, s40, v190
	v_cvt_pk_fp8_f32 v9, v5, v7
	v_mul_f32_e32 v6, v6, v133
	v_mul_f32_e32 v14, 0x3e000000, v6
	v_add_u32_e32 v6, 16, v4
	v_med3_f32 v5, v13, s40, v190
	v_med3_f32 v7, v14, s40, v190
	v_cvt_pk_fp8_f32 v9, v5, v7 op_sel:[0,0,1]
	v_ashrrev_i32_e32 v7, 31, v6
	v_lshlrev_b64 v[6:7], 7, v[6:7]
	v_lshl_add_u64 v[6:7], s[12:13], 0, v[6:7]
	v_lshl_add_u64 v[6:7], v[6:7], 0, v[2:3]
	v_mul_f32_e32 v5, 0x3c800000, v126
	flat_store_dwordx2 v[6:7], v[8:9]
	v_mul_f32_e32 v6, 0xbfb8aa3b, v5
	v_exp_f32_e32 v6, v6
	s_nop 0
	v_add_f32_e32 v6, 1.0, v6
	v_rcp_f32_e32 v6, v6
	s_nop 0
	v_mul_f32_e32 v5, v5, v6
	v_mul_f32_e32 v6, 0x3c800000, v127
	v_mul_f32_e32 v7, 0xbfb8aa3b, v6
	v_exp_f32_e32 v7, v7
	v_mul_f32_e32 v5, v5, v122
	v_mul_f32_e32 v5, 0x3e000000, v5
	v_med3_f32 v5, v5, s40, v190
	v_add_f32_e32 v7, 1.0, v7
	v_rcp_f32_e32 v7, v7
	s_nop 0
	v_mul_f32_e32 v6, v6, v7
	v_mul_f32_e32 v6, v6, v123
	v_mul_f32_e32 v7, 0x3e000000, v6
	v_mul_f32_e32 v6, 0x3c800000, v128
	v_mul_f32_e32 v8, 0xbfb8aa3b, v6
	v_exp_f32_e32 v8, v8
	v_med3_f32 v7, v7, s40, v190
	v_add_f32_e32 v8, 1.0, v8
	v_rcp_f32_e32 v8, v8
	s_nop 0
	v_mul_f32_e32 v6, v6, v8
	v_mul_f32_e32 v6, v6, v124
	v_mul_f32_e32 v9, 0x3e000000, v6
	v_mul_f32_e32 v6, 0x3c800000, v129
	v_mul_f32_e32 v8, 0xbfb8aa3b, v6
	v_exp_f32_e32 v8, v8
	s_nop 0
	v_add_f32_e32 v8, 1.0, v8
	v_rcp_f32_e32 v8, v8
	s_nop 0
	v_mul_f32_e32 v6, v6, v8
	v_mul_f32_e32 v6, v6, v125
	v_mul_f32_e32 v10, 0x3e000000, v6
	v_mul_f32_e32 v6, 0x3c800000, v118
	v_mul_f32_e32 v8, 0xbfb8aa3b, v6
	v_exp_f32_e32 v8, v8
	s_nop 0
	v_add_f32_e32 v8, 1.0, v8
	v_rcp_f32_e32 v8, v8
	s_nop 0
	v_mul_f32_e32 v6, v6, v8
	v_mul_f32_e32 v6, v6, v114
	v_mul_f32_e32 v11, 0x3e000000, v6
	v_mul_f32_e32 v6, 0x3c800000, v119
	v_mul_f32_e32 v8, 0xbfb8aa3b, v6
	v_exp_f32_e32 v8, v8
	s_nop 0
	v_add_f32_e32 v8, 1.0, v8
	v_rcp_f32_e32 v8, v8
	s_nop 0
	v_mul_f32_e32 v6, v6, v8
	v_mul_f32_e32 v6, v6, v115
	v_mul_f32_e32 v12, 0x3e000000, v6
	v_mul_f32_e32 v6, 0x3c800000, v120
	v_mul_f32_e32 v8, 0xbfb8aa3b, v6
	v_exp_f32_e32 v8, v8
	s_nop 0
	v_add_f32_e32 v8, 1.0, v8
	v_rcp_f32_e32 v8, v8
	s_nop 0
	v_mul_f32_e32 v6, v6, v8
	v_mul_f32_e32 v6, v6, v116
	v_mul_f32_e32 v13, 0x3e000000, v6
	v_mul_f32_e32 v6, 0x3c800000, v121
	v_mul_f32_e32 v8, 0xbfb8aa3b, v6
	v_exp_f32_e32 v8, v8
	s_nop 0
	v_add_f32_e32 v8, 1.0, v8
	v_rcp_f32_e32 v8, v8
	s_nop 0
	v_mul_f32_e32 v6, v6, v8
	v_mov_b32_e32 v8, v163
	v_cvt_pk_fp8_f32 v8, v5, v7
	v_med3_f32 v5, v9, s40, v190
	v_med3_f32 v7, v10, s40, v190
	v_mov_b32_e32 v9, v163
	v_cvt_pk_fp8_f32 v8, v5, v7 op_sel:[0,0,1]
	v_med3_f32 v5, v11, s40, v190
	v_med3_f32 v7, v12, s40, v190
	v_cvt_pk_fp8_f32 v9, v5, v7
	v_mul_f32_e32 v6, v6, v117
	v_mul_f32_e32 v14, 0x3e000000, v6
	v_add_u32_e32 v6, 32, v4
	v_med3_f32 v5, v13, s40, v190
	v_med3_f32 v7, v14, s40, v190
	v_cvt_pk_fp8_f32 v9, v5, v7 op_sel:[0,0,1]
	v_ashrrev_i32_e32 v7, 31, v6
	v_lshlrev_b64 v[6:7], 7, v[6:7]
	v_lshl_add_u64 v[6:7], s[12:13], 0, v[6:7]
	v_lshl_add_u64 v[6:7], v[6:7], 0, v[2:3]
	v_mul_f32_e32 v5, 0x3c800000, v110
	flat_store_dwordx2 v[6:7], v[8:9]
	v_mul_f32_e32 v6, 0xbfb8aa3b, v5
	v_exp_f32_e32 v6, v6
	s_nop 0
	v_add_f32_e32 v6, 1.0, v6
	v_rcp_f32_e32 v6, v6
	s_nop 0
	v_mul_f32_e32 v5, v5, v6
	v_mul_f32_e32 v6, 0x3c800000, v111
	v_mul_f32_e32 v7, 0xbfb8aa3b, v6
	v_exp_f32_e32 v7, v7
	v_mul_f32_e32 v5, v5, v106
	v_mul_f32_e32 v5, 0x3e000000, v5
	v_med3_f32 v5, v5, s40, v190
	v_add_f32_e32 v7, 1.0, v7
	v_rcp_f32_e32 v7, v7
	s_nop 0
	v_mul_f32_e32 v6, v6, v7
	v_mul_f32_e32 v6, v6, v107
	v_mul_f32_e32 v7, 0x3e000000, v6
	v_mul_f32_e32 v6, 0x3c800000, v112
	v_mul_f32_e32 v8, 0xbfb8aa3b, v6
	v_exp_f32_e32 v8, v8
	v_med3_f32 v7, v7, s40, v190
	v_add_f32_e32 v8, 1.0, v8
	v_rcp_f32_e32 v8, v8
	s_nop 0
	v_mul_f32_e32 v6, v6, v8
	v_mul_f32_e32 v6, v6, v108
	v_mul_f32_e32 v9, 0x3e000000, v6
	v_mul_f32_e32 v6, 0x3c800000, v113
	v_mul_f32_e32 v8, 0xbfb8aa3b, v6
	v_exp_f32_e32 v8, v8
	s_nop 0
	v_add_f32_e32 v8, 1.0, v8
	v_rcp_f32_e32 v8, v8
	s_nop 0
	v_mul_f32_e32 v6, v6, v8
	v_mul_f32_e32 v6, v6, v109
	v_mul_f32_e32 v10, 0x3e000000, v6
	v_mul_f32_e32 v6, 0x3c800000, v102
	v_mul_f32_e32 v8, 0xbfb8aa3b, v6
	v_exp_f32_e32 v8, v8
	s_nop 0
	v_add_f32_e32 v8, 1.0, v8
	v_rcp_f32_e32 v8, v8
	s_nop 0
	v_mul_f32_e32 v6, v6, v8
	v_mul_f32_e32 v6, v6, v98
	v_mul_f32_e32 v11, 0x3e000000, v6
	v_mul_f32_e32 v6, 0x3c800000, v103
	v_mul_f32_e32 v8, 0xbfb8aa3b, v6
	v_exp_f32_e32 v8, v8
	s_nop 0
	v_add_f32_e32 v8, 1.0, v8
	v_rcp_f32_e32 v8, v8
	s_nop 0
	v_mul_f32_e32 v6, v6, v8
	v_mul_f32_e32 v6, v6, v99
	v_mul_f32_e32 v12, 0x3e000000, v6
	v_mul_f32_e32 v6, 0x3c800000, v104
	v_mul_f32_e32 v8, 0xbfb8aa3b, v6
	v_exp_f32_e32 v8, v8
	s_nop 0
	v_add_f32_e32 v8, 1.0, v8
	v_rcp_f32_e32 v8, v8
	s_nop 0
	v_mul_f32_e32 v6, v6, v8
	v_mul_f32_e32 v6, v6, v100
	v_mul_f32_e32 v13, 0x3e000000, v6
	v_mul_f32_e32 v6, 0x3c800000, v105
	v_mul_f32_e32 v8, 0xbfb8aa3b, v6
	v_exp_f32_e32 v8, v8
	s_nop 0
	v_add_f32_e32 v8, 1.0, v8
	v_rcp_f32_e32 v8, v8
	s_nop 0
	v_mul_f32_e32 v6, v6, v8
	v_mov_b32_e32 v8, v163
	v_cvt_pk_fp8_f32 v8, v5, v7
	v_med3_f32 v5, v9, s40, v190
	v_med3_f32 v7, v10, s40, v190
	v_mov_b32_e32 v9, v163
	v_cvt_pk_fp8_f32 v8, v5, v7 op_sel:[0,0,1]
	v_med3_f32 v5, v11, s40, v190
	v_med3_f32 v7, v12, s40, v190
	v_cvt_pk_fp8_f32 v9, v5, v7
	v_mul_f32_e32 v6, v6, v101
	v_mul_f32_e32 v14, 0x3e000000, v6
	v_add_u32_e32 v6, 48, v4
	v_med3_f32 v5, v13, s40, v190
	v_med3_f32 v7, v14, s40, v190
	v_cvt_pk_fp8_f32 v9, v5, v7 op_sel:[0,0,1]
	v_ashrrev_i32_e32 v7, 31, v6
	v_lshlrev_b64 v[6:7], 7, v[6:7]
	v_lshl_add_u64 v[6:7], s[12:13], 0, v[6:7]
	v_lshl_add_u64 v[6:7], v[6:7], 0, v[2:3]
	v_mul_f32_e32 v5, 0x3c800000, v94
	flat_store_dwordx2 v[6:7], v[8:9]
	v_mul_f32_e32 v7, 0xbfb8aa3b, v5
	v_exp_f32_e32 v7, v7
	v_add_u32_e32 v6, 0x80, v4
	v_add_f32_e32 v7, 1.0, v7
	v_rcp_f32_e32 v7, v7
	s_nop 0
	v_mul_f32_e32 v5, v5, v7
	v_mul_f32_e32 v7, 0x3c800000, v95
	v_mul_f32_e32 v8, 0xbfb8aa3b, v7
	v_exp_f32_e32 v8, v8
	v_mul_f32_e32 v5, v5, v90
	v_mul_f32_e32 v5, 0x3e000000, v5
	v_med3_f32 v5, v5, s40, v190
	v_add_f32_e32 v8, 1.0, v8
	v_rcp_f32_e32 v8, v8
	s_nop 0
	v_mul_f32_e32 v7, v7, v8
	v_mul_f32_e32 v8, 0x3c800000, v96
	v_mul_f32_e32 v9, 0xbfb8aa3b, v8
	v_exp_f32_e32 v9, v9
	v_mul_f32_e32 v7, v7, v91
	v_mul_f32_e32 v7, 0x3e000000, v7
	v_med3_f32 v7, v7, s40, v190
	v_add_f32_e32 v9, 1.0, v9
	v_rcp_f32_e32 v9, v9
	s_nop 0
	v_mul_f32_e32 v8, v8, v9
	v_mul_f32_e32 v8, v8, v92
	v_mul_f32_e32 v9, 0x3e000000, v8
	v_mul_f32_e32 v8, 0x3c800000, v97
	v_mul_f32_e32 v10, 0xbfb8aa3b, v8
	v_exp_f32_e32 v10, v10
	s_nop 0
	v_add_f32_e32 v10, 1.0, v10
	v_rcp_f32_e32 v10, v10
	s_nop 0
	v_mul_f32_e32 v8, v8, v10
	v_mul_f32_e32 v8, v8, v93
	v_mul_f32_e32 v10, 0x3e000000, v8
	v_mul_f32_e32 v8, 0x3c800000, v86
	v_mul_f32_e32 v11, 0xbfb8aa3b, v8
	v_exp_f32_e32 v11, v11
	s_nop 0
	v_add_f32_e32 v11, 1.0, v11
	v_rcp_f32_e32 v11, v11
	s_nop 0
	v_mul_f32_e32 v8, v8, v11
	v_mul_f32_e32 v8, v8, v82
	v_mul_f32_e32 v11, 0x3e000000, v8
	v_mul_f32_e32 v8, 0x3c800000, v87
	v_mul_f32_e32 v12, 0xbfb8aa3b, v8
	v_exp_f32_e32 v12, v12
	s_nop 0
	v_add_f32_e32 v12, 1.0, v12
	v_rcp_f32_e32 v12, v12
	s_nop 0
	v_mul_f32_e32 v8, v8, v12
	v_mul_f32_e32 v8, v8, v83
	v_mul_f32_e32 v12, 0x3e000000, v8
	v_mul_f32_e32 v8, 0x3c800000, v88
	v_mul_f32_e32 v13, 0xbfb8aa3b, v8
	v_exp_f32_e32 v13, v13
	s_nop 0
	v_add_f32_e32 v13, 1.0, v13
	v_rcp_f32_e32 v13, v13
	s_nop 0
	v_mul_f32_e32 v8, v8, v13
	v_mul_f32_e32 v8, v8, v84
	v_mul_f32_e32 v13, 0x3e000000, v8
	v_mul_f32_e32 v8, 0x3c800000, v89
	v_mul_f32_e32 v14, 0xbfb8aa3b, v8
	v_exp_f32_e32 v14, v14
	s_nop 0
	v_add_f32_e32 v14, 1.0, v14
	v_rcp_f32_e32 v14, v14
	s_nop 0
	v_mul_f32_e32 v8, v8, v14
	v_mul_f32_e32 v8, v8, v85
	v_mul_f32_e32 v14, 0x3e000000, v8
	v_mov_b32_e32 v8, v163
	v_cvt_pk_fp8_f32 v8, v5, v7
	v_med3_f32 v5, v9, s40, v190
	v_med3_f32 v7, v10, s40, v190
	v_mov_b32_e32 v9, v163
	v_cvt_pk_fp8_f32 v8, v5, v7 op_sel:[0,0,1]
	v_med3_f32 v5, v11, s40, v190
	v_med3_f32 v7, v12, s40, v190
	v_cvt_pk_fp8_f32 v9, v5, v7
	v_med3_f32 v5, v13, s40, v190
	v_med3_f32 v7, v14, s40, v190
	v_cvt_pk_fp8_f32 v9, v5, v7 op_sel:[0,0,1]
	v_ashrrev_i32_e32 v7, 31, v6
	v_lshlrev_b64 v[6:7], 7, v[6:7]
	v_lshl_add_u64 v[6:7], s[12:13], 0, v[6:7]
	v_lshl_add_u64 v[6:7], v[6:7], 0, v[2:3]
	v_mul_f32_e32 v5, 0x3c800000, v78
	flat_store_dwordx2 v[6:7], v[8:9]
	v_mul_f32_e32 v6, 0xbfb8aa3b, v5
	v_exp_f32_e32 v6, v6
	s_nop 0
	v_add_f32_e32 v6, 1.0, v6
	v_rcp_f32_e32 v6, v6
	s_nop 0
	v_mul_f32_e32 v5, v5, v6
	v_mul_f32_e32 v6, 0x3c800000, v79
	v_mul_f32_e32 v7, 0xbfb8aa3b, v6
	v_exp_f32_e32 v7, v7
	v_mul_f32_e32 v5, v5, v74
	v_mul_f32_e32 v5, 0x3e000000, v5
	v_med3_f32 v5, v5, s40, v190
	v_add_f32_e32 v7, 1.0, v7
	v_rcp_f32_e32 v7, v7
	s_nop 0
	v_mul_f32_e32 v6, v6, v7
	v_mul_f32_e32 v6, v6, v75
	v_mul_f32_e32 v7, 0x3e000000, v6
	v_mul_f32_e32 v6, 0x3c800000, v80
	v_mul_f32_e32 v8, 0xbfb8aa3b, v6
	v_exp_f32_e32 v8, v8
	v_med3_f32 v7, v7, s40, v190
	v_add_f32_e32 v8, 1.0, v8
	v_rcp_f32_e32 v8, v8
	s_nop 0
	v_mul_f32_e32 v6, v6, v8
	v_mul_f32_e32 v6, v6, v76
	v_mul_f32_e32 v9, 0x3e000000, v6
	v_mul_f32_e32 v6, 0x3c800000, v81
	v_mul_f32_e32 v8, 0xbfb8aa3b, v6
	v_exp_f32_e32 v8, v8
	s_nop 0
	v_add_f32_e32 v8, 1.0, v8
	v_rcp_f32_e32 v8, v8
	s_nop 0
	v_mul_f32_e32 v6, v6, v8
	v_mul_f32_e32 v6, v6, v77
	v_mul_f32_e32 v10, 0x3e000000, v6
	v_mul_f32_e32 v6, 0x3c800000, v70
	v_mul_f32_e32 v8, 0xbfb8aa3b, v6
	v_exp_f32_e32 v8, v8
	s_nop 0
	v_add_f32_e32 v8, 1.0, v8
	v_rcp_f32_e32 v8, v8
	s_nop 0
	v_mul_f32_e32 v6, v6, v8
	v_mul_f32_e32 v6, v6, v66
	v_mul_f32_e32 v11, 0x3e000000, v6
	v_mul_f32_e32 v6, 0x3c800000, v71
	v_mul_f32_e32 v8, 0xbfb8aa3b, v6
	v_exp_f32_e32 v8, v8
	s_nop 0
	v_add_f32_e32 v8, 1.0, v8
	v_rcp_f32_e32 v8, v8
	s_nop 0
	v_mul_f32_e32 v6, v6, v8
	v_mul_f32_e32 v6, v6, v67
	v_mul_f32_e32 v12, 0x3e000000, v6
	v_mul_f32_e32 v6, 0x3c800000, v72
	v_mul_f32_e32 v8, 0xbfb8aa3b, v6
	v_exp_f32_e32 v8, v8
	s_nop 0
	v_add_f32_e32 v8, 1.0, v8
	v_rcp_f32_e32 v8, v8
	s_nop 0
	v_mul_f32_e32 v6, v6, v8
	v_mul_f32_e32 v6, v6, v68
	v_mul_f32_e32 v13, 0x3e000000, v6
	v_mul_f32_e32 v6, 0x3c800000, v73
	v_mul_f32_e32 v8, 0xbfb8aa3b, v6
	v_exp_f32_e32 v8, v8
	s_nop 0
	v_add_f32_e32 v8, 1.0, v8
	v_rcp_f32_e32 v8, v8
	s_nop 0
	v_mul_f32_e32 v6, v6, v8
	v_mov_b32_e32 v8, v163
	v_cvt_pk_fp8_f32 v8, v5, v7
	v_med3_f32 v5, v9, s40, v190
	v_med3_f32 v7, v10, s40, v190
	v_mov_b32_e32 v9, v163
	v_cvt_pk_fp8_f32 v8, v5, v7 op_sel:[0,0,1]
	v_med3_f32 v5, v11, s40, v190
	v_med3_f32 v7, v12, s40, v190
	v_cvt_pk_fp8_f32 v9, v5, v7
	v_mul_f32_e32 v6, v6, v69
	v_mul_f32_e32 v14, 0x3e000000, v6
	v_add_u32_e32 v6, 0x90, v4
	v_med3_f32 v5, v13, s40, v190
	v_med3_f32 v7, v14, s40, v190
	v_cvt_pk_fp8_f32 v9, v5, v7 op_sel:[0,0,1]
	v_ashrrev_i32_e32 v7, 31, v6
	v_lshlrev_b64 v[6:7], 7, v[6:7]
	v_lshl_add_u64 v[6:7], s[12:13], 0, v[6:7]
	v_lshl_add_u64 v[6:7], v[6:7], 0, v[2:3]
	v_mul_f32_e32 v5, 0x3c800000, v62
	flat_store_dwordx2 v[6:7], v[8:9]
	v_mul_f32_e32 v6, 0xbfb8aa3b, v5
	v_exp_f32_e32 v6, v6
	s_nop 0
	v_add_f32_e32 v6, 1.0, v6
	v_rcp_f32_e32 v6, v6
	s_nop 0
	v_mul_f32_e32 v5, v5, v6
	v_mul_f32_e32 v6, 0x3c800000, v63
	v_mul_f32_e32 v7, 0xbfb8aa3b, v6
	v_exp_f32_e32 v7, v7
	v_mul_f32_e32 v5, v5, v58
	v_mul_f32_e32 v5, 0x3e000000, v5
	v_med3_f32 v5, v5, s40, v190
	v_add_f32_e32 v7, 1.0, v7
	v_rcp_f32_e32 v7, v7
	s_nop 0
	v_mul_f32_e32 v6, v6, v7
	v_mul_f32_e32 v6, v6, v59
	v_mul_f32_e32 v7, 0x3e000000, v6
	v_mul_f32_e32 v6, 0x3c800000, v64
	v_mul_f32_e32 v8, 0xbfb8aa3b, v6
	v_exp_f32_e32 v8, v8
	v_med3_f32 v7, v7, s40, v190
	v_add_f32_e32 v8, 1.0, v8
	v_rcp_f32_e32 v8, v8
	s_nop 0
	v_mul_f32_e32 v6, v6, v8
	v_mul_f32_e32 v6, v6, v60
	v_mul_f32_e32 v9, 0x3e000000, v6
	v_mul_f32_e32 v6, 0x3c800000, v65
	v_mul_f32_e32 v8, 0xbfb8aa3b, v6
	v_exp_f32_e32 v8, v8
	s_nop 0
	v_add_f32_e32 v8, 1.0, v8
	v_rcp_f32_e32 v8, v8
	s_nop 0
	v_mul_f32_e32 v6, v6, v8
	v_mul_f32_e32 v6, v6, v61
	v_mul_f32_e32 v10, 0x3e000000, v6
	v_mul_f32_e32 v6, 0x3c800000, v54
	v_mul_f32_e32 v8, 0xbfb8aa3b, v6
	v_exp_f32_e32 v8, v8
	s_nop 0
	v_add_f32_e32 v8, 1.0, v8
	v_rcp_f32_e32 v8, v8
	s_nop 0
	v_mul_f32_e32 v6, v6, v8
	v_mul_f32_e32 v6, v6, v50
	v_mul_f32_e32 v11, 0x3e000000, v6
	v_mul_f32_e32 v6, 0x3c800000, v55
	v_mul_f32_e32 v8, 0xbfb8aa3b, v6
	v_exp_f32_e32 v8, v8
	s_nop 0
	v_add_f32_e32 v8, 1.0, v8
	v_rcp_f32_e32 v8, v8
	s_nop 0
	v_mul_f32_e32 v6, v6, v8
	v_mul_f32_e32 v6, v6, v51
	v_mul_f32_e32 v12, 0x3e000000, v6
	v_mul_f32_e32 v6, 0x3c800000, v56
	v_mul_f32_e32 v8, 0xbfb8aa3b, v6
	v_exp_f32_e32 v8, v8
	s_nop 0
	v_add_f32_e32 v8, 1.0, v8
	v_rcp_f32_e32 v8, v8
	s_nop 0
	v_mul_f32_e32 v6, v6, v8
	v_mul_f32_e32 v6, v6, v52
	v_mul_f32_e32 v13, 0x3e000000, v6
	v_mul_f32_e32 v6, 0x3c800000, v57
	v_mul_f32_e32 v8, 0xbfb8aa3b, v6
	v_exp_f32_e32 v8, v8
	s_nop 0
	v_add_f32_e32 v8, 1.0, v8
	v_rcp_f32_e32 v8, v8
	s_nop 0
	v_mul_f32_e32 v6, v6, v8
	v_mov_b32_e32 v8, v163
	v_cvt_pk_fp8_f32 v8, v5, v7
	v_med3_f32 v5, v9, s40, v190
	v_med3_f32 v7, v10, s40, v190
	v_mov_b32_e32 v9, v163
	v_cvt_pk_fp8_f32 v8, v5, v7 op_sel:[0,0,1]
	v_med3_f32 v5, v11, s40, v190
	v_med3_f32 v7, v12, s40, v190
	v_cvt_pk_fp8_f32 v9, v5, v7
	v_mul_f32_e32 v6, v6, v53
	v_mul_f32_e32 v14, 0x3e000000, v6
	v_add_u32_e32 v6, 0xa0, v4
	v_med3_f32 v5, v13, s40, v190
	v_med3_f32 v7, v14, s40, v190
	v_cvt_pk_fp8_f32 v9, v5, v7 op_sel:[0,0,1]
	v_ashrrev_i32_e32 v7, 31, v6
	v_lshlrev_b64 v[6:7], 7, v[6:7]
	v_lshl_add_u64 v[6:7], s[12:13], 0, v[6:7]
	v_lshl_add_u64 v[6:7], v[6:7], 0, v[2:3]
	v_mul_f32_e32 v5, 0x3c800000, v46
	flat_store_dwordx2 v[6:7], v[8:9]
	v_mul_f32_e32 v6, 0xbfb8aa3b, v5
	v_exp_f32_e32 v6, v6
	v_add_u32_e32 v4, 0xb0, v4
	v_add_f32_e32 v6, 1.0, v6
	v_rcp_f32_e32 v6, v6
	s_nop 0
	v_mul_f32_e32 v5, v5, v6
	v_mul_f32_e32 v6, 0x3c800000, v47
	v_mul_f32_e32 v7, 0xbfb8aa3b, v6
	v_exp_f32_e32 v7, v7
	v_mul_f32_e32 v5, v5, v42
	v_mul_f32_e32 v5, 0x3e000000, v5
	v_med3_f32 v5, v5, s40, v190
	v_add_f32_e32 v7, 1.0, v7
	v_rcp_f32_e32 v7, v7
	s_nop 0
	v_mul_f32_e32 v6, v6, v7
	v_mul_f32_e32 v7, 0x3c800000, v48
	v_mul_f32_e32 v8, 0xbfb8aa3b, v7
	v_exp_f32_e32 v8, v8
	v_mul_f32_e32 v6, v6, v43
	v_mul_f32_e32 v6, 0x3e000000, v6
	v_add_f32_e32 v8, 1.0, v8
	v_rcp_f32_e32 v8, v8
	s_nop 0
	v_mul_f32_e32 v7, v7, v8
	v_mul_f32_e32 v8, 0x3c800000, v49
	v_mul_f32_e32 v9, 0xbfb8aa3b, v8
	v_exp_f32_e32 v9, v9
	v_mul_f32_e32 v7, v7, v44
	v_mul_f32_e32 v7, 0x3e000000, v7
	v_add_f32_e32 v9, 1.0, v9
	v_rcp_f32_e32 v9, v9
	s_nop 0
	v_mul_f32_e32 v8, v8, v9
	v_mul_f32_e32 v9, 0x3c800000, v38
	v_mul_f32_e32 v10, 0xbfb8aa3b, v9
	v_exp_f32_e32 v10, v10
	v_mul_f32_e32 v8, v8, v45
	v_mul_f32_e32 v8, 0x3e000000, v8
	v_add_f32_e32 v10, 1.0, v10
	v_rcp_f32_e32 v10, v10
	s_nop 0
	v_mul_f32_e32 v9, v9, v10
	v_mul_f32_e32 v10, 0x3c800000, v39
	v_mul_f32_e32 v11, 0xbfb8aa3b, v10
	v_exp_f32_e32 v11, v11
	v_mul_f32_e32 v9, v9, v34
	v_mul_f32_e32 v9, 0x3e000000, v9
	v_add_f32_e32 v11, 1.0, v11
	v_rcp_f32_e32 v11, v11
	s_nop 0
	v_mul_f32_e32 v10, v10, v11
	v_mul_f32_e32 v11, 0x3c800000, v40
	v_mul_f32_e32 v12, 0xbfb8aa3b, v11
	v_exp_f32_e32 v12, v12
	v_mul_f32_e32 v10, v10, v35
	v_mul_f32_e32 v10, 0x3e000000, v10
	v_add_f32_e32 v12, 1.0, v12
	v_rcp_f32_e32 v12, v12
	s_nop 0
	v_mul_f32_e32 v11, v11, v12
	v_mul_f32_e32 v12, 0x3c800000, v41
	v_mul_f32_e32 v13, 0xbfb8aa3b, v12
	v_exp_f32_e32 v13, v13
	v_mul_f32_e32 v11, v11, v36
	v_mul_f32_e32 v11, 0x3e000000, v11
	v_add_f32_e32 v13, 1.0, v13
	v_rcp_f32_e32 v13, v13
	s_nop 0
	v_mul_f32_e32 v12, v12, v13
	v_med3_f32 v13, v6, s40, v190
	v_mov_b32_e32 v6, v163
	v_cvt_pk_fp8_f32 v6, v5, v13
	v_med3_f32 v5, v7, s40, v190
	v_med3_f32 v7, v8, s40, v190
	v_med3_f32 v8, v10, s40, v190
	v_cvt_pk_fp8_f32 v6, v5, v7 op_sel:[0,0,1]
	v_med3_f32 v5, v9, s40, v190
	v_mov_b32_e32 v7, v163
	v_cvt_pk_fp8_f32 v7, v5, v8
	v_mul_f32_e32 v12, v12, v37
	v_mul_f32_e32 v12, 0x3e000000, v12
	v_med3_f32 v5, v11, s40, v190
	v_med3_f32 v8, v12, s40, v190
	v_cvt_pk_fp8_f32 v7, v5, v8 op_sel:[0,0,1]
	v_ashrrev_i32_e32 v5, 31, v4
	v_lshlrev_b64 v[4:5], 7, v[4:5]
	v_lshl_add_u64 v[4:5], s[12:13], 0, v[4:5]
	v_lshl_add_u64 v[2:3], v[4:5], 0, v[2:3]
	flat_store_dwordx2 v[2:3], v[6:7]
	s_cbranch_vccz .LBB0_1291
	s_waitcnt vmcnt(0)
	s_cmpk_gt_u32 s42, 0xff
	s_cbranch_scc1 .LBB0_1237
	s_barrier
	s_branch .LBB0_1237

.LBB0_1369:
	ds_read_b128 v[2:5], v169
	ds_read_b128 v[6:9], v169 offset:1024
	ds_read_b128 v[10:13], v169 offset:2048
	ds_read_b128 v[14:17], v169 offset:3072
	s_add_u32 s0, s28, 0x4000
	s_addc_u32 s1, s29, 0
	s_cmp_eq_u32 s53, 4
	s_cselect_b32 s36, s49, s0
	s_cselect_b32 s37, s21, s1
	s_cselect_b32 s30, s50, s51
	s_cselect_b32 s31, s19, s52
	s_add_u32 s34, s36, 0x8000
	s_addc_u32 s35, s37, 0
	v_lshl_add_u64 v[162:163], s[28:29], 0, v[156:157]
	s_add_i32 m0, s17, 0xc000
	ds_read_b128 v[174:177], v170
	ds_read_b128 v[178:181], v170 offset:1024
	ds_read_b128 v[182:185], v170 offset:2048
	ds_read_b128 v[186:189], v170 offset:3072
	ds_read_b128 v[190:193], v170 offset:4096
	ds_read_b128 v[194:197], v170 offset:5120
	ds_read_b128 v[198:201], v170 offset:6144
	ds_read_b128 v[202:205], v170 offset:7168
	global_load_lds_dwordx4 v[162:163], off
	v_lshl_add_u64 v[162:163], s[28:29], 0, v[154:155]
	s_add_i32 m0, s17, 0xe000
	s_nop 0
	global_load_lds_dwordx4 v[162:163], off
	s_waitcnt lgkmcnt(8)
	s_waitcnt vmcnt(10)
	s_barrier
	s_waitcnt lgkmcnt(0)
	s_waitcnt lgkmcnt(0)
	v_mfma_scale_f32_16x16x128_f8f6f4 v[142:145], v[2:9], v[174:181], v[142:145], v171, v171 op_sel_hi:[0,0,0]
	v_mfma_scale_f32_16x16x128_f8f6f4 v[138:141], v[10:17], v[174:181], v[138:141], v171, v171 op_sel_hi:[0,0,0]
	v_mfma_scale_f32_16x16x128_f8f6f4 v[126:129], v[2:9], v[182:189], v[126:129], v171, v171 op_sel_hi:[0,0,0]
	v_mfma_scale_f32_16x16x128_f8f6f4 v[122:125], v[10:17], v[182:189], v[122:125], v171, v171 op_sel_hi:[0,0,0]
	v_mfma_scale_f32_16x16x128_f8f6f4 v[110:113], v[2:9], v[190:197], v[110:113], v171, v171 op_sel_hi:[0,0,0]
	v_mfma_scale_f32_16x16x128_f8f6f4 v[106:109], v[10:17], v[190:197], v[106:109], v171, v171 op_sel_hi:[0,0,0]
	v_mfma_scale_f32_16x16x128_f8f6f4 v[94:97], v[2:9], v[198:205], v[94:97], v171, v171 op_sel_hi:[0,0,0]
	v_mfma_scale_f32_16x16x128_f8f6f4 v[90:93], v[10:17], v[198:205], v[90:93], v171, v171 op_sel_hi:[0,0,0]
	s_barrier
	s_add_i32 s0, s45, s11
	v_lshl_add_u64 v[162:163], s[30:31], 0, v[150:151]
	s_mov_b32 m0, s0
	ds_read_b128 v[206:209], v172
	ds_read_b128 v[210:213], v172 offset:1024
	ds_read_b128 v[214:217], v172 offset:2048
	ds_read_b128 v[218:221], v172 offset:3072
	global_load_lds_dwordx4 v[162:163], off
	v_lshl_add_u64 v[164:165], s[30:31], 0, v[146:147]
	s_add_i32 m0, s0, 0x2000
	s_nop 0
	global_load_lds_dwordx4 v[164:165], off
	s_waitcnt vmcnt(10)
	s_barrier
	s_waitcnt lgkmcnt(0)
	s_waitcnt lgkmcnt(0)
	v_mfma_scale_f32_16x16x128_f8f6f4 v[134:137], v[206:213], v[174:181], v[134:137], v171, v171 op_sel_hi:[0,0,0]
	v_mfma_scale_f32_16x16x128_f8f6f4 v[130:133], v[214:221], v[174:181], v[130:133], v171, v171 op_sel_hi:[0,0,0]
	v_mfma_scale_f32_16x16x128_f8f6f4 v[118:121], v[206:213], v[182:189], v[118:121], v171, v171 op_sel_hi:[0,0,0]
	v_mfma_scale_f32_16x16x128_f8f6f4 v[114:117], v[214:221], v[182:189], v[114:117], v171, v171 op_sel_hi:[0,0,0]
	v_mfma_scale_f32_16x16x128_f8f6f4 v[102:105], v[206:213], v[190:197], v[102:105], v171, v171 op_sel_hi:[0,0,0]
	v_mfma_scale_f32_16x16x128_f8f6f4 v[98:101], v[214:221], v[190:197], v[98:101], v171, v171 op_sel_hi:[0,0,0]
	v_mfma_scale_f32_16x16x128_f8f6f4 v[86:89], v[206:213], v[198:205], v[86:89], v171, v171 op_sel_hi:[0,0,0]
	v_mfma_scale_f32_16x16x128_f8f6f4 v[82:85], v[214:221], v[198:205], v[82:85], v171, v171 op_sel_hi:[0,0,0]
	s_mov_b32 m0, s17
	v_lshl_add_u64 v[222:223], s[36:37], 0, v[152:153]
	s_barrier
	ds_read_b128 v[174:177], v170 offset:16384
	ds_read_b128 v[178:181], v170 offset:17408
	ds_read_b128 v[182:185], v170 offset:18432
	ds_read_b128 v[186:189], v170 offset:19456
	ds_read_b128 v[190:193], v170 offset:20480
	ds_read_b128 v[194:197], v170 offset:21504
	ds_read_b128 v[198:201], v170 offset:22528
	ds_read_b128 v[202:205], v170 offset:23552
	global_load_lds_dwordx4 v[222:223], off
	v_lshl_add_u64 v[222:223], s[36:37], 0, v[148:149]
	s_mov_b32 m0, s27
	s_nop 0
	global_load_lds_dwordx4 v[222:223], off
	s_waitcnt vmcnt(10)
	s_barrier
	s_waitcnt lgkmcnt(0)
	s_waitcnt lgkmcnt(0)
	v_mfma_scale_f32_16x16x128_f8f6f4 v[78:81], v[2:9], v[174:181], v[78:81], v171, v171 op_sel_hi:[0,0,0]
	v_mfma_scale_f32_16x16x128_f8f6f4 v[74:77], v[10:17], v[174:181], v[74:77], v171, v171 op_sel_hi:[0,0,0]
	v_mfma_scale_f32_16x16x128_f8f6f4 v[62:65], v[2:9], v[182:189], v[62:65], v171, v171 op_sel_hi:[0,0,0]
	v_mfma_scale_f32_16x16x128_f8f6f4 v[58:61], v[10:17], v[182:189], v[58:61], v171, v171 op_sel_hi:[0,0,0]
	v_mfma_scale_f32_16x16x128_f8f6f4 v[46:49], v[2:9], v[190:197], v[46:49], v171, v171 op_sel_hi:[0,0,0]
	v_mfma_scale_f32_16x16x128_f8f6f4 v[42:45], v[10:17], v[190:197], v[42:45], v171, v171 op_sel_hi:[0,0,0]
	v_mfma_scale_f32_16x16x128_f8f6f4 v[30:33], v[2:9], v[198:205], v[30:33], v171, v171 op_sel_hi:[0,0,0]
	v_mfma_scale_f32_16x16x128_f8f6f4 v[26:29], v[10:17], v[198:205], v[26:29], v171, v171 op_sel_hi:[0,0,0]
	s_barrier
	s_add_u32 s0, s30, 0x20000
	s_addc_u32 s1, s31, 0
	s_add_i32 s54, s46, s11
	v_lshl_add_u64 v[2:3], s[0:1], 0, v[150:151]
	s_mov_b32 m0, s54
	s_nop 0
	global_load_lds_dwordx4 v[2:3], off
	v_lshl_add_u64 v[2:3], s[0:1], 0, v[146:147]
	s_add_i32 m0, s54, 0x2000
	s_nop 0
	global_load_lds_dwordx4 v[2:3], off
	s_waitcnt vmcnt(10)
	s_barrier
	v_mfma_scale_f32_16x16x128_f8f6f4 v[70:73], v[206:213], v[174:181], v[70:73], v171, v171 op_sel_hi:[0,0,0]
	v_mfma_scale_f32_16x16x128_f8f6f4 v[66:69], v[214:221], v[174:181], v[66:69], v171, v171 op_sel_hi:[0,0,0]
	v_mfma_scale_f32_16x16x128_f8f6f4 v[54:57], v[206:213], v[182:189], v[54:57], v171, v171 op_sel_hi:[0,0,0]
	v_mfma_scale_f32_16x16x128_f8f6f4 v[50:53], v[214:221], v[182:189], v[50:53], v171, v171 op_sel_hi:[0,0,0]
	v_mfma_scale_f32_16x16x128_f8f6f4 v[38:41], v[206:213], v[190:197], v[38:41], v171, v171 op_sel_hi:[0,0,0]
	v_mfma_scale_f32_16x16x128_f8f6f4 v[34:37], v[214:221], v[190:197], v[34:37], v171, v171 op_sel_hi:[0,0,0]
	v_mfma_scale_f32_16x16x128_f8f6f4 v[22:25], v[206:213], v[198:205], v[22:25], v171, v171 op_sel_hi:[0,0,0]
	v_mfma_scale_f32_16x16x128_f8f6f4 v[18:21], v[214:221], v[198:205], v[18:21], v171, v171 op_sel_hi:[0,0,0]
	s_add_i32 s54, 0, 0x18000
	v_add_u32_e32 v14, s54, v168
	s_barrier
	ds_read_b128 v[2:5], v14
	ds_read_b128 v[6:9], v14 offset:1024
	ds_read_b128 v[10:13], v14 offset:2048
	ds_read_b128 v[14:17], v14 offset:3072
	s_add_u32 s0, s36, 0x4000
	s_addc_u32 s1, s37, 0
	s_mov_b32 m0, s38
	v_lshl_add_u64 v[206:207], s[0:1], 0, v[152:153]
	ds_read_b128 v[174:177], v170 offset:32768
	ds_read_b128 v[178:181], v170 offset:33792
	ds_read_b128 v[182:185], v170 offset:34816
	ds_read_b128 v[186:189], v170 offset:35840
	ds_read_b128 v[190:193], v170 offset:36864
	ds_read_b128 v[194:197], v170 offset:37888
	ds_read_b128 v[198:201], v170 offset:38912
	ds_read_b128 v[202:205], v170 offset:39936
	global_load_lds_dwordx4 v[206:207], off
	v_lshl_add_u64 v[206:207], s[0:1], 0, v[148:149]
	s_mov_b32 m0, s39
	s_nop 0
	global_load_lds_dwordx4 v[206:207], off
	s_waitcnt lgkmcnt(8)
	s_waitcnt vmcnt(10)
	s_barrier
	s_waitcnt lgkmcnt(0)
	s_waitcnt lgkmcnt(0)
	v_mfma_scale_f32_16x16x128_f8f6f4 v[142:145], v[2:9], v[174:181], v[142:145], v171, v171 op_sel_hi:[0,0,0]
	v_mfma_scale_f32_16x16x128_f8f6f4 v[138:141], v[10:17], v[174:181], v[138:141], v171, v171 op_sel_hi:[0,0,0]
	v_mfma_scale_f32_16x16x128_f8f6f4 v[126:129], v[2:9], v[182:189], v[126:129], v171, v171 op_sel_hi:[0,0,0]
	v_mfma_scale_f32_16x16x128_f8f6f4 v[122:125], v[10:17], v[182:189], v[122:125], v171, v171 op_sel_hi:[0,0,0]
	v_mfma_scale_f32_16x16x128_f8f6f4 v[110:113], v[2:9], v[190:197], v[110:113], v171, v171 op_sel_hi:[0,0,0]
	v_mfma_scale_f32_16x16x128_f8f6f4 v[106:109], v[10:17], v[190:197], v[106:109], v171, v171 op_sel_hi:[0,0,0]
	v_mfma_scale_f32_16x16x128_f8f6f4 v[94:97], v[2:9], v[198:205], v[94:97], v171, v171 op_sel_hi:[0,0,0]
	v_mfma_scale_f32_16x16x128_f8f6f4 v[90:93], v[10:17], v[198:205], v[90:93], v171, v171 op_sel_hi:[0,0,0]
	s_barrier
	s_add_i32 s36, 0, 0x1c000
	s_add_i32 s0, s54, s11
	v_add_u32_e32 v218, s36, v168
	v_lshl_add_u64 v[162:163], v[162:163], 0, s[14:15]
	s_mov_b32 m0, s0
	ds_read_b128 v[206:209], v218
	ds_read_b128 v[210:213], v218 offset:1024
	ds_read_b128 v[214:217], v218 offset:2048
	ds_read_b128 v[218:221], v218 offset:3072
	global_load_lds_dwordx4 v[162:163], off
	v_lshl_add_u64 v[162:163], v[164:165], 0, s[14:15]
	s_add_i32 m0, s0, 0x2000
	s_nop 0
	global_load_lds_dwordx4 v[162:163], off
	s_waitcnt vmcnt(10)
	s_barrier
	s_waitcnt lgkmcnt(0)
	s_waitcnt lgkmcnt(0)
	v_mfma_scale_f32_16x16x128_f8f6f4 v[134:137], v[206:213], v[174:181], v[134:137], v171, v171 op_sel_hi:[0,0,0]
	v_mfma_scale_f32_16x16x128_f8f6f4 v[130:133], v[214:221], v[174:181], v[130:133], v171, v171 op_sel_hi:[0,0,0]
	v_mfma_scale_f32_16x16x128_f8f6f4 v[118:121], v[206:213], v[182:189], v[118:121], v171, v171 op_sel_hi:[0,0,0]
	v_mfma_scale_f32_16x16x128_f8f6f4 v[114:117], v[214:221], v[182:189], v[114:117], v171, v171 op_sel_hi:[0,0,0]
	v_mfma_scale_f32_16x16x128_f8f6f4 v[102:105], v[206:213], v[190:197], v[102:105], v171, v171 op_sel_hi:[0,0,0]
	v_mfma_scale_f32_16x16x128_f8f6f4 v[98:101], v[214:221], v[190:197], v[98:101], v171, v171 op_sel_hi:[0,0,0]
	v_mfma_scale_f32_16x16x128_f8f6f4 v[86:89], v[206:213], v[198:205], v[86:89], v171, v171 op_sel_hi:[0,0,0]
	v_mfma_scale_f32_16x16x128_f8f6f4 v[82:85], v[214:221], v[198:205], v[82:85], v171, v171 op_sel_hi:[0,0,0]
	s_mov_b32 m0, s43
	v_lshl_add_u64 v[162:163], s[34:35], 0, v[152:153]
	s_barrier
	ds_read_b128 v[174:177], v170 offset:49152
	ds_read_b128 v[178:181], v170 offset:50176
	ds_read_b128 v[182:185], v170 offset:51200
	ds_read_b128 v[186:189], v170 offset:52224
	ds_read_b128 v[190:193], v170 offset:53248
	ds_read_b128 v[194:197], v170 offset:54272
	ds_read_b128 v[198:201], v170 offset:55296
	ds_read_b128 v[202:205], v170 offset:56320
	global_load_lds_dwordx4 v[162:163], off
	v_lshl_add_u64 v[162:163], s[34:35], 0, v[148:149]
	s_mov_b32 m0, s44
	s_nop 0
	global_load_lds_dwordx4 v[162:163], off
	s_waitcnt vmcnt(10)
	s_barrier
	s_waitcnt lgkmcnt(0)
	s_waitcnt lgkmcnt(0)
	v_mfma_scale_f32_16x16x128_f8f6f4 v[78:81], v[2:9], v[174:181], v[78:81], v171, v171 op_sel_hi:[0,0,0]
	v_mfma_scale_f32_16x16x128_f8f6f4 v[74:77], v[10:17], v[174:181], v[74:77], v171, v171 op_sel_hi:[0,0,0]
	v_mfma_scale_f32_16x16x128_f8f6f4 v[62:65], v[2:9], v[182:189], v[62:65], v171, v171 op_sel_hi:[0,0,0]
	v_mfma_scale_f32_16x16x128_f8f6f4 v[58:61], v[10:17], v[182:189], v[58:61], v171, v171 op_sel_hi:[0,0,0]
	v_mfma_scale_f32_16x16x128_f8f6f4 v[46:49], v[2:9], v[190:197], v[46:49], v171, v171 op_sel_hi:[0,0,0]
	v_mfma_scale_f32_16x16x128_f8f6f4 v[42:45], v[10:17], v[190:197], v[42:45], v171, v171 op_sel_hi:[0,0,0]
	v_mfma_scale_f32_16x16x128_f8f6f4 v[30:33], v[2:9], v[198:205], v[30:33], v171, v171 op_sel_hi:[0,0,0]
	v_mfma_scale_f32_16x16x128_f8f6f4 v[26:29], v[10:17], v[198:205], v[26:29], v171, v171 op_sel_hi:[0,0,0]
	s_barrier
	s_add_u32 s0, s30, 0x20080
	s_addc_u32 s1, s31, 0
	s_add_i32 s30, s36, s11
	v_lshl_add_u64 v[2:3], s[0:1], 0, v[150:151]
	s_mov_b32 m0, s30
	s_nop 0
	global_load_lds_dwordx4 v[2:3], off
	v_lshl_add_u64 v[2:3], s[0:1], 0, v[146:147]
	s_add_i32 m0, s30, 0x2000
	s_nop 0
	global_load_lds_dwordx4 v[2:3], off
	s_waitcnt vmcnt(10)
	s_barrier
	v_mfma_scale_f32_16x16x128_f8f6f4 v[70:73], v[206:213], v[174:181], v[70:73], v171, v171 op_sel_hi:[0,0,0]
	v_mfma_scale_f32_16x16x128_f8f6f4 v[66:69], v[214:221], v[174:181], v[66:69], v171, v171 op_sel_hi:[0,0,0]
	v_mfma_scale_f32_16x16x128_f8f6f4 v[54:57], v[206:213], v[182:189], v[54:57], v171, v171 op_sel_hi:[0,0,0]
	v_mfma_scale_f32_16x16x128_f8f6f4 v[50:53], v[214:221], v[182:189], v[50:53], v171, v171 op_sel_hi:[0,0,0]
	v_mfma_scale_f32_16x16x128_f8f6f4 v[38:41], v[206:213], v[190:197], v[38:41], v171, v171 op_sel_hi:[0,0,0]
	v_mfma_scale_f32_16x16x128_f8f6f4 v[34:37], v[214:221], v[190:197], v[34:37], v171, v171 op_sel_hi:[0,0,0]
	v_mfma_scale_f32_16x16x128_f8f6f4 v[22:25], v[206:213], v[198:205], v[22:25], v171, v171 op_sel_hi:[0,0,0]
	v_mfma_scale_f32_16x16x128_f8f6f4 v[18:21], v[214:221], v[198:205], v[18:21], v171, v171 op_sel_hi:[0,0,0]
	s_add_i32 s53, s53, 2
	s_add_u32 s51, s51, 0x100
	s_addc_u32 s52, s52, 0
	s_add_u32 s28, s28, 0x10000
	s_addc_u32 s29, s29, 0
	s_cmp_gt_u32 s53, 5
	s_barrier
	s_cbranch_scc0 .LBB0_1369
	v_pk_mul_f32 v[10:11], v[142:143], s[16:17] op_sel_hi:[1,0]
	v_pk_mul_f32 v[8:9], v[144:145], s[16:17] op_sel_hi:[1,0]
	v_med3_f32 v5, v10, s47, v173
	v_med3_f32 v11, v11, s47, v173
	v_mov_b32_e32 v10, 0
	v_cvt_pk_fp8_f32 v10, v5, v11
	v_mov_b32_e32 v3, v166
	v_mov_b32_e32 v2, v167
	s_lshl_b32 s0, s48, 8
	v_pk_mul_f32 v[14:15], v[138:139], s[16:17] op_sel_hi:[1,0]
	v_med3_f32 v5, v8, s47, v173
	v_med3_f32 v8, v9, s47, v173
	s_nop 15
	s_nop 15
	s_or_b32 s0, s0, s42
	v_cvt_pk_fp8_f32 v10, v5, v8 op_sel:[0,0,1]
	v_med3_f32 v5, v14, s47, v173
	v_med3_f32 v8, v15, s47, v173
	v_mov_b32_e32 v11, 0
	v_lshl_add_u32 v2, v2, 3, s0
	s_lshl_b32 s0, s26, 8
	v_cvt_pk_fp8_f32 v11, v5, v8
	s_add_i32 s0, s0, s41
	v_add_u32_e32 v4, s0, v3
	v_pk_mul_f32 v[12:13], v[140:141], s[16:17] op_sel_hi:[1,0]
	v_mov_b32_e32 v6, v4
	v_med3_f32 v5, v12, s47, v173
	v_med3_f32 v8, v13, s47, v173
	v_cvt_pk_fp8_f32 v11, v5, v8 op_sel:[0,0,1]
	v_ashrrev_i32_e32 v7, 31, v6
	v_lshlrev_b64 v[6:7], 10, v[6:7]
	v_ashrrev_i32_e32 v3, 31, v2
	v_lshl_add_u64 v[6:7], s[12:13], 0, v[6:7]
	v_lshl_add_u64 v[6:7], v[6:7], 0, v[2:3]
	flat_store_dwordx2 v[6:7], v[10:11]
	v_pk_mul_f32 v[10:11], v[134:135], s[16:17] op_sel_hi:[1,0]
	v_pk_mul_f32 v[8:9], v[136:137], s[16:17] op_sel_hi:[1,0]
	v_med3_f32 v5, v10, s47, v173
	v_med3_f32 v11, v11, s47, v173
	v_mov_b32_e32 v10, 0
	v_cvt_pk_fp8_f32 v10, v5, v11
	v_pk_mul_f32 v[14:15], v[130:131], s[16:17] op_sel_hi:[1,0]
	v_med3_f32 v5, v8, s47, v173
	v_med3_f32 v8, v9, s47, v173
	v_cvt_pk_fp8_f32 v10, v5, v8 op_sel:[0,0,1]
	v_med3_f32 v5, v14, s47, v173
	v_med3_f32 v8, v15, s47, v173
	v_mov_b32_e32 v11, 0
	v_cvt_pk_fp8_f32 v11, v5, v8
	v_pk_mul_f32 v[12:13], v[132:133], s[16:17] op_sel_hi:[1,0]
	v_pk_mul_f32 v[14:15], v[122:123], s[16:17] op_sel_hi:[1,0]
	v_med3_f32 v5, v12, s47, v173
	v_med3_f32 v8, v13, s47, v173
	v_cvt_pk_fp8_f32 v11, v5, v8 op_sel:[0,0,1]
	v_pk_mul_f32 v[8:9], v[128:129], s[16:17] op_sel_hi:[1,0]
	v_pk_mul_f32 v[12:13], v[124:125], s[16:17] op_sel_hi:[1,0]
	s_and_b64 vcc, exec, s[8:9]
	flat_store_dwordx2 v[6:7], v[10:11] offset:128
	v_pk_mul_f32 v[10:11], v[126:127], s[16:17] op_sel_hi:[1,0]
	v_add_u32_e32 v6, 16, v4
	v_med3_f32 v5, v10, s47, v173
	v_med3_f32 v11, v11, s47, v173
	v_mov_b32_e32 v10, 0
	v_cvt_pk_fp8_f32 v10, v5, v11
	v_med3_f32 v5, v8, s47, v173
	v_med3_f32 v8, v9, s47, v173
	v_mov_b32_e32 v11, 0
	v_cvt_pk_fp8_f32 v10, v5, v8 op_sel:[0,0,1]
	v_med3_f32 v5, v14, s47, v173
	v_med3_f32 v8, v15, s47, v173
	v_cvt_pk_fp8_f32 v11, v5, v8
	v_med3_f32 v5, v12, s47, v173
	v_med3_f32 v8, v13, s47, v173
	v_cvt_pk_fp8_f32 v11, v5, v8 op_sel:[0,0,1]
	v_ashrrev_i32_e32 v7, 31, v6
	v_lshlrev_b64 v[6:7], 10, v[6:7]
	v_lshl_add_u64 v[6:7], s[12:13], 0, v[6:7]
	v_lshl_add_u64 v[6:7], v[6:7], 0, v[2:3]
	flat_store_dwordx2 v[6:7], v[10:11]
	v_pk_mul_f32 v[10:11], v[118:119], s[16:17] op_sel_hi:[1,0]
	v_pk_mul_f32 v[8:9], v[120:121], s[16:17] op_sel_hi:[1,0]
	v_med3_f32 v5, v10, s47, v173
	v_med3_f32 v11, v11, s47, v173
	v_mov_b32_e32 v10, 0
	v_cvt_pk_fp8_f32 v10, v5, v11
	v_pk_mul_f32 v[14:15], v[114:115], s[16:17] op_sel_hi:[1,0]
	v_med3_f32 v5, v8, s47, v173
	v_med3_f32 v8, v9, s47, v173
	v_cvt_pk_fp8_f32 v10, v5, v8 op_sel:[0,0,1]
	v_med3_f32 v5, v14, s47, v173
	v_med3_f32 v8, v15, s47, v173
	v_mov_b32_e32 v11, 0
	v_cvt_pk_fp8_f32 v11, v5, v8
	v_pk_mul_f32 v[12:13], v[116:117], s[16:17] op_sel_hi:[1,0]
	v_pk_mul_f32 v[14:15], v[106:107], s[16:17] op_sel_hi:[1,0]
	v_med3_f32 v5, v12, s47, v173
	v_med3_f32 v8, v13, s47, v173
	v_cvt_pk_fp8_f32 v11, v5, v8 op_sel:[0,0,1]
	v_pk_mul_f32 v[8:9], v[112:113], s[16:17] op_sel_hi:[1,0]
	v_pk_mul_f32 v[12:13], v[108:109], s[16:17] op_sel_hi:[1,0]
	s_mov_b32 s48, s18
	flat_store_dwordx2 v[6:7], v[10:11] offset:128
	v_pk_mul_f32 v[10:11], v[110:111], s[16:17] op_sel_hi:[1,0]
	v_add_u32_e32 v6, 32, v4
	v_med3_f32 v5, v10, s47, v173
	v_med3_f32 v11, v11, s47, v173
	v_mov_b32_e32 v10, 0
	v_cvt_pk_fp8_f32 v10, v5, v11
	v_med3_f32 v5, v8, s47, v173
	v_med3_f32 v8, v9, s47, v173
	v_mov_b32_e32 v11, 0
	v_cvt_pk_fp8_f32 v10, v5, v8 op_sel:[0,0,1]
	v_med3_f32 v5, v14, s47, v173
	v_med3_f32 v8, v15, s47, v173
	v_cvt_pk_fp8_f32 v11, v5, v8
	v_med3_f32 v5, v12, s47, v173
	v_med3_f32 v8, v13, s47, v173
	v_cvt_pk_fp8_f32 v11, v5, v8 op_sel:[0,0,1]
	v_ashrrev_i32_e32 v7, 31, v6
	v_lshlrev_b64 v[6:7], 10, v[6:7]
	v_lshl_add_u64 v[6:7], s[12:13], 0, v[6:7]
	v_lshl_add_u64 v[6:7], v[6:7], 0, v[2:3]
	flat_store_dwordx2 v[6:7], v[10:11]
	v_pk_mul_f32 v[10:11], v[102:103], s[16:17] op_sel_hi:[1,0]
	v_pk_mul_f32 v[8:9], v[104:105], s[16:17] op_sel_hi:[1,0]
	v_med3_f32 v5, v10, s47, v173
	v_med3_f32 v11, v11, s47, v173
	v_mov_b32_e32 v10, 0
	v_cvt_pk_fp8_f32 v10, v5, v11
	v_pk_mul_f32 v[14:15], v[98:99], s[16:17] op_sel_hi:[1,0]
	v_med3_f32 v5, v8, s47, v173
	v_med3_f32 v8, v9, s47, v173
	v_cvt_pk_fp8_f32 v10, v5, v8 op_sel:[0,0,1]
	v_med3_f32 v5, v14, s47, v173
	v_med3_f32 v8, v15, s47, v173
	v_mov_b32_e32 v11, 0
	v_cvt_pk_fp8_f32 v11, v5, v8
	v_pk_mul_f32 v[12:13], v[100:101], s[16:17] op_sel_hi:[1,0]
	v_pk_mul_f32 v[14:15], v[90:91], s[16:17] op_sel_hi:[1,0]
	v_med3_f32 v5, v12, s47, v173
	v_med3_f32 v8, v13, s47, v173
	v_cvt_pk_fp8_f32 v11, v5, v8 op_sel:[0,0,1]
	v_pk_mul_f32 v[8:9], v[96:97], s[16:17] op_sel_hi:[1,0]
	v_pk_mul_f32 v[12:13], v[92:93], s[16:17] op_sel_hi:[1,0]
	s_mov_b32 s26, s20
	flat_store_dwordx2 v[6:7], v[10:11] offset:128
	v_pk_mul_f32 v[10:11], v[94:95], s[16:17] op_sel_hi:[1,0]
	v_add_u32_e32 v6, 48, v4
	v_med3_f32 v5, v10, s47, v173
	v_med3_f32 v11, v11, s47, v173
	v_mov_b32_e32 v10, 0
	v_cvt_pk_fp8_f32 v10, v5, v11
	v_med3_f32 v5, v8, s47, v173
	v_med3_f32 v8, v9, s47, v173
	v_mov_b32_e32 v11, 0
	v_cvt_pk_fp8_f32 v10, v5, v8 op_sel:[0,0,1]
	v_med3_f32 v5, v14, s47, v173
	v_med3_f32 v8, v15, s47, v173
	v_cvt_pk_fp8_f32 v11, v5, v8
	v_med3_f32 v5, v12, s47, v173
	v_med3_f32 v8, v13, s47, v173
	v_cvt_pk_fp8_f32 v11, v5, v8 op_sel:[0,0,1]
	v_ashrrev_i32_e32 v7, 31, v6
	v_lshlrev_b64 v[6:7], 10, v[6:7]
	v_lshl_add_u64 v[6:7], s[12:13], 0, v[6:7]
	v_lshl_add_u64 v[6:7], v[6:7], 0, v[2:3]
	flat_store_dwordx2 v[6:7], v[10:11]
	v_pk_mul_f32 v[10:11], v[86:87], s[16:17] op_sel_hi:[1,0]
	v_pk_mul_f32 v[8:9], v[88:89], s[16:17] op_sel_hi:[1,0]
	v_med3_f32 v5, v10, s47, v173
	v_med3_f32 v11, v11, s47, v173
	v_mov_b32_e32 v10, 0
	v_cvt_pk_fp8_f32 v10, v5, v11
	v_pk_mul_f32 v[14:15], v[82:83], s[16:17] op_sel_hi:[1,0]
	v_med3_f32 v5, v8, s47, v173
	v_med3_f32 v8, v9, s47, v173
	v_cvt_pk_fp8_f32 v10, v5, v8 op_sel:[0,0,1]
	v_med3_f32 v5, v14, s47, v173
	v_med3_f32 v8, v15, s47, v173
	v_mov_b32_e32 v11, 0
	v_cvt_pk_fp8_f32 v11, v5, v8
	v_pk_mul_f32 v[12:13], v[84:85], s[16:17] op_sel_hi:[1,0]
	v_pk_mul_f32 v[14:15], v[74:75], s[16:17] op_sel_hi:[1,0]
	v_med3_f32 v5, v12, s47, v173
	v_med3_f32 v8, v13, s47, v173
	v_cvt_pk_fp8_f32 v11, v5, v8 op_sel:[0,0,1]
	v_pk_mul_f32 v[8:9], v[80:81], s[16:17] op_sel_hi:[1,0]
	v_pk_mul_f32 v[12:13], v[76:77], s[16:17] op_sel_hi:[1,0]
	s_mov_b64 s[28:29], s[24:25]
	flat_store_dwordx2 v[6:7], v[10:11] offset:128
	v_pk_mul_f32 v[10:11], v[78:79], s[16:17] op_sel_hi:[1,0]
	v_add_u32_e32 v6, 0x80, v4
	v_med3_f32 v5, v10, s47, v173
	v_med3_f32 v11, v11, s47, v173
	v_mov_b32_e32 v10, 0
	v_cvt_pk_fp8_f32 v10, v5, v11
	v_med3_f32 v5, v8, s47, v173
	v_med3_f32 v8, v9, s47, v173
	v_mov_b32_e32 v11, 0
	v_cvt_pk_fp8_f32 v10, v5, v8 op_sel:[0,0,1]
	v_med3_f32 v5, v14, s47, v173
	v_med3_f32 v8, v15, s47, v173
	v_cvt_pk_fp8_f32 v11, v5, v8
	v_med3_f32 v5, v12, s47, v173
	v_med3_f32 v8, v13, s47, v173
	v_cvt_pk_fp8_f32 v11, v5, v8 op_sel:[0,0,1]
	v_ashrrev_i32_e32 v7, 31, v6
	v_lshlrev_b64 v[6:7], 10, v[6:7]
	v_lshl_add_u64 v[6:7], s[12:13], 0, v[6:7]
	v_lshl_add_u64 v[6:7], v[6:7], 0, v[2:3]
	flat_store_dwordx2 v[6:7], v[10:11]
	v_pk_mul_f32 v[10:11], v[70:71], s[16:17] op_sel_hi:[1,0]
	v_pk_mul_f32 v[8:9], v[72:73], s[16:17] op_sel_hi:[1,0]
	v_med3_f32 v5, v10, s47, v173
	v_med3_f32 v11, v11, s47, v173
	v_mov_b32_e32 v10, 0
	v_cvt_pk_fp8_f32 v10, v5, v11
	v_pk_mul_f32 v[14:15], v[66:67], s[16:17] op_sel_hi:[1,0]
	v_med3_f32 v5, v8, s47, v173
	v_med3_f32 v8, v9, s47, v173
	v_cvt_pk_fp8_f32 v10, v5, v8 op_sel:[0,0,1]
	v_med3_f32 v5, v14, s47, v173
	v_med3_f32 v8, v15, s47, v173
	v_mov_b32_e32 v11, 0
	v_cvt_pk_fp8_f32 v11, v5, v8
	v_pk_mul_f32 v[12:13], v[68:69], s[16:17] op_sel_hi:[1,0]
	v_pk_mul_f32 v[14:15], v[58:59], s[16:17] op_sel_hi:[1,0]
	v_med3_f32 v5, v12, s47, v173
	v_med3_f32 v8, v13, s47, v173
	v_cvt_pk_fp8_f32 v11, v5, v8 op_sel:[0,0,1]
	v_pk_mul_f32 v[8:9], v[64:65], s[16:17] op_sel_hi:[1,0]
	v_pk_mul_f32 v[12:13], v[60:61], s[16:17] op_sel_hi:[1,0]
	s_mov_b64 s[30:31], s[22:23]
	flat_store_dwordx2 v[6:7], v[10:11] offset:128
	v_pk_mul_f32 v[10:11], v[62:63], s[16:17] op_sel_hi:[1,0]
	v_add_u32_e32 v6, 0x90, v4
	v_med3_f32 v5, v10, s47, v173
	v_med3_f32 v11, v11, s47, v173
	v_mov_b32_e32 v10, 0
	v_cvt_pk_fp8_f32 v10, v5, v11
	v_med3_f32 v5, v8, s47, v173
	v_med3_f32 v8, v9, s47, v173
	v_mov_b32_e32 v11, 0
	v_cvt_pk_fp8_f32 v10, v5, v8 op_sel:[0,0,1]
	v_med3_f32 v5, v14, s47, v173
	v_med3_f32 v8, v15, s47, v173
	v_cvt_pk_fp8_f32 v11, v5, v8
	v_med3_f32 v5, v12, s47, v173
	v_med3_f32 v8, v13, s47, v173
	v_cvt_pk_fp8_f32 v11, v5, v8 op_sel:[0,0,1]
	v_ashrrev_i32_e32 v7, 31, v6
	v_lshlrev_b64 v[6:7], 10, v[6:7]
	v_lshl_add_u64 v[6:7], s[12:13], 0, v[6:7]
	v_lshl_add_u64 v[6:7], v[6:7], 0, v[2:3]
	flat_store_dwordx2 v[6:7], v[10:11]
	v_pk_mul_f32 v[10:11], v[54:55], s[16:17] op_sel_hi:[1,0]
	v_pk_mul_f32 v[8:9], v[56:57], s[16:17] op_sel_hi:[1,0]
	v_med3_f32 v5, v10, s47, v173
	v_med3_f32 v11, v11, s47, v173
	v_mov_b32_e32 v10, 0
	v_cvt_pk_fp8_f32 v10, v5, v11
	v_pk_mul_f32 v[14:15], v[50:51], s[16:17] op_sel_hi:[1,0]
	v_med3_f32 v5, v8, s47, v173
	v_med3_f32 v8, v9, s47, v173
	v_cvt_pk_fp8_f32 v10, v5, v8 op_sel:[0,0,1]
	v_med3_f32 v5, v14, s47, v173
	v_med3_f32 v8, v15, s47, v173
	v_mov_b32_e32 v11, 0
	v_cvt_pk_fp8_f32 v11, v5, v8
	v_pk_mul_f32 v[12:13], v[52:53], s[16:17] op_sel_hi:[1,0]
	v_pk_mul_f32 v[14:15], v[42:43], s[16:17] op_sel_hi:[1,0]
	v_med3_f32 v5, v12, s47, v173
	v_med3_f32 v8, v13, s47, v173
	v_cvt_pk_fp8_f32 v11, v5, v8 op_sel:[0,0,1]
	v_pk_mul_f32 v[8:9], v[48:49], s[16:17] op_sel_hi:[1,0]
	v_pk_mul_f32 v[12:13], v[44:45], s[16:17] op_sel_hi:[1,0]
	flat_store_dwordx2 v[6:7], v[10:11] offset:128
	v_pk_mul_f32 v[10:11], v[46:47], s[16:17] op_sel_hi:[1,0]
	v_add_u32_e32 v6, 0xa0, v4
	v_med3_f32 v5, v10, s47, v173
	v_med3_f32 v11, v11, s47, v173
	v_mov_b32_e32 v10, 0
	v_cvt_pk_fp8_f32 v10, v5, v11
	v_med3_f32 v5, v8, s47, v173
	v_med3_f32 v8, v9, s47, v173
	v_mov_b32_e32 v11, 0
	v_cvt_pk_fp8_f32 v10, v5, v8 op_sel:[0,0,1]
	v_med3_f32 v5, v14, s47, v173
	v_med3_f32 v8, v15, s47, v173
	v_cvt_pk_fp8_f32 v11, v5, v8
	v_med3_f32 v5, v12, s47, v173
	v_med3_f32 v8, v13, s47, v173
	v_cvt_pk_fp8_f32 v11, v5, v8 op_sel:[0,0,1]
	v_ashrrev_i32_e32 v7, 31, v6
	v_lshlrev_b64 v[6:7], 10, v[6:7]
	v_lshl_add_u64 v[6:7], s[12:13], 0, v[6:7]
	v_lshl_add_u64 v[6:7], v[6:7], 0, v[2:3]
	flat_store_dwordx2 v[6:7], v[10:11]
	v_pk_mul_f32 v[10:11], v[38:39], s[16:17] op_sel_hi:[1,0]
	v_pk_mul_f32 v[8:9], v[40:41], s[16:17] op_sel_hi:[1,0]
	v_med3_f32 v5, v10, s47, v173
	v_med3_f32 v11, v11, s47, v173
	v_mov_b32_e32 v10, 0
	v_cvt_pk_fp8_f32 v10, v5, v11
	v_pk_mul_f32 v[14:15], v[34:35], s[16:17] op_sel_hi:[1,0]
	v_med3_f32 v5, v8, s47, v173
	v_med3_f32 v8, v9, s47, v173
	v_cvt_pk_fp8_f32 v10, v5, v8 op_sel:[0,0,1]
	v_med3_f32 v5, v14, s47, v173
	v_med3_f32 v8, v15, s47, v173
	v_mov_b32_e32 v11, 0
	v_cvt_pk_fp8_f32 v11, v5, v8
	v_pk_mul_f32 v[12:13], v[36:37], s[16:17] op_sel_hi:[1,0]
	v_add_u32_e32 v4, 0xb0, v4
	v_med3_f32 v5, v12, s47, v173
	v_med3_f32 v8, v13, s47, v173
	v_cvt_pk_fp8_f32 v11, v5, v8 op_sel:[0,0,1]
	v_pk_mul_f32 v[8:9], v[28:29], s[16:17] op_sel_hi:[1,0]
	flat_store_dwordx2 v[6:7], v[10:11] offset:128
	v_pk_mul_f32 v[6:7], v[30:31], s[16:17] op_sel_hi:[1,0]
	v_pk_mul_f32 v[10:11], v[26:27], s[16:17] op_sel_hi:[1,0]
	v_ashrrev_i32_e32 v5, 31, v4
	v_med3_f32 v12, v6, s47, v173
	v_med3_f32 v7, v7, s47, v173
	v_mov_b32_e32 v6, 0
	v_lshlrev_b64 v[4:5], 10, v[4:5]
	v_cvt_pk_fp8_f32 v6, v12, v7
	v_lshl_add_u64 v[4:5], s[12:13], 0, v[4:5]
	v_lshl_add_u64 v[2:3], v[4:5], 0, v[2:3]
	v_pk_mul_f32 v[4:5], v[32:33], s[16:17] op_sel_hi:[1,0]
	v_mov_b32_e32 v7, 0
	v_med3_f32 v4, v4, s47, v173
	v_med3_f32 v5, v5, s47, v173
	v_cvt_pk_fp8_f32 v6, v4, v5 op_sel:[0,0,1]
	v_med3_f32 v4, v10, s47, v173
	v_med3_f32 v5, v11, s47, v173
	v_cvt_pk_fp8_f32 v7, v4, v5
	v_med3_f32 v4, v8, s47, v173
	v_med3_f32 v5, v9, s47, v173
	v_pk_mul_f32 v[10:11], v[18:19], s[16:17] op_sel_hi:[1,0]
	v_cvt_pk_fp8_f32 v7, v4, v5 op_sel:[0,0,1]
	v_pk_mul_f32 v[4:5], v[24:25], s[16:17] op_sel_hi:[1,0]
	v_pk_mul_f32 v[8:9], v[20:21], s[16:17] op_sel_hi:[1,0]
	v_med3_f32 v4, v4, s47, v173
	flat_store_dwordx2 v[2:3], v[6:7]
	v_pk_mul_f32 v[6:7], v[22:23], s[16:17] op_sel_hi:[1,0]
	v_med3_f32 v5, v5, s47, v173
	v_med3_f32 v12, v6, s47, v173
	v_med3_f32 v7, v7, s47, v173
	v_mov_b32_e32 v6, 0
	v_cvt_pk_fp8_f32 v6, v12, v7
	v_mov_b32_e32 v7, 0
	v_cvt_pk_fp8_f32 v6, v4, v5 op_sel:[0,0,1]
	v_med3_f32 v4, v10, s47, v173
	v_med3_f32 v5, v11, s47, v173
	v_cvt_pk_fp8_f32 v7, v4, v5
	v_med3_f32 v4, v8, s47, v173
	v_med3_f32 v5, v9, s47, v173
	v_cvt_pk_fp8_f32 v7, v4, v5 op_sel:[0,0,1]
	flat_store_dwordx2 v[2:3], v[6:7] offset:128
	s_cbranch_vccz .LBB0_1362
	s_waitcnt vmcnt(0)
	s_cmpk_gt_u32 s4, 0xff
	s_cbranch_scc1 .LBB0_1373
	s_barrier

.LBB0_1513:
	ds_read_b128 v[152:155], v149
	ds_read_b128 v[156:159], v149 offset:1024
	ds_read_b128 v[160:163], v149 offset:2048
	ds_read_b128 v[164:167], v149 offset:3072
	s_add_u32 s0, s26, 0xfffc0080
	s_addc_u32 s1, s27, -1
	s_cmp_eq_u32 s49, 12
	s_cselect_b32 s31, s21, s1
	s_cselect_b32 s30, s45, s0
	s_cselect_b32 s29, s19, s48
	s_cselect_b32 s28, s46, s47
	v_lshl_add_u64 v[200:201], s[26:27], 0, v[140:141]
	s_add_i32 m0, s10, 0xc000
	ds_read_b128 v[168:171], v150
	ds_read_b128 v[172:175], v150 offset:1024
	ds_read_b128 v[176:179], v150 offset:2048
	ds_read_b128 v[180:183], v150 offset:3072
	ds_read_b128 v[184:187], v150 offset:4096
	ds_read_b128 v[188:191], v150 offset:5120
	ds_read_b128 v[192:195], v150 offset:6144
	ds_read_b128 v[196:199], v150 offset:7168
	global_load_lds_dwordx4 v[200:201], off
	v_lshl_add_u64 v[200:201], s[26:27], 0, v[138:139]
	s_add_i32 m0, s10, 0xe000
	s_nop 0
	global_load_lds_dwordx4 v[200:201], off
	s_waitcnt lgkmcnt(8)
	s_waitcnt vmcnt(10)
	s_barrier
	s_waitcnt lgkmcnt(0)
	s_waitcnt lgkmcnt(0)
	v_mfma_f32_16x16x32_bf16 v[126:129], v[152:155], v[168:171], v[126:129]
	v_mfma_f32_16x16x32_bf16 v[122:125], v[160:163], v[168:171], v[122:125]
	v_mfma_f32_16x16x32_bf16 v[118:121], v[152:155], v[176:179], v[118:121]
	v_mfma_f32_16x16x32_bf16 v[110:113], v[160:163], v[176:179], v[110:113]
	v_mfma_f32_16x16x32_bf16 v[102:105], v[152:155], v[184:187], v[102:105]
	v_mfma_f32_16x16x32_bf16 v[94:97], v[160:163], v[184:187], v[94:97]
	v_mfma_f32_16x16x32_bf16 v[86:89], v[152:155], v[192:195], v[86:89]
	v_mfma_f32_16x16x32_bf16 v[78:81], v[160:163], v[192:195], v[78:81]
	v_mfma_f32_16x16x32_bf16 v[126:129], v[156:159], v[172:175], v[126:129]
	v_mfma_f32_16x16x32_bf16 v[122:125], v[164:167], v[172:175], v[122:125]
	v_mfma_f32_16x16x32_bf16 v[118:121], v[156:159], v[180:183], v[118:121]
	v_mfma_f32_16x16x32_bf16 v[110:113], v[164:167], v[180:183], v[110:113]
	v_mfma_f32_16x16x32_bf16 v[102:105], v[156:159], v[188:191], v[102:105]
	v_mfma_f32_16x16x32_bf16 v[94:97], v[164:167], v[188:191], v[94:97]
	v_mfma_f32_16x16x32_bf16 v[86:89], v[156:159], v[196:199], v[86:89]
	v_mfma_f32_16x16x32_bf16 v[78:81], v[164:167], v[196:199], v[78:81]
	s_barrier
	s_add_i32 s0, s42, s9
	v_lshl_add_u64 v[216:217], s[28:29], 0, v[134:135]
	s_mov_b32 m0, s0
	ds_read_b128 v[200:203], v151
	ds_read_b128 v[204:207], v151 offset:1024
	ds_read_b128 v[208:211], v151 offset:2048
	ds_read_b128 v[212:215], v151 offset:3072
	global_load_lds_dwordx4 v[216:217], off
	v_lshl_add_u64 v[218:219], s[28:29], 0, v[130:131]
	s_add_i32 m0, s0, 0x2000
	s_nop 0
	global_load_lds_dwordx4 v[218:219], off
	s_waitcnt vmcnt(10)
	s_barrier
	s_waitcnt lgkmcnt(0)
	s_waitcnt lgkmcnt(0)
	v_mfma_f32_16x16x32_bf16 v[114:117], v[200:203], v[168:171], v[114:117]
	v_mfma_f32_16x16x32_bf16 v[106:109], v[208:211], v[168:171], v[106:109]
	v_mfma_f32_16x16x32_bf16 v[98:101], v[200:203], v[176:179], v[98:101]
	v_mfma_f32_16x16x32_bf16 v[90:93], v[208:211], v[176:179], v[90:93]
	v_mfma_f32_16x16x32_bf16 v[82:85], v[200:203], v[184:187], v[82:85]
	v_mfma_f32_16x16x32_bf16 v[74:77], v[208:211], v[184:187], v[74:77]
	v_mfma_f32_16x16x32_bf16 v[70:73], v[200:203], v[192:195], v[70:73]
	v_mfma_f32_16x16x32_bf16 v[66:69], v[208:211], v[192:195], v[66:69]
	v_mfma_f32_16x16x32_bf16 v[114:117], v[204:207], v[172:175], v[114:117]
	v_mfma_f32_16x16x32_bf16 v[106:109], v[212:215], v[172:175], v[106:109]
	v_mfma_f32_16x16x32_bf16 v[98:101], v[204:207], v[180:183], v[98:101]
	v_mfma_f32_16x16x32_bf16 v[90:93], v[212:215], v[180:183], v[90:93]
	v_mfma_f32_16x16x32_bf16 v[82:85], v[204:207], v[188:191], v[82:85]
	v_mfma_f32_16x16x32_bf16 v[74:77], v[212:215], v[188:191], v[74:77]
	v_mfma_f32_16x16x32_bf16 v[70:73], v[204:207], v[196:199], v[70:73]
	v_mfma_f32_16x16x32_bf16 v[66:69], v[212:215], v[196:199], v[66:69]
	s_mov_b32 m0, s10
	v_lshl_add_u64 v[220:221], s[30:31], 0, v[136:137]
	s_barrier
	ds_read_b128 v[168:171], v150 offset:16384
	ds_read_b128 v[172:175], v150 offset:17408
	ds_read_b128 v[176:179], v150 offset:18432
	ds_read_b128 v[180:183], v150 offset:19456
	ds_read_b128 v[184:187], v150 offset:20480
	ds_read_b128 v[188:191], v150 offset:21504
	ds_read_b128 v[192:195], v150 offset:22528
	ds_read_b128 v[196:199], v150 offset:23552
	global_load_lds_dwordx4 v[220:221], off
	v_lshl_add_u64 v[222:223], s[30:31], 0, v[132:133]
	s_mov_b32 m0, s11
	s_nop 0
	global_load_lds_dwordx4 v[222:223], off
	s_waitcnt vmcnt(10)
	s_barrier
	s_waitcnt lgkmcnt(0)
	s_waitcnt lgkmcnt(0)
	v_mfma_f32_16x16x32_bf16 v[62:65], v[152:155], v[168:171], v[62:65]
	v_mfma_f32_16x16x32_bf16 v[58:61], v[160:163], v[168:171], v[58:61]
	v_mfma_f32_16x16x32_bf16 v[54:57], v[152:155], v[176:179], v[54:57]
	v_mfma_f32_16x16x32_bf16 v[50:53], v[160:163], v[176:179], v[50:53]
	v_mfma_f32_16x16x32_bf16 v[38:41], v[152:155], v[184:187], v[38:41]
	v_mfma_f32_16x16x32_bf16 v[34:37], v[160:163], v[184:187], v[34:37]
	v_mfma_f32_16x16x32_bf16 v[22:25], v[152:155], v[192:195], v[22:25]
	v_mfma_f32_16x16x32_bf16 v[18:21], v[160:163], v[192:195], v[18:21]
	v_mfma_f32_16x16x32_bf16 v[62:65], v[156:159], v[172:175], v[62:65]
	v_mfma_f32_16x16x32_bf16 v[58:61], v[164:167], v[172:175], v[58:61]
	v_mfma_f32_16x16x32_bf16 v[54:57], v[156:159], v[180:183], v[54:57]
	v_mfma_f32_16x16x32_bf16 v[50:53], v[164:167], v[180:183], v[50:53]
	v_mfma_f32_16x16x32_bf16 v[38:41], v[156:159], v[188:191], v[38:41]
	v_mfma_f32_16x16x32_bf16 v[34:37], v[164:167], v[188:191], v[34:37]
	v_mfma_f32_16x16x32_bf16 v[22:25], v[156:159], v[196:199], v[22:25]
	v_mfma_f32_16x16x32_bf16 v[18:21], v[164:167], v[196:199], v[18:21]
	s_barrier
	s_add_u32 s0, s28, 0x40000
	s_addc_u32 s1, s29, 0
	s_add_i32 s50, s43, s9
	v_lshl_add_u64 v[152:153], s[0:1], 0, v[134:135]
	s_mov_b32 m0, s50
	s_nop 0
	global_load_lds_dwordx4 v[152:153], off
	v_lshl_add_u64 v[152:153], s[0:1], 0, v[130:131]
	s_add_i32 m0, s50, 0x2000
	s_nop 0
	global_load_lds_dwordx4 v[152:153], off
	s_waitcnt vmcnt(10)
	s_barrier
	v_mfma_f32_16x16x32_bf16 v[46:49], v[200:203], v[168:171], v[46:49]
	v_mfma_f32_16x16x32_bf16 v[42:45], v[208:211], v[168:171], v[42:45]
	v_mfma_f32_16x16x32_bf16 v[30:33], v[200:203], v[176:179], v[30:33]
	v_mfma_f32_16x16x32_bf16 v[26:29], v[208:211], v[176:179], v[26:29]
	v_mfma_f32_16x16x32_bf16 v[14:17], v[200:203], v[184:187], v[14:17]
	v_mfma_f32_16x16x32_bf16 v[10:13], v[208:211], v[184:187], v[10:13]
	v_mfma_f32_16x16x32_bf16 v[6:9], v[200:203], v[192:195], v[6:9]
	v_mfma_f32_16x16x32_bf16 v[2:5], v[208:211], v[192:195], v[2:5]
	v_mfma_f32_16x16x32_bf16 v[46:49], v[204:207], v[172:175], v[46:49]
	v_mfma_f32_16x16x32_bf16 v[42:45], v[212:215], v[172:175], v[42:45]
	v_mfma_f32_16x16x32_bf16 v[30:33], v[204:207], v[180:183], v[30:33]
	v_mfma_f32_16x16x32_bf16 v[26:29], v[212:215], v[180:183], v[26:29]
	v_mfma_f32_16x16x32_bf16 v[14:17], v[204:207], v[188:191], v[14:17]
	v_mfma_f32_16x16x32_bf16 v[10:13], v[212:215], v[188:191], v[10:13]
	v_mfma_f32_16x16x32_bf16 v[6:9], v[204:207], v[196:199], v[6:9]
	v_mfma_f32_16x16x32_bf16 v[2:5], v[212:215], v[196:199], v[2:5]
	s_add_i32 s50, 0, 0x18000
	v_add_u32_e32 v164, s50, v148
	s_barrier
	ds_read_b128 v[152:155], v164
	ds_read_b128 v[156:159], v164 offset:1024
	ds_read_b128 v[160:163], v164 offset:2048
	ds_read_b128 v[164:167], v164 offset:3072
	s_add_u32 s0, s30, 0x40000
	s_addc_u32 s1, s31, 0
	s_mov_b32 m0, s17
	v_lshl_add_u64 v[200:201], s[0:1], 0, v[136:137]
	ds_read_b128 v[168:171], v150 offset:32768
	ds_read_b128 v[172:175], v150 offset:33792
	ds_read_b128 v[176:179], v150 offset:34816
	ds_read_b128 v[180:183], v150 offset:35840
	ds_read_b128 v[184:187], v150 offset:36864
	ds_read_b128 v[188:191], v150 offset:37888
	ds_read_b128 v[192:195], v150 offset:38912
	ds_read_b128 v[196:199], v150 offset:39936
	global_load_lds_dwordx4 v[200:201], off
	v_lshl_add_u64 v[200:201], s[0:1], 0, v[132:133]
	s_mov_b32 m0, s34
	s_nop 0
	global_load_lds_dwordx4 v[200:201], off
	s_waitcnt lgkmcnt(8)
	s_waitcnt vmcnt(10)
	s_barrier
	s_waitcnt lgkmcnt(0)
	s_waitcnt lgkmcnt(0)
	v_mfma_f32_16x16x32_bf16 v[126:129], v[152:155], v[168:171], v[126:129]
	v_mfma_f32_16x16x32_bf16 v[122:125], v[160:163], v[168:171], v[122:125]
	v_mfma_f32_16x16x32_bf16 v[118:121], v[152:155], v[176:179], v[118:121]
	v_mfma_f32_16x16x32_bf16 v[110:113], v[160:163], v[176:179], v[110:113]
	v_mfma_f32_16x16x32_bf16 v[102:105], v[152:155], v[184:187], v[102:105]
	v_mfma_f32_16x16x32_bf16 v[94:97], v[160:163], v[184:187], v[94:97]
	v_mfma_f32_16x16x32_bf16 v[86:89], v[152:155], v[192:195], v[86:89]
	v_mfma_f32_16x16x32_bf16 v[78:81], v[160:163], v[192:195], v[78:81]
	v_mfma_f32_16x16x32_bf16 v[126:129], v[156:159], v[172:175], v[126:129]
	v_mfma_f32_16x16x32_bf16 v[122:125], v[164:167], v[172:175], v[122:125]
	v_mfma_f32_16x16x32_bf16 v[118:121], v[156:159], v[180:183], v[118:121]
	v_mfma_f32_16x16x32_bf16 v[110:113], v[164:167], v[180:183], v[110:113]
	v_mfma_f32_16x16x32_bf16 v[102:105], v[156:159], v[188:191], v[102:105]
	v_mfma_f32_16x16x32_bf16 v[94:97], v[164:167], v[188:191], v[94:97]
	v_mfma_f32_16x16x32_bf16 v[86:89], v[156:159], v[196:199], v[86:89]
	v_mfma_f32_16x16x32_bf16 v[78:81], v[164:167], v[196:199], v[78:81]
	s_barrier
	s_add_i32 s30, 0, 0x1c000
	s_add_i32 s0, s50, s9
	v_add_u32_e32 v212, s30, v148
	v_lshl_add_u64 v[216:217], v[216:217], 0, s[14:15]
	s_mov_b32 m0, s0
	ds_read_b128 v[200:203], v212
	ds_read_b128 v[204:207], v212 offset:1024
	ds_read_b128 v[208:211], v212 offset:2048
	ds_read_b128 v[212:215], v212 offset:3072
	global_load_lds_dwordx4 v[216:217], off
	v_lshl_add_u64 v[216:217], v[218:219], 0, s[14:15]
	s_add_i32 m0, s0, 0x2000
	s_nop 0
	global_load_lds_dwordx4 v[216:217], off
	s_waitcnt vmcnt(10)
	s_barrier
	s_waitcnt lgkmcnt(0)
	s_waitcnt lgkmcnt(0)
	v_mfma_f32_16x16x32_bf16 v[114:117], v[200:203], v[168:171], v[114:117]
	v_mfma_f32_16x16x32_bf16 v[106:109], v[208:211], v[168:171], v[106:109]
	v_mfma_f32_16x16x32_bf16 v[98:101], v[200:203], v[176:179], v[98:101]
	v_mfma_f32_16x16x32_bf16 v[90:93], v[208:211], v[176:179], v[90:93]
	v_mfma_f32_16x16x32_bf16 v[82:85], v[200:203], v[184:187], v[82:85]
	v_mfma_f32_16x16x32_bf16 v[74:77], v[208:211], v[184:187], v[74:77]
	v_mfma_f32_16x16x32_bf16 v[70:73], v[200:203], v[192:195], v[70:73]
	v_mfma_f32_16x16x32_bf16 v[66:69], v[208:211], v[192:195], v[66:69]
	v_mfma_f32_16x16x32_bf16 v[114:117], v[204:207], v[172:175], v[114:117]
	v_mfma_f32_16x16x32_bf16 v[106:109], v[212:215], v[172:175], v[106:109]
	v_mfma_f32_16x16x32_bf16 v[98:101], v[204:207], v[180:183], v[98:101]
	v_mfma_f32_16x16x32_bf16 v[90:93], v[212:215], v[180:183], v[90:93]
	v_mfma_f32_16x16x32_bf16 v[82:85], v[204:207], v[188:191], v[82:85]
	v_mfma_f32_16x16x32_bf16 v[74:77], v[212:215], v[188:191], v[74:77]
	v_mfma_f32_16x16x32_bf16 v[70:73], v[204:207], v[196:199], v[70:73]
	v_mfma_f32_16x16x32_bf16 v[66:69], v[212:215], v[196:199], v[66:69]
	s_mov_b32 m0, s40
	v_lshl_add_u64 v[216:217], v[220:221], 0, s[14:15]
	s_barrier
	ds_read_b128 v[168:171], v150 offset:49152
	ds_read_b128 v[172:175], v150 offset:50176
	ds_read_b128 v[176:179], v150 offset:51200
	ds_read_b128 v[180:183], v150 offset:52224
	ds_read_b128 v[184:187], v150 offset:53248
	ds_read_b128 v[188:191], v150 offset:54272
	ds_read_b128 v[192:195], v150 offset:55296
	ds_read_b128 v[196:199], v150 offset:56320
	global_load_lds_dwordx4 v[216:217], off
	v_lshl_add_u64 v[216:217], v[222:223], 0, s[14:15]
	s_mov_b32 m0, s41
	s_nop 0
	global_load_lds_dwordx4 v[216:217], off
	s_waitcnt vmcnt(10)
	s_barrier
	s_waitcnt lgkmcnt(0)
	s_waitcnt lgkmcnt(0)
	v_mfma_f32_16x16x32_bf16 v[62:65], v[152:155], v[168:171], v[62:65]
	v_mfma_f32_16x16x32_bf16 v[58:61], v[160:163], v[168:171], v[58:61]
	v_mfma_f32_16x16x32_bf16 v[54:57], v[152:155], v[176:179], v[54:57]
	v_mfma_f32_16x16x32_bf16 v[50:53], v[160:163], v[176:179], v[50:53]
	v_mfma_f32_16x16x32_bf16 v[38:41], v[152:155], v[184:187], v[38:41]
	v_mfma_f32_16x16x32_bf16 v[34:37], v[160:163], v[184:187], v[34:37]
	v_mfma_f32_16x16x32_bf16 v[22:25], v[152:155], v[192:195], v[22:25]
	v_mfma_f32_16x16x32_bf16 v[18:21], v[160:163], v[192:195], v[18:21]
	v_mfma_f32_16x16x32_bf16 v[62:65], v[156:159], v[172:175], v[62:65]
	v_mfma_f32_16x16x32_bf16 v[58:61], v[164:167], v[172:175], v[58:61]
	v_mfma_f32_16x16x32_bf16 v[54:57], v[156:159], v[180:183], v[54:57]
	v_mfma_f32_16x16x32_bf16 v[50:53], v[164:167], v[180:183], v[50:53]
	v_mfma_f32_16x16x32_bf16 v[38:41], v[156:159], v[188:191], v[38:41]
	v_mfma_f32_16x16x32_bf16 v[34:37], v[164:167], v[188:191], v[34:37]
	v_mfma_f32_16x16x32_bf16 v[22:25], v[156:159], v[196:199], v[22:25]
	v_mfma_f32_16x16x32_bf16 v[18:21], v[164:167], v[196:199], v[18:21]
	s_barrier
	s_add_u32 s0, s28, 0x40080
	s_addc_u32 s1, s29, 0
	s_add_i32 s28, s30, s9
	v_lshl_add_u64 v[152:153], s[0:1], 0, v[134:135]
	s_mov_b32 m0, s28
	s_nop 0
	global_load_lds_dwordx4 v[152:153], off
	v_lshl_add_u64 v[152:153], s[0:1], 0, v[130:131]
	s_add_i32 m0, s28, 0x2000
	s_nop 0
	global_load_lds_dwordx4 v[152:153], off
	s_waitcnt vmcnt(10)
	s_barrier
	v_mfma_f32_16x16x32_bf16 v[46:49], v[200:203], v[168:171], v[46:49]
	v_mfma_f32_16x16x32_bf16 v[42:45], v[208:211], v[168:171], v[42:45]
	v_mfma_f32_16x16x32_bf16 v[30:33], v[200:203], v[176:179], v[30:33]
	v_mfma_f32_16x16x32_bf16 v[26:29], v[208:211], v[176:179], v[26:29]
	v_mfma_f32_16x16x32_bf16 v[14:17], v[200:203], v[184:187], v[14:17]
	v_mfma_f32_16x16x32_bf16 v[10:13], v[208:211], v[184:187], v[10:13]
	v_mfma_f32_16x16x32_bf16 v[6:9], v[200:203], v[192:195], v[6:9]
	v_mfma_f32_16x16x32_bf16 v[2:5], v[208:211], v[192:195], v[2:5]
	v_mfma_f32_16x16x32_bf16 v[46:49], v[204:207], v[172:175], v[46:49]
	v_mfma_f32_16x16x32_bf16 v[42:45], v[212:215], v[172:175], v[42:45]
	v_mfma_f32_16x16x32_bf16 v[30:33], v[204:207], v[180:183], v[30:33]
	v_mfma_f32_16x16x32_bf16 v[26:29], v[212:215], v[180:183], v[26:29]
	v_mfma_f32_16x16x32_bf16 v[14:17], v[204:207], v[188:191], v[14:17]
	v_mfma_f32_16x16x32_bf16 v[10:13], v[212:215], v[188:191], v[10:13]
	v_mfma_f32_16x16x32_bf16 v[6:9], v[204:207], v[196:199], v[6:9]
	v_mfma_f32_16x16x32_bf16 v[2:5], v[212:215], v[196:199], v[2:5]
	s_add_i32 s49, s49, 2
	s_add_u32 s47, s47, 0x100
	s_addc_u32 s48, s48, 0
	s_add_u32 s26, s26, 0x100
	s_addc_u32 s27, s27, 0
	s_cmp_gt_u32 s49, 13
	s_barrier
	s_cbranch_scc0 .LBB0_1513
	v_mov_b32_e32 v152, v146
	v_mov_b32_e32 v153, v147
	s_cmp_gt_i32 s44, 7
	s_cbranch_scc1 .LBB0_1505
	s_ashr_i32 s0, s44, 31
	s_lshr_b32 s0, s0, 30
	s_add_i32 s0, s44, s0
	s_ashr_i32 s0, s0, 2
	s_ashr_i32 s1, s0, 31
	s_lshl_b32 s19, s44, 8
	s_lshl_b64 s[26:27], s[0:1], 27
	s_add_u32 s26, s36, s26
	s_addc_u32 s27, s37, s27
	s_or_b32 s1, s19, s39
	s_lshl_b32 s0, s0, 10
	s_sub_i32 s0, s1, s0
	v_lshl_add_u32 v154, v153, 3, s0
	s_lshl_b32 s0, s16, 8
	s_add_i32 s0, s0, s38
	v_add_u32_e32 v156, s0, v152
	v_mov_b32_e32 v152, v156
	v_ashrrev_i32_e32 v155, 31, v154
	v_lshl_add_u64 v[154:155], v[154:155], 1, s[26:27]
	v_ashrrev_i32_e32 v153, 31, v152
	v_lshlrev_b64 v[152:153], 11, v[152:153]
	v_lshl_add_u64 v[152:153], v[154:155], 0, v[152:153]
	v_cvt_pk_bf16_f32 v126, v126, v127
	v_cvt_pk_bf16_f32 v127, v128, v129
	v_cvt_pk_bf16_f32 v128, v122, v123
	v_cvt_pk_bf16_f32 v129, v124, v125
	v_cvt_pk_bf16_f32 v114, v114, v115
	v_cvt_pk_bf16_f32 v115, v116, v117
	v_cvt_pk_bf16_f32 v116, v106, v107
	v_cvt_pk_bf16_f32 v117, v108, v109
	v_add_u32_e32 v106, 16, v156
	flat_store_dwordx4 v[152:153], v[126:129]
	flat_store_dwordx4 v[152:153], v[114:117] offset:256
	v_cvt_pk_bf16_f32 v108, v110, v111
	v_ashrrev_i32_e32 v107, 31, v106
	v_lshlrev_b64 v[106:107], 11, v[106:107]
	v_lshl_add_u64 v[114:115], v[154:155], 0, v[106:107]
	v_cvt_pk_bf16_f32 v106, v118, v119
	v_cvt_pk_bf16_f32 v107, v120, v121
	v_cvt_pk_bf16_f32 v109, v112, v113
	v_cvt_pk_bf16_f32 v98, v98, v99
	v_cvt_pk_bf16_f32 v99, v100, v101
	v_cvt_pk_bf16_f32 v100, v90, v91
	v_cvt_pk_bf16_f32 v101, v92, v93
	v_add_u32_e32 v90, 32, v156
	flat_store_dwordx4 v[114:115], v[106:109]
	flat_store_dwordx4 v[114:115], v[98:101] offset:256
	v_cvt_pk_bf16_f32 v92, v94, v95
	v_ashrrev_i32_e32 v91, 31, v90
	v_lshlrev_b64 v[90:91], 11, v[90:91]
	v_lshl_add_u64 v[98:99], v[154:155], 0, v[90:91]
	v_cvt_pk_bf16_f32 v90, v102, v103
	v_cvt_pk_bf16_f32 v91, v104, v105
	v_cvt_pk_bf16_f32 v93, v96, v97
	v_cvt_pk_bf16_f32 v82, v82, v83
	v_cvt_pk_bf16_f32 v83, v84, v85
	v_cvt_pk_bf16_f32 v84, v74, v75
	v_cvt_pk_bf16_f32 v85, v76, v77
	v_add_u32_e32 v74, 48, v156
	flat_store_dwordx4 v[98:99], v[90:93]
	flat_store_dwordx4 v[98:99], v[82:85] offset:256
	v_cvt_pk_bf16_f32 v76, v78, v79
	v_ashrrev_i32_e32 v75, 31, v74
	v_lshlrev_b64 v[74:75], 11, v[74:75]
	v_lshl_add_u64 v[82:83], v[154:155], 0, v[74:75]
	v_cvt_pk_bf16_f32 v74, v86, v87
	v_cvt_pk_bf16_f32 v75, v88, v89
	v_cvt_pk_bf16_f32 v77, v80, v81
	v_cvt_pk_bf16_f32 v70, v70, v71
	v_cvt_pk_bf16_f32 v71, v72, v73
	v_cvt_pk_bf16_f32 v72, v66, v67
	v_cvt_pk_bf16_f32 v73, v68, v69
	v_add_u32_e32 v66, 0x80, v156
	flat_store_dwordx4 v[82:83], v[74:77]
	flat_store_dwordx4 v[82:83], v[70:73] offset:256
	v_cvt_pk_bf16_f32 v62, v62, v63
	v_ashrrev_i32_e32 v67, 31, v66
	v_lshlrev_b64 v[66:67], 11, v[66:67]
	v_lshl_add_u64 v[66:67], v[154:155], 0, v[66:67]
	v_cvt_pk_bf16_f32 v63, v64, v65
	v_cvt_pk_bf16_f32 v64, v58, v59
	v_cvt_pk_bf16_f32 v65, v60, v61
	v_cvt_pk_bf16_f32 v46, v46, v47
	v_cvt_pk_bf16_f32 v47, v48, v49
	v_cvt_pk_bf16_f32 v48, v42, v43
	v_cvt_pk_bf16_f32 v49, v44, v45
	v_add_u32_e32 v42, 0x90, v156
	flat_store_dwordx4 v[66:67], v[62:65]
	flat_store_dwordx4 v[66:67], v[46:49] offset:256
	v_cvt_pk_bf16_f32 v44, v50, v51
	v_ashrrev_i32_e32 v43, 31, v42
	v_lshlrev_b64 v[42:43], 11, v[42:43]
	v_lshl_add_u64 v[46:47], v[154:155], 0, v[42:43]
	v_cvt_pk_bf16_f32 v42, v54, v55
	v_cvt_pk_bf16_f32 v43, v56, v57
	v_cvt_pk_bf16_f32 v45, v52, v53
	v_cvt_pk_bf16_f32 v30, v30, v31
	v_cvt_pk_bf16_f32 v31, v32, v33
	v_cvt_pk_bf16_f32 v32, v26, v27
	v_cvt_pk_bf16_f32 v33, v28, v29
	v_add_u32_e32 v26, 0xa0, v156
	flat_store_dwordx4 v[46:47], v[42:45]
	flat_store_dwordx4 v[46:47], v[30:33] offset:256
	v_cvt_pk_bf16_f32 v28, v34, v35
	v_ashrrev_i32_e32 v27, 31, v26
	v_lshlrev_b64 v[26:27], 11, v[26:27]
	v_lshl_add_u64 v[30:31], v[154:155], 0, v[26:27]
	v_cvt_pk_bf16_f32 v26, v38, v39
	v_cvt_pk_bf16_f32 v27, v40, v41
	v_cvt_pk_bf16_f32 v29, v36, v37
	v_cvt_pk_bf16_f32 v14, v14, v15
	v_cvt_pk_bf16_f32 v15, v16, v17
	v_cvt_pk_bf16_f32 v16, v10, v11
	v_cvt_pk_bf16_f32 v17, v12, v13
	v_add_u32_e32 v10, 0xb0, v156
	flat_store_dwordx4 v[30:31], v[26:29]
	flat_store_dwordx4 v[30:31], v[14:17] offset:256
	v_cvt_pk_bf16_f32 v12, v18, v19
	v_ashrrev_i32_e32 v11, 31, v10
	v_lshlrev_b64 v[10:11], 11, v[10:11]
	v_lshl_add_u64 v[14:15], v[154:155], 0, v[10:11]
	v_cvt_pk_bf16_f32 v10, v22, v23
	v_cvt_pk_bf16_f32 v11, v24, v25
	v_cvt_pk_bf16_f32 v13, v20, v21
	v_cvt_pk_bf16_f32 v6, v6, v7
	v_cvt_pk_bf16_f32 v7, v8, v9
	v_cvt_pk_bf16_f32 v8, v2, v3
	v_cvt_pk_bf16_f32 v9, v4, v5
	flat_store_dwordx4 v[14:15], v[10:13]
	flat_store_dwordx4 v[14:15], v[6:9] offset:256
	s_branch .LBB0_1505

.LBB0_1645:
	s_add_u32 s57, s48, s56
	s_addc_u32 s58, s49, 0
	s_add_u32 s59, s57, 0x100
	s_addc_u32 s60, s58, 0
	s_and_b64 s[0:1], s[54:55], exec
	s_cselect_b32 s61, s43, s60
	s_cselect_b32 s60, s83, s59
	s_add_u32 s0, s14, s56
	s_addc_u32 s1, s15, 0
	s_add_u32 s56, s0, 0x100
	s_addc_u32 s59, s1, 0
	s_and_b64 s[0:1], s[54:55], exec
	s_cselect_b32 s63, s41, s59
	s_cselect_b32 s62, s94, s56
	s_add_u32 s64, s57, 0x40080
	s_addc_u32 s65, s58, 0
	s_add_i32 s0, s85, s37
	s_add_i32 m0, s39, 0xc000
	s_add_i32 s71, s39, 0xe000
	s_add_i32 s70, s0, 0x2000
	s_add_u32 s58, s62, 0x10000
	s_addc_u32 s59, s63, 0
	s_add_i32 s1, s4, s37
	ds_read_b128 v[26:29], v225
	ds_read_b128 v[30:33], v225 offset:1024
	ds_read_b128 v[42:45], v225 offset:2048
	ds_read_b128 v[46:49], v225 offset:3072
	s_add_i32 s96, s1, 0x2000
	s_add_i32 s81, 0, 0x18000
	s_add_u32 s56, s60, 0x40000
	s_addc_u32 s57, s61, 0
	s_add_i32 s78, s81, s37
	s_add_i32 s79, 0, 0x1c000
	s_add_i32 s80, s78, 0x2000
	s_add_u32 s54, s62, 0x10080
	s_addc_u32 s55, s63, 0
	s_add_i32 vcc_hi, s79, s37
	s_add_i32 vcc_lo, vcc_hi, 0x2000
	v_lshl_add_u64 v[190:191], s[64:65], 0, v[160:161]
	ds_read_b128 v[146:149], v226
	ds_read_b128 v[150:153], v226 offset:1024
	ds_read_b128 v[166:169], v226 offset:2048
	ds_read_b128 v[170:173], v226 offset:3072
	ds_read_b128 v[174:177], v226 offset:4096
	ds_read_b128 v[178:181], v226 offset:5120
	ds_read_b128 v[182:185], v226 offset:6144
	ds_read_b128 v[186:189], v226 offset:7168
	global_load_lds_dwordx4 v[190:191], off
	v_lshl_add_u64 v[190:191], s[64:65], 0, v[156:157]
	s_mov_b32 m0, s71
	s_nop 0
	global_load_lds_dwordx4 v[190:191], off
	s_waitcnt lgkmcnt(8)
	s_waitcnt vmcnt(10)
	s_barrier
	s_waitcnt lgkmcnt(0)
	s_waitcnt lgkmcnt(0)
	v_mfma_f32_16x16x32_bf16 v[142:145], v[26:29], v[146:149], v[142:145]
	v_mfma_f32_16x16x32_bf16 v[134:137], v[42:45], v[146:149], v[134:137]
	v_mfma_f32_16x16x32_bf16 v[126:129], v[26:29], v[166:169], v[126:129]
	v_mfma_f32_16x16x32_bf16 v[118:121], v[42:45], v[166:169], v[118:121]
	v_mfma_f32_16x16x32_bf16 v[110:113], v[26:29], v[174:177], v[110:113]
	v_mfma_f32_16x16x32_bf16 v[102:105], v[42:45], v[174:177], v[102:105]
	v_mfma_f32_16x16x32_bf16 v[94:97], v[26:29], v[182:185], v[94:97]
	v_mfma_f32_16x16x32_bf16 v[86:89], v[42:45], v[182:185], v[86:89]
	v_mfma_f32_16x16x32_bf16 v[142:145], v[30:33], v[150:153], v[142:145]
	v_mfma_f32_16x16x32_bf16 v[134:137], v[46:49], v[150:153], v[134:137]
	v_mfma_f32_16x16x32_bf16 v[126:129], v[30:33], v[170:173], v[126:129]
	v_mfma_f32_16x16x32_bf16 v[118:121], v[46:49], v[170:173], v[118:121]
	v_mfma_f32_16x16x32_bf16 v[110:113], v[30:33], v[178:181], v[110:113]
	v_mfma_f32_16x16x32_bf16 v[102:105], v[46:49], v[178:181], v[102:105]
	v_mfma_f32_16x16x32_bf16 v[94:97], v[30:33], v[186:189], v[94:97]
	v_mfma_f32_16x16x32_bf16 v[86:89], v[46:49], v[186:189], v[86:89]
	s_barrier
	s_mov_b32 m0, s0
	v_lshl_add_u64 v[206:207], s[62:63], 0, v[158:159]
	ds_read_b128 v[190:193], v227
	ds_read_b128 v[194:197], v227 offset:1024
	ds_read_b128 v[198:201], v227 offset:2048
	ds_read_b128 v[202:205], v227 offset:3072
	global_load_lds_dwordx4 v[206:207], off
	v_lshl_add_u64 v[208:209], s[62:63], 0, v[154:155]
	s_mov_b32 m0, s70
	s_nop 0
	global_load_lds_dwordx4 v[208:209], off
	s_waitcnt vmcnt(10)
	s_barrier
	s_waitcnt lgkmcnt(0)
	s_waitcnt lgkmcnt(0)
	v_mfma_f32_16x16x32_bf16 v[138:141], v[190:193], v[146:149], v[138:141]
	v_mfma_f32_16x16x32_bf16 v[130:133], v[198:201], v[146:149], v[130:133]
	v_mfma_f32_16x16x32_bf16 v[122:125], v[190:193], v[166:169], v[122:125]
	v_mfma_f32_16x16x32_bf16 v[114:117], v[198:201], v[166:169], v[114:117]
	v_mfma_f32_16x16x32_bf16 v[106:109], v[190:193], v[174:177], v[106:109]
	v_mfma_f32_16x16x32_bf16 v[98:101], v[198:201], v[174:177], v[98:101]
	v_mfma_f32_16x16x32_bf16 v[90:93], v[190:193], v[182:185], v[90:93]
	v_mfma_f32_16x16x32_bf16 v[82:85], v[198:201], v[182:185], v[82:85]
	v_mfma_f32_16x16x32_bf16 v[138:141], v[194:197], v[150:153], v[138:141]
	v_mfma_f32_16x16x32_bf16 v[130:133], v[202:205], v[150:153], v[130:133]
	v_mfma_f32_16x16x32_bf16 v[122:125], v[194:197], v[170:173], v[122:125]
	v_mfma_f32_16x16x32_bf16 v[114:117], v[202:205], v[170:173], v[114:117]
	v_mfma_f32_16x16x32_bf16 v[106:109], v[194:197], v[178:181], v[106:109]
	v_mfma_f32_16x16x32_bf16 v[98:101], v[202:205], v[178:181], v[98:101]
	v_mfma_f32_16x16x32_bf16 v[90:93], v[194:197], v[186:189], v[90:93]
	v_mfma_f32_16x16x32_bf16 v[82:85], v[202:205], v[186:189], v[82:85]
	s_mov_b32 m0, s39
	v_lshl_add_u64 v[210:211], s[60:61], 0, v[160:161]
	s_barrier
	ds_read_b128 v[146:149], v226 offset:16384
	ds_read_b128 v[150:153], v226 offset:17408
	ds_read_b128 v[166:169], v226 offset:18432
	ds_read_b128 v[170:173], v226 offset:19456
	ds_read_b128 v[174:177], v226 offset:20480
	ds_read_b128 v[178:181], v226 offset:21504
	ds_read_b128 v[182:185], v226 offset:22528
	ds_read_b128 v[186:189], v226 offset:23552
	global_load_lds_dwordx4 v[210:211], off
	v_lshl_add_u64 v[212:213], s[60:61], 0, v[156:157]
	s_mov_b32 m0, s53
	s_nop 0
	global_load_lds_dwordx4 v[212:213], off
	s_waitcnt vmcnt(10)
	s_barrier
	s_waitcnt lgkmcnt(0)
	s_waitcnt lgkmcnt(0)
	v_mfma_f32_16x16x32_bf16 v[78:81], v[26:29], v[146:149], v[78:81]
	v_mfma_f32_16x16x32_bf16 v[70:73], v[42:45], v[146:149], v[70:73]
	v_mfma_f32_16x16x32_bf16 v[62:65], v[26:29], v[166:169], v[62:65]
	v_mfma_f32_16x16x32_bf16 v[54:57], v[42:45], v[166:169], v[54:57]
	v_mfma_f32_16x16x32_bf16 v[38:41], v[26:29], v[174:177], v[38:41]
	v_mfma_f32_16x16x32_bf16 v[22:25], v[42:45], v[174:177], v[22:25]
	v_mfma_f32_16x16x32_bf16 v[14:17], v[26:29], v[182:185], v[14:17]
	v_mfma_f32_16x16x32_bf16 v[6:9], v[42:45], v[182:185], v[6:9]
	v_mfma_f32_16x16x32_bf16 v[78:81], v[30:33], v[150:153], v[78:81]
	v_mfma_f32_16x16x32_bf16 v[70:73], v[46:49], v[150:153], v[70:73]
	v_mfma_f32_16x16x32_bf16 v[62:65], v[30:33], v[170:173], v[62:65]
	v_mfma_f32_16x16x32_bf16 v[54:57], v[46:49], v[170:173], v[54:57]
	v_mfma_f32_16x16x32_bf16 v[38:41], v[30:33], v[178:181], v[38:41]
	v_mfma_f32_16x16x32_bf16 v[22:25], v[46:49], v[178:181], v[22:25]
	v_mfma_f32_16x16x32_bf16 v[14:17], v[30:33], v[186:189], v[14:17]
	v_mfma_f32_16x16x32_bf16 v[6:9], v[46:49], v[186:189], v[6:9]
	s_barrier
	s_mov_b32 m0, s1
	v_lshl_add_u64 v[26:27], s[58:59], 0, v[158:159]
	global_load_lds_dwordx4 v[26:27], off
	v_lshl_add_u64 v[26:27], s[58:59], 0, v[154:155]
	s_mov_b32 m0, s96
	s_nop 0
	global_load_lds_dwordx4 v[26:27], off
	s_waitcnt vmcnt(10)
	s_barrier
	v_mfma_f32_16x16x32_bf16 v[34:37], v[190:193], v[174:177], v[34:37]
	v_mfma_f32_16x16x32_bf16 v[18:21], v[198:201], v[174:177], v[18:21]
	v_mfma_f32_16x16x32_bf16 v[10:13], v[190:193], v[182:185], v[10:13]
	v_mfma_f32_16x16x32_bf16 v[2:5], v[198:201], v[182:185], v[2:5]
	v_mfma_f32_16x16x32_bf16 v[26:29], v[190:193], v[146:149], v[74:77]
	v_mfma_f32_16x16x32_bf16 v[30:33], v[198:201], v[146:149], v[66:69]
	v_mfma_f32_16x16x32_bf16 v[42:45], v[190:193], v[166:169], v[58:61]
	v_mfma_f32_16x16x32_bf16 v[46:49], v[198:201], v[166:169], v[50:53]
	v_mfma_f32_16x16x32_bf16 v[34:37], v[194:197], v[178:181], v[34:37]
	v_mfma_f32_16x16x32_bf16 v[18:21], v[202:205], v[178:181], v[18:21]
	v_mfma_f32_16x16x32_bf16 v[10:13], v[194:197], v[186:189], v[10:13]
	v_mfma_f32_16x16x32_bf16 v[2:5], v[202:205], v[186:189], v[2:5]
	v_mfma_f32_16x16x32_bf16 v[26:29], v[194:197], v[150:153], v[26:29]
	v_mfma_f32_16x16x32_bf16 v[30:33], v[202:205], v[150:153], v[30:33]
	v_mfma_f32_16x16x32_bf16 v[42:45], v[194:197], v[170:173], v[42:45]
	v_mfma_f32_16x16x32_bf16 v[46:49], v[202:205], v[170:173], v[46:49]
	v_add_u32_e32 v74, s81, v224
	s_barrier
	ds_read_b128 v[50:53], v74
	ds_read_b128 v[58:61], v74 offset:1024
	ds_read_b128 v[66:69], v74 offset:2048
	ds_read_b128 v[74:77], v74 offset:3072
	s_mov_b32 m0, s66
	v_lshl_add_u64 v[190:191], s[56:57], 0, v[160:161]
	ds_read_b128 v[146:149], v226 offset:32768
	ds_read_b128 v[150:153], v226 offset:33792
	ds_read_b128 v[166:169], v226 offset:34816
	ds_read_b128 v[170:173], v226 offset:35840
	ds_read_b128 v[174:177], v226 offset:36864
	ds_read_b128 v[178:181], v226 offset:37888
	ds_read_b128 v[182:185], v226 offset:38912
	ds_read_b128 v[186:189], v226 offset:39936
	global_load_lds_dwordx4 v[190:191], off
	v_lshl_add_u64 v[190:191], s[56:57], 0, v[156:157]
	s_mov_b32 m0, s67
	s_nop 0
	global_load_lds_dwordx4 v[190:191], off
	s_waitcnt lgkmcnt(8)
	s_waitcnt vmcnt(10)
	s_barrier
	s_waitcnt lgkmcnt(0)
	s_waitcnt lgkmcnt(0)
	v_mfma_f32_16x16x32_bf16 v[142:145], v[50:53], v[146:149], v[142:145]
	v_mfma_f32_16x16x32_bf16 v[134:137], v[66:69], v[146:149], v[134:137]
	v_mfma_f32_16x16x32_bf16 v[126:129], v[50:53], v[166:169], v[126:129]
	v_mfma_f32_16x16x32_bf16 v[118:121], v[66:69], v[166:169], v[118:121]
	v_mfma_f32_16x16x32_bf16 v[110:113], v[50:53], v[174:177], v[110:113]
	v_mfma_f32_16x16x32_bf16 v[102:105], v[66:69], v[174:177], v[102:105]
	v_mfma_f32_16x16x32_bf16 v[94:97], v[50:53], v[182:185], v[94:97]
	v_mfma_f32_16x16x32_bf16 v[86:89], v[66:69], v[182:185], v[86:89]
	v_mfma_f32_16x16x32_bf16 v[142:145], v[58:61], v[150:153], v[142:145]
	v_mfma_f32_16x16x32_bf16 v[134:137], v[74:77], v[150:153], v[134:137]
	v_mfma_f32_16x16x32_bf16 v[126:129], v[58:61], v[170:173], v[126:129]
	v_mfma_f32_16x16x32_bf16 v[118:121], v[74:77], v[170:173], v[118:121]
	v_mfma_f32_16x16x32_bf16 v[110:113], v[58:61], v[178:181], v[110:113]
	v_mfma_f32_16x16x32_bf16 v[102:105], v[74:77], v[178:181], v[102:105]
	v_mfma_f32_16x16x32_bf16 v[94:97], v[58:61], v[186:189], v[94:97]
	v_mfma_f32_16x16x32_bf16 v[86:89], v[74:77], v[186:189], v[86:89]
	s_barrier
	s_mov_b32 m0, s78
	v_add_u32_e32 v202, s79, v224
	v_lshl_add_u64 v[206:207], v[206:207], 0, s[26:27]
	ds_read_b128 v[190:193], v202
	ds_read_b128 v[194:197], v202 offset:1024
	ds_read_b128 v[198:201], v202 offset:2048
	ds_read_b128 v[202:205], v202 offset:3072
	global_load_lds_dwordx4 v[206:207], off
	v_lshl_add_u64 v[206:207], v[208:209], 0, s[26:27]
	s_mov_b32 m0, s80
	s_nop 0
	global_load_lds_dwordx4 v[206:207], off
	s_waitcnt vmcnt(10)
	s_barrier
	s_waitcnt lgkmcnt(0)
	s_waitcnt lgkmcnt(0)
	v_mfma_f32_16x16x32_bf16 v[138:141], v[190:193], v[146:149], v[138:141]
	v_mfma_f32_16x16x32_bf16 v[130:133], v[198:201], v[146:149], v[130:133]
	v_mfma_f32_16x16x32_bf16 v[122:125], v[190:193], v[166:169], v[122:125]
	v_mfma_f32_16x16x32_bf16 v[114:117], v[198:201], v[166:169], v[114:117]
	v_mfma_f32_16x16x32_bf16 v[106:109], v[190:193], v[174:177], v[106:109]
	v_mfma_f32_16x16x32_bf16 v[98:101], v[198:201], v[174:177], v[98:101]
	v_mfma_f32_16x16x32_bf16 v[90:93], v[190:193], v[182:185], v[90:93]
	v_mfma_f32_16x16x32_bf16 v[82:85], v[198:201], v[182:185], v[82:85]
	v_mfma_f32_16x16x32_bf16 v[138:141], v[194:197], v[150:153], v[138:141]
	v_mfma_f32_16x16x32_bf16 v[130:133], v[202:205], v[150:153], v[130:133]
	v_mfma_f32_16x16x32_bf16 v[122:125], v[194:197], v[170:173], v[122:125]
	v_mfma_f32_16x16x32_bf16 v[114:117], v[202:205], v[170:173], v[114:117]
	v_mfma_f32_16x16x32_bf16 v[106:109], v[194:197], v[178:181], v[106:109]
	v_mfma_f32_16x16x32_bf16 v[98:101], v[202:205], v[178:181], v[98:101]
	v_mfma_f32_16x16x32_bf16 v[90:93], v[194:197], v[186:189], v[90:93]
	v_mfma_f32_16x16x32_bf16 v[82:85], v[202:205], v[186:189], v[82:85]
	s_mov_b32 m0, s6
	v_lshl_add_u64 v[206:207], v[210:211], 0, s[26:27]
	s_barrier
	ds_read_b128 v[146:149], v226 offset:49152
	ds_read_b128 v[150:153], v226 offset:50176
	ds_read_b128 v[166:169], v226 offset:51200
	ds_read_b128 v[170:173], v226 offset:52224
	ds_read_b128 v[174:177], v226 offset:53248
	ds_read_b128 v[178:181], v226 offset:54272
	ds_read_b128 v[182:185], v226 offset:55296
	ds_read_b128 v[186:189], v226 offset:56320
	global_load_lds_dwordx4 v[206:207], off
	v_lshl_add_u64 v[206:207], v[212:213], 0, s[26:27]
	s_mov_b32 m0, s7
	s_nop 0
	global_load_lds_dwordx4 v[206:207], off
	s_waitcnt vmcnt(10)
	s_barrier
	s_waitcnt lgkmcnt(0)
	s_waitcnt lgkmcnt(0)
	v_mfma_f32_16x16x32_bf16 v[78:81], v[50:53], v[146:149], v[78:81]
	v_mfma_f32_16x16x32_bf16 v[70:73], v[66:69], v[146:149], v[70:73]
	v_mfma_f32_16x16x32_bf16 v[62:65], v[50:53], v[166:169], v[62:65]
	v_mfma_f32_16x16x32_bf16 v[54:57], v[66:69], v[166:169], v[54:57]
	v_mfma_f32_16x16x32_bf16 v[38:41], v[50:53], v[174:177], v[38:41]
	v_mfma_f32_16x16x32_bf16 v[22:25], v[66:69], v[174:177], v[22:25]
	v_mfma_f32_16x16x32_bf16 v[14:17], v[50:53], v[182:185], v[14:17]
	v_mfma_f32_16x16x32_bf16 v[6:9], v[66:69], v[182:185], v[6:9]
	v_mfma_f32_16x16x32_bf16 v[78:81], v[58:61], v[150:153], v[78:81]
	v_mfma_f32_16x16x32_bf16 v[70:73], v[74:77], v[150:153], v[70:73]
	v_mfma_f32_16x16x32_bf16 v[62:65], v[58:61], v[170:173], v[62:65]
	v_mfma_f32_16x16x32_bf16 v[54:57], v[74:77], v[170:173], v[54:57]
	v_mfma_f32_16x16x32_bf16 v[38:41], v[58:61], v[178:181], v[38:41]
	v_mfma_f32_16x16x32_bf16 v[22:25], v[74:77], v[178:181], v[22:25]
	v_mfma_f32_16x16x32_bf16 v[14:17], v[58:61], v[186:189], v[14:17]
	v_mfma_f32_16x16x32_bf16 v[6:9], v[74:77], v[186:189], v[6:9]
	s_barrier
	s_mov_b32 m0, vcc_hi
	v_lshl_add_u64 v[50:51], s[54:55], 0, v[158:159]
	global_load_lds_dwordx4 v[50:51], off
	v_lshl_add_u64 v[50:51], s[54:55], 0, v[154:155]
	s_mov_b32 m0, vcc_lo
	s_nop 0
	global_load_lds_dwordx4 v[50:51], off
	s_waitcnt vmcnt(10)
	s_barrier
	v_mfma_f32_16x16x32_bf16 v[26:29], v[190:193], v[146:149], v[26:29]
	v_mfma_f32_16x16x32_bf16 v[74:77], v[194:197], v[150:153], v[26:29]
	v_mfma_f32_16x16x32_bf16 v[26:29], v[198:201], v[146:149], v[30:33]
	v_mfma_f32_16x16x32_bf16 v[66:69], v[202:205], v[150:153], v[26:29]
	v_mfma_f32_16x16x32_bf16 v[26:29], v[190:193], v[166:169], v[42:45]
	v_mfma_f32_16x16x32_bf16 v[58:61], v[194:197], v[170:173], v[26:29]
	v_mfma_f32_16x16x32_bf16 v[26:29], v[198:201], v[166:169], v[46:49]
	v_mfma_f32_16x16x32_bf16 v[50:53], v[202:205], v[170:173], v[26:29]
	v_mfma_f32_16x16x32_bf16 v[26:29], v[190:193], v[174:177], v[34:37]
	v_mfma_f32_16x16x32_bf16 v[18:21], v[198:201], v[174:177], v[18:21]
	v_mfma_f32_16x16x32_bf16 v[10:13], v[190:193], v[182:185], v[10:13]
	v_mfma_f32_16x16x32_bf16 v[2:5], v[198:201], v[182:185], v[2:5]
	v_mfma_f32_16x16x32_bf16 v[34:37], v[194:197], v[178:181], v[26:29]
	v_mfma_f32_16x16x32_bf16 v[18:21], v[202:205], v[178:181], v[18:21]
	v_mfma_f32_16x16x32_bf16 v[10:13], v[194:197], v[186:189], v[10:13]
	v_mfma_f32_16x16x32_bf16 v[2:5], v[202:205], v[186:189], v[2:5]
	s_movk_i32 s56, 0x100
	s_andn2_b64 vcc, exec, s[50:51]
	s_mov_b64 s[54:55], -1
	s_mov_b64 s[50:51], 0
	s_barrier
	s_cbranch_vccz .LBB0_1645
	s_lshl_b32 s0, s82, 7
	s_and_b32 s1, s0, 0x380
	v_mov_b32_e32 v167, v222
	v_mov_b32_e32 v26, v223
	s_or_b32 s1, s1, s11
	s_cmp_lt_u32 s82, 8
	v_lshl_add_u32 v166, v26, 3, s1
	s_mov_b32 s1, 0x32100000
	s_cselect_b32 s1, s1, 0x1a100000
	s_cselect_b32 s49, s9, s17
	s_cselect_b32 s48, s8, s16
	s_add_u32 s50, s18, s1
	s_addc_u32 s51, s19, 0
	s_and_b32 s0, s0, 0xfffffc00
	v_add_u32_e32 v26, s0, v166
	s_load_dwordx2 s[0:1], s[20:21], 0x78
	v_ashrrev_i32_e32 v27, 31, v26
	v_readlane_b32 s56, v254, 5
	v_lshlrev_b64 v[146:147], 2, v[26:27]
	v_readlane_b32 s57, v254, 6
	v_readlane_b32 s58, v254, 7
	v_readlane_b32 s59, v254, 8
	s_waitcnt lgkmcnt(0)
	v_lshl_add_u64 v[26:27], s[0:1], 0, v[146:147]
	v_lshl_add_u64 v[42:43], s[56:57], 0, v[146:147]
	v_lshl_add_u64 v[150:151], s[58:59], 0, v[146:147]
	global_load_dwordx4 v[30:33], v[26:27], off offset:16
	global_load_dwordx4 v[46:49], v[26:27], off
	s_nop 0
	global_load_dwordx4 v[26:29], v[42:43], off offset:16
	s_nop 0
	global_load_dwordx4 v[42:45], v[42:43], off
	s_nop 0
	global_load_dwordx4 v[146:149], v[150:151], off offset:16
	s_nop 0
	global_load_dwordx4 v[150:153], v[150:151], off
	s_lshl_b32 s0, s52, 8
	s_add_i32 s0, s0, s10
	s_waitcnt vmcnt(0)
	v_add_f32_e32 v134, v134, v30
	v_add_f32_e32 v142, v142, v46
	v_add_f32_e32 v138, v138, v42
	v_max_f32_e32 v168, v150, v150
	v_mul_f32_e64 v150, |v150|, s5
	v_exp_f32_e32 v232, v150
	v_mul_f32_e32 v138, 0xbfb8aa3b, v138
	v_exp_f32_e32 v138, v138
	v_mul_f32_e32 v142, 0xbfb8aa3b, v142
	v_add_f32_e32 v172, 1.0, v232
	v_add_f32_e32 v150, -1.0, v172
	v_sub_f32_e32 v169, v150, v172
	v_add_f32_e32 v169, 1.0, v169
	v_sub_f32_e32 v150, v232, v150
	v_add_f32_e32 v174, v150, v169
	v_max_f32_e32 v150, v151, v151
	v_min_f32_e32 v169, 0, v150
	v_mul_f32_e64 v150, |v151|, s5
	v_exp_f32_e32 v233, v150
	v_cvt_f64_f32_e32 v[170:171], v172
	v_frexp_exp_i32_f64_e32 v170, v[170:171]
	v_frexp_mant_f32_e32 v173, v172
	v_add_f32_e32 v171, 1.0, v233
	v_add_f32_e32 v150, -1.0, v171
	v_sub_f32_e32 v151, v150, v171
	v_add_f32_e32 v151, 1.0, v151
	v_sub_f32_e32 v150, v233, v150
	v_add_f32_e32 v175, v150, v151
	v_frexp_mant_f32_e32 v176, v171
	v_cvt_f64_f32_e32 v[150:151], v171
	v_cmp_gt_f32_e32 vcc, s72, v173
	v_frexp_exp_i32_f64_e32 v150, v[150:151]
	v_cmp_gt_f32_e64 s[14:15], s72, v176
	v_subbrev_co_u32_e32 v176, vcc, 0, v170, vcc
	s_nop 0
	v_subbrev_co_u32_e64 v173, s[14:15], 0, v150, s[14:15]
	v_sub_u32_e32 v151, 0, v176
	v_ldexp_f32 v150, v172, v151
	v_sub_u32_e32 v172, 0, v173
	v_ldexp_f32 v170, v174, v151
	v_ldexp_f32 v151, v171, v172
	v_ldexp_f32 v171, v175, v172
	v_pk_add_f32 v[174:175], v[150:151], 1.0 op_sel_hi:[1,0]
	v_pk_add_f32 v[184:185], v[150:151], -1.0 op_sel_hi:[1,0]
	v_pk_add_f32 v[178:179], v[174:175], -1.0 op_sel_hi:[1,0]
	v_pk_add_f32 v[186:187], v[184:185], 1.0 op_sel_hi:[1,0]
	v_pk_add_f32 v[178:179], v[150:151], v[178:179] neg_lo:[0,1] neg_hi:[0,1]
	v_pk_add_f32 v[150:151], v[150:151], v[186:187] neg_lo:[0,1] neg_hi:[0,1]
	v_pk_add_f32 v[178:179], v[170:171], v[178:179]
	v_pk_add_f32 v[150:151], v[170:171], v[150:151]
	v_pk_add_f32 v[180:181], v[174:175], v[178:179]
	v_pk_add_f32 v[170:171], v[184:185], v[150:151]
	v_rcp_f32_e32 v182, v180
	v_rcp_f32_e32 v183, v181
	v_pk_add_f32 v[174:175], v[180:181], v[174:175] neg_lo:[0,1] neg_hi:[0,1]
	v_pk_add_f32 v[184:185], v[170:171], v[184:185] neg_lo:[0,1] neg_hi:[0,1]
	v_pk_add_f32 v[174:175], v[178:179], v[174:175] neg_lo:[0,1] neg_hi:[0,1]
	v_pk_mul_f32 v[186:187], v[170:171], v[182:183]
	v_pk_add_f32 v[150:151], v[150:151], v[184:185] neg_lo:[0,1] neg_hi:[0,1]
	v_pk_mul_f32 v[178:179], v[180:181], v[186:187]
	s_mov_b32 s14, 0x3ecc95a3
	v_pk_fma_f32 v[184:185], v[186:187], v[180:181], v[178:179] neg_lo:[0,0,1] neg_hi:[0,0,1]
	v_cvt_f32_i32_e32 v177, v173
	v_pk_fma_f32 v[184:185], v[186:187], v[174:175], v[184:185]
	v_cvt_f32_i32_e32 v176, v176
	v_pk_add_f32 v[188:189], v[178:179], v[184:185]
	v_add_f32_e32 v138, 1.0, v138
	v_pk_add_f32 v[190:191], v[170:171], v[188:189] neg_lo:[0,1] neg_hi:[0,1]
	v_pk_add_f32 v[178:179], v[188:189], v[178:179] neg_lo:[0,1] neg_hi:[0,1]
	v_pk_add_f32 v[170:171], v[170:171], v[190:191] neg_lo:[0,1] neg_hi:[0,1]
	v_rcp_f32_e32 v249, v138
	v_pk_add_f32 v[170:171], v[170:171], v[188:189] neg_lo:[0,1] neg_hi:[0,1]
	v_add_f32_e32 v138, v143, v47
	v_pk_add_f32 v[150:151], v[150:151], v[170:171]
	v_pk_add_f32 v[170:171], v[178:179], v[184:185] neg_lo:[0,1] neg_hi:[0,1]
	v_mul_f32_e32 v138, 0xbfb8aa3b, v138
	v_pk_add_f32 v[150:151], v[170:171], v[150:151]
	v_exp_f32_e32 v138, v138
	v_pk_add_f32 v[170:171], v[190:191], v[150:151]
	v_exp_f32_e32 v142, v142
	v_pk_mul_f32 v[178:179], v[182:183], v[170:171]
	v_pk_add_f32 v[190:191], v[190:191], v[170:171] neg_lo:[0,1] neg_hi:[0,1]
	v_pk_mul_f32 v[184:185], v[180:181], v[178:179]
	v_pk_add_f32 v[150:151], v[150:151], v[190:191]
	v_pk_fma_f32 v[180:181], v[178:179], v[180:181], v[184:185] neg_lo:[0,0,1] neg_hi:[0,0,1]
	v_pk_add_f32 v[196:197], v[186:187], v[178:179]
	v_pk_fma_f32 v[174:175], v[178:179], v[174:175], v[180:181]
	v_add_f32_e32 v138, 1.0, v138
	v_pk_add_f32 v[180:181], v[184:185], v[174:175]
	v_rcp_f32_e32 v143, v138
	v_pk_add_f32 v[192:193], v[170:171], v[180:181] neg_lo:[0,1] neg_hi:[0,1]
	v_pk_add_f32 v[188:189], v[180:181], v[184:185] neg_lo:[0,1] neg_hi:[0,1]
	v_pk_add_f32 v[194:195], v[170:171], v[192:193] neg_lo:[0,1] neg_hi:[0,1]
	v_mov_b32_e32 v170, v181
	v_mov_b32_e32 v184, v185
	v_mov_b32_e32 v185, v193
	v_pk_add_f32 v[194:195], v[194:195], v[180:181] neg_lo:[0,1] neg_hi:[0,1]
	v_pk_add_f32 v[170:171], v[170:171], v[184:185] neg_lo:[0,1] neg_hi:[0,1]
	v_mov_b32_e32 v180, v175
	v_pk_add_f32 v[170:171], v[170:171], v[180:181] neg_lo:[0,1] neg_hi:[0,1]
	v_pk_add_f32 v[188:189], v[188:189], v[174:175] neg_lo:[0,1] neg_hi:[0,1]
	v_mov_b32_e32 v195, v171
	v_pk_add_f32 v[150:151], v[150:151], v[194:195]
	v_mov_b32_e32 v189, v170
	v_pk_add_f32 v[150:151], v[188:189], v[150:151]
	v_pk_add_f32 v[170:171], v[196:197], v[186:187] neg_lo:[0,1] neg_hi:[0,1]
	v_pk_add_f32 v[150:151], v[192:193], v[150:151]
	v_pk_add_f32 v[170:171], v[178:179], v[170:171] neg_lo:[0,1] neg_hi:[0,1]
	v_pk_mul_f32 v[150:151], v[182:183], v[150:151]
	v_pk_mul_f32 v[182:183], v[176:177], s[34:35] op_sel_hi:[1,0]
	v_pk_add_f32 v[150:151], v[170:171], v[150:151]
	v_pk_fma_f32 v[184:185], v[176:177], s[34:35], v[182:183] op_sel_hi:[1,0,1] neg_lo:[0,0,1] neg_hi:[0,0,1]
	v_pk_add_f32 v[174:175], v[196:197], v[150:151]
	v_pk_fma_f32 v[184:185], v[176:177], s[36:37], v[184:185] op_sel_hi:[1,0,1]
	v_pk_add_f32 v[170:171], v[174:175], v[196:197] neg_lo:[0,1] neg_hi:[0,1]
	v_pk_mul_f32 v[178:179], v[174:175], v[174:175]
	v_pk_add_f32 v[170:171], v[150:151], v[170:171] neg_lo:[0,1] neg_hi:[0,1]
	v_mov_b64_e32 v[150:151], s[14:15]
	v_pk_fma_f32 v[180:181], v[178:179], s[28:29], v[150:151] op_sel_hi:[1,0,0]
	v_ldexp_f32 v172, v174, 1
	v_pk_fma_f32 v[180:181], v[178:179], v[180:181], s[30:31] op_sel_hi:[1,1,0]
	v_ldexp_f32 v173, v175, 1
	v_pk_mul_f32 v[174:175], v[174:175], v[178:179]
	v_ldexp_f32 v170, v170, 1
	v_pk_mul_f32 v[174:175], v[174:175], v[180:181]
	v_ldexp_f32 v171, v171, 1
	v_pk_add_f32 v[178:179], v[172:173], v[174:175]
	v_pk_add_f32 v[176:177], v[182:183], v[184:185]
	v_pk_add_f32 v[172:173], v[178:179], v[172:173] neg_lo:[0,1] neg_hi:[0,1]
	v_pk_add_f32 v[182:183], v[176:177], v[182:183] neg_lo:[0,1] neg_hi:[0,1]
	v_pk_add_f32 v[172:173], v[174:175], v[172:173] neg_lo:[0,1] neg_hi:[0,1]
	v_pk_add_f32 v[182:183], v[184:185], v[182:183] neg_lo:[0,1] neg_hi:[0,1]
	v_pk_add_f32 v[170:171], v[170:171], v[172:173]
	v_add_f32_e32 v138, v139, v43
	v_pk_add_f32 v[190:191], v[178:179], v[170:171]
	v_mul_f32_e32 v138, 0xbfb8aa3b, v138
	v_pk_add_f32 v[172:173], v[190:191], v[178:179] neg_lo:[0,1] neg_hi:[0,1]
	v_exp_f32_e32 v138, v138
	v_pk_add_f32 v[170:171], v[170:171], v[172:173] neg_lo:[0,1] neg_hi:[0,1]
	v_add_f32_e32 v142, 1.0, v142
	v_pk_add_f32 v[184:185], v[182:183], v[170:171]
	v_add_f32_e32 v138, 1.0, v138
	v_pk_add_f32 v[172:173], v[184:185], v[182:183] neg_lo:[0,1] neg_hi:[0,1]
	v_rcp_f32_e32 v250, v138
	v_pk_add_f32 v[188:189], v[170:171], v[172:173] neg_lo:[0,1] neg_hi:[0,1]
	v_max_f32_e32 v170, v152, v152
	v_mul_f32_e64 v152, |v152|, s5
	v_exp_f32_e32 v236, v152
	v_pk_add_f32 v[174:175], v[184:185], v[172:173] neg_lo:[0,1] neg_hi:[0,1]
	v_min_f32_e32 v180, 0, v170
	v_pk_add_f32 v[186:187], v[182:183], v[174:175] neg_lo:[0,1] neg_hi:[0,1]
	v_add_f32_e32 v172, 1.0, v236
	v_add_f32_e32 v152, -1.0, v172
	v_sub_f32_e32 v170, v152, v172
	v_add_f32_e32 v170, 1.0, v170
	v_sub_f32_e32 v152, v236, v152
	v_add_f32_e32 v173, v152, v170
	v_max_f32_e32 v152, v153, v153
	v_min_f32_e32 v181, 0, v152
	v_mul_f32_e64 v152, |v153|, s5
	v_exp_f32_e32 v238, v152
	v_cvt_f64_f32_e32 v[170:171], v172
	v_frexp_exp_i32_f64_e32 v170, v[170:171]
	v_frexp_mant_f32_e32 v174, v172
	v_add_f32_e32 v171, 1.0, v238
	v_add_f32_e32 v152, -1.0, v171
	v_sub_f32_e32 v153, v152, v171
	v_add_f32_e32 v153, 1.0, v153
	v_sub_f32_e32 v152, v238, v152
	v_add_f32_e32 v175, v152, v153
	v_frexp_mant_f32_e32 v178, v171
	v_cvt_f64_f32_e32 v[152:153], v171
	v_cmp_gt_f32_e32 vcc, s72, v174
	v_frexp_exp_i32_f64_e32 v152, v[152:153]
	v_cmp_gt_f32_e64 s[14:15], s72, v178
	v_subbrev_co_u32_e32 v207, vcc, 0, v170, vcc
	s_nop 0
	v_subbrev_co_u32_e64 v206, s[14:15], 0, v152, s[14:15]
	v_sub_u32_e32 v153, 0, v207
	v_ldexp_f32 v152, v172, v153
	v_sub_u32_e32 v172, 0, v206
	v_ldexp_f32 v170, v173, v153
	v_ldexp_f32 v153, v171, v172
	v_ldexp_f32 v171, v175, v172
	v_pk_add_f32 v[172:173], v[152:153], 1.0 op_sel_hi:[1,0]
	v_pk_add_f32 v[192:193], v[152:153], -1.0 op_sel_hi:[1,0]
	v_pk_add_f32 v[174:175], v[172:173], -1.0 op_sel_hi:[1,0]
	v_pk_add_f32 v[194:195], v[192:193], 1.0 op_sel_hi:[1,0]
	v_pk_add_f32 v[174:175], v[152:153], v[174:175] neg_lo:[0,1] neg_hi:[0,1]
	v_pk_add_f32 v[152:153], v[152:153], v[194:195] neg_lo:[0,1] neg_hi:[0,1]
	v_pk_add_f32 v[174:175], v[170:171], v[174:175]
	v_pk_add_f32 v[152:153], v[170:171], v[152:153]
	v_pk_add_f32 v[178:179], v[172:173], v[174:175]
	v_pk_add_f32 v[170:171], v[192:193], v[152:153]
	v_rcp_f32_e32 v182, v178
	v_rcp_f32_e32 v183, v179
	v_pk_add_f32 v[172:173], v[178:179], v[172:173] neg_lo:[0,1] neg_hi:[0,1]
	v_pk_add_f32 v[192:193], v[170:171], v[192:193] neg_lo:[0,1] neg_hi:[0,1]
	v_pk_add_f32 v[172:173], v[174:175], v[172:173] neg_lo:[0,1] neg_hi:[0,1]
	v_pk_mul_f32 v[194:195], v[170:171], v[182:183]
	v_pk_add_f32 v[152:153], v[152:153], v[192:193] neg_lo:[0,1] neg_hi:[0,1]
	v_pk_mul_f32 v[174:175], v[178:179], v[194:195]
	v_add_f32_e32 v138, v144, v48
	v_pk_fma_f32 v[192:193], v[194:195], v[178:179], v[174:175] neg_lo:[0,0,1] neg_hi:[0,0,1]
	v_mul_f32_e32 v138, 0xbfb8aa3b, v138
	v_pk_fma_f32 v[192:193], v[194:195], v[172:173], v[192:193]
	v_exp_f32_e32 v138, v138
	v_pk_add_f32 v[196:197], v[174:175], v[192:193]
	v_rcp_f32_e32 v142, v142
	v_pk_add_f32 v[198:199], v[170:171], v[196:197] neg_lo:[0,1] neg_hi:[0,1]
	v_pk_add_f32 v[174:175], v[196:197], v[174:175] neg_lo:[0,1] neg_hi:[0,1]
	v_pk_add_f32 v[170:171], v[170:171], v[198:199] neg_lo:[0,1] neg_hi:[0,1]
	v_add_f32_e32 v138, 1.0, v138
	v_pk_add_f32 v[170:171], v[170:171], v[196:197] neg_lo:[0,1] neg_hi:[0,1]
	v_min_f32_e32 v168, 0, v168
	v_pk_add_f32 v[152:153], v[152:153], v[170:171]
	v_pk_add_f32 v[170:171], v[174:175], v[192:193] neg_lo:[0,1] neg_hi:[0,1]
	v_add_f32_e32 v130, v130, v26
	v_pk_add_f32 v[152:153], v[170:171], v[152:153]
	v_mul_f32_e32 v130, 0xbfb8aa3b, v130
	v_pk_add_f32 v[170:171], v[198:199], v[152:153]
	v_exp_f32_e32 v130, v130
	v_pk_mul_f32 v[174:175], v[182:183], v[170:171]
	v_pk_add_f32 v[198:199], v[198:199], v[170:171] neg_lo:[0,1] neg_hi:[0,1]
	v_pk_mul_f32 v[192:193], v[178:179], v[174:175]
	v_pk_add_f32 v[152:153], v[152:153], v[198:199]
	v_pk_fma_f32 v[178:179], v[174:175], v[178:179], v[192:193] neg_lo:[0,0,1] neg_hi:[0,0,1]
	v_pk_add_f32 v[204:205], v[194:195], v[174:175]
	v_pk_fma_f32 v[172:173], v[174:175], v[172:173], v[178:179]
	v_add_f32_e32 v130, 1.0, v130
	v_pk_add_f32 v[178:179], v[192:193], v[172:173]
	v_mul_f32_e32 v134, 0xbfb8aa3b, v134
	v_pk_add_f32 v[200:201], v[170:171], v[178:179] neg_lo:[0,1] neg_hi:[0,1]
	v_pk_add_f32 v[196:197], v[178:179], v[192:193] neg_lo:[0,1] neg_hi:[0,1]
	v_pk_add_f32 v[202:203], v[170:171], v[200:201] neg_lo:[0,1] neg_hi:[0,1]
	v_mov_b32_e32 v170, v179
	v_mov_b32_e32 v192, v193
	v_mov_b32_e32 v193, v201
	v_pk_add_f32 v[202:203], v[202:203], v[178:179] neg_lo:[0,1] neg_hi:[0,1]
	v_pk_add_f32 v[170:171], v[170:171], v[192:193] neg_lo:[0,1] neg_hi:[0,1]
	v_mov_b32_e32 v178, v173
	v_pk_add_f32 v[170:171], v[170:171], v[178:179] neg_lo:[0,1] neg_hi:[0,1]
	v_pk_add_f32 v[196:197], v[196:197], v[172:173] neg_lo:[0,1] neg_hi:[0,1]
	v_mov_b32_e32 v203, v171
	v_pk_add_f32 v[152:153], v[152:153], v[202:203]
	v_mov_b32_e32 v197, v170
	v_pk_add_f32 v[152:153], v[196:197], v[152:153]
	v_pk_add_f32 v[170:171], v[204:205], v[194:195] neg_lo:[0,1] neg_hi:[0,1]
	v_pk_add_f32 v[152:153], v[200:201], v[152:153]
	v_pk_add_f32 v[170:171], v[174:175], v[170:171] neg_lo:[0,1] neg_hi:[0,1]
	v_pk_mul_f32 v[152:153], v[182:183], v[152:153]
	v_cvt_f32_i32_e32 v183, v206
	v_pk_add_f32 v[152:153], v[170:171], v[152:153]
	v_cvt_f32_i32_e32 v182, v207
	v_pk_add_f32 v[170:171], v[204:205], v[152:153]
	v_exp_f32_e32 v134, v134
	v_pk_mul_f32 v[174:175], v[170:171], v[170:171]
	v_pk_add_f32 v[172:173], v[170:171], v[204:205] neg_lo:[0,1] neg_hi:[0,1]
	v_pk_fma_f32 v[178:179], v[174:175], s[28:29], v[150:151] op_sel_hi:[1,0,0]
	v_pk_add_f32 v[152:153], v[152:153], v[172:173] neg_lo:[0,1] neg_hi:[0,1]
	v_ldexp_f32 v172, v170, 1
	v_pk_fma_f32 v[178:179], v[174:175], v[178:179], s[30:31] op_sel_hi:[1,1,0]
	v_ldexp_f32 v173, v171, 1
	v_pk_mul_f32 v[170:171], v[170:171], v[174:175]
	v_pk_mul_f32 v[192:193], v[182:183], s[34:35] op_sel_hi:[1,0]
	v_pk_mul_f32 v[170:171], v[170:171], v[178:179]
	v_ldexp_f32 v152, v152, 1
	v_pk_add_f32 v[174:175], v[172:173], v[170:171]
	v_pk_fma_f32 v[194:195], v[182:183], s[34:35], v[192:193] op_sel_hi:[1,0,1] neg_lo:[0,0,1] neg_hi:[0,0,1]
	v_pk_add_f32 v[172:173], v[174:175], v[172:173] neg_lo:[0,1] neg_hi:[0,1]
	v_ldexp_f32 v153, v153, 1
	v_pk_add_f32 v[170:171], v[170:171], v[172:173] neg_lo:[0,1] neg_hi:[0,1]
	v_pk_fma_f32 v[182:183], v[182:183], s[36:37], v[194:195] op_sel_hi:[1,0,1]
	v_pk_add_f32 v[152:153], v[152:153], v[170:171]
	v_pk_add_f32 v[202:203], v[192:193], v[182:183]
	v_pk_add_f32 v[210:211], v[174:175], v[152:153]
	v_pk_add_f32 v[192:193], v[202:203], v[192:193] neg_lo:[0,1] neg_hi:[0,1]
	v_pk_add_f32 v[170:171], v[210:211], v[174:175] neg_lo:[0,1] neg_hi:[0,1]
	v_pk_add_f32 v[182:183], v[182:183], v[192:193] neg_lo:[0,1] neg_hi:[0,1]
	v_pk_add_f32 v[152:153], v[152:153], v[170:171] neg_lo:[0,1] neg_hi:[0,1]
	v_add_f32_e32 v134, 1.0, v134
	v_pk_add_f32 v[204:205], v[182:183], v[152:153]
	v_rcp_f32_e32 v134, v134
	v_pk_add_f32 v[170:171], v[204:205], v[182:183] neg_lo:[0,1] neg_hi:[0,1]
	v_add_f32_e32 v126, v126, v46
	v_pk_add_f32 v[208:209], v[152:153], v[170:171] neg_lo:[0,1] neg_hi:[0,1]
	v_max_f32_e32 v152, v146, v146
	v_mul_f32_e64 v146, |v146|, s5
	v_exp_f32_e32 v235, v146
	v_pk_add_f32 v[172:173], v[204:205], v[170:171] neg_lo:[0,1] neg_hi:[0,1]
	v_min_f32_e32 v178, 0, v152
	v_pk_add_f32 v[206:207], v[182:183], v[172:173] neg_lo:[0,1] neg_hi:[0,1]
	v_add_f32_e32 v170, 1.0, v235
	v_add_f32_e32 v146, -1.0, v170
	v_sub_f32_e32 v152, v146, v170
	v_add_f32_e32 v152, 1.0, v152
	v_sub_f32_e32 v146, v235, v146
	v_add_f32_e32 v171, v146, v152
	v_max_f32_e32 v146, v147, v147
	v_min_f32_e32 v179, 0, v146
	v_mul_f32_e64 v146, |v147|, s5
	v_exp_f32_e32 v237, v146
	v_cvt_f64_f32_e32 v[152:153], v170
	v_frexp_exp_i32_f64_e32 v152, v[152:153]
	v_frexp_mant_f32_e32 v172, v170
	v_add_f32_e32 v153, 1.0, v237
	v_add_f32_e32 v146, -1.0, v153
	v_sub_f32_e32 v147, v146, v153
	v_add_f32_e32 v147, 1.0, v147
	v_sub_f32_e32 v146, v237, v146
	v_add_f32_e32 v173, v146, v147
	v_frexp_mant_f32_e32 v174, v153
	v_cvt_f64_f32_e32 v[146:147], v153
	v_cmp_gt_f32_e32 vcc, s72, v172
	v_frexp_exp_i32_f64_e32 v146, v[146:147]
	v_cmp_gt_f32_e64 s[14:15], s72, v174
	v_subbrev_co_u32_e32 v217, vcc, 0, v152, vcc
	s_nop 0
	v_subbrev_co_u32_e64 v216, s[14:15], 0, v146, s[14:15]
	v_sub_u32_e32 v147, 0, v217
	v_ldexp_f32 v146, v170, v147
	v_sub_u32_e32 v170, 0, v216
	v_ldexp_f32 v152, v171, v147
	v_ldexp_f32 v147, v153, v170
	v_ldexp_f32 v153, v173, v170
	v_pk_add_f32 v[170:171], v[146:147], 1.0 op_sel_hi:[1,0]
	v_pk_add_f32 v[192:193], v[146:147], -1.0 op_sel_hi:[1,0]
	v_pk_add_f32 v[172:173], v[170:171], -1.0 op_sel_hi:[1,0]
	v_pk_add_f32 v[194:195], v[192:193], 1.0 op_sel_hi:[1,0]
	v_pk_add_f32 v[172:173], v[146:147], v[172:173] neg_lo:[0,1] neg_hi:[0,1]
	v_pk_add_f32 v[146:147], v[146:147], v[194:195] neg_lo:[0,1] neg_hi:[0,1]
	v_pk_add_f32 v[172:173], v[152:153], v[172:173]
	v_pk_add_f32 v[146:147], v[152:153], v[146:147]
	v_pk_add_f32 v[174:175], v[170:171], v[172:173]
	v_pk_add_f32 v[152:153], v[192:193], v[146:147]
	v_rcp_f32_e32 v182, v174
	v_rcp_f32_e32 v183, v175
	v_pk_add_f32 v[170:171], v[174:175], v[170:171] neg_lo:[0,1] neg_hi:[0,1]
	v_pk_add_f32 v[192:193], v[152:153], v[192:193] neg_lo:[0,1] neg_hi:[0,1]
	v_pk_add_f32 v[170:171], v[172:173], v[170:171] neg_lo:[0,1] neg_hi:[0,1]
	v_pk_mul_f32 v[194:195], v[152:153], v[182:183]
	v_pk_add_f32 v[146:147], v[146:147], v[192:193] neg_lo:[0,1] neg_hi:[0,1]
	v_pk_mul_f32 v[172:173], v[174:175], v[194:195]
	v_mul_f32_e32 v126, 0xbfb8aa3b, v126
	v_pk_fma_f32 v[192:193], v[194:195], v[174:175], v[172:173] neg_lo:[0,0,1] neg_hi:[0,0,1]
	v_exp_f32_e32 v126, v126
	v_pk_fma_f32 v[192:193], v[194:195], v[170:171], v[192:193]
	v_add_f32_e32 v122, v122, v42
	v_pk_add_f32 v[196:197], v[172:173], v[192:193]
	v_add_f32_e32 v126, 1.0, v126
	v_pk_add_f32 v[198:199], v[152:153], v[196:197] neg_lo:[0,1] neg_hi:[0,1]
	v_pk_add_f32 v[172:173], v[196:197], v[172:173] neg_lo:[0,1] neg_hi:[0,1]
	v_pk_add_f32 v[152:153], v[152:153], v[198:199] neg_lo:[0,1] neg_hi:[0,1]
	v_rcp_f32_e32 v126, v126
	v_pk_add_f32 v[152:153], v[152:153], v[196:197] neg_lo:[0,1] neg_hi:[0,1]
	v_mul_f32_e32 v122, 0xbfb8aa3b, v122
	v_pk_add_f32 v[146:147], v[146:147], v[152:153]
	v_pk_add_f32 v[152:153], v[172:173], v[192:193] neg_lo:[0,1] neg_hi:[0,1]
	v_exp_f32_e32 v122, v122
	v_pk_add_f32 v[146:147], v[152:153], v[146:147]
	v_add_f32_e32 v123, v123, v43
	v_pk_add_f32 v[152:153], v[198:199], v[146:147]
	v_add_f32_e32 v122, 1.0, v122
	v_pk_mul_f32 v[172:173], v[182:183], v[152:153]
	v_pk_add_f32 v[198:199], v[198:199], v[152:153] neg_lo:[0,1] neg_hi:[0,1]
	v_pk_mul_f32 v[192:193], v[174:175], v[172:173]
	v_pk_add_f32 v[146:147], v[146:147], v[198:199]
	v_pk_fma_f32 v[174:175], v[172:173], v[174:175], v[192:193] neg_lo:[0,0,1] neg_hi:[0,0,1]
	v_pk_add_f32 v[214:215], v[194:195], v[172:173]
	v_pk_fma_f32 v[170:171], v[172:173], v[170:171], v[174:175]
	v_rcp_f32_e32 v122, v122
	v_pk_add_f32 v[174:175], v[192:193], v[170:171]
	v_mul_f32_e32 v123, 0xbfb8aa3b, v123
	v_pk_add_f32 v[200:201], v[152:153], v[174:175] neg_lo:[0,1] neg_hi:[0,1]
	v_pk_add_f32 v[196:197], v[174:175], v[192:193] neg_lo:[0,1] neg_hi:[0,1]
	v_pk_add_f32 v[212:213], v[152:153], v[200:201] neg_lo:[0,1] neg_hi:[0,1]
	v_mov_b32_e32 v152, v175
	v_mov_b32_e32 v192, v193
	v_mov_b32_e32 v193, v201
	v_pk_add_f32 v[212:213], v[212:213], v[174:175] neg_lo:[0,1] neg_hi:[0,1]
	v_pk_add_f32 v[152:153], v[152:153], v[192:193] neg_lo:[0,1] neg_hi:[0,1]
	v_mov_b32_e32 v174, v171
	v_pk_add_f32 v[152:153], v[152:153], v[174:175] neg_lo:[0,1] neg_hi:[0,1]
	v_pk_add_f32 v[196:197], v[196:197], v[170:171] neg_lo:[0,1] neg_hi:[0,1]
	v_mov_b32_e32 v213, v153
	v_pk_add_f32 v[146:147], v[146:147], v[212:213]
	v_mov_b32_e32 v197, v152
	v_pk_add_f32 v[146:147], v[196:197], v[146:147]
	v_pk_add_f32 v[152:153], v[214:215], v[194:195] neg_lo:[0,1] neg_hi:[0,1]
	v_pk_add_f32 v[146:147], v[200:201], v[146:147]
	v_pk_add_f32 v[152:153], v[172:173], v[152:153] neg_lo:[0,1] neg_hi:[0,1]
	v_pk_mul_f32 v[146:147], v[182:183], v[146:147]
	v_cvt_f32_i32_e32 v183, v216
	v_pk_add_f32 v[146:147], v[152:153], v[146:147]
	v_cvt_f32_i32_e32 v182, v217
	v_pk_add_f32 v[152:153], v[214:215], v[146:147]
	v_exp_f32_e32 v123, v123
	v_pk_mul_f32 v[172:173], v[152:153], v[152:153]
	v_pk_add_f32 v[170:171], v[152:153], v[214:215] neg_lo:[0,1] neg_hi:[0,1]
	v_pk_fma_f32 v[174:175], v[172:173], s[28:29], v[150:151] op_sel_hi:[1,0,0]
	v_pk_add_f32 v[146:147], v[146:147], v[170:171] neg_lo:[0,1] neg_hi:[0,1]
	v_ldexp_f32 v170, v152, 1
	v_pk_fma_f32 v[174:175], v[172:173], v[174:175], s[30:31] op_sel_hi:[1,1,0]
	v_ldexp_f32 v171, v153, 1
	v_pk_mul_f32 v[152:153], v[152:153], v[172:173]
	v_pk_mul_f32 v[194:195], v[182:183], s[34:35] op_sel_hi:[1,0]
	v_pk_mul_f32 v[152:153], v[152:153], v[174:175]
	v_ldexp_f32 v146, v146, 1
	v_pk_add_f32 v[172:173], v[170:171], v[152:153]
	v_pk_fma_f32 v[192:193], v[182:183], s[34:35], v[194:195] op_sel_hi:[1,0,1] neg_lo:[0,0,1] neg_hi:[0,0,1]
	v_pk_add_f32 v[170:171], v[172:173], v[170:171] neg_lo:[0,1] neg_hi:[0,1]
	v_ldexp_f32 v147, v147, 1
	v_pk_add_f32 v[152:153], v[152:153], v[170:171] neg_lo:[0,1] neg_hi:[0,1]
	v_pk_fma_f32 v[182:183], v[182:183], s[36:37], v[192:193] op_sel_hi:[1,0,1]
	v_pk_add_f32 v[146:147], v[146:147], v[152:153]
	v_pk_add_f32 v[192:193], v[194:195], v[182:183]
	v_pk_add_f32 v[200:201], v[172:173], v[146:147]
	v_pk_add_f32 v[194:195], v[192:193], v[194:195] neg_lo:[0,1] neg_hi:[0,1]
	v_pk_add_f32 v[152:153], v[200:201], v[172:173] neg_lo:[0,1] neg_hi:[0,1]
	v_pk_add_f32 v[182:183], v[182:183], v[194:195] neg_lo:[0,1] neg_hi:[0,1]
	v_pk_add_f32 v[146:147], v[146:147], v[152:153] neg_lo:[0,1] neg_hi:[0,1]
	v_add_f32_e32 v123, 1.0, v123
	v_pk_add_f32 v[194:195], v[182:183], v[146:147]
	v_rcp_f32_e32 v123, v123
	v_pk_add_f32 v[152:153], v[194:195], v[182:183] neg_lo:[0,1] neg_hi:[0,1]
	v_add_f32_e32 v124, v124, v44
	v_pk_add_f32 v[170:171], v[194:195], v[152:153] neg_lo:[0,1] neg_hi:[0,1]
	v_pk_add_f32 v[198:199], v[146:147], v[152:153] neg_lo:[0,1] neg_hi:[0,1]
	v_max_f32_e32 v146, v148, v148
	v_pk_add_f32 v[196:197], v[182:183], v[170:171] neg_lo:[0,1] neg_hi:[0,1]
	v_min_f32_e32 v182, 0, v146
	v_mul_f32_e64 v146, |v148|, s5
	v_exp_f32_e32 v239, v146
	v_mul_f32_e32 v124, 0xbfb8aa3b, v124
	v_exp_f32_e32 v124, v124
	v_add_f32_e32 v118, v118, v30
	v_add_f32_e32 v148, 1.0, v239
	v_add_f32_e32 v146, -1.0, v148
	v_sub_f32_e32 v147, v146, v148
	v_add_f32_e32 v147, 1.0, v147
	v_sub_f32_e32 v146, v239, v146
	v_add_f32_e32 v152, v146, v147
	v_cvt_f64_f32_e32 v[146:147], v148
	v_frexp_exp_i32_f64_e32 v170, v[146:147]
	v_max_f32_e32 v146, v149, v149
	v_min_f32_e32 v183, 0, v146
	v_mul_f32_e64 v146, |v149|, s5
	v_exp_f32_e32 v240, v146
	v_frexp_mant_f32_e32 v153, v148
	v_cmp_gt_f32_e32 vcc, s72, v153
	v_add_f32_e32 v124, 1.0, v124
	v_add_f32_e32 v149, 1.0, v240
	v_add_f32_e32 v146, -1.0, v149
	v_sub_f32_e32 v147, v146, v149
	v_add_f32_e32 v147, 1.0, v147
	v_sub_f32_e32 v146, v240, v146
	v_add_f32_e32 v171, v146, v147
	v_frexp_mant_f32_e32 v172, v149
	v_cvt_f64_f32_e32 v[146:147], v149
	v_frexp_exp_i32_f64_e32 v146, v[146:147]
	v_cmp_gt_f32_e64 s[14:15], s72, v172
	v_subbrev_co_u32_e32 v241, vcc, 0, v170, vcc
	s_nop 0
	v_subbrev_co_u32_e64 v234, s[14:15], 0, v146, s[14:15]
	v_sub_u32_e32 v147, 0, v241
	v_ldexp_f32 v146, v148, v147
	v_ldexp_f32 v148, v152, v147
	v_sub_u32_e32 v152, 0, v234
	v_ldexp_f32 v147, v149, v152
	v_ldexp_f32 v149, v171, v152
	v_pk_add_f32 v[152:153], v[146:147], 1.0 op_sel_hi:[1,0]
	v_pk_add_f32 v[212:213], v[146:147], -1.0 op_sel_hi:[1,0]
	v_pk_add_f32 v[170:171], v[152:153], -1.0 op_sel_hi:[1,0]
	v_pk_add_f32 v[214:215], v[212:213], 1.0 op_sel_hi:[1,0]
	v_pk_add_f32 v[170:171], v[146:147], v[170:171] neg_lo:[0,1] neg_hi:[0,1]
	v_pk_add_f32 v[146:147], v[146:147], v[214:215] neg_lo:[0,1] neg_hi:[0,1]
	v_pk_add_f32 v[170:171], v[148:149], v[170:171]
	v_pk_add_f32 v[146:147], v[148:149], v[146:147]
	v_pk_add_f32 v[172:173], v[152:153], v[170:171]
	v_pk_add_f32 v[148:149], v[212:213], v[146:147]
	v_rcp_f32_e32 v174, v172
	v_rcp_f32_e32 v175, v173
	v_pk_add_f32 v[152:153], v[172:173], v[152:153] neg_lo:[0,1] neg_hi:[0,1]
	v_pk_add_f32 v[212:213], v[148:149], v[212:213] neg_lo:[0,1] neg_hi:[0,1]
	v_pk_add_f32 v[152:153], v[170:171], v[152:153] neg_lo:[0,1] neg_hi:[0,1]
	v_pk_mul_f32 v[214:215], v[148:149], v[174:175]
	v_pk_add_f32 v[146:147], v[146:147], v[212:213] neg_lo:[0,1] neg_hi:[0,1]
	v_pk_mul_f32 v[170:171], v[172:173], v[214:215]
	v_cmp_lt_f32_e64 s[14:15], |v233|, s77
	v_pk_fma_f32 v[212:213], v[214:215], v[172:173], v[170:171] neg_lo:[0,0,1] neg_hi:[0,0,1]
	v_rcp_f32_e32 v124, v124
	v_pk_fma_f32 v[212:213], v[214:215], v[152:153], v[212:213]
	v_add_f32_e32 v125, v125, v45
	v_pk_add_f32 v[216:217], v[170:171], v[212:213]
	v_mul_f32_e32 v118, 0xbfb8aa3b, v118
	v_pk_add_f32 v[218:219], v[148:149], v[216:217] neg_lo:[0,1] neg_hi:[0,1]
	v_pk_add_f32 v[170:171], v[216:217], v[170:171] neg_lo:[0,1] neg_hi:[0,1]
	v_pk_add_f32 v[148:149], v[148:149], v[218:219] neg_lo:[0,1] neg_hi:[0,1]
	v_mul_f32_e32 v125, 0xbfb8aa3b, v125
	v_pk_add_f32 v[148:149], v[148:149], v[216:217] neg_lo:[0,1] neg_hi:[0,1]
	v_exp_f32_e32 v118, v118
	v_pk_add_f32 v[146:147], v[146:147], v[148:149]
	v_pk_add_f32 v[148:149], v[170:171], v[212:213] neg_lo:[0,1] neg_hi:[0,1]
	v_exp_f32_e32 v125, v125
	v_pk_add_f32 v[146:147], v[148:149], v[146:147]
	v_add_f32_e32 v118, 1.0, v118
	v_pk_add_f32 v[148:149], v[218:219], v[146:147]
	v_add_f32_e32 v125, 1.0, v125
	v_pk_mul_f32 v[170:171], v[174:175], v[148:149]
	v_pk_add_f32 v[218:219], v[218:219], v[148:149] neg_lo:[0,1] neg_hi:[0,1]
	v_pk_mul_f32 v[212:213], v[172:173], v[170:171]
	v_pk_add_f32 v[146:147], v[146:147], v[218:219]
	v_pk_fma_f32 v[172:173], v[170:171], v[172:173], v[212:213] neg_lo:[0,0,1] neg_hi:[0,0,1]
	v_pk_add_f32 v[244:245], v[214:215], v[170:171]
	v_pk_fma_f32 v[152:153], v[170:171], v[152:153], v[172:173]
	v_rcp_f32_e32 v118, v118
	v_pk_add_f32 v[172:173], v[212:213], v[152:153]
	v_rcp_f32_e32 v125, v125
	v_pk_add_f32 v[220:221], v[148:149], v[172:173] neg_lo:[0,1] neg_hi:[0,1]
	v_pk_add_f32 v[216:217], v[172:173], v[212:213] neg_lo:[0,1] neg_hi:[0,1]
	v_pk_add_f32 v[242:243], v[148:149], v[220:221] neg_lo:[0,1] neg_hi:[0,1]
	v_mov_b32_e32 v148, v173
	v_mov_b32_e32 v212, v213
	v_mov_b32_e32 v213, v221
	v_pk_add_f32 v[242:243], v[242:243], v[172:173] neg_lo:[0,1] neg_hi:[0,1]
	v_pk_add_f32 v[148:149], v[148:149], v[212:213] neg_lo:[0,1] neg_hi:[0,1]
	v_mov_b32_e32 v172, v153
	v_pk_add_f32 v[148:149], v[148:149], v[172:173] neg_lo:[0,1] neg_hi:[0,1]
	v_pk_add_f32 v[216:217], v[216:217], v[152:153] neg_lo:[0,1] neg_hi:[0,1]
	v_mov_b32_e32 v243, v149
	v_pk_add_f32 v[146:147], v[146:147], v[242:243]
	v_mov_b32_e32 v217, v148
	v_pk_add_f32 v[146:147], v[216:217], v[146:147]
	v_pk_add_f32 v[148:149], v[244:245], v[214:215] neg_lo:[0,1] neg_hi:[0,1]
	v_pk_add_f32 v[146:147], v[220:221], v[146:147]
	v_pk_add_f32 v[148:149], v[170:171], v[148:149] neg_lo:[0,1] neg_hi:[0,1]
	v_pk_mul_f32 v[146:147], v[174:175], v[146:147]
	v_cvt_f32_i32_e32 v173, v234
	v_pk_add_f32 v[146:147], v[148:149], v[146:147]
	v_cvt_f32_i32_e32 v172, v241
	v_pk_add_f32 v[148:149], v[244:245], v[146:147]
	v_add_u32_e32 v234, s0, v167
	v_pk_mul_f32 v[170:171], v[148:149], v[148:149]
	v_pk_add_f32 v[152:153], v[148:149], v[244:245] neg_lo:[0,1] neg_hi:[0,1]
	v_pk_fma_f32 v[150:151], v[170:171], s[28:29], v[150:151] op_sel_hi:[1,0,0]
	v_pk_add_f32 v[146:147], v[146:147], v[152:153] neg_lo:[0,1] neg_hi:[0,1]
	v_ldexp_f32 v152, v148, 1
	v_pk_fma_f32 v[150:151], v[170:171], v[150:151], s[30:31] op_sel_hi:[1,1,0]
	v_ldexp_f32 v153, v149, 1
	v_pk_mul_f32 v[148:149], v[148:149], v[170:171]
	v_pk_mul_f32 v[174:175], v[172:173], s[34:35] op_sel_hi:[1,0]
	v_pk_mul_f32 v[148:149], v[148:149], v[150:151]
	v_ldexp_f32 v146, v146, 1
	v_pk_add_f32 v[150:151], v[152:153], v[148:149]
	v_pk_fma_f32 v[212:213], v[172:173], s[34:35], v[174:175] op_sel_hi:[1,0,1] neg_lo:[0,0,1] neg_hi:[0,0,1]
	v_pk_add_f32 v[152:153], v[150:151], v[152:153] neg_lo:[0,1] neg_hi:[0,1]
	v_ldexp_f32 v147, v147, 1
	v_pk_add_f32 v[148:149], v[148:149], v[152:153] neg_lo:[0,1] neg_hi:[0,1]
	v_pk_fma_f32 v[172:173], v[172:173], s[36:37], v[212:213] op_sel_hi:[1,0,1]
	v_pk_add_f32 v[146:147], v[146:147], v[148:149]
	v_pk_add_f32 v[212:213], v[174:175], v[172:173]
	v_pk_add_f32 v[220:221], v[150:151], v[146:147]
	v_pk_add_f32 v[174:175], v[212:213], v[174:175] neg_lo:[0,1] neg_hi:[0,1]
	v_pk_add_f32 v[148:149], v[220:221], v[150:151] neg_lo:[0,1] neg_hi:[0,1]
	v_pk_add_f32 v[172:173], v[172:173], v[174:175] neg_lo:[0,1] neg_hi:[0,1]
	v_pk_add_f32 v[146:147], v[146:147], v[148:149] neg_lo:[0,1] neg_hi:[0,1]
	v_ashrrev_i32_e32 v167, 31, v166
	v_pk_add_f32 v[214:215], v[172:173], v[146:147]
	v_mov_b32_e32 v242, v190
	v_pk_add_f32 v[148:149], v[214:215], v[172:173] neg_lo:[0,1] neg_hi:[0,1]
	v_mov_b32_e32 v243, v176
	v_pk_add_f32 v[218:219], v[146:147], v[148:149] neg_lo:[0,1] neg_hi:[0,1]
	v_mov_b32_e32 v146, v234
	v_pk_add_f32 v[150:151], v[214:215], v[148:149] neg_lo:[0,1] neg_hi:[0,1]
	v_ashrrev_i32_e32 v147, 31, v146
	v_lshlrev_b64 v[146:147], 10, v[146:147]
	v_lshl_add_u64 v[146:147], v[146:147], 0, v[166:167]
	v_lshlrev_b64 v[148:149], 1, v[146:147]
	v_lshl_add_u64 v[174:175], s[24:25], 0, v[148:149]
	v_pk_add_f32 v[216:217], v[172:173], v[150:151] neg_lo:[0,1] neg_hi:[0,1]
	flat_load_dwordx4 v[150:153], v[174:175]
	v_lshl_add_u64 v[170:171], s[50:51], 0, v[146:147]
	v_add_co_u32_e32 v146, vcc, s84, v174
	v_lshl_add_u64 v[172:173], s[48:49], 0, v[148:149]
	s_nop 0
	v_addc_co_u32_e32 v147, vcc, 0, v175, vcc
	flat_load_dwordx4 v[146:149], v[146:147]
	v_cmp_neq_f32_e32 vcc, s73, v232
	v_add_f32_e32 v114, v114, v26
	v_add_f32_e32 v119, v119, v31
	v_mul_f32_e32 v114, 0xbfb8aa3b, v114
	v_mul_f32_e32 v119, 0xbfb8aa3b, v119
	v_exp_f32_e32 v114, v114
	v_exp_f32_e32 v119, v119
	v_add_f32_e32 v120, v120, v32
	v_add_f32_e32 v115, v115, v27
	v_add_f32_e32 v114, 1.0, v114
	v_add_f32_e32 v119, 1.0, v119
	v_rcp_f32_e32 v114, v114
	v_rcp_f32_e32 v119, v119
	v_mul_f32_e32 v120, 0xbfb8aa3b, v120
	v_mul_f32_e32 v115, 0xbfb8aa3b, v115
	v_exp_f32_e32 v120, v120
	v_exp_f32_e32 v115, v115
	v_add_f32_e32 v121, v121, v33
	v_add_f32_e32 v116, v116, v28
	v_add_f32_e32 v120, 1.0, v120
	v_add_f32_e32 v115, 1.0, v115
	v_rcp_f32_e32 v120, v120
	v_rcp_f32_e32 v115, v115
	v_mul_f32_e32 v121, 0xbfb8aa3b, v121
	v_mul_f32_e32 v116, 0xbfb8aa3b, v116
	v_exp_f32_e32 v121, v121
	v_exp_f32_e32 v116, v116
	v_add_f32_e32 v117, v117, v29
	v_mul_f32_e32 v117, 0xbfb8aa3b, v117
	v_add_f32_e32 v121, 1.0, v121
	v_add_f32_e32 v116, 1.0, v116
	v_rcp_f32_e32 v121, v121
	v_rcp_f32_e32 v116, v116
	v_exp_f32_e32 v117, v117
	s_waitcnt vmcnt(0) lgkmcnt(0)
	v_lshlrev_b32_e32 v241, 16, v150
	v_and_b32_e32 v246, 0xffff0000, v150
	v_rcp_f32_e32 v150, v138
	v_add_f32_e32 v138, v140, v44
	v_mul_f32_e32 v138, 0xbfb8aa3b, v138
	v_exp_f32_e32 v138, v138
	v_lshlrev_b32_e32 v247, 16, v151
	v_and_b32_e32 v248, 0xffff0000, v151
	v_add_f32_e32 v117, 1.0, v117
	v_add_f32_e32 v138, 1.0, v138
	v_rcp_f32_e32 v251, v138
	v_add_f32_e32 v138, v145, v49
	v_mul_f32_e32 v138, 0xbfb8aa3b, v138
	v_exp_f32_e32 v138, v138
	v_rcp_f32_e32 v117, v117
	v_add_f32_e32 v138, 1.0, v138
	v_rcp_f32_e32 v151, v138
	v_add_f32_e32 v138, v141, v45
	v_mul_f32_e32 v138, 0xbfb8aa3b, v138
	v_exp_f32_e32 v138, v138
	s_nop 0
	v_add_f32_e32 v138, 1.0, v138
	v_rcp_f32_e32 v252, v138
	v_pk_add_f32 v[138:139], v[176:177], v[190:191]
	s_nop 0
	v_pk_add_f32 v[140:141], v[138:139], v[176:177] neg_lo:[0,1] neg_hi:[0,1]
	v_mov_b32_e32 v176, v191
	v_pk_add_f32 v[144:145], v[138:139], v[140:141] neg_lo:[0,1] neg_hi:[0,1]
	v_mov_b32_e32 v244, v140
	v_mov_b32_e32 v245, v144
	v_mov_b32_e32 v144, v141
	v_pk_add_f32 v[242:243], v[242:243], v[244:245] neg_lo:[0,1] neg_hi:[0,1]
	v_pk_add_f32 v[140:141], v[176:177], v[144:145] neg_lo:[0,1] neg_hi:[0,1]
	v_pk_add_f32 v[242:243], v[242:243], v[242:243] op_sel:[0,1] op_sel_hi:[1,0]
	v_pk_add_f32 v[140:141], v[140:141], v[140:141] op_sel_hi:[0,1]
	v_mov_b32_e32 v243, v185
	v_mov_b32_e32 v185, v141
	v_pk_add_f32 v[140:141], v[242:243], v[184:185]
	v_pk_add_f32 v[176:177], v[188:189], v[186:187]
	v_pk_add_f32 v[144:145], v[138:139], v[140:141]
	s_nop 0
	v_pk_add_f32 v[138:139], v[144:145], v[138:139] neg_lo:[0,1] neg_hi:[0,1]
	s_nop 0
	v_pk_add_f32 v[138:139], v[140:141], v[138:139] neg_lo:[0,1] neg_hi:[0,1]
	s_nop 0
	v_pk_add_f32 v[138:139], v[176:177], v[138:139]
	v_mov_b32_e32 v176, v210
	v_pk_add_f32 v[138:139], v[144:145], v[138:139]
	v_mov_b32_e32 v177, v202
	v_cndmask_b32_e32 v138, v228, v138, vcc
	v_cmp_neq_f32_e32 vcc, s73, v233
	s_nop 1
	v_cndmask_b32_e32 v139, v228, v139, vcc
	v_cmp_ngt_f32_e32 vcc, -1.0, v233
	s_nop 1
	v_cndmask_b32_e32 v139, v229, v139, vcc
	v_cmp_ngt_f32_e32 vcc, -1.0, v232
	s_nop 1
	v_cndmask_b32_e32 v138, v229, v138, vcc
	v_cmp_neq_f32_e32 vcc, -1.0, v232
	s_nop 1
	v_cndmask_b32_e32 v138, v230, v138, vcc
	v_cmp_neq_f32_e32 vcc, -1.0, v233
	s_nop 1
	v_cndmask_b32_e32 v139, v230, v139, vcc
	v_cmp_lt_f32_e64 vcc, |v232|, s77
	v_cndmask_b32_e64 v139, v139, v233, s[14:15]
	v_cmp_lt_f32_e64 s[14:15], |v238|, s77
	v_cndmask_b32_e32 v138, v138, v232, vcc
	v_pk_add_f32 v[138:139], v[168:169], v[138:139] neg_lo:[0,1] neg_hi:[0,1]
	v_cmp_neq_f32_e32 vcc, s73, v236
	v_pk_mul_f32 v[144:145], v[138:139], s[38:39] op_sel_hi:[1,0]
	s_nop 0
	v_pk_mul_f32 v[138:139], v[142:143], v[144:145]
	v_mul_f32_e32 v126, v126, v144
	v_add_f32_e32 v140, v138, v138
	v_mul_f32_e32 v140, 0x3fb8aa3b, v140
	v_exp_f32_e32 v140, v140
	v_cvt_pk_bf16_f32 v138, v138, v139
	v_sub_f32_e32 v140, 1.0, v140
	v_max_f32_e32 v140, 0, v140
	v_sqrt_f32_e32 v140, v140
	s_nop 0
	v_mul_f32_e32 v140, v249, v140
	v_mul_f32_e32 v186, v140, v241
	v_add_f32_e32 v140, v139, v139
	v_mul_f32_e32 v140, 0x3fb8aa3b, v140
	v_exp_f32_e32 v140, v140
	s_nop 0
	v_sub_f32_e32 v140, 1.0, v140
	v_max_f32_e32 v140, 0, v140
	v_sqrt_f32_e32 v140, v140
	s_nop 0
	v_mul_f32_e32 v140, v250, v140
	v_mul_f32_e32 v187, v140, v246
	v_pk_add_f32 v[140:141], v[202:203], v[210:211]
	s_nop 0
	v_pk_add_f32 v[142:143], v[140:141], v[202:203] neg_lo:[0,1] neg_hi:[0,1]
	v_mov_b32_e32 v202, v211
	v_pk_add_f32 v[168:169], v[140:141], v[142:143] neg_lo:[0,1] neg_hi:[0,1]
	v_mov_b32_e32 v184, v142
	v_mov_b32_e32 v185, v168
	v_mov_b32_e32 v168, v143
	v_pk_add_f32 v[176:177], v[176:177], v[184:185] neg_lo:[0,1] neg_hi:[0,1]
	v_pk_add_f32 v[142:143], v[202:203], v[168:169] neg_lo:[0,1] neg_hi:[0,1]
	v_pk_add_f32 v[176:177], v[176:177], v[176:177] op_sel:[0,1] op_sel_hi:[1,0]
	v_pk_add_f32 v[142:143], v[142:143], v[142:143] op_sel_hi:[0,1]
	v_mov_b32_e32 v177, v205
	v_mov_b32_e32 v205, v143
	v_pk_add_f32 v[142:143], v[176:177], v[204:205]
	v_pk_add_f32 v[176:177], v[208:209], v[206:207]
	v_pk_add_f32 v[168:169], v[140:141], v[142:143]
	s_nop 0
	v_pk_add_f32 v[140:141], v[168:169], v[140:141] neg_lo:[0,1] neg_hi:[0,1]
	s_nop 0
	v_pk_add_f32 v[140:141], v[142:143], v[140:141] neg_lo:[0,1] neg_hi:[0,1]
	s_nop 0
	v_pk_add_f32 v[140:141], v[176:177], v[140:141]
	v_rcp_f32_e32 v177, v130
	v_add_f32_e32 v130, v135, v31
	v_pk_add_f32 v[140:141], v[168:169], v[140:141]
	v_mul_f32_e32 v130, 0xbfb8aa3b, v130
	v_cndmask_b32_e32 v139, v228, v140, vcc
	v_cmp_neq_f32_e32 vcc, s73, v238
	v_exp_f32_e32 v130, v130
	v_and_b32_e32 v176, 0xffff0000, v152
	v_cndmask_b32_e32 v140, v228, v141, vcc
	v_cmp_ngt_f32_e32 vcc, -1.0, v238
	v_add_f32_e32 v130, 1.0, v130
	v_rcp_f32_e32 v135, v130
	v_cndmask_b32_e32 v140, v229, v140, vcc
	v_cmp_ngt_f32_e32 vcc, -1.0, v236
	v_add_f32_e32 v130, v131, v27
	v_mul_f32_e32 v130, 0xbfb8aa3b, v130
	v_cndmask_b32_e32 v139, v229, v139, vcc
	v_cmp_neq_f32_e32 vcc, -1.0, v236
	v_exp_f32_e32 v130, v130
	s_nop 0
	v_cndmask_b32_e32 v139, v230, v139, vcc
	v_cmp_neq_f32_e32 vcc, -1.0, v238
	v_add_f32_e32 v130, 1.0, v130
	v_rcp_f32_e32 v184, v130
	v_cndmask_b32_e32 v140, v230, v140, vcc
	v_cmp_lt_f32_e64 vcc, |v236|, s77
	v_cndmask_b32_e64 v141, v140, v238, s[14:15]
	v_add_f32_e32 v130, v136, v32
	v_cndmask_b32_e32 v140, v139, v236, vcc
	v_pk_add_f32 v[140:141], v[180:181], v[140:141] neg_lo:[0,1] neg_hi:[0,1]
	v_mul_f32_e32 v130, 0xbfb8aa3b, v130
	v_pk_mul_f32 v[142:143], v[140:141], s[38:39] op_sel_hi:[1,0]
	v_exp_f32_e32 v130, v130
	v_pk_mul_f32 v[140:141], v[150:151], v[142:143]
	v_lshlrev_b32_e32 v180, 16, v153
	v_add_f32_e32 v139, v140, v140
	v_mul_f32_e32 v139, 0x3fb8aa3b, v139
	v_exp_f32_e32 v139, v139
	v_add_f32_e32 v130, 1.0, v130
	v_rcp_f32_e32 v136, v130
	v_add_f32_e32 v130, v132, v28
	v_sub_f32_e32 v139, 1.0, v139
	v_max_f32_e32 v139, 0, v139
	v_sqrt_f32_e32 v139, v139
	v_mul_f32_e32 v130, 0xbfb8aa3b, v130
	v_exp_f32_e32 v130, v130
	v_and_b32_e32 v181, 0xffff0000, v153
	v_mul_f32_e32 v139, v251, v139
	v_mul_f32_e32 v150, v139, v247
	v_add_f32_e32 v139, v141, v141
	v_mul_f32_e32 v139, 0x3fb8aa3b, v139
	v_exp_f32_e32 v139, v139
	v_add_f32_e32 v130, 1.0, v130
	v_rcp_f32_e32 v185, v130
	v_add_f32_e32 v130, v137, v33
	v_mul_f32_e32 v130, 0xbfb8aa3b, v130
	v_exp_f32_e32 v130, v130
	v_sub_f32_e32 v139, 1.0, v139
	v_max_f32_e32 v139, 0, v139
	v_sqrt_f32_e32 v139, v139
	v_add_f32_e32 v130, 1.0, v130
	v_rcp_f32_e32 v137, v130
	v_add_f32_e32 v130, v133, v29
	v_mul_f32_e32 v130, 0xbfb8aa3b, v130
	v_mul_f32_e32 v139, v252, v139
	v_exp_f32_e32 v130, v130
	v_mul_f32_e32 v151, v139, v248
	v_cvt_pk_bf16_f32 v139, v140, v141
	v_mul_f32_e32 v140, 0x42000000, v186
	v_mul_f32_e32 v141, 0x42000000, v187
	v_mul_f32_e32 v168, 0x42000000, v150
	v_med3_f32 v140, v140, s29, v231
	v_med3_f32 v141, v141, s29, v231
	v_mov_b32_e32 v150, 0
	v_cvt_pk_fp8_f32 v150, v140, v141
	v_add_f32_e32 v130, 1.0, v130
	v_mul_f32_e32 v151, 0x42000000, v151
	v_rcp_f32_e32 v186, v130
	v_pk_add_f32 v[130:131], v[192:193], v[200:201]
	v_med3_f32 v140, v168, s29, v231
	v_med3_f32 v141, v151, s29, v231
	v_pk_add_f32 v[132:133], v[130:131], v[192:193] neg_lo:[0,1] neg_hi:[0,1]
	v_cvt_pk_fp8_f32 v150, v140, v141 op_sel:[0,0,1]
	v_pk_add_f32 v[140:141], v[130:131], v[132:133] neg_lo:[0,1] neg_hi:[0,1]
	v_lshlrev_b32_e32 v151, 16, v152
	v_mov_b32_e32 v152, v200
	v_mov_b32_e32 v153, v192
	v_mov_b32_e32 v168, v132
	v_mov_b32_e32 v169, v140
	v_mov_b32_e32 v192, v201
	v_mov_b32_e32 v140, v133
	v_pk_add_f32 v[152:153], v[152:153], v[168:169] neg_lo:[0,1] neg_hi:[0,1]
	v_pk_add_f32 v[132:133], v[192:193], v[140:141] neg_lo:[0,1] neg_hi:[0,1]
	v_pk_add_f32 v[152:153], v[152:153], v[152:153] op_sel:[0,1] op_sel_hi:[1,0]
	v_pk_add_f32 v[132:133], v[132:133], v[132:133] op_sel_hi:[0,1]
	v_mov_b32_e32 v153, v195
	v_mov_b32_e32 v195, v133
	v_pk_add_f32 v[132:133], v[152:153], v[194:195]
	v_pk_add_f32 v[152:153], v[198:199], v[196:197]
	v_pk_add_f32 v[140:141], v[130:131], v[132:133]
	v_cmp_neq_f32_e32 vcc, s73, v235
	v_pk_add_f32 v[130:131], v[140:141], v[130:131] neg_lo:[0,1] neg_hi:[0,1]
	v_cmp_lt_f32_e64 s[14:15], |v237|, s77
	v_pk_add_f32 v[130:131], v[132:133], v[130:131] neg_lo:[0,1] neg_hi:[0,1]
	v_mov_b32_e32 v168, v220
	v_pk_add_f32 v[130:131], v[152:153], v[130:131]
	v_mov_b32_e32 v169, v212
	v_pk_add_f32 v[130:131], v[140:141], v[130:131]
	s_nop 0
	v_cndmask_b32_e32 v130, v228, v130, vcc
	v_cmp_neq_f32_e32 vcc, s73, v237
	s_nop 1
	v_cndmask_b32_e32 v131, v228, v131, vcc
	v_cmp_ngt_f32_e32 vcc, -1.0, v237
	s_nop 1
	v_cndmask_b32_e32 v131, v229, v131, vcc
	v_cmp_ngt_f32_e32 vcc, -1.0, v235
	s_nop 1
	v_cndmask_b32_e32 v130, v229, v130, vcc
	v_cmp_neq_f32_e32 vcc, -1.0, v235
	s_nop 1
	v_cndmask_b32_e32 v130, v230, v130, vcc
	v_cmp_neq_f32_e32 vcc, -1.0, v237
	s_nop 1
	v_cndmask_b32_e32 v131, v230, v131, vcc
	v_cmp_lt_f32_e64 vcc, |v235|, s77
	v_cndmask_b32_e64 v131, v131, v237, s[14:15]
	v_cmp_lt_f32_e64 s[14:15], |v240|, s77
	v_cndmask_b32_e32 v130, v130, v235, vcc
	v_pk_add_f32 v[130:131], v[178:179], v[130:131] neg_lo:[0,1] neg_hi:[0,1]
	v_cmp_neq_f32_e32 vcc, s73, v239
	v_pk_mul_f32 v[130:131], v[130:131], s[38:39] op_sel_hi:[1,0]
	s_nop 0
	v_pk_mul_f32 v[132:133], v[134:135], v[130:131]
	v_mul_f32_e32 v118, v118, v130
	v_add_f32_e32 v134, v132, v132
	v_mul_f32_e32 v134, 0x3fb8aa3b, v134
	v_exp_f32_e32 v134, v134
	v_cvt_pk_bf16_f32 v140, v132, v133
	v_mul_f32_e32 v119, v119, v131
	v_sub_f32_e32 v134, 1.0, v134
	v_max_f32_e32 v134, 0, v134
	v_sqrt_f32_e32 v134, v134
	s_nop 0
	v_mul_f32_e32 v134, v177, v134
	v_mul_f32_e32 v151, v134, v151
	v_add_f32_e32 v134, v133, v133
	v_mul_f32_e32 v134, 0x3fb8aa3b, v134
	v_exp_f32_e32 v134, v134
	v_pk_add_f32 v[132:133], v[212:213], v[220:221]
	v_sub_f32_e32 v134, 1.0, v134
	v_max_f32_e32 v134, 0, v134
	v_sqrt_f32_e32 v134, v134
	s_nop 0
	v_mul_f32_e32 v134, v184, v134
	v_mul_f32_e32 v178, v134, v176
	v_pk_add_f32 v[134:135], v[132:133], v[212:213] neg_lo:[0,1] neg_hi:[0,1]
	v_mov_b32_e32 v212, v221
	v_pk_add_f32 v[152:153], v[132:133], v[134:135] neg_lo:[0,1] neg_hi:[0,1]
	v_mov_b32_e32 v176, v134
	v_mov_b32_e32 v177, v152
	v_mov_b32_e32 v152, v135
	v_pk_add_f32 v[168:169], v[168:169], v[176:177] neg_lo:[0,1] neg_hi:[0,1]
	v_pk_add_f32 v[134:135], v[212:213], v[152:153] neg_lo:[0,1] neg_hi:[0,1]
	v_pk_add_f32 v[168:169], v[168:169], v[168:169] op_sel:[0,1] op_sel_hi:[1,0]
	v_pk_add_f32 v[134:135], v[134:135], v[134:135] op_sel_hi:[0,1]
	v_mov_b32_e32 v169, v215
	v_mov_b32_e32 v215, v135
	v_pk_add_f32 v[134:135], v[168:169], v[214:215]
	v_pk_add_f32 v[168:169], v[218:219], v[216:217]
	v_pk_add_f32 v[152:153], v[132:133], v[134:135]
	s_nop 0
	v_pk_add_f32 v[132:133], v[152:153], v[132:133] neg_lo:[0,1] neg_hi:[0,1]
	s_nop 0
	v_pk_add_f32 v[132:133], v[134:135], v[132:133] neg_lo:[0,1] neg_hi:[0,1]
	s_nop 0
	v_pk_add_f32 v[132:133], v[168:169], v[132:133]
	s_nop 0
	v_pk_add_f32 v[132:133], v[152:153], v[132:133]
	s_nop 0
	v_cndmask_b32_e32 v132, v228, v132, vcc
	v_cmp_neq_f32_e32 vcc, s73, v240
	s_nop 1
	v_cndmask_b32_e32 v133, v228, v133, vcc
	v_cmp_ngt_f32_e32 vcc, -1.0, v240
	s_nop 1
	v_cndmask_b32_e32 v133, v229, v133, vcc
	v_cmp_ngt_f32_e32 vcc, -1.0, v239
	s_nop 1
	v_cndmask_b32_e32 v132, v229, v132, vcc
	v_cmp_neq_f32_e32 vcc, -1.0, v239
	s_nop 1
	v_cndmask_b32_e32 v132, v230, v132, vcc
	v_cmp_neq_f32_e32 vcc, -1.0, v240
	s_nop 1
	v_cndmask_b32_e32 v133, v230, v133, vcc
	v_cmp_lt_f32_e64 vcc, |v239|, s77
	v_cndmask_b32_e64 v133, v133, v240, s[14:15]
	s_nop 0
	v_cndmask_b32_e32 v132, v132, v239, vcc
	v_pk_add_f32 v[132:133], v[182:183], v[132:133] neg_lo:[0,1] neg_hi:[0,1]
	s_nop 0
	v_pk_mul_f32 v[132:133], v[132:133], s[38:39] op_sel_hi:[1,0]
	s_nop 0
	v_pk_mul_f32 v[134:135], v[136:137], v[132:133]
	v_mul_f32_e32 v120, v120, v132
	v_add_f32_e32 v136, v134, v134
	v_add_f32_e32 v137, v135, v135
	v_mul_f32_e32 v136, 0x3fb8aa3b, v136
	v_mul_f32_e32 v137, 0x3fb8aa3b, v137
	v_exp_f32_e32 v136, v136
	v_exp_f32_e32 v137, v137
	v_cvt_pk_bf16_f32 v141, v134, v135
	v_mul_f32_e32 v134, 0x42000000, v151
	v_sub_f32_e32 v136, 1.0, v136
	v_sub_f32_e32 v137, 1.0, v137
	v_max_f32_e32 v136, 0, v136
	v_max_f32_e32 v137, 0, v137
	v_sqrt_f32_e32 v136, v136
	v_sqrt_f32_e32 v137, v137
	v_mul_f32_e32 v135, 0x42000000, v178
	v_med3_f32 v134, v134, s29, v231
	v_med3_f32 v135, v135, s29, v231
	v_mov_b32_e32 v151, 0
	v_mul_f32_e32 v136, v185, v136
	v_mul_f32_e32 v137, v186, v137
	v_cvt_pk_fp8_f32 v151, v134, v135
	v_mul_f32_e32 v136, v136, v180
	v_mul_f32_e32 v137, v137, v181
	v_mul_f32_e32 v136, 0x42000000, v136
	v_mul_f32_e32 v137, 0x42000000, v137
	v_med3_f32 v134, v136, s29, v231
	v_med3_f32 v135, v137, s29, v231
	v_cvt_pk_fp8_f32 v151, v134, v135 op_sel:[0,0,1]
	flat_store_dwordx4 v[172:173], v[138:141]
	flat_store_dwordx2 v[170:171], v[150:151]
	s_nop 0
	v_add_f32_e32 v138, v126, v126
	v_mul_f32_e32 v138, 0x3fb8aa3b, v138
	v_exp_f32_e32 v138, v138
	v_lshlrev_b32_e32 v134, 16, v146
	v_and_b32_e32 v135, 0xffff0000, v146
	v_lshlrev_b32_e32 v136, 16, v147
	v_sub_f32_e32 v138, 1.0, v138
	v_max_f32_e32 v138, 0, v138
	v_sqrt_f32_e32 v138, v138
	v_and_b32_e32 v137, 0xffff0000, v147
	v_mul_f32_e32 v121, v121, v133
	v_mul_f32_e32 v122, v122, v138
	v_mul_f32_e32 v134, v122, v134
	v_add_f32_e32 v122, v127, v47
	v_mul_f32_e32 v122, 0xbfb8aa3b, v122
	v_exp_f32_e32 v122, v122
	s_nop 0
	v_add_f32_e32 v122, 1.0, v122
	v_rcp_f32_e32 v122, v122
	s_nop 0
	v_mul_f32_e32 v122, v122, v145
	v_add_f32_e32 v127, v122, v122
	v_mul_f32_e32 v127, 0x3fb8aa3b, v127
	v_exp_f32_e32 v127, v127
	v_cvt_pk_bf16_f32 v122, v126, v122
	v_mul_f32_e32 v126, 0x42000000, v134
	v_sub_f32_e32 v127, 1.0, v127
	v_max_f32_e32 v127, 0, v127
	v_sqrt_f32_e32 v127, v127
	s_nop 0
	v_mul_f32_e32 v123, v123, v127
	v_mul_f32_e32 v127, v123, v135
	v_add_f32_e32 v123, v128, v48
	v_mul_f32_e32 v123, 0xbfb8aa3b, v123
	v_exp_f32_e32 v123, v123
	v_mul_f32_e32 v127, 0x42000000, v127
	v_med3_f32 v127, v127, s29, v231
	v_add_f32_e32 v123, 1.0, v123
	v_rcp_f32_e32 v123, v123
	s_nop 0
	v_mul_f32_e32 v123, v123, v142
	v_add_f32_e32 v128, v123, v123
	v_mul_f32_e32 v128, 0x3fb8aa3b, v128
	v_exp_f32_e32 v128, v128
	s_nop 0
	v_sub_f32_e32 v128, 1.0, v128
	v_max_f32_e32 v128, 0, v128
	v_sqrt_f32_e32 v128, v128
	s_nop 0
	v_mul_f32_e32 v124, v124, v128
	v_add_f32_e32 v128, v129, v49
	v_mul_f32_e32 v128, 0xbfb8aa3b, v128
	v_exp_f32_e32 v128, v128
	v_mul_f32_e32 v124, v124, v136
	v_mul_f32_e32 v124, 0x42000000, v124
	v_med3_f32 v124, v124, s29, v231
	v_add_f32_e32 v128, 1.0, v128
	v_rcp_f32_e32 v128, v128
	s_nop 0
	v_mul_f32_e32 v128, v128, v143
	v_add_f32_e32 v129, v128, v128
	v_mul_f32_e32 v129, 0x3fb8aa3b, v129
	v_exp_f32_e32 v129, v129
	v_cvt_pk_bf16_f32 v123, v123, v128
	v_med3_f32 v128, v126, s29, v231
	v_mov_b32_e32 v126, 0
	v_sub_f32_e32 v129, 1.0, v129
	v_max_f32_e32 v129, 0, v129
	v_sqrt_f32_e32 v129, v129
	v_cvt_pk_fp8_f32 v126, v128, v127
	v_lshlrev_b32_e32 v127, 16, v149
	v_and_b32_e32 v128, 0xffff0000, v149
	v_mul_f32_e32 v125, v125, v129
	v_add_f32_e32 v129, v118, v118
	v_mul_f32_e32 v129, 0x3fb8aa3b, v129
	v_exp_f32_e32 v129, v129
	v_mul_f32_e32 v125, v125, v137
	v_mul_f32_e32 v125, 0x42000000, v125
	v_med3_f32 v125, v125, s29, v231
	v_sub_f32_e32 v129, 1.0, v129
	v_max_f32_e32 v129, 0, v129
	v_sqrt_f32_e32 v129, v129
	v_cvt_pk_fp8_f32 v126, v124, v125 op_sel:[0,0,1]
	v_lshlrev_b32_e32 v124, 16, v148
	v_and_b32_e32 v125, 0xffff0000, v148
	v_mul_f32_e32 v114, v114, v129
	v_mul_f32_e32 v114, v114, v124
	v_add_f32_e32 v124, v119, v119
	v_mul_f32_e32 v124, 0x3fb8aa3b, v124
	v_exp_f32_e32 v124, v124
	v_mul_f32_e32 v114, 0x42000000, v114
	v_med3_f32 v114, v114, s29, v231
	v_sub_f32_e32 v124, 1.0, v124
	v_max_f32_e32 v124, 0, v124
	v_sqrt_f32_e32 v124, v124
	s_nop 0
	v_mul_f32_e32 v115, v115, v124
	v_add_f32_e32 v124, v120, v120
	v_mul_f32_e32 v124, 0x3fb8aa3b, v124
	v_exp_f32_e32 v124, v124
	v_mul_f32_e32 v115, v115, v125
	v_mul_f32_e32 v115, 0x42000000, v115
	v_med3_f32 v115, v115, s29, v231
	v_sub_f32_e32 v124, 1.0, v124
	v_max_f32_e32 v124, 0, v124
	v_sqrt_f32_e32 v124, v124
	v_cvt_pk_bf16_f32 v125, v120, v121
	v_mul_f32_e32 v116, v116, v124
	v_add_f32_e32 v124, v121, v121
	v_mul_f32_e32 v124, 0x3fb8aa3b, v124
	v_exp_f32_e32 v124, v124
	v_mul_f32_e32 v116, v116, v127
	v_mov_b32_e32 v127, 0
	v_cvt_pk_fp8_f32 v127, v114, v115
	v_sub_f32_e32 v124, 1.0, v124
	v_max_f32_e32 v124, 0, v124
	v_sqrt_f32_e32 v124, v124
	v_mul_f32_e32 v116, 0x42000000, v116
	v_med3_f32 v114, v116, s29, v231
	v_mul_f32_e32 v117, v117, v124
	v_mul_f32_e32 v117, v117, v128
	v_mul_f32_e32 v117, 0x42000000, v117
	v_med3_f32 v115, v117, s29, v231
	v_cvt_pk_fp8_f32 v127, v114, v115 op_sel:[0,0,1]
	v_add_co_u32_e32 v114, vcc, s84, v172
	v_cvt_pk_bf16_f32 v124, v118, v119
	s_nop 0
	v_addc_co_u32_e32 v115, vcc, 0, v173, vcc
	flat_store_dwordx4 v[114:115], v[122:125]
	v_add_co_u32_e32 v114, vcc, s93, v170
	s_nop 1
	v_addc_co_u32_e32 v115, vcc, 0, v171, vcc
	flat_store_dwordx2 v[114:115], v[126:127]
	v_add_co_u32_e32 v114, vcc, s92, v174
	v_add_f32_e32 v110, v110, v46
	s_nop 0
	v_addc_co_u32_e32 v115, vcc, 0, v175, vcc
	flat_load_dwordx4 v[114:117], v[114:115]
	v_mul_f32_e32 v110, 0xbfb8aa3b, v110
	v_add_f32_e32 v111, v111, v47
	v_exp_f32_e32 v110, v110
	v_mul_f32_e32 v111, 0xbfb8aa3b, v111
	v_exp_f32_e32 v111, v111
	v_add_f32_e32 v112, v112, v48
	v_add_f32_e32 v113, v113, v49
	v_add_f32_e32 v110, 1.0, v110
	v_mul_f32_e32 v112, 0xbfb8aa3b, v112
	v_mul_f32_e32 v113, 0xbfb8aa3b, v113
	v_rcp_f32_e32 v110, v110
	v_exp_f32_e32 v112, v112
	v_exp_f32_e32 v113, v113
	v_add_f32_e32 v111, 1.0, v111
	v_rcp_f32_e32 v111, v111
	v_add_co_u32_e32 v118, vcc, s89, v174
	v_add_f32_e32 v120, v106, v42
	s_nop 0
	v_addc_co_u32_e32 v119, vcc, 0, v175, vcc
	v_add_f32_e32 v122, v108, v44
	v_mul_f32_e32 v110, v110, v144
	v_add_f32_e32 v121, v107, v43
	v_add_f32_e32 v123, v109, v45
	flat_load_dwordx4 v[106:109], v[118:119]
	v_mul_f32_e32 v118, 0xbfb8aa3b, v120
	v_mul_f32_e32 v120, 0xbfb8aa3b, v122
	v_add_f32_e32 v112, 1.0, v112
	v_add_f32_e32 v113, 1.0, v113
	v_add_f32_e32 v122, v110, v110
	v_rcp_f32_e32 v112, v112
	v_rcp_f32_e32 v113, v113
	v_mul_f32_e32 v111, v111, v145
	v_mul_f32_e32 v122, 0x3fb8aa3b, v122
	v_mul_f32_e32 v119, 0xbfb8aa3b, v121
	v_mul_f32_e32 v121, 0xbfb8aa3b, v123
	v_add_f32_e32 v123, v111, v111
	v_exp_f32_e32 v122, v122
	v_exp_f32_e32 v118, v118
	v_mul_f32_e32 v123, 0x3fb8aa3b, v123
	v_exp_f32_e32 v123, v123
	v_exp_f32_e32 v119, v119
	v_mul_f32_e32 v112, v112, v142
	v_mul_f32_e32 v113, v113, v143
	v_add_f32_e32 v124, v112, v112
	v_add_f32_e32 v125, v113, v113
	v_sub_f32_e32 v122, 1.0, v122
	v_add_f32_e32 v118, 1.0, v118
	v_mul_f32_e32 v124, 0x3fb8aa3b, v124
	v_mul_f32_e32 v125, 0x3fb8aa3b, v125
	v_max_f32_e32 v122, 0, v122
	v_rcp_f32_e32 v118, v118
	v_exp_f32_e32 v124, v124
	v_exp_f32_e32 v125, v125
	v_sub_f32_e32 v123, 1.0, v123
	v_sqrt_f32_e32 v122, v122
	v_exp_f32_e32 v120, v120
	v_exp_f32_e32 v121, v121
	v_add_f32_e32 v119, 1.0, v119
	v_max_f32_e32 v123, 0, v123
	v_rcp_f32_e32 v119, v119
	v_sqrt_f32_e32 v123, v123
	v_add_f32_e32 v102, v102, v30
	v_mul_f32_e32 v102, 0xbfb8aa3b, v102
	v_sub_f32_e32 v124, 1.0, v124
	v_sub_f32_e32 v125, 1.0, v125
	v_mul_f32_e32 v118, v118, v122
	v_exp_f32_e32 v102, v102
	v_add_f32_e32 v120, 1.0, v120
	v_add_f32_e32 v121, 1.0, v121
	v_max_f32_e32 v124, 0, v124
	v_rcp_f32_e32 v120, v120
	v_rcp_f32_e32 v121, v121
	v_sqrt_f32_e32 v124, v124
	v_mul_f32_e32 v119, v119, v123
	v_cvt_pk_bf16_f32 v110, v110, v111
	v_cvt_pk_bf16_f32 v111, v112, v113
	v_add_f32_e32 v102, 1.0, v102
	v_rcp_f32_e32 v102, v102
	s_waitcnt vmcnt(0) lgkmcnt(0)
	v_lshlrev_b32_e32 v122, 16, v114
	v_mul_f32_e32 v118, v118, v122
	v_max_f32_e32 v122, 0, v125
	v_and_b32_e32 v114, 0xffff0000, v114
	v_sqrt_f32_e32 v122, v122
	v_mul_f32_e32 v114, v119, v114
	v_mul_f32_e32 v112, 0x42000000, v118
	v_mul_f32_e32 v113, 0x42000000, v114
	v_med3_f32 v112, v112, s29, v231
	v_med3_f32 v113, v113, s29, v231
	v_mov_b32_e32 v114, 0
	v_lshlrev_b32_e32 v123, 16, v115
	v_and_b32_e32 v115, 0xffff0000, v115
	v_mul_f32_e32 v119, v120, v124
	v_mul_f32_e32 v120, v121, v122
	v_cvt_pk_fp8_f32 v114, v112, v113
	v_mul_f32_e32 v119, v119, v123
	v_mul_f32_e32 v115, v120, v115
	v_mul_f32_e32 v118, 0x42000000, v119
	v_mul_f32_e32 v112, 0x42000000, v115
	v_med3_f32 v113, v118, s29, v231
	v_med3_f32 v112, v112, s29, v231
	v_mul_f32_e32 v102, v102, v130
	v_cvt_pk_fp8_f32 v114, v113, v112 op_sel:[0,0,1]
	v_lshlrev_b32_e32 v112, 16, v116
	v_and_b32_e32 v113, 0xffff0000, v116
	v_add_f32_e32 v116, v102, v102
	v_add_f32_e32 v103, v103, v31
	v_add_f32_e32 v98, v98, v26
	v_mul_f32_e32 v116, 0x3fb8aa3b, v116
	v_mul_f32_e32 v103, 0xbfb8aa3b, v103
	v_mul_f32_e32 v98, 0xbfb8aa3b, v98
	v_exp_f32_e32 v116, v116
	v_exp_f32_e32 v103, v103
	v_exp_f32_e32 v98, v98
	v_add_f32_e32 v104, v104, v32
	v_sub_f32_e32 v116, 1.0, v116
	v_add_f32_e32 v103, 1.0, v103
	v_add_f32_e32 v98, 1.0, v98
	v_max_f32_e32 v116, 0, v116
	v_rcp_f32_e32 v103, v103
	v_rcp_f32_e32 v98, v98
	v_sqrt_f32_e32 v116, v116
	v_add_f32_e32 v105, v105, v33
	v_mul_f32_e32 v103, v103, v131
	v_add_f32_e32 v99, v99, v27
	v_mul_f32_e32 v98, v98, v116
	v_add_f32_e32 v116, v103, v103
	v_mul_f32_e32 v116, 0x3fb8aa3b, v116
	v_mul_f32_e32 v104, 0xbfb8aa3b, v104
	v_mul_f32_e32 v105, 0xbfb8aa3b, v105
	v_mul_f32_e32 v99, 0xbfb8aa3b, v99
	v_exp_f32_e32 v116, v116
	v_exp_f32_e32 v104, v104
	v_exp_f32_e32 v105, v105
	v_exp_f32_e32 v99, v99
	v_sub_f32_e32 v116, 1.0, v116
	v_add_f32_e32 v104, 1.0, v104
	v_add_f32_e32 v105, 1.0, v105
	v_add_f32_e32 v99, 1.0, v99
	v_max_f32_e32 v116, 0, v116
	v_rcp_f32_e32 v104, v104
	v_rcp_f32_e32 v105, v105
	v_rcp_f32_e32 v99, v99
	v_sqrt_f32_e32 v116, v116
	v_mul_f32_e32 v104, v104, v132
	v_mul_f32_e32 v105, v105, v133
	v_mul_f32_e32 v98, v98, v112
	v_mul_f32_e32 v99, v99, v116
	v_add_f32_e32 v112, v104, v104
	v_add_f32_e32 v116, v105, v105
	v_add_f32_e32 v100, v100, v28
	v_mul_f32_e32 v112, 0x3fb8aa3b, v112
	v_add_f32_e32 v101, v101, v29
	v_mul_f32_e32 v116, 0x3fb8aa3b, v116
	v_mul_f32_e32 v100, 0xbfb8aa3b, v100
	v_exp_f32_e32 v112, v112
	v_mul_f32_e32 v101, 0xbfb8aa3b, v101
	v_exp_f32_e32 v116, v116
	v_add_f32_e32 v94, v94, v46
	v_exp_f32_e32 v100, v100
	v_exp_f32_e32 v101, v101
	v_mul_f32_e32 v94, 0xbfb8aa3b, v94
	v_exp_f32_e32 v94, v94
	v_sub_f32_e32 v112, 1.0, v112
	v_sub_f32_e32 v116, 1.0, v116
	v_add_f32_e32 v100, 1.0, v100
	v_max_f32_e32 v112, 0, v112
	v_add_f32_e32 v101, 1.0, v101
	v_max_f32_e32 v116, 0, v116
	v_rcp_f32_e32 v100, v100
	v_sqrt_f32_e32 v112, v112
	v_rcp_f32_e32 v101, v101
	v_sqrt_f32_e32 v116, v116
	v_add_f32_e32 v94, 1.0, v94
	v_rcp_f32_e32 v94, v94
	v_mul_f32_e32 v99, v99, v113
	v_lshlrev_b32_e32 v115, 16, v117
	v_and_b32_e32 v117, 0xffff0000, v117
	v_mul_f32_e32 v100, v100, v112
	v_mul_f32_e32 v101, v101, v116
	v_mul_f32_e32 v98, 0x42000000, v98
	v_mul_f32_e32 v99, 0x42000000, v99
	v_mul_f32_e32 v100, v100, v115
	v_mul_f32_e32 v101, v101, v117
	v_med3_f32 v98, v98, s29, v231
	v_med3_f32 v99, v99, s29, v231
	v_mov_b32_e32 v115, 0
	v_mul_f32_e32 v94, v94, v144
	v_cvt_pk_fp8_f32 v115, v98, v99
	v_mul_f32_e32 v98, 0x42000000, v101
	v_add_f32_e32 v101, v94, v94
	v_add_f32_e32 v95, v95, v47
	v_add_f32_e32 v90, v90, v42
	v_mul_f32_e32 v101, 0x3fb8aa3b, v101
	v_mul_f32_e32 v95, 0xbfb8aa3b, v95
	v_mul_f32_e32 v90, 0xbfb8aa3b, v90
	v_exp_f32_e32 v101, v101
	v_exp_f32_e32 v95, v95
	v_exp_f32_e32 v90, v90
	v_add_f32_e32 v91, v91, v43
	v_sub_f32_e32 v101, 1.0, v101
	v_add_f32_e32 v95, 1.0, v95
	v_add_f32_e32 v90, 1.0, v90
	v_max_f32_e32 v101, 0, v101
	v_rcp_f32_e32 v95, v95
	v_rcp_f32_e32 v90, v90
	v_sqrt_f32_e32 v101, v101
	v_add_f32_e32 v96, v96, v48
	v_mul_f32_e32 v95, v95, v145
	v_mul_f32_e32 v91, 0xbfb8aa3b, v91
	v_mul_f32_e32 v90, v90, v101
	v_add_f32_e32 v101, v95, v95
	v_mul_f32_e32 v101, 0x3fb8aa3b, v101
	v_exp_f32_e32 v101, v101
	v_mul_f32_e32 v96, 0xbfb8aa3b, v96
	v_add_f32_e32 v97, v97, v49
	v_exp_f32_e32 v91, v91
	v_exp_f32_e32 v96, v96
	v_mul_f32_e32 v97, 0xbfb8aa3b, v97
	v_exp_f32_e32 v97, v97
	v_mul_f32_e32 v100, 0x42000000, v100
	v_med3_f32 v99, v100, s29, v231
	v_med3_f32 v98, v98, s29, v231
	v_sub_f32_e32 v101, 1.0, v101
	v_add_f32_e32 v92, v92, v44
	v_cvt_pk_fp8_f32 v115, v99, v98 op_sel:[0,0,1]
	v_add_co_u32_e32 v98, vcc, s92, v172
	v_add_f32_e32 v91, 1.0, v91
	v_max_f32_e32 v101, 0, v101
	v_add_f32_e32 v96, 1.0, v96
	v_mul_f32_e32 v92, 0xbfb8aa3b, v92
	v_cvt_pk_bf16_f32 v112, v102, v103
	v_cvt_pk_bf16_f32 v113, v104, v105
	v_addc_co_u32_e32 v99, vcc, 0, v173, vcc
	v_rcp_f32_e32 v91, v91
	v_sqrt_f32_e32 v101, v101
	v_exp_f32_e32 v92, v92
	v_rcp_f32_e32 v96, v96
	v_add_f32_e32 v97, 1.0, v97
	flat_store_dwordx4 v[98:99], v[110:113]
	v_add_co_u32_e32 v98, vcc, s84, v170
	v_rcp_f32_e32 v97, v97
	s_nop 0
	v_addc_co_u32_e32 v99, vcc, 0, v171, vcc
	flat_store_dwordx2 v[98:99], v[114:115]
	v_lshlrev_b32_e32 v98, 16, v106
	v_mul_f32_e32 v98, v90, v98
	v_mul_f32_e32 v90, v91, v101
	v_add_f32_e32 v91, 1.0, v92
	v_mul_f32_e32 v92, v96, v142
	v_add_f32_e32 v96, v92, v92
	v_mul_f32_e32 v97, v97, v143
	v_mul_f32_e32 v96, 0x3fb8aa3b, v96
	v_add_f32_e32 v101, v97, v97
	v_exp_f32_e32 v96, v96
	v_add_f32_e32 v93, v93, v45
	v_mul_f32_e32 v101, 0x3fb8aa3b, v101
	v_mul_f32_e32 v93, 0xbfb8aa3b, v93
	v_exp_f32_e32 v101, v101
	v_exp_f32_e32 v93, v93
	v_add_f32_e32 v86, v86, v30
	v_mul_f32_e32 v86, 0xbfb8aa3b, v86
	v_sub_f32_e32 v96, 1.0, v96
	v_exp_f32_e32 v86, v86
	v_max_f32_e32 v96, 0, v96
	v_sub_f32_e32 v101, 1.0, v101
	v_rcp_f32_e32 v91, v91
	v_sqrt_f32_e32 v96, v96
	v_add_f32_e32 v93, 1.0, v93
	v_max_f32_e32 v101, 0, v101
	v_rcp_f32_e32 v93, v93
	v_sqrt_f32_e32 v101, v101
	v_add_f32_e32 v86, 1.0, v86
	v_and_b32_e32 v99, 0xffff0000, v106
	v_rcp_f32_e32 v86, v86
	v_lshlrev_b32_e32 v100, 16, v107
	v_mul_f32_e32 v99, v90, v99
	v_mul_f32_e32 v90, v91, v96
	v_and_b32_e32 v102, 0xffff0000, v107
	v_mul_f32_e32 v96, v90, v100
	v_mul_f32_e32 v90, v93, v101
	v_mul_f32_e32 v93, v90, v102
	v_cvt_pk_bf16_f32 v90, v94, v95
	v_cvt_pk_bf16_f32 v91, v92, v97
	v_mul_f32_e32 v92, 0x42000000, v98
	v_mul_f32_e32 v94, 0x42000000, v99
	v_mul_f32_e32 v95, 0x42000000, v96
	v_med3_f32 v92, v92, s29, v231
	v_med3_f32 v96, v94, s29, v231
	v_mov_b32_e32 v94, 0
	v_mul_f32_e32 v86, v86, v130
	v_cvt_pk_fp8_f32 v94, v92, v96
	v_add_f32_e32 v96, v86, v86
	v_add_f32_e32 v87, v87, v31
	v_add_f32_e32 v82, v82, v26
	v_mul_f32_e32 v96, 0x3fb8aa3b, v96
	v_mul_f32_e32 v87, 0xbfb8aa3b, v87
	v_mul_f32_e32 v82, 0xbfb8aa3b, v82
	v_exp_f32_e32 v96, v96
	v_exp_f32_e32 v87, v87
	v_exp_f32_e32 v82, v82
	v_add_f32_e32 v88, v88, v32
	v_sub_f32_e32 v96, 1.0, v96
	v_add_f32_e32 v87, 1.0, v87
	v_add_f32_e32 v82, 1.0, v82
	v_max_f32_e32 v96, 0, v96
	v_rcp_f32_e32 v87, v87
	v_rcp_f32_e32 v82, v82
	v_sqrt_f32_e32 v96, v96
	v_mul_f32_e32 v88, 0xbfb8aa3b, v88
	v_mul_f32_e32 v87, v87, v131
	v_exp_f32_e32 v88, v88
	v_mul_f32_e32 v82, v82, v96
	v_add_f32_e32 v96, v87, v87
	v_add_f32_e32 v89, v89, v33
	v_add_f32_e32 v83, v83, v27
	v_mul_f32_e32 v96, 0x3fb8aa3b, v96
	v_mul_f32_e32 v89, 0xbfb8aa3b, v89
	v_mul_f32_e32 v83, 0xbfb8aa3b, v83
	v_exp_f32_e32 v96, v96
	v_exp_f32_e32 v89, v89
	v_exp_f32_e32 v83, v83
	v_add_f32_e32 v88, 1.0, v88
	v_rcp_f32_e32 v88, v88
	v_sub_f32_e32 v96, 1.0, v96
	v_add_f32_e32 v89, 1.0, v89
	v_mul_f32_e32 v92, 0x42000000, v93
	v_add_f32_e32 v83, 1.0, v83
	v_max_f32_e32 v96, 0, v96
	v_rcp_f32_e32 v89, v89
	v_med3_f32 v93, v95, s29, v231
	v_med3_f32 v92, v92, s29, v231
	v_rcp_f32_e32 v83, v83
	v_sqrt_f32_e32 v96, v96
	v_cvt_pk_fp8_f32 v94, v93, v92 op_sel:[0,0,1]
	v_lshlrev_b32_e32 v92, 16, v108
	v_mul_f32_e32 v88, v88, v132
	v_mul_f32_e32 v82, v82, v92
	v_add_f32_e32 v92, v88, v88
	v_add_f32_e32 v84, v84, v28
	v_mul_f32_e32 v92, 0x3fb8aa3b, v92
	v_mul_f32_e32 v89, v89, v133
	v_mul_f32_e32 v84, 0xbfb8aa3b, v84
	v_mul_f32_e32 v83, v83, v96
	v_exp_f32_e32 v92, v92
	v_add_f32_e32 v96, v89, v89
	v_exp_f32_e32 v84, v84
	v_add_f32_e32 v85, v85, v29
	v_mul_f32_e32 v96, 0x3fb8aa3b, v96
	v_mul_f32_e32 v85, 0xbfb8aa3b, v85
	v_exp_f32_e32 v96, v96
	v_exp_f32_e32 v85, v85
	v_sub_f32_e32 v92, 1.0, v92
	v_add_f32_e32 v84, 1.0, v84
	v_max_f32_e32 v92, 0, v92
	v_rcp_f32_e32 v84, v84
	v_sqrt_f32_e32 v92, v92
	v_sub_f32_e32 v96, 1.0, v96
	v_add_f32_e32 v85, 1.0, v85
	v_max_f32_e32 v96, 0, v96
	v_and_b32_e32 v93, 0xffff0000, v108
	v_rcp_f32_e32 v85, v85
	v_sqrt_f32_e32 v96, v96
	v_mul_f32_e32 v83, v83, v93
	v_lshlrev_b32_e32 v95, 16, v109
	v_mul_f32_e32 v84, v84, v92
	v_mul_f32_e32 v82, 0x42000000, v82
	v_mul_f32_e32 v83, 0x42000000, v83
	v_mul_f32_e32 v84, v84, v95
	v_med3_f32 v82, v82, s29, v231
	v_med3_f32 v83, v83, s29, v231
	v_mov_b32_e32 v95, 0
	v_and_b32_e32 v97, 0xffff0000, v109
	v_mul_f32_e32 v85, v85, v96
	v_cvt_pk_fp8_f32 v95, v82, v83
	v_mul_f32_e32 v85, v85, v97
	v_mul_f32_e32 v84, 0x42000000, v84
	v_mul_f32_e32 v82, 0x42000000, v85
	v_med3_f32 v83, v84, s29, v231
	v_med3_f32 v82, v82, s29, v231
	v_cvt_pk_fp8_f32 v95, v83, v82 op_sel:[0,0,1]
	v_add_co_u32_e32 v82, vcc, s89, v172
	v_cvt_pk_bf16_f32 v92, v86, v87
	v_cvt_pk_bf16_f32 v93, v88, v89
	v_addc_co_u32_e32 v83, vcc, 0, v173, vcc
	s_mov_b32 s0, 0xc000
	flat_store_dwordx4 v[82:83], v[90:93]
	v_add_co_u32_e32 v82, vcc, s0, v170
	s_nop 1
	v_addc_co_u32_e32 v83, vcc, 0, v171, vcc
	flat_store_dwordx2 v[82:83], v[94:95]
	v_add_u32_e32 v82, 0x80, v234
	v_add_f32_e32 v78, v78, v46
	v_ashrrev_i32_e32 v83, 31, v82
	v_lshlrev_b64 v[82:83], 10, v[82:83]
	v_lshl_add_u64 v[88:89], v[82:83], 0, v[166:167]
	v_lshlrev_b64 v[90:91], 1, v[88:89]
	v_lshl_add_u64 v[82:83], s[24:25], 0, v[90:91]
	flat_load_dwordx4 v[84:87], v[82:83]
	v_mul_f32_e32 v78, 0xbfb8aa3b, v78
	v_exp_f32_e32 v92, v78
	v_add_f32_e32 v79, v79, v47
	v_add_f32_e32 v80, v80, v48
	v_mul_f32_e32 v79, 0xbfb8aa3b, v79
	v_add_f32_e32 v74, v74, v42
	v_add_f32_e32 v81, v81, v49
	v_mul_f32_e32 v80, 0xbfb8aa3b, v80
	v_exp_f32_e32 v93, v79
	v_add_f32_e32 v75, v75, v43
	v_add_f32_e32 v76, v76, v44
	v_add_f32_e32 v77, v77, v45
	v_mul_f32_e32 v74, 0xbfb8aa3b, v74
	v_mul_f32_e32 v81, 0xbfb8aa3b, v81
	v_exp_f32_e32 v94, v80
	v_lshl_add_u64 v[78:79], s[50:51], 0, v[88:89]
	v_add_f32_e32 v88, 1.0, v92
	v_mul_f32_e32 v75, 0xbfb8aa3b, v75
	v_mul_f32_e32 v76, 0xbfb8aa3b, v76
	v_mul_f32_e32 v77, 0xbfb8aa3b, v77
	v_exp_f32_e32 v74, v74
	v_exp_f32_e32 v95, v81
	v_rcp_f32_e32 v88, v88
	v_exp_f32_e32 v75, v75
	v_exp_f32_e32 v76, v76
	v_exp_f32_e32 v77, v77
	v_lshl_add_u64 v[80:81], s[48:49], 0, v[90:91]
	v_add_f32_e32 v90, 1.0, v93
	v_add_f32_e32 v92, 1.0, v94
	v_rcp_f32_e32 v90, v90
	v_add_f32_e32 v89, 1.0, v74
	v_add_f32_e32 v93, 1.0, v95
	v_add_co_u32_e32 v74, vcc, s84, v82
	v_rcp_f32_e32 v92, v92
	v_mul_f32_e32 v88, v88, v144
	v_add_f32_e32 v91, 1.0, v75
	v_add_f32_e32 v76, 1.0, v76
	v_add_f32_e32 v77, 1.0, v77
	v_addc_co_u32_e32 v75, vcc, 0, v83, vcc
	v_rcp_f32_e32 v93, v93
	v_add_f32_e32 v96, v88, v88
	v_rcp_f32_e32 v94, v76
	v_rcp_f32_e32 v95, v77
	flat_load_dwordx4 v[74:77], v[74:75]
	v_mul_f32_e32 v96, 0x3fb8aa3b, v96
	v_mul_f32_e32 v90, v90, v145
	v_exp_f32_e32 v96, v96
	v_mul_f32_e32 v92, v92, v142
	v_add_f32_e32 v97, v90, v90
	v_mul_f32_e32 v93, v93, v143
	v_add_f32_e32 v98, v92, v92
	v_mul_f32_e32 v97, 0x3fb8aa3b, v97
	v_add_f32_e32 v99, v93, v93
	v_mul_f32_e32 v98, 0x3fb8aa3b, v98
	v_exp_f32_e32 v97, v97
	v_mul_f32_e32 v99, 0x3fb8aa3b, v99
	v_exp_f32_e32 v98, v98
	v_sub_f32_e32 v96, 1.0, v96
	v_exp_f32_e32 v99, v99
	v_max_f32_e32 v96, 0, v96
	v_rcp_f32_e32 v89, v89
	v_sqrt_f32_e32 v96, v96
	v_add_f32_e32 v70, v70, v30
	v_sub_f32_e32 v97, 1.0, v97
	v_mul_f32_e32 v70, 0xbfb8aa3b, v70
	v_sub_f32_e32 v98, 1.0, v98
	v_max_f32_e32 v97, 0, v97
	v_exp_f32_e32 v70, v70
	v_rcp_f32_e32 v91, v91
	v_sub_f32_e32 v99, 1.0, v99
	v_max_f32_e32 v98, 0, v98
	v_sqrt_f32_e32 v97, v97
	v_max_f32_e32 v99, 0, v99
	v_sqrt_f32_e32 v98, v98
	v_mul_f32_e32 v89, v89, v96
	v_add_f32_e32 v70, 1.0, v70
	v_mul_f32_e32 v91, v91, v97
	s_waitcnt vmcnt(0) lgkmcnt(0)
	v_lshlrev_b32_e32 v96, 16, v84
	v_mul_f32_e32 v89, v89, v96
	v_sqrt_f32_e32 v96, v99
	v_and_b32_e32 v84, 0xffff0000, v84
	v_rcp_f32_e32 v70, v70
	v_lshlrev_b32_e32 v97, 16, v85
	v_mul_f32_e32 v91, v91, v84
	v_mul_f32_e32 v84, v94, v98
	v_and_b32_e32 v85, 0xffff0000, v85
	v_mul_f32_e32 v94, v84, v97
	v_mul_f32_e32 v84, v95, v96
	v_mul_f32_e32 v95, v84, v85
	v_cvt_pk_bf16_f32 v84, v88, v90
	v_mul_f32_e32 v88, 0x42000000, v89
	v_mul_f32_e32 v89, 0x42000000, v91
	v_med3_f32 v91, v88, s29, v231
	v_med3_f32 v89, v89, s29, v231
	v_mov_b32_e32 v88, 0
	v_mul_f32_e32 v70, v70, v130
	v_cvt_pk_fp8_f32 v88, v91, v89
	v_add_f32_e32 v91, v70, v70
	v_add_f32_e32 v71, v71, v31
	v_add_f32_e32 v66, v66, v26
	v_mul_f32_e32 v91, 0x3fb8aa3b, v91
	v_mul_f32_e32 v71, 0xbfb8aa3b, v71
	v_mul_f32_e32 v66, 0xbfb8aa3b, v66
	v_exp_f32_e32 v91, v91
	v_exp_f32_e32 v71, v71
	v_exp_f32_e32 v66, v66
	v_add_f32_e32 v73, v73, v33
	v_sub_f32_e32 v91, 1.0, v91
	v_add_f32_e32 v71, 1.0, v71
	v_add_f32_e32 v66, 1.0, v66
	v_max_f32_e32 v91, 0, v91
	v_rcp_f32_e32 v71, v71
	v_rcp_f32_e32 v66, v66
	v_sqrt_f32_e32 v91, v91
	v_add_f32_e32 v67, v67, v27
	v_mul_f32_e32 v71, v71, v131
	v_add_f32_e32 v72, v72, v32
	v_mul_f32_e32 v66, v66, v91
	v_add_f32_e32 v91, v71, v71
	v_mul_f32_e32 v91, 0x3fb8aa3b, v91
	v_mul_f32_e32 v73, 0xbfb8aa3b, v73
	v_mul_f32_e32 v67, 0xbfb8aa3b, v67
	v_exp_f32_e32 v91, v91
	v_mul_f32_e32 v72, 0xbfb8aa3b, v72
	v_exp_f32_e32 v73, v73
	v_exp_f32_e32 v67, v67
	v_exp_f32_e32 v72, v72
	v_sub_f32_e32 v91, 1.0, v91
	v_add_f32_e32 v73, 1.0, v73
	v_add_f32_e32 v67, 1.0, v67
	v_max_f32_e32 v91, 0, v91
	v_add_f32_e32 v72, 1.0, v72
	v_rcp_f32_e32 v73, v73
	v_rcp_f32_e32 v67, v67
	v_sqrt_f32_e32 v91, v91
	v_rcp_f32_e32 v72, v72
	v_mul_f32_e32 v90, 0x42000000, v94
	v_mul_f32_e32 v89, 0x42000000, v95
	v_med3_f32 v90, v90, s29, v231
	v_med3_f32 v89, v89, s29, v231
	v_mul_f32_e32 v73, v73, v133
	v_cvt_pk_fp8_f32 v88, v90, v89 op_sel:[0,0,1]
	v_lshlrev_b32_e32 v89, 16, v86
	v_mul_f32_e32 v67, v67, v91
	v_mul_f32_e32 v72, v72, v132
	v_add_f32_e32 v91, v73, v73
	v_mul_f32_e32 v66, v66, v89
	v_add_f32_e32 v89, v72, v72
	v_add_f32_e32 v69, v69, v29
	v_mul_f32_e32 v91, 0x3fb8aa3b, v91
	v_add_f32_e32 v68, v68, v28
	v_mul_f32_e32 v89, 0x3fb8aa3b, v89
	v_mul_f32_e32 v69, 0xbfb8aa3b, v69
	v_exp_f32_e32 v91, v91
	v_add_f32_e32 v62, v62, v46
	v_mul_f32_e32 v68, 0xbfb8aa3b, v68
	v_exp_f32_e32 v89, v89
	v_exp_f32_e32 v69, v69
	v_mul_f32_e32 v62, 0xbfb8aa3b, v62
	v_exp_f32_e32 v68, v68
	v_exp_f32_e32 v62, v62
	v_sub_f32_e32 v91, 1.0, v91
	v_sub_f32_e32 v89, 1.0, v89
	v_add_f32_e32 v69, 1.0, v69
	v_max_f32_e32 v91, 0, v91
	v_add_f32_e32 v68, 1.0, v68
	v_max_f32_e32 v89, 0, v89
	v_rcp_f32_e32 v69, v69
	v_sqrt_f32_e32 v91, v91
	v_add_f32_e32 v62, 1.0, v62
	v_rcp_f32_e32 v68, v68
	v_sqrt_f32_e32 v89, v89
	v_rcp_f32_e32 v62, v62
	v_and_b32_e32 v86, 0xffff0000, v86
	v_mul_f32_e32 v67, v67, v86
	v_lshlrev_b32_e32 v90, 16, v87
	v_and_b32_e32 v87, 0xffff0000, v87
	v_mul_f32_e32 v69, v69, v91
	v_mul_f32_e32 v66, 0x42000000, v66
	v_mul_f32_e32 v67, 0x42000000, v67
	v_mul_f32_e32 v68, v68, v89
	v_mul_f32_e32 v69, v69, v87
	v_med3_f32 v66, v66, s29, v231
	v_med3_f32 v67, v67, s29, v231
	v_mov_b32_e32 v89, 0
	v_mul_f32_e32 v62, v62, v144
	v_cvt_pk_fp8_f32 v89, v66, v67
	v_mul_f32_e32 v66, 0x42000000, v69
	v_add_f32_e32 v69, v62, v62
	v_add_f32_e32 v63, v63, v47
	v_add_f32_e32 v58, v58, v42
	v_mul_f32_e32 v69, 0x3fb8aa3b, v69
	v_mul_f32_e32 v63, 0xbfb8aa3b, v63
	v_mul_f32_e32 v58, 0xbfb8aa3b, v58
	v_exp_f32_e32 v69, v69
	v_exp_f32_e32 v63, v63
	v_exp_f32_e32 v58, v58
	v_add_f32_e32 v59, v59, v43
	v_sub_f32_e32 v69, 1.0, v69
	v_add_f32_e32 v63, 1.0, v63
	v_add_f32_e32 v58, 1.0, v58
	v_max_f32_e32 v69, 0, v69
	v_rcp_f32_e32 v63, v63
	v_rcp_f32_e32 v58, v58
	v_sqrt_f32_e32 v69, v69
	v_add_f32_e32 v64, v64, v48
	v_mul_f32_e32 v63, v63, v145
	v_mul_f32_e32 v59, 0xbfb8aa3b, v59
	v_mul_f32_e32 v58, v58, v69
	v_add_f32_e32 v69, v63, v63
	v_mul_f32_e32 v69, 0x3fb8aa3b, v69
	v_exp_f32_e32 v69, v69
	v_mul_f32_e32 v64, 0xbfb8aa3b, v64
	v_add_f32_e32 v65, v65, v49
	v_exp_f32_e32 v59, v59
	v_exp_f32_e32 v64, v64
	v_mul_f32_e32 v65, 0xbfb8aa3b, v65
	v_exp_f32_e32 v65, v65
	v_sub_f32_e32 v69, 1.0, v69
	v_add_f32_e32 v60, v60, v44
	v_add_f32_e32 v59, 1.0, v59
	v_max_f32_e32 v69, 0, v69
	v_add_f32_e32 v64, 1.0, v64
	v_mul_f32_e32 v60, 0xbfb8aa3b, v60
	v_mul_f32_e32 v68, v68, v90
	v_rcp_f32_e32 v59, v59
	v_sqrt_f32_e32 v69, v69
	v_exp_f32_e32 v60, v60
	v_rcp_f32_e32 v64, v64
	v_add_f32_e32 v65, 1.0, v65
	v_mul_f32_e32 v68, 0x42000000, v68
	v_rcp_f32_e32 v65, v65
	v_med3_f32 v67, v68, s29, v231
	v_med3_f32 v66, v66, s29, v231
	v_cvt_pk_fp8_f32 v89, v67, v66 op_sel:[0,0,1]
	v_lshlrev_b32_e32 v66, 16, v74
	v_mul_f32_e32 v66, v58, v66
	v_mul_f32_e32 v58, v59, v69
	v_add_f32_e32 v59, 1.0, v60
	v_mul_f32_e32 v60, v64, v142
	v_add_f32_e32 v64, v60, v60
	v_mul_f32_e32 v65, v65, v143
	v_mul_f32_e32 v64, 0x3fb8aa3b, v64
	v_add_f32_e32 v69, v65, v65
	v_exp_f32_e32 v64, v64
	v_add_f32_e32 v61, v61, v45
	v_mul_f32_e32 v69, 0x3fb8aa3b, v69
	v_mul_f32_e32 v61, 0xbfb8aa3b, v61
	v_exp_f32_e32 v69, v69
	v_exp_f32_e32 v61, v61
	v_add_f32_e32 v54, v54, v30
	v_mul_f32_e32 v54, 0xbfb8aa3b, v54
	v_sub_f32_e32 v64, 1.0, v64
	v_exp_f32_e32 v54, v54
	v_max_f32_e32 v64, 0, v64
	v_sub_f32_e32 v69, 1.0, v69
	v_rcp_f32_e32 v59, v59
	v_sqrt_f32_e32 v64, v64
	v_add_f32_e32 v61, 1.0, v61
	v_max_f32_e32 v69, 0, v69
	v_rcp_f32_e32 v61, v61
	v_sqrt_f32_e32 v69, v69
	v_add_f32_e32 v54, 1.0, v54
	v_and_b32_e32 v67, 0xffff0000, v74
	v_rcp_f32_e32 v54, v54
	v_lshlrev_b32_e32 v68, 16, v75
	v_mul_f32_e32 v67, v58, v67
	v_mul_f32_e32 v58, v59, v64
	v_cvt_pk_bf16_f32 v86, v70, v71
	v_and_b32_e32 v70, 0xffff0000, v75
	v_mul_f32_e32 v64, v58, v68
	v_mul_f32_e32 v58, v61, v69
	v_mul_f32_e32 v61, v58, v70
	v_cvt_pk_bf16_f32 v58, v62, v63
	v_cvt_pk_bf16_f32 v59, v60, v65
	v_mul_f32_e32 v60, 0x42000000, v66
	v_mul_f32_e32 v62, 0x42000000, v67
	v_mul_f32_e32 v63, 0x42000000, v64
	v_med3_f32 v60, v60, s29, v231
	v_med3_f32 v64, v62, s29, v231
	v_mov_b32_e32 v62, 0
	v_mul_f32_e32 v54, v54, v130
	v_cvt_pk_fp8_f32 v62, v60, v64
	v_add_f32_e32 v64, v54, v54
	v_add_f32_e32 v55, v55, v31
	v_add_f32_e32 v50, v50, v26
	v_mul_f32_e32 v64, 0x3fb8aa3b, v64
	v_mul_f32_e32 v55, 0xbfb8aa3b, v55
	v_mul_f32_e32 v50, 0xbfb8aa3b, v50
	v_exp_f32_e32 v64, v64
	v_exp_f32_e32 v55, v55
	v_exp_f32_e32 v50, v50
	v_add_f32_e32 v56, v56, v32
	v_sub_f32_e32 v64, 1.0, v64
	v_add_f32_e32 v55, 1.0, v55
	v_add_f32_e32 v50, 1.0, v50
	v_max_f32_e32 v64, 0, v64
	v_rcp_f32_e32 v55, v55
	v_rcp_f32_e32 v50, v50
	v_sqrt_f32_e32 v64, v64
	v_mul_f32_e32 v56, 0xbfb8aa3b, v56
	v_mul_f32_e32 v55, v55, v131
	v_exp_f32_e32 v56, v56
	v_mul_f32_e32 v50, v50, v64
	v_add_f32_e32 v64, v55, v55
	v_add_f32_e32 v57, v57, v33
	v_add_f32_e32 v51, v51, v27
	v_mul_f32_e32 v64, 0x3fb8aa3b, v64
	v_mul_f32_e32 v57, 0xbfb8aa3b, v57
	v_mul_f32_e32 v51, 0xbfb8aa3b, v51
	v_exp_f32_e32 v64, v64
	v_exp_f32_e32 v57, v57
	v_exp_f32_e32 v51, v51
	v_add_f32_e32 v56, 1.0, v56
	v_rcp_f32_e32 v56, v56
	v_sub_f32_e32 v64, 1.0, v64
	v_add_f32_e32 v57, 1.0, v57
	v_mul_f32_e32 v60, 0x42000000, v61
	v_add_f32_e32 v51, 1.0, v51
	v_max_f32_e32 v64, 0, v64
	v_rcp_f32_e32 v57, v57
	v_med3_f32 v61, v63, s29, v231
	v_med3_f32 v60, v60, s29, v231
	v_rcp_f32_e32 v51, v51
	v_sqrt_f32_e32 v64, v64
	v_cvt_pk_fp8_f32 v62, v61, v60 op_sel:[0,0,1]
	v_lshlrev_b32_e32 v60, 16, v76
	v_mul_f32_e32 v56, v56, v132
	v_mul_f32_e32 v50, v50, v60
	v_add_f32_e32 v60, v56, v56
	v_add_f32_e32 v52, v52, v28
	v_mul_f32_e32 v60, 0x3fb8aa3b, v60
	v_mul_f32_e32 v57, v57, v133
	v_mul_f32_e32 v52, 0xbfb8aa3b, v52
	v_mul_f32_e32 v51, v51, v64
	v_exp_f32_e32 v60, v60
	v_add_f32_e32 v64, v57, v57
	v_exp_f32_e32 v52, v52
	v_add_f32_e32 v53, v53, v29
	v_mul_f32_e32 v64, 0x3fb8aa3b, v64
	v_mul_f32_e32 v53, 0xbfb8aa3b, v53
	v_exp_f32_e32 v64, v64
	v_exp_f32_e32 v53, v53
	v_sub_f32_e32 v60, 1.0, v60
	v_add_f32_e32 v52, 1.0, v52
	v_max_f32_e32 v60, 0, v60
	v_rcp_f32_e32 v52, v52
	v_sqrt_f32_e32 v60, v60
	v_sub_f32_e32 v64, 1.0, v64
	v_add_f32_e32 v53, 1.0, v53
	v_max_f32_e32 v64, 0, v64
	v_and_b32_e32 v61, 0xffff0000, v76
	v_rcp_f32_e32 v53, v53
	v_sqrt_f32_e32 v64, v64
	v_mul_f32_e32 v51, v51, v61
	v_lshlrev_b32_e32 v63, 16, v77
	v_mul_f32_e32 v52, v52, v60
	v_mul_f32_e32 v50, 0x42000000, v50
	v_mul_f32_e32 v51, 0x42000000, v51
	v_mul_f32_e32 v52, v52, v63
	v_med3_f32 v50, v50, s29, v231
	v_med3_f32 v51, v51, s29, v231
	v_mov_b32_e32 v63, 0
	v_and_b32_e32 v65, 0xffff0000, v77
	v_mul_f32_e32 v53, v53, v64
	v_cvt_pk_fp8_f32 v63, v50, v51
	v_mul_f32_e32 v53, v53, v65
	v_mul_f32_e32 v52, 0x42000000, v52
	v_mul_f32_e32 v50, 0x42000000, v53
	v_med3_f32 v51, v52, s29, v231
	v_med3_f32 v50, v50, s29, v231
	v_cvt_pk_fp8_f32 v63, v51, v50 op_sel:[0,0,1]
	v_add_co_u32_e32 v50, vcc, s84, v80
	v_cvt_pk_bf16_f32 v85, v92, v93
	v_cvt_pk_bf16_f32 v87, v72, v73
	v_cvt_pk_bf16_f32 v60, v54, v55
	v_cvt_pk_bf16_f32 v61, v56, v57
	v_addc_co_u32_e32 v51, vcc, 0, v81, vcc
	flat_store_dwordx4 v[80:81], v[84:87]
	flat_store_dwordx2 v[78:79], v[88:89]
	flat_store_dwordx4 v[50:51], v[58:61]
	v_add_co_u32_e32 v50, vcc, s93, v78
	s_nop 1
	v_addc_co_u32_e32 v51, vcc, 0, v79, vcc
	flat_store_dwordx2 v[50:51], v[62:63]
	v_add_co_u32_e32 v50, vcc, s92, v82
	v_add_f32_e32 v38, v38, v46
	s_nop 0
	v_addc_co_u32_e32 v51, vcc, 0, v83, vcc
	flat_load_dwordx4 v[54:57], v[50:51]
	v_mul_f32_e32 v38, 0xbfb8aa3b, v38
	v_exp_f32_e32 v38, v38
	v_add_f32_e32 v34, v34, v42
	v_mul_f32_e32 v34, 0xbfb8aa3b, v34
	v_exp_f32_e32 v34, v34
	v_add_f32_e32 v38, 1.0, v38
	v_rcp_f32_e32 v38, v38
	v_add_f32_e32 v39, v39, v47
	v_add_f32_e32 v34, 1.0, v34
	v_mul_f32_e32 v39, 0xbfb8aa3b, v39
	v_exp_f32_e32 v39, v39
	v_add_f32_e32 v35, v35, v43
	v_mul_f32_e32 v35, 0xbfb8aa3b, v35
	v_exp_f32_e32 v35, v35
	v_add_f32_e32 v39, 1.0, v39
	v_rcp_f32_e32 v39, v39
	v_add_f32_e32 v36, v36, v44
	v_add_f32_e32 v35, 1.0, v35
	v_rcp_f32_e32 v35, v35
	v_mul_f32_e32 v39, v39, v145
	v_mul_f32_e32 v36, 0xbfb8aa3b, v36
	v_exp_f32_e32 v36, v36
	v_add_co_u32_e32 v50, vcc, s89, v82
	v_add_f32_e32 v22, v22, v30
	v_add_f32_e32 v36, 1.0, v36
	v_rcp_f32_e32 v36, v36
	v_addc_co_u32_e32 v51, vcc, 0, v83, vcc
	flat_load_dwordx4 v[50:53], v[50:51]
	v_add_f32_e32 v37, v37, v45
	v_mul_f32_e32 v22, 0xbfb8aa3b, v22
	v_mul_f32_e32 v37, 0xbfb8aa3b, v37
	v_exp_f32_e32 v22, v22
	v_exp_f32_e32 v37, v37
	v_add_f32_e32 v18, v18, v26
	v_add_f32_e32 v23, v23, v31
	v_add_f32_e32 v22, 1.0, v22
	v_add_f32_e32 v37, 1.0, v37
	v_rcp_f32_e32 v22, v22
	v_rcp_f32_e32 v37, v37
	v_mul_f32_e32 v18, 0xbfb8aa3b, v18
	v_mul_f32_e32 v23, 0xbfb8aa3b, v23
	v_mul_f32_e32 v22, v22, v130
	v_exp_f32_e32 v18, v18
	v_exp_f32_e32 v23, v23
	v_add_f32_e32 v24, v24, v32
	v_add_f32_e32 v19, v19, v27
	v_add_f32_e32 v18, 1.0, v18
	v_add_f32_e32 v23, 1.0, v23
	v_rcp_f32_e32 v18, v18
	v_rcp_f32_e32 v23, v23
	v_mul_f32_e32 v24, 0xbfb8aa3b, v24
	v_mul_f32_e32 v19, 0xbfb8aa3b, v19
	v_exp_f32_e32 v24, v24
	v_mul_f32_e32 v23, v23, v131
	v_exp_f32_e32 v19, v19
	v_add_f32_e32 v25, v25, v33
	v_add_f32_e32 v24, 1.0, v24
	v_rcp_f32_e32 v24, v24
	v_add_f32_e32 v19, 1.0, v19
	v_rcp_f32_e32 v19, v19
	v_add_f32_e32 v20, v20, v28
	v_mul_f32_e32 v24, v24, v132
	v_mul_f32_e32 v25, 0xbfb8aa3b, v25
	v_mul_f32_e32 v20, 0xbfb8aa3b, v20
	v_exp_f32_e32 v25, v25
	v_exp_f32_e32 v20, v20
	v_add_f32_e32 v14, v14, v46
	v_add_f32_e32 v21, v21, v29
	v_add_f32_e32 v25, 1.0, v25
	v_add_f32_e32 v20, 1.0, v20
	v_rcp_f32_e32 v25, v25
	v_rcp_f32_e32 v20, v20
	v_mul_f32_e32 v14, 0xbfb8aa3b, v14
	v_mul_f32_e32 v21, 0xbfb8aa3b, v21
	v_mul_f32_e32 v25, v25, v133
	v_exp_f32_e32 v14, v14
	v_exp_f32_e32 v21, v21
	s_waitcnt vmcnt(0) lgkmcnt(0)
	v_lshlrev_b32_e32 v58, 16, v54
	v_and_b32_e32 v59, 0xffff0000, v54
	v_lshlrev_b32_e32 v60, 16, v55
	v_and_b32_e32 v54, 0xffff0000, v55
	v_rcp_f32_e32 v55, v34
	v_mul_f32_e32 v34, v38, v144
	v_add_f32_e32 v38, v34, v34
	v_mul_f32_e32 v38, 0x3fb8aa3b, v38
	v_exp_f32_e32 v38, v38
	v_cvt_pk_bf16_f32 v34, v34, v39
	v_add_f32_e32 v14, 1.0, v14
	v_add_f32_e32 v21, 1.0, v21
	v_sub_f32_e32 v38, 1.0, v38
	v_max_f32_e32 v38, 0, v38
	v_sqrt_f32_e32 v38, v38
	v_rcp_f32_e32 v14, v14
	v_rcp_f32_e32 v21, v21
	v_add_f32_e32 v10, v10, v42
	v_mul_f32_e32 v38, v55, v38
	v_add_f32_e32 v55, v39, v39
	v_mul_f32_e32 v55, 0x3fb8aa3b, v55
	v_exp_f32_e32 v55, v55
	v_mul_f32_e32 v38, v38, v58
	v_mul_f32_e32 v38, 0x42000000, v38
	v_mul_f32_e32 v14, v14, v144
	v_sub_f32_e32 v55, 1.0, v55
	v_max_f32_e32 v55, 0, v55
	v_sqrt_f32_e32 v55, v55
	v_mul_f32_e32 v10, 0xbfb8aa3b, v10
	v_exp_f32_e32 v10, v10
	v_add_f32_e32 v11, v11, v43
	v_mul_f32_e32 v35, v35, v55
	v_mul_f32_e32 v55, v35, v59
	v_add_f32_e32 v35, v40, v48
	v_mul_f32_e32 v35, 0xbfb8aa3b, v35
	v_exp_f32_e32 v35, v35
	v_mul_f32_e32 v39, 0x42000000, v55
	v_med3_f32 v39, v39, s29, v231
	v_add_f32_e32 v10, 1.0, v10
	v_add_f32_e32 v35, 1.0, v35
	v_rcp_f32_e32 v35, v35
	v_rcp_f32_e32 v10, v10
	v_mul_f32_e32 v11, 0xbfb8aa3b, v11
	v_exp_f32_e32 v11, v11
	v_mul_f32_e32 v35, v35, v142
	v_add_f32_e32 v40, v35, v35
	v_mul_f32_e32 v40, 0x3fb8aa3b, v40
	v_exp_f32_e32 v40, v40
	v_add_f32_e32 v11, 1.0, v11
	v_rcp_f32_e32 v11, v11
	v_add_f32_e32 v12, v12, v44
	v_sub_f32_e32 v40, 1.0, v40
	v_max_f32_e32 v40, 0, v40
	v_sqrt_f32_e32 v40, v40
	v_mul_f32_e32 v12, 0xbfb8aa3b, v12
	v_exp_f32_e32 v12, v12
	v_add_f32_e32 v6, v6, v30
	v_mul_f32_e32 v36, v36, v40
	v_add_f32_e32 v40, v41, v49
	v_mul_f32_e32 v40, 0xbfb8aa3b, v40
	v_exp_f32_e32 v40, v40
	v_mul_f32_e32 v36, v36, v60
	v_mul_f32_e32 v36, 0x42000000, v36
	v_med3_f32 v36, v36, s29, v231
	v_add_f32_e32 v40, 1.0, v40
	v_rcp_f32_e32 v40, v40
	v_add_f32_e32 v12, 1.0, v12
	v_rcp_f32_e32 v12, v12
	v_add_f32_e32 v13, v13, v45
	v_mul_f32_e32 v40, v40, v143
	v_add_f32_e32 v41, v40, v40
	v_mul_f32_e32 v41, 0x3fb8aa3b, v41
	v_exp_f32_e32 v41, v41
	v_cvt_pk_bf16_f32 v35, v35, v40
	v_med3_f32 v40, v38, s29, v231
	v_mov_b32_e32 v38, 0
	v_sub_f32_e32 v41, 1.0, v41
	v_max_f32_e32 v41, 0, v41
	v_sqrt_f32_e32 v41, v41
	v_cvt_pk_fp8_f32 v38, v40, v39
	v_lshlrev_b32_e32 v39, 16, v57
	v_and_b32_e32 v40, 0xffff0000, v57
	v_mul_f32_e32 v37, v37, v41
	v_add_f32_e32 v41, v22, v22
	v_mul_f32_e32 v41, 0x3fb8aa3b, v41
	v_exp_f32_e32 v41, v41
	v_mul_f32_e32 v37, v37, v54
	v_mul_f32_e32 v37, 0x42000000, v37
	v_med3_f32 v37, v37, s29, v231
	v_sub_f32_e32 v41, 1.0, v41
	v_max_f32_e32 v41, 0, v41
	v_sqrt_f32_e32 v41, v41
	v_cvt_pk_fp8_f32 v38, v36, v37 op_sel:[0,0,1]
	v_lshlrev_b32_e32 v36, 16, v56
	v_and_b32_e32 v37, 0xffff0000, v56
	v_mul_f32_e32 v18, v18, v41
	v_mul_f32_e32 v18, v18, v36
	v_add_f32_e32 v36, v23, v23
	v_mul_f32_e32 v36, 0x3fb8aa3b, v36
	v_exp_f32_e32 v36, v36
	v_mul_f32_e32 v18, 0x42000000, v18
	v_med3_f32 v18, v18, s29, v231
	v_mul_f32_e32 v6, 0xbfb8aa3b, v6
	v_sub_f32_e32 v36, 1.0, v36
	v_max_f32_e32 v36, 0, v36
	v_sqrt_f32_e32 v36, v36
	v_mul_f32_e32 v13, 0xbfb8aa3b, v13
	v_exp_f32_e32 v6, v6
	v_exp_f32_e32 v13, v13
	v_mul_f32_e32 v19, v19, v36
	v_add_f32_e32 v36, v24, v24
	v_mul_f32_e32 v36, 0x3fb8aa3b, v36
	v_exp_f32_e32 v36, v36
	v_mul_f32_e32 v19, v19, v37
	v_mul_f32_e32 v19, 0x42000000, v19
	v_med3_f32 v19, v19, s29, v231
	v_sub_f32_e32 v36, 1.0, v36
	v_max_f32_e32 v36, 0, v36
	v_sqrt_f32_e32 v36, v36
	v_cvt_pk_bf16_f32 v37, v24, v25
	v_add_f32_e32 v6, 1.0, v6
	v_add_f32_e32 v13, 1.0, v13
	v_mul_f32_e32 v20, v20, v36
	v_add_f32_e32 v36, v25, v25
	v_mul_f32_e32 v36, 0x3fb8aa3b, v36
	v_exp_f32_e32 v36, v36
	v_mul_f32_e32 v20, v20, v39
	v_mov_b32_e32 v39, 0
	v_cvt_pk_fp8_f32 v39, v18, v19
	v_sub_f32_e32 v36, 1.0, v36
	v_max_f32_e32 v36, 0, v36
	v_sqrt_f32_e32 v36, v36
	v_mul_f32_e32 v20, 0x42000000, v20
	v_med3_f32 v18, v20, s29, v231
	v_rcp_f32_e32 v6, v6
	v_mul_f32_e32 v21, v21, v36
	v_cvt_pk_bf16_f32 v36, v22, v23
	v_add_f32_e32 v22, v14, v14
	v_mul_f32_e32 v22, 0x3fb8aa3b, v22
	v_exp_f32_e32 v22, v22
	v_mul_f32_e32 v21, v21, v40
	v_mul_f32_e32 v21, 0x42000000, v21
	v_med3_f32 v19, v21, s29, v231
	v_sub_f32_e32 v22, 1.0, v22
	v_max_f32_e32 v22, 0, v22
	v_cvt_pk_fp8_f32 v39, v18, v19 op_sel:[0,0,1]
	v_add_co_u32_e32 v18, vcc, s92, v80
	v_sqrt_f32_e32 v22, v22
	s_nop 0
	v_addc_co_u32_e32 v19, vcc, 0, v81, vcc
	flat_store_dwordx4 v[18:19], v[34:37]
	v_add_co_u32_e32 v18, vcc, s84, v78
	v_mul_f32_e32 v10, v10, v22
	s_nop 0
	v_addc_co_u32_e32 v19, vcc, 0, v79, vcc
	flat_store_dwordx2 v[18:19], v[38:39]
	v_lshlrev_b32_e32 v18, 16, v50
	v_mul_f32_e32 v18, v10, v18
	v_add_f32_e32 v10, v15, v47
	v_mul_f32_e32 v10, 0xbfb8aa3b, v10
	v_exp_f32_e32 v10, v10
	v_and_b32_e32 v19, 0xffff0000, v50
	v_rcp_f32_e32 v13, v13
	v_mul_f32_e32 v6, v6, v130
	v_add_f32_e32 v10, 1.0, v10
	v_rcp_f32_e32 v10, v10
	v_add_f32_e32 v2, v2, v26
	v_add_f32_e32 v7, v7, v31
	v_mul_f32_e32 v2, 0xbfb8aa3b, v2
	v_mul_f32_e32 v10, v10, v145
	v_add_f32_e32 v15, v10, v10
	v_mul_f32_e32 v15, 0x3fb8aa3b, v15
	v_exp_f32_e32 v15, v15
	v_mul_f32_e32 v7, 0xbfb8aa3b, v7
	v_exp_f32_e32 v2, v2
	v_exp_f32_e32 v7, v7
	v_sub_f32_e32 v15, 1.0, v15
	v_max_f32_e32 v15, 0, v15
	v_sqrt_f32_e32 v15, v15
	v_cvt_pk_bf16_f32 v10, v14, v10
	v_mul_f32_e32 v14, 0x42000000, v18
	v_add_f32_e32 v2, 1.0, v2
	v_mul_f32_e32 v11, v11, v15
	v_mul_f32_e32 v15, v11, v19
	v_add_f32_e32 v11, v16, v48
	v_mul_f32_e32 v11, 0xbfb8aa3b, v11
	v_exp_f32_e32 v11, v11
	v_mul_f32_e32 v15, 0x42000000, v15
	v_med3_f32 v15, v15, s29, v231
	v_add_f32_e32 v7, 1.0, v7
	v_add_f32_e32 v11, 1.0, v11
	v_rcp_f32_e32 v11, v11
	v_lshlrev_b32_e32 v20, 16, v51
	v_and_b32_e32 v21, 0xffff0000, v51
	v_rcp_f32_e32 v2, v2
	v_mul_f32_e32 v11, v11, v142
	v_add_f32_e32 v16, v11, v11
	v_mul_f32_e32 v16, 0x3fb8aa3b, v16
	v_exp_f32_e32 v16, v16
	v_rcp_f32_e32 v7, v7
	v_add_f32_e32 v8, v8, v32
	v_add_f32_e32 v3, v3, v27
	v_sub_f32_e32 v16, 1.0, v16
	v_max_f32_e32 v16, 0, v16
	v_sqrt_f32_e32 v16, v16
	v_mul_f32_e32 v7, v7, v131
	v_mul_f32_e32 v8, 0xbfb8aa3b, v8
	v_mul_f32_e32 v3, 0xbfb8aa3b, v3
	v_mul_f32_e32 v12, v12, v16
	v_add_f32_e32 v16, v17, v49
	v_mul_f32_e32 v16, 0xbfb8aa3b, v16
	v_exp_f32_e32 v16, v16
	v_mul_f32_e32 v12, v12, v20
	v_mul_f32_e32 v12, 0x42000000, v12
	v_med3_f32 v12, v12, s29, v231
	v_add_f32_e32 v16, 1.0, v16
	v_rcp_f32_e32 v16, v16
	v_exp_f32_e32 v8, v8
	v_exp_f32_e32 v3, v3
	v_add_f32_e32 v9, v9, v33
	v_mul_f32_e32 v16, v16, v143
	v_add_f32_e32 v17, v16, v16
	v_mul_f32_e32 v17, 0x3fb8aa3b, v17
	v_exp_f32_e32 v17, v17
	v_cvt_pk_bf16_f32 v11, v11, v16
	v_med3_f32 v16, v14, s29, v231
	v_mov_b32_e32 v14, 0
	v_sub_f32_e32 v17, 1.0, v17
	v_max_f32_e32 v17, 0, v17
	v_sqrt_f32_e32 v17, v17
	v_cvt_pk_fp8_f32 v14, v16, v15
	v_add_f32_e32 v8, 1.0, v8
	v_add_f32_e32 v3, 1.0, v3
	v_mul_f32_e32 v13, v13, v17
	v_add_f32_e32 v17, v6, v6
	v_mul_f32_e32 v17, 0x3fb8aa3b, v17
	v_exp_f32_e32 v17, v17
	v_mul_f32_e32 v13, v13, v21
	v_mul_f32_e32 v13, 0x42000000, v13
	v_med3_f32 v13, v13, s29, v231
	v_sub_f32_e32 v17, 1.0, v17
	v_max_f32_e32 v17, 0, v17
	v_sqrt_f32_e32 v17, v17
	v_cvt_pk_fp8_f32 v14, v12, v13 op_sel:[0,0,1]
	v_lshlrev_b32_e32 v12, 16, v52
	v_rcp_f32_e32 v8, v8
	v_mul_f32_e32 v2, v2, v17
	v_mul_f32_e32 v2, v2, v12
	v_add_f32_e32 v12, v7, v7
	v_mul_f32_e32 v12, 0x3fb8aa3b, v12
	v_exp_f32_e32 v12, v12
	v_rcp_f32_e32 v3, v3
	v_mul_f32_e32 v8, v8, v132
	v_add_f32_e32 v4, v4, v28
	v_sub_f32_e32 v12, 1.0, v12
	v_max_f32_e32 v12, 0, v12
	v_sqrt_f32_e32 v12, v12
	v_mul_f32_e32 v9, 0xbfb8aa3b, v9
	v_mul_f32_e32 v4, 0xbfb8aa3b, v4
	v_exp_f32_e32 v9, v9
	v_mul_f32_e32 v3, v3, v12
	v_add_f32_e32 v12, v8, v8
	v_mul_f32_e32 v12, 0x3fb8aa3b, v12
	v_exp_f32_e32 v12, v12
	v_exp_f32_e32 v4, v4
	v_add_f32_e32 v9, 1.0, v9
	v_rcp_f32_e32 v9, v9
	v_sub_f32_e32 v12, 1.0, v12
	v_add_f32_e32 v4, 1.0, v4
	v_max_f32_e32 v12, 0, v12
	v_rcp_f32_e32 v4, v4
	v_sqrt_f32_e32 v12, v12
	v_mul_f32_e32 v9, v9, v133
	v_add_f32_e32 v5, v5, v29
	v_mul_f32_e32 v5, 0xbfb8aa3b, v5
	v_mul_f32_e32 v4, v4, v12
	v_add_f32_e32 v12, v9, v9
	v_mul_f32_e32 v12, 0x3fb8aa3b, v12
	v_exp_f32_e32 v12, v12
	v_exp_f32_e32 v5, v5
	v_and_b32_e32 v13, 0xffff0000, v52
	v_mul_f32_e32 v3, v3, v13
	v_sub_f32_e32 v12, 1.0, v12
	v_add_f32_e32 v5, 1.0, v5
	v_max_f32_e32 v12, 0, v12
	v_rcp_f32_e32 v5, v5
	v_sqrt_f32_e32 v12, v12
	v_lshlrev_b32_e32 v15, 16, v53
	v_mul_f32_e32 v2, 0x42000000, v2
	v_mul_f32_e32 v3, 0x42000000, v3
	v_mul_f32_e32 v4, v4, v15
	v_med3_f32 v2, v2, s29, v231
	v_med3_f32 v3, v3, s29, v231
	v_mov_b32_e32 v15, 0
	v_and_b32_e32 v16, 0xffff0000, v53
	v_mul_f32_e32 v5, v5, v12
	v_cvt_pk_fp8_f32 v15, v2, v3
	v_mul_f32_e32 v5, v5, v16
	v_mul_f32_e32 v4, 0x42000000, v4
	v_mul_f32_e32 v5, 0x42000000, v5
	v_med3_f32 v2, v4, s29, v231
	v_med3_f32 v3, v5, s29, v231
	v_cvt_pk_fp8_f32 v15, v2, v3 op_sel:[0,0,1]
	v_add_co_u32_e32 v2, vcc, 0x18000, v80
	v_cvt_pk_bf16_f32 v12, v6, v7
	v_cvt_pk_bf16_f32 v13, v8, v9
	v_addc_co_u32_e32 v3, vcc, 0, v81, vcc
	flat_store_dwordx4 v[2:3], v[10:13]
	v_add_co_u32_e32 v2, vcc, 0xc000, v78
	s_nop 1
	v_addc_co_u32_e32 v3, vcc, 0, v79, vcc
	flat_store_dwordx2 v[2:3], v[14:15]
	s_and_b64 vcc, exec, s[12:13]
	s_mov_b32 s82, s40
	s_mov_b32 s52, s42
	s_mov_b64 s[14:15], s[46:47]
	s_mov_b64 s[48:49], s[44:45]
	s_mov_b32 s94, s23
	s_cbranch_vccz .LBB0_1638
	s_waitcnt vmcnt(0)
	s_cmpk_gt_u32 s22, 0xff
	v_readlane_b32 s81, v253, 46
	v_readlane_b32 s80, v253, 45
	v_readlane_b32 s89, v253, 44
	s_cbranch_scc1 .LBB0_1649
	s_barrier

.LBB0_1786:
	ds_read_b128 v[130:133], v168
	ds_read_b128 v[134:137], v168 offset:1024
	ds_read_b128 v[138:141], v168 offset:2048
	ds_read_b128 v[142:145], v168 offset:3072
	s_add_u32 s0, s38, 0xfffc0080
	s_addc_u32 s1, s39, -1
	s_cmp_eq_u32 s66, 12
	s_cselect_b32 s43, s60, s1
	s_cselect_b32 s42, s61, s0
	s_cselect_b32 s41, s62, s65
	s_cselect_b32 s40, s63, s64
	s_mov_b32 m0, s50
	v_lshl_add_u64 v[164:165], s[38:39], 0, v[162:163]
	ds_read_b128 v[146:149], v169
	ds_read_b128 v[172:175], v169 offset:1024
	ds_read_b128 v[176:179], v169 offset:2048
	ds_read_b128 v[180:183], v169 offset:3072
	ds_read_b128 v[184:187], v169 offset:4096
	ds_read_b128 v[188:191], v169 offset:5120
	ds_read_b128 v[192:195], v169 offset:6144
	ds_read_b128 v[196:199], v169 offset:7168
	global_load_lds_dwordx4 v[164:165], off
	v_lshl_add_u64 v[164:165], s[38:39], 0, v[160:161]
	s_mov_b32 m0, s51
	s_nop 0
	global_load_lds_dwordx4 v[164:165], off
	s_waitcnt lgkmcnt(8)
	s_waitcnt vmcnt(10)
	s_barrier
	s_waitcnt lgkmcnt(0)
	s_waitcnt lgkmcnt(0)
	v_mfma_f32_16x16x32_bf16 v[126:129], v[130:133], v[146:149], v[126:129]
	v_mfma_f32_16x16x32_bf16 v[122:125], v[138:141], v[146:149], v[122:125]
	v_mfma_f32_16x16x32_bf16 v[118:121], v[130:133], v[176:179], v[118:121]
	v_mfma_f32_16x16x32_bf16 v[110:113], v[138:141], v[176:179], v[110:113]
	v_mfma_f32_16x16x32_bf16 v[98:101], v[130:133], v[184:187], v[98:101]
	v_mfma_f32_16x16x32_bf16 v[90:93], v[138:141], v[184:187], v[90:93]
	v_mfma_f32_16x16x32_bf16 v[82:85], v[130:133], v[192:195], v[82:85]
	v_mfma_f32_16x16x32_bf16 v[74:77], v[138:141], v[192:195], v[74:77]
	v_mfma_f32_16x16x32_bf16 v[126:129], v[134:137], v[172:175], v[126:129]
	v_mfma_f32_16x16x32_bf16 v[122:125], v[142:145], v[172:175], v[122:125]
	v_mfma_f32_16x16x32_bf16 v[118:121], v[134:137], v[180:183], v[118:121]
	v_mfma_f32_16x16x32_bf16 v[110:113], v[142:145], v[180:183], v[110:113]
	v_mfma_f32_16x16x32_bf16 v[98:101], v[134:137], v[188:191], v[98:101]
	v_mfma_f32_16x16x32_bf16 v[90:93], v[142:145], v[188:191], v[90:93]
	v_mfma_f32_16x16x32_bf16 v[82:85], v[134:137], v[196:199], v[82:85]
	v_mfma_f32_16x16x32_bf16 v[74:77], v[142:145], v[196:199], v[74:77]
	s_barrier
	s_mov_b32 m0, s52
	v_lshl_add_u64 v[164:165], s[40:41], 0, v[156:157]
	ds_read_b128 v[200:203], v170
	ds_read_b128 v[204:207], v170 offset:1024
	ds_read_b128 v[208:211], v170 offset:2048
	ds_read_b128 v[212:215], v170 offset:3072
	global_load_lds_dwordx4 v[164:165], off
	v_lshl_add_u64 v[216:217], s[40:41], 0, v[152:153]
	s_mov_b32 m0, s53
	s_nop 0
	global_load_lds_dwordx4 v[216:217], off
	s_waitcnt vmcnt(10)
	s_barrier
	s_waitcnt lgkmcnt(0)
	s_waitcnt lgkmcnt(0)
	v_mfma_f32_16x16x32_bf16 v[114:117], v[200:203], v[146:149], v[114:117]
	v_mfma_f32_16x16x32_bf16 v[106:109], v[208:211], v[146:149], v[106:109]
	v_mfma_f32_16x16x32_bf16 v[102:105], v[200:203], v[176:179], v[102:105]
	v_mfma_f32_16x16x32_bf16 v[94:97], v[208:211], v[176:179], v[94:97]
	v_mfma_f32_16x16x32_bf16 v[86:89], v[200:203], v[184:187], v[86:89]
	v_mfma_f32_16x16x32_bf16 v[78:81], v[208:211], v[184:187], v[78:81]
	v_mfma_f32_16x16x32_bf16 v[70:73], v[200:203], v[192:195], v[70:73]
	v_mfma_f32_16x16x32_bf16 v[66:69], v[208:211], v[192:195], v[66:69]
	v_mfma_f32_16x16x32_bf16 v[114:117], v[204:207], v[172:175], v[114:117]
	v_mfma_f32_16x16x32_bf16 v[106:109], v[212:215], v[172:175], v[106:109]
	v_mfma_f32_16x16x32_bf16 v[102:105], v[204:207], v[180:183], v[102:105]
	v_mfma_f32_16x16x32_bf16 v[94:97], v[212:215], v[180:183], v[94:97]
	v_mfma_f32_16x16x32_bf16 v[86:89], v[204:207], v[188:191], v[86:89]
	v_mfma_f32_16x16x32_bf16 v[78:81], v[212:215], v[188:191], v[78:81]
	v_mfma_f32_16x16x32_bf16 v[70:73], v[204:207], v[196:199], v[70:73]
	v_mfma_f32_16x16x32_bf16 v[66:69], v[212:215], v[196:199], v[66:69]
	s_mov_b32 m0, s8
	v_lshl_add_u64 v[218:219], s[42:43], 0, v[158:159]
	s_barrier
	ds_read_b128 v[146:149], v169 offset:16384
	ds_read_b128 v[172:175], v169 offset:17408
	ds_read_b128 v[176:179], v169 offset:18432
	ds_read_b128 v[180:183], v169 offset:19456
	ds_read_b128 v[184:187], v169 offset:20480
	ds_read_b128 v[188:191], v169 offset:21504
	ds_read_b128 v[192:195], v169 offset:22528
	ds_read_b128 v[196:199], v169 offset:23552
	global_load_lds_dwordx4 v[218:219], off
	v_lshl_add_u64 v[220:221], s[42:43], 0, v[154:155]
	s_mov_b32 m0, s9
	s_nop 0
	global_load_lds_dwordx4 v[220:221], off
	s_waitcnt vmcnt(10)
	s_barrier
	s_waitcnt lgkmcnt(0)
	s_waitcnt lgkmcnt(0)
	v_mfma_f32_16x16x32_bf16 v[62:65], v[130:133], v[146:149], v[62:65]
	v_mfma_f32_16x16x32_bf16 v[58:61], v[138:141], v[146:149], v[58:61]
	v_mfma_f32_16x16x32_bf16 v[50:53], v[130:133], v[176:179], v[50:53]
	v_mfma_f32_16x16x32_bf16 v[42:45], v[138:141], v[176:179], v[42:45]
	v_mfma_f32_16x16x32_bf16 v[34:37], v[130:133], v[184:187], v[34:37]
	v_mfma_f32_16x16x32_bf16 v[26:29], v[138:141], v[184:187], v[26:29]
	v_mfma_f32_16x16x32_bf16 v[18:21], v[130:133], v[192:195], v[18:21]
	v_mfma_f32_16x16x32_bf16 v[10:13], v[138:141], v[192:195], v[10:13]
	v_mfma_f32_16x16x32_bf16 v[62:65], v[134:137], v[172:175], v[62:65]
	v_mfma_f32_16x16x32_bf16 v[58:61], v[142:145], v[172:175], v[58:61]
	v_mfma_f32_16x16x32_bf16 v[50:53], v[134:137], v[180:183], v[50:53]
	v_mfma_f32_16x16x32_bf16 v[42:45], v[142:145], v[180:183], v[42:45]
	v_mfma_f32_16x16x32_bf16 v[34:37], v[134:137], v[188:191], v[34:37]
	v_mfma_f32_16x16x32_bf16 v[26:29], v[142:145], v[188:191], v[26:29]
	v_mfma_f32_16x16x32_bf16 v[18:21], v[134:137], v[196:199], v[18:21]
	v_mfma_f32_16x16x32_bf16 v[10:13], v[142:145], v[196:199], v[10:13]
	s_barrier
	s_add_u32 s0, s40, 0x40000
	s_addc_u32 s1, s41, 0
	s_mov_b32 m0, s54
	v_lshl_add_u64 v[130:131], s[0:1], 0, v[156:157]
	global_load_lds_dwordx4 v[130:131], off
	v_lshl_add_u64 v[130:131], s[0:1], 0, v[152:153]
	s_add_i32 m0, s54, 0x2000
	s_nop 0
	global_load_lds_dwordx4 v[130:131], off
	s_waitcnt vmcnt(10)
	s_barrier
	v_mfma_f32_16x16x32_bf16 v[54:57], v[200:203], v[146:149], v[54:57]
	v_mfma_f32_16x16x32_bf16 v[46:49], v[208:211], v[146:149], v[46:49]
	v_mfma_f32_16x16x32_bf16 v[38:41], v[200:203], v[176:179], v[38:41]
	v_mfma_f32_16x16x32_bf16 v[30:33], v[208:211], v[176:179], v[30:33]
	v_mfma_f32_16x16x32_bf16 v[22:25], v[200:203], v[184:187], v[22:25]
	v_mfma_f32_16x16x32_bf16 v[14:17], v[208:211], v[184:187], v[14:17]
	v_mfma_f32_16x16x32_bf16 v[6:9], v[200:203], v[192:195], v[6:9]
	v_mfma_f32_16x16x32_bf16 v[2:5], v[208:211], v[192:195], v[2:5]
	v_mfma_f32_16x16x32_bf16 v[54:57], v[204:207], v[172:175], v[54:57]
	v_mfma_f32_16x16x32_bf16 v[46:49], v[212:215], v[172:175], v[46:49]
	v_mfma_f32_16x16x32_bf16 v[38:41], v[204:207], v[180:183], v[38:41]
	v_mfma_f32_16x16x32_bf16 v[30:33], v[212:215], v[180:183], v[30:33]
	v_mfma_f32_16x16x32_bf16 v[22:25], v[204:207], v[188:191], v[22:25]
	v_mfma_f32_16x16x32_bf16 v[14:17], v[212:215], v[188:191], v[14:17]
	v_mfma_f32_16x16x32_bf16 v[6:9], v[204:207], v[196:199], v[6:9]
	v_mfma_f32_16x16x32_bf16 v[2:5], v[212:215], v[196:199], v[2:5]
	s_add_i32 s67, 0, 0x18000
	v_add_u32_e32 v142, s67, v167
	s_barrier
	ds_read_b128 v[130:133], v142
	ds_read_b128 v[134:137], v142 offset:1024
	ds_read_b128 v[138:141], v142 offset:2048
	ds_read_b128 v[142:145], v142 offset:3072
	s_add_u32 s0, s42, 0x40000
	s_addc_u32 s1, s43, 0
	s_mov_b32 m0, s10
	v_lshl_add_u64 v[200:201], s[0:1], 0, v[158:159]
	ds_read_b128 v[146:149], v169 offset:32768
	ds_read_b128 v[172:175], v169 offset:33792
	ds_read_b128 v[176:179], v169 offset:34816
	ds_read_b128 v[180:183], v169 offset:35840
	ds_read_b128 v[184:187], v169 offset:36864
	ds_read_b128 v[188:191], v169 offset:37888
	ds_read_b128 v[192:195], v169 offset:38912
	ds_read_b128 v[196:199], v169 offset:39936
	global_load_lds_dwordx4 v[200:201], off
	v_lshl_add_u64 v[200:201], s[0:1], 0, v[154:155]
	s_mov_b32 m0, s11
	s_nop 0
	global_load_lds_dwordx4 v[200:201], off
	s_waitcnt lgkmcnt(8)
	s_waitcnt vmcnt(10)
	s_barrier
	s_waitcnt lgkmcnt(0)
	s_waitcnt lgkmcnt(0)
	v_mfma_f32_16x16x32_bf16 v[126:129], v[130:133], v[146:149], v[126:129]
	v_mfma_f32_16x16x32_bf16 v[122:125], v[138:141], v[146:149], v[122:125]
	v_mfma_f32_16x16x32_bf16 v[118:121], v[130:133], v[176:179], v[118:121]
	v_mfma_f32_16x16x32_bf16 v[110:113], v[138:141], v[176:179], v[110:113]
	v_mfma_f32_16x16x32_bf16 v[98:101], v[130:133], v[184:187], v[98:101]
	v_mfma_f32_16x16x32_bf16 v[90:93], v[138:141], v[184:187], v[90:93]
	v_mfma_f32_16x16x32_bf16 v[82:85], v[130:133], v[192:195], v[82:85]
	v_mfma_f32_16x16x32_bf16 v[74:77], v[138:141], v[192:195], v[74:77]
	v_mfma_f32_16x16x32_bf16 v[126:129], v[134:137], v[172:175], v[126:129]
	v_mfma_f32_16x16x32_bf16 v[122:125], v[142:145], v[172:175], v[122:125]
	v_mfma_f32_16x16x32_bf16 v[118:121], v[134:137], v[180:183], v[118:121]
	v_mfma_f32_16x16x32_bf16 v[110:113], v[142:145], v[180:183], v[110:113]
	v_mfma_f32_16x16x32_bf16 v[98:101], v[134:137], v[188:191], v[98:101]
	v_mfma_f32_16x16x32_bf16 v[90:93], v[142:145], v[188:191], v[90:93]
	v_mfma_f32_16x16x32_bf16 v[82:85], v[134:137], v[196:199], v[82:85]
	v_mfma_f32_16x16x32_bf16 v[74:77], v[142:145], v[196:199], v[74:77]
	s_barrier
	s_add_i32 s42, 0, 0x1c000
	s_add_i32 s0, s67, s7
	v_add_u32_e32 v171, s42, v167
	v_lshl_add_u64 v[164:165], v[164:165], 0, s[28:29]
	s_mov_b32 m0, s0
	ds_read_b128 v[200:203], v171
	ds_read_b128 v[204:207], v171 offset:1024
	ds_read_b128 v[208:211], v171 offset:2048
	ds_read_b128 v[212:215], v171 offset:3072
	global_load_lds_dwordx4 v[164:165], off
	v_lshl_add_u64 v[164:165], v[216:217], 0, s[28:29]
	s_add_i32 m0, s0, 0x2000
	s_nop 0
	global_load_lds_dwordx4 v[164:165], off
	s_waitcnt vmcnt(10)
	s_barrier
	s_waitcnt lgkmcnt(0)
	s_waitcnt lgkmcnt(0)
	v_mfma_f32_16x16x32_bf16 v[114:117], v[200:203], v[146:149], v[114:117]
	v_mfma_f32_16x16x32_bf16 v[106:109], v[208:211], v[146:149], v[106:109]
	v_mfma_f32_16x16x32_bf16 v[102:105], v[200:203], v[176:179], v[102:105]
	v_mfma_f32_16x16x32_bf16 v[94:97], v[208:211], v[176:179], v[94:97]
	v_mfma_f32_16x16x32_bf16 v[86:89], v[200:203], v[184:187], v[86:89]
	v_mfma_f32_16x16x32_bf16 v[78:81], v[208:211], v[184:187], v[78:81]
	v_mfma_f32_16x16x32_bf16 v[70:73], v[200:203], v[192:195], v[70:73]
	v_mfma_f32_16x16x32_bf16 v[66:69], v[208:211], v[192:195], v[66:69]
	v_mfma_f32_16x16x32_bf16 v[114:117], v[204:207], v[172:175], v[114:117]
	v_mfma_f32_16x16x32_bf16 v[106:109], v[212:215], v[172:175], v[106:109]
	v_mfma_f32_16x16x32_bf16 v[102:105], v[204:207], v[180:183], v[102:105]
	v_mfma_f32_16x16x32_bf16 v[94:97], v[212:215], v[180:183], v[94:97]
	v_mfma_f32_16x16x32_bf16 v[86:89], v[204:207], v[188:191], v[86:89]
	v_mfma_f32_16x16x32_bf16 v[78:81], v[212:215], v[188:191], v[78:81]
	v_mfma_f32_16x16x32_bf16 v[70:73], v[204:207], v[196:199], v[70:73]
	v_mfma_f32_16x16x32_bf16 v[66:69], v[212:215], v[196:199], v[66:69]
	s_mov_b32 m0, s48
	v_lshl_add_u64 v[164:165], v[218:219], 0, s[28:29]
	s_barrier
	ds_read_b128 v[146:149], v169 offset:49152
	ds_read_b128 v[172:175], v169 offset:50176
	ds_read_b128 v[176:179], v169 offset:51200
	ds_read_b128 v[180:183], v169 offset:52224
	ds_read_b128 v[184:187], v169 offset:53248
	ds_read_b128 v[188:191], v169 offset:54272
	ds_read_b128 v[192:195], v169 offset:55296
	ds_read_b128 v[196:199], v169 offset:56320
	global_load_lds_dwordx4 v[164:165], off
	v_lshl_add_u64 v[164:165], v[220:221], 0, s[28:29]
	s_mov_b32 m0, s49
	s_nop 0
	global_load_lds_dwordx4 v[164:165], off
	s_waitcnt vmcnt(10)
	s_barrier
	s_waitcnt lgkmcnt(0)
	s_waitcnt lgkmcnt(0)
	v_mfma_f32_16x16x32_bf16 v[62:65], v[130:133], v[146:149], v[62:65]
	v_mfma_f32_16x16x32_bf16 v[58:61], v[138:141], v[146:149], v[58:61]
	v_mfma_f32_16x16x32_bf16 v[50:53], v[130:133], v[176:179], v[50:53]
	v_mfma_f32_16x16x32_bf16 v[42:45], v[138:141], v[176:179], v[42:45]
	v_mfma_f32_16x16x32_bf16 v[34:37], v[130:133], v[184:187], v[34:37]
	v_mfma_f32_16x16x32_bf16 v[26:29], v[138:141], v[184:187], v[26:29]
	v_mfma_f32_16x16x32_bf16 v[18:21], v[130:133], v[192:195], v[18:21]
	v_mfma_f32_16x16x32_bf16 v[10:13], v[138:141], v[192:195], v[10:13]
	v_mfma_f32_16x16x32_bf16 v[62:65], v[134:137], v[172:175], v[62:65]
	v_mfma_f32_16x16x32_bf16 v[58:61], v[142:145], v[172:175], v[58:61]
	v_mfma_f32_16x16x32_bf16 v[50:53], v[134:137], v[180:183], v[50:53]
	v_mfma_f32_16x16x32_bf16 v[42:45], v[142:145], v[180:183], v[42:45]
	v_mfma_f32_16x16x32_bf16 v[34:37], v[134:137], v[188:191], v[34:37]
	v_mfma_f32_16x16x32_bf16 v[26:29], v[142:145], v[188:191], v[26:29]
	v_mfma_f32_16x16x32_bf16 v[18:21], v[134:137], v[196:199], v[18:21]
	v_mfma_f32_16x16x32_bf16 v[10:13], v[142:145], v[196:199], v[10:13]
	s_barrier
	s_add_u32 s0, s40, 0x40080
	s_addc_u32 s1, s41, 0
	s_add_i32 s40, s42, s7
	v_lshl_add_u64 v[130:131], s[0:1], 0, v[156:157]
	s_mov_b32 m0, s40
	s_nop 0
	global_load_lds_dwordx4 v[130:131], off
	v_lshl_add_u64 v[130:131], s[0:1], 0, v[152:153]
	s_add_i32 m0, s40, 0x2000
	s_nop 0
	global_load_lds_dwordx4 v[130:131], off
	s_waitcnt vmcnt(10)
	s_barrier
	v_mfma_f32_16x16x32_bf16 v[54:57], v[200:203], v[146:149], v[54:57]
	v_mfma_f32_16x16x32_bf16 v[46:49], v[208:211], v[146:149], v[46:49]
	v_mfma_f32_16x16x32_bf16 v[38:41], v[200:203], v[176:179], v[38:41]
	v_mfma_f32_16x16x32_bf16 v[30:33], v[208:211], v[176:179], v[30:33]
	v_mfma_f32_16x16x32_bf16 v[22:25], v[200:203], v[184:187], v[22:25]
	v_mfma_f32_16x16x32_bf16 v[14:17], v[208:211], v[184:187], v[14:17]
	v_mfma_f32_16x16x32_bf16 v[6:9], v[200:203], v[192:195], v[6:9]
	v_mfma_f32_16x16x32_bf16 v[2:5], v[208:211], v[192:195], v[2:5]
	v_mfma_f32_16x16x32_bf16 v[54:57], v[204:207], v[172:175], v[54:57]
	v_mfma_f32_16x16x32_bf16 v[46:49], v[212:215], v[172:175], v[46:49]
	v_mfma_f32_16x16x32_bf16 v[38:41], v[204:207], v[180:183], v[38:41]
	v_mfma_f32_16x16x32_bf16 v[30:33], v[212:215], v[180:183], v[30:33]
	v_mfma_f32_16x16x32_bf16 v[22:25], v[204:207], v[188:191], v[22:25]
	v_mfma_f32_16x16x32_bf16 v[14:17], v[212:215], v[188:191], v[14:17]
	v_mfma_f32_16x16x32_bf16 v[6:9], v[204:207], v[196:199], v[6:9]
	v_mfma_f32_16x16x32_bf16 v[2:5], v[212:215], v[196:199], v[2:5]
	s_add_i32 s66, s66, 2
	s_add_u32 s64, s64, 0x100
	s_addc_u32 s65, s65, 0
	s_add_u32 s38, s38, 0x100
	s_addc_u32 s39, s39, 0
	s_cmp_gt_u32 s66, 13
	s_barrier
	s_cbranch_scc0 .LBB0_1786
	s_lshl_b32 s0, s58, 8
	v_mov_b32_e32 v130, v151
	v_mov_b32_e32 v131, v166
	s_or_b32 s0, s0, s45
	s_mov_b32 s58, s57
	v_lshl_add_u32 v164, v131, 3, s0
	s_lshl_b32 s0, s59, 8
	s_add_i32 s0, s0, s44
	v_add_u32_e32 v171, s0, v130
	v_mov_b32_e32 v130, v171
	v_ashrrev_i32_e32 v165, 31, v164
	v_ashrrev_i32_e32 v131, 31, v130
	v_lshlrev_b64 v[130:131], 10, v[130:131]
	v_lshl_add_u64 v[130:131], v[130:131], 0, v[164:165]
	v_lshlrev_b64 v[184:185], 1, v[130:131]
	v_lshl_add_u64 v[130:131], s[14:15], 0, v[184:185]
	flat_load_dwordx4 v[172:175], v[130:131]
	flat_load_dwordx4 v[176:179], v[130:131] offset:256
	v_add_co_u32_e32 v132, vcc, s47, v130
	s_mov_b32 s59, s56
	s_nop 0
	v_addc_co_u32_e32 v133, vcc, 0, v131, vcc
	flat_load_dwordx4 v[180:183], v[132:133]
	flat_load_dwordx4 v[146:149], v[132:133] offset:256
	v_add_co_u32_e32 v132, vcc, s31, v130
	s_waitcnt vmcnt(0) lgkmcnt(0)
	v_lshlrev_b32_e32 v186, 16, v172
	v_addc_co_u32_e32 v133, vcc, 0, v131, vcc
	flat_load_dwordx4 v[142:145], v[132:133]
	flat_load_dwordx4 v[138:141], v[132:133] offset:256
	v_add_co_u32_e32 v130, vcc, s46, v130
	v_and_b32_e32 v187, 0xffff0000, v172
	s_nop 0
	v_addc_co_u32_e32 v131, vcc, 0, v131, vcc
	flat_load_dwordx4 v[134:137], v[130:131]
	s_nop 0
	flat_load_dwordx4 v[130:133], v[130:131] offset:256
	v_lshlrev_b32_e32 v172, 16, v173
	v_and_b32_e32 v173, 0xffff0000, v173
	v_lshlrev_b32_e32 v188, 16, v174
	v_and_b32_e32 v189, 0xffff0000, v174
	v_lshlrev_b32_e32 v174, 16, v175
	v_and_b32_e32 v175, 0xffff0000, v175
	v_pk_fma_f32 v[128:129], v[172:173], s[30:31], v[128:129] op_sel_hi:[1,0,1]
	v_pk_fma_f32 v[126:127], v[186:187], s[30:31], v[126:127] op_sel_hi:[1,0,1]
	v_pk_fma_f32 v[172:173], v[174:175], s[30:31], v[124:125] op_sel_hi:[1,0,1]
	v_pk_fma_f32 v[122:123], v[188:189], s[30:31], v[122:123] op_sel_hi:[1,0,1]
	v_cvt_pk_bf16_f32 v124, v126, v127
	v_cvt_pk_bf16_f32 v125, v128, v129
	v_cvt_pk_bf16_f32 v126, v122, v123
	v_cvt_pk_bf16_f32 v127, v172, v173
	v_lshl_add_u64 v[122:123], s[20:21], 0, v[184:185]
	flat_store_dwordx4 v[122:123], v[124:127]
	v_lshlrev_b32_e32 v128, 16, v178
	v_and_b32_e32 v129, 0xffff0000, v178
	v_lshlrev_b32_e32 v124, 16, v176
	v_and_b32_e32 v125, 0xffff0000, v176
	v_lshlrev_b32_e32 v126, 16, v177
	v_and_b32_e32 v127, 0xffff0000, v177
	v_lshlrev_b32_e32 v172, 16, v179
	v_and_b32_e32 v173, 0xffff0000, v179
	v_pk_fma_f32 v[116:117], v[126:127], s[30:31], v[116:117] op_sel_hi:[1,0,1]
	v_pk_fma_f32 v[114:115], v[124:125], s[30:31], v[114:115] op_sel_hi:[1,0,1]
	v_pk_fma_f32 v[124:125], v[172:173], s[30:31], v[108:109] op_sel_hi:[1,0,1]
	v_pk_fma_f32 v[108:109], v[128:129], s[30:31], v[106:107] op_sel_hi:[1,0,1]
	v_cvt_pk_bf16_f32 v106, v114, v115
	v_cvt_pk_bf16_f32 v107, v116, v117
	v_cvt_pk_bf16_f32 v108, v108, v109
	v_cvt_pk_bf16_f32 v109, v124, v125
	flat_store_dwordx4 v[122:123], v[106:109] offset:256
	v_lshlrev_b32_e32 v114, 16, v182
	v_and_b32_e32 v115, 0xffff0000, v182
	v_lshlrev_b32_e32 v106, 16, v180
	v_and_b32_e32 v107, 0xffff0000, v180
	v_lshlrev_b32_e32 v108, 16, v181
	v_and_b32_e32 v109, 0xffff0000, v181
	v_lshlrev_b32_e32 v116, 16, v183
	v_and_b32_e32 v117, 0xffff0000, v183
	v_pk_fma_f32 v[108:109], v[108:109], s[30:31], v[120:121] op_sel_hi:[1,0,1]
	v_pk_fma_f32 v[106:107], v[106:107], s[30:31], v[118:119] op_sel_hi:[1,0,1]
	v_pk_fma_f32 v[110:111], v[114:115], s[30:31], v[110:111] op_sel_hi:[1,0,1]
	v_pk_fma_f32 v[112:113], v[116:117], s[30:31], v[112:113] op_sel_hi:[1,0,1]
	v_cvt_pk_bf16_f32 v106, v106, v107
	v_cvt_pk_bf16_f32 v107, v108, v109
	v_cvt_pk_bf16_f32 v108, v110, v111
	v_add_co_u32_e32 v110, vcc, s47, v122
	v_cvt_pk_bf16_f32 v109, v112, v113
	s_nop 0
	v_addc_co_u32_e32 v111, vcc, 0, v123, vcc
	flat_store_dwordx4 v[110:111], v[106:109]
	v_lshlrev_b32_e32 v112, 16, v148
	v_and_b32_e32 v113, 0xffff0000, v148
	v_lshlrev_b32_e32 v106, 16, v146
	v_and_b32_e32 v107, 0xffff0000, v146
	v_lshlrev_b32_e32 v108, 16, v147
	v_and_b32_e32 v109, 0xffff0000, v147
	v_lshlrev_b32_e32 v114, 16, v149
	v_and_b32_e32 v115, 0xffff0000, v149
	v_pk_fma_f32 v[104:105], v[108:109], s[30:31], v[104:105] op_sel_hi:[1,0,1]
	v_pk_fma_f32 v[102:103], v[106:107], s[30:31], v[102:103] op_sel_hi:[1,0,1]
	v_pk_fma_f32 v[106:107], v[114:115], s[30:31], v[96:97] op_sel_hi:[1,0,1]
	v_pk_fma_f32 v[96:97], v[112:113], s[30:31], v[94:95] op_sel_hi:[1,0,1]
	v_cvt_pk_bf16_f32 v94, v102, v103
	v_cvt_pk_bf16_f32 v95, v104, v105
	v_cvt_pk_bf16_f32 v96, v96, v97
	v_cvt_pk_bf16_f32 v97, v106, v107
	flat_store_dwordx4 v[110:111], v[94:97] offset:256
	s_waitcnt vmcnt(0) lgkmcnt(0)
	v_lshlrev_b32_e32 v102, 16, v144
	v_lshlrev_b32_e32 v94, 16, v142
	v_and_b32_e32 v95, 0xffff0000, v142
	v_lshlrev_b32_e32 v96, 16, v143
	v_and_b32_e32 v97, 0xffff0000, v143
	v_and_b32_e32 v103, 0xffff0000, v144
	v_lshlrev_b32_e32 v104, 16, v145
	v_and_b32_e32 v105, 0xffff0000, v145
	v_pk_fma_f32 v[94:95], v[94:95], s[30:31], v[98:99] op_sel_hi:[1,0,1]
	v_pk_fma_f32 v[96:97], v[96:97], s[30:31], v[100:101] op_sel_hi:[1,0,1]
	v_pk_fma_f32 v[98:99], v[104:105], s[30:31], v[92:93] op_sel_hi:[1,0,1]
	v_pk_fma_f32 v[92:93], v[102:103], s[30:31], v[90:91] op_sel_hi:[1,0,1]
	v_cvt_pk_bf16_f32 v90, v94, v95
	v_add_co_u32_e32 v94, vcc, s31, v122
	v_cvt_pk_bf16_f32 v91, v96, v97
	v_cvt_pk_bf16_f32 v92, v92, v93
	v_cvt_pk_bf16_f32 v93, v98, v99
	v_addc_co_u32_e32 v95, vcc, 0, v123, vcc
	flat_store_dwordx4 v[94:95], v[90:93]
	v_lshlrev_b32_e32 v96, 16, v140
	v_and_b32_e32 v97, 0xffff0000, v140
	v_lshlrev_b32_e32 v90, 16, v138
	v_and_b32_e32 v91, 0xffff0000, v138
	v_lshlrev_b32_e32 v92, 16, v139
	v_and_b32_e32 v93, 0xffff0000, v139
	v_lshlrev_b32_e32 v98, 16, v141
	v_and_b32_e32 v99, 0xffff0000, v141
	v_pk_fma_f32 v[88:89], v[92:93], s[30:31], v[88:89] op_sel_hi:[1,0,1]
	v_pk_fma_f32 v[86:87], v[90:91], s[30:31], v[86:87] op_sel_hi:[1,0,1]
	v_pk_fma_f32 v[90:91], v[98:99], s[30:31], v[80:81] op_sel_hi:[1,0,1]
	v_pk_fma_f32 v[80:81], v[96:97], s[30:31], v[78:79] op_sel_hi:[1,0,1]
	v_cvt_pk_bf16_f32 v78, v86, v87
	v_cvt_pk_bf16_f32 v79, v88, v89
	v_cvt_pk_bf16_f32 v80, v80, v81
	v_cvt_pk_bf16_f32 v81, v90, v91
	flat_store_dwordx4 v[94:95], v[78:81] offset:256
	v_lshlrev_b32_e32 v86, 16, v136
	v_and_b32_e32 v87, 0xffff0000, v136
	v_lshlrev_b32_e32 v78, 16, v134
	v_and_b32_e32 v79, 0xffff0000, v134
	v_lshlrev_b32_e32 v80, 16, v135
	v_and_b32_e32 v81, 0xffff0000, v135
	v_lshlrev_b32_e32 v88, 16, v137
	v_and_b32_e32 v89, 0xffff0000, v137
	v_pk_fma_f32 v[78:79], v[78:79], s[30:31], v[82:83] op_sel_hi:[1,0,1]
	v_pk_fma_f32 v[80:81], v[80:81], s[30:31], v[84:85] op_sel_hi:[1,0,1]
	v_pk_fma_f32 v[82:83], v[88:89], s[30:31], v[76:77] op_sel_hi:[1,0,1]
	v_pk_fma_f32 v[76:77], v[86:87], s[30:31], v[74:75] op_sel_hi:[1,0,1]
	v_cvt_pk_bf16_f32 v74, v78, v79
	v_add_co_u32_e32 v78, vcc, s46, v122
	v_cvt_pk_bf16_f32 v75, v80, v81
	v_cvt_pk_bf16_f32 v76, v76, v77
	v_cvt_pk_bf16_f32 v77, v82, v83
	v_addc_co_u32_e32 v79, vcc, 0, v123, vcc
	flat_store_dwordx4 v[78:79], v[74:77]
	v_lshlrev_b32_e32 v80, 16, v132
	v_and_b32_e32 v81, 0xffff0000, v132
	v_lshlrev_b32_e32 v74, 16, v130
	v_and_b32_e32 v75, 0xffff0000, v130
	v_lshlrev_b32_e32 v76, 16, v131
	v_and_b32_e32 v77, 0xffff0000, v131
	v_lshlrev_b32_e32 v82, 16, v133
	v_and_b32_e32 v83, 0xffff0000, v133
	v_pk_fma_f32 v[72:73], v[76:77], s[30:31], v[72:73] op_sel_hi:[1,0,1]
	v_pk_fma_f32 v[70:71], v[74:75], s[30:31], v[70:71] op_sel_hi:[1,0,1]
	v_pk_fma_f32 v[74:75], v[82:83], s[30:31], v[68:69] op_sel_hi:[1,0,1]
	v_pk_fma_f32 v[68:69], v[80:81], s[30:31], v[66:67] op_sel_hi:[1,0,1]
	v_cvt_pk_bf16_f32 v66, v70, v71
	v_cvt_pk_bf16_f32 v67, v72, v73
	v_cvt_pk_bf16_f32 v68, v68, v69
	v_cvt_pk_bf16_f32 v69, v74, v75
	flat_store_dwordx4 v[78:79], v[66:69] offset:256
	s_nop 1
	v_add_u32_e32 v66, 0x80, v171
	s_nop 0
	v_ashrrev_i32_e32 v67, 31, v66
	v_lshlrev_b64 v[66:67], 10, v[66:67]
	v_lshl_add_u64 v[66:67], v[66:67], 0, v[164:165]
	v_lshlrev_b64 v[98:99], 1, v[66:67]
	v_lshl_add_u64 v[90:91], s[14:15], 0, v[98:99]
	flat_load_dwordx4 v[66:69], v[90:91]
	flat_load_dwordx4 v[70:73], v[90:91] offset:256
	v_add_co_u32_e32 v78, vcc, s47, v90
	s_waitcnt vmcnt(0) lgkmcnt(0)
	v_lshlrev_b32_e32 v100, 16, v66
	v_addc_co_u32_e32 v79, vcc, 0, v91, vcc
	flat_load_dwordx4 v[74:77], v[78:79]
	s_nop 0
	flat_load_dwordx4 v[78:81], v[78:79] offset:256
	v_add_co_u32_e32 v86, vcc, s31, v90
	v_and_b32_e32 v101, 0xffff0000, v66
	s_nop 0
	v_addc_co_u32_e32 v87, vcc, 0, v91, vcc
	flat_load_dwordx4 v[82:85], v[86:87]
	s_nop 0
	flat_load_dwordx4 v[86:89], v[86:87] offset:256
	v_add_co_u32_e32 v94, vcc, s46, v90
	v_lshlrev_b32_e32 v66, 16, v67
	s_nop 0
	v_addc_co_u32_e32 v95, vcc, 0, v91, vcc
	flat_load_dwordx4 v[90:93], v[94:95]
	s_nop 0
	flat_load_dwordx4 v[94:97], v[94:95] offset:256
	v_and_b32_e32 v67, 0xffff0000, v67
	v_lshlrev_b32_e32 v102, 16, v68
	v_and_b32_e32 v103, 0xffff0000, v68
	v_lshlrev_b32_e32 v68, 16, v69
	v_and_b32_e32 v69, 0xffff0000, v69
	v_pk_fma_f32 v[64:65], v[66:67], s[30:31], v[64:65] op_sel_hi:[1,0,1]
	v_pk_fma_f32 v[62:63], v[100:101], s[30:31], v[62:63] op_sel_hi:[1,0,1]
	v_pk_fma_f32 v[66:67], v[68:69], s[30:31], v[60:61] op_sel_hi:[1,0,1]
	v_pk_fma_f32 v[60:61], v[102:103], s[30:31], v[58:59] op_sel_hi:[1,0,1]
	v_cvt_pk_bf16_f32 v58, v62, v63
	v_cvt_pk_bf16_f32 v59, v64, v65
	v_cvt_pk_bf16_f32 v60, v60, v61
	v_cvt_pk_bf16_f32 v61, v66, v67
	v_lshl_add_u64 v[62:63], s[20:21], 0, v[98:99]
	flat_store_dwordx4 v[62:63], v[58:61]
	v_lshlrev_b32_e32 v64, 16, v72
	v_and_b32_e32 v65, 0xffff0000, v72
	v_lshlrev_b32_e32 v58, 16, v70
	v_and_b32_e32 v59, 0xffff0000, v70
	v_lshlrev_b32_e32 v60, 16, v71
	v_and_b32_e32 v61, 0xffff0000, v71
	v_lshlrev_b32_e32 v66, 16, v73
	v_and_b32_e32 v67, 0xffff0000, v73
	v_pk_fma_f32 v[56:57], v[60:61], s[30:31], v[56:57] op_sel_hi:[1,0,1]
	v_pk_fma_f32 v[54:55], v[58:59], s[30:31], v[54:55] op_sel_hi:[1,0,1]
	v_pk_fma_f32 v[58:59], v[66:67], s[30:31], v[48:49] op_sel_hi:[1,0,1]
	v_pk_fma_f32 v[48:49], v[64:65], s[30:31], v[46:47] op_sel_hi:[1,0,1]
	v_cvt_pk_bf16_f32 v46, v54, v55
	v_cvt_pk_bf16_f32 v47, v56, v57
	v_cvt_pk_bf16_f32 v48, v48, v49
	v_cvt_pk_bf16_f32 v49, v58, v59
	flat_store_dwordx4 v[62:63], v[46:49] offset:256
	s_waitcnt vmcnt(0) lgkmcnt(0)
	v_lshlrev_b32_e32 v54, 16, v76
	v_lshlrev_b32_e32 v46, 16, v74
	v_and_b32_e32 v47, 0xffff0000, v74
	v_lshlrev_b32_e32 v48, 16, v75
	v_and_b32_e32 v49, 0xffff0000, v75
	v_and_b32_e32 v55, 0xffff0000, v76
	v_lshlrev_b32_e32 v56, 16, v77
	v_and_b32_e32 v57, 0xffff0000, v77
	v_pk_fma_f32 v[46:47], v[46:47], s[30:31], v[50:51] op_sel_hi:[1,0,1]
	v_pk_fma_f32 v[48:49], v[48:49], s[30:31], v[52:53] op_sel_hi:[1,0,1]
	v_pk_fma_f32 v[50:51], v[56:57], s[30:31], v[44:45] op_sel_hi:[1,0,1]
	v_pk_fma_f32 v[44:45], v[54:55], s[30:31], v[42:43] op_sel_hi:[1,0,1]
	v_cvt_pk_bf16_f32 v42, v46, v47
	v_add_co_u32_e32 v46, vcc, s47, v62
	v_cvt_pk_bf16_f32 v43, v48, v49
	v_cvt_pk_bf16_f32 v44, v44, v45
	v_cvt_pk_bf16_f32 v45, v50, v51
	v_addc_co_u32_e32 v47, vcc, 0, v63, vcc
	flat_store_dwordx4 v[46:47], v[42:45]
	v_lshlrev_b32_e32 v48, 16, v80
	v_and_b32_e32 v49, 0xffff0000, v80
	v_lshlrev_b32_e32 v42, 16, v78
	v_and_b32_e32 v43, 0xffff0000, v78
	v_lshlrev_b32_e32 v44, 16, v79
	v_and_b32_e32 v45, 0xffff0000, v79
	v_lshlrev_b32_e32 v50, 16, v81
	v_and_b32_e32 v51, 0xffff0000, v81
	v_pk_fma_f32 v[40:41], v[44:45], s[30:31], v[40:41] op_sel_hi:[1,0,1]
	v_pk_fma_f32 v[38:39], v[42:43], s[30:31], v[38:39] op_sel_hi:[1,0,1]
	v_pk_fma_f32 v[42:43], v[50:51], s[30:31], v[32:33] op_sel_hi:[1,0,1]
	v_pk_fma_f32 v[32:33], v[48:49], s[30:31], v[30:31] op_sel_hi:[1,0,1]
	v_cvt_pk_bf16_f32 v30, v38, v39
	v_cvt_pk_bf16_f32 v31, v40, v41
	v_cvt_pk_bf16_f32 v32, v32, v33
	v_cvt_pk_bf16_f32 v33, v42, v43
	flat_store_dwordx4 v[46:47], v[30:33] offset:256
	v_lshlrev_b32_e32 v38, 16, v84
	v_and_b32_e32 v39, 0xffff0000, v84
	v_lshlrev_b32_e32 v30, 16, v82
	v_and_b32_e32 v31, 0xffff0000, v82
	v_lshlrev_b32_e32 v32, 16, v83
	v_and_b32_e32 v33, 0xffff0000, v83
	v_lshlrev_b32_e32 v40, 16, v85
	v_and_b32_e32 v41, 0xffff0000, v85
	v_pk_fma_f32 v[30:31], v[30:31], s[30:31], v[34:35] op_sel_hi:[1,0,1]
	v_pk_fma_f32 v[32:33], v[32:33], s[30:31], v[36:37] op_sel_hi:[1,0,1]
	v_pk_fma_f32 v[34:35], v[40:41], s[30:31], v[28:29] op_sel_hi:[1,0,1]
	v_pk_fma_f32 v[28:29], v[38:39], s[30:31], v[26:27] op_sel_hi:[1,0,1]
	v_cvt_pk_bf16_f32 v26, v30, v31
	v_add_co_u32_e32 v30, vcc, s31, v62
	v_cvt_pk_bf16_f32 v27, v32, v33
	v_cvt_pk_bf16_f32 v28, v28, v29
	v_cvt_pk_bf16_f32 v29, v34, v35
	v_addc_co_u32_e32 v31, vcc, 0, v63, vcc
	flat_store_dwordx4 v[30:31], v[26:29]
	v_lshlrev_b32_e32 v32, 16, v88
	v_and_b32_e32 v33, 0xffff0000, v88
	v_lshlrev_b32_e32 v26, 16, v86
	v_and_b32_e32 v27, 0xffff0000, v86
	v_lshlrev_b32_e32 v28, 16, v87
	v_and_b32_e32 v29, 0xffff0000, v87
	v_lshlrev_b32_e32 v34, 16, v89
	v_and_b32_e32 v35, 0xffff0000, v89
	v_pk_fma_f32 v[24:25], v[28:29], s[30:31], v[24:25] op_sel_hi:[1,0,1]
	v_pk_fma_f32 v[22:23], v[26:27], s[30:31], v[22:23] op_sel_hi:[1,0,1]
	v_pk_fma_f32 v[26:27], v[34:35], s[30:31], v[16:17] op_sel_hi:[1,0,1]
	v_pk_fma_f32 v[16:17], v[32:33], s[30:31], v[14:15] op_sel_hi:[1,0,1]
	v_cvt_pk_bf16_f32 v14, v22, v23
	v_cvt_pk_bf16_f32 v15, v24, v25
	v_cvt_pk_bf16_f32 v16, v16, v17
	v_cvt_pk_bf16_f32 v17, v26, v27
	flat_store_dwordx4 v[30:31], v[14:17] offset:256
	v_lshlrev_b32_e32 v22, 16, v92
	v_and_b32_e32 v23, 0xffff0000, v92
	v_lshlrev_b32_e32 v14, 16, v90
	v_and_b32_e32 v15, 0xffff0000, v90
	v_lshlrev_b32_e32 v16, 16, v91
	v_and_b32_e32 v17, 0xffff0000, v91
	v_lshlrev_b32_e32 v24, 16, v93
	v_and_b32_e32 v25, 0xffff0000, v93
	v_pk_fma_f32 v[14:15], v[14:15], s[30:31], v[18:19] op_sel_hi:[1,0,1]
	v_pk_fma_f32 v[16:17], v[16:17], s[30:31], v[20:21] op_sel_hi:[1,0,1]
	v_pk_fma_f32 v[18:19], v[24:25], s[30:31], v[12:13] op_sel_hi:[1,0,1]
	v_pk_fma_f32 v[12:13], v[22:23], s[30:31], v[10:11] op_sel_hi:[1,0,1]
	v_cvt_pk_bf16_f32 v10, v14, v15
	v_add_co_u32_e32 v14, vcc, s46, v62
	v_cvt_pk_bf16_f32 v11, v16, v17
	v_cvt_pk_bf16_f32 v12, v12, v13
	v_cvt_pk_bf16_f32 v13, v18, v19
	v_addc_co_u32_e32 v15, vcc, 0, v63, vcc
	flat_store_dwordx4 v[14:15], v[10:13]
	v_lshlrev_b32_e32 v16, 16, v96
	v_and_b32_e32 v17, 0xffff0000, v96
	v_lshlrev_b32_e32 v10, 16, v94
	v_and_b32_e32 v11, 0xffff0000, v94
	v_lshlrev_b32_e32 v12, 16, v95
	v_and_b32_e32 v13, 0xffff0000, v95
	v_lshlrev_b32_e32 v18, 16, v97
	v_and_b32_e32 v19, 0xffff0000, v97
	v_pk_fma_f32 v[8:9], v[12:13], s[30:31], v[8:9] op_sel_hi:[1,0,1]
	v_pk_fma_f32 v[6:7], v[10:11], s[30:31], v[6:7] op_sel_hi:[1,0,1]
	v_pk_fma_f32 v[10:11], v[18:19], s[30:31], v[4:5] op_sel_hi:[1,0,1]
	v_pk_fma_f32 v[4:5], v[16:17], s[30:31], v[2:3] op_sel_hi:[1,0,1]
	v_cvt_pk_bf16_f32 v2, v6, v7
	v_cvt_pk_bf16_f32 v3, v8, v9
	v_cvt_pk_bf16_f32 v4, v4, v5
	v_cvt_pk_bf16_f32 v5, v10, v11
	s_and_b64 vcc, exec, s[34:35]
	flat_store_dwordx4 v[14:15], v[2:5] offset:256
	s_cbranch_vccz .LBB0_1785
	s_waitcnt vmcnt(0)
	s_cmpk_gt_u32 s4, 0xff
	s_cbranch_scc1 .LBB0_1790
	s_barrier

.LBB0_2041:
	s_add_u32 s14, s38, 0x100
	s_addc_u32 s15, s39, 0
	s_add_u32 s36, s35, s38
	s_addc_u32 s37, s55, s39
	s_cmpk_eq_i32 s38, 0x300
	s_cselect_b64 vcc, -1, 0
	s_and_b64 s[0:1], vcc, exec
	s_cselect_b32 s1, 0, s14
	s_cselect_b32 s0, 0, s15
	s_cselect_b32 s36, s31, s36
	s_cselect_b32 s37, s29, s37
	s_add_u32 s40, s18, s1
	s_addc_u32 s41, s19, s0
	s_add_i32 s1, 0, 0x10000
	v_add_u32_e32 v14, s1, v197
	ds_read_b128 v[2:5], v14
	ds_read_b128 v[6:9], v14 offset:1024
	ds_read_b128 v[10:13], v14 offset:2048
	ds_read_b128 v[14:17], v14 offset:3072
	v_cndmask_b32_e32 v162, v168, v171, vcc
	v_cndmask_b32_e32 v184, v170, v198, vcc
	v_cndmask_b32_e32 v175, v172, v199, vcc
	v_cndmask_b32_e32 v173, v174, v200, vcc
	v_lshl_add_u64 v[18:19], v[178:179], 0, s[38:39]
	s_add_i32 m0, s45, 0xc000
	ds_read_b128 v[202:205], v169
	ds_read_b128 v[206:209], v169 offset:1024
	ds_read_b128 v[210:213], v169 offset:2048
	ds_read_b128 v[214:217], v169 offset:3072
	ds_read_b128 v[218:221], v169 offset:4096
	ds_read_b128 v[222:225], v169 offset:5120
	ds_read_b128 v[226:229], v169 offset:6144
	ds_read_b128 v[230:233], v169 offset:7168
	global_load_lds_dwordx4 v[18:19], off
	v_lshl_add_u64 v[18:19], v[176:177], 0, s[38:39]
	s_add_i32 m0, s45, 0xe000
	s_nop 0
	global_load_lds_dwordx4 v[18:19], off
	s_waitcnt lgkmcnt(8)
	s_waitcnt vmcnt(10)
	s_barrier
	s_waitcnt lgkmcnt(0)
	s_waitcnt lgkmcnt(0)
	v_mfma_scale_f32_16x16x128_f8f6f4 v[158:161], v[2:9], v[202:209], v[158:161], v188, v188 op_sel_hi:[0,0,0]
	v_mfma_scale_f32_16x16x128_f8f6f4 v[150:153], v[10:17], v[202:209], v[150:153], v188, v188 op_sel_hi:[0,0,0]
	v_mfma_scale_f32_16x16x128_f8f6f4 v[142:145], v[2:9], v[210:217], v[142:145], v188, v188 op_sel_hi:[0,0,0]
	v_mfma_scale_f32_16x16x128_f8f6f4 v[134:137], v[10:17], v[210:217], v[134:137], v188, v188 op_sel_hi:[0,0,0]
	v_mfma_scale_f32_16x16x128_f8f6f4 v[126:129], v[2:9], v[218:225], v[126:129], v188, v188 op_sel_hi:[0,0,0]
	v_mfma_scale_f32_16x16x128_f8f6f4 v[118:121], v[10:17], v[218:225], v[118:121], v188, v188 op_sel_hi:[0,0,0]
	v_mfma_scale_f32_16x16x128_f8f6f4 v[110:113], v[2:9], v[226:233], v[110:113], v188, v188 op_sel_hi:[0,0,0]
	v_mfma_scale_f32_16x16x128_f8f6f4 v[102:105], v[10:17], v[226:233], v[102:105], v188, v188 op_sel_hi:[0,0,0]
	s_barrier
	s_add_i32 s0, 0, 0x14000
	s_add_i32 s1, s1, s43
	v_add_u32_e32 v30, s0, v197
	v_lshl_add_u64 v[180:181], s[36:37], 0, v[164:165]
	s_mov_b32 m0, s1
	ds_read_b128 v[18:21], v30
	ds_read_b128 v[22:25], v30 offset:1024
	ds_read_b128 v[26:29], v30 offset:2048
	ds_read_b128 v[30:33], v30 offset:3072
	global_load_lds_dwordx4 v[180:181], off
	v_lshl_add_u64 v[182:183], s[36:37], 0, v[166:167]
	s_add_i32 m0, s1, 0x2000
	s_nop 0
	global_load_lds_dwordx4 v[182:183], off
	s_waitcnt vmcnt(10)
	s_barrier
	s_waitcnt lgkmcnt(0)
	s_waitcnt lgkmcnt(0)
	v_mfma_scale_f32_16x16x128_f8f6f4 v[154:157], v[18:25], v[202:209], v[154:157], v188, v188 op_sel_hi:[0,0,0]
	v_mfma_scale_f32_16x16x128_f8f6f4 v[146:149], v[26:33], v[202:209], v[146:149], v188, v188 op_sel_hi:[0,0,0]
	v_mfma_scale_f32_16x16x128_f8f6f4 v[138:141], v[18:25], v[210:217], v[138:141], v188, v188 op_sel_hi:[0,0,0]
	v_mfma_scale_f32_16x16x128_f8f6f4 v[130:133], v[26:33], v[210:217], v[130:133], v188, v188 op_sel_hi:[0,0,0]
	v_mfma_scale_f32_16x16x128_f8f6f4 v[122:125], v[18:25], v[218:225], v[122:125], v188, v188 op_sel_hi:[0,0,0]
	v_mfma_scale_f32_16x16x128_f8f6f4 v[114:117], v[26:33], v[218:225], v[114:117], v188, v188 op_sel_hi:[0,0,0]
	v_mfma_scale_f32_16x16x128_f8f6f4 v[106:109], v[18:25], v[226:233], v[106:109], v188, v188 op_sel_hi:[0,0,0]
	v_mfma_scale_f32_16x16x128_f8f6f4 v[98:101], v[26:33], v[226:233], v[98:101], v188, v188 op_sel_hi:[0,0,0]
	s_mov_b32 m0, s45
	s_barrier
	ds_read_b128 v[202:205], v169 offset:16384
	ds_read_b128 v[206:209], v169 offset:17408
	ds_read_b128 v[210:213], v169 offset:18432
	ds_read_b128 v[214:217], v169 offset:19456
	ds_read_b128 v[218:221], v169 offset:20480
	ds_read_b128 v[222:225], v169 offset:21504
	ds_read_b128 v[226:229], v169 offset:22528
	ds_read_b128 v[230:233], v169 offset:23552
	global_load_lds_dwordx4 v162, s[40:41]
	s_mov_b32 m0, s46
	v_mov_b32_e32 v185, v163
	global_load_lds_dwordx4 v184, s[40:41]
	s_waitcnt vmcnt(10)
	s_barrier
	s_waitcnt lgkmcnt(0)
	v_lshl_add_u64 v[186:187], s[40:41], 0, v[162:163]
	v_lshl_add_u64 v[184:185], s[40:41], 0, v[184:185]
	s_waitcnt lgkmcnt(0)
	v_mfma_scale_f32_16x16x128_f8f6f4 v[94:97], v[2:9], v[202:209], v[94:97], v188, v188 op_sel_hi:[0,0,0]
	v_mfma_scale_f32_16x16x128_f8f6f4 v[86:89], v[10:17], v[202:209], v[86:89], v188, v188 op_sel_hi:[0,0,0]
	v_mfma_scale_f32_16x16x128_f8f6f4 v[78:81], v[2:9], v[210:217], v[78:81], v188, v188 op_sel_hi:[0,0,0]
	v_mfma_scale_f32_16x16x128_f8f6f4 v[70:73], v[10:17], v[210:217], v[70:73], v188, v188 op_sel_hi:[0,0,0]
	v_mfma_scale_f32_16x16x128_f8f6f4 v[62:65], v[2:9], v[218:225], v[62:65], v188, v188 op_sel_hi:[0,0,0]
	v_mfma_scale_f32_16x16x128_f8f6f4 v[54:57], v[10:17], v[218:225], v[54:57], v188, v188 op_sel_hi:[0,0,0]
	v_mfma_scale_f32_16x16x128_f8f6f4 v[46:49], v[2:9], v[226:233], v[46:49], v188, v188 op_sel_hi:[0,0,0]
	v_mfma_scale_f32_16x16x128_f8f6f4 v[38:41], v[10:17], v[226:233], v[38:41], v188, v188 op_sel_hi:[0,0,0]
	s_barrier
	s_add_u32 s38, s36, 0x20000
	s_addc_u32 s39, s37, 0
	s_add_i32 s0, s0, s43
	v_lshl_add_u64 v[2:3], s[38:39], 0, v[164:165]
	s_mov_b32 m0, s0
	s_nop 0
	global_load_lds_dwordx4 v[2:3], off
	v_lshl_add_u64 v[2:3], s[38:39], 0, v[166:167]
	s_add_i32 m0, s0, 0x2000
	s_nop 0
	global_load_lds_dwordx4 v[2:3], off
	s_waitcnt vmcnt(10)
	s_barrier
	v_mfma_scale_f32_16x16x128_f8f6f4 v[90:93], v[18:25], v[202:209], v[90:93], v188, v188 op_sel_hi:[0,0,0]
	v_mfma_scale_f32_16x16x128_f8f6f4 v[82:85], v[26:33], v[202:209], v[82:85], v188, v188 op_sel_hi:[0,0,0]
	v_mfma_scale_f32_16x16x128_f8f6f4 v[74:77], v[18:25], v[210:217], v[74:77], v188, v188 op_sel_hi:[0,0,0]
	v_mfma_scale_f32_16x16x128_f8f6f4 v[66:69], v[26:33], v[210:217], v[66:69], v188, v188 op_sel_hi:[0,0,0]
	v_mfma_scale_f32_16x16x128_f8f6f4 v[58:61], v[18:25], v[218:225], v[58:61], v188, v188 op_sel_hi:[0,0,0]
	v_mfma_scale_f32_16x16x128_f8f6f4 v[50:53], v[26:33], v[218:225], v[50:53], v188, v188 op_sel_hi:[0,0,0]
	v_mfma_scale_f32_16x16x128_f8f6f4 v[42:45], v[18:25], v[226:233], v[42:45], v188, v188 op_sel_hi:[0,0,0]
	v_mfma_scale_f32_16x16x128_f8f6f4 v[34:37], v[26:33], v[226:233], v[34:37], v188, v188 op_sel_hi:[0,0,0]
	s_add_i32 s0, 0, 0x18000
	v_add_u32_e32 v14, s0, v197
	s_barrier
	ds_read_b128 v[2:5], v14
	ds_read_b128 v[6:9], v14 offset:1024
	ds_read_b128 v[10:13], v14 offset:2048
	ds_read_b128 v[14:17], v14 offset:3072
	s_mov_b32 m0, s47
	ds_read_b128 v[18:21], v169 offset:32768
	ds_read_b128 v[22:25], v169 offset:33792
	ds_read_b128 v[26:29], v169 offset:34816
	ds_read_b128 v[30:33], v169 offset:35840
	ds_read_b128 v[202:205], v169 offset:36864
	ds_read_b128 v[206:209], v169 offset:37888
	ds_read_b128 v[210:213], v169 offset:38912
	ds_read_b128 v[214:217], v169 offset:39936
	global_load_lds_dwordx4 v175, s[40:41]
	s_mov_b32 m0, s48
	s_nop 0
	global_load_lds_dwordx4 v173, s[40:41]
	s_waitcnt lgkmcnt(8)
	s_waitcnt vmcnt(10)
	s_barrier
	s_waitcnt lgkmcnt(0)
	s_waitcnt lgkmcnt(0)
	v_mfma_scale_f32_16x16x128_f8f6f4 v[158:161], v[2:9], v[18:25], v[158:161], v188, v188 op_sel_hi:[0,0,0]
	v_mfma_scale_f32_16x16x128_f8f6f4 v[150:153], v[10:17], v[18:25], v[150:153], v188, v188 op_sel_hi:[0,0,0]
	v_mfma_scale_f32_16x16x128_f8f6f4 v[142:145], v[2:9], v[26:33], v[142:145], v188, v188 op_sel_hi:[0,0,0]
	v_mfma_scale_f32_16x16x128_f8f6f4 v[134:137], v[10:17], v[26:33], v[134:137], v188, v188 op_sel_hi:[0,0,0]
	v_mfma_scale_f32_16x16x128_f8f6f4 v[126:129], v[2:9], v[202:209], v[126:129], v188, v188 op_sel_hi:[0,0,0]
	v_mfma_scale_f32_16x16x128_f8f6f4 v[118:121], v[10:17], v[202:209], v[118:121], v188, v188 op_sel_hi:[0,0,0]
	v_mfma_scale_f32_16x16x128_f8f6f4 v[110:113], v[2:9], v[210:217], v[110:113], v188, v188 op_sel_hi:[0,0,0]
	v_mfma_scale_f32_16x16x128_f8f6f4 v[102:105], v[10:17], v[210:217], v[102:105], v188, v188 op_sel_hi:[0,0,0]
	s_barrier
	s_add_i32 s38, 0, 0x1c000
	s_add_i32 s0, s0, s43
	v_add_u32_e32 v162, s38, v197
	v_lshl_add_u64 v[180:181], v[180:181], 0, s[24:25]
	s_mov_b32 m0, s0
	ds_read_b128 v[218:221], v162
	ds_read_b128 v[222:225], v162 offset:1024
	ds_read_b128 v[226:229], v162 offset:2048
	ds_read_b128 v[230:233], v162 offset:3072
	global_load_lds_dwordx4 v[180:181], off
	v_lshl_add_u64 v[180:181], v[182:183], 0, s[24:25]
	s_add_i32 m0, s0, 0x2000
	s_nop 0
	global_load_lds_dwordx4 v[180:181], off
	s_waitcnt vmcnt(10)
	s_barrier
	s_waitcnt lgkmcnt(0)
	s_waitcnt lgkmcnt(0)
	v_mfma_scale_f32_16x16x128_f8f6f4 v[154:157], v[218:225], v[18:25], v[154:157], v188, v188 op_sel_hi:[0,0,0]
	v_mfma_scale_f32_16x16x128_f8f6f4 v[146:149], v[226:233], v[18:25], v[146:149], v188, v188 op_sel_hi:[0,0,0]
	v_mfma_scale_f32_16x16x128_f8f6f4 v[138:141], v[218:225], v[26:33], v[138:141], v188, v188 op_sel_hi:[0,0,0]
	v_mfma_scale_f32_16x16x128_f8f6f4 v[130:133], v[226:233], v[26:33], v[130:133], v188, v188 op_sel_hi:[0,0,0]
	v_mfma_scale_f32_16x16x128_f8f6f4 v[122:125], v[218:225], v[202:209], v[122:125], v188, v188 op_sel_hi:[0,0,0]
	v_mfma_scale_f32_16x16x128_f8f6f4 v[114:117], v[226:233], v[202:209], v[114:117], v188, v188 op_sel_hi:[0,0,0]
	v_mfma_scale_f32_16x16x128_f8f6f4 v[106:109], v[218:225], v[210:217], v[106:109], v188, v188 op_sel_hi:[0,0,0]
	v_mfma_scale_f32_16x16x128_f8f6f4 v[98:101], v[226:233], v[210:217], v[98:101], v188, v188 op_sel_hi:[0,0,0]
	s_mov_b32 m0, s51
	v_lshl_add_u64 v[180:181], v[186:187], 0, s[24:25]
	s_barrier
	ds_read_b128 v[18:21], v169 offset:49152
	ds_read_b128 v[22:25], v169 offset:50176
	ds_read_b128 v[26:29], v169 offset:51200
	ds_read_b128 v[30:33], v169 offset:52224
	ds_read_b128 v[202:205], v169 offset:53248
	ds_read_b128 v[206:209], v169 offset:54272
	ds_read_b128 v[210:213], v169 offset:55296
	ds_read_b128 v[214:217], v169 offset:56320
	global_load_lds_dwordx4 v[180:181], off
	v_lshl_add_u64 v[180:181], v[184:185], 0, s[24:25]
	s_mov_b32 m0, s52
	s_nop 0
	global_load_lds_dwordx4 v[180:181], off
	s_waitcnt vmcnt(10)
	s_barrier
	s_waitcnt lgkmcnt(0)
	s_waitcnt lgkmcnt(0)
	v_mfma_scale_f32_16x16x128_f8f6f4 v[94:97], v[2:9], v[18:25], v[94:97], v188, v188 op_sel_hi:[0,0,0]
	v_mfma_scale_f32_16x16x128_f8f6f4 v[86:89], v[10:17], v[18:25], v[86:89], v188, v188 op_sel_hi:[0,0,0]
	v_mfma_scale_f32_16x16x128_f8f6f4 v[78:81], v[2:9], v[26:33], v[78:81], v188, v188 op_sel_hi:[0,0,0]
	v_mfma_scale_f32_16x16x128_f8f6f4 v[70:73], v[10:17], v[26:33], v[70:73], v188, v188 op_sel_hi:[0,0,0]
	v_mfma_scale_f32_16x16x128_f8f6f4 v[62:65], v[2:9], v[202:209], v[62:65], v188, v188 op_sel_hi:[0,0,0]
	v_mfma_scale_f32_16x16x128_f8f6f4 v[54:57], v[10:17], v[202:209], v[54:57], v188, v188 op_sel_hi:[0,0,0]
	v_mfma_scale_f32_16x16x128_f8f6f4 v[46:49], v[2:9], v[210:217], v[46:49], v188, v188 op_sel_hi:[0,0,0]
	v_mfma_scale_f32_16x16x128_f8f6f4 v[38:41], v[10:17], v[210:217], v[38:41], v188, v188 op_sel_hi:[0,0,0]
	s_barrier
	s_add_u32 s0, s36, 0x20080
	s_addc_u32 s1, s37, 0
	s_add_i32 s36, s38, s43
	v_lshl_add_u64 v[2:3], s[0:1], 0, v[164:165]
	s_mov_b32 m0, s36
	s_nop 0
	global_load_lds_dwordx4 v[2:3], off
	v_lshl_add_u64 v[2:3], s[0:1], 0, v[166:167]
	s_add_i32 m0, s36, 0x2000
	s_nop 0
	global_load_lds_dwordx4 v[2:3], off
	s_waitcnt vmcnt(10)
	s_barrier
	v_mfma_scale_f32_16x16x128_f8f6f4 v[90:93], v[218:225], v[18:25], v[90:93], v188, v188 op_sel_hi:[0,0,0]
	v_mfma_scale_f32_16x16x128_f8f6f4 v[82:85], v[226:233], v[18:25], v[82:85], v188, v188 op_sel_hi:[0,0,0]
	v_mfma_scale_f32_16x16x128_f8f6f4 v[74:77], v[218:225], v[26:33], v[74:77], v188, v188 op_sel_hi:[0,0,0]
	v_mfma_scale_f32_16x16x128_f8f6f4 v[66:69], v[226:233], v[26:33], v[66:69], v188, v188 op_sel_hi:[0,0,0]
	v_mfma_scale_f32_16x16x128_f8f6f4 v[58:61], v[218:225], v[202:209], v[58:61], v188, v188 op_sel_hi:[0,0,0]
	v_mfma_scale_f32_16x16x128_f8f6f4 v[50:53], v[226:233], v[202:209], v[50:53], v188, v188 op_sel_hi:[0,0,0]
	v_mfma_scale_f32_16x16x128_f8f6f4 v[42:45], v[218:225], v[210:217], v[42:45], v188, v188 op_sel_hi:[0,0,0]
	v_mfma_scale_f32_16x16x128_f8f6f4 v[34:37], v[226:233], v[210:217], v[34:37], v188, v188 op_sel_hi:[0,0,0]
	s_add_i32 s56, s56, 2
	s_cmp_gt_u32 s56, 5
	s_mov_b64 s[38:39], s[14:15]
	s_barrier
	s_cbranch_scc0 .LBB0_2041
	v_mul_f32_e32 v5, 0x3c800000, v158
	v_mul_f32_e32 v6, 0xbfb8aa3b, v5
	v_exp_f32_e32 v6, v6
	s_ashr_i32 s35, s34, 31
	s_ashr_i32 s31, s30, 31
	s_lshl_b64 s[14:15], s[34:35], 18
	v_add_f32_e32 v6, 1.0, v6
	v_rcp_f32_e32 v6, v6
	s_lshl_b64 s[30:31], s[30:31], 15
	v_mov_b32_e32 v3, v195
	s_add_u32 s0, s6, s14
	v_mul_f32_e32 v5, v5, v6
	v_mul_f32_e32 v6, 0x3c800000, v159
	v_mul_f32_e32 v7, 0xbfb8aa3b, v6
	v_exp_f32_e32 v7, v7
	v_mul_f32_e32 v5, v5, v154
	v_mul_f32_e32 v5, 0x3e000000, v5
	v_med3_f32 v5, v5, s10, v190
	v_add_f32_e32 v7, 1.0, v7
	v_rcp_f32_e32 v7, v7
	s_nop 15
	s_nop 15
	v_mov_b32_e32 v2, v196
	v_mul_f32_e32 v6, v6, v7
	v_mul_f32_e32 v7, 0x3c800000, v160
	v_mul_f32_e32 v8, 0xbfb8aa3b, v7
	v_exp_f32_e32 v8, v8
	v_mul_f32_e32 v6, v6, v155
	v_mul_f32_e32 v6, 0x3e000000, v6
	v_add_u32_e32 v4, s49, v3
	v_add_f32_e32 v8, 1.0, v8
	v_rcp_f32_e32 v8, v8
	s_addc_u32 s1, s7, s15
	s_add_u32 s14, s0, s30
	v_mul_f32_e32 v7, v7, v8
	v_mul_f32_e32 v8, 0x3c800000, v161
	v_mul_f32_e32 v9, 0xbfb8aa3b, v8
	v_exp_f32_e32 v9, v9
	v_mul_f32_e32 v7, v7, v156
	v_mul_f32_e32 v7, 0x3e000000, v7
	v_lshl_add_u32 v2, v2, 3, s50
	v_add_f32_e32 v9, 1.0, v9
	v_rcp_f32_e32 v9, v9
	s_addc_u32 s15, s1, s31
	v_ashrrev_i32_e32 v3, 31, v2
	s_and_b64 vcc, exec, s[12:13]
	v_mul_f32_e32 v8, v8, v9
	v_mul_f32_e32 v9, 0x3c800000, v150
	v_mul_f32_e32 v10, 0xbfb8aa3b, v9
	v_exp_f32_e32 v10, v10
	v_mul_f32_e32 v8, v8, v157
	v_mul_f32_e32 v8, 0x3e000000, v8
	v_mov_b32_e32 v174, v200
	v_add_f32_e32 v10, 1.0, v10
	v_rcp_f32_e32 v10, v10
	v_mov_b32_e32 v172, v199
	v_mov_b32_e32 v170, v198
	v_mov_b32_e32 v168, v171
	v_mul_f32_e32 v9, v9, v10
	v_mul_f32_e32 v10, 0x3c800000, v151
	v_mul_f32_e32 v11, 0xbfb8aa3b, v10
	v_exp_f32_e32 v11, v11
	v_mul_f32_e32 v9, v9, v146
	v_mul_f32_e32 v9, 0x3e000000, v9
	s_mov_b32 s30, s28
	v_add_f32_e32 v11, 1.0, v11
	v_rcp_f32_e32 v11, v11
	s_mov_b32 s34, s54
	s_mov_b64 s[36:37], s[16:17]
	v_mul_f32_e32 v10, v10, v11
	v_mul_f32_e32 v11, 0x3c800000, v152
	v_mul_f32_e32 v12, 0xbfb8aa3b, v11
	v_exp_f32_e32 v12, v12
	v_mul_f32_e32 v10, v10, v147
	v_mul_f32_e32 v10, 0x3e000000, v10
	v_add_f32_e32 v12, 1.0, v12
	v_rcp_f32_e32 v12, v12
	s_nop 0
	v_mul_f32_e32 v11, v11, v12
	v_mul_f32_e32 v12, 0x3c800000, v153
	v_mul_f32_e32 v13, 0xbfb8aa3b, v12
	v_exp_f32_e32 v13, v13
	v_mul_f32_e32 v11, v11, v148
	v_mul_f32_e32 v11, 0x3e000000, v11
	v_add_f32_e32 v13, 1.0, v13
	v_rcp_f32_e32 v13, v13
	s_nop 0
	v_mul_f32_e32 v12, v12, v13
	v_med3_f32 v13, v6, s10, v190
	v_mov_b32_e32 v6, v163
	v_cvt_pk_fp8_f32 v6, v5, v13
	v_med3_f32 v5, v7, s10, v190
	v_med3_f32 v7, v8, s10, v190
	v_med3_f32 v8, v10, s10, v190
	v_cvt_pk_fp8_f32 v6, v5, v7 op_sel:[0,0,1]
	v_med3_f32 v5, v9, s10, v190
	v_mov_b32_e32 v7, v163
	v_cvt_pk_fp8_f32 v7, v5, v8
	v_mul_f32_e32 v12, v12, v149
	v_mul_f32_e32 v12, 0x3e000000, v12
	v_med3_f32 v5, v11, s10, v190
	v_med3_f32 v8, v12, s10, v190
	v_cvt_pk_fp8_f32 v7, v5, v8 op_sel:[0,0,1]
	v_ashrrev_i32_e32 v5, 31, v4
	v_lshlrev_b64 v[8:9], 7, v[4:5]
	v_lshl_add_u64 v[8:9], s[14:15], 0, v[8:9]
	v_lshl_add_u64 v[8:9], v[8:9], 0, v[2:3]
	v_mul_f32_e32 v5, 0x3c800000, v142
	flat_store_dwordx2 v[8:9], v[6:7]
	v_mul_f32_e32 v6, 0xbfb8aa3b, v5
	v_exp_f32_e32 v6, v6
	s_nop 0
	v_add_f32_e32 v6, 1.0, v6
	v_rcp_f32_e32 v6, v6
	s_nop 0
	v_mul_f32_e32 v5, v5, v6
	v_mul_f32_e32 v6, 0x3c800000, v143
	v_mul_f32_e32 v7, 0xbfb8aa3b, v6
	v_exp_f32_e32 v7, v7
	v_mul_f32_e32 v5, v5, v138
	v_mul_f32_e32 v5, 0x3e000000, v5
	v_med3_f32 v5, v5, s10, v190
	v_add_f32_e32 v7, 1.0, v7
	v_rcp_f32_e32 v7, v7
	s_nop 0
	v_mul_f32_e32 v6, v6, v7
	v_mul_f32_e32 v6, v6, v139
	v_mul_f32_e32 v7, 0x3e000000, v6
	v_mul_f32_e32 v6, 0x3c800000, v144
	v_mul_f32_e32 v8, 0xbfb8aa3b, v6
	v_exp_f32_e32 v8, v8
	v_med3_f32 v7, v7, s10, v190
	v_add_f32_e32 v8, 1.0, v8
	v_rcp_f32_e32 v8, v8
	s_nop 0
	v_mul_f32_e32 v6, v6, v8
	v_mul_f32_e32 v6, v6, v140
	v_mul_f32_e32 v9, 0x3e000000, v6
	v_mul_f32_e32 v6, 0x3c800000, v145
	v_mul_f32_e32 v8, 0xbfb8aa3b, v6
	v_exp_f32_e32 v8, v8
	s_nop 0
	v_add_f32_e32 v8, 1.0, v8
	v_rcp_f32_e32 v8, v8
	s_nop 0
	v_mul_f32_e32 v6, v6, v8
	v_mul_f32_e32 v6, v6, v141
	v_mul_f32_e32 v10, 0x3e000000, v6
	v_mul_f32_e32 v6, 0x3c800000, v134
	v_mul_f32_e32 v8, 0xbfb8aa3b, v6
	v_exp_f32_e32 v8, v8
	s_nop 0
	v_add_f32_e32 v8, 1.0, v8
	v_rcp_f32_e32 v8, v8
	s_nop 0
	v_mul_f32_e32 v6, v6, v8
	v_mul_f32_e32 v6, v6, v130
	v_mul_f32_e32 v11, 0x3e000000, v6
	v_mul_f32_e32 v6, 0x3c800000, v135
	v_mul_f32_e32 v8, 0xbfb8aa3b, v6
	v_exp_f32_e32 v8, v8
	s_nop 0
	v_add_f32_e32 v8, 1.0, v8
	v_rcp_f32_e32 v8, v8
	s_nop 0
	v_mul_f32_e32 v6, v6, v8
	v_mul_f32_e32 v6, v6, v131
	v_mul_f32_e32 v12, 0x3e000000, v6
	v_mul_f32_e32 v6, 0x3c800000, v136
	v_mul_f32_e32 v8, 0xbfb8aa3b, v6
	v_exp_f32_e32 v8, v8
	s_nop 0
	v_add_f32_e32 v8, 1.0, v8
	v_rcp_f32_e32 v8, v8
	s_nop 0
	v_mul_f32_e32 v6, v6, v8
	v_mul_f32_e32 v6, v6, v132
	v_mul_f32_e32 v13, 0x3e000000, v6
	v_mul_f32_e32 v6, 0x3c800000, v137
	v_mul_f32_e32 v8, 0xbfb8aa3b, v6
	v_exp_f32_e32 v8, v8
	s_nop 0
	v_add_f32_e32 v8, 1.0, v8
	v_rcp_f32_e32 v8, v8
	s_nop 0
	v_mul_f32_e32 v6, v6, v8
	v_mov_b32_e32 v8, v163
	v_cvt_pk_fp8_f32 v8, v5, v7
	v_med3_f32 v5, v9, s10, v190
	v_med3_f32 v7, v10, s10, v190
	v_mov_b32_e32 v9, v163
	v_cvt_pk_fp8_f32 v8, v5, v7 op_sel:[0,0,1]
	v_med3_f32 v5, v11, s10, v190
	v_med3_f32 v7, v12, s10, v190
	v_cvt_pk_fp8_f32 v9, v5, v7
	v_mul_f32_e32 v6, v6, v133
	v_mul_f32_e32 v14, 0x3e000000, v6
	v_add_u32_e32 v6, 16, v4
	v_med3_f32 v5, v13, s10, v190
	v_med3_f32 v7, v14, s10, v190
	v_cvt_pk_fp8_f32 v9, v5, v7 op_sel:[0,0,1]
	v_ashrrev_i32_e32 v7, 31, v6
	v_lshlrev_b64 v[6:7], 7, v[6:7]
	v_lshl_add_u64 v[6:7], s[14:15], 0, v[6:7]
	v_lshl_add_u64 v[6:7], v[6:7], 0, v[2:3]
	v_mul_f32_e32 v5, 0x3c800000, v126
	flat_store_dwordx2 v[6:7], v[8:9]
	v_mul_f32_e32 v6, 0xbfb8aa3b, v5
	v_exp_f32_e32 v6, v6
	s_nop 0
	v_add_f32_e32 v6, 1.0, v6
	v_rcp_f32_e32 v6, v6
	s_nop 0
	v_mul_f32_e32 v5, v5, v6
	v_mul_f32_e32 v6, 0x3c800000, v127
	v_mul_f32_e32 v7, 0xbfb8aa3b, v6
	v_exp_f32_e32 v7, v7
	v_mul_f32_e32 v5, v5, v122
	v_mul_f32_e32 v5, 0x3e000000, v5
	v_med3_f32 v5, v5, s10, v190
	v_add_f32_e32 v7, 1.0, v7
	v_rcp_f32_e32 v7, v7
	s_nop 0
	v_mul_f32_e32 v6, v6, v7
	v_mul_f32_e32 v6, v6, v123
	v_mul_f32_e32 v7, 0x3e000000, v6
	v_mul_f32_e32 v6, 0x3c800000, v128
	v_mul_f32_e32 v8, 0xbfb8aa3b, v6
	v_exp_f32_e32 v8, v8
	v_med3_f32 v7, v7, s10, v190
	v_add_f32_e32 v8, 1.0, v8
	v_rcp_f32_e32 v8, v8
	s_nop 0
	v_mul_f32_e32 v6, v6, v8
	v_mul_f32_e32 v6, v6, v124
	v_mul_f32_e32 v9, 0x3e000000, v6
	v_mul_f32_e32 v6, 0x3c800000, v129
	v_mul_f32_e32 v8, 0xbfb8aa3b, v6
	v_exp_f32_e32 v8, v8
	s_nop 0
	v_add_f32_e32 v8, 1.0, v8
	v_rcp_f32_e32 v8, v8
	s_nop 0
	v_mul_f32_e32 v6, v6, v8
	v_mul_f32_e32 v6, v6, v125
	v_mul_f32_e32 v10, 0x3e000000, v6
	v_mul_f32_e32 v6, 0x3c800000, v118
	v_mul_f32_e32 v8, 0xbfb8aa3b, v6
	v_exp_f32_e32 v8, v8
	s_nop 0
	v_add_f32_e32 v8, 1.0, v8
	v_rcp_f32_e32 v8, v8
	s_nop 0
	v_mul_f32_e32 v6, v6, v8
	v_mul_f32_e32 v6, v6, v114
	v_mul_f32_e32 v11, 0x3e000000, v6
	v_mul_f32_e32 v6, 0x3c800000, v119
	v_mul_f32_e32 v8, 0xbfb8aa3b, v6
	v_exp_f32_e32 v8, v8
	s_nop 0
	v_add_f32_e32 v8, 1.0, v8
	v_rcp_f32_e32 v8, v8
	s_nop 0
	v_mul_f32_e32 v6, v6, v8
	v_mul_f32_e32 v6, v6, v115
	v_mul_f32_e32 v12, 0x3e000000, v6
	v_mul_f32_e32 v6, 0x3c800000, v120
	v_mul_f32_e32 v8, 0xbfb8aa3b, v6
	v_exp_f32_e32 v8, v8
	s_nop 0
	v_add_f32_e32 v8, 1.0, v8
	v_rcp_f32_e32 v8, v8
	s_nop 0
	v_mul_f32_e32 v6, v6, v8
	v_mul_f32_e32 v6, v6, v116
	v_mul_f32_e32 v13, 0x3e000000, v6
	v_mul_f32_e32 v6, 0x3c800000, v121
	v_mul_f32_e32 v8, 0xbfb8aa3b, v6
	v_exp_f32_e32 v8, v8
	s_nop 0
	v_add_f32_e32 v8, 1.0, v8
	v_rcp_f32_e32 v8, v8
	s_nop 0
	v_mul_f32_e32 v6, v6, v8
	v_mov_b32_e32 v8, v163
	v_cvt_pk_fp8_f32 v8, v5, v7
	v_med3_f32 v5, v9, s10, v190
	v_med3_f32 v7, v10, s10, v190
	v_mov_b32_e32 v9, v163
	v_cvt_pk_fp8_f32 v8, v5, v7 op_sel:[0,0,1]
	v_med3_f32 v5, v11, s10, v190
	v_med3_f32 v7, v12, s10, v190
	v_cvt_pk_fp8_f32 v9, v5, v7
	v_mul_f32_e32 v6, v6, v117
	v_mul_f32_e32 v14, 0x3e000000, v6
	v_add_u32_e32 v6, 32, v4
	v_med3_f32 v5, v13, s10, v190
	v_med3_f32 v7, v14, s10, v190
	v_cvt_pk_fp8_f32 v9, v5, v7 op_sel:[0,0,1]
	v_ashrrev_i32_e32 v7, 31, v6
	v_lshlrev_b64 v[6:7], 7, v[6:7]
	v_lshl_add_u64 v[6:7], s[14:15], 0, v[6:7]
	v_lshl_add_u64 v[6:7], v[6:7], 0, v[2:3]
	v_mul_f32_e32 v5, 0x3c800000, v110
	flat_store_dwordx2 v[6:7], v[8:9]
	v_mul_f32_e32 v6, 0xbfb8aa3b, v5
	v_exp_f32_e32 v6, v6
	s_nop 0
	v_add_f32_e32 v6, 1.0, v6
	v_rcp_f32_e32 v6, v6
	s_nop 0
	v_mul_f32_e32 v5, v5, v6
	v_mul_f32_e32 v6, 0x3c800000, v111
	v_mul_f32_e32 v7, 0xbfb8aa3b, v6
	v_exp_f32_e32 v7, v7
	v_mul_f32_e32 v5, v5, v106
	v_mul_f32_e32 v5, 0x3e000000, v5
	v_med3_f32 v5, v5, s10, v190
	v_add_f32_e32 v7, 1.0, v7
	v_rcp_f32_e32 v7, v7
	s_nop 0
	v_mul_f32_e32 v6, v6, v7
	v_mul_f32_e32 v6, v6, v107
	v_mul_f32_e32 v7, 0x3e000000, v6
	v_mul_f32_e32 v6, 0x3c800000, v112
	v_mul_f32_e32 v8, 0xbfb8aa3b, v6
	v_exp_f32_e32 v8, v8
	v_med3_f32 v7, v7, s10, v190
	v_add_f32_e32 v8, 1.0, v8
	v_rcp_f32_e32 v8, v8
	s_nop 0
	v_mul_f32_e32 v6, v6, v8
	v_mul_f32_e32 v6, v6, v108
	v_mul_f32_e32 v9, 0x3e000000, v6
	v_mul_f32_e32 v6, 0x3c800000, v113
	v_mul_f32_e32 v8, 0xbfb8aa3b, v6
	v_exp_f32_e32 v8, v8
	s_nop 0
	v_add_f32_e32 v8, 1.0, v8
	v_rcp_f32_e32 v8, v8
	s_nop 0
	v_mul_f32_e32 v6, v6, v8
	v_mul_f32_e32 v6, v6, v109
	v_mul_f32_e32 v10, 0x3e000000, v6
	v_mul_f32_e32 v6, 0x3c800000, v102
	v_mul_f32_e32 v8, 0xbfb8aa3b, v6
	v_exp_f32_e32 v8, v8
	s_nop 0
	v_add_f32_e32 v8, 1.0, v8
	v_rcp_f32_e32 v8, v8
	s_nop 0
	v_mul_f32_e32 v6, v6, v8
	v_mul_f32_e32 v6, v6, v98
	v_mul_f32_e32 v11, 0x3e000000, v6
	v_mul_f32_e32 v6, 0x3c800000, v103
	v_mul_f32_e32 v8, 0xbfb8aa3b, v6
	v_exp_f32_e32 v8, v8
	s_nop 0
	v_add_f32_e32 v8, 1.0, v8
	v_rcp_f32_e32 v8, v8
	s_nop 0
	v_mul_f32_e32 v6, v6, v8
	v_mul_f32_e32 v6, v6, v99
	v_mul_f32_e32 v12, 0x3e000000, v6
	v_mul_f32_e32 v6, 0x3c800000, v104
	v_mul_f32_e32 v8, 0xbfb8aa3b, v6
	v_exp_f32_e32 v8, v8
	s_nop 0
	v_add_f32_e32 v8, 1.0, v8
	v_rcp_f32_e32 v8, v8
	s_nop 0
	v_mul_f32_e32 v6, v6, v8
	v_mul_f32_e32 v6, v6, v100
	v_mul_f32_e32 v13, 0x3e000000, v6
	v_mul_f32_e32 v6, 0x3c800000, v105
	v_mul_f32_e32 v8, 0xbfb8aa3b, v6
	v_exp_f32_e32 v8, v8
	s_nop 0
	v_add_f32_e32 v8, 1.0, v8
	v_rcp_f32_e32 v8, v8
	s_nop 0
	v_mul_f32_e32 v6, v6, v8
	v_mov_b32_e32 v8, v163
	v_cvt_pk_fp8_f32 v8, v5, v7
	v_med3_f32 v5, v9, s10, v190
	v_med3_f32 v7, v10, s10, v190
	v_mov_b32_e32 v9, v163
	v_cvt_pk_fp8_f32 v8, v5, v7 op_sel:[0,0,1]
	v_med3_f32 v5, v11, s10, v190
	v_med3_f32 v7, v12, s10, v190
	v_cvt_pk_fp8_f32 v9, v5, v7
	v_mul_f32_e32 v6, v6, v101
	v_mul_f32_e32 v14, 0x3e000000, v6
	v_add_u32_e32 v6, 48, v4
	v_med3_f32 v5, v13, s10, v190
	v_med3_f32 v7, v14, s10, v190
	v_cvt_pk_fp8_f32 v9, v5, v7 op_sel:[0,0,1]
	v_ashrrev_i32_e32 v7, 31, v6
	v_lshlrev_b64 v[6:7], 7, v[6:7]
	v_lshl_add_u64 v[6:7], s[14:15], 0, v[6:7]
	v_lshl_add_u64 v[6:7], v[6:7], 0, v[2:3]
	v_mul_f32_e32 v5, 0x3c800000, v94
	flat_store_dwordx2 v[6:7], v[8:9]
	v_mul_f32_e32 v7, 0xbfb8aa3b, v5
	v_exp_f32_e32 v7, v7
	v_add_u32_e32 v6, 0x80, v4
	v_add_f32_e32 v7, 1.0, v7
	v_rcp_f32_e32 v7, v7
	s_nop 0
	v_mul_f32_e32 v5, v5, v7
	v_mul_f32_e32 v7, 0x3c800000, v95
	v_mul_f32_e32 v8, 0xbfb8aa3b, v7
	v_exp_f32_e32 v8, v8
	v_mul_f32_e32 v5, v5, v90
	v_mul_f32_e32 v5, 0x3e000000, v5
	v_med3_f32 v5, v5, s10, v190
	v_add_f32_e32 v8, 1.0, v8
	v_rcp_f32_e32 v8, v8
	s_nop 0
	v_mul_f32_e32 v7, v7, v8
	v_mul_f32_e32 v8, 0x3c800000, v96
	v_mul_f32_e32 v9, 0xbfb8aa3b, v8
	v_exp_f32_e32 v9, v9
	v_mul_f32_e32 v7, v7, v91
	v_mul_f32_e32 v7, 0x3e000000, v7
	v_med3_f32 v7, v7, s10, v190
	v_add_f32_e32 v9, 1.0, v9
	v_rcp_f32_e32 v9, v9
	s_nop 0
	v_mul_f32_e32 v8, v8, v9
	v_mul_f32_e32 v8, v8, v92
	v_mul_f32_e32 v9, 0x3e000000, v8
	v_mul_f32_e32 v8, 0x3c800000, v97
	v_mul_f32_e32 v10, 0xbfb8aa3b, v8
	v_exp_f32_e32 v10, v10
	s_nop 0
	v_add_f32_e32 v10, 1.0, v10
	v_rcp_f32_e32 v10, v10
	s_nop 0
	v_mul_f32_e32 v8, v8, v10
	v_mul_f32_e32 v8, v8, v93
	v_mul_f32_e32 v10, 0x3e000000, v8
	v_mul_f32_e32 v8, 0x3c800000, v86
	v_mul_f32_e32 v11, 0xbfb8aa3b, v8
	v_exp_f32_e32 v11, v11
	s_nop 0
	v_add_f32_e32 v11, 1.0, v11
	v_rcp_f32_e32 v11, v11
	s_nop 0
	v_mul_f32_e32 v8, v8, v11
	v_mul_f32_e32 v8, v8, v82
	v_mul_f32_e32 v11, 0x3e000000, v8
	v_mul_f32_e32 v8, 0x3c800000, v87
	v_mul_f32_e32 v12, 0xbfb8aa3b, v8
	v_exp_f32_e32 v12, v12
	s_nop 0
	v_add_f32_e32 v12, 1.0, v12
	v_rcp_f32_e32 v12, v12
	s_nop 0
	v_mul_f32_e32 v8, v8, v12
	v_mul_f32_e32 v8, v8, v83
	v_mul_f32_e32 v12, 0x3e000000, v8
	v_mul_f32_e32 v8, 0x3c800000, v88
	v_mul_f32_e32 v13, 0xbfb8aa3b, v8
	v_exp_f32_e32 v13, v13
	s_nop 0
	v_add_f32_e32 v13, 1.0, v13
	v_rcp_f32_e32 v13, v13
	s_nop 0
	v_mul_f32_e32 v8, v8, v13
	v_mul_f32_e32 v8, v8, v84
	v_mul_f32_e32 v13, 0x3e000000, v8
	v_mul_f32_e32 v8, 0x3c800000, v89
	v_mul_f32_e32 v14, 0xbfb8aa3b, v8
	v_exp_f32_e32 v14, v14
	s_nop 0
	v_add_f32_e32 v14, 1.0, v14
	v_rcp_f32_e32 v14, v14
	s_nop 0
	v_mul_f32_e32 v8, v8, v14
	v_mul_f32_e32 v8, v8, v85
	v_mul_f32_e32 v14, 0x3e000000, v8
	v_mov_b32_e32 v8, v163
	v_cvt_pk_fp8_f32 v8, v5, v7
	v_med3_f32 v5, v9, s10, v190
	v_med3_f32 v7, v10, s10, v190
	v_mov_b32_e32 v9, v163
	v_cvt_pk_fp8_f32 v8, v5, v7 op_sel:[0,0,1]
	v_med3_f32 v5, v11, s10, v190
	v_med3_f32 v7, v12, s10, v190
	v_cvt_pk_fp8_f32 v9, v5, v7
	v_med3_f32 v5, v13, s10, v190
	v_med3_f32 v7, v14, s10, v190
	v_cvt_pk_fp8_f32 v9, v5, v7 op_sel:[0,0,1]
	v_ashrrev_i32_e32 v7, 31, v6
	v_lshlrev_b64 v[6:7], 7, v[6:7]
	v_lshl_add_u64 v[6:7], s[14:15], 0, v[6:7]
	v_lshl_add_u64 v[6:7], v[6:7], 0, v[2:3]
	v_mul_f32_e32 v5, 0x3c800000, v78
	flat_store_dwordx2 v[6:7], v[8:9]
	v_mul_f32_e32 v6, 0xbfb8aa3b, v5
	v_exp_f32_e32 v6, v6
	s_nop 0
	v_add_f32_e32 v6, 1.0, v6
	v_rcp_f32_e32 v6, v6
	s_nop 0
	v_mul_f32_e32 v5, v5, v6
	v_mul_f32_e32 v6, 0x3c800000, v79
	v_mul_f32_e32 v7, 0xbfb8aa3b, v6
	v_exp_f32_e32 v7, v7
	v_mul_f32_e32 v5, v5, v74
	v_mul_f32_e32 v5, 0x3e000000, v5
	v_med3_f32 v5, v5, s10, v190
	v_add_f32_e32 v7, 1.0, v7
	v_rcp_f32_e32 v7, v7
	s_nop 0
	v_mul_f32_e32 v6, v6, v7
	v_mul_f32_e32 v6, v6, v75
	v_mul_f32_e32 v7, 0x3e000000, v6
	v_mul_f32_e32 v6, 0x3c800000, v80
	v_mul_f32_e32 v8, 0xbfb8aa3b, v6
	v_exp_f32_e32 v8, v8
	v_med3_f32 v7, v7, s10, v190
	v_add_f32_e32 v8, 1.0, v8
	v_rcp_f32_e32 v8, v8
	s_nop 0
	v_mul_f32_e32 v6, v6, v8
	v_mul_f32_e32 v6, v6, v76
	v_mul_f32_e32 v9, 0x3e000000, v6
	v_mul_f32_e32 v6, 0x3c800000, v81
	v_mul_f32_e32 v8, 0xbfb8aa3b, v6
	v_exp_f32_e32 v8, v8
	s_nop 0
	v_add_f32_e32 v8, 1.0, v8
	v_rcp_f32_e32 v8, v8
	s_nop 0
	v_mul_f32_e32 v6, v6, v8
	v_mul_f32_e32 v6, v6, v77
	v_mul_f32_e32 v10, 0x3e000000, v6
	v_mul_f32_e32 v6, 0x3c800000, v70
	v_mul_f32_e32 v8, 0xbfb8aa3b, v6
	v_exp_f32_e32 v8, v8
	s_nop 0
	v_add_f32_e32 v8, 1.0, v8
	v_rcp_f32_e32 v8, v8
	s_nop 0
	v_mul_f32_e32 v6, v6, v8
	v_mul_f32_e32 v6, v6, v66
	v_mul_f32_e32 v11, 0x3e000000, v6
	v_mul_f32_e32 v6, 0x3c800000, v71
	v_mul_f32_e32 v8, 0xbfb8aa3b, v6
	v_exp_f32_e32 v8, v8
	s_nop 0
	v_add_f32_e32 v8, 1.0, v8
	v_rcp_f32_e32 v8, v8
	s_nop 0
	v_mul_f32_e32 v6, v6, v8
	v_mul_f32_e32 v6, v6, v67
	v_mul_f32_e32 v12, 0x3e000000, v6
	v_mul_f32_e32 v6, 0x3c800000, v72
	v_mul_f32_e32 v8, 0xbfb8aa3b, v6
	v_exp_f32_e32 v8, v8
	s_nop 0
	v_add_f32_e32 v8, 1.0, v8
	v_rcp_f32_e32 v8, v8
	s_nop 0
	v_mul_f32_e32 v6, v6, v8
	v_mul_f32_e32 v6, v6, v68
	v_mul_f32_e32 v13, 0x3e000000, v6
	v_mul_f32_e32 v6, 0x3c800000, v73
	v_mul_f32_e32 v8, 0xbfb8aa3b, v6
	v_exp_f32_e32 v8, v8
	s_nop 0
	v_add_f32_e32 v8, 1.0, v8
	v_rcp_f32_e32 v8, v8
	s_nop 0
	v_mul_f32_e32 v6, v6, v8
	v_mov_b32_e32 v8, v163
	v_cvt_pk_fp8_f32 v8, v5, v7
	v_med3_f32 v5, v9, s10, v190
	v_med3_f32 v7, v10, s10, v190
	v_mov_b32_e32 v9, v163
	v_cvt_pk_fp8_f32 v8, v5, v7 op_sel:[0,0,1]
	v_med3_f32 v5, v11, s10, v190
	v_med3_f32 v7, v12, s10, v190
	v_cvt_pk_fp8_f32 v9, v5, v7
	v_mul_f32_e32 v6, v6, v69
	v_mul_f32_e32 v14, 0x3e000000, v6
	v_add_u32_e32 v6, 0x90, v4
	v_med3_f32 v5, v13, s10, v190
	v_med3_f32 v7, v14, s10, v190
	v_cvt_pk_fp8_f32 v9, v5, v7 op_sel:[0,0,1]
	v_ashrrev_i32_e32 v7, 31, v6
	v_lshlrev_b64 v[6:7], 7, v[6:7]
	v_lshl_add_u64 v[6:7], s[14:15], 0, v[6:7]
	v_lshl_add_u64 v[6:7], v[6:7], 0, v[2:3]
	v_mul_f32_e32 v5, 0x3c800000, v62
	flat_store_dwordx2 v[6:7], v[8:9]
	v_mul_f32_e32 v6, 0xbfb8aa3b, v5
	v_exp_f32_e32 v6, v6
	s_nop 0
	v_add_f32_e32 v6, 1.0, v6
	v_rcp_f32_e32 v6, v6
	s_nop 0
	v_mul_f32_e32 v5, v5, v6
	v_mul_f32_e32 v6, 0x3c800000, v63
	v_mul_f32_e32 v7, 0xbfb8aa3b, v6
	v_exp_f32_e32 v7, v7
	v_mul_f32_e32 v5, v5, v58
	v_mul_f32_e32 v5, 0x3e000000, v5
	v_med3_f32 v5, v5, s10, v190
	v_add_f32_e32 v7, 1.0, v7
	v_rcp_f32_e32 v7, v7
	s_nop 0
	v_mul_f32_e32 v6, v6, v7
	v_mul_f32_e32 v6, v6, v59
	v_mul_f32_e32 v7, 0x3e000000, v6
	v_mul_f32_e32 v6, 0x3c800000, v64
	v_mul_f32_e32 v8, 0xbfb8aa3b, v6
	v_exp_f32_e32 v8, v8
	v_med3_f32 v7, v7, s10, v190
	v_add_f32_e32 v8, 1.0, v8
	v_rcp_f32_e32 v8, v8
	s_nop 0
	v_mul_f32_e32 v6, v6, v8
	v_mul_f32_e32 v6, v6, v60
	v_mul_f32_e32 v9, 0x3e000000, v6
	v_mul_f32_e32 v6, 0x3c800000, v65
	v_mul_f32_e32 v8, 0xbfb8aa3b, v6
	v_exp_f32_e32 v8, v8
	s_nop 0
	v_add_f32_e32 v8, 1.0, v8
	v_rcp_f32_e32 v8, v8
	s_nop 0
	v_mul_f32_e32 v6, v6, v8
	v_mul_f32_e32 v6, v6, v61
	v_mul_f32_e32 v10, 0x3e000000, v6
	v_mul_f32_e32 v6, 0x3c800000, v54
	v_mul_f32_e32 v8, 0xbfb8aa3b, v6
	v_exp_f32_e32 v8, v8
	s_nop 0
	v_add_f32_e32 v8, 1.0, v8
	v_rcp_f32_e32 v8, v8
	s_nop 0
	v_mul_f32_e32 v6, v6, v8
	v_mul_f32_e32 v6, v6, v50
	v_mul_f32_e32 v11, 0x3e000000, v6
	v_mul_f32_e32 v6, 0x3c800000, v55
	v_mul_f32_e32 v8, 0xbfb8aa3b, v6
	v_exp_f32_e32 v8, v8
	s_nop 0
	v_add_f32_e32 v8, 1.0, v8
	v_rcp_f32_e32 v8, v8
	s_nop 0
	v_mul_f32_e32 v6, v6, v8
	v_mul_f32_e32 v6, v6, v51
	v_mul_f32_e32 v12, 0x3e000000, v6
	v_mul_f32_e32 v6, 0x3c800000, v56
	v_mul_f32_e32 v8, 0xbfb8aa3b, v6
	v_exp_f32_e32 v8, v8
	s_nop 0
	v_add_f32_e32 v8, 1.0, v8
	v_rcp_f32_e32 v8, v8
	s_nop 0
	v_mul_f32_e32 v6, v6, v8
	v_mul_f32_e32 v6, v6, v52
	v_mul_f32_e32 v13, 0x3e000000, v6
	v_mul_f32_e32 v6, 0x3c800000, v57
	v_mul_f32_e32 v8, 0xbfb8aa3b, v6
	v_exp_f32_e32 v8, v8
	s_nop 0
	v_add_f32_e32 v8, 1.0, v8
	v_rcp_f32_e32 v8, v8
	s_nop 0
	v_mul_f32_e32 v6, v6, v8
	v_mov_b32_e32 v8, v163
	v_cvt_pk_fp8_f32 v8, v5, v7
	v_med3_f32 v5, v9, s10, v190
	v_med3_f32 v7, v10, s10, v190
	v_mov_b32_e32 v9, v163
	v_cvt_pk_fp8_f32 v8, v5, v7 op_sel:[0,0,1]
	v_med3_f32 v5, v11, s10, v190
	v_med3_f32 v7, v12, s10, v190
	v_cvt_pk_fp8_f32 v9, v5, v7
	v_mul_f32_e32 v6, v6, v53
	v_mul_f32_e32 v14, 0x3e000000, v6
	v_add_u32_e32 v6, 0xa0, v4
	v_med3_f32 v5, v13, s10, v190
	v_med3_f32 v7, v14, s10, v190
	v_cvt_pk_fp8_f32 v9, v5, v7 op_sel:[0,0,1]
	v_ashrrev_i32_e32 v7, 31, v6
	v_lshlrev_b64 v[6:7], 7, v[6:7]
	v_lshl_add_u64 v[6:7], s[14:15], 0, v[6:7]
	v_lshl_add_u64 v[6:7], v[6:7], 0, v[2:3]
	v_mul_f32_e32 v5, 0x3c800000, v46
	flat_store_dwordx2 v[6:7], v[8:9]
	v_mul_f32_e32 v6, 0xbfb8aa3b, v5
	v_exp_f32_e32 v6, v6
	v_add_u32_e32 v4, 0xb0, v4
	v_add_f32_e32 v6, 1.0, v6
	v_rcp_f32_e32 v6, v6
	s_nop 0
	v_mul_f32_e32 v5, v5, v6
	v_mul_f32_e32 v6, 0x3c800000, v47
	v_mul_f32_e32 v7, 0xbfb8aa3b, v6
	v_exp_f32_e32 v7, v7
	v_mul_f32_e32 v5, v5, v42
	v_mul_f32_e32 v5, 0x3e000000, v5
	v_med3_f32 v5, v5, s10, v190
	v_add_f32_e32 v7, 1.0, v7
	v_rcp_f32_e32 v7, v7
	s_nop 0
	v_mul_f32_e32 v6, v6, v7
	v_mul_f32_e32 v7, 0x3c800000, v48
	v_mul_f32_e32 v8, 0xbfb8aa3b, v7
	v_exp_f32_e32 v8, v8
	v_mul_f32_e32 v6, v6, v43
	v_mul_f32_e32 v6, 0x3e000000, v6
	v_add_f32_e32 v8, 1.0, v8
	v_rcp_f32_e32 v8, v8
	s_nop 0
	v_mul_f32_e32 v7, v7, v8
	v_mul_f32_e32 v8, 0x3c800000, v49
	v_mul_f32_e32 v9, 0xbfb8aa3b, v8
	v_exp_f32_e32 v9, v9
	v_mul_f32_e32 v7, v7, v44
	v_mul_f32_e32 v7, 0x3e000000, v7
	v_add_f32_e32 v9, 1.0, v9
	v_rcp_f32_e32 v9, v9
	s_nop 0
	v_mul_f32_e32 v8, v8, v9
	v_mul_f32_e32 v9, 0x3c800000, v38
	v_mul_f32_e32 v10, 0xbfb8aa3b, v9
	v_exp_f32_e32 v10, v10
	v_mul_f32_e32 v8, v8, v45
	v_mul_f32_e32 v8, 0x3e000000, v8
	v_add_f32_e32 v10, 1.0, v10
	v_rcp_f32_e32 v10, v10
	s_nop 0
	v_mul_f32_e32 v9, v9, v10
	v_mul_f32_e32 v10, 0x3c800000, v39
	v_mul_f32_e32 v11, 0xbfb8aa3b, v10
	v_exp_f32_e32 v11, v11
	v_mul_f32_e32 v9, v9, v34
	v_mul_f32_e32 v9, 0x3e000000, v9
	v_add_f32_e32 v11, 1.0, v11
	v_rcp_f32_e32 v11, v11
	s_nop 0
	v_mul_f32_e32 v10, v10, v11
	v_mul_f32_e32 v11, 0x3c800000, v40
	v_mul_f32_e32 v12, 0xbfb8aa3b, v11
	v_exp_f32_e32 v12, v12
	v_mul_f32_e32 v10, v10, v35
	v_mul_f32_e32 v10, 0x3e000000, v10
	v_add_f32_e32 v12, 1.0, v12
	v_rcp_f32_e32 v12, v12
	s_nop 0
	v_mul_f32_e32 v11, v11, v12
	v_mul_f32_e32 v12, 0x3c800000, v41
	v_mul_f32_e32 v13, 0xbfb8aa3b, v12
	v_exp_f32_e32 v13, v13
	v_mul_f32_e32 v11, v11, v36
	v_mul_f32_e32 v11, 0x3e000000, v11
	v_add_f32_e32 v13, 1.0, v13
	v_rcp_f32_e32 v13, v13
	s_nop 0
	v_mul_f32_e32 v12, v12, v13
	v_med3_f32 v13, v6, s10, v190
	v_mov_b32_e32 v6, v163
	v_cvt_pk_fp8_f32 v6, v5, v13
	v_med3_f32 v5, v7, s10, v190
	v_med3_f32 v7, v8, s10, v190
	v_med3_f32 v8, v10, s10, v190
	v_cvt_pk_fp8_f32 v6, v5, v7 op_sel:[0,0,1]
	v_med3_f32 v5, v9, s10, v190
	v_mov_b32_e32 v7, v163
	v_cvt_pk_fp8_f32 v7, v5, v8
	v_mul_f32_e32 v12, v12, v37
	v_mul_f32_e32 v12, 0x3e000000, v12
	v_med3_f32 v5, v11, s10, v190
	v_med3_f32 v8, v12, s10, v190
	v_cvt_pk_fp8_f32 v7, v5, v8 op_sel:[0,0,1]
	v_ashrrev_i32_e32 v5, 31, v4
	v_lshlrev_b64 v[4:5], 7, v[4:5]
	v_lshl_add_u64 v[4:5], s[14:15], 0, v[4:5]
	v_lshl_add_u64 v[2:3], v[4:5], 0, v[2:3]
	flat_store_dwordx2 v[2:3], v[6:7]
	s_cbranch_vccz .LBB0_2030
	s_waitcnt vmcnt(0)
	s_cmpk_gt_u32 s42, 0xff
	s_cbranch_scc1 .LBB0_1976
	s_barrier
	s_branch .LBB0_1976

.LBB0_2108:
	ds_read_b128 v[2:5], v169
	ds_read_b128 v[6:9], v169 offset:1024
	ds_read_b128 v[10:13], v169 offset:2048
	ds_read_b128 v[14:17], v169 offset:3072
	s_add_u32 s0, s30, 0x4000
	s_addc_u32 s1, s31, 0
	s_cmp_eq_u32 s53, 4
	s_cselect_b32 s38, s49, s0
	s_cselect_b32 s39, s23, s1
	s_cselect_b32 s34, s50, s51
	s_cselect_b32 s35, s21, s52
	s_add_u32 s36, s38, 0x8000
	s_addc_u32 s37, s39, 0
	v_lshl_add_u64 v[162:163], s[30:31], 0, v[156:157]
	s_add_i32 m0, s10, 0xc000
	ds_read_b128 v[174:177], v170
	ds_read_b128 v[178:181], v170 offset:1024
	ds_read_b128 v[182:185], v170 offset:2048
	ds_read_b128 v[186:189], v170 offset:3072
	ds_read_b128 v[190:193], v170 offset:4096
	ds_read_b128 v[194:197], v170 offset:5120
	ds_read_b128 v[198:201], v170 offset:6144
	ds_read_b128 v[202:205], v170 offset:7168
	global_load_lds_dwordx4 v[162:163], off
	v_lshl_add_u64 v[162:163], s[30:31], 0, v[154:155]
	s_add_i32 m0, s10, 0xe000
	s_nop 0
	global_load_lds_dwordx4 v[162:163], off
	s_waitcnt lgkmcnt(8)
	s_waitcnt vmcnt(10)
	s_barrier
	s_waitcnt lgkmcnt(0)
	s_waitcnt lgkmcnt(0)
	v_mfma_scale_f32_16x16x128_f8f6f4 v[142:145], v[2:9], v[174:181], v[142:145], v171, v171 op_sel_hi:[0,0,0]
	v_mfma_scale_f32_16x16x128_f8f6f4 v[138:141], v[10:17], v[174:181], v[138:141], v171, v171 op_sel_hi:[0,0,0]
	v_mfma_scale_f32_16x16x128_f8f6f4 v[126:129], v[2:9], v[182:189], v[126:129], v171, v171 op_sel_hi:[0,0,0]
	v_mfma_scale_f32_16x16x128_f8f6f4 v[122:125], v[10:17], v[182:189], v[122:125], v171, v171 op_sel_hi:[0,0,0]
	v_mfma_scale_f32_16x16x128_f8f6f4 v[110:113], v[2:9], v[190:197], v[110:113], v171, v171 op_sel_hi:[0,0,0]
	v_mfma_scale_f32_16x16x128_f8f6f4 v[106:109], v[10:17], v[190:197], v[106:109], v171, v171 op_sel_hi:[0,0,0]
	v_mfma_scale_f32_16x16x128_f8f6f4 v[94:97], v[2:9], v[198:205], v[94:97], v171, v171 op_sel_hi:[0,0,0]
	v_mfma_scale_f32_16x16x128_f8f6f4 v[90:93], v[10:17], v[198:205], v[90:93], v171, v171 op_sel_hi:[0,0,0]
	s_barrier
	s_add_i32 s0, s45, s9
	v_lshl_add_u64 v[162:163], s[34:35], 0, v[150:151]
	s_mov_b32 m0, s0
	ds_read_b128 v[206:209], v172
	ds_read_b128 v[210:213], v172 offset:1024
	ds_read_b128 v[214:217], v172 offset:2048
	ds_read_b128 v[218:221], v172 offset:3072
	global_load_lds_dwordx4 v[162:163], off
	v_lshl_add_u64 v[164:165], s[34:35], 0, v[146:147]
	s_add_i32 m0, s0, 0x2000
	s_nop 0
	global_load_lds_dwordx4 v[164:165], off
	s_waitcnt vmcnt(10)
	s_barrier
	s_waitcnt lgkmcnt(0)
	s_waitcnt lgkmcnt(0)
	v_mfma_scale_f32_16x16x128_f8f6f4 v[134:137], v[206:213], v[174:181], v[134:137], v171, v171 op_sel_hi:[0,0,0]
	v_mfma_scale_f32_16x16x128_f8f6f4 v[130:133], v[214:221], v[174:181], v[130:133], v171, v171 op_sel_hi:[0,0,0]
	v_mfma_scale_f32_16x16x128_f8f6f4 v[118:121], v[206:213], v[182:189], v[118:121], v171, v171 op_sel_hi:[0,0,0]
	v_mfma_scale_f32_16x16x128_f8f6f4 v[114:117], v[214:221], v[182:189], v[114:117], v171, v171 op_sel_hi:[0,0,0]
	v_mfma_scale_f32_16x16x128_f8f6f4 v[102:105], v[206:213], v[190:197], v[102:105], v171, v171 op_sel_hi:[0,0,0]
	v_mfma_scale_f32_16x16x128_f8f6f4 v[98:101], v[214:221], v[190:197], v[98:101], v171, v171 op_sel_hi:[0,0,0]
	v_mfma_scale_f32_16x16x128_f8f6f4 v[86:89], v[206:213], v[198:205], v[86:89], v171, v171 op_sel_hi:[0,0,0]
	v_mfma_scale_f32_16x16x128_f8f6f4 v[82:85], v[214:221], v[198:205], v[82:85], v171, v171 op_sel_hi:[0,0,0]
	s_mov_b32 m0, s10
	v_lshl_add_u64 v[222:223], s[38:39], 0, v[152:153]
	s_barrier
	ds_read_b128 v[174:177], v170 offset:16384
	ds_read_b128 v[178:181], v170 offset:17408
	ds_read_b128 v[182:185], v170 offset:18432
	ds_read_b128 v[186:189], v170 offset:19456
	ds_read_b128 v[190:193], v170 offset:20480
	ds_read_b128 v[194:197], v170 offset:21504
	ds_read_b128 v[198:201], v170 offset:22528
	ds_read_b128 v[202:205], v170 offset:23552
	global_load_lds_dwordx4 v[222:223], off
	v_lshl_add_u64 v[222:223], s[38:39], 0, v[148:149]
	s_mov_b32 m0, s11
	s_nop 0
	global_load_lds_dwordx4 v[222:223], off
	s_waitcnt vmcnt(10)
	s_barrier
	s_waitcnt lgkmcnt(0)
	s_waitcnt lgkmcnt(0)
	v_mfma_scale_f32_16x16x128_f8f6f4 v[78:81], v[2:9], v[174:181], v[78:81], v171, v171 op_sel_hi:[0,0,0]
	v_mfma_scale_f32_16x16x128_f8f6f4 v[74:77], v[10:17], v[174:181], v[74:77], v171, v171 op_sel_hi:[0,0,0]
	v_mfma_scale_f32_16x16x128_f8f6f4 v[62:65], v[2:9], v[182:189], v[62:65], v171, v171 op_sel_hi:[0,0,0]
	v_mfma_scale_f32_16x16x128_f8f6f4 v[58:61], v[10:17], v[182:189], v[58:61], v171, v171 op_sel_hi:[0,0,0]
	v_mfma_scale_f32_16x16x128_f8f6f4 v[46:49], v[2:9], v[190:197], v[46:49], v171, v171 op_sel_hi:[0,0,0]
	v_mfma_scale_f32_16x16x128_f8f6f4 v[42:45], v[10:17], v[190:197], v[42:45], v171, v171 op_sel_hi:[0,0,0]
	v_mfma_scale_f32_16x16x128_f8f6f4 v[30:33], v[2:9], v[198:205], v[30:33], v171, v171 op_sel_hi:[0,0,0]
	v_mfma_scale_f32_16x16x128_f8f6f4 v[26:29], v[10:17], v[198:205], v[26:29], v171, v171 op_sel_hi:[0,0,0]
	s_barrier
	s_add_u32 s0, s34, 0x20000
	s_addc_u32 s1, s35, 0
	s_add_i32 s54, s46, s9
	v_lshl_add_u64 v[2:3], s[0:1], 0, v[150:151]
	s_mov_b32 m0, s54
	s_nop 0
	global_load_lds_dwordx4 v[2:3], off
	v_lshl_add_u64 v[2:3], s[0:1], 0, v[146:147]
	s_add_i32 m0, s54, 0x2000
	s_nop 0
	global_load_lds_dwordx4 v[2:3], off
	s_waitcnt vmcnt(10)
	s_barrier
	v_mfma_scale_f32_16x16x128_f8f6f4 v[70:73], v[206:213], v[174:181], v[70:73], v171, v171 op_sel_hi:[0,0,0]
	v_mfma_scale_f32_16x16x128_f8f6f4 v[66:69], v[214:221], v[174:181], v[66:69], v171, v171 op_sel_hi:[0,0,0]
	v_mfma_scale_f32_16x16x128_f8f6f4 v[54:57], v[206:213], v[182:189], v[54:57], v171, v171 op_sel_hi:[0,0,0]
	v_mfma_scale_f32_16x16x128_f8f6f4 v[50:53], v[214:221], v[182:189], v[50:53], v171, v171 op_sel_hi:[0,0,0]
	v_mfma_scale_f32_16x16x128_f8f6f4 v[38:41], v[206:213], v[190:197], v[38:41], v171, v171 op_sel_hi:[0,0,0]
	v_mfma_scale_f32_16x16x128_f8f6f4 v[34:37], v[214:221], v[190:197], v[34:37], v171, v171 op_sel_hi:[0,0,0]
	v_mfma_scale_f32_16x16x128_f8f6f4 v[22:25], v[206:213], v[198:205], v[22:25], v171, v171 op_sel_hi:[0,0,0]
	v_mfma_scale_f32_16x16x128_f8f6f4 v[18:21], v[214:221], v[198:205], v[18:21], v171, v171 op_sel_hi:[0,0,0]
	s_add_i32 s54, 0, 0x18000
	v_add_u32_e32 v14, s54, v168
	s_barrier
	ds_read_b128 v[2:5], v14
	ds_read_b128 v[6:9], v14 offset:1024
	ds_read_b128 v[10:13], v14 offset:2048
	ds_read_b128 v[14:17], v14 offset:3072
	s_add_u32 s0, s38, 0x4000
	s_addc_u32 s1, s39, 0
	s_mov_b32 m0, s19
	v_lshl_add_u64 v[206:207], s[0:1], 0, v[152:153]
	ds_read_b128 v[174:177], v170 offset:32768
	ds_read_b128 v[178:181], v170 offset:33792
	ds_read_b128 v[182:185], v170 offset:34816
	ds_read_b128 v[186:189], v170 offset:35840
	ds_read_b128 v[190:193], v170 offset:36864
	ds_read_b128 v[194:197], v170 offset:37888
	ds_read_b128 v[198:201], v170 offset:38912
	ds_read_b128 v[202:205], v170 offset:39936
	global_load_lds_dwordx4 v[206:207], off
	v_lshl_add_u64 v[206:207], s[0:1], 0, v[148:149]
	s_mov_b32 m0, s29
	s_nop 0
	global_load_lds_dwordx4 v[206:207], off
	s_waitcnt lgkmcnt(8)
	s_waitcnt vmcnt(10)
	s_barrier
	s_waitcnt lgkmcnt(0)
	s_waitcnt lgkmcnt(0)
	v_mfma_scale_f32_16x16x128_f8f6f4 v[142:145], v[2:9], v[174:181], v[142:145], v171, v171 op_sel_hi:[0,0,0]
	v_mfma_scale_f32_16x16x128_f8f6f4 v[138:141], v[10:17], v[174:181], v[138:141], v171, v171 op_sel_hi:[0,0,0]
	v_mfma_scale_f32_16x16x128_f8f6f4 v[126:129], v[2:9], v[182:189], v[126:129], v171, v171 op_sel_hi:[0,0,0]
	v_mfma_scale_f32_16x16x128_f8f6f4 v[122:125], v[10:17], v[182:189], v[122:125], v171, v171 op_sel_hi:[0,0,0]
	v_mfma_scale_f32_16x16x128_f8f6f4 v[110:113], v[2:9], v[190:197], v[110:113], v171, v171 op_sel_hi:[0,0,0]
	v_mfma_scale_f32_16x16x128_f8f6f4 v[106:109], v[10:17], v[190:197], v[106:109], v171, v171 op_sel_hi:[0,0,0]
	v_mfma_scale_f32_16x16x128_f8f6f4 v[94:97], v[2:9], v[198:205], v[94:97], v171, v171 op_sel_hi:[0,0,0]
	v_mfma_scale_f32_16x16x128_f8f6f4 v[90:93], v[10:17], v[198:205], v[90:93], v171, v171 op_sel_hi:[0,0,0]
	s_barrier
	s_add_i32 s38, 0, 0x1c000
	s_add_i32 s0, s54, s9
	v_add_u32_e32 v218, s38, v168
	v_lshl_add_u64 v[162:163], v[162:163], 0, s[16:17]
	s_mov_b32 m0, s0
	ds_read_b128 v[206:209], v218
	ds_read_b128 v[210:213], v218 offset:1024
	ds_read_b128 v[214:217], v218 offset:2048
	ds_read_b128 v[218:221], v218 offset:3072
	global_load_lds_dwordx4 v[162:163], off
	v_lshl_add_u64 v[162:163], v[164:165], 0, s[16:17]
	s_add_i32 m0, s0, 0x2000
	s_nop 0
	global_load_lds_dwordx4 v[162:163], off
	s_waitcnt vmcnt(10)
	s_barrier
	s_waitcnt lgkmcnt(0)
	s_waitcnt lgkmcnt(0)
	v_mfma_scale_f32_16x16x128_f8f6f4 v[134:137], v[206:213], v[174:181], v[134:137], v171, v171 op_sel_hi:[0,0,0]
	v_mfma_scale_f32_16x16x128_f8f6f4 v[130:133], v[214:221], v[174:181], v[130:133], v171, v171 op_sel_hi:[0,0,0]
	v_mfma_scale_f32_16x16x128_f8f6f4 v[118:121], v[206:213], v[182:189], v[118:121], v171, v171 op_sel_hi:[0,0,0]
	v_mfma_scale_f32_16x16x128_f8f6f4 v[114:117], v[214:221], v[182:189], v[114:117], v171, v171 op_sel_hi:[0,0,0]
	v_mfma_scale_f32_16x16x128_f8f6f4 v[102:105], v[206:213], v[190:197], v[102:105], v171, v171 op_sel_hi:[0,0,0]
	v_mfma_scale_f32_16x16x128_f8f6f4 v[98:101], v[214:221], v[190:197], v[98:101], v171, v171 op_sel_hi:[0,0,0]
	v_mfma_scale_f32_16x16x128_f8f6f4 v[86:89], v[206:213], v[198:205], v[86:89], v171, v171 op_sel_hi:[0,0,0]
	v_mfma_scale_f32_16x16x128_f8f6f4 v[82:85], v[214:221], v[198:205], v[82:85], v171, v171 op_sel_hi:[0,0,0]
	s_mov_b32 m0, s43
	v_lshl_add_u64 v[162:163], s[36:37], 0, v[152:153]
	s_barrier
	ds_read_b128 v[174:177], v170 offset:49152
	ds_read_b128 v[178:181], v170 offset:50176
	ds_read_b128 v[182:185], v170 offset:51200
	ds_read_b128 v[186:189], v170 offset:52224
	ds_read_b128 v[190:193], v170 offset:53248
	ds_read_b128 v[194:197], v170 offset:54272
	ds_read_b128 v[198:201], v170 offset:55296
	ds_read_b128 v[202:205], v170 offset:56320
	global_load_lds_dwordx4 v[162:163], off
	v_lshl_add_u64 v[162:163], s[36:37], 0, v[148:149]
	s_mov_b32 m0, s44
	s_nop 0
	global_load_lds_dwordx4 v[162:163], off
	s_waitcnt vmcnt(10)
	s_barrier
	s_waitcnt lgkmcnt(0)
	s_waitcnt lgkmcnt(0)
	v_mfma_scale_f32_16x16x128_f8f6f4 v[78:81], v[2:9], v[174:181], v[78:81], v171, v171 op_sel_hi:[0,0,0]
	v_mfma_scale_f32_16x16x128_f8f6f4 v[74:77], v[10:17], v[174:181], v[74:77], v171, v171 op_sel_hi:[0,0,0]
	v_mfma_scale_f32_16x16x128_f8f6f4 v[62:65], v[2:9], v[182:189], v[62:65], v171, v171 op_sel_hi:[0,0,0]
	v_mfma_scale_f32_16x16x128_f8f6f4 v[58:61], v[10:17], v[182:189], v[58:61], v171, v171 op_sel_hi:[0,0,0]
	v_mfma_scale_f32_16x16x128_f8f6f4 v[46:49], v[2:9], v[190:197], v[46:49], v171, v171 op_sel_hi:[0,0,0]
	v_mfma_scale_f32_16x16x128_f8f6f4 v[42:45], v[10:17], v[190:197], v[42:45], v171, v171 op_sel_hi:[0,0,0]
	v_mfma_scale_f32_16x16x128_f8f6f4 v[30:33], v[2:9], v[198:205], v[30:33], v171, v171 op_sel_hi:[0,0,0]
	v_mfma_scale_f32_16x16x128_f8f6f4 v[26:29], v[10:17], v[198:205], v[26:29], v171, v171 op_sel_hi:[0,0,0]
	s_barrier
	s_add_u32 s0, s34, 0x20080
	s_addc_u32 s1, s35, 0
	s_add_i32 s34, s38, s9
	v_lshl_add_u64 v[2:3], s[0:1], 0, v[150:151]
	s_mov_b32 m0, s34
	s_nop 0
	global_load_lds_dwordx4 v[2:3], off
	v_lshl_add_u64 v[2:3], s[0:1], 0, v[146:147]
	s_add_i32 m0, s34, 0x2000
	s_nop 0
	global_load_lds_dwordx4 v[2:3], off
	s_waitcnt vmcnt(10)
	s_barrier
	v_mfma_scale_f32_16x16x128_f8f6f4 v[70:73], v[206:213], v[174:181], v[70:73], v171, v171 op_sel_hi:[0,0,0]
	v_mfma_scale_f32_16x16x128_f8f6f4 v[66:69], v[214:221], v[174:181], v[66:69], v171, v171 op_sel_hi:[0,0,0]
	v_mfma_scale_f32_16x16x128_f8f6f4 v[54:57], v[206:213], v[182:189], v[54:57], v171, v171 op_sel_hi:[0,0,0]
	v_mfma_scale_f32_16x16x128_f8f6f4 v[50:53], v[214:221], v[182:189], v[50:53], v171, v171 op_sel_hi:[0,0,0]
	v_mfma_scale_f32_16x16x128_f8f6f4 v[38:41], v[206:213], v[190:197], v[38:41], v171, v171 op_sel_hi:[0,0,0]
	v_mfma_scale_f32_16x16x128_f8f6f4 v[34:37], v[214:221], v[190:197], v[34:37], v171, v171 op_sel_hi:[0,0,0]
	v_mfma_scale_f32_16x16x128_f8f6f4 v[22:25], v[206:213], v[198:205], v[22:25], v171, v171 op_sel_hi:[0,0,0]
	v_mfma_scale_f32_16x16x128_f8f6f4 v[18:21], v[214:221], v[198:205], v[18:21], v171, v171 op_sel_hi:[0,0,0]
	s_add_i32 s53, s53, 2
	s_add_u32 s51, s51, 0x100
	s_addc_u32 s52, s52, 0
	s_add_u32 s30, s30, 0x10000
	s_addc_u32 s31, s31, 0
	s_cmp_gt_u32 s53, 5
	s_barrier
	s_cbranch_scc0 .LBB0_2108
	v_pk_mul_f32 v[10:11], v[142:143], s[18:19] op_sel_hi:[1,0]
	v_pk_mul_f32 v[8:9], v[144:145], s[18:19] op_sel_hi:[1,0]
	v_med3_f32 v5, v10, s47, v173
	v_med3_f32 v11, v11, s47, v173
	v_mov_b32_e32 v10, 0
	v_cvt_pk_fp8_f32 v10, v5, v11
	v_mov_b32_e32 v3, v166
	v_mov_b32_e32 v2, v167
	s_lshl_b32 s0, s48, 8
	v_pk_mul_f32 v[14:15], v[138:139], s[18:19] op_sel_hi:[1,0]
	v_med3_f32 v5, v8, s47, v173
	v_med3_f32 v8, v9, s47, v173
	s_nop 15
	s_nop 15
	s_or_b32 s0, s0, s42
	v_cvt_pk_fp8_f32 v10, v5, v8 op_sel:[0,0,1]
	v_med3_f32 v5, v14, s47, v173
	v_med3_f32 v8, v15, s47, v173
	v_mov_b32_e32 v11, 0
	v_lshl_add_u32 v2, v2, 3, s0
	s_lshl_b32 s0, s28, 8
	v_cvt_pk_fp8_f32 v11, v5, v8
	s_add_i32 s0, s0, s41
	v_add_u32_e32 v4, s0, v3
	v_pk_mul_f32 v[12:13], v[140:141], s[18:19] op_sel_hi:[1,0]
	v_mov_b32_e32 v6, v4
	v_med3_f32 v5, v12, s47, v173
	v_med3_f32 v8, v13, s47, v173
	v_cvt_pk_fp8_f32 v11, v5, v8 op_sel:[0,0,1]
	v_ashrrev_i32_e32 v7, 31, v6
	v_lshlrev_b64 v[6:7], 10, v[6:7]
	v_ashrrev_i32_e32 v3, 31, v2
	v_lshl_add_u64 v[6:7], s[14:15], 0, v[6:7]
	v_lshl_add_u64 v[6:7], v[6:7], 0, v[2:3]
	flat_store_dwordx2 v[6:7], v[10:11]
	v_pk_mul_f32 v[10:11], v[134:135], s[18:19] op_sel_hi:[1,0]
	v_pk_mul_f32 v[8:9], v[136:137], s[18:19] op_sel_hi:[1,0]
	v_med3_f32 v5, v10, s47, v173
	v_med3_f32 v11, v11, s47, v173
	v_mov_b32_e32 v10, 0
	v_cvt_pk_fp8_f32 v10, v5, v11
	v_pk_mul_f32 v[14:15], v[130:131], s[18:19] op_sel_hi:[1,0]
	v_med3_f32 v5, v8, s47, v173
	v_med3_f32 v8, v9, s47, v173
	v_cvt_pk_fp8_f32 v10, v5, v8 op_sel:[0,0,1]
	v_med3_f32 v5, v14, s47, v173
	v_med3_f32 v8, v15, s47, v173
	v_mov_b32_e32 v11, 0
	v_cvt_pk_fp8_f32 v11, v5, v8
	v_pk_mul_f32 v[12:13], v[132:133], s[18:19] op_sel_hi:[1,0]
	v_pk_mul_f32 v[14:15], v[122:123], s[18:19] op_sel_hi:[1,0]
	v_med3_f32 v5, v12, s47, v173
	v_med3_f32 v8, v13, s47, v173
	v_cvt_pk_fp8_f32 v11, v5, v8 op_sel:[0,0,1]
	v_pk_mul_f32 v[8:9], v[128:129], s[18:19] op_sel_hi:[1,0]
	v_pk_mul_f32 v[12:13], v[124:125], s[18:19] op_sel_hi:[1,0]
	s_and_b64 vcc, exec, s[12:13]
	flat_store_dwordx2 v[6:7], v[10:11] offset:128
	v_pk_mul_f32 v[10:11], v[126:127], s[18:19] op_sel_hi:[1,0]
	v_add_u32_e32 v6, 16, v4
	v_med3_f32 v5, v10, s47, v173
	v_med3_f32 v11, v11, s47, v173
	v_mov_b32_e32 v10, 0
	v_cvt_pk_fp8_f32 v10, v5, v11
	v_med3_f32 v5, v8, s47, v173
	v_med3_f32 v8, v9, s47, v173
	v_mov_b32_e32 v11, 0
	v_cvt_pk_fp8_f32 v10, v5, v8 op_sel:[0,0,1]
	v_med3_f32 v5, v14, s47, v173
	v_med3_f32 v8, v15, s47, v173
	v_cvt_pk_fp8_f32 v11, v5, v8
	v_med3_f32 v5, v12, s47, v173
	v_med3_f32 v8, v13, s47, v173
	v_cvt_pk_fp8_f32 v11, v5, v8 op_sel:[0,0,1]
	v_ashrrev_i32_e32 v7, 31, v6
	v_lshlrev_b64 v[6:7], 10, v[6:7]
	v_lshl_add_u64 v[6:7], s[14:15], 0, v[6:7]
	v_lshl_add_u64 v[6:7], v[6:7], 0, v[2:3]
	flat_store_dwordx2 v[6:7], v[10:11]
	v_pk_mul_f32 v[10:11], v[118:119], s[18:19] op_sel_hi:[1,0]
	v_pk_mul_f32 v[8:9], v[120:121], s[18:19] op_sel_hi:[1,0]
	v_med3_f32 v5, v10, s47, v173
	v_med3_f32 v11, v11, s47, v173
	v_mov_b32_e32 v10, 0
	v_cvt_pk_fp8_f32 v10, v5, v11
	v_pk_mul_f32 v[14:15], v[114:115], s[18:19] op_sel_hi:[1,0]
	v_med3_f32 v5, v8, s47, v173
	v_med3_f32 v8, v9, s47, v173
	v_cvt_pk_fp8_f32 v10, v5, v8 op_sel:[0,0,1]
	v_med3_f32 v5, v14, s47, v173
	v_med3_f32 v8, v15, s47, v173
	v_mov_b32_e32 v11, 0
	v_cvt_pk_fp8_f32 v11, v5, v8
	v_pk_mul_f32 v[12:13], v[116:117], s[18:19] op_sel_hi:[1,0]
	v_pk_mul_f32 v[14:15], v[106:107], s[18:19] op_sel_hi:[1,0]
	v_med3_f32 v5, v12, s47, v173
	v_med3_f32 v8, v13, s47, v173
	v_cvt_pk_fp8_f32 v11, v5, v8 op_sel:[0,0,1]
	v_pk_mul_f32 v[8:9], v[112:113], s[18:19] op_sel_hi:[1,0]
	v_pk_mul_f32 v[12:13], v[108:109], s[18:19] op_sel_hi:[1,0]
	s_mov_b32 s48, s20
	flat_store_dwordx2 v[6:7], v[10:11] offset:128
	v_pk_mul_f32 v[10:11], v[110:111], s[18:19] op_sel_hi:[1,0]
	v_add_u32_e32 v6, 32, v4
	v_med3_f32 v5, v10, s47, v173
	v_med3_f32 v11, v11, s47, v173
	v_mov_b32_e32 v10, 0
	v_cvt_pk_fp8_f32 v10, v5, v11
	v_med3_f32 v5, v8, s47, v173
	v_med3_f32 v8, v9, s47, v173
	v_mov_b32_e32 v11, 0
	v_cvt_pk_fp8_f32 v10, v5, v8 op_sel:[0,0,1]
	v_med3_f32 v5, v14, s47, v173
	v_med3_f32 v8, v15, s47, v173
	v_cvt_pk_fp8_f32 v11, v5, v8
	v_med3_f32 v5, v12, s47, v173
	v_med3_f32 v8, v13, s47, v173
	v_cvt_pk_fp8_f32 v11, v5, v8 op_sel:[0,0,1]
	v_ashrrev_i32_e32 v7, 31, v6
	v_lshlrev_b64 v[6:7], 10, v[6:7]
	v_lshl_add_u64 v[6:7], s[14:15], 0, v[6:7]
	v_lshl_add_u64 v[6:7], v[6:7], 0, v[2:3]
	flat_store_dwordx2 v[6:7], v[10:11]
	v_pk_mul_f32 v[10:11], v[102:103], s[18:19] op_sel_hi:[1,0]
	v_pk_mul_f32 v[8:9], v[104:105], s[18:19] op_sel_hi:[1,0]
	v_med3_f32 v5, v10, s47, v173
	v_med3_f32 v11, v11, s47, v173
	v_mov_b32_e32 v10, 0
	v_cvt_pk_fp8_f32 v10, v5, v11
	v_pk_mul_f32 v[14:15], v[98:99], s[18:19] op_sel_hi:[1,0]
	v_med3_f32 v5, v8, s47, v173
	v_med3_f32 v8, v9, s47, v173
	v_cvt_pk_fp8_f32 v10, v5, v8 op_sel:[0,0,1]
	v_med3_f32 v5, v14, s47, v173
	v_med3_f32 v8, v15, s47, v173
	v_mov_b32_e32 v11, 0
	v_cvt_pk_fp8_f32 v11, v5, v8
	v_pk_mul_f32 v[12:13], v[100:101], s[18:19] op_sel_hi:[1,0]
	v_pk_mul_f32 v[14:15], v[90:91], s[18:19] op_sel_hi:[1,0]
	v_med3_f32 v5, v12, s47, v173
	v_med3_f32 v8, v13, s47, v173
	v_cvt_pk_fp8_f32 v11, v5, v8 op_sel:[0,0,1]
	v_pk_mul_f32 v[8:9], v[96:97], s[18:19] op_sel_hi:[1,0]
	v_pk_mul_f32 v[12:13], v[92:93], s[18:19] op_sel_hi:[1,0]
	s_mov_b32 s28, s22
	flat_store_dwordx2 v[6:7], v[10:11] offset:128
	v_pk_mul_f32 v[10:11], v[94:95], s[18:19] op_sel_hi:[1,0]
	v_add_u32_e32 v6, 48, v4
	v_med3_f32 v5, v10, s47, v173
	v_med3_f32 v11, v11, s47, v173
	v_mov_b32_e32 v10, 0
	v_cvt_pk_fp8_f32 v10, v5, v11
	v_med3_f32 v5, v8, s47, v173
	v_med3_f32 v8, v9, s47, v173
	v_mov_b32_e32 v11, 0
	v_cvt_pk_fp8_f32 v10, v5, v8 op_sel:[0,0,1]
	v_med3_f32 v5, v14, s47, v173
	v_med3_f32 v8, v15, s47, v173
	v_cvt_pk_fp8_f32 v11, v5, v8
	v_med3_f32 v5, v12, s47, v173
	v_med3_f32 v8, v13, s47, v173
	v_cvt_pk_fp8_f32 v11, v5, v8 op_sel:[0,0,1]
	v_ashrrev_i32_e32 v7, 31, v6
	v_lshlrev_b64 v[6:7], 10, v[6:7]
	v_lshl_add_u64 v[6:7], s[14:15], 0, v[6:7]
	v_lshl_add_u64 v[6:7], v[6:7], 0, v[2:3]
	flat_store_dwordx2 v[6:7], v[10:11]
	v_pk_mul_f32 v[10:11], v[86:87], s[18:19] op_sel_hi:[1,0]
	v_pk_mul_f32 v[8:9], v[88:89], s[18:19] op_sel_hi:[1,0]
	v_med3_f32 v5, v10, s47, v173
	v_med3_f32 v11, v11, s47, v173
	v_mov_b32_e32 v10, 0
	v_cvt_pk_fp8_f32 v10, v5, v11
	v_pk_mul_f32 v[14:15], v[82:83], s[18:19] op_sel_hi:[1,0]
	v_med3_f32 v5, v8, s47, v173
	v_med3_f32 v8, v9, s47, v173
	v_cvt_pk_fp8_f32 v10, v5, v8 op_sel:[0,0,1]
	v_med3_f32 v5, v14, s47, v173
	v_med3_f32 v8, v15, s47, v173
	v_mov_b32_e32 v11, 0
	v_cvt_pk_fp8_f32 v11, v5, v8
	v_pk_mul_f32 v[12:13], v[84:85], s[18:19] op_sel_hi:[1,0]
	v_pk_mul_f32 v[14:15], v[74:75], s[18:19] op_sel_hi:[1,0]
	v_med3_f32 v5, v12, s47, v173
	v_med3_f32 v8, v13, s47, v173
	v_cvt_pk_fp8_f32 v11, v5, v8 op_sel:[0,0,1]
	v_pk_mul_f32 v[8:9], v[80:81], s[18:19] op_sel_hi:[1,0]
	v_pk_mul_f32 v[12:13], v[76:77], s[18:19] op_sel_hi:[1,0]
	s_mov_b64 s[30:31], s[26:27]
	flat_store_dwordx2 v[6:7], v[10:11] offset:128
	v_pk_mul_f32 v[10:11], v[78:79], s[18:19] op_sel_hi:[1,0]
	v_add_u32_e32 v6, 0x80, v4
	v_med3_f32 v5, v10, s47, v173
	v_med3_f32 v11, v11, s47, v173
	v_mov_b32_e32 v10, 0
	v_cvt_pk_fp8_f32 v10, v5, v11
	v_med3_f32 v5, v8, s47, v173
	v_med3_f32 v8, v9, s47, v173
	v_mov_b32_e32 v11, 0
	v_cvt_pk_fp8_f32 v10, v5, v8 op_sel:[0,0,1]
	v_med3_f32 v5, v14, s47, v173
	v_med3_f32 v8, v15, s47, v173
	v_cvt_pk_fp8_f32 v11, v5, v8
	v_med3_f32 v5, v12, s47, v173
	v_med3_f32 v8, v13, s47, v173
	v_cvt_pk_fp8_f32 v11, v5, v8 op_sel:[0,0,1]
	v_ashrrev_i32_e32 v7, 31, v6
	v_lshlrev_b64 v[6:7], 10, v[6:7]
	v_lshl_add_u64 v[6:7], s[14:15], 0, v[6:7]
	v_lshl_add_u64 v[6:7], v[6:7], 0, v[2:3]
	flat_store_dwordx2 v[6:7], v[10:11]
	v_pk_mul_f32 v[10:11], v[70:71], s[18:19] op_sel_hi:[1,0]
	v_pk_mul_f32 v[8:9], v[72:73], s[18:19] op_sel_hi:[1,0]
	v_med3_f32 v5, v10, s47, v173
	v_med3_f32 v11, v11, s47, v173
	v_mov_b32_e32 v10, 0
	v_cvt_pk_fp8_f32 v10, v5, v11
	v_pk_mul_f32 v[14:15], v[66:67], s[18:19] op_sel_hi:[1,0]
	v_med3_f32 v5, v8, s47, v173
	v_med3_f32 v8, v9, s47, v173
	v_cvt_pk_fp8_f32 v10, v5, v8 op_sel:[0,0,1]
	v_med3_f32 v5, v14, s47, v173
	v_med3_f32 v8, v15, s47, v173
	v_mov_b32_e32 v11, 0
	v_cvt_pk_fp8_f32 v11, v5, v8
	v_pk_mul_f32 v[12:13], v[68:69], s[18:19] op_sel_hi:[1,0]
	v_pk_mul_f32 v[14:15], v[58:59], s[18:19] op_sel_hi:[1,0]
	v_med3_f32 v5, v12, s47, v173
	v_med3_f32 v8, v13, s47, v173
	v_cvt_pk_fp8_f32 v11, v5, v8 op_sel:[0,0,1]
	v_pk_mul_f32 v[8:9], v[64:65], s[18:19] op_sel_hi:[1,0]
	v_pk_mul_f32 v[12:13], v[60:61], s[18:19] op_sel_hi:[1,0]
	s_mov_b64 s[34:35], s[24:25]
	flat_store_dwordx2 v[6:7], v[10:11] offset:128
	v_pk_mul_f32 v[10:11], v[62:63], s[18:19] op_sel_hi:[1,0]
	v_add_u32_e32 v6, 0x90, v4
	v_med3_f32 v5, v10, s47, v173
	v_med3_f32 v11, v11, s47, v173
	v_mov_b32_e32 v10, 0
	v_cvt_pk_fp8_f32 v10, v5, v11
	v_med3_f32 v5, v8, s47, v173
	v_med3_f32 v8, v9, s47, v173
	v_mov_b32_e32 v11, 0
	v_cvt_pk_fp8_f32 v10, v5, v8 op_sel:[0,0,1]
	v_med3_f32 v5, v14, s47, v173
	v_med3_f32 v8, v15, s47, v173
	v_cvt_pk_fp8_f32 v11, v5, v8
	v_med3_f32 v5, v12, s47, v173
	v_med3_f32 v8, v13, s47, v173
	v_cvt_pk_fp8_f32 v11, v5, v8 op_sel:[0,0,1]
	v_ashrrev_i32_e32 v7, 31, v6
	v_lshlrev_b64 v[6:7], 10, v[6:7]
	v_lshl_add_u64 v[6:7], s[14:15], 0, v[6:7]
	v_lshl_add_u64 v[6:7], v[6:7], 0, v[2:3]
	flat_store_dwordx2 v[6:7], v[10:11]
	v_pk_mul_f32 v[10:11], v[54:55], s[18:19] op_sel_hi:[1,0]
	v_pk_mul_f32 v[8:9], v[56:57], s[18:19] op_sel_hi:[1,0]
	v_med3_f32 v5, v10, s47, v173
	v_med3_f32 v11, v11, s47, v173
	v_mov_b32_e32 v10, 0
	v_cvt_pk_fp8_f32 v10, v5, v11
	v_pk_mul_f32 v[14:15], v[50:51], s[18:19] op_sel_hi:[1,0]
	v_med3_f32 v5, v8, s47, v173
	v_med3_f32 v8, v9, s47, v173
	v_cvt_pk_fp8_f32 v10, v5, v8 op_sel:[0,0,1]
	v_med3_f32 v5, v14, s47, v173
	v_med3_f32 v8, v15, s47, v173
	v_mov_b32_e32 v11, 0
	v_cvt_pk_fp8_f32 v11, v5, v8
	v_pk_mul_f32 v[12:13], v[52:53], s[18:19] op_sel_hi:[1,0]
	v_pk_mul_f32 v[14:15], v[42:43], s[18:19] op_sel_hi:[1,0]
	v_med3_f32 v5, v12, s47, v173
	v_med3_f32 v8, v13, s47, v173
	v_cvt_pk_fp8_f32 v11, v5, v8 op_sel:[0,0,1]
	v_pk_mul_f32 v[8:9], v[48:49], s[18:19] op_sel_hi:[1,0]
	v_pk_mul_f32 v[12:13], v[44:45], s[18:19] op_sel_hi:[1,0]
	flat_store_dwordx2 v[6:7], v[10:11] offset:128
	v_pk_mul_f32 v[10:11], v[46:47], s[18:19] op_sel_hi:[1,0]
	v_add_u32_e32 v6, 0xa0, v4
	v_med3_f32 v5, v10, s47, v173
	v_med3_f32 v11, v11, s47, v173
	v_mov_b32_e32 v10, 0
	v_cvt_pk_fp8_f32 v10, v5, v11
	v_med3_f32 v5, v8, s47, v173
	v_med3_f32 v8, v9, s47, v173
	v_mov_b32_e32 v11, 0
	v_cvt_pk_fp8_f32 v10, v5, v8 op_sel:[0,0,1]
	v_med3_f32 v5, v14, s47, v173
	v_med3_f32 v8, v15, s47, v173
	v_cvt_pk_fp8_f32 v11, v5, v8
	v_med3_f32 v5, v12, s47, v173
	v_med3_f32 v8, v13, s47, v173
	v_cvt_pk_fp8_f32 v11, v5, v8 op_sel:[0,0,1]
	v_ashrrev_i32_e32 v7, 31, v6
	v_lshlrev_b64 v[6:7], 10, v[6:7]
	v_lshl_add_u64 v[6:7], s[14:15], 0, v[6:7]
	v_lshl_add_u64 v[6:7], v[6:7], 0, v[2:3]
	flat_store_dwordx2 v[6:7], v[10:11]
	v_pk_mul_f32 v[10:11], v[38:39], s[18:19] op_sel_hi:[1,0]
	v_pk_mul_f32 v[8:9], v[40:41], s[18:19] op_sel_hi:[1,0]
	v_med3_f32 v5, v10, s47, v173
	v_med3_f32 v11, v11, s47, v173
	v_mov_b32_e32 v10, 0
	v_cvt_pk_fp8_f32 v10, v5, v11
	v_pk_mul_f32 v[14:15], v[34:35], s[18:19] op_sel_hi:[1,0]
	v_med3_f32 v5, v8, s47, v173
	v_med3_f32 v8, v9, s47, v173
	v_cvt_pk_fp8_f32 v10, v5, v8 op_sel:[0,0,1]
	v_med3_f32 v5, v14, s47, v173
	v_med3_f32 v8, v15, s47, v173
	v_mov_b32_e32 v11, 0
	v_cvt_pk_fp8_f32 v11, v5, v8
	v_pk_mul_f32 v[12:13], v[36:37], s[18:19] op_sel_hi:[1,0]
	v_add_u32_e32 v4, 0xb0, v4
	v_med3_f32 v5, v12, s47, v173
	v_med3_f32 v8, v13, s47, v173
	v_cvt_pk_fp8_f32 v11, v5, v8 op_sel:[0,0,1]
	v_pk_mul_f32 v[8:9], v[28:29], s[18:19] op_sel_hi:[1,0]
	flat_store_dwordx2 v[6:7], v[10:11] offset:128
	v_pk_mul_f32 v[6:7], v[30:31], s[18:19] op_sel_hi:[1,0]
	v_pk_mul_f32 v[10:11], v[26:27], s[18:19] op_sel_hi:[1,0]
	v_ashrrev_i32_e32 v5, 31, v4
	v_med3_f32 v12, v6, s47, v173
	v_med3_f32 v7, v7, s47, v173
	v_mov_b32_e32 v6, 0
	v_lshlrev_b64 v[4:5], 10, v[4:5]
	v_cvt_pk_fp8_f32 v6, v12, v7
	v_lshl_add_u64 v[4:5], s[14:15], 0, v[4:5]
	v_lshl_add_u64 v[2:3], v[4:5], 0, v[2:3]
	v_pk_mul_f32 v[4:5], v[32:33], s[18:19] op_sel_hi:[1,0]
	v_mov_b32_e32 v7, 0
	v_med3_f32 v4, v4, s47, v173
	v_med3_f32 v5, v5, s47, v173
	v_cvt_pk_fp8_f32 v6, v4, v5 op_sel:[0,0,1]
	v_med3_f32 v4, v10, s47, v173
	v_med3_f32 v5, v11, s47, v173
	v_cvt_pk_fp8_f32 v7, v4, v5
	v_med3_f32 v4, v8, s47, v173
	v_med3_f32 v5, v9, s47, v173
	v_pk_mul_f32 v[10:11], v[18:19], s[18:19] op_sel_hi:[1,0]
	v_cvt_pk_fp8_f32 v7, v4, v5 op_sel:[0,0,1]
	v_pk_mul_f32 v[4:5], v[24:25], s[18:19] op_sel_hi:[1,0]
	v_pk_mul_f32 v[8:9], v[20:21], s[18:19] op_sel_hi:[1,0]
	v_med3_f32 v4, v4, s47, v173
	flat_store_dwordx2 v[2:3], v[6:7]
	v_pk_mul_f32 v[6:7], v[22:23], s[18:19] op_sel_hi:[1,0]
	v_med3_f32 v5, v5, s47, v173
	v_med3_f32 v12, v6, s47, v173
	v_med3_f32 v7, v7, s47, v173
	v_mov_b32_e32 v6, 0
	v_cvt_pk_fp8_f32 v6, v12, v7
	v_mov_b32_e32 v7, 0
	v_cvt_pk_fp8_f32 v6, v4, v5 op_sel:[0,0,1]
	v_med3_f32 v4, v10, s47, v173
	v_med3_f32 v5, v11, s47, v173
	v_cvt_pk_fp8_f32 v7, v4, v5
	v_med3_f32 v4, v8, s47, v173
	v_med3_f32 v5, v9, s47, v173
	v_cvt_pk_fp8_f32 v7, v4, v5 op_sel:[0,0,1]
	flat_store_dwordx2 v[2:3], v[6:7] offset:128
	s_cbranch_vccz .LBB0_2101
	s_waitcnt vmcnt(0)
	s_cmpk_gt_u32 s4, 0xff
	s_cbranch_scc1 .LBB0_2112
	s_barrier

.LBB0_2245:
	ds_read_b128 v[150:153], v146
	ds_read_b128 v[154:157], v146 offset:1024
	ds_read_b128 v[158:161], v146 offset:2048
	ds_read_b128 v[162:165], v146 offset:3072
	s_add_u32 s0, s30, 0xfffc0080
	s_addc_u32 s1, s31, -1
	s_cmp_eq_u32 s61, 12
	s_cselect_b32 s37, s55, s1
	s_cselect_b32 s36, s56, s0
	s_cselect_b32 s35, s57, s60
	s_cselect_b32 s34, s58, s59
	s_mov_b32 m0, s46
	v_lshl_add_u64 v[198:199], s[30:31], 0, v[140:141]
	ds_read_b128 v[166:169], v147
	ds_read_b128 v[170:173], v147 offset:1024
	ds_read_b128 v[174:177], v147 offset:2048
	ds_read_b128 v[178:181], v147 offset:3072
	ds_read_b128 v[182:185], v147 offset:4096
	ds_read_b128 v[186:189], v147 offset:5120
	ds_read_b128 v[190:193], v147 offset:6144
	ds_read_b128 v[194:197], v147 offset:7168
	global_load_lds_dwordx4 v[198:199], off
	v_lshl_add_u64 v[198:199], s[30:31], 0, v[138:139]
	s_mov_b32 m0, s47
	s_nop 0
	global_load_lds_dwordx4 v[198:199], off
	s_waitcnt lgkmcnt(8)
	s_waitcnt vmcnt(10)
	s_barrier
	s_waitcnt lgkmcnt(0)
	s_waitcnt lgkmcnt(0)
	v_mfma_f32_16x16x32_bf16 v[126:129], v[150:153], v[166:169], v[126:129]
	v_mfma_f32_16x16x32_bf16 v[122:125], v[158:161], v[166:169], v[122:125]
	v_mfma_f32_16x16x32_bf16 v[118:121], v[150:153], v[174:177], v[118:121]
	v_mfma_f32_16x16x32_bf16 v[114:117], v[158:161], v[174:177], v[114:117]
	v_mfma_f32_16x16x32_bf16 v[102:105], v[150:153], v[182:185], v[102:105]
	v_mfma_f32_16x16x32_bf16 v[98:101], v[158:161], v[182:185], v[98:101]
	v_mfma_f32_16x16x32_bf16 v[86:89], v[150:153], v[190:193], v[86:89]
	v_mfma_f32_16x16x32_bf16 v[82:85], v[158:161], v[190:193], v[82:85]
	v_mfma_f32_16x16x32_bf16 v[126:129], v[154:157], v[170:173], v[126:129]
	v_mfma_f32_16x16x32_bf16 v[122:125], v[162:165], v[170:173], v[122:125]
	v_mfma_f32_16x16x32_bf16 v[118:121], v[154:157], v[178:181], v[118:121]
	v_mfma_f32_16x16x32_bf16 v[114:117], v[162:165], v[178:181], v[114:117]
	v_mfma_f32_16x16x32_bf16 v[102:105], v[154:157], v[186:189], v[102:105]
	v_mfma_f32_16x16x32_bf16 v[98:101], v[162:165], v[186:189], v[98:101]
	v_mfma_f32_16x16x32_bf16 v[86:89], v[154:157], v[194:197], v[86:89]
	v_mfma_f32_16x16x32_bf16 v[82:85], v[162:165], v[194:197], v[82:85]
	s_barrier
	s_mov_b32 m0, s48
	v_lshl_add_u64 v[214:215], s[34:35], 0, v[134:135]
	ds_read_b128 v[198:201], v148
	ds_read_b128 v[202:205], v148 offset:1024
	ds_read_b128 v[206:209], v148 offset:2048
	ds_read_b128 v[210:213], v148 offset:3072
	global_load_lds_dwordx4 v[214:215], off
	v_lshl_add_u64 v[216:217], s[34:35], 0, v[130:131]
	s_mov_b32 m0, s49
	s_nop 0
	global_load_lds_dwordx4 v[216:217], off
	s_waitcnt vmcnt(10)
	s_barrier
	s_waitcnt lgkmcnt(0)
	s_waitcnt lgkmcnt(0)
	v_mfma_f32_16x16x32_bf16 v[110:113], v[198:201], v[166:169], v[110:113]
	v_mfma_f32_16x16x32_bf16 v[106:109], v[206:209], v[166:169], v[106:109]
	v_mfma_f32_16x16x32_bf16 v[94:97], v[198:201], v[174:177], v[94:97]
	v_mfma_f32_16x16x32_bf16 v[90:93], v[206:209], v[174:177], v[90:93]
	v_mfma_f32_16x16x32_bf16 v[78:81], v[198:201], v[182:185], v[78:81]
	v_mfma_f32_16x16x32_bf16 v[74:77], v[206:209], v[182:185], v[74:77]
	v_mfma_f32_16x16x32_bf16 v[70:73], v[198:201], v[190:193], v[70:73]
	v_mfma_f32_16x16x32_bf16 v[66:69], v[206:209], v[190:193], v[66:69]
	v_mfma_f32_16x16x32_bf16 v[110:113], v[202:205], v[170:173], v[110:113]
	v_mfma_f32_16x16x32_bf16 v[106:109], v[210:213], v[170:173], v[106:109]
	v_mfma_f32_16x16x32_bf16 v[94:97], v[202:205], v[178:181], v[94:97]
	v_mfma_f32_16x16x32_bf16 v[90:93], v[210:213], v[178:181], v[90:93]
	v_mfma_f32_16x16x32_bf16 v[78:81], v[202:205], v[186:189], v[78:81]
	v_mfma_f32_16x16x32_bf16 v[74:77], v[210:213], v[186:189], v[74:77]
	v_mfma_f32_16x16x32_bf16 v[70:73], v[202:205], v[194:197], v[70:73]
	v_mfma_f32_16x16x32_bf16 v[66:69], v[210:213], v[194:197], v[66:69]
	s_mov_b32 m0, s9
	v_lshl_add_u64 v[218:219], s[36:37], 0, v[136:137]
	s_barrier
	ds_read_b128 v[166:169], v147 offset:16384
	ds_read_b128 v[170:173], v147 offset:17408
	ds_read_b128 v[174:177], v147 offset:18432
	ds_read_b128 v[178:181], v147 offset:19456
	ds_read_b128 v[182:185], v147 offset:20480
	ds_read_b128 v[186:189], v147 offset:21504
	ds_read_b128 v[190:193], v147 offset:22528
	ds_read_b128 v[194:197], v147 offset:23552
	global_load_lds_dwordx4 v[218:219], off
	v_lshl_add_u64 v[220:221], s[36:37], 0, v[132:133]
	s_mov_b32 m0, s21
	s_nop 0
	global_load_lds_dwordx4 v[220:221], off
	s_waitcnt vmcnt(10)
	s_barrier
	s_waitcnt lgkmcnt(0)
	s_waitcnt lgkmcnt(0)
	v_mfma_f32_16x16x32_bf16 v[62:65], v[150:153], v[166:169], v[62:65]
	v_mfma_f32_16x16x32_bf16 v[58:61], v[158:161], v[166:169], v[58:61]
	v_mfma_f32_16x16x32_bf16 v[54:57], v[150:153], v[174:177], v[54:57]
	v_mfma_f32_16x16x32_bf16 v[50:53], v[158:161], v[174:177], v[50:53]
	v_mfma_f32_16x16x32_bf16 v[38:41], v[150:153], v[182:185], v[38:41]
	v_mfma_f32_16x16x32_bf16 v[34:37], v[158:161], v[182:185], v[34:37]
	v_mfma_f32_16x16x32_bf16 v[22:25], v[150:153], v[190:193], v[22:25]
	v_mfma_f32_16x16x32_bf16 v[18:21], v[158:161], v[190:193], v[18:21]
	v_mfma_f32_16x16x32_bf16 v[62:65], v[154:157], v[170:173], v[62:65]
	v_mfma_f32_16x16x32_bf16 v[58:61], v[162:165], v[170:173], v[58:61]
	v_mfma_f32_16x16x32_bf16 v[54:57], v[154:157], v[178:181], v[54:57]
	v_mfma_f32_16x16x32_bf16 v[50:53], v[162:165], v[178:181], v[50:53]
	v_mfma_f32_16x16x32_bf16 v[38:41], v[154:157], v[186:189], v[38:41]
	v_mfma_f32_16x16x32_bf16 v[34:37], v[162:165], v[186:189], v[34:37]
	v_mfma_f32_16x16x32_bf16 v[22:25], v[154:157], v[194:197], v[22:25]
	v_mfma_f32_16x16x32_bf16 v[18:21], v[162:165], v[194:197], v[18:21]
	s_barrier
	s_add_u32 s0, s34, 0x40000
	s_addc_u32 s1, s35, 0
	s_add_i32 s62, s44, s8
	v_lshl_add_u64 v[150:151], s[0:1], 0, v[134:135]
	s_mov_b32 m0, s62
	s_nop 0
	global_load_lds_dwordx4 v[150:151], off
	v_lshl_add_u64 v[150:151], s[0:1], 0, v[130:131]
	s_add_i32 m0, s62, 0x2000
	s_nop 0
	global_load_lds_dwordx4 v[150:151], off
	s_waitcnt vmcnt(10)
	s_barrier
	v_mfma_f32_16x16x32_bf16 v[46:49], v[198:201], v[166:169], v[46:49]
	v_mfma_f32_16x16x32_bf16 v[42:45], v[206:209], v[166:169], v[42:45]
	v_mfma_f32_16x16x32_bf16 v[30:33], v[198:201], v[174:177], v[30:33]
	v_mfma_f32_16x16x32_bf16 v[26:29], v[206:209], v[174:177], v[26:29]
	v_mfma_f32_16x16x32_bf16 v[14:17], v[198:201], v[182:185], v[14:17]
	v_mfma_f32_16x16x32_bf16 v[10:13], v[206:209], v[182:185], v[10:13]
	v_mfma_f32_16x16x32_bf16 v[6:9], v[198:201], v[190:193], v[6:9]
	v_mfma_f32_16x16x32_bf16 v[2:5], v[206:209], v[190:193], v[2:5]
	v_mfma_f32_16x16x32_bf16 v[46:49], v[202:205], v[170:173], v[46:49]
	v_mfma_f32_16x16x32_bf16 v[42:45], v[210:213], v[170:173], v[42:45]
	v_mfma_f32_16x16x32_bf16 v[30:33], v[202:205], v[178:181], v[30:33]
	v_mfma_f32_16x16x32_bf16 v[26:29], v[210:213], v[178:181], v[26:29]
	v_mfma_f32_16x16x32_bf16 v[14:17], v[202:205], v[186:189], v[14:17]
	v_mfma_f32_16x16x32_bf16 v[10:13], v[210:213], v[186:189], v[10:13]
	v_mfma_f32_16x16x32_bf16 v[6:9], v[202:205], v[194:197], v[6:9]
	v_mfma_f32_16x16x32_bf16 v[2:5], v[210:213], v[194:197], v[2:5]
	s_add_i32 s62, 0, 0x18000
	v_add_u32_e32 v149, s62, v145
	s_barrier
	ds_read_b128 v[150:153], v149
	ds_read_b128 v[154:157], v149 offset:1024
	ds_read_b128 v[158:161], v149 offset:2048
	ds_read_b128 v[162:165], v149 offset:3072
	s_add_u32 s0, s36, 0x40000
	s_addc_u32 s1, s37, 0
	s_mov_b32 m0, s38
	v_lshl_add_u64 v[198:199], s[0:1], 0, v[136:137]
	ds_read_b128 v[166:169], v147 offset:32768
	ds_read_b128 v[170:173], v147 offset:33792
	ds_read_b128 v[174:177], v147 offset:34816
	ds_read_b128 v[178:181], v147 offset:35840
	ds_read_b128 v[182:185], v147 offset:36864
	ds_read_b128 v[186:189], v147 offset:37888
	ds_read_b128 v[190:193], v147 offset:38912
	ds_read_b128 v[194:197], v147 offset:39936
	global_load_lds_dwordx4 v[198:199], off
	v_lshl_add_u64 v[198:199], s[0:1], 0, v[132:133]
	s_mov_b32 m0, s39
	s_nop 0
	global_load_lds_dwordx4 v[198:199], off
	s_waitcnt lgkmcnt(8)
	s_waitcnt vmcnt(10)
	s_barrier
	s_waitcnt lgkmcnt(0)
	s_waitcnt lgkmcnt(0)
	v_mfma_f32_16x16x32_bf16 v[126:129], v[150:153], v[166:169], v[126:129]
	v_mfma_f32_16x16x32_bf16 v[122:125], v[158:161], v[166:169], v[122:125]
	v_mfma_f32_16x16x32_bf16 v[118:121], v[150:153], v[174:177], v[118:121]
	v_mfma_f32_16x16x32_bf16 v[114:117], v[158:161], v[174:177], v[114:117]
	v_mfma_f32_16x16x32_bf16 v[102:105], v[150:153], v[182:185], v[102:105]
	v_mfma_f32_16x16x32_bf16 v[98:101], v[158:161], v[182:185], v[98:101]
	v_mfma_f32_16x16x32_bf16 v[86:89], v[150:153], v[190:193], v[86:89]
	v_mfma_f32_16x16x32_bf16 v[82:85], v[158:161], v[190:193], v[82:85]
	v_mfma_f32_16x16x32_bf16 v[126:129], v[154:157], v[170:173], v[126:129]
	v_mfma_f32_16x16x32_bf16 v[122:125], v[162:165], v[170:173], v[122:125]
	v_mfma_f32_16x16x32_bf16 v[118:121], v[154:157], v[178:181], v[118:121]
	v_mfma_f32_16x16x32_bf16 v[114:117], v[162:165], v[178:181], v[114:117]
	v_mfma_f32_16x16x32_bf16 v[102:105], v[154:157], v[186:189], v[102:105]
	v_mfma_f32_16x16x32_bf16 v[98:101], v[162:165], v[186:189], v[98:101]
	v_mfma_f32_16x16x32_bf16 v[86:89], v[154:157], v[194:197], v[86:89]
	v_mfma_f32_16x16x32_bf16 v[82:85], v[162:165], v[194:197], v[82:85]
	s_barrier
	s_add_i32 s36, 0, 0x1c000
	s_add_i32 s0, s62, s8
	v_add_u32_e32 v149, s36, v145
	v_lshl_add_u64 v[214:215], v[214:215], 0, s[24:25]
	s_mov_b32 m0, s0
	ds_read_b128 v[198:201], v149
	ds_read_b128 v[202:205], v149 offset:1024
	ds_read_b128 v[206:209], v149 offset:2048
	ds_read_b128 v[210:213], v149 offset:3072
	global_load_lds_dwordx4 v[214:215], off
	v_lshl_add_u64 v[214:215], v[216:217], 0, s[24:25]
	s_add_i32 m0, s0, 0x2000
	s_nop 0
	global_load_lds_dwordx4 v[214:215], off
	s_waitcnt vmcnt(10)
	s_barrier
	s_waitcnt lgkmcnt(0)
	s_waitcnt lgkmcnt(0)
	v_mfma_f32_16x16x32_bf16 v[110:113], v[198:201], v[166:169], v[110:113]
	v_mfma_f32_16x16x32_bf16 v[106:109], v[206:209], v[166:169], v[106:109]
	v_mfma_f32_16x16x32_bf16 v[94:97], v[198:201], v[174:177], v[94:97]
	v_mfma_f32_16x16x32_bf16 v[90:93], v[206:209], v[174:177], v[90:93]
	v_mfma_f32_16x16x32_bf16 v[78:81], v[198:201], v[182:185], v[78:81]
	v_mfma_f32_16x16x32_bf16 v[74:77], v[206:209], v[182:185], v[74:77]
	v_mfma_f32_16x16x32_bf16 v[70:73], v[198:201], v[190:193], v[70:73]
	v_mfma_f32_16x16x32_bf16 v[66:69], v[206:209], v[190:193], v[66:69]
	v_mfma_f32_16x16x32_bf16 v[110:113], v[202:205], v[170:173], v[110:113]
	v_mfma_f32_16x16x32_bf16 v[106:109], v[210:213], v[170:173], v[106:109]
	v_mfma_f32_16x16x32_bf16 v[94:97], v[202:205], v[178:181], v[94:97]
	v_mfma_f32_16x16x32_bf16 v[90:93], v[210:213], v[178:181], v[90:93]
	v_mfma_f32_16x16x32_bf16 v[78:81], v[202:205], v[186:189], v[78:81]
	v_mfma_f32_16x16x32_bf16 v[74:77], v[210:213], v[186:189], v[74:77]
	v_mfma_f32_16x16x32_bf16 v[70:73], v[202:205], v[194:197], v[70:73]
	v_mfma_f32_16x16x32_bf16 v[66:69], v[210:213], v[194:197], v[66:69]
	s_mov_b32 m0, s42
	v_lshl_add_u64 v[214:215], v[218:219], 0, s[24:25]
	s_barrier
	ds_read_b128 v[166:169], v147 offset:49152
	ds_read_b128 v[170:173], v147 offset:50176
	ds_read_b128 v[174:177], v147 offset:51200
	ds_read_b128 v[178:181], v147 offset:52224
	ds_read_b128 v[182:185], v147 offset:53248
	ds_read_b128 v[186:189], v147 offset:54272
	ds_read_b128 v[190:193], v147 offset:55296
	ds_read_b128 v[194:197], v147 offset:56320
	global_load_lds_dwordx4 v[214:215], off
	v_lshl_add_u64 v[214:215], v[220:221], 0, s[24:25]
	s_mov_b32 m0, s43
	s_nop 0
	global_load_lds_dwordx4 v[214:215], off
	s_waitcnt vmcnt(10)
	s_barrier
	s_waitcnt lgkmcnt(0)
	s_waitcnt lgkmcnt(0)
	v_mfma_f32_16x16x32_bf16 v[62:65], v[150:153], v[166:169], v[62:65]
	v_mfma_f32_16x16x32_bf16 v[58:61], v[158:161], v[166:169], v[58:61]
	v_mfma_f32_16x16x32_bf16 v[54:57], v[150:153], v[174:177], v[54:57]
	v_mfma_f32_16x16x32_bf16 v[50:53], v[158:161], v[174:177], v[50:53]
	v_mfma_f32_16x16x32_bf16 v[38:41], v[150:153], v[182:185], v[38:41]
	v_mfma_f32_16x16x32_bf16 v[34:37], v[158:161], v[182:185], v[34:37]
	v_mfma_f32_16x16x32_bf16 v[22:25], v[150:153], v[190:193], v[22:25]
	v_mfma_f32_16x16x32_bf16 v[18:21], v[158:161], v[190:193], v[18:21]
	v_mfma_f32_16x16x32_bf16 v[62:65], v[154:157], v[170:173], v[62:65]
	v_mfma_f32_16x16x32_bf16 v[58:61], v[162:165], v[170:173], v[58:61]
	v_mfma_f32_16x16x32_bf16 v[54:57], v[154:157], v[178:181], v[54:57]
	v_mfma_f32_16x16x32_bf16 v[50:53], v[162:165], v[178:181], v[50:53]
	v_mfma_f32_16x16x32_bf16 v[38:41], v[154:157], v[186:189], v[38:41]
	v_mfma_f32_16x16x32_bf16 v[34:37], v[162:165], v[186:189], v[34:37]
	v_mfma_f32_16x16x32_bf16 v[22:25], v[154:157], v[194:197], v[22:25]
	v_mfma_f32_16x16x32_bf16 v[18:21], v[162:165], v[194:197], v[18:21]
	s_barrier
	s_add_u32 s0, s34, 0x40080
	s_addc_u32 s1, s35, 0
	s_add_i32 s34, s36, s8
	v_lshl_add_u64 v[150:151], s[0:1], 0, v[134:135]
	s_mov_b32 m0, s34
	s_nop 0
	global_load_lds_dwordx4 v[150:151], off
	v_lshl_add_u64 v[150:151], s[0:1], 0, v[130:131]
	s_add_i32 m0, s34, 0x2000
	s_nop 0
	global_load_lds_dwordx4 v[150:151], off
	s_waitcnt vmcnt(10)
	s_barrier
	v_mfma_f32_16x16x32_bf16 v[46:49], v[198:201], v[166:169], v[46:49]
	v_mfma_f32_16x16x32_bf16 v[42:45], v[206:209], v[166:169], v[42:45]
	v_mfma_f32_16x16x32_bf16 v[30:33], v[198:201], v[174:177], v[30:33]
	v_mfma_f32_16x16x32_bf16 v[26:29], v[206:209], v[174:177], v[26:29]
	v_mfma_f32_16x16x32_bf16 v[14:17], v[198:201], v[182:185], v[14:17]
	v_mfma_f32_16x16x32_bf16 v[10:13], v[206:209], v[182:185], v[10:13]
	v_mfma_f32_16x16x32_bf16 v[6:9], v[198:201], v[190:193], v[6:9]
	v_mfma_f32_16x16x32_bf16 v[2:5], v[206:209], v[190:193], v[2:5]
	v_mfma_f32_16x16x32_bf16 v[46:49], v[202:205], v[170:173], v[46:49]
	v_mfma_f32_16x16x32_bf16 v[42:45], v[210:213], v[170:173], v[42:45]
	v_mfma_f32_16x16x32_bf16 v[30:33], v[202:205], v[178:181], v[30:33]
	v_mfma_f32_16x16x32_bf16 v[26:29], v[210:213], v[178:181], v[26:29]
	v_mfma_f32_16x16x32_bf16 v[14:17], v[202:205], v[186:189], v[14:17]
	v_mfma_f32_16x16x32_bf16 v[10:13], v[210:213], v[186:189], v[10:13]
	v_mfma_f32_16x16x32_bf16 v[6:9], v[202:205], v[194:197], v[6:9]
	v_mfma_f32_16x16x32_bf16 v[2:5], v[210:213], v[194:197], v[2:5]
	s_add_i32 s61, s61, 2
	s_add_u32 s59, s59, 0x100
	s_addc_u32 s60, s60, 0
	s_add_u32 s30, s30, 0x100
	s_addc_u32 s31, s31, 0
	s_cmp_gt_u32 s61, 13
	s_barrier
	s_cbranch_scc0 .LBB0_2245
	v_mov_b32_e32 v149, v143
	v_mov_b32_e32 v150, v144
	s_lshl_b32 s0, s53, 8
	s_or_b32 s0, s0, s41
	v_lshl_add_u32 v150, v150, 3, s0
	s_lshl_b32 s0, s54, 8
	s_add_i32 s0, s0, s40
	v_add_u32_e32 v149, s0, v149
	v_ashrrev_i32_e32 v151, 31, v150
	v_mov_b32_e32 v152, v149
	v_lshl_add_u64 v[150:151], v[150:151], 1, s[18:19]
	v_cvt_pk_bf16_f32 v126, v126, v127
	v_mad_i64_i32 v[152:153], s[0:1], v152, s45, v[150:151]
	v_cvt_pk_bf16_f32 v127, v128, v129
	v_cvt_pk_bf16_f32 v128, v122, v123
	v_cvt_pk_bf16_f32 v129, v124, v125
	v_cvt_pk_bf16_f32 v110, v110, v111
	v_cvt_pk_bf16_f32 v111, v112, v113
	v_cvt_pk_bf16_f32 v112, v106, v107
	v_cvt_pk_bf16_f32 v113, v108, v109
	v_add_u32_e32 v106, 16, v149
	flat_store_dwordx4 v[152:153], v[126:129]
	flat_store_dwordx4 v[152:153], v[110:113] offset:256
	v_cvt_pk_bf16_f32 v107, v120, v121
	v_cvt_pk_bf16_f32 v108, v114, v115
	v_mad_i64_i32 v[110:111], s[0:1], v106, s45, v[150:151]
	v_cvt_pk_bf16_f32 v106, v118, v119
	v_cvt_pk_bf16_f32 v109, v116, v117
	v_cvt_pk_bf16_f32 v94, v94, v95
	v_cvt_pk_bf16_f32 v95, v96, v97
	v_cvt_pk_bf16_f32 v96, v90, v91
	v_cvt_pk_bf16_f32 v97, v92, v93
	v_add_u32_e32 v90, 32, v149
	flat_store_dwordx4 v[110:111], v[106:109]
	flat_store_dwordx4 v[110:111], v[94:97] offset:256
	v_cvt_pk_bf16_f32 v91, v104, v105
	v_cvt_pk_bf16_f32 v92, v98, v99
	v_mad_i64_i32 v[94:95], s[0:1], v90, s45, v[150:151]
	v_cvt_pk_bf16_f32 v90, v102, v103
	v_cvt_pk_bf16_f32 v93, v100, v101
	v_cvt_pk_bf16_f32 v78, v78, v79
	v_cvt_pk_bf16_f32 v79, v80, v81
	v_cvt_pk_bf16_f32 v80, v74, v75
	v_cvt_pk_bf16_f32 v81, v76, v77
	v_add_u32_e32 v74, 48, v149
	flat_store_dwordx4 v[94:95], v[90:93]
	flat_store_dwordx4 v[94:95], v[78:81] offset:256
	v_cvt_pk_bf16_f32 v75, v88, v89
	v_cvt_pk_bf16_f32 v76, v82, v83
	v_mad_i64_i32 v[78:79], s[0:1], v74, s45, v[150:151]
	v_cvt_pk_bf16_f32 v74, v86, v87
	v_cvt_pk_bf16_f32 v77, v84, v85
	v_cvt_pk_bf16_f32 v70, v70, v71
	v_cvt_pk_bf16_f32 v71, v72, v73
	v_cvt_pk_bf16_f32 v72, v66, v67
	v_cvt_pk_bf16_f32 v73, v68, v69
	v_add_u32_e32 v66, 0x80, v149
	flat_store_dwordx4 v[78:79], v[74:77]
	flat_store_dwordx4 v[78:79], v[70:73] offset:256
	v_cvt_pk_bf16_f32 v62, v62, v63
	v_mad_i64_i32 v[66:67], s[0:1], v66, s45, v[150:151]
	v_cvt_pk_bf16_f32 v63, v64, v65
	v_cvt_pk_bf16_f32 v64, v58, v59
	v_cvt_pk_bf16_f32 v65, v60, v61
	v_cvt_pk_bf16_f32 v46, v46, v47
	v_cvt_pk_bf16_f32 v47, v48, v49
	v_cvt_pk_bf16_f32 v48, v42, v43
	v_cvt_pk_bf16_f32 v49, v44, v45
	v_add_u32_e32 v42, 0x90, v149
	flat_store_dwordx4 v[66:67], v[62:65]
	flat_store_dwordx4 v[66:67], v[46:49] offset:256
	v_cvt_pk_bf16_f32 v43, v56, v57
	v_cvt_pk_bf16_f32 v44, v50, v51
	v_mad_i64_i32 v[46:47], s[0:1], v42, s45, v[150:151]
	v_cvt_pk_bf16_f32 v42, v54, v55
	v_cvt_pk_bf16_f32 v45, v52, v53
	v_cvt_pk_bf16_f32 v30, v30, v31
	v_cvt_pk_bf16_f32 v31, v32, v33
	v_cvt_pk_bf16_f32 v32, v26, v27
	v_cvt_pk_bf16_f32 v33, v28, v29
	v_add_u32_e32 v26, 0xa0, v149
	flat_store_dwordx4 v[46:47], v[42:45]
	flat_store_dwordx4 v[46:47], v[30:33] offset:256
	v_cvt_pk_bf16_f32 v27, v40, v41
	v_cvt_pk_bf16_f32 v28, v34, v35
	v_mad_i64_i32 v[30:31], s[0:1], v26, s45, v[150:151]
	v_cvt_pk_bf16_f32 v26, v38, v39
	v_cvt_pk_bf16_f32 v29, v36, v37
	v_cvt_pk_bf16_f32 v14, v14, v15
	v_cvt_pk_bf16_f32 v15, v16, v17
	v_cvt_pk_bf16_f32 v16, v10, v11
	v_cvt_pk_bf16_f32 v17, v12, v13
	v_add_u32_e32 v10, 0xb0, v149
	flat_store_dwordx4 v[30:31], v[26:29]
	flat_store_dwordx4 v[30:31], v[14:17] offset:256
	v_cvt_pk_bf16_f32 v11, v24, v25
	v_cvt_pk_bf16_f32 v12, v18, v19
	v_mad_i64_i32 v[14:15], s[0:1], v10, s45, v[150:151]
	v_cvt_pk_bf16_f32 v10, v22, v23
	v_cvt_pk_bf16_f32 v13, v20, v21
	v_cvt_pk_bf16_f32 v6, v6, v7
	v_cvt_pk_bf16_f32 v7, v8, v9
	v_cvt_pk_bf16_f32 v8, v2, v3
	v_cvt_pk_bf16_f32 v9, v4, v5
	s_and_b64 vcc, exec, s[26:27]
	s_mov_b32 s53, s52
	s_mov_b32 s54, s51
	flat_store_dwordx4 v[14:15], v[10:13]
	flat_store_dwordx4 v[14:15], v[6:9] offset:256
	s_cbranch_vccz .LBB0_2244
	s_waitcnt vmcnt(0)
	s_cmpk_gt_u32 s5, 0xff
	s_cbranch_scc1 .LBB0_2249
	s_barrier

.LBB0_2325:
	ds_read_b128 v[130:133], v165
	ds_read_b128 v[134:137], v165 offset:1024
	ds_read_b128 v[154:157], v165 offset:2048
	ds_read_b128 v[158:161], v165 offset:3072
	s_add_u32 s36, s34, 0x100
	s_addc_u32 s37, s35, 0
	s_cmp_eq_u32 s59, 2
	s_cselect_b32 s41, s13, s37
	s_cselect_b32 s40, s12, s36
	s_cselect_b32 s39, s15, s58
	s_cselect_b32 s38, s14, s20
	v_lshl_add_u64 v[202:203], s[34:35], 0, v[148:149]
	s_add_i32 m0, s17, 0xc000
	ds_read_b128 v[170:173], v166
	ds_read_b128 v[174:177], v166 offset:1024
	ds_read_b128 v[178:181], v166 offset:2048
	ds_read_b128 v[182:185], v166 offset:3072
	ds_read_b128 v[186:189], v166 offset:4096
	ds_read_b128 v[190:193], v166 offset:5120
	ds_read_b128 v[194:197], v166 offset:6144
	ds_read_b128 v[198:201], v166 offset:7168
	global_load_lds_dwordx4 v[202:203], off
	v_lshl_add_u64 v[202:203], s[34:35], 0, v[146:147]
	s_add_i32 m0, s17, 0xe000
	s_nop 0
	global_load_lds_dwordx4 v[202:203], off
	s_waitcnt lgkmcnt(8)
	s_waitcnt vmcnt(10)
	s_barrier
	s_waitcnt lgkmcnt(0)
	s_waitcnt lgkmcnt(0)
	v_mfma_f32_16x16x32_bf16 v[126:129], v[130:133], v[170:173], v[126:129]
	v_mfma_f32_16x16x32_bf16 v[122:125], v[154:157], v[170:173], v[122:125]
	v_mfma_f32_16x16x32_bf16 v[114:117], v[130:133], v[178:181], v[114:117]
	v_mfma_f32_16x16x32_bf16 v[106:109], v[154:157], v[178:181], v[106:109]
	v_mfma_f32_16x16x32_bf16 v[98:101], v[130:133], v[186:189], v[98:101]
	v_mfma_f32_16x16x32_bf16 v[90:93], v[154:157], v[186:189], v[90:93]
	v_mfma_f32_16x16x32_bf16 v[82:85], v[130:133], v[194:197], v[82:85]
	v_mfma_f32_16x16x32_bf16 v[74:77], v[154:157], v[194:197], v[74:77]
	v_mfma_f32_16x16x32_bf16 v[126:129], v[134:137], v[174:177], v[126:129]
	v_mfma_f32_16x16x32_bf16 v[122:125], v[158:161], v[174:177], v[122:125]
	v_mfma_f32_16x16x32_bf16 v[114:117], v[134:137], v[182:185], v[114:117]
	v_mfma_f32_16x16x32_bf16 v[106:109], v[158:161], v[182:185], v[106:109]
	v_mfma_f32_16x16x32_bf16 v[98:101], v[134:137], v[190:193], v[98:101]
	v_mfma_f32_16x16x32_bf16 v[90:93], v[158:161], v[190:193], v[90:93]
	v_mfma_f32_16x16x32_bf16 v[82:85], v[134:137], v[198:201], v[82:85]
	v_mfma_f32_16x16x32_bf16 v[74:77], v[158:161], v[198:201], v[74:77]
	s_barrier
	s_add_i32 s0, s49, s8
	v_lshl_add_u64 v[218:219], s[38:39], 0, v[142:143]
	s_mov_b32 m0, s0
	ds_read_b128 v[202:205], v167
	ds_read_b128 v[206:209], v167 offset:1024
	ds_read_b128 v[210:213], v167 offset:2048
	ds_read_b128 v[214:217], v167 offset:3072
	global_load_lds_dwordx4 v[218:219], off
	v_lshl_add_u64 v[220:221], s[38:39], 0, v[138:139]
	s_add_i32 m0, s0, 0x2000
	s_nop 0
	global_load_lds_dwordx4 v[220:221], off
	s_waitcnt vmcnt(10)
	s_barrier
	s_waitcnt lgkmcnt(0)
	s_waitcnt lgkmcnt(0)
	v_mfma_f32_16x16x32_bf16 v[118:121], v[202:205], v[170:173], v[118:121]
	v_mfma_f32_16x16x32_bf16 v[110:113], v[210:213], v[170:173], v[110:113]
	v_mfma_f32_16x16x32_bf16 v[102:105], v[202:205], v[178:181], v[102:105]
	v_mfma_f32_16x16x32_bf16 v[94:97], v[210:213], v[178:181], v[94:97]
	v_mfma_f32_16x16x32_bf16 v[86:89], v[202:205], v[186:189], v[86:89]
	v_mfma_f32_16x16x32_bf16 v[78:81], v[210:213], v[186:189], v[78:81]
	v_mfma_f32_16x16x32_bf16 v[70:73], v[202:205], v[194:197], v[70:73]
	v_mfma_f32_16x16x32_bf16 v[66:69], v[210:213], v[194:197], v[66:69]
	v_mfma_f32_16x16x32_bf16 v[118:121], v[206:209], v[174:177], v[118:121]
	v_mfma_f32_16x16x32_bf16 v[110:113], v[214:217], v[174:177], v[110:113]
	v_mfma_f32_16x16x32_bf16 v[102:105], v[206:209], v[182:185], v[102:105]
	v_mfma_f32_16x16x32_bf16 v[94:97], v[214:217], v[182:185], v[94:97]
	v_mfma_f32_16x16x32_bf16 v[86:89], v[206:209], v[190:193], v[86:89]
	v_mfma_f32_16x16x32_bf16 v[78:81], v[214:217], v[190:193], v[78:81]
	v_mfma_f32_16x16x32_bf16 v[70:73], v[206:209], v[198:201], v[70:73]
	v_mfma_f32_16x16x32_bf16 v[66:69], v[214:217], v[198:201], v[66:69]
	s_mov_b32 m0, s17
	v_lshl_add_u64 v[222:223], s[40:41], 0, v[144:145]
	s_barrier
	ds_read_b128 v[170:173], v166 offset:16384
	ds_read_b128 v[174:177], v166 offset:17408
	ds_read_b128 v[178:181], v166 offset:18432
	ds_read_b128 v[182:185], v166 offset:19456
	ds_read_b128 v[186:189], v166 offset:20480
	ds_read_b128 v[190:193], v166 offset:21504
	ds_read_b128 v[194:197], v166 offset:22528
	ds_read_b128 v[198:201], v166 offset:23552
	global_load_lds_dwordx4 v[222:223], off
	v_lshl_add_u64 v[224:225], s[40:41], 0, v[140:141]
	s_mov_b32 m0, s42
	s_nop 0
	global_load_lds_dwordx4 v[224:225], off
	s_waitcnt vmcnt(10)
	s_barrier
	s_waitcnt lgkmcnt(0)
	s_waitcnt lgkmcnt(0)
	v_mfma_f32_16x16x32_bf16 v[62:65], v[130:133], v[170:173], v[62:65]
	v_mfma_f32_16x16x32_bf16 v[58:61], v[154:157], v[170:173], v[58:61]
	v_mfma_f32_16x16x32_bf16 v[50:53], v[130:133], v[178:181], v[50:53]
	v_mfma_f32_16x16x32_bf16 v[42:45], v[154:157], v[178:181], v[42:45]
	v_mfma_f32_16x16x32_bf16 v[34:37], v[130:133], v[186:189], v[34:37]
	v_mfma_f32_16x16x32_bf16 v[26:29], v[154:157], v[186:189], v[26:29]
	v_mfma_f32_16x16x32_bf16 v[18:21], v[130:133], v[194:197], v[18:21]
	v_mfma_f32_16x16x32_bf16 v[10:13], v[154:157], v[194:197], v[10:13]
	v_mfma_f32_16x16x32_bf16 v[62:65], v[134:137], v[174:177], v[62:65]
	v_mfma_f32_16x16x32_bf16 v[58:61], v[158:161], v[174:177], v[58:61]
	v_mfma_f32_16x16x32_bf16 v[50:53], v[134:137], v[182:185], v[50:53]
	v_mfma_f32_16x16x32_bf16 v[42:45], v[158:161], v[182:185], v[42:45]
	v_mfma_f32_16x16x32_bf16 v[34:37], v[134:137], v[190:193], v[34:37]
	v_mfma_f32_16x16x32_bf16 v[26:29], v[158:161], v[190:193], v[26:29]
	v_mfma_f32_16x16x32_bf16 v[18:21], v[134:137], v[198:201], v[18:21]
	v_mfma_f32_16x16x32_bf16 v[10:13], v[158:161], v[198:201], v[10:13]
	s_barrier
	s_add_u32 s0, s38, 0x18000
	s_addc_u32 s1, s39, 0
	s_add_i32 s34, s50, s8
	v_lshl_add_u64 v[130:131], s[0:1], 0, v[142:143]
	s_mov_b32 m0, s34
	s_nop 0
	global_load_lds_dwordx4 v[130:131], off
	v_lshl_add_u64 v[130:131], s[0:1], 0, v[138:139]
	s_add_i32 m0, s34, 0x2000
	s_nop 0
	global_load_lds_dwordx4 v[130:131], off
	s_waitcnt vmcnt(10)
	s_barrier
	v_mfma_f32_16x16x32_bf16 v[54:57], v[202:205], v[170:173], v[54:57]
	v_mfma_f32_16x16x32_bf16 v[46:49], v[210:213], v[170:173], v[46:49]
	v_mfma_f32_16x16x32_bf16 v[38:41], v[202:205], v[178:181], v[38:41]
	v_mfma_f32_16x16x32_bf16 v[30:33], v[210:213], v[178:181], v[30:33]
	v_mfma_f32_16x16x32_bf16 v[22:25], v[202:205], v[186:189], v[22:25]
	v_mfma_f32_16x16x32_bf16 v[14:17], v[210:213], v[186:189], v[14:17]
	v_mfma_f32_16x16x32_bf16 v[6:9], v[202:205], v[194:197], v[6:9]
	v_mfma_f32_16x16x32_bf16 v[2:5], v[210:213], v[194:197], v[2:5]
	v_mfma_f32_16x16x32_bf16 v[54:57], v[206:209], v[174:177], v[54:57]
	v_mfma_f32_16x16x32_bf16 v[46:49], v[214:217], v[174:177], v[46:49]
	v_mfma_f32_16x16x32_bf16 v[38:41], v[206:209], v[182:185], v[38:41]
	v_mfma_f32_16x16x32_bf16 v[30:33], v[214:217], v[182:185], v[30:33]
	v_mfma_f32_16x16x32_bf16 v[22:25], v[206:209], v[190:193], v[22:25]
	v_mfma_f32_16x16x32_bf16 v[14:17], v[214:217], v[190:193], v[14:17]
	v_mfma_f32_16x16x32_bf16 v[6:9], v[206:209], v[198:201], v[6:9]
	v_mfma_f32_16x16x32_bf16 v[2:5], v[214:217], v[198:201], v[2:5]
	s_add_i32 s34, 0, 0x18000
	v_add_u32_e32 v158, s34, v164
	s_barrier
	ds_read_b128 v[130:133], v158
	ds_read_b128 v[134:137], v158 offset:1024
	ds_read_b128 v[154:157], v158 offset:2048
	ds_read_b128 v[158:161], v158 offset:3072
	s_add_u32 s0, s40, 0x18000
	s_addc_u32 s1, s41, 0
	s_mov_b32 m0, s43
	v_lshl_add_u64 v[202:203], s[0:1], 0, v[144:145]
	ds_read_b128 v[170:173], v166 offset:32768
	ds_read_b128 v[174:177], v166 offset:33792
	ds_read_b128 v[178:181], v166 offset:34816
	ds_read_b128 v[182:185], v166 offset:35840
	ds_read_b128 v[186:189], v166 offset:36864
	ds_read_b128 v[190:193], v166 offset:37888
	ds_read_b128 v[194:197], v166 offset:38912
	ds_read_b128 v[198:201], v166 offset:39936
	global_load_lds_dwordx4 v[202:203], off
	v_lshl_add_u64 v[202:203], s[0:1], 0, v[140:141]
	s_mov_b32 m0, s44
	s_nop 0
	global_load_lds_dwordx4 v[202:203], off
	s_waitcnt lgkmcnt(8)
	s_waitcnt vmcnt(10)
	s_barrier
	s_waitcnt lgkmcnt(0)
	s_waitcnt lgkmcnt(0)
	v_mfma_f32_16x16x32_bf16 v[126:129], v[130:133], v[170:173], v[126:129]
	v_mfma_f32_16x16x32_bf16 v[122:125], v[154:157], v[170:173], v[122:125]
	v_mfma_f32_16x16x32_bf16 v[114:117], v[130:133], v[178:181], v[114:117]
	v_mfma_f32_16x16x32_bf16 v[106:109], v[154:157], v[178:181], v[106:109]
	v_mfma_f32_16x16x32_bf16 v[98:101], v[130:133], v[186:189], v[98:101]
	v_mfma_f32_16x16x32_bf16 v[90:93], v[154:157], v[186:189], v[90:93]
	v_mfma_f32_16x16x32_bf16 v[82:85], v[130:133], v[194:197], v[82:85]
	v_mfma_f32_16x16x32_bf16 v[74:77], v[154:157], v[194:197], v[74:77]
	v_mfma_f32_16x16x32_bf16 v[126:129], v[134:137], v[174:177], v[126:129]
	v_mfma_f32_16x16x32_bf16 v[122:125], v[158:161], v[174:177], v[122:125]
	v_mfma_f32_16x16x32_bf16 v[114:117], v[134:137], v[182:185], v[114:117]
	v_mfma_f32_16x16x32_bf16 v[106:109], v[158:161], v[182:185], v[106:109]
	v_mfma_f32_16x16x32_bf16 v[98:101], v[134:137], v[190:193], v[98:101]
	v_mfma_f32_16x16x32_bf16 v[90:93], v[158:161], v[190:193], v[90:93]
	v_mfma_f32_16x16x32_bf16 v[82:85], v[134:137], v[198:201], v[82:85]
	v_mfma_f32_16x16x32_bf16 v[74:77], v[158:161], v[198:201], v[74:77]
	s_barrier
	s_add_i32 s35, 0, 0x1c000
	s_add_i32 s0, s34, s8
	v_add_u32_e32 v169, s35, v164
	v_lshl_add_u64 v[218:219], v[218:219], 0, s[30:31]
	s_mov_b32 m0, s0
	ds_read_b128 v[202:205], v169
	ds_read_b128 v[206:209], v169 offset:1024
	ds_read_b128 v[210:213], v169 offset:2048
	ds_read_b128 v[214:217], v169 offset:3072
	global_load_lds_dwordx4 v[218:219], off
	v_lshl_add_u64 v[218:219], v[220:221], 0, s[30:31]
	s_add_i32 m0, s0, 0x2000
	s_nop 0
	global_load_lds_dwordx4 v[218:219], off
	s_waitcnt vmcnt(10)
	s_barrier
	s_waitcnt lgkmcnt(0)
	s_waitcnt lgkmcnt(0)
	v_mfma_f32_16x16x32_bf16 v[118:121], v[202:205], v[170:173], v[118:121]
	v_mfma_f32_16x16x32_bf16 v[110:113], v[210:213], v[170:173], v[110:113]
	v_mfma_f32_16x16x32_bf16 v[102:105], v[202:205], v[178:181], v[102:105]
	v_mfma_f32_16x16x32_bf16 v[94:97], v[210:213], v[178:181], v[94:97]
	v_mfma_f32_16x16x32_bf16 v[86:89], v[202:205], v[186:189], v[86:89]
	v_mfma_f32_16x16x32_bf16 v[78:81], v[210:213], v[186:189], v[78:81]
	v_mfma_f32_16x16x32_bf16 v[70:73], v[202:205], v[194:197], v[70:73]
	v_mfma_f32_16x16x32_bf16 v[66:69], v[210:213], v[194:197], v[66:69]
	v_mfma_f32_16x16x32_bf16 v[118:121], v[206:209], v[174:177], v[118:121]
	v_mfma_f32_16x16x32_bf16 v[110:113], v[214:217], v[174:177], v[110:113]
	v_mfma_f32_16x16x32_bf16 v[102:105], v[206:209], v[182:185], v[102:105]
	v_mfma_f32_16x16x32_bf16 v[94:97], v[214:217], v[182:185], v[94:97]
	v_mfma_f32_16x16x32_bf16 v[86:89], v[206:209], v[190:193], v[86:89]
	v_mfma_f32_16x16x32_bf16 v[78:81], v[214:217], v[190:193], v[78:81]
	v_mfma_f32_16x16x32_bf16 v[70:73], v[206:209], v[198:201], v[70:73]
	v_mfma_f32_16x16x32_bf16 v[66:69], v[214:217], v[198:201], v[66:69]
	s_mov_b32 m0, s46
	v_lshl_add_u64 v[218:219], v[222:223], 0, s[30:31]
	s_barrier
	ds_read_b128 v[170:173], v166 offset:49152
	ds_read_b128 v[174:177], v166 offset:50176
	ds_read_b128 v[178:181], v166 offset:51200
	ds_read_b128 v[182:185], v166 offset:52224
	ds_read_b128 v[186:189], v166 offset:53248
	ds_read_b128 v[190:193], v166 offset:54272
	ds_read_b128 v[194:197], v166 offset:55296
	ds_read_b128 v[198:201], v166 offset:56320
	global_load_lds_dwordx4 v[218:219], off
	v_lshl_add_u64 v[218:219], v[224:225], 0, s[30:31]
	s_mov_b32 m0, s47
	s_nop 0
	global_load_lds_dwordx4 v[218:219], off
	s_waitcnt vmcnt(10)
	s_barrier
	s_waitcnt lgkmcnt(0)
	s_waitcnt lgkmcnt(0)
	v_mfma_f32_16x16x32_bf16 v[62:65], v[130:133], v[170:173], v[62:65]
	v_mfma_f32_16x16x32_bf16 v[58:61], v[154:157], v[170:173], v[58:61]
	v_mfma_f32_16x16x32_bf16 v[50:53], v[130:133], v[178:181], v[50:53]
	v_mfma_f32_16x16x32_bf16 v[42:45], v[154:157], v[178:181], v[42:45]
	v_mfma_f32_16x16x32_bf16 v[34:37], v[130:133], v[186:189], v[34:37]
	v_mfma_f32_16x16x32_bf16 v[26:29], v[154:157], v[186:189], v[26:29]
	v_mfma_f32_16x16x32_bf16 v[18:21], v[130:133], v[194:197], v[18:21]
	v_mfma_f32_16x16x32_bf16 v[10:13], v[154:157], v[194:197], v[10:13]
	v_mfma_f32_16x16x32_bf16 v[62:65], v[134:137], v[174:177], v[62:65]
	v_mfma_f32_16x16x32_bf16 v[58:61], v[158:161], v[174:177], v[58:61]
	v_mfma_f32_16x16x32_bf16 v[50:53], v[134:137], v[182:185], v[50:53]
	v_mfma_f32_16x16x32_bf16 v[42:45], v[158:161], v[182:185], v[42:45]
	v_mfma_f32_16x16x32_bf16 v[34:37], v[134:137], v[190:193], v[34:37]
	v_mfma_f32_16x16x32_bf16 v[26:29], v[158:161], v[190:193], v[26:29]
	v_mfma_f32_16x16x32_bf16 v[18:21], v[134:137], v[198:201], v[18:21]
	v_mfma_f32_16x16x32_bf16 v[10:13], v[158:161], v[198:201], v[10:13]
	s_barrier
	s_add_u32 s0, s38, 0x18080
	s_addc_u32 s1, s39, 0
	s_add_i32 s34, s35, s8
	v_lshl_add_u64 v[130:131], s[0:1], 0, v[142:143]
	s_mov_b32 m0, s34
	s_nop 0
	global_load_lds_dwordx4 v[130:131], off
	v_lshl_add_u64 v[130:131], s[0:1], 0, v[138:139]
	s_add_i32 m0, s34, 0x2000
	s_nop 0
	global_load_lds_dwordx4 v[130:131], off
	s_waitcnt vmcnt(10)
	s_barrier
	v_mfma_f32_16x16x32_bf16 v[54:57], v[202:205], v[170:173], v[54:57]
	v_mfma_f32_16x16x32_bf16 v[46:49], v[210:213], v[170:173], v[46:49]
	v_mfma_f32_16x16x32_bf16 v[38:41], v[202:205], v[178:181], v[38:41]
	v_mfma_f32_16x16x32_bf16 v[30:33], v[210:213], v[178:181], v[30:33]
	v_mfma_f32_16x16x32_bf16 v[22:25], v[202:205], v[186:189], v[22:25]
	v_mfma_f32_16x16x32_bf16 v[14:17], v[210:213], v[186:189], v[14:17]
	v_mfma_f32_16x16x32_bf16 v[6:9], v[202:205], v[194:197], v[6:9]
	v_mfma_f32_16x16x32_bf16 v[2:5], v[210:213], v[194:197], v[2:5]
	v_mfma_f32_16x16x32_bf16 v[54:57], v[206:209], v[174:177], v[54:57]
	v_mfma_f32_16x16x32_bf16 v[46:49], v[214:217], v[174:177], v[46:49]
	v_mfma_f32_16x16x32_bf16 v[38:41], v[206:209], v[182:185], v[38:41]
	v_mfma_f32_16x16x32_bf16 v[30:33], v[214:217], v[182:185], v[30:33]
	v_mfma_f32_16x16x32_bf16 v[22:25], v[206:209], v[190:193], v[22:25]
	v_mfma_f32_16x16x32_bf16 v[14:17], v[214:217], v[190:193], v[14:17]
	v_mfma_f32_16x16x32_bf16 v[6:9], v[206:209], v[198:201], v[6:9]
	v_mfma_f32_16x16x32_bf16 v[2:5], v[214:217], v[198:201], v[2:5]
	s_add_i32 s59, s59, 2
	s_add_u32 s20, s20, 0x100
	s_addc_u32 s58, s58, 0
	s_cmp_gt_u32 s59, 3
	s_mov_b64 s[34:35], s[36:37]
	s_barrier
	s_cbranch_scc0 .LBB0_2325
	v_mov_b32_e32 v169, v162
	v_mov_b32_e32 v130, v163
	s_mov_b64 s[34:35], -1
	v_lshlrev_b32_e32 v154, 3, v130
	s_cmp_gt_i32 s57, 3
	v_ashrrev_i32_e32 v155, 31, v154
	s_cbranch_scc0 .LBB0_2328
	s_lshl_b32 s0, s56, 8
	s_add_i32 s0, s0, s45
	v_add_u32_e32 v248, s0, v169
	v_mov_b32_e32 v136, v248
	v_lshlrev_b64 v[132:133], 2, v[154:155]
	v_ashrrev_i32_e32 v137, 31, v136
	v_lshl_add_u64 v[130:131], s[26:27], 0, v[132:133]
	v_lshlrev_b64 v[134:135], 7, v[136:137]
	v_lshl_add_u64 v[156:157], v[130:131], 0, v[134:135]
	v_lshl_add_u64 v[132:133], s[24:25], 0, v[132:133]
	flat_load_dwordx4 v[170:173], v[156:157]
	flat_load_dwordx4 v[174:177], v[156:157] offset:16
	v_lshl_add_u64 v[134:135], v[132:133], 0, v[134:135]
	flat_load_dwordx4 v[178:181], v[134:135]
	flat_load_dwordx4 v[182:185], v[134:135] offset:16
	v_add_u32_e32 v160, 16, v136
	v_ashrrev_i32_e32 v161, 31, v160
	v_lshlrev_b64 v[134:135], 7, v[160:161]
	v_lshl_add_u64 v[156:157], v[130:131], 0, v[134:135]
	flat_load_dwordx4 v[186:189], v[156:157]
	flat_load_dwordx4 v[194:197], v[156:157] offset:16
	v_lshl_add_u64 v[134:135], v[132:133], 0, v[134:135]
	flat_load_dwordx4 v[190:193], v[134:135]
	flat_load_dwordx4 v[198:201], v[134:135] offset:16
	v_add_u32_e32 v238, 32, v136
	v_add_u32_e32 v134, 48, v136
	v_ashrrev_i32_e32 v239, 31, v238
	v_ashrrev_i32_e32 v135, 31, v134
	v_lshlrev_b64 v[202:203], 7, v[238:239]
	v_lshlrev_b64 v[204:205], 7, v[134:135]
	v_lshl_add_u64 v[206:207], v[132:133], 0, v[202:203]
	v_lshl_add_u64 v[214:215], v[130:131], 0, v[202:203]
	v_lshl_add_u64 v[222:223], v[132:133], 0, v[204:205]
	v_lshl_add_u64 v[230:231], v[130:131], 0, v[204:205]
	flat_load_dwordx4 v[202:205], v[206:207]
	s_nop 0
	flat_load_dwordx4 v[206:209], v[206:207] offset:16
	s_nop 0
	flat_load_dwordx4 v[210:213], v[214:215]
	s_nop 0
	flat_load_dwordx4 v[214:217], v[214:215] offset:16
	s_nop 0
	flat_load_dwordx4 v[218:221], v[222:223]
	s_nop 0
	flat_load_dwordx4 v[222:225], v[222:223] offset:16
	s_nop 0
	flat_load_dwordx4 v[226:229], v[230:231]
	s_nop 0
	flat_load_dwordx4 v[230:233], v[230:231] offset:16
	v_mov_b32_e32 v234, 0
	v_mov_b32_e32 v235, 0
	v_mov_b32_e32 v236, 0
	v_mov_b32_e32 v237, 0
	s_lshl_b32 s0, s57, 2
	s_add_i32 s0, s48, s0
	v_mov_b64_e32 v[156:157], s[22:23]
	s_mul_i32 s20, s0, 0xc0
	v_lshl_add_u64 v[158:159], s[20:21], 0, v[154:155]
	v_mad_i64_i32 v[136:137], s[0:1], v136, s52, v[156:157]
	v_lshl_add_u64 v[136:137], v[136:137], 0, v[158:159]
	s_mov_b64 s[34:35], 0
	s_waitcnt vmcnt(0) lgkmcnt(0)
	v_pk_mul_f32 v[240:241], v[120:121], v[172:173]
	v_pk_mul_f32 v[242:243], v[118:119], v[170:171]
	v_pk_mul_f32 v[172:173], v[128:129], v[172:173]
	v_pk_mul_f32 v[246:247], v[110:111], v[174:175]
	v_pk_mul_f32 v[170:171], v[126:127], v[170:171]
	v_pk_mul_f32 v[174:175], v[122:123], v[174:175]
	v_pk_fma_f32 v[240:241], v[128:129], v[180:181], v[240:241] neg_lo:[0,0,1] neg_hi:[0,0,1]
	v_pk_fma_f32 v[242:243], v[126:127], v[178:179], v[242:243] neg_lo:[0,0,1] neg_hi:[0,0,1]
	v_pk_fma_f32 v[172:173], v[120:121], v[180:181], v[172:173]
	v_pk_fma_f32 v[180:181], v[122:123], v[182:183], v[246:247] neg_lo:[0,0,1] neg_hi:[0,0,1]
	v_pk_fma_f32 v[170:171], v[118:119], v[178:179], v[170:171]
	v_pk_fma_f32 v[174:175], v[110:111], v[182:183], v[174:175]
	v_med3_f32 v135, v242, s51, v168
	v_med3_f32 v161, v243, s51, v168
	v_med3_f32 v180, v180, s51, v168
	v_med3_f32 v181, v181, s51, v168
	v_med3_f32 v170, v170, s51, v168
	v_med3_f32 v171, v171, s51, v168
	v_med3_f32 v174, v174, s51, v168
	v_med3_f32 v175, v175, s51, v168
	v_cvt_pk_fp8_f32 v234, v135, v161
	v_cvt_pk_fp8_f32 v235, v180, v181
	v_pk_mul_f32 v[244:245], v[112:113], v[176:177]
	v_cvt_pk_fp8_f32 v236, v170, v171
	v_cvt_pk_fp8_f32 v237, v174, v175
	v_pk_mul_f32 v[176:177], v[124:125], v[176:177]
	v_pk_fma_f32 v[178:179], v[124:125], v[184:185], v[244:245] neg_lo:[0,0,1] neg_hi:[0,0,1]
	v_pk_fma_f32 v[176:177], v[112:113], v[184:185], v[176:177]
	v_med3_f32 v184, v240, s51, v168
	v_med3_f32 v185, v241, s51, v168
	v_med3_f32 v178, v178, s51, v168
	v_med3_f32 v179, v179, s51, v168
	v_med3_f32 v172, v172, s51, v168
	v_med3_f32 v173, v173, s51, v168
	v_med3_f32 v176, v176, s51, v168
	v_med3_f32 v177, v177, s51, v168
	v_cvt_pk_fp8_f32 v234, v184, v185 op_sel:[0,0,1]
	v_cvt_pk_fp8_f32 v235, v178, v179 op_sel:[0,0,1]
	v_cvt_pk_fp8_f32 v236, v172, v173 op_sel:[0,0,1]
	v_cvt_pk_fp8_f32 v237, v176, v177 op_sel:[0,0,1]
	v_pk_mul_f32 v[170:171], v[102:103], v[186:187]
	v_pk_mul_f32 v[182:183], v[104:105], v[188:189]
	flat_store_dwordx2 v[136:137], v[234:235] offset:128
	flat_store_dwordx2 v[136:137], v[236:237] offset:160
	v_pk_fma_f32 v[136:137], v[114:115], v[190:191], v[170:171] neg_lo:[0,0,1] neg_hi:[0,0,1]
	v_pk_mul_f32 v[178:179], v[94:95], v[194:195]
	v_pk_fma_f32 v[172:173], v[116:117], v[192:193], v[182:183] neg_lo:[0,0,1] neg_hi:[0,0,1]
	v_pk_fma_f32 v[178:179], v[106:107], v[198:199], v[178:179] neg_lo:[0,0,1] neg_hi:[0,0,1]
	v_med3_f32 v135, v136, s51, v168
	v_med3_f32 v137, v137, s51, v168
	v_mov_b32_e32 v136, 0
	v_cvt_pk_fp8_f32 v136, v135, v137
	v_med3_f32 v135, v172, s51, v168
	v_med3_f32 v161, v173, s51, v168
	v_med3_f32 v172, v178, s51, v168
	v_med3_f32 v173, v179, s51, v168
	v_mov_b32_e32 v137, 0
	v_cvt_pk_fp8_f32 v137, v172, v173
	v_pk_mul_f32 v[176:177], v[96:97], v[196:197]
	v_pk_mul_f32 v[174:175], v[114:115], v[186:187]
	v_pk_fma_f32 v[176:177], v[108:109], v[200:201], v[176:177] neg_lo:[0,0,1] neg_hi:[0,0,1]
	v_pk_mul_f32 v[170:171], v[116:117], v[188:189]
	v_pk_fma_f32 v[174:175], v[102:103], v[190:191], v[174:175]
	v_pk_mul_f32 v[182:183], v[106:107], v[194:195]
	v_cvt_pk_fp8_f32 v136, v135, v161 op_sel:[0,0,1]
	v_med3_f32 v135, v176, s51, v168
	v_med3_f32 v161, v177, s51, v168
	v_pk_fma_f32 v[170:171], v[104:105], v[192:193], v[170:171]
	v_pk_fma_f32 v[182:183], v[94:95], v[198:199], v[182:183]
	v_cvt_pk_fp8_f32 v137, v135, v161 op_sel:[0,0,1]
	v_med3_f32 v135, v174, s51, v168
	v_med3_f32 v161, v175, s51, v168
	v_mov_b32_e32 v172, 0
	v_cvt_pk_fp8_f32 v172, v135, v161
	v_med3_f32 v135, v170, s51, v168
	v_med3_f32 v161, v171, s51, v168
	v_med3_f32 v170, v182, s51, v168
	v_med3_f32 v171, v183, s51, v168
	v_mov_b32_e32 v173, 0
	v_cvt_pk_fp8_f32 v173, v170, v171
	v_pk_mul_f32 v[180:181], v[108:109], v[196:197]
	v_cvt_pk_fp8_f32 v172, v135, v161 op_sel:[0,0,1]
	v_pk_fma_f32 v[180:181], v[96:97], v[200:201], v[180:181]
	v_pk_mul_f32 v[176:177], v[78:79], v[214:215]
	v_med3_f32 v135, v180, s51, v168
	v_med3_f32 v161, v181, s51, v168
	v_cvt_pk_fp8_f32 v173, v135, v161 op_sel:[0,0,1]
	v_mad_i64_i32 v[160:161], s[0:1], v160, s52, v[156:157]
	v_lshl_add_u64 v[160:161], v[160:161], 0, v[158:159]
	flat_store_dwordx2 v[160:161], v[136:137] offset:128
	flat_store_dwordx2 v[160:161], v[172:173] offset:160
	v_pk_mul_f32 v[160:161], v[86:87], v[210:211]
	v_pk_mul_f32 v[136:137], v[88:89], v[212:213]
	v_pk_fma_f32 v[160:161], v[98:99], v[202:203], v[160:161] neg_lo:[0,0,1] neg_hi:[0,0,1]
	v_pk_fma_f32 v[136:137], v[100:101], v[204:205], v[136:137] neg_lo:[0,0,1] neg_hi:[0,0,1]
	v_pk_fma_f32 v[176:177], v[90:91], v[206:207], v[176:177] neg_lo:[0,0,1] neg_hi:[0,0,1]
	v_med3_f32 v135, v160, s51, v168
	v_med3_f32 v161, v161, s51, v168
	v_mov_b32_e32 v160, 0
	v_cvt_pk_fp8_f32 v160, v135, v161
	v_med3_f32 v135, v136, s51, v168
	v_med3_f32 v136, v137, s51, v168
	v_med3_f32 v137, v176, s51, v168
	v_med3_f32 v176, v177, s51, v168
	v_mov_b32_e32 v161, 0
	v_cvt_pk_fp8_f32 v161, v137, v176
	v_pk_mul_f32 v[174:175], v[80:81], v[216:217]
	v_pk_mul_f32 v[172:173], v[98:99], v[210:211]
	v_pk_fma_f32 v[174:175], v[92:93], v[208:209], v[174:175] neg_lo:[0,0,1] neg_hi:[0,0,1]
	v_pk_mul_f32 v[170:171], v[100:101], v[212:213]
	v_pk_fma_f32 v[172:173], v[86:87], v[202:203], v[172:173]
	v_pk_mul_f32 v[180:181], v[90:91], v[214:215]
	v_cvt_pk_fp8_f32 v160, v135, v136 op_sel:[0,0,1]
	v_med3_f32 v135, v174, s51, v168
	v_med3_f32 v136, v175, s51, v168
	v_pk_fma_f32 v[170:171], v[88:89], v[204:205], v[170:171]
	v_pk_fma_f32 v[180:181], v[78:79], v[206:207], v[180:181]
	v_cvt_pk_fp8_f32 v161, v135, v136 op_sel:[0,0,1]
	v_med3_f32 v135, v172, s51, v168
	v_med3_f32 v137, v173, s51, v168
	v_mov_b32_e32 v136, 0
	v_cvt_pk_fp8_f32 v136, v135, v137
	v_med3_f32 v135, v170, s51, v168
	v_med3_f32 v170, v171, s51, v168
	v_med3_f32 v171, v180, s51, v168
	v_med3_f32 v172, v181, s51, v168
	v_mov_b32_e32 v137, 0
	v_cvt_pk_fp8_f32 v137, v171, v172
	v_pk_mul_f32 v[178:179], v[92:93], v[216:217]
	v_cvt_pk_fp8_f32 v136, v135, v170 op_sel:[0,0,1]
	v_pk_fma_f32 v[178:179], v[80:81], v[208:209], v[178:179]
	v_pk_mul_f32 v[176:177], v[66:67], v[230:231]
	v_med3_f32 v135, v178, s51, v168
	v_med3_f32 v170, v179, s51, v168
	v_cvt_pk_fp8_f32 v137, v135, v170 op_sel:[0,0,1]
	v_mad_i64_i32 v[170:171], s[0:1], v238, s52, v[156:157]
	v_lshl_add_u64 v[170:171], v[170:171], 0, v[158:159]
	flat_store_dwordx2 v[170:171], v[160:161] offset:128
	flat_store_dwordx2 v[170:171], v[136:137] offset:160
	v_pk_mul_f32 v[160:161], v[70:71], v[226:227]
	v_pk_mul_f32 v[136:137], v[72:73], v[228:229]
	v_pk_fma_f32 v[160:161], v[82:83], v[218:219], v[160:161] neg_lo:[0,0,1] neg_hi:[0,0,1]
	v_pk_fma_f32 v[136:137], v[84:85], v[220:221], v[136:137] neg_lo:[0,0,1] neg_hi:[0,0,1]
	v_pk_fma_f32 v[176:177], v[74:75], v[222:223], v[176:177] neg_lo:[0,0,1] neg_hi:[0,0,1]
	v_med3_f32 v135, v160, s51, v168
	v_med3_f32 v161, v161, s51, v168
	v_mov_b32_e32 v160, 0
	v_cvt_pk_fp8_f32 v160, v135, v161
	v_med3_f32 v135, v136, s51, v168
	v_med3_f32 v136, v137, s51, v168
	v_med3_f32 v137, v176, s51, v168
	v_med3_f32 v176, v177, s51, v168
	v_mov_b32_e32 v161, 0
	v_cvt_pk_fp8_f32 v161, v137, v176
	v_pk_mul_f32 v[174:175], v[68:69], v[232:233]
	v_pk_mul_f32 v[172:173], v[82:83], v[226:227]
	v_pk_fma_f32 v[174:175], v[76:77], v[224:225], v[174:175] neg_lo:[0,0,1] neg_hi:[0,0,1]
	v_pk_mul_f32 v[170:171], v[84:85], v[228:229]
	v_pk_fma_f32 v[172:173], v[70:71], v[218:219], v[172:173]
	v_pk_mul_f32 v[180:181], v[74:75], v[230:231]
	v_cvt_pk_fp8_f32 v160, v135, v136 op_sel:[0,0,1]
	v_med3_f32 v135, v174, s51, v168
	v_med3_f32 v136, v175, s51, v168
	v_pk_fma_f32 v[170:171], v[72:73], v[220:221], v[170:171]
	v_pk_fma_f32 v[180:181], v[66:67], v[222:223], v[180:181]
	v_cvt_pk_fp8_f32 v161, v135, v136 op_sel:[0,0,1]
	v_med3_f32 v135, v172, s51, v168
	v_med3_f32 v137, v173, s51, v168
	v_mov_b32_e32 v136, 0
	v_cvt_pk_fp8_f32 v136, v135, v137
	v_med3_f32 v135, v170, s51, v168
	v_med3_f32 v170, v171, s51, v168
	v_med3_f32 v171, v180, s51, v168
	v_med3_f32 v172, v181, s51, v168
	v_mov_b32_e32 v137, 0
	v_cvt_pk_fp8_f32 v137, v171, v172
	v_pk_mul_f32 v[178:179], v[76:77], v[232:233]
	v_cvt_pk_fp8_f32 v136, v135, v170 op_sel:[0,0,1]
	v_pk_fma_f32 v[178:179], v[68:69], v[224:225], v[178:179]
	v_add_u32_e32 v226, 0x80, v248
	v_med3_f32 v135, v178, s51, v168
	v_med3_f32 v170, v179, s51, v168
	v_cvt_pk_fp8_f32 v137, v135, v170 op_sel:[0,0,1]
	v_mad_i64_i32 v[134:135], s[0:1], v134, s52, v[156:157]
	v_lshl_add_u64 v[134:135], v[134:135], 0, v[158:159]
	flat_store_dwordx2 v[134:135], v[160:161] offset:128
	flat_store_dwordx2 v[134:135], v[136:137] offset:160
	s_nop 0
	v_ashrrev_i32_e32 v227, 31, v226
	v_lshlrev_b64 v[134:135], 7, v[226:227]
	v_lshl_add_u64 v[136:137], v[130:131], 0, v[134:135]
	flat_load_dwordx4 v[170:173], v[136:137]
	v_lshl_add_u64 v[134:135], v[132:133], 0, v[134:135]
	flat_load_dwordx4 v[174:177], v[134:135]
	flat_load_dwordx4 v[178:181], v[136:137] offset:16
	flat_load_dwordx4 v[182:185], v[134:135] offset:16
	v_add_u32_e32 v228, 16, v226
	v_ashrrev_i32_e32 v229, 31, v228
	v_lshlrev_b64 v[134:135], 7, v[228:229]
	v_lshl_add_u64 v[136:137], v[130:131], 0, v[134:135]
	flat_load_dwordx4 v[186:189], v[136:137]
	v_lshl_add_u64 v[134:135], v[132:133], 0, v[134:135]
	flat_load_dwordx4 v[190:193], v[134:135]
	flat_load_dwordx4 v[194:197], v[136:137] offset:16
	flat_load_dwordx4 v[198:201], v[134:135] offset:16
	v_add_u32_e32 v230, 32, v226
	v_ashrrev_i32_e32 v231, 31, v230
	v_lshlrev_b64 v[134:135], 7, v[230:231]
	v_lshl_add_u64 v[136:137], v[132:133], 0, v[134:135]
	v_lshl_add_u64 v[134:135], v[130:131], 0, v[134:135]
	flat_load_dwordx4 v[202:205], v[136:137]
	flat_load_dwordx4 v[206:209], v[136:137] offset:16
	flat_load_dwordx4 v[210:213], v[134:135]
	flat_load_dwordx4 v[214:217], v[134:135] offset:16
	v_add_u32_e32 v160, 48, v226
	v_ashrrev_i32_e32 v161, 31, v160
	v_lshlrev_b64 v[134:135], 7, v[160:161]
	v_lshl_add_u64 v[132:133], v[132:133], 0, v[134:135]
	v_lshl_add_u64 v[134:135], v[130:131], 0, v[134:135]
	flat_load_dwordx4 v[218:221], v[132:133]
	s_nop 0
	flat_load_dwordx4 v[130:133], v[132:133] offset:16
	s_nop 0
	flat_load_dwordx4 v[222:225], v[134:135]
	s_nop 0
	flat_load_dwordx4 v[134:137], v[134:135] offset:16
	s_waitcnt vmcnt(0) lgkmcnt(0)
	v_pk_mul_f32 v[232:233], v[56:57], v[172:173]
	v_pk_mul_f32 v[234:235], v[54:55], v[170:171]
	v_pk_mul_f32 v[172:173], v[64:65], v[172:173]
	v_pk_fma_f32 v[232:233], v[64:65], v[176:177], v[232:233] neg_lo:[0,0,1] neg_hi:[0,0,1]
	v_pk_fma_f32 v[234:235], v[62:63], v[174:175], v[234:235] neg_lo:[0,0,1] neg_hi:[0,0,1]
	v_pk_fma_f32 v[172:173], v[56:57], v[176:177], v[172:173]
	v_pk_mul_f32 v[176:177], v[46:47], v[178:179]
	v_pk_mul_f32 v[178:179], v[58:59], v[178:179]
	v_pk_fma_f32 v[176:177], v[58:59], v[182:183], v[176:177] neg_lo:[0,0,1] neg_hi:[0,0,1]
	v_pk_fma_f32 v[178:179], v[46:47], v[182:183], v[178:179]
	v_med3_f32 v161, v234, s51, v168
	v_med3_f32 v183, v235, s51, v168
	v_mov_b32_e32 v182, 0
	v_cvt_pk_fp8_f32 v182, v161, v183
	v_med3_f32 v176, v176, s51, v168
	v_med3_f32 v177, v177, s51, v168
	v_mov_b32_e32 v183, 0
	v_pk_mul_f32 v[170:171], v[62:63], v[170:171]
	v_cvt_pk_fp8_f32 v183, v176, v177
	v_pk_fma_f32 v[170:171], v[54:55], v[174:175], v[170:171]
	v_pk_mul_f32 v[174:175], v[48:49], v[180:181]
	v_pk_mul_f32 v[180:181], v[60:61], v[180:181]
	v_pk_fma_f32 v[174:175], v[60:61], v[184:185], v[174:175] neg_lo:[0,0,1] neg_hi:[0,0,1]
	v_pk_fma_f32 v[180:181], v[48:49], v[184:185], v[180:181]
	v_med3_f32 v161, v232, s51, v168
	v_med3_f32 v184, v233, s51, v168
	v_cvt_pk_fp8_f32 v182, v161, v184 op_sel:[0,0,1]
	v_med3_f32 v161, v174, s51, v168
	v_med3_f32 v174, v175, s51, v168
	v_cvt_pk_fp8_f32 v183, v161, v174 op_sel:[0,0,1]
	v_med3_f32 v161, v170, s51, v168
	v_med3_f32 v171, v171, s51, v168
	v_mov_b32_e32 v170, 0
	v_cvt_pk_fp8_f32 v170, v161, v171
	v_med3_f32 v161, v172, s51, v168
	v_med3_f32 v172, v173, s51, v168
	v_med3_f32 v173, v178, s51, v168
	v_med3_f32 v174, v179, s51, v168
	v_mov_b32_e32 v171, 0
	v_cvt_pk_fp8_f32 v171, v173, v174
	v_cvt_pk_fp8_f32 v170, v161, v172 op_sel:[0,0,1]
	v_med3_f32 v161, v180, s51, v168
	v_med3_f32 v172, v181, s51, v168
	v_cvt_pk_fp8_f32 v171, v161, v172 op_sel:[0,0,1]
	v_mad_i64_i32 v[172:173], s[0:1], v226, s52, v[156:157]
	v_lshl_add_u64 v[172:173], v[172:173], 0, v[158:159]
	flat_store_dwordx2 v[172:173], v[182:183] offset:128
	flat_store_dwordx2 v[172:173], v[170:171] offset:160
	v_pk_mul_f32 v[172:173], v[38:39], v[186:187]
	v_pk_mul_f32 v[170:171], v[40:41], v[188:189]
	v_pk_fma_f32 v[172:173], v[50:51], v[190:191], v[172:173] neg_lo:[0,0,1] neg_hi:[0,0,1]
	v_pk_mul_f32 v[180:181], v[30:31], v[194:195]
	v_pk_fma_f32 v[170:171], v[52:53], v[192:193], v[170:171] neg_lo:[0,0,1] neg_hi:[0,0,1]
	v_pk_fma_f32 v[180:181], v[42:43], v[198:199], v[180:181] neg_lo:[0,0,1] neg_hi:[0,0,1]
	v_med3_f32 v161, v172, s51, v168
	v_med3_f32 v173, v173, s51, v168
	v_mov_b32_e32 v172, 0
	v_cvt_pk_fp8_f32 v172, v161, v173
	v_med3_f32 v161, v170, s51, v168
	v_med3_f32 v170, v171, s51, v168
	v_med3_f32 v171, v180, s51, v168
	v_med3_f32 v180, v181, s51, v168
	v_mov_b32_e32 v173, 0
	v_cvt_pk_fp8_f32 v173, v171, v180
	v_pk_mul_f32 v[178:179], v[32:33], v[196:197]
	v_pk_mul_f32 v[176:177], v[50:51], v[186:187]
	v_pk_fma_f32 v[178:179], v[44:45], v[200:201], v[178:179] neg_lo:[0,0,1] neg_hi:[0,0,1]
	v_pk_mul_f32 v[174:175], v[52:53], v[188:189]
	v_pk_fma_f32 v[176:177], v[38:39], v[190:191], v[176:177]
	v_pk_mul_f32 v[184:185], v[42:43], v[194:195]
	v_cvt_pk_fp8_f32 v172, v161, v170 op_sel:[0,0,1]
	v_med3_f32 v161, v178, s51, v168
	v_med3_f32 v170, v179, s51, v168
	v_pk_fma_f32 v[174:175], v[40:41], v[192:193], v[174:175]
	v_pk_fma_f32 v[184:185], v[30:31], v[198:199], v[184:185]
	v_cvt_pk_fp8_f32 v173, v161, v170 op_sel:[0,0,1]
	v_med3_f32 v161, v176, s51, v168
	v_med3_f32 v171, v177, s51, v168
	v_mov_b32_e32 v170, 0
	v_cvt_pk_fp8_f32 v170, v161, v171
	v_med3_f32 v161, v174, s51, v168
	v_med3_f32 v174, v175, s51, v168
	v_med3_f32 v175, v184, s51, v168
	v_med3_f32 v176, v185, s51, v168
	v_mov_b32_e32 v171, 0
	v_cvt_pk_fp8_f32 v171, v175, v176
	v_pk_mul_f32 v[182:183], v[44:45], v[196:197]
	v_cvt_pk_fp8_f32 v170, v161, v174 op_sel:[0,0,1]
	v_pk_fma_f32 v[182:183], v[32:33], v[200:201], v[182:183]
	v_pk_mul_f32 v[180:181], v[14:15], v[214:215]
	v_med3_f32 v161, v182, s51, v168
	v_med3_f32 v174, v183, s51, v168
	v_cvt_pk_fp8_f32 v171, v161, v174 op_sel:[0,0,1]
	v_mad_i64_i32 v[174:175], s[0:1], v228, s52, v[156:157]
	v_lshl_add_u64 v[174:175], v[174:175], 0, v[158:159]
	flat_store_dwordx2 v[174:175], v[172:173] offset:128
	flat_store_dwordx2 v[174:175], v[170:171] offset:160
	v_pk_mul_f32 v[172:173], v[22:23], v[210:211]
	v_pk_mul_f32 v[170:171], v[24:25], v[212:213]
	v_pk_fma_f32 v[172:173], v[34:35], v[202:203], v[172:173] neg_lo:[0,0,1] neg_hi:[0,0,1]
	v_pk_fma_f32 v[170:171], v[36:37], v[204:205], v[170:171] neg_lo:[0,0,1] neg_hi:[0,0,1]
	v_pk_fma_f32 v[180:181], v[26:27], v[206:207], v[180:181] neg_lo:[0,0,1] neg_hi:[0,0,1]
	v_med3_f32 v161, v172, s51, v168
	v_med3_f32 v173, v173, s51, v168
	v_mov_b32_e32 v172, 0
	v_cvt_pk_fp8_f32 v172, v161, v173
	v_med3_f32 v161, v170, s51, v168
	v_med3_f32 v170, v171, s51, v168
	v_med3_f32 v171, v180, s51, v168
	v_med3_f32 v180, v181, s51, v168
	v_mov_b32_e32 v173, 0
	v_cvt_pk_fp8_f32 v173, v171, v180
	v_pk_mul_f32 v[178:179], v[16:17], v[216:217]
	v_pk_mul_f32 v[176:177], v[34:35], v[210:211]
	v_pk_fma_f32 v[178:179], v[28:29], v[208:209], v[178:179] neg_lo:[0,0,1] neg_hi:[0,0,1]
	v_pk_mul_f32 v[174:175], v[36:37], v[212:213]
	v_pk_fma_f32 v[176:177], v[22:23], v[202:203], v[176:177]
	v_pk_mul_f32 v[184:185], v[26:27], v[214:215]
	v_cvt_pk_fp8_f32 v172, v161, v170 op_sel:[0,0,1]
	v_med3_f32 v161, v178, s51, v168
	v_med3_f32 v170, v179, s51, v168
	v_pk_fma_f32 v[174:175], v[24:25], v[204:205], v[174:175]
	v_pk_fma_f32 v[184:185], v[14:15], v[206:207], v[184:185]
	v_cvt_pk_fp8_f32 v173, v161, v170 op_sel:[0,0,1]
	v_med3_f32 v161, v176, s51, v168
	v_med3_f32 v171, v177, s51, v168
	v_mov_b32_e32 v170, 0
	v_cvt_pk_fp8_f32 v170, v161, v171
	v_med3_f32 v161, v174, s51, v168
	v_med3_f32 v174, v175, s51, v168
	v_med3_f32 v175, v184, s51, v168
	v_med3_f32 v176, v185, s51, v168
	v_mov_b32_e32 v171, 0
	v_cvt_pk_fp8_f32 v171, v175, v176
	v_pk_mul_f32 v[182:183], v[28:29], v[216:217]
	v_cvt_pk_fp8_f32 v170, v161, v174 op_sel:[0,0,1]
	v_pk_fma_f32 v[182:183], v[16:17], v[208:209], v[182:183]
	v_pk_mul_f32 v[178:179], v[4:5], v[136:137]
	v_med3_f32 v161, v182, s51, v168
	v_med3_f32 v174, v183, s51, v168
	v_cvt_pk_fp8_f32 v171, v161, v174 op_sel:[0,0,1]
	v_mad_i64_i32 v[174:175], s[0:1], v230, s52, v[156:157]
	v_lshl_add_u64 v[174:175], v[174:175], 0, v[158:159]
	flat_store_dwordx2 v[174:175], v[172:173] offset:128
	flat_store_dwordx2 v[174:175], v[170:171] offset:160
	v_pk_mul_f32 v[172:173], v[6:7], v[222:223]
	v_pk_mul_f32 v[170:171], v[8:9], v[224:225]
	v_pk_fma_f32 v[172:173], v[18:19], v[218:219], v[172:173] neg_lo:[0,0,1] neg_hi:[0,0,1]
	v_pk_mul_f32 v[180:181], v[2:3], v[134:135]
	v_pk_mul_f32 v[136:137], v[12:13], v[136:137]
	v_pk_mul_f32 v[134:135], v[10:11], v[134:135]
	v_pk_fma_f32 v[170:171], v[20:21], v[220:221], v[170:171] neg_lo:[0,0,1] neg_hi:[0,0,1]
	v_pk_fma_f32 v[178:179], v[12:13], v[132:133], v[178:179] neg_lo:[0,0,1] neg_hi:[0,0,1]
	v_pk_fma_f32 v[180:181], v[10:11], v[130:131], v[180:181] neg_lo:[0,0,1] neg_hi:[0,0,1]
	v_pk_fma_f32 v[132:133], v[4:5], v[132:133], v[136:137]
	v_pk_fma_f32 v[130:131], v[2:3], v[130:131], v[134:135]
	v_med3_f32 v135, v172, s51, v168
	v_med3_f32 v136, v173, s51, v168
	v_mov_b32_e32 v134, 0
	v_cvt_pk_fp8_f32 v134, v135, v136
	v_med3_f32 v136, v170, s51, v168
	v_med3_f32 v161, v180, s51, v168
	v_med3_f32 v170, v181, s51, v168
	v_mov_b32_e32 v135, 0
	v_cvt_pk_fp8_f32 v135, v161, v170
	v_pk_mul_f32 v[176:177], v[18:19], v[222:223]
	v_med3_f32 v137, v171, s51, v168
	v_pk_fma_f32 v[176:177], v[6:7], v[218:219], v[176:177]
	v_cvt_pk_fp8_f32 v134, v136, v137 op_sel:[0,0,1]
	v_med3_f32 v136, v178, s51, v168
	v_med3_f32 v137, v179, s51, v168
	v_cvt_pk_fp8_f32 v135, v136, v137 op_sel:[0,0,1]
	v_med3_f32 v137, v176, s51, v168
	v_med3_f32 v161, v177, s51, v168
	v_mov_b32_e32 v136, 0
	v_cvt_pk_fp8_f32 v136, v137, v161
	v_med3_f32 v130, v130, s51, v168
	v_med3_f32 v131, v131, s51, v168
	v_mov_b32_e32 v137, 0
	v_cvt_pk_fp8_f32 v137, v130, v131
	v_pk_mul_f32 v[174:175], v[20:21], v[224:225]
	v_med3_f32 v130, v132, s51, v168
	v_pk_fma_f32 v[174:175], v[8:9], v[220:221], v[174:175]
	v_med3_f32 v131, v133, s51, v168
	v_med3_f32 v161, v174, s51, v168
	v_med3_f32 v170, v175, s51, v168
	v_cvt_pk_fp8_f32 v136, v161, v170 op_sel:[0,0,1]
	v_cvt_pk_fp8_f32 v137, v130, v131 op_sel:[0,0,1]
	v_mad_i64_i32 v[130:131], s[0:1], v160, s52, v[156:157]
	v_lshl_add_u64 v[130:131], v[130:131], 0, v[158:159]
	flat_store_dwordx2 v[130:131], v[134:135] offset:128
	flat_store_dwordx2 v[130:131], v[136:137] offset:160

.LBB0_2344:
	s_add_u32 s39, s30, s38
	s_addc_u32 s40, s31, 0
	s_add_u32 s41, s39, 0x100
	s_addc_u32 s42, s40, 0
	s_and_b64 s[0:1], s[36:37], exec
	s_cselect_b32 s43, s21, s42
	s_cselect_b32 s42, s62, s41
	s_add_u32 s0, s28, s38
	s_addc_u32 s1, s29, 0
	s_add_u32 s38, s0, 0x100
	s_addc_u32 s41, s1, 0
	s_and_b64 s[0:1], s[36:37], exec
	s_cselect_b32 s45, s19, s41
	s_cselect_b32 s44, s63, s38
	s_add_u32 s46, s39, 0x10080
	s_addc_u32 s47, s40, 0
	s_add_i32 s70, s58, s9
	s_add_i32 m0, s27, 0xc000
	s_add_i32 s71, s27, 0xe000
	s_add_i32 s0, s70, 0x2000
	s_add_u32 s40, s44, 0x10000
	s_addc_u32 s41, s45, 0
	s_add_i32 s77, s59, s9
	ds_read_b128 v[152:155], v147
	ds_read_b128 v[156:159], v147 offset:1024
	ds_read_b128 v[160:163], v147 offset:2048
	ds_read_b128 v[164:167], v147 offset:3072
	s_add_i32 s1, s77, 0x2000
	s_add_i32 s73, 0, 0x18000
	s_add_u32 s38, s42, 0x10000
	s_addc_u32 s39, s43, 0
	s_add_i32 s72, s73, s9
	s_add_i32 s69, 0, 0x1c000
	s_add_i32 s67, s72, 0x2000
	s_add_u32 s36, s44, 0x10080
	s_addc_u32 s37, s45, 0
	s_add_i32 s65, s69, s9
	s_add_i32 s64, s65, 0x2000
	v_lshl_add_u64 v[142:143], s[46:47], 0, v[136:137]
	ds_read_b128 v[168:171], v148
	ds_read_b128 v[172:175], v148 offset:1024
	ds_read_b128 v[176:179], v148 offset:2048
	ds_read_b128 v[180:183], v148 offset:3072
	ds_read_b128 v[184:187], v148 offset:4096
	ds_read_b128 v[188:191], v148 offset:5120
	ds_read_b128 v[192:195], v148 offset:6144
	ds_read_b128 v[196:199], v148 offset:7168
	global_load_lds_dwordx4 v[142:143], off
	v_lshl_add_u64 v[142:143], s[46:47], 0, v[132:133]
	s_mov_b32 m0, s71
	s_nop 0
	global_load_lds_dwordx4 v[142:143], off
	s_waitcnt lgkmcnt(8)
	s_waitcnt vmcnt(10)
	s_barrier
	s_waitcnt lgkmcnt(0)
	s_waitcnt lgkmcnt(0)
	v_mfma_f32_16x16x32_bf16 v[126:129], v[152:155], v[168:171], v[126:129]
	v_mfma_f32_16x16x32_bf16 v[122:125], v[160:163], v[168:171], v[122:125]
	v_mfma_f32_16x16x32_bf16 v[110:113], v[152:155], v[176:179], v[110:113]
	v_mfma_f32_16x16x32_bf16 v[106:109], v[160:163], v[176:179], v[106:109]
	v_mfma_f32_16x16x32_bf16 v[94:97], v[152:155], v[184:187], v[94:97]
	v_mfma_f32_16x16x32_bf16 v[90:93], v[160:163], v[184:187], v[90:93]
	v_mfma_f32_16x16x32_bf16 v[78:81], v[152:155], v[192:195], v[78:81]
	v_mfma_f32_16x16x32_bf16 v[74:77], v[160:163], v[192:195], v[74:77]
	v_mfma_f32_16x16x32_bf16 v[126:129], v[156:159], v[172:175], v[126:129]
	v_mfma_f32_16x16x32_bf16 v[122:125], v[164:167], v[172:175], v[122:125]
	v_mfma_f32_16x16x32_bf16 v[110:113], v[156:159], v[180:183], v[110:113]
	v_mfma_f32_16x16x32_bf16 v[106:109], v[164:167], v[180:183], v[106:109]
	v_mfma_f32_16x16x32_bf16 v[94:97], v[156:159], v[188:191], v[94:97]
	v_mfma_f32_16x16x32_bf16 v[90:93], v[164:167], v[188:191], v[90:93]
	v_mfma_f32_16x16x32_bf16 v[78:81], v[156:159], v[196:199], v[78:81]
	v_mfma_f32_16x16x32_bf16 v[74:77], v[164:167], v[196:199], v[74:77]
	s_barrier
	s_mov_b32 m0, s70
	v_lshl_add_u64 v[142:143], s[44:45], 0, v[134:135]
	ds_read_b128 v[200:203], v149
	ds_read_b128 v[204:207], v149 offset:1024
	ds_read_b128 v[208:211], v149 offset:2048
	ds_read_b128 v[212:215], v149 offset:3072
	global_load_lds_dwordx4 v[142:143], off
	v_lshl_add_u64 v[216:217], s[44:45], 0, v[130:131]
	s_mov_b32 m0, s0
	s_nop 0
	global_load_lds_dwordx4 v[216:217], off
	s_waitcnt vmcnt(10)
	s_barrier
	s_waitcnt lgkmcnt(0)
	s_waitcnt lgkmcnt(0)
	v_mfma_f32_16x16x32_bf16 v[118:121], v[200:203], v[168:171], v[118:121]
	v_mfma_f32_16x16x32_bf16 v[114:117], v[208:211], v[168:171], v[114:117]
	v_mfma_f32_16x16x32_bf16 v[102:105], v[200:203], v[176:179], v[102:105]
	v_mfma_f32_16x16x32_bf16 v[98:101], v[208:211], v[176:179], v[98:101]
	v_mfma_f32_16x16x32_bf16 v[86:89], v[200:203], v[184:187], v[86:89]
	v_mfma_f32_16x16x32_bf16 v[82:85], v[208:211], v[184:187], v[82:85]
	v_mfma_f32_16x16x32_bf16 v[70:73], v[200:203], v[192:195], v[70:73]
	v_mfma_f32_16x16x32_bf16 v[66:69], v[208:211], v[192:195], v[66:69]
	v_mfma_f32_16x16x32_bf16 v[118:121], v[204:207], v[172:175], v[118:121]
	v_mfma_f32_16x16x32_bf16 v[114:117], v[212:215], v[172:175], v[114:117]
	v_mfma_f32_16x16x32_bf16 v[102:105], v[204:207], v[180:183], v[102:105]
	v_mfma_f32_16x16x32_bf16 v[98:101], v[212:215], v[180:183], v[98:101]
	v_mfma_f32_16x16x32_bf16 v[86:89], v[204:207], v[188:191], v[86:89]
	v_mfma_f32_16x16x32_bf16 v[82:85], v[212:215], v[188:191], v[82:85]
	v_mfma_f32_16x16x32_bf16 v[70:73], v[204:207], v[196:199], v[70:73]
	v_mfma_f32_16x16x32_bf16 v[66:69], v[212:215], v[196:199], v[66:69]
	s_mov_b32 m0, s27
	v_lshl_add_u64 v[218:219], s[42:43], 0, v[136:137]
	s_barrier
	ds_read_b128 v[168:171], v148 offset:16384
	ds_read_b128 v[172:175], v148 offset:17408
	ds_read_b128 v[176:179], v148 offset:18432
	ds_read_b128 v[180:183], v148 offset:19456
	ds_read_b128 v[184:187], v148 offset:20480
	ds_read_b128 v[188:191], v148 offset:21504
	ds_read_b128 v[192:195], v148 offset:22528
	ds_read_b128 v[196:199], v148 offset:23552
	global_load_lds_dwordx4 v[218:219], off
	v_lshl_add_u64 v[220:221], s[42:43], 0, v[132:133]
	s_mov_b32 m0, s48
	s_nop 0
	global_load_lds_dwordx4 v[220:221], off
	s_waitcnt vmcnt(10)
	s_barrier
	s_waitcnt lgkmcnt(0)
	s_waitcnt lgkmcnt(0)
	v_mfma_f32_16x16x32_bf16 v[62:65], v[152:155], v[168:171], v[62:65]
	v_mfma_f32_16x16x32_bf16 v[58:61], v[160:163], v[168:171], v[58:61]
	v_mfma_f32_16x16x32_bf16 v[46:49], v[152:155], v[176:179], v[46:49]
	v_mfma_f32_16x16x32_bf16 v[42:45], v[160:163], v[176:179], v[42:45]
	v_mfma_f32_16x16x32_bf16 v[30:33], v[152:155], v[184:187], v[30:33]
	v_mfma_f32_16x16x32_bf16 v[26:29], v[160:163], v[184:187], v[26:29]
	v_mfma_f32_16x16x32_bf16 v[14:17], v[152:155], v[192:195], v[14:17]
	v_mfma_f32_16x16x32_bf16 v[10:13], v[160:163], v[192:195], v[10:13]
	v_mfma_f32_16x16x32_bf16 v[62:65], v[156:159], v[172:175], v[62:65]
	v_mfma_f32_16x16x32_bf16 v[58:61], v[164:167], v[172:175], v[58:61]
	v_mfma_f32_16x16x32_bf16 v[46:49], v[156:159], v[180:183], v[46:49]
	v_mfma_f32_16x16x32_bf16 v[42:45], v[164:167], v[180:183], v[42:45]
	v_mfma_f32_16x16x32_bf16 v[30:33], v[156:159], v[188:191], v[30:33]
	v_mfma_f32_16x16x32_bf16 v[26:29], v[164:167], v[188:191], v[26:29]
	v_mfma_f32_16x16x32_bf16 v[14:17], v[156:159], v[196:199], v[14:17]
	v_mfma_f32_16x16x32_bf16 v[10:13], v[164:167], v[196:199], v[10:13]
	s_barrier
	s_mov_b32 m0, s77
	v_lshl_add_u64 v[152:153], s[40:41], 0, v[134:135]
	global_load_lds_dwordx4 v[152:153], off
	v_lshl_add_u64 v[152:153], s[40:41], 0, v[130:131]
	s_mov_b32 m0, s1
	s_nop 0
	global_load_lds_dwordx4 v[152:153], off
	s_waitcnt vmcnt(10)
	s_barrier
	v_mfma_f32_16x16x32_bf16 v[54:57], v[200:203], v[168:171], v[54:57]
	v_mfma_f32_16x16x32_bf16 v[50:53], v[208:211], v[168:171], v[50:53]
	v_mfma_f32_16x16x32_bf16 v[38:41], v[200:203], v[176:179], v[38:41]
	v_mfma_f32_16x16x32_bf16 v[34:37], v[208:211], v[176:179], v[34:37]
	v_mfma_f32_16x16x32_bf16 v[22:25], v[200:203], v[184:187], v[22:25]
	v_mfma_f32_16x16x32_bf16 v[18:21], v[208:211], v[184:187], v[18:21]
	v_mfma_f32_16x16x32_bf16 v[6:9], v[200:203], v[192:195], v[6:9]
	v_mfma_f32_16x16x32_bf16 v[2:5], v[208:211], v[192:195], v[2:5]
	v_mfma_f32_16x16x32_bf16 v[54:57], v[204:207], v[172:175], v[54:57]
	v_mfma_f32_16x16x32_bf16 v[50:53], v[212:215], v[172:175], v[50:53]
	v_mfma_f32_16x16x32_bf16 v[38:41], v[204:207], v[180:183], v[38:41]
	v_mfma_f32_16x16x32_bf16 v[34:37], v[212:215], v[180:183], v[34:37]
	v_mfma_f32_16x16x32_bf16 v[22:25], v[204:207], v[188:191], v[22:25]
	v_mfma_f32_16x16x32_bf16 v[18:21], v[212:215], v[188:191], v[18:21]
	v_mfma_f32_16x16x32_bf16 v[6:9], v[204:207], v[196:199], v[6:9]
	v_mfma_f32_16x16x32_bf16 v[2:5], v[212:215], v[196:199], v[2:5]
	v_add_u32_e32 v151, s73, v146
	s_barrier
	ds_read_b128 v[152:155], v151
	ds_read_b128 v[156:159], v151 offset:1024
	ds_read_b128 v[160:163], v151 offset:2048
	ds_read_b128 v[164:167], v151 offset:3072
	s_mov_b32 m0, s49
	v_lshl_add_u64 v[200:201], s[38:39], 0, v[136:137]
	ds_read_b128 v[168:171], v148 offset:32768
	ds_read_b128 v[172:175], v148 offset:33792
	ds_read_b128 v[176:179], v148 offset:34816
	ds_read_b128 v[180:183], v148 offset:35840
	ds_read_b128 v[184:187], v148 offset:36864
	ds_read_b128 v[188:191], v148 offset:37888
	ds_read_b128 v[192:195], v148 offset:38912
	ds_read_b128 v[196:199], v148 offset:39936
	global_load_lds_dwordx4 v[200:201], off
	v_lshl_add_u64 v[200:201], s[38:39], 0, v[132:133]
	s_mov_b32 m0, s50
	s_nop 0
	global_load_lds_dwordx4 v[200:201], off
	s_waitcnt lgkmcnt(8)
	s_waitcnt vmcnt(10)
	s_barrier
	s_waitcnt lgkmcnt(0)
	s_waitcnt lgkmcnt(0)
	v_mfma_f32_16x16x32_bf16 v[126:129], v[152:155], v[168:171], v[126:129]
	v_mfma_f32_16x16x32_bf16 v[122:125], v[160:163], v[168:171], v[122:125]
	v_mfma_f32_16x16x32_bf16 v[110:113], v[152:155], v[176:179], v[110:113]
	v_mfma_f32_16x16x32_bf16 v[106:109], v[160:163], v[176:179], v[106:109]
	v_mfma_f32_16x16x32_bf16 v[94:97], v[152:155], v[184:187], v[94:97]
	v_mfma_f32_16x16x32_bf16 v[90:93], v[160:163], v[184:187], v[90:93]
	v_mfma_f32_16x16x32_bf16 v[78:81], v[152:155], v[192:195], v[78:81]
	v_mfma_f32_16x16x32_bf16 v[74:77], v[160:163], v[192:195], v[74:77]
	v_mfma_f32_16x16x32_bf16 v[126:129], v[156:159], v[172:175], v[126:129]
	v_mfma_f32_16x16x32_bf16 v[122:125], v[164:167], v[172:175], v[122:125]
	v_mfma_f32_16x16x32_bf16 v[110:113], v[156:159], v[180:183], v[110:113]
	v_mfma_f32_16x16x32_bf16 v[106:109], v[164:167], v[180:183], v[106:109]
	v_mfma_f32_16x16x32_bf16 v[94:97], v[156:159], v[188:191], v[94:97]
	v_mfma_f32_16x16x32_bf16 v[90:93], v[164:167], v[188:191], v[90:93]
	v_mfma_f32_16x16x32_bf16 v[78:81], v[156:159], v[196:199], v[78:81]
	v_mfma_f32_16x16x32_bf16 v[74:77], v[164:167], v[196:199], v[74:77]
	s_barrier
	s_mov_b32 m0, s72
	v_add_u32_e32 v151, s69, v146
	v_lshl_add_u64 v[142:143], v[142:143], 0, s[16:17]
	ds_read_b128 v[200:203], v151
	ds_read_b128 v[204:207], v151 offset:1024
	ds_read_b128 v[208:211], v151 offset:2048
	ds_read_b128 v[212:215], v151 offset:3072
	global_load_lds_dwordx4 v[142:143], off
	v_lshl_add_u64 v[142:143], v[216:217], 0, s[16:17]
	s_mov_b32 m0, s67
	s_nop 0
	global_load_lds_dwordx4 v[142:143], off
	s_waitcnt vmcnt(10)
	s_barrier
	s_waitcnt lgkmcnt(0)
	s_waitcnt lgkmcnt(0)
	v_mfma_f32_16x16x32_bf16 v[118:121], v[200:203], v[168:171], v[118:121]
	v_mfma_f32_16x16x32_bf16 v[114:117], v[208:211], v[168:171], v[114:117]
	v_mfma_f32_16x16x32_bf16 v[102:105], v[200:203], v[176:179], v[102:105]
	v_mfma_f32_16x16x32_bf16 v[98:101], v[208:211], v[176:179], v[98:101]
	v_mfma_f32_16x16x32_bf16 v[86:89], v[200:203], v[184:187], v[86:89]
	v_mfma_f32_16x16x32_bf16 v[82:85], v[208:211], v[184:187], v[82:85]
	v_mfma_f32_16x16x32_bf16 v[70:73], v[200:203], v[192:195], v[70:73]
	v_mfma_f32_16x16x32_bf16 v[66:69], v[208:211], v[192:195], v[66:69]
	v_mfma_f32_16x16x32_bf16 v[118:121], v[204:207], v[172:175], v[118:121]
	v_mfma_f32_16x16x32_bf16 v[114:117], v[212:215], v[172:175], v[114:117]
	v_mfma_f32_16x16x32_bf16 v[102:105], v[204:207], v[180:183], v[102:105]
	v_mfma_f32_16x16x32_bf16 v[98:101], v[212:215], v[180:183], v[98:101]
	v_mfma_f32_16x16x32_bf16 v[86:89], v[204:207], v[188:191], v[86:89]
	v_mfma_f32_16x16x32_bf16 v[82:85], v[212:215], v[188:191], v[82:85]
	v_mfma_f32_16x16x32_bf16 v[70:73], v[204:207], v[196:199], v[70:73]
	v_mfma_f32_16x16x32_bf16 v[66:69], v[212:215], v[196:199], v[66:69]
	s_mov_b32 m0, s56
	v_lshl_add_u64 v[142:143], v[218:219], 0, s[16:17]
	s_barrier
	ds_read_b128 v[168:171], v148 offset:49152
	ds_read_b128 v[172:175], v148 offset:50176
	ds_read_b128 v[176:179], v148 offset:51200
	ds_read_b128 v[180:183], v148 offset:52224
	ds_read_b128 v[184:187], v148 offset:53248
	ds_read_b128 v[188:191], v148 offset:54272
	ds_read_b128 v[192:195], v148 offset:55296
	ds_read_b128 v[196:199], v148 offset:56320
	global_load_lds_dwordx4 v[142:143], off
	v_lshl_add_u64 v[142:143], v[220:221], 0, s[16:17]
	s_mov_b32 m0, s57
	s_nop 0
	global_load_lds_dwordx4 v[142:143], off
	s_waitcnt vmcnt(10)
	s_barrier
	s_waitcnt lgkmcnt(0)
	s_waitcnt lgkmcnt(0)
	v_mfma_f32_16x16x32_bf16 v[62:65], v[152:155], v[168:171], v[62:65]
	v_mfma_f32_16x16x32_bf16 v[58:61], v[160:163], v[168:171], v[58:61]
	v_mfma_f32_16x16x32_bf16 v[46:49], v[152:155], v[176:179], v[46:49]
	v_mfma_f32_16x16x32_bf16 v[42:45], v[160:163], v[176:179], v[42:45]
	v_mfma_f32_16x16x32_bf16 v[30:33], v[152:155], v[184:187], v[30:33]
	v_mfma_f32_16x16x32_bf16 v[26:29], v[160:163], v[184:187], v[26:29]
	v_mfma_f32_16x16x32_bf16 v[14:17], v[152:155], v[192:195], v[14:17]
	v_mfma_f32_16x16x32_bf16 v[10:13], v[160:163], v[192:195], v[10:13]
	v_mfma_f32_16x16x32_bf16 v[62:65], v[156:159], v[172:175], v[62:65]
	v_mfma_f32_16x16x32_bf16 v[58:61], v[164:167], v[172:175], v[58:61]
	v_mfma_f32_16x16x32_bf16 v[46:49], v[156:159], v[180:183], v[46:49]
	v_mfma_f32_16x16x32_bf16 v[42:45], v[164:167], v[180:183], v[42:45]
	v_mfma_f32_16x16x32_bf16 v[30:33], v[156:159], v[188:191], v[30:33]
	v_mfma_f32_16x16x32_bf16 v[26:29], v[164:167], v[188:191], v[26:29]
	v_mfma_f32_16x16x32_bf16 v[14:17], v[156:159], v[196:199], v[14:17]
	v_mfma_f32_16x16x32_bf16 v[10:13], v[164:167], v[196:199], v[10:13]
	s_barrier
	s_mov_b32 m0, s65
	v_lshl_add_u64 v[142:143], s[36:37], 0, v[134:135]
	global_load_lds_dwordx4 v[142:143], off
	v_lshl_add_u64 v[142:143], s[36:37], 0, v[130:131]
	s_mov_b32 m0, s64
	s_nop 0
	global_load_lds_dwordx4 v[142:143], off
	s_waitcnt vmcnt(10)
	s_barrier
	v_mfma_f32_16x16x32_bf16 v[54:57], v[200:203], v[168:171], v[54:57]
	v_mfma_f32_16x16x32_bf16 v[50:53], v[208:211], v[168:171], v[50:53]
	v_mfma_f32_16x16x32_bf16 v[38:41], v[200:203], v[176:179], v[38:41]
	v_mfma_f32_16x16x32_bf16 v[34:37], v[208:211], v[176:179], v[34:37]
	v_mfma_f32_16x16x32_bf16 v[22:25], v[200:203], v[184:187], v[22:25]
	v_mfma_f32_16x16x32_bf16 v[18:21], v[208:211], v[184:187], v[18:21]
	v_mfma_f32_16x16x32_bf16 v[6:9], v[200:203], v[192:195], v[6:9]
	v_mfma_f32_16x16x32_bf16 v[2:5], v[208:211], v[192:195], v[2:5]
	v_mfma_f32_16x16x32_bf16 v[54:57], v[204:207], v[172:175], v[54:57]
	v_mfma_f32_16x16x32_bf16 v[50:53], v[212:215], v[172:175], v[50:53]
	v_mfma_f32_16x16x32_bf16 v[38:41], v[204:207], v[180:183], v[38:41]
	v_mfma_f32_16x16x32_bf16 v[34:37], v[212:215], v[180:183], v[34:37]
	v_mfma_f32_16x16x32_bf16 v[22:25], v[204:207], v[188:191], v[22:25]
	v_mfma_f32_16x16x32_bf16 v[18:21], v[212:215], v[188:191], v[18:21]
	v_mfma_f32_16x16x32_bf16 v[6:9], v[204:207], v[196:199], v[6:9]
	v_mfma_f32_16x16x32_bf16 v[2:5], v[212:215], v[196:199], v[2:5]
	s_movk_i32 s38, 0x100
	s_andn2_b64 vcc, exec, s[34:35]
	s_mov_b64 s[36:37], -1
	s_mov_b64 s[34:35], 0
	s_barrier
	s_cbranch_vccz .LBB0_2344
	s_lshl_b32 s0, s26, 8
	v_mov_b32_e32 v143, v144
	s_add_i32 s0, s0, s53
	v_mov_b32_e32 v142, v145
	v_add_u32_e32 v151, s0, v143
	v_mov_b32_e32 v154, v151
	v_max_f32_e32 v126, v126, v126
	v_ashrrev_i32_e32 v152, 8, v154
	v_and_b32_e32 v152, -8, v152
	v_add_u32_e32 v152, s55, v152
	v_ashrrev_i32_e32 v153, 31, v152
	v_lshlrev_b64 v[152:153], 11, v[152:153]
	v_and_or_b32 v152, v154, s60, v152
	v_med3_f32 v154, v126, s61, v150
	v_max_f32_e32 v126, v127, v127
	v_med3_f32 v127, v126, s61, v150
	v_mov_b32_e32 v126, 0
	v_cvt_pk_fp8_f32 v126, v154, v127
	v_max_f32_e32 v127, v128, v128
	v_max_f32_e32 v128, v129, v129
	v_med3_f32 v127, v127, s61, v150
	v_med3_f32 v128, v128, s61, v150
	v_max_f32_e32 v122, v122, v122
	v_max_f32_e32 v123, v123, v123
	v_cvt_pk_fp8_f32 v126, v127, v128 op_sel:[0,0,1]
	v_med3_f32 v122, v122, s61, v150
	v_med3_f32 v123, v123, s61, v150
	v_mov_b32_e32 v127, 0
	v_cvt_pk_fp8_f32 v127, v122, v123
	v_max_f32_e32 v122, v124, v124
	v_max_f32_e32 v123, v125, v125
	v_med3_f32 v122, v122, s61, v150
	v_med3_f32 v123, v123, s61, v150
	v_lshl_add_u32 v142, v142, 3, s54
	v_cvt_pk_fp8_f32 v127, v122, v123 op_sel:[0,0,1]
	v_mov_b64_e32 v[122:123], s[12:13]
	v_ashrrev_i32_e32 v143, 31, v142
	v_mad_u64_u32 v[124:125], s[0:1], v152, s51, v[122:123]
	v_cvt_pk_bf16_f32 v118, v118, v119
	v_cvt_pk_bf16_f32 v119, v120, v121
	v_cvt_pk_bf16_f32 v120, v114, v115
	v_lshlrev_b64 v[114:115], 8, v[152:153]
	v_mad_i32_i24 v125, v153, s51, v125
	v_cvt_pk_bf16_f32 v121, v116, v117
	v_lshl_add_u64 v[116:117], s[14:15], 0, v[114:115]
	v_lshlrev_b64 v[114:115], 1, v[142:143]
	v_lshl_add_u64 v[124:125], v[124:125], 0, v[142:143]
	v_lshl_add_u64 v[116:117], v[116:117], 0, v[114:115]
	flat_store_dwordx2 v[124:125], v[126:127]
	flat_store_dwordx4 v[116:117], v[118:121]
	v_max_f32_e32 v110, v110, v110
	v_max_f32_e32 v106, v106, v106
	v_add_u32_e32 v118, 16, v151
	v_max_f32_e32 v107, v107, v107
	v_ashrrev_i32_e32 v116, 8, v118
	v_and_b32_e32 v116, -8, v116
	v_add_u32_e32 v116, s55, v116
	v_ashrrev_i32_e32 v117, 31, v116
	v_lshlrev_b64 v[116:117], 11, v[116:117]
	v_and_or_b32 v116, v118, s60, v116
	v_med3_f32 v118, v110, s61, v150
	v_max_f32_e32 v110, v111, v111
	v_med3_f32 v111, v110, s61, v150
	v_mov_b32_e32 v110, 0
	v_cvt_pk_fp8_f32 v110, v118, v111
	v_max_f32_e32 v111, v112, v112
	v_max_f32_e32 v112, v113, v113
	v_med3_f32 v111, v111, s61, v150
	v_med3_f32 v112, v112, s61, v150
	v_cvt_pk_fp8_f32 v110, v111, v112 op_sel:[0,0,1]
	v_med3_f32 v106, v106, s61, v150
	v_med3_f32 v107, v107, s61, v150
	v_mov_b32_e32 v111, 0
	v_cvt_pk_fp8_f32 v111, v106, v107
	v_max_f32_e32 v106, v108, v108
	v_max_f32_e32 v107, v109, v109
	v_med3_f32 v106, v106, s61, v150
	v_med3_f32 v107, v107, s61, v150
	v_cvt_pk_fp8_f32 v111, v106, v107 op_sel:[0,0,1]
	v_mad_u64_u32 v[106:107], s[0:1], v116, s51, v[122:123]
	v_cvt_pk_bf16_f32 v102, v102, v103
	v_cvt_pk_bf16_f32 v103, v104, v105
	v_cvt_pk_bf16_f32 v104, v98, v99
	v_lshlrev_b64 v[98:99], 8, v[116:117]
	v_mad_i32_i24 v107, v117, s51, v107
	v_lshl_add_u64 v[98:99], s[14:15], 0, v[98:99]
	v_lshl_add_u64 v[106:107], v[106:107], 0, v[142:143]
	v_cvt_pk_bf16_f32 v105, v100, v101
	v_lshl_add_u64 v[98:99], v[98:99], 0, v[114:115]
	v_add_u32_e32 v100, 32, v151
	flat_store_dwordx2 v[106:107], v[110:111]
	flat_store_dwordx4 v[98:99], v[102:105]
	v_max_f32_e32 v94, v94, v94
	v_ashrrev_i32_e32 v98, 8, v100
	v_and_b32_e32 v98, -8, v98
	v_add_u32_e32 v98, s55, v98
	v_ashrrev_i32_e32 v99, 31, v98
	v_lshlrev_b64 v[98:99], 11, v[98:99]
	v_and_or_b32 v98, v100, s60, v98
	v_med3_f32 v100, v94, s61, v150
	v_max_f32_e32 v94, v95, v95
	v_med3_f32 v95, v94, s61, v150
	v_mov_b32_e32 v94, 0
	v_cvt_pk_fp8_f32 v94, v100, v95
	v_max_f32_e32 v95, v96, v96
	v_max_f32_e32 v96, v97, v97
	v_med3_f32 v95, v95, s61, v150
	v_med3_f32 v96, v96, s61, v150
	v_max_f32_e32 v90, v90, v90
	v_max_f32_e32 v91, v91, v91
	v_cvt_pk_fp8_f32 v94, v95, v96 op_sel:[0,0,1]
	v_med3_f32 v90, v90, s61, v150
	v_med3_f32 v91, v91, s61, v150
	v_mov_b32_e32 v95, 0
	v_cvt_pk_fp8_f32 v95, v90, v91
	v_max_f32_e32 v90, v92, v92
	v_max_f32_e32 v91, v93, v93
	v_med3_f32 v90, v90, s61, v150
	v_med3_f32 v91, v91, s61, v150
	v_cvt_pk_fp8_f32 v95, v90, v91 op_sel:[0,0,1]
	v_mad_u64_u32 v[90:91], s[0:1], v98, s51, v[122:123]
	v_cvt_pk_bf16_f32 v86, v86, v87
	v_cvt_pk_bf16_f32 v87, v88, v89
	v_cvt_pk_bf16_f32 v88, v82, v83
	v_lshlrev_b64 v[82:83], 8, v[98:99]
	v_mad_i32_i24 v91, v99, s51, v91
	v_lshl_add_u64 v[82:83], s[14:15], 0, v[82:83]
	v_lshl_add_u64 v[90:91], v[90:91], 0, v[142:143]
	v_cvt_pk_bf16_f32 v89, v84, v85
	v_lshl_add_u64 v[82:83], v[82:83], 0, v[114:115]
	v_add_u32_e32 v84, 48, v151
	flat_store_dwordx2 v[90:91], v[94:95]
	flat_store_dwordx4 v[82:83], v[86:89]
	v_max_f32_e32 v78, v78, v78
	v_ashrrev_i32_e32 v82, 8, v84
	v_and_b32_e32 v82, -8, v82
	v_add_u32_e32 v82, s55, v82
	v_ashrrev_i32_e32 v83, 31, v82
	v_lshlrev_b64 v[82:83], 11, v[82:83]
	v_and_or_b32 v82, v84, s60, v82
	v_med3_f32 v84, v78, s61, v150
	v_max_f32_e32 v78, v79, v79
	v_med3_f32 v79, v78, s61, v150
	v_mov_b32_e32 v78, 0
	v_cvt_pk_fp8_f32 v78, v84, v79
	v_max_f32_e32 v79, v80, v80
	v_max_f32_e32 v80, v81, v81
	v_med3_f32 v79, v79, s61, v150
	v_med3_f32 v80, v80, s61, v150
	v_max_f32_e32 v74, v74, v74
	v_max_f32_e32 v75, v75, v75
	v_cvt_pk_fp8_f32 v78, v79, v80 op_sel:[0,0,1]
	v_med3_f32 v74, v74, s61, v150
	v_med3_f32 v75, v75, s61, v150
	v_mov_b32_e32 v79, 0
	v_cvt_pk_fp8_f32 v79, v74, v75
	v_max_f32_e32 v74, v76, v76
	v_max_f32_e32 v75, v77, v77
	v_med3_f32 v74, v74, s61, v150
	v_med3_f32 v75, v75, s61, v150
	v_cvt_pk_fp8_f32 v79, v74, v75 op_sel:[0,0,1]
	v_mad_u64_u32 v[74:75], s[0:1], v82, s51, v[122:123]
	v_cvt_pk_bf16_f32 v70, v70, v71
	v_cvt_pk_bf16_f32 v71, v72, v73
	v_cvt_pk_bf16_f32 v72, v66, v67
	v_lshlrev_b64 v[66:67], 8, v[82:83]
	v_mad_i32_i24 v75, v83, s51, v75
	v_lshl_add_u64 v[66:67], s[14:15], 0, v[66:67]
	v_lshl_add_u64 v[74:75], v[74:75], 0, v[142:143]
	v_cvt_pk_bf16_f32 v73, v68, v69
	v_lshl_add_u64 v[66:67], v[66:67], 0, v[114:115]
	v_add_u32_e32 v68, 0x80, v151
	flat_store_dwordx2 v[74:75], v[78:79]
	flat_store_dwordx4 v[66:67], v[70:73]
	v_max_f32_e32 v62, v62, v62
	v_ashrrev_i32_e32 v66, 8, v68
	v_and_b32_e32 v66, -8, v66
	v_add_u32_e32 v66, s55, v66
	v_ashrrev_i32_e32 v67, 31, v66
	v_lshlrev_b64 v[66:67], 11, v[66:67]
	v_and_or_b32 v66, v68, s60, v66
	v_med3_f32 v68, v62, s61, v150
	v_max_f32_e32 v62, v63, v63
	v_med3_f32 v63, v62, s61, v150
	v_mov_b32_e32 v62, 0
	v_cvt_pk_fp8_f32 v62, v68, v63
	v_max_f32_e32 v63, v64, v64
	v_max_f32_e32 v64, v65, v65
	v_med3_f32 v63, v63, s61, v150
	v_med3_f32 v64, v64, s61, v150
	v_max_f32_e32 v58, v58, v58
	v_max_f32_e32 v59, v59, v59
	v_cvt_pk_fp8_f32 v62, v63, v64 op_sel:[0,0,1]
	v_med3_f32 v58, v58, s61, v150
	v_med3_f32 v59, v59, s61, v150
	v_mov_b32_e32 v63, 0
	v_cvt_pk_fp8_f32 v63, v58, v59
	v_max_f32_e32 v58, v60, v60
	v_max_f32_e32 v59, v61, v61
	v_med3_f32 v58, v58, s61, v150
	v_med3_f32 v59, v59, s61, v150
	v_cvt_pk_fp8_f32 v63, v58, v59 op_sel:[0,0,1]
	v_mad_u64_u32 v[58:59], s[0:1], v66, s51, v[122:123]
	v_cvt_pk_bf16_f32 v54, v54, v55
	v_cvt_pk_bf16_f32 v55, v56, v57
	v_cvt_pk_bf16_f32 v56, v50, v51
	v_lshlrev_b64 v[50:51], 8, v[66:67]
	v_mad_i32_i24 v59, v67, s51, v59
	v_lshl_add_u64 v[50:51], s[14:15], 0, v[50:51]
	v_lshl_add_u64 v[58:59], v[58:59], 0, v[142:143]
	v_cvt_pk_bf16_f32 v57, v52, v53
	v_lshl_add_u64 v[50:51], v[50:51], 0, v[114:115]
	v_add_u32_e32 v52, 0x90, v151
	flat_store_dwordx2 v[58:59], v[62:63]
	flat_store_dwordx4 v[50:51], v[54:57]
	v_max_f32_e32 v46, v46, v46
	v_ashrrev_i32_e32 v50, 8, v52
	v_and_b32_e32 v50, -8, v50
	v_add_u32_e32 v50, s55, v50
	v_ashrrev_i32_e32 v51, 31, v50
	v_lshlrev_b64 v[50:51], 11, v[50:51]
	v_and_or_b32 v50, v52, s60, v50
	v_med3_f32 v52, v46, s61, v150
	v_max_f32_e32 v46, v47, v47
	v_med3_f32 v47, v46, s61, v150
	v_mov_b32_e32 v46, 0
	v_cvt_pk_fp8_f32 v46, v52, v47
	v_max_f32_e32 v47, v48, v48
	v_max_f32_e32 v48, v49, v49
	v_med3_f32 v47, v47, s61, v150
	v_med3_f32 v48, v48, s61, v150
	v_max_f32_e32 v42, v42, v42
	v_max_f32_e32 v43, v43, v43
	v_cvt_pk_fp8_f32 v46, v47, v48 op_sel:[0,0,1]
	v_med3_f32 v42, v42, s61, v150
	v_med3_f32 v43, v43, s61, v150
	v_mov_b32_e32 v47, 0
	v_cvt_pk_fp8_f32 v47, v42, v43
	v_max_f32_e32 v42, v44, v44
	v_max_f32_e32 v43, v45, v45
	v_med3_f32 v42, v42, s61, v150
	v_med3_f32 v43, v43, s61, v150
	v_cvt_pk_fp8_f32 v47, v42, v43 op_sel:[0,0,1]
	v_mad_u64_u32 v[42:43], s[0:1], v50, s51, v[122:123]
	v_cvt_pk_bf16_f32 v38, v38, v39
	v_cvt_pk_bf16_f32 v39, v40, v41
	v_cvt_pk_bf16_f32 v40, v34, v35
	v_lshlrev_b64 v[34:35], 8, v[50:51]
	v_mad_i32_i24 v43, v51, s51, v43
	v_lshl_add_u64 v[34:35], s[14:15], 0, v[34:35]
	v_lshl_add_u64 v[42:43], v[42:43], 0, v[142:143]
	v_cvt_pk_bf16_f32 v41, v36, v37
	v_lshl_add_u64 v[34:35], v[34:35], 0, v[114:115]
	v_add_u32_e32 v36, 0xa0, v151
	flat_store_dwordx2 v[42:43], v[46:47]
	flat_store_dwordx4 v[34:35], v[38:41]
	v_max_f32_e32 v30, v30, v30
	v_ashrrev_i32_e32 v34, 8, v36
	v_and_b32_e32 v34, -8, v34
	v_add_u32_e32 v34, s55, v34
	v_ashrrev_i32_e32 v35, 31, v34
	v_lshlrev_b64 v[34:35], 11, v[34:35]
	v_and_or_b32 v34, v36, s60, v34
	v_med3_f32 v36, v30, s61, v150
	v_max_f32_e32 v30, v31, v31
	v_med3_f32 v31, v30, s61, v150
	v_mov_b32_e32 v30, 0
	v_cvt_pk_fp8_f32 v30, v36, v31
	v_max_f32_e32 v31, v32, v32
	v_max_f32_e32 v32, v33, v33
	v_med3_f32 v31, v31, s61, v150
	v_med3_f32 v32, v32, s61, v150
	v_max_f32_e32 v26, v26, v26
	v_max_f32_e32 v27, v27, v27
	v_cvt_pk_fp8_f32 v30, v31, v32 op_sel:[0,0,1]
	v_med3_f32 v26, v26, s61, v150
	v_med3_f32 v27, v27, s61, v150
	v_mov_b32_e32 v31, 0
	v_cvt_pk_fp8_f32 v31, v26, v27
	v_max_f32_e32 v26, v28, v28
	v_max_f32_e32 v27, v29, v29
	v_med3_f32 v26, v26, s61, v150
	v_med3_f32 v27, v27, s61, v150
	v_cvt_pk_fp8_f32 v31, v26, v27 op_sel:[0,0,1]
	v_mad_u64_u32 v[26:27], s[0:1], v34, s51, v[122:123]
	v_cvt_pk_bf16_f32 v22, v22, v23
	v_cvt_pk_bf16_f32 v23, v24, v25
	v_cvt_pk_bf16_f32 v24, v18, v19
	v_lshlrev_b64 v[18:19], 8, v[34:35]
	v_mad_i32_i24 v27, v35, s51, v27
	v_lshl_add_u64 v[18:19], s[14:15], 0, v[18:19]
	v_lshl_add_u64 v[26:27], v[26:27], 0, v[142:143]
	v_cvt_pk_bf16_f32 v25, v20, v21
	v_lshl_add_u64 v[18:19], v[18:19], 0, v[114:115]
	v_add_u32_e32 v20, 0xb0, v151
	flat_store_dwordx2 v[26:27], v[30:31]
	flat_store_dwordx4 v[18:19], v[22:25]
	v_max_f32_e32 v14, v14, v14
	v_ashrrev_i32_e32 v18, 8, v20
	v_and_b32_e32 v18, -8, v18
	v_add_u32_e32 v18, s55, v18
	v_ashrrev_i32_e32 v19, 31, v18
	v_lshlrev_b64 v[18:19], 11, v[18:19]
	v_and_or_b32 v18, v20, s60, v18
	v_med3_f32 v20, v14, s61, v150
	v_max_f32_e32 v14, v15, v15
	v_med3_f32 v15, v14, s61, v150
	v_mov_b32_e32 v14, 0
	v_cvt_pk_fp8_f32 v14, v20, v15
	v_max_f32_e32 v15, v16, v16
	v_max_f32_e32 v16, v17, v17
	v_med3_f32 v15, v15, s61, v150
	v_med3_f32 v16, v16, s61, v150
	v_max_f32_e32 v10, v10, v10
	v_max_f32_e32 v11, v11, v11
	v_cvt_pk_fp8_f32 v14, v15, v16 op_sel:[0,0,1]
	v_med3_f32 v10, v10, s61, v150
	v_med3_f32 v11, v11, s61, v150
	v_mov_b32_e32 v15, 0
	v_cvt_pk_fp8_f32 v15, v10, v11
	v_max_f32_e32 v10, v12, v12
	v_max_f32_e32 v11, v13, v13
	v_med3_f32 v10, v10, s61, v150
	v_med3_f32 v11, v11, s61, v150
	v_cvt_pk_fp8_f32 v15, v10, v11 op_sel:[0,0,1]
	v_mad_u64_u32 v[10:11], s[0:1], v18, s51, v[122:123]
	v_cvt_pk_bf16_f32 v6, v6, v7
	v_cvt_pk_bf16_f32 v7, v8, v9
	v_cvt_pk_bf16_f32 v8, v2, v3
	v_lshlrev_b64 v[2:3], 8, v[18:19]
	v_mad_i32_i24 v11, v19, s51, v11
	v_lshl_add_u64 v[2:3], s[14:15], 0, v[2:3]
	v_readlane_b32 s72, v254, 2
	v_lshl_add_u64 v[10:11], v[10:11], 0, v[142:143]
	v_cvt_pk_bf16_f32 v9, v4, v5
	v_lshl_add_u64 v[2:3], v[2:3], 0, v[114:115]
	s_and_b64 vcc, exec, s[10:11]
	s_mov_b32 s55, s18
	s_mov_b32 s26, s20
	s_mov_b64 s[28:29], s[24:25]
	s_mov_b64 s[30:31], s[22:23]
	v_readlane_b32 s73, v254, 3
	flat_store_dwordx2 v[10:11], v[14:15]
	flat_store_dwordx4 v[2:3], v[6:9]
	s_cbranch_vccz .LBB0_2337
	s_waitcnt vmcnt(0)
	s_cmpk_gt_u32 s5, 0xff
	s_cbranch_scc1 .LBB0_2348
	s_barrier

.LBB0_2495:
	ds_read_b128 v[130:133], v168
	ds_read_b128 v[134:137], v168 offset:1024
	ds_read_b128 v[138:141], v168 offset:2048
	ds_read_b128 v[142:145], v168 offset:3072
	s_add_u32 s0, s36, 0xfffc0080
	s_addc_u32 s1, s37, -1
	s_cmp_eq_u32 s69, 12
	s_cselect_b32 s41, s61, s1
	s_cselect_b32 s40, s62, s0
	s_cselect_b32 s39, s63, s67
	s_cselect_b32 s38, s64, s65
	s_mov_b32 m0, s51
	v_lshl_add_u64 v[164:165], s[36:37], 0, v[162:163]
	ds_read_b128 v[146:149], v169
	ds_read_b128 v[172:175], v169 offset:1024
	ds_read_b128 v[176:179], v169 offset:2048
	ds_read_b128 v[180:183], v169 offset:3072
	ds_read_b128 v[184:187], v169 offset:4096
	ds_read_b128 v[188:191], v169 offset:5120
	ds_read_b128 v[192:195], v169 offset:6144
	ds_read_b128 v[196:199], v169 offset:7168
	global_load_lds_dwordx4 v[164:165], off
	v_lshl_add_u64 v[164:165], s[36:37], 0, v[160:161]
	s_mov_b32 m0, s52
	s_nop 0
	global_load_lds_dwordx4 v[164:165], off
	s_waitcnt lgkmcnt(8)
	s_waitcnt vmcnt(10)
	s_barrier
	s_waitcnt lgkmcnt(0)
	s_waitcnt lgkmcnt(0)
	v_mfma_f32_16x16x32_bf16 v[126:129], v[130:133], v[146:149], v[126:129]
	v_mfma_f32_16x16x32_bf16 v[122:125], v[138:141], v[146:149], v[122:125]
	v_mfma_f32_16x16x32_bf16 v[118:121], v[130:133], v[176:179], v[118:121]
	v_mfma_f32_16x16x32_bf16 v[110:113], v[138:141], v[176:179], v[110:113]
	v_mfma_f32_16x16x32_bf16 v[98:101], v[130:133], v[184:187], v[98:101]
	v_mfma_f32_16x16x32_bf16 v[90:93], v[138:141], v[184:187], v[90:93]
	v_mfma_f32_16x16x32_bf16 v[82:85], v[130:133], v[192:195], v[82:85]
	v_mfma_f32_16x16x32_bf16 v[74:77], v[138:141], v[192:195], v[74:77]
	v_mfma_f32_16x16x32_bf16 v[126:129], v[134:137], v[172:175], v[126:129]
	v_mfma_f32_16x16x32_bf16 v[122:125], v[142:145], v[172:175], v[122:125]
	v_mfma_f32_16x16x32_bf16 v[118:121], v[134:137], v[180:183], v[118:121]
	v_mfma_f32_16x16x32_bf16 v[110:113], v[142:145], v[180:183], v[110:113]
	v_mfma_f32_16x16x32_bf16 v[98:101], v[134:137], v[188:191], v[98:101]
	v_mfma_f32_16x16x32_bf16 v[90:93], v[142:145], v[188:191], v[90:93]
	v_mfma_f32_16x16x32_bf16 v[82:85], v[134:137], v[196:199], v[82:85]
	v_mfma_f32_16x16x32_bf16 v[74:77], v[142:145], v[196:199], v[74:77]
	s_barrier
	s_mov_b32 m0, s53
	v_lshl_add_u64 v[164:165], s[38:39], 0, v[156:157]
	ds_read_b128 v[200:203], v170
	ds_read_b128 v[204:207], v170 offset:1024
	ds_read_b128 v[208:211], v170 offset:2048
	ds_read_b128 v[212:215], v170 offset:3072
	global_load_lds_dwordx4 v[164:165], off
	v_lshl_add_u64 v[216:217], s[38:39], 0, v[152:153]
	s_mov_b32 m0, s54
	s_nop 0
	global_load_lds_dwordx4 v[216:217], off
	s_waitcnt vmcnt(10)
	s_barrier
	s_waitcnt lgkmcnt(0)
	s_waitcnt lgkmcnt(0)
	v_mfma_f32_16x16x32_bf16 v[114:117], v[200:203], v[146:149], v[114:117]
	v_mfma_f32_16x16x32_bf16 v[106:109], v[208:211], v[146:149], v[106:109]
	v_mfma_f32_16x16x32_bf16 v[102:105], v[200:203], v[176:179], v[102:105]
	v_mfma_f32_16x16x32_bf16 v[94:97], v[208:211], v[176:179], v[94:97]
	v_mfma_f32_16x16x32_bf16 v[86:89], v[200:203], v[184:187], v[86:89]
	v_mfma_f32_16x16x32_bf16 v[78:81], v[208:211], v[184:187], v[78:81]
	v_mfma_f32_16x16x32_bf16 v[70:73], v[200:203], v[192:195], v[70:73]
	v_mfma_f32_16x16x32_bf16 v[66:69], v[208:211], v[192:195], v[66:69]
	v_mfma_f32_16x16x32_bf16 v[114:117], v[204:207], v[172:175], v[114:117]
	v_mfma_f32_16x16x32_bf16 v[106:109], v[212:215], v[172:175], v[106:109]
	v_mfma_f32_16x16x32_bf16 v[102:105], v[204:207], v[180:183], v[102:105]
	v_mfma_f32_16x16x32_bf16 v[94:97], v[212:215], v[180:183], v[94:97]
	v_mfma_f32_16x16x32_bf16 v[86:89], v[204:207], v[188:191], v[86:89]
	v_mfma_f32_16x16x32_bf16 v[78:81], v[212:215], v[188:191], v[78:81]
	v_mfma_f32_16x16x32_bf16 v[70:73], v[204:207], v[196:199], v[70:73]
	v_mfma_f32_16x16x32_bf16 v[66:69], v[212:215], v[196:199], v[66:69]
	s_mov_b32 m0, s9
	v_lshl_add_u64 v[218:219], s[40:41], 0, v[158:159]
	s_barrier
	ds_read_b128 v[146:149], v169 offset:16384
	ds_read_b128 v[172:175], v169 offset:17408
	ds_read_b128 v[176:179], v169 offset:18432
	ds_read_b128 v[180:183], v169 offset:19456
	ds_read_b128 v[184:187], v169 offset:20480
	ds_read_b128 v[188:191], v169 offset:21504
	ds_read_b128 v[192:195], v169 offset:22528
	ds_read_b128 v[196:199], v169 offset:23552
	global_load_lds_dwordx4 v[218:219], off
	v_lshl_add_u64 v[220:221], s[40:41], 0, v[154:155]
	s_mov_b32 m0, s29
	s_nop 0
	global_load_lds_dwordx4 v[220:221], off
	s_waitcnt vmcnt(10)
	s_barrier
	s_waitcnt lgkmcnt(0)
	s_waitcnt lgkmcnt(0)
	v_mfma_f32_16x16x32_bf16 v[62:65], v[130:133], v[146:149], v[62:65]
	v_mfma_f32_16x16x32_bf16 v[58:61], v[138:141], v[146:149], v[58:61]
	v_mfma_f32_16x16x32_bf16 v[50:53], v[130:133], v[176:179], v[50:53]
	v_mfma_f32_16x16x32_bf16 v[42:45], v[138:141], v[176:179], v[42:45]
	v_mfma_f32_16x16x32_bf16 v[34:37], v[130:133], v[184:187], v[34:37]
	v_mfma_f32_16x16x32_bf16 v[26:29], v[138:141], v[184:187], v[26:29]
	v_mfma_f32_16x16x32_bf16 v[18:21], v[130:133], v[192:195], v[18:21]
	v_mfma_f32_16x16x32_bf16 v[10:13], v[138:141], v[192:195], v[10:13]
	v_mfma_f32_16x16x32_bf16 v[62:65], v[134:137], v[172:175], v[62:65]
	v_mfma_f32_16x16x32_bf16 v[58:61], v[142:145], v[172:175], v[58:61]
	v_mfma_f32_16x16x32_bf16 v[50:53], v[134:137], v[180:183], v[50:53]
	v_mfma_f32_16x16x32_bf16 v[42:45], v[142:145], v[180:183], v[42:45]
	v_mfma_f32_16x16x32_bf16 v[34:37], v[134:137], v[188:191], v[34:37]
	v_mfma_f32_16x16x32_bf16 v[26:29], v[142:145], v[188:191], v[26:29]
	v_mfma_f32_16x16x32_bf16 v[18:21], v[134:137], v[196:199], v[18:21]
	v_mfma_f32_16x16x32_bf16 v[10:13], v[142:145], v[196:199], v[10:13]
	s_barrier
	s_add_u32 s0, s38, 0x40000
	s_addc_u32 s1, s39, 0
	s_mov_b32 m0, s55
	v_lshl_add_u64 v[130:131], s[0:1], 0, v[156:157]
	global_load_lds_dwordx4 v[130:131], off
	v_lshl_add_u64 v[130:131], s[0:1], 0, v[152:153]
	s_add_i32 m0, s55, 0x2000
	s_nop 0
	global_load_lds_dwordx4 v[130:131], off
	s_waitcnt vmcnt(10)
	s_barrier
	v_mfma_f32_16x16x32_bf16 v[54:57], v[200:203], v[146:149], v[54:57]
	v_mfma_f32_16x16x32_bf16 v[46:49], v[208:211], v[146:149], v[46:49]
	v_mfma_f32_16x16x32_bf16 v[38:41], v[200:203], v[176:179], v[38:41]
	v_mfma_f32_16x16x32_bf16 v[30:33], v[208:211], v[176:179], v[30:33]
	v_mfma_f32_16x16x32_bf16 v[22:25], v[200:203], v[184:187], v[22:25]
	v_mfma_f32_16x16x32_bf16 v[14:17], v[208:211], v[184:187], v[14:17]
	v_mfma_f32_16x16x32_bf16 v[6:9], v[200:203], v[192:195], v[6:9]
	v_mfma_f32_16x16x32_bf16 v[2:5], v[208:211], v[192:195], v[2:5]
	v_mfma_f32_16x16x32_bf16 v[54:57], v[204:207], v[172:175], v[54:57]
	v_mfma_f32_16x16x32_bf16 v[46:49], v[212:215], v[172:175], v[46:49]
	v_mfma_f32_16x16x32_bf16 v[38:41], v[204:207], v[180:183], v[38:41]
	v_mfma_f32_16x16x32_bf16 v[30:33], v[212:215], v[180:183], v[30:33]
	v_mfma_f32_16x16x32_bf16 v[22:25], v[204:207], v[188:191], v[22:25]
	v_mfma_f32_16x16x32_bf16 v[14:17], v[212:215], v[188:191], v[14:17]
	v_mfma_f32_16x16x32_bf16 v[6:9], v[204:207], v[196:199], v[6:9]
	v_mfma_f32_16x16x32_bf16 v[2:5], v[212:215], v[196:199], v[2:5]
	s_add_i32 s70, 0, 0x18000
	v_add_u32_e32 v142, s70, v167
	s_barrier
	ds_read_b128 v[130:133], v142
	ds_read_b128 v[134:137], v142 offset:1024
	ds_read_b128 v[138:141], v142 offset:2048
	ds_read_b128 v[142:145], v142 offset:3072
	s_add_u32 s0, s40, 0x40000
	s_addc_u32 s1, s41, 0
	s_mov_b32 m0, s42
	v_lshl_add_u64 v[200:201], s[0:1], 0, v[158:159]
	ds_read_b128 v[146:149], v169 offset:32768
	ds_read_b128 v[172:175], v169 offset:33792
	ds_read_b128 v[176:179], v169 offset:34816
	ds_read_b128 v[180:183], v169 offset:35840
	ds_read_b128 v[184:187], v169 offset:36864
	ds_read_b128 v[188:191], v169 offset:37888
	ds_read_b128 v[192:195], v169 offset:38912
	ds_read_b128 v[196:199], v169 offset:39936
	global_load_lds_dwordx4 v[200:201], off
	v_lshl_add_u64 v[200:201], s[0:1], 0, v[154:155]
	s_mov_b32 m0, s43
	s_nop 0
	global_load_lds_dwordx4 v[200:201], off
	s_waitcnt lgkmcnt(8)
	s_waitcnt vmcnt(10)
	s_barrier
	s_waitcnt lgkmcnt(0)
	s_waitcnt lgkmcnt(0)
	v_mfma_f32_16x16x32_bf16 v[126:129], v[130:133], v[146:149], v[126:129]
	v_mfma_f32_16x16x32_bf16 v[122:125], v[138:141], v[146:149], v[122:125]
	v_mfma_f32_16x16x32_bf16 v[118:121], v[130:133], v[176:179], v[118:121]
	v_mfma_f32_16x16x32_bf16 v[110:113], v[138:141], v[176:179], v[110:113]
	v_mfma_f32_16x16x32_bf16 v[98:101], v[130:133], v[184:187], v[98:101]
	v_mfma_f32_16x16x32_bf16 v[90:93], v[138:141], v[184:187], v[90:93]
	v_mfma_f32_16x16x32_bf16 v[82:85], v[130:133], v[192:195], v[82:85]
	v_mfma_f32_16x16x32_bf16 v[74:77], v[138:141], v[192:195], v[74:77]
	v_mfma_f32_16x16x32_bf16 v[126:129], v[134:137], v[172:175], v[126:129]
	v_mfma_f32_16x16x32_bf16 v[122:125], v[142:145], v[172:175], v[122:125]
	v_mfma_f32_16x16x32_bf16 v[118:121], v[134:137], v[180:183], v[118:121]
	v_mfma_f32_16x16x32_bf16 v[110:113], v[142:145], v[180:183], v[110:113]
	v_mfma_f32_16x16x32_bf16 v[98:101], v[134:137], v[188:191], v[98:101]
	v_mfma_f32_16x16x32_bf16 v[90:93], v[142:145], v[188:191], v[90:93]
	v_mfma_f32_16x16x32_bf16 v[82:85], v[134:137], v[196:199], v[82:85]
	v_mfma_f32_16x16x32_bf16 v[74:77], v[142:145], v[196:199], v[74:77]
	s_barrier
	s_add_i32 s40, 0, 0x1c000
	s_add_i32 s0, s70, s8
	v_add_u32_e32 v171, s40, v167
	v_lshl_add_u64 v[164:165], v[164:165], 0, s[26:27]
	s_mov_b32 m0, s0
	ds_read_b128 v[200:203], v171
	ds_read_b128 v[204:207], v171 offset:1024
	ds_read_b128 v[208:211], v171 offset:2048
	ds_read_b128 v[212:215], v171 offset:3072
	global_load_lds_dwordx4 v[164:165], off
	v_lshl_add_u64 v[164:165], v[216:217], 0, s[26:27]
	s_add_i32 m0, s0, 0x2000
	s_nop 0
	global_load_lds_dwordx4 v[164:165], off
	s_waitcnt vmcnt(10)
	s_barrier
	s_waitcnt lgkmcnt(0)
	s_waitcnt lgkmcnt(0)
	v_mfma_f32_16x16x32_bf16 v[114:117], v[200:203], v[146:149], v[114:117]
	v_mfma_f32_16x16x32_bf16 v[106:109], v[208:211], v[146:149], v[106:109]
	v_mfma_f32_16x16x32_bf16 v[102:105], v[200:203], v[176:179], v[102:105]
	v_mfma_f32_16x16x32_bf16 v[94:97], v[208:211], v[176:179], v[94:97]
	v_mfma_f32_16x16x32_bf16 v[86:89], v[200:203], v[184:187], v[86:89]
	v_mfma_f32_16x16x32_bf16 v[78:81], v[208:211], v[184:187], v[78:81]
	v_mfma_f32_16x16x32_bf16 v[70:73], v[200:203], v[192:195], v[70:73]
	v_mfma_f32_16x16x32_bf16 v[66:69], v[208:211], v[192:195], v[66:69]
	v_mfma_f32_16x16x32_bf16 v[114:117], v[204:207], v[172:175], v[114:117]
	v_mfma_f32_16x16x32_bf16 v[106:109], v[212:215], v[172:175], v[106:109]
	v_mfma_f32_16x16x32_bf16 v[102:105], v[204:207], v[180:183], v[102:105]
	v_mfma_f32_16x16x32_bf16 v[94:97], v[212:215], v[180:183], v[94:97]
	v_mfma_f32_16x16x32_bf16 v[86:89], v[204:207], v[188:191], v[86:89]
	v_mfma_f32_16x16x32_bf16 v[78:81], v[212:215], v[188:191], v[78:81]
	v_mfma_f32_16x16x32_bf16 v[70:73], v[204:207], v[196:199], v[70:73]
	v_mfma_f32_16x16x32_bf16 v[66:69], v[212:215], v[196:199], v[66:69]
	s_mov_b32 m0, s49
	v_lshl_add_u64 v[164:165], v[218:219], 0, s[26:27]
	s_barrier
	ds_read_b128 v[146:149], v169 offset:49152
	ds_read_b128 v[172:175], v169 offset:50176
	ds_read_b128 v[176:179], v169 offset:51200
	ds_read_b128 v[180:183], v169 offset:52224
	ds_read_b128 v[184:187], v169 offset:53248
	ds_read_b128 v[188:191], v169 offset:54272
	ds_read_b128 v[192:195], v169 offset:55296
	ds_read_b128 v[196:199], v169 offset:56320
	global_load_lds_dwordx4 v[164:165], off
	v_lshl_add_u64 v[164:165], v[220:221], 0, s[26:27]
	s_mov_b32 m0, s50
	s_nop 0
	global_load_lds_dwordx4 v[164:165], off
	s_waitcnt vmcnt(10)
	s_barrier
	s_waitcnt lgkmcnt(0)
	s_waitcnt lgkmcnt(0)
	v_mfma_f32_16x16x32_bf16 v[62:65], v[130:133], v[146:149], v[62:65]
	v_mfma_f32_16x16x32_bf16 v[58:61], v[138:141], v[146:149], v[58:61]
	v_mfma_f32_16x16x32_bf16 v[50:53], v[130:133], v[176:179], v[50:53]
	v_mfma_f32_16x16x32_bf16 v[42:45], v[138:141], v[176:179], v[42:45]
	v_mfma_f32_16x16x32_bf16 v[34:37], v[130:133], v[184:187], v[34:37]
	v_mfma_f32_16x16x32_bf16 v[26:29], v[138:141], v[184:187], v[26:29]
	v_mfma_f32_16x16x32_bf16 v[18:21], v[130:133], v[192:195], v[18:21]
	v_mfma_f32_16x16x32_bf16 v[10:13], v[138:141], v[192:195], v[10:13]
	v_mfma_f32_16x16x32_bf16 v[62:65], v[134:137], v[172:175], v[62:65]
	v_mfma_f32_16x16x32_bf16 v[58:61], v[142:145], v[172:175], v[58:61]
	v_mfma_f32_16x16x32_bf16 v[50:53], v[134:137], v[180:183], v[50:53]
	v_mfma_f32_16x16x32_bf16 v[42:45], v[142:145], v[180:183], v[42:45]
	v_mfma_f32_16x16x32_bf16 v[34:37], v[134:137], v[188:191], v[34:37]
	v_mfma_f32_16x16x32_bf16 v[26:29], v[142:145], v[188:191], v[26:29]
	v_mfma_f32_16x16x32_bf16 v[18:21], v[134:137], v[196:199], v[18:21]
	v_mfma_f32_16x16x32_bf16 v[10:13], v[142:145], v[196:199], v[10:13]
	s_barrier
	s_add_u32 s0, s38, 0x40080
	s_addc_u32 s1, s39, 0
	s_add_i32 s38, s40, s8
	v_lshl_add_u64 v[130:131], s[0:1], 0, v[156:157]
	s_mov_b32 m0, s38
	s_nop 0
	global_load_lds_dwordx4 v[130:131], off
	v_lshl_add_u64 v[130:131], s[0:1], 0, v[152:153]
	s_add_i32 m0, s38, 0x2000
	s_nop 0
	global_load_lds_dwordx4 v[130:131], off
	s_waitcnt vmcnt(10)
	s_barrier
	v_mfma_f32_16x16x32_bf16 v[54:57], v[200:203], v[146:149], v[54:57]
	v_mfma_f32_16x16x32_bf16 v[46:49], v[208:211], v[146:149], v[46:49]
	v_mfma_f32_16x16x32_bf16 v[38:41], v[200:203], v[176:179], v[38:41]
	v_mfma_f32_16x16x32_bf16 v[30:33], v[208:211], v[176:179], v[30:33]
	v_mfma_f32_16x16x32_bf16 v[22:25], v[200:203], v[184:187], v[22:25]
	v_mfma_f32_16x16x32_bf16 v[14:17], v[208:211], v[184:187], v[14:17]
	v_mfma_f32_16x16x32_bf16 v[6:9], v[200:203], v[192:195], v[6:9]
	v_mfma_f32_16x16x32_bf16 v[2:5], v[208:211], v[192:195], v[2:5]
	v_mfma_f32_16x16x32_bf16 v[54:57], v[204:207], v[172:175], v[54:57]
	v_mfma_f32_16x16x32_bf16 v[46:49], v[212:215], v[172:175], v[46:49]
	v_mfma_f32_16x16x32_bf16 v[38:41], v[204:207], v[180:183], v[38:41]
	v_mfma_f32_16x16x32_bf16 v[30:33], v[212:215], v[180:183], v[30:33]
	v_mfma_f32_16x16x32_bf16 v[22:25], v[204:207], v[188:191], v[22:25]
	v_mfma_f32_16x16x32_bf16 v[14:17], v[212:215], v[188:191], v[14:17]
	v_mfma_f32_16x16x32_bf16 v[6:9], v[204:207], v[196:199], v[6:9]
	v_mfma_f32_16x16x32_bf16 v[2:5], v[212:215], v[196:199], v[2:5]
	s_add_i32 s69, s69, 2
	s_add_u32 s65, s65, 0x100
	s_addc_u32 s67, s67, 0
	s_add_u32 s36, s36, 0x100
	s_addc_u32 s37, s37, 0
	s_cmp_gt_u32 s69, 13
	s_barrier
	s_cbranch_scc0 .LBB0_2495
	s_lshl_b32 s0, s59, 8
	v_mov_b32_e32 v130, v151
	v_mov_b32_e32 v131, v166
	s_or_b32 s0, s0, s46
	s_mov_b32 s59, s58
	v_lshl_add_u32 v164, v131, 3, s0
	s_lshl_b32 s0, s60, 8
	s_add_i32 s0, s0, s45
	v_add_u32_e32 v171, s0, v130
	v_mov_b32_e32 v130, v171
	v_ashrrev_i32_e32 v165, 31, v164
	v_ashrrev_i32_e32 v131, 31, v130
	v_lshlrev_b64 v[130:131], 10, v[130:131]
	v_lshl_add_u64 v[130:131], v[130:131], 0, v[164:165]
	v_lshlrev_b64 v[184:185], 1, v[130:131]
	v_lshl_add_u64 v[130:131], s[10:11], 0, v[184:185]
	flat_load_dwordx4 v[172:175], v[130:131]
	flat_load_dwordx4 v[176:179], v[130:131] offset:256
	v_add_co_u32_e32 v132, vcc, s48, v130
	s_mov_b32 s60, s57
	s_nop 0
	v_addc_co_u32_e32 v133, vcc, 0, v131, vcc
	flat_load_dwordx4 v[180:183], v[132:133]
	flat_load_dwordx4 v[146:149], v[132:133] offset:256
	v_add_co_u32_e32 v132, vcc, s44, v130
	s_waitcnt vmcnt(0) lgkmcnt(0)
	v_lshlrev_b32_e32 v186, 16, v172
	v_addc_co_u32_e32 v133, vcc, 0, v131, vcc
	flat_load_dwordx4 v[142:145], v[132:133]
	flat_load_dwordx4 v[138:141], v[132:133] offset:256
	v_add_co_u32_e32 v130, vcc, s47, v130
	v_and_b32_e32 v187, 0xffff0000, v172
	s_nop 0
	v_addc_co_u32_e32 v131, vcc, 0, v131, vcc
	flat_load_dwordx4 v[134:137], v[130:131]
	s_nop 0
	flat_load_dwordx4 v[130:133], v[130:131] offset:256
	v_lshlrev_b32_e32 v172, 16, v173
	v_and_b32_e32 v173, 0xffff0000, v173
	v_lshlrev_b32_e32 v188, 16, v174
	v_and_b32_e32 v189, 0xffff0000, v174
	v_lshlrev_b32_e32 v174, 16, v175
	v_and_b32_e32 v175, 0xffff0000, v175
	v_pk_fma_f32 v[128:129], v[172:173], s[28:29], v[128:129] op_sel_hi:[1,0,1]
	v_pk_fma_f32 v[126:127], v[186:187], s[28:29], v[126:127] op_sel_hi:[1,0,1]
	v_pk_fma_f32 v[172:173], v[174:175], s[28:29], v[124:125] op_sel_hi:[1,0,1]
	v_pk_fma_f32 v[122:123], v[188:189], s[28:29], v[122:123] op_sel_hi:[1,0,1]
	v_cvt_pk_bf16_f32 v124, v126, v127
	v_cvt_pk_bf16_f32 v125, v128, v129
	v_cvt_pk_bf16_f32 v126, v122, v123
	v_cvt_pk_bf16_f32 v127, v172, v173
	v_lshl_add_u64 v[122:123], s[16:17], 0, v[184:185]
	flat_store_dwordx4 v[122:123], v[124:127]
	v_lshlrev_b32_e32 v128, 16, v178
	v_and_b32_e32 v129, 0xffff0000, v178
	v_lshlrev_b32_e32 v124, 16, v176
	v_and_b32_e32 v125, 0xffff0000, v176
	v_lshlrev_b32_e32 v126, 16, v177
	v_and_b32_e32 v127, 0xffff0000, v177
	v_lshlrev_b32_e32 v172, 16, v179
	v_and_b32_e32 v173, 0xffff0000, v179
	v_pk_fma_f32 v[116:117], v[126:127], s[28:29], v[116:117] op_sel_hi:[1,0,1]
	v_pk_fma_f32 v[114:115], v[124:125], s[28:29], v[114:115] op_sel_hi:[1,0,1]
	v_pk_fma_f32 v[124:125], v[172:173], s[28:29], v[108:109] op_sel_hi:[1,0,1]
	v_pk_fma_f32 v[108:109], v[128:129], s[28:29], v[106:107] op_sel_hi:[1,0,1]
	v_cvt_pk_bf16_f32 v106, v114, v115
	v_cvt_pk_bf16_f32 v107, v116, v117
	v_cvt_pk_bf16_f32 v108, v108, v109
	v_cvt_pk_bf16_f32 v109, v124, v125
	flat_store_dwordx4 v[122:123], v[106:109] offset:256
	v_lshlrev_b32_e32 v114, 16, v182
	v_and_b32_e32 v115, 0xffff0000, v182
	v_lshlrev_b32_e32 v106, 16, v180
	v_and_b32_e32 v107, 0xffff0000, v180
	v_lshlrev_b32_e32 v108, 16, v181
	v_and_b32_e32 v109, 0xffff0000, v181
	v_lshlrev_b32_e32 v116, 16, v183
	v_and_b32_e32 v117, 0xffff0000, v183
	v_pk_fma_f32 v[108:109], v[108:109], s[28:29], v[120:121] op_sel_hi:[1,0,1]
	v_pk_fma_f32 v[106:107], v[106:107], s[28:29], v[118:119] op_sel_hi:[1,0,1]
	v_pk_fma_f32 v[110:111], v[114:115], s[28:29], v[110:111] op_sel_hi:[1,0,1]
	v_pk_fma_f32 v[112:113], v[116:117], s[28:29], v[112:113] op_sel_hi:[1,0,1]
	v_cvt_pk_bf16_f32 v106, v106, v107
	v_cvt_pk_bf16_f32 v107, v108, v109
	v_cvt_pk_bf16_f32 v108, v110, v111
	v_add_co_u32_e32 v110, vcc, s48, v122
	v_cvt_pk_bf16_f32 v109, v112, v113
	s_nop 0
	v_addc_co_u32_e32 v111, vcc, 0, v123, vcc
	flat_store_dwordx4 v[110:111], v[106:109]
	v_lshlrev_b32_e32 v112, 16, v148
	v_and_b32_e32 v113, 0xffff0000, v148
	v_lshlrev_b32_e32 v106, 16, v146
	v_and_b32_e32 v107, 0xffff0000, v146
	v_lshlrev_b32_e32 v108, 16, v147
	v_and_b32_e32 v109, 0xffff0000, v147
	v_lshlrev_b32_e32 v114, 16, v149
	v_and_b32_e32 v115, 0xffff0000, v149
	v_pk_fma_f32 v[104:105], v[108:109], s[28:29], v[104:105] op_sel_hi:[1,0,1]
	v_pk_fma_f32 v[102:103], v[106:107], s[28:29], v[102:103] op_sel_hi:[1,0,1]
	v_pk_fma_f32 v[106:107], v[114:115], s[28:29], v[96:97] op_sel_hi:[1,0,1]
	v_pk_fma_f32 v[96:97], v[112:113], s[28:29], v[94:95] op_sel_hi:[1,0,1]
	v_cvt_pk_bf16_f32 v94, v102, v103
	v_cvt_pk_bf16_f32 v95, v104, v105
	v_cvt_pk_bf16_f32 v96, v96, v97
	v_cvt_pk_bf16_f32 v97, v106, v107
	flat_store_dwordx4 v[110:111], v[94:97] offset:256
	s_waitcnt vmcnt(0) lgkmcnt(0)
	v_lshlrev_b32_e32 v102, 16, v144
	v_lshlrev_b32_e32 v94, 16, v142
	v_and_b32_e32 v95, 0xffff0000, v142
	v_lshlrev_b32_e32 v96, 16, v143
	v_and_b32_e32 v97, 0xffff0000, v143
	v_and_b32_e32 v103, 0xffff0000, v144
	v_lshlrev_b32_e32 v104, 16, v145
	v_and_b32_e32 v105, 0xffff0000, v145
	v_pk_fma_f32 v[94:95], v[94:95], s[28:29], v[98:99] op_sel_hi:[1,0,1]
	v_pk_fma_f32 v[96:97], v[96:97], s[28:29], v[100:101] op_sel_hi:[1,0,1]
	v_pk_fma_f32 v[98:99], v[104:105], s[28:29], v[92:93] op_sel_hi:[1,0,1]
	v_pk_fma_f32 v[92:93], v[102:103], s[28:29], v[90:91] op_sel_hi:[1,0,1]
	v_cvt_pk_bf16_f32 v90, v94, v95
	v_add_co_u32_e32 v94, vcc, s44, v122
	v_cvt_pk_bf16_f32 v91, v96, v97
	v_cvt_pk_bf16_f32 v92, v92, v93
	v_cvt_pk_bf16_f32 v93, v98, v99
	v_addc_co_u32_e32 v95, vcc, 0, v123, vcc
	flat_store_dwordx4 v[94:95], v[90:93]
	v_lshlrev_b32_e32 v96, 16, v140
	v_and_b32_e32 v97, 0xffff0000, v140
	v_lshlrev_b32_e32 v90, 16, v138
	v_and_b32_e32 v91, 0xffff0000, v138
	v_lshlrev_b32_e32 v92, 16, v139
	v_and_b32_e32 v93, 0xffff0000, v139
	v_lshlrev_b32_e32 v98, 16, v141
	v_and_b32_e32 v99, 0xffff0000, v141
	v_pk_fma_f32 v[88:89], v[92:93], s[28:29], v[88:89] op_sel_hi:[1,0,1]
	v_pk_fma_f32 v[86:87], v[90:91], s[28:29], v[86:87] op_sel_hi:[1,0,1]
	v_pk_fma_f32 v[90:91], v[98:99], s[28:29], v[80:81] op_sel_hi:[1,0,1]
	v_pk_fma_f32 v[80:81], v[96:97], s[28:29], v[78:79] op_sel_hi:[1,0,1]
	v_cvt_pk_bf16_f32 v78, v86, v87
	v_cvt_pk_bf16_f32 v79, v88, v89
	v_cvt_pk_bf16_f32 v80, v80, v81
	v_cvt_pk_bf16_f32 v81, v90, v91
	flat_store_dwordx4 v[94:95], v[78:81] offset:256
	v_lshlrev_b32_e32 v86, 16, v136
	v_and_b32_e32 v87, 0xffff0000, v136
	v_lshlrev_b32_e32 v78, 16, v134
	v_and_b32_e32 v79, 0xffff0000, v134
	v_lshlrev_b32_e32 v80, 16, v135
	v_and_b32_e32 v81, 0xffff0000, v135
	v_lshlrev_b32_e32 v88, 16, v137
	v_and_b32_e32 v89, 0xffff0000, v137
	v_pk_fma_f32 v[78:79], v[78:79], s[28:29], v[82:83] op_sel_hi:[1,0,1]
	v_pk_fma_f32 v[80:81], v[80:81], s[28:29], v[84:85] op_sel_hi:[1,0,1]
	v_pk_fma_f32 v[82:83], v[88:89], s[28:29], v[76:77] op_sel_hi:[1,0,1]
	v_pk_fma_f32 v[76:77], v[86:87], s[28:29], v[74:75] op_sel_hi:[1,0,1]
	v_cvt_pk_bf16_f32 v74, v78, v79
	v_add_co_u32_e32 v78, vcc, s47, v122
	v_cvt_pk_bf16_f32 v75, v80, v81
	v_cvt_pk_bf16_f32 v76, v76, v77
	v_cvt_pk_bf16_f32 v77, v82, v83
	v_addc_co_u32_e32 v79, vcc, 0, v123, vcc
	flat_store_dwordx4 v[78:79], v[74:77]
	v_lshlrev_b32_e32 v80, 16, v132
	v_and_b32_e32 v81, 0xffff0000, v132
	v_lshlrev_b32_e32 v74, 16, v130
	v_and_b32_e32 v75, 0xffff0000, v130
	v_lshlrev_b32_e32 v76, 16, v131
	v_and_b32_e32 v77, 0xffff0000, v131
	v_lshlrev_b32_e32 v82, 16, v133
	v_and_b32_e32 v83, 0xffff0000, v133
	v_pk_fma_f32 v[72:73], v[76:77], s[28:29], v[72:73] op_sel_hi:[1,0,1]
	v_pk_fma_f32 v[70:71], v[74:75], s[28:29], v[70:71] op_sel_hi:[1,0,1]
	v_pk_fma_f32 v[74:75], v[82:83], s[28:29], v[68:69] op_sel_hi:[1,0,1]
	v_pk_fma_f32 v[68:69], v[80:81], s[28:29], v[66:67] op_sel_hi:[1,0,1]
	v_cvt_pk_bf16_f32 v66, v70, v71
	v_cvt_pk_bf16_f32 v67, v72, v73
	v_cvt_pk_bf16_f32 v68, v68, v69
	v_cvt_pk_bf16_f32 v69, v74, v75
	flat_store_dwordx4 v[78:79], v[66:69] offset:256
	s_nop 1
	v_add_u32_e32 v66, 0x80, v171
	s_nop 0
	v_ashrrev_i32_e32 v67, 31, v66
	v_lshlrev_b64 v[66:67], 10, v[66:67]
	v_lshl_add_u64 v[66:67], v[66:67], 0, v[164:165]
	v_lshlrev_b64 v[98:99], 1, v[66:67]
	v_lshl_add_u64 v[90:91], s[10:11], 0, v[98:99]
	flat_load_dwordx4 v[66:69], v[90:91]
	flat_load_dwordx4 v[70:73], v[90:91] offset:256
	v_add_co_u32_e32 v78, vcc, s48, v90
	s_waitcnt vmcnt(0) lgkmcnt(0)
	v_lshlrev_b32_e32 v100, 16, v66
	v_addc_co_u32_e32 v79, vcc, 0, v91, vcc
	flat_load_dwordx4 v[74:77], v[78:79]
	s_nop 0
	flat_load_dwordx4 v[78:81], v[78:79] offset:256
	v_add_co_u32_e32 v86, vcc, s44, v90
	v_and_b32_e32 v101, 0xffff0000, v66
	s_nop 0
	v_addc_co_u32_e32 v87, vcc, 0, v91, vcc
	flat_load_dwordx4 v[82:85], v[86:87]
	s_nop 0
	flat_load_dwordx4 v[86:89], v[86:87] offset:256
	v_add_co_u32_e32 v94, vcc, s47, v90
	v_lshlrev_b32_e32 v66, 16, v67
	s_nop 0
	v_addc_co_u32_e32 v95, vcc, 0, v91, vcc
	flat_load_dwordx4 v[90:93], v[94:95]
	s_nop 0
	flat_load_dwordx4 v[94:97], v[94:95] offset:256
	v_and_b32_e32 v67, 0xffff0000, v67
	v_lshlrev_b32_e32 v102, 16, v68
	v_and_b32_e32 v103, 0xffff0000, v68
	v_lshlrev_b32_e32 v68, 16, v69
	v_and_b32_e32 v69, 0xffff0000, v69
	v_pk_fma_f32 v[64:65], v[66:67], s[28:29], v[64:65] op_sel_hi:[1,0,1]
	v_pk_fma_f32 v[62:63], v[100:101], s[28:29], v[62:63] op_sel_hi:[1,0,1]
	v_pk_fma_f32 v[66:67], v[68:69], s[28:29], v[60:61] op_sel_hi:[1,0,1]
	v_pk_fma_f32 v[60:61], v[102:103], s[28:29], v[58:59] op_sel_hi:[1,0,1]
	v_cvt_pk_bf16_f32 v58, v62, v63
	v_cvt_pk_bf16_f32 v59, v64, v65
	v_cvt_pk_bf16_f32 v60, v60, v61
	v_cvt_pk_bf16_f32 v61, v66, v67
	v_lshl_add_u64 v[62:63], s[16:17], 0, v[98:99]
	flat_store_dwordx4 v[62:63], v[58:61]
	v_lshlrev_b32_e32 v64, 16, v72
	v_and_b32_e32 v65, 0xffff0000, v72
	v_lshlrev_b32_e32 v58, 16, v70
	v_and_b32_e32 v59, 0xffff0000, v70
	v_lshlrev_b32_e32 v60, 16, v71
	v_and_b32_e32 v61, 0xffff0000, v71
	v_lshlrev_b32_e32 v66, 16, v73
	v_and_b32_e32 v67, 0xffff0000, v73
	v_pk_fma_f32 v[56:57], v[60:61], s[28:29], v[56:57] op_sel_hi:[1,0,1]
	v_pk_fma_f32 v[54:55], v[58:59], s[28:29], v[54:55] op_sel_hi:[1,0,1]
	v_pk_fma_f32 v[58:59], v[66:67], s[28:29], v[48:49] op_sel_hi:[1,0,1]
	v_pk_fma_f32 v[48:49], v[64:65], s[28:29], v[46:47] op_sel_hi:[1,0,1]
	v_cvt_pk_bf16_f32 v46, v54, v55
	v_cvt_pk_bf16_f32 v47, v56, v57
	v_cvt_pk_bf16_f32 v48, v48, v49
	v_cvt_pk_bf16_f32 v49, v58, v59
	flat_store_dwordx4 v[62:63], v[46:49] offset:256
	s_waitcnt vmcnt(0) lgkmcnt(0)
	v_lshlrev_b32_e32 v54, 16, v76
	v_lshlrev_b32_e32 v46, 16, v74
	v_and_b32_e32 v47, 0xffff0000, v74
	v_lshlrev_b32_e32 v48, 16, v75
	v_and_b32_e32 v49, 0xffff0000, v75
	v_and_b32_e32 v55, 0xffff0000, v76
	v_lshlrev_b32_e32 v56, 16, v77
	v_and_b32_e32 v57, 0xffff0000, v77
	v_pk_fma_f32 v[46:47], v[46:47], s[28:29], v[50:51] op_sel_hi:[1,0,1]
	v_pk_fma_f32 v[48:49], v[48:49], s[28:29], v[52:53] op_sel_hi:[1,0,1]
	v_pk_fma_f32 v[50:51], v[56:57], s[28:29], v[44:45] op_sel_hi:[1,0,1]
	v_pk_fma_f32 v[44:45], v[54:55], s[28:29], v[42:43] op_sel_hi:[1,0,1]
	v_cvt_pk_bf16_f32 v42, v46, v47
	v_add_co_u32_e32 v46, vcc, s48, v62
	v_cvt_pk_bf16_f32 v43, v48, v49
	v_cvt_pk_bf16_f32 v44, v44, v45
	v_cvt_pk_bf16_f32 v45, v50, v51
	v_addc_co_u32_e32 v47, vcc, 0, v63, vcc
	flat_store_dwordx4 v[46:47], v[42:45]
	v_lshlrev_b32_e32 v48, 16, v80
	v_and_b32_e32 v49, 0xffff0000, v80
	v_lshlrev_b32_e32 v42, 16, v78
	v_and_b32_e32 v43, 0xffff0000, v78
	v_lshlrev_b32_e32 v44, 16, v79
	v_and_b32_e32 v45, 0xffff0000, v79
	v_lshlrev_b32_e32 v50, 16, v81
	v_and_b32_e32 v51, 0xffff0000, v81
	v_pk_fma_f32 v[40:41], v[44:45], s[28:29], v[40:41] op_sel_hi:[1,0,1]
	v_pk_fma_f32 v[38:39], v[42:43], s[28:29], v[38:39] op_sel_hi:[1,0,1]
	v_pk_fma_f32 v[42:43], v[50:51], s[28:29], v[32:33] op_sel_hi:[1,0,1]
	v_pk_fma_f32 v[32:33], v[48:49], s[28:29], v[30:31] op_sel_hi:[1,0,1]
	v_cvt_pk_bf16_f32 v30, v38, v39
	v_cvt_pk_bf16_f32 v31, v40, v41
	v_cvt_pk_bf16_f32 v32, v32, v33
	v_cvt_pk_bf16_f32 v33, v42, v43
	flat_store_dwordx4 v[46:47], v[30:33] offset:256
	v_lshlrev_b32_e32 v38, 16, v84
	v_and_b32_e32 v39, 0xffff0000, v84
	v_lshlrev_b32_e32 v30, 16, v82
	v_and_b32_e32 v31, 0xffff0000, v82
	v_lshlrev_b32_e32 v32, 16, v83
	v_and_b32_e32 v33, 0xffff0000, v83
	v_lshlrev_b32_e32 v40, 16, v85
	v_and_b32_e32 v41, 0xffff0000, v85
	v_pk_fma_f32 v[30:31], v[30:31], s[28:29], v[34:35] op_sel_hi:[1,0,1]
	v_pk_fma_f32 v[32:33], v[32:33], s[28:29], v[36:37] op_sel_hi:[1,0,1]
	v_pk_fma_f32 v[34:35], v[40:41], s[28:29], v[28:29] op_sel_hi:[1,0,1]
	v_pk_fma_f32 v[28:29], v[38:39], s[28:29], v[26:27] op_sel_hi:[1,0,1]
	v_cvt_pk_bf16_f32 v26, v30, v31
	v_add_co_u32_e32 v30, vcc, s44, v62
	v_cvt_pk_bf16_f32 v27, v32, v33
	v_cvt_pk_bf16_f32 v28, v28, v29
	v_cvt_pk_bf16_f32 v29, v34, v35
	v_addc_co_u32_e32 v31, vcc, 0, v63, vcc
	flat_store_dwordx4 v[30:31], v[26:29]
	v_lshlrev_b32_e32 v32, 16, v88
	v_and_b32_e32 v33, 0xffff0000, v88
	v_lshlrev_b32_e32 v26, 16, v86
	v_and_b32_e32 v27, 0xffff0000, v86
	v_lshlrev_b32_e32 v28, 16, v87
	v_and_b32_e32 v29, 0xffff0000, v87
	v_lshlrev_b32_e32 v34, 16, v89
	v_and_b32_e32 v35, 0xffff0000, v89
	v_pk_fma_f32 v[24:25], v[28:29], s[28:29], v[24:25] op_sel_hi:[1,0,1]
	v_pk_fma_f32 v[22:23], v[26:27], s[28:29], v[22:23] op_sel_hi:[1,0,1]
	v_pk_fma_f32 v[26:27], v[34:35], s[28:29], v[16:17] op_sel_hi:[1,0,1]
	v_pk_fma_f32 v[16:17], v[32:33], s[28:29], v[14:15] op_sel_hi:[1,0,1]
	v_cvt_pk_bf16_f32 v14, v22, v23
	v_cvt_pk_bf16_f32 v15, v24, v25
	v_cvt_pk_bf16_f32 v16, v16, v17
	v_cvt_pk_bf16_f32 v17, v26, v27
	flat_store_dwordx4 v[30:31], v[14:17] offset:256
	v_lshlrev_b32_e32 v22, 16, v92
	v_and_b32_e32 v23, 0xffff0000, v92
	v_lshlrev_b32_e32 v14, 16, v90
	v_and_b32_e32 v15, 0xffff0000, v90
	v_lshlrev_b32_e32 v16, 16, v91
	v_and_b32_e32 v17, 0xffff0000, v91
	v_lshlrev_b32_e32 v24, 16, v93
	v_and_b32_e32 v25, 0xffff0000, v93
	v_pk_fma_f32 v[14:15], v[14:15], s[28:29], v[18:19] op_sel_hi:[1,0,1]
	v_pk_fma_f32 v[16:17], v[16:17], s[28:29], v[20:21] op_sel_hi:[1,0,1]
	v_pk_fma_f32 v[18:19], v[24:25], s[28:29], v[12:13] op_sel_hi:[1,0,1]
	v_pk_fma_f32 v[12:13], v[22:23], s[28:29], v[10:11] op_sel_hi:[1,0,1]
	v_cvt_pk_bf16_f32 v10, v14, v15
	v_add_co_u32_e32 v14, vcc, s47, v62
	v_cvt_pk_bf16_f32 v11, v16, v17
	v_cvt_pk_bf16_f32 v12, v12, v13
	v_cvt_pk_bf16_f32 v13, v18, v19
	v_addc_co_u32_e32 v15, vcc, 0, v63, vcc
	flat_store_dwordx4 v[14:15], v[10:13]
	v_lshlrev_b32_e32 v16, 16, v96
	v_and_b32_e32 v17, 0xffff0000, v96
	v_lshlrev_b32_e32 v10, 16, v94
	v_and_b32_e32 v11, 0xffff0000, v94
	v_lshlrev_b32_e32 v12, 16, v95
	v_and_b32_e32 v13, 0xffff0000, v95
	v_lshlrev_b32_e32 v18, 16, v97
	v_and_b32_e32 v19, 0xffff0000, v97
	v_pk_fma_f32 v[8:9], v[12:13], s[28:29], v[8:9] op_sel_hi:[1,0,1]
	v_pk_fma_f32 v[6:7], v[10:11], s[28:29], v[6:7] op_sel_hi:[1,0,1]
	v_pk_fma_f32 v[10:11], v[18:19], s[28:29], v[4:5] op_sel_hi:[1,0,1]
	v_pk_fma_f32 v[4:5], v[16:17], s[28:29], v[2:3] op_sel_hi:[1,0,1]
	v_cvt_pk_bf16_f32 v2, v6, v7
	v_cvt_pk_bf16_f32 v3, v8, v9
	v_cvt_pk_bf16_f32 v4, v4, v5
	v_cvt_pk_bf16_f32 v5, v10, v11
	s_and_b64 vcc, exec, s[30:31]
	flat_store_dwordx4 v[14:15], v[2:5] offset:256
	s_cbranch_vccz .LBB0_2494
	s_waitcnt vmcnt(0)
	s_cmpk_gt_u32 s5, 0xff
	s_cbranch_scc1 .LBB0_2499
	s_barrier

.LBB0_2749:
	s_add_u32 s10, s34, 0x100
	s_addc_u32 s11, s35, 0
	s_add_u32 s30, s29, s34
	s_addc_u32 s31, s55, s35
	s_cmpk_eq_i32 s34, 0x300
	s_cselect_b64 vcc, -1, 0
	s_and_b64 s[0:1], vcc, exec
	s_cselect_b32 s1, 0, s10
	s_cselect_b32 s0, 0, s11
	s_cselect_b32 s30, s27, s30
	s_cselect_b32 s31, s25, s31
	s_add_u32 s36, s14, s1
	s_addc_u32 s37, s15, s0
	s_add_i32 s1, 0, 0x10000
	v_add_u32_e32 v14, s1, v196
	ds_read_b128 v[2:5], v14
	ds_read_b128 v[6:9], v14 offset:1024
	ds_read_b128 v[10:13], v14 offset:2048
	ds_read_b128 v[14:17], v14 offset:3072
	v_cndmask_b32_e32 v162, v168, v171, vcc
	v_cndmask_b32_e32 v184, v170, v197, vcc
	v_cndmask_b32_e32 v175, v172, v198, vcc
	v_cndmask_b32_e32 v173, v174, v199, vcc
	v_lshl_add_u64 v[18:19], v[178:179], 0, s[34:35]
	s_add_i32 m0, s45, 0xc000
	ds_read_b128 v[200:203], v169
	ds_read_b128 v[204:207], v169 offset:1024
	ds_read_b128 v[208:211], v169 offset:2048
	ds_read_b128 v[212:215], v169 offset:3072
	ds_read_b128 v[216:219], v169 offset:4096
	ds_read_b128 v[220:223], v169 offset:5120
	ds_read_b128 v[224:227], v169 offset:6144
	ds_read_b128 v[228:231], v169 offset:7168
	global_load_lds_dwordx4 v[18:19], off
	v_lshl_add_u64 v[18:19], v[176:177], 0, s[34:35]
	s_add_i32 m0, s45, 0xe000
	s_nop 0
	global_load_lds_dwordx4 v[18:19], off
	s_waitcnt lgkmcnt(8)
	s_waitcnt vmcnt(10)
	s_barrier
	s_waitcnt lgkmcnt(0)
	s_waitcnt lgkmcnt(0)
	v_mfma_scale_f32_16x16x128_f8f6f4 v[158:161], v[2:9], v[200:207], v[158:161], v1, v1 op_sel_hi:[0,0,0]
	v_mfma_scale_f32_16x16x128_f8f6f4 v[150:153], v[10:17], v[200:207], v[150:153], v1, v1 op_sel_hi:[0,0,0]
	v_mfma_scale_f32_16x16x128_f8f6f4 v[142:145], v[2:9], v[208:215], v[142:145], v1, v1 op_sel_hi:[0,0,0]
	v_mfma_scale_f32_16x16x128_f8f6f4 v[134:137], v[10:17], v[208:215], v[134:137], v1, v1 op_sel_hi:[0,0,0]
	v_mfma_scale_f32_16x16x128_f8f6f4 v[126:129], v[2:9], v[216:223], v[126:129], v1, v1 op_sel_hi:[0,0,0]
	v_mfma_scale_f32_16x16x128_f8f6f4 v[118:121], v[10:17], v[216:223], v[118:121], v1, v1 op_sel_hi:[0,0,0]
	v_mfma_scale_f32_16x16x128_f8f6f4 v[110:113], v[2:9], v[224:231], v[110:113], v1, v1 op_sel_hi:[0,0,0]
	v_mfma_scale_f32_16x16x128_f8f6f4 v[102:105], v[10:17], v[224:231], v[102:105], v1, v1 op_sel_hi:[0,0,0]
	s_barrier
	s_add_i32 s0, 0, 0x14000
	s_add_i32 s1, s1, s43
	v_add_u32_e32 v30, s0, v196
	v_lshl_add_u64 v[180:181], s[30:31], 0, v[164:165]
	s_mov_b32 m0, s1
	ds_read_b128 v[18:21], v30
	ds_read_b128 v[22:25], v30 offset:1024
	ds_read_b128 v[26:29], v30 offset:2048
	ds_read_b128 v[30:33], v30 offset:3072
	global_load_lds_dwordx4 v[180:181], off
	v_lshl_add_u64 v[182:183], s[30:31], 0, v[166:167]
	s_add_i32 m0, s1, 0x2000
	s_nop 0
	global_load_lds_dwordx4 v[182:183], off
	s_waitcnt vmcnt(10)
	s_barrier
	s_waitcnt lgkmcnt(0)
	s_waitcnt lgkmcnt(0)
	v_mfma_scale_f32_16x16x128_f8f6f4 v[154:157], v[18:25], v[200:207], v[154:157], v1, v1 op_sel_hi:[0,0,0]
	v_mfma_scale_f32_16x16x128_f8f6f4 v[146:149], v[26:33], v[200:207], v[146:149], v1, v1 op_sel_hi:[0,0,0]
	v_mfma_scale_f32_16x16x128_f8f6f4 v[138:141], v[18:25], v[208:215], v[138:141], v1, v1 op_sel_hi:[0,0,0]
	v_mfma_scale_f32_16x16x128_f8f6f4 v[130:133], v[26:33], v[208:215], v[130:133], v1, v1 op_sel_hi:[0,0,0]
	v_mfma_scale_f32_16x16x128_f8f6f4 v[122:125], v[18:25], v[216:223], v[122:125], v1, v1 op_sel_hi:[0,0,0]
	v_mfma_scale_f32_16x16x128_f8f6f4 v[114:117], v[26:33], v[216:223], v[114:117], v1, v1 op_sel_hi:[0,0,0]
	v_mfma_scale_f32_16x16x128_f8f6f4 v[106:109], v[18:25], v[224:231], v[106:109], v1, v1 op_sel_hi:[0,0,0]
	v_mfma_scale_f32_16x16x128_f8f6f4 v[98:101], v[26:33], v[224:231], v[98:101], v1, v1 op_sel_hi:[0,0,0]
	s_mov_b32 m0, s45
	s_barrier
	ds_read_b128 v[200:203], v169 offset:16384
	ds_read_b128 v[204:207], v169 offset:17408
	ds_read_b128 v[208:211], v169 offset:18432
	ds_read_b128 v[212:215], v169 offset:19456
	ds_read_b128 v[216:219], v169 offset:20480
	ds_read_b128 v[220:223], v169 offset:21504
	ds_read_b128 v[224:227], v169 offset:22528
	ds_read_b128 v[228:231], v169 offset:23552
	global_load_lds_dwordx4 v162, s[36:37]
	s_mov_b32 m0, s46
	v_mov_b32_e32 v185, v163
	global_load_lds_dwordx4 v184, s[36:37]
	s_waitcnt vmcnt(10)
	s_barrier
	s_waitcnt lgkmcnt(0)
	v_lshl_add_u64 v[186:187], s[36:37], 0, v[162:163]
	v_lshl_add_u64 v[184:185], s[36:37], 0, v[184:185]
	s_waitcnt lgkmcnt(0)
	v_mfma_scale_f32_16x16x128_f8f6f4 v[94:97], v[2:9], v[200:207], v[94:97], v1, v1 op_sel_hi:[0,0,0]
	v_mfma_scale_f32_16x16x128_f8f6f4 v[86:89], v[10:17], v[200:207], v[86:89], v1, v1 op_sel_hi:[0,0,0]
	v_mfma_scale_f32_16x16x128_f8f6f4 v[78:81], v[2:9], v[208:215], v[78:81], v1, v1 op_sel_hi:[0,0,0]
	v_mfma_scale_f32_16x16x128_f8f6f4 v[70:73], v[10:17], v[208:215], v[70:73], v1, v1 op_sel_hi:[0,0,0]
	v_mfma_scale_f32_16x16x128_f8f6f4 v[62:65], v[2:9], v[216:223], v[62:65], v1, v1 op_sel_hi:[0,0,0]
	v_mfma_scale_f32_16x16x128_f8f6f4 v[54:57], v[10:17], v[216:223], v[54:57], v1, v1 op_sel_hi:[0,0,0]
	v_mfma_scale_f32_16x16x128_f8f6f4 v[46:49], v[2:9], v[224:231], v[46:49], v1, v1 op_sel_hi:[0,0,0]
	v_mfma_scale_f32_16x16x128_f8f6f4 v[38:41], v[10:17], v[224:231], v[38:41], v1, v1 op_sel_hi:[0,0,0]
	s_barrier
	s_add_u32 s34, s30, 0x20000
	s_addc_u32 s35, s31, 0
	s_add_i32 s0, s0, s43
	v_lshl_add_u64 v[2:3], s[34:35], 0, v[164:165]
	s_mov_b32 m0, s0
	s_nop 0
	global_load_lds_dwordx4 v[2:3], off
	v_lshl_add_u64 v[2:3], s[34:35], 0, v[166:167]
	s_add_i32 m0, s0, 0x2000
	s_nop 0
	global_load_lds_dwordx4 v[2:3], off
	s_waitcnt vmcnt(10)
	s_barrier
	v_mfma_scale_f32_16x16x128_f8f6f4 v[90:93], v[18:25], v[200:207], v[90:93], v1, v1 op_sel_hi:[0,0,0]
	v_mfma_scale_f32_16x16x128_f8f6f4 v[82:85], v[26:33], v[200:207], v[82:85], v1, v1 op_sel_hi:[0,0,0]
	v_mfma_scale_f32_16x16x128_f8f6f4 v[74:77], v[18:25], v[208:215], v[74:77], v1, v1 op_sel_hi:[0,0,0]
	v_mfma_scale_f32_16x16x128_f8f6f4 v[66:69], v[26:33], v[208:215], v[66:69], v1, v1 op_sel_hi:[0,0,0]
	v_mfma_scale_f32_16x16x128_f8f6f4 v[58:61], v[18:25], v[216:223], v[58:61], v1, v1 op_sel_hi:[0,0,0]
	v_mfma_scale_f32_16x16x128_f8f6f4 v[50:53], v[26:33], v[216:223], v[50:53], v1, v1 op_sel_hi:[0,0,0]
	v_mfma_scale_f32_16x16x128_f8f6f4 v[42:45], v[18:25], v[224:231], v[42:45], v1, v1 op_sel_hi:[0,0,0]
	v_mfma_scale_f32_16x16x128_f8f6f4 v[34:37], v[26:33], v[224:231], v[34:37], v1, v1 op_sel_hi:[0,0,0]
	s_add_i32 s0, 0, 0x18000
	v_add_u32_e32 v14, s0, v196
	s_barrier
	ds_read_b128 v[2:5], v14
	ds_read_b128 v[6:9], v14 offset:1024
	ds_read_b128 v[10:13], v14 offset:2048
	ds_read_b128 v[14:17], v14 offset:3072
	s_mov_b32 m0, s47
	ds_read_b128 v[18:21], v169 offset:32768
	ds_read_b128 v[22:25], v169 offset:33792
	ds_read_b128 v[26:29], v169 offset:34816
	ds_read_b128 v[30:33], v169 offset:35840
	ds_read_b128 v[200:203], v169 offset:36864
	ds_read_b128 v[204:207], v169 offset:37888
	ds_read_b128 v[208:211], v169 offset:38912
	ds_read_b128 v[212:215], v169 offset:39936
	global_load_lds_dwordx4 v175, s[36:37]
	s_mov_b32 m0, s48
	s_nop 0
	global_load_lds_dwordx4 v173, s[36:37]
	s_waitcnt lgkmcnt(8)
	s_waitcnt vmcnt(10)
	s_barrier
	s_waitcnt lgkmcnt(0)
	s_waitcnt lgkmcnt(0)
	v_mfma_scale_f32_16x16x128_f8f6f4 v[158:161], v[2:9], v[18:25], v[158:161], v1, v1 op_sel_hi:[0,0,0]
	v_mfma_scale_f32_16x16x128_f8f6f4 v[150:153], v[10:17], v[18:25], v[150:153], v1, v1 op_sel_hi:[0,0,0]
	v_mfma_scale_f32_16x16x128_f8f6f4 v[142:145], v[2:9], v[26:33], v[142:145], v1, v1 op_sel_hi:[0,0,0]
	v_mfma_scale_f32_16x16x128_f8f6f4 v[134:137], v[10:17], v[26:33], v[134:137], v1, v1 op_sel_hi:[0,0,0]
	v_mfma_scale_f32_16x16x128_f8f6f4 v[126:129], v[2:9], v[200:207], v[126:129], v1, v1 op_sel_hi:[0,0,0]
	v_mfma_scale_f32_16x16x128_f8f6f4 v[118:121], v[10:17], v[200:207], v[118:121], v1, v1 op_sel_hi:[0,0,0]
	v_mfma_scale_f32_16x16x128_f8f6f4 v[110:113], v[2:9], v[208:215], v[110:113], v1, v1 op_sel_hi:[0,0,0]
	v_mfma_scale_f32_16x16x128_f8f6f4 v[102:105], v[10:17], v[208:215], v[102:105], v1, v1 op_sel_hi:[0,0,0]
	s_barrier
	s_add_i32 s34, 0, 0x1c000
	s_add_i32 s0, s0, s43
	v_add_u32_e32 v162, s34, v196
	v_lshl_add_u64 v[180:181], v[180:181], 0, s[20:21]
	s_mov_b32 m0, s0
	ds_read_b128 v[216:219], v162
	ds_read_b128 v[220:223], v162 offset:1024
	ds_read_b128 v[224:227], v162 offset:2048
	ds_read_b128 v[228:231], v162 offset:3072
	global_load_lds_dwordx4 v[180:181], off
	v_lshl_add_u64 v[180:181], v[182:183], 0, s[20:21]
	s_add_i32 m0, s0, 0x2000
	s_nop 0
	global_load_lds_dwordx4 v[180:181], off
	s_waitcnt vmcnt(10)
	s_barrier
	s_waitcnt lgkmcnt(0)
	s_waitcnt lgkmcnt(0)
	v_mfma_scale_f32_16x16x128_f8f6f4 v[154:157], v[216:223], v[18:25], v[154:157], v1, v1 op_sel_hi:[0,0,0]
	v_mfma_scale_f32_16x16x128_f8f6f4 v[146:149], v[224:231], v[18:25], v[146:149], v1, v1 op_sel_hi:[0,0,0]
	v_mfma_scale_f32_16x16x128_f8f6f4 v[138:141], v[216:223], v[26:33], v[138:141], v1, v1 op_sel_hi:[0,0,0]
	v_mfma_scale_f32_16x16x128_f8f6f4 v[130:133], v[224:231], v[26:33], v[130:133], v1, v1 op_sel_hi:[0,0,0]
	v_mfma_scale_f32_16x16x128_f8f6f4 v[122:125], v[216:223], v[200:207], v[122:125], v1, v1 op_sel_hi:[0,0,0]
	v_mfma_scale_f32_16x16x128_f8f6f4 v[114:117], v[224:231], v[200:207], v[114:117], v1, v1 op_sel_hi:[0,0,0]
	v_mfma_scale_f32_16x16x128_f8f6f4 v[106:109], v[216:223], v[208:215], v[106:109], v1, v1 op_sel_hi:[0,0,0]
	v_mfma_scale_f32_16x16x128_f8f6f4 v[98:101], v[224:231], v[208:215], v[98:101], v1, v1 op_sel_hi:[0,0,0]
	s_mov_b32 m0, s51
	v_lshl_add_u64 v[180:181], v[186:187], 0, s[20:21]
	s_barrier
	ds_read_b128 v[18:21], v169 offset:49152
	ds_read_b128 v[22:25], v169 offset:50176
	ds_read_b128 v[26:29], v169 offset:51200
	ds_read_b128 v[30:33], v169 offset:52224
	ds_read_b128 v[200:203], v169 offset:53248
	ds_read_b128 v[204:207], v169 offset:54272
	ds_read_b128 v[208:211], v169 offset:55296
	ds_read_b128 v[212:215], v169 offset:56320
	global_load_lds_dwordx4 v[180:181], off
	v_lshl_add_u64 v[180:181], v[184:185], 0, s[20:21]
	s_mov_b32 m0, s52
	s_nop 0
	global_load_lds_dwordx4 v[180:181], off
	s_waitcnt vmcnt(10)
	s_barrier
	s_waitcnt lgkmcnt(0)
	s_waitcnt lgkmcnt(0)
	v_mfma_scale_f32_16x16x128_f8f6f4 v[94:97], v[2:9], v[18:25], v[94:97], v1, v1 op_sel_hi:[0,0,0]
	v_mfma_scale_f32_16x16x128_f8f6f4 v[86:89], v[10:17], v[18:25], v[86:89], v1, v1 op_sel_hi:[0,0,0]
	v_mfma_scale_f32_16x16x128_f8f6f4 v[78:81], v[2:9], v[26:33], v[78:81], v1, v1 op_sel_hi:[0,0,0]
	v_mfma_scale_f32_16x16x128_f8f6f4 v[70:73], v[10:17], v[26:33], v[70:73], v1, v1 op_sel_hi:[0,0,0]
	v_mfma_scale_f32_16x16x128_f8f6f4 v[62:65], v[2:9], v[200:207], v[62:65], v1, v1 op_sel_hi:[0,0,0]
	v_mfma_scale_f32_16x16x128_f8f6f4 v[54:57], v[10:17], v[200:207], v[54:57], v1, v1 op_sel_hi:[0,0,0]
	v_mfma_scale_f32_16x16x128_f8f6f4 v[46:49], v[2:9], v[208:215], v[46:49], v1, v1 op_sel_hi:[0,0,0]
	v_mfma_scale_f32_16x16x128_f8f6f4 v[38:41], v[10:17], v[208:215], v[38:41], v1, v1 op_sel_hi:[0,0,0]
	s_barrier
	s_add_u32 s0, s30, 0x20080
	s_addc_u32 s1, s31, 0
	s_add_i32 s30, s34, s43
	v_lshl_add_u64 v[2:3], s[0:1], 0, v[164:165]
	s_mov_b32 m0, s30
	s_nop 0
	global_load_lds_dwordx4 v[2:3], off
	v_lshl_add_u64 v[2:3], s[0:1], 0, v[166:167]
	s_add_i32 m0, s30, 0x2000
	s_nop 0
	global_load_lds_dwordx4 v[2:3], off
	s_waitcnt vmcnt(10)
	s_barrier
	v_mfma_scale_f32_16x16x128_f8f6f4 v[90:93], v[216:223], v[18:25], v[90:93], v1, v1 op_sel_hi:[0,0,0]
	v_mfma_scale_f32_16x16x128_f8f6f4 v[82:85], v[224:231], v[18:25], v[82:85], v1, v1 op_sel_hi:[0,0,0]
	v_mfma_scale_f32_16x16x128_f8f6f4 v[74:77], v[216:223], v[26:33], v[74:77], v1, v1 op_sel_hi:[0,0,0]
	v_mfma_scale_f32_16x16x128_f8f6f4 v[66:69], v[224:231], v[26:33], v[66:69], v1, v1 op_sel_hi:[0,0,0]
	v_mfma_scale_f32_16x16x128_f8f6f4 v[58:61], v[216:223], v[200:207], v[58:61], v1, v1 op_sel_hi:[0,0,0]
	v_mfma_scale_f32_16x16x128_f8f6f4 v[50:53], v[224:231], v[200:207], v[50:53], v1, v1 op_sel_hi:[0,0,0]
	v_mfma_scale_f32_16x16x128_f8f6f4 v[42:45], v[216:223], v[208:215], v[42:45], v1, v1 op_sel_hi:[0,0,0]
	v_mfma_scale_f32_16x16x128_f8f6f4 v[34:37], v[224:231], v[208:215], v[34:37], v1, v1 op_sel_hi:[0,0,0]
	s_add_i32 s56, s56, 2
	s_cmp_gt_u32 s56, 5
	s_mov_b64 s[34:35], s[10:11]
	s_barrier
	s_cbranch_scc0 .LBB0_2749
	v_mul_f32_e32 v5, 0x3c800000, v158
	v_mul_f32_e32 v6, 0xbfb8aa3b, v5
	v_exp_f32_e32 v6, v6
	s_ashr_i32 s29, s28, 31
	s_ashr_i32 s27, s26, 31
	s_lshl_b64 s[10:11], s[28:29], 18
	v_add_f32_e32 v6, 1.0, v6
	v_rcp_f32_e32 v6, v6
	s_lshl_b64 s[26:27], s[26:27], 15
	v_mov_b32_e32 v3, v194
	s_add_u32 s0, s8, s10
	v_mul_f32_e32 v5, v5, v6
	v_mul_f32_e32 v6, 0x3c800000, v159
	v_mul_f32_e32 v7, 0xbfb8aa3b, v6
	v_exp_f32_e32 v7, v7
	v_mul_f32_e32 v5, v5, v154
	v_mul_f32_e32 v5, 0x3e000000, v5
	v_med3_f32 v5, v5, s40, v189
	v_add_f32_e32 v7, 1.0, v7
	v_rcp_f32_e32 v7, v7
	s_nop 15
	s_nop 15
	v_mov_b32_e32 v2, v195
	v_mul_f32_e32 v6, v6, v7
	v_mul_f32_e32 v7, 0x3c800000, v160
	v_mul_f32_e32 v8, 0xbfb8aa3b, v7
	v_exp_f32_e32 v8, v8
	v_mul_f32_e32 v6, v6, v155
	v_mul_f32_e32 v6, 0x3e000000, v6
	v_add_u32_e32 v4, s49, v3
	v_add_f32_e32 v8, 1.0, v8
	v_rcp_f32_e32 v8, v8
	s_addc_u32 s1, s9, s11
	s_add_u32 s10, s0, s26
	v_mul_f32_e32 v7, v7, v8
	v_mul_f32_e32 v8, 0x3c800000, v161
	v_mul_f32_e32 v9, 0xbfb8aa3b, v8
	v_exp_f32_e32 v9, v9
	v_mul_f32_e32 v7, v7, v156
	v_mul_f32_e32 v7, 0x3e000000, v7
	v_lshl_add_u32 v2, v2, 3, s50
	v_add_f32_e32 v9, 1.0, v9
	v_rcp_f32_e32 v9, v9
	s_addc_u32 s11, s1, s27
	v_ashrrev_i32_e32 v3, 31, v2
	s_and_b64 vcc, exec, s[6:7]
	v_mul_f32_e32 v8, v8, v9
	v_mul_f32_e32 v9, 0x3c800000, v150
	v_mul_f32_e32 v10, 0xbfb8aa3b, v9
	v_exp_f32_e32 v10, v10
	v_mul_f32_e32 v8, v8, v157
	v_mul_f32_e32 v8, 0x3e000000, v8
	v_mov_b32_e32 v174, v199
	v_add_f32_e32 v10, 1.0, v10
	v_rcp_f32_e32 v10, v10
	v_mov_b32_e32 v172, v198
	v_mov_b32_e32 v170, v197
	v_mov_b32_e32 v168, v171
	v_mul_f32_e32 v9, v9, v10
	v_mul_f32_e32 v10, 0x3c800000, v151
	v_mul_f32_e32 v11, 0xbfb8aa3b, v10
	v_exp_f32_e32 v11, v11
	v_mul_f32_e32 v9, v9, v146
	v_mul_f32_e32 v9, 0x3e000000, v9
	s_mov_b32 s26, s24
	v_add_f32_e32 v11, 1.0, v11
	v_rcp_f32_e32 v11, v11
	s_mov_b32 s28, s54
	s_mov_b64 s[30:31], s[12:13]
	v_mul_f32_e32 v10, v10, v11
	v_mul_f32_e32 v11, 0x3c800000, v152
	v_mul_f32_e32 v12, 0xbfb8aa3b, v11
	v_exp_f32_e32 v12, v12
	v_mul_f32_e32 v10, v10, v147
	v_mul_f32_e32 v10, 0x3e000000, v10
	v_add_f32_e32 v12, 1.0, v12
	v_rcp_f32_e32 v12, v12
	s_nop 0
	v_mul_f32_e32 v11, v11, v12
	v_mul_f32_e32 v12, 0x3c800000, v153
	v_mul_f32_e32 v13, 0xbfb8aa3b, v12
	v_exp_f32_e32 v13, v13
	v_mul_f32_e32 v11, v11, v148
	v_mul_f32_e32 v11, 0x3e000000, v11
	v_add_f32_e32 v13, 1.0, v13
	v_rcp_f32_e32 v13, v13
	s_nop 0
	v_mul_f32_e32 v12, v12, v13
	v_med3_f32 v13, v6, s40, v189
	v_mov_b32_e32 v6, v163
	v_cvt_pk_fp8_f32 v6, v5, v13
	v_med3_f32 v5, v7, s40, v189
	v_med3_f32 v7, v8, s40, v189
	v_med3_f32 v8, v10, s40, v189
	v_cvt_pk_fp8_f32 v6, v5, v7 op_sel:[0,0,1]
	v_med3_f32 v5, v9, s40, v189
	v_mov_b32_e32 v7, v163
	v_cvt_pk_fp8_f32 v7, v5, v8
	v_mul_f32_e32 v12, v12, v149
	v_mul_f32_e32 v12, 0x3e000000, v12
	v_med3_f32 v5, v11, s40, v189
	v_med3_f32 v8, v12, s40, v189
	v_cvt_pk_fp8_f32 v7, v5, v8 op_sel:[0,0,1]
	v_ashrrev_i32_e32 v5, 31, v4
	v_lshlrev_b64 v[8:9], 7, v[4:5]
	v_lshl_add_u64 v[8:9], s[10:11], 0, v[8:9]
	v_lshl_add_u64 v[8:9], v[8:9], 0, v[2:3]
	v_mul_f32_e32 v5, 0x3c800000, v142
	flat_store_dwordx2 v[8:9], v[6:7]
	v_mul_f32_e32 v6, 0xbfb8aa3b, v5
	v_exp_f32_e32 v6, v6
	s_nop 0
	v_add_f32_e32 v6, 1.0, v6
	v_rcp_f32_e32 v6, v6
	s_nop 0
	v_mul_f32_e32 v5, v5, v6
	v_mul_f32_e32 v6, 0x3c800000, v143
	v_mul_f32_e32 v7, 0xbfb8aa3b, v6
	v_exp_f32_e32 v7, v7
	v_mul_f32_e32 v5, v5, v138
	v_mul_f32_e32 v5, 0x3e000000, v5
	v_med3_f32 v5, v5, s40, v189
	v_add_f32_e32 v7, 1.0, v7
	v_rcp_f32_e32 v7, v7
	s_nop 0
	v_mul_f32_e32 v6, v6, v7
	v_mul_f32_e32 v6, v6, v139
	v_mul_f32_e32 v7, 0x3e000000, v6
	v_mul_f32_e32 v6, 0x3c800000, v144
	v_mul_f32_e32 v8, 0xbfb8aa3b, v6
	v_exp_f32_e32 v8, v8
	v_med3_f32 v7, v7, s40, v189
	v_add_f32_e32 v8, 1.0, v8
	v_rcp_f32_e32 v8, v8
	s_nop 0
	v_mul_f32_e32 v6, v6, v8
	v_mul_f32_e32 v6, v6, v140
	v_mul_f32_e32 v9, 0x3e000000, v6
	v_mul_f32_e32 v6, 0x3c800000, v145
	v_mul_f32_e32 v8, 0xbfb8aa3b, v6
	v_exp_f32_e32 v8, v8
	s_nop 0
	v_add_f32_e32 v8, 1.0, v8
	v_rcp_f32_e32 v8, v8
	s_nop 0
	v_mul_f32_e32 v6, v6, v8
	v_mul_f32_e32 v6, v6, v141
	v_mul_f32_e32 v10, 0x3e000000, v6
	v_mul_f32_e32 v6, 0x3c800000, v134
	v_mul_f32_e32 v8, 0xbfb8aa3b, v6
	v_exp_f32_e32 v8, v8
	s_nop 0
	v_add_f32_e32 v8, 1.0, v8
	v_rcp_f32_e32 v8, v8
	s_nop 0
	v_mul_f32_e32 v6, v6, v8
	v_mul_f32_e32 v6, v6, v130
	v_mul_f32_e32 v11, 0x3e000000, v6
	v_mul_f32_e32 v6, 0x3c800000, v135
	v_mul_f32_e32 v8, 0xbfb8aa3b, v6
	v_exp_f32_e32 v8, v8
	s_nop 0
	v_add_f32_e32 v8, 1.0, v8
	v_rcp_f32_e32 v8, v8
	s_nop 0
	v_mul_f32_e32 v6, v6, v8
	v_mul_f32_e32 v6, v6, v131
	v_mul_f32_e32 v12, 0x3e000000, v6
	v_mul_f32_e32 v6, 0x3c800000, v136
	v_mul_f32_e32 v8, 0xbfb8aa3b, v6
	v_exp_f32_e32 v8, v8
	s_nop 0
	v_add_f32_e32 v8, 1.0, v8
	v_rcp_f32_e32 v8, v8
	s_nop 0
	v_mul_f32_e32 v6, v6, v8
	v_mul_f32_e32 v6, v6, v132
	v_mul_f32_e32 v13, 0x3e000000, v6
	v_mul_f32_e32 v6, 0x3c800000, v137
	v_mul_f32_e32 v8, 0xbfb8aa3b, v6
	v_exp_f32_e32 v8, v8
	s_nop 0
	v_add_f32_e32 v8, 1.0, v8
	v_rcp_f32_e32 v8, v8
	s_nop 0
	v_mul_f32_e32 v6, v6, v8
	v_mov_b32_e32 v8, v163
	v_cvt_pk_fp8_f32 v8, v5, v7
	v_med3_f32 v5, v9, s40, v189
	v_med3_f32 v7, v10, s40, v189
	v_mov_b32_e32 v9, v163
	v_cvt_pk_fp8_f32 v8, v5, v7 op_sel:[0,0,1]
	v_med3_f32 v5, v11, s40, v189
	v_med3_f32 v7, v12, s40, v189
	v_cvt_pk_fp8_f32 v9, v5, v7
	v_mul_f32_e32 v6, v6, v133
	v_mul_f32_e32 v14, 0x3e000000, v6
	v_add_u32_e32 v6, 16, v4
	v_med3_f32 v5, v13, s40, v189
	v_med3_f32 v7, v14, s40, v189
	v_cvt_pk_fp8_f32 v9, v5, v7 op_sel:[0,0,1]
	v_ashrrev_i32_e32 v7, 31, v6
	v_lshlrev_b64 v[6:7], 7, v[6:7]
	v_lshl_add_u64 v[6:7], s[10:11], 0, v[6:7]
	v_lshl_add_u64 v[6:7], v[6:7], 0, v[2:3]
	v_mul_f32_e32 v5, 0x3c800000, v126
	flat_store_dwordx2 v[6:7], v[8:9]
	v_mul_f32_e32 v6, 0xbfb8aa3b, v5
	v_exp_f32_e32 v6, v6
	s_nop 0
	v_add_f32_e32 v6, 1.0, v6
	v_rcp_f32_e32 v6, v6
	s_nop 0
	v_mul_f32_e32 v5, v5, v6
	v_mul_f32_e32 v6, 0x3c800000, v127
	v_mul_f32_e32 v7, 0xbfb8aa3b, v6
	v_exp_f32_e32 v7, v7
	v_mul_f32_e32 v5, v5, v122
	v_mul_f32_e32 v5, 0x3e000000, v5
	v_med3_f32 v5, v5, s40, v189
	v_add_f32_e32 v7, 1.0, v7
	v_rcp_f32_e32 v7, v7
	s_nop 0
	v_mul_f32_e32 v6, v6, v7
	v_mul_f32_e32 v6, v6, v123
	v_mul_f32_e32 v7, 0x3e000000, v6
	v_mul_f32_e32 v6, 0x3c800000, v128
	v_mul_f32_e32 v8, 0xbfb8aa3b, v6
	v_exp_f32_e32 v8, v8
	v_med3_f32 v7, v7, s40, v189
	v_add_f32_e32 v8, 1.0, v8
	v_rcp_f32_e32 v8, v8
	s_nop 0
	v_mul_f32_e32 v6, v6, v8
	v_mul_f32_e32 v6, v6, v124
	v_mul_f32_e32 v9, 0x3e000000, v6
	v_mul_f32_e32 v6, 0x3c800000, v129
	v_mul_f32_e32 v8, 0xbfb8aa3b, v6
	v_exp_f32_e32 v8, v8
	s_nop 0
	v_add_f32_e32 v8, 1.0, v8
	v_rcp_f32_e32 v8, v8
	s_nop 0
	v_mul_f32_e32 v6, v6, v8
	v_mul_f32_e32 v6, v6, v125
	v_mul_f32_e32 v10, 0x3e000000, v6
	v_mul_f32_e32 v6, 0x3c800000, v118
	v_mul_f32_e32 v8, 0xbfb8aa3b, v6
	v_exp_f32_e32 v8, v8
	s_nop 0
	v_add_f32_e32 v8, 1.0, v8
	v_rcp_f32_e32 v8, v8
	s_nop 0
	v_mul_f32_e32 v6, v6, v8
	v_mul_f32_e32 v6, v6, v114
	v_mul_f32_e32 v11, 0x3e000000, v6
	v_mul_f32_e32 v6, 0x3c800000, v119
	v_mul_f32_e32 v8, 0xbfb8aa3b, v6
	v_exp_f32_e32 v8, v8
	s_nop 0
	v_add_f32_e32 v8, 1.0, v8
	v_rcp_f32_e32 v8, v8
	s_nop 0
	v_mul_f32_e32 v6, v6, v8
	v_mul_f32_e32 v6, v6, v115
	v_mul_f32_e32 v12, 0x3e000000, v6
	v_mul_f32_e32 v6, 0x3c800000, v120
	v_mul_f32_e32 v8, 0xbfb8aa3b, v6
	v_exp_f32_e32 v8, v8
	s_nop 0
	v_add_f32_e32 v8, 1.0, v8
	v_rcp_f32_e32 v8, v8
	s_nop 0
	v_mul_f32_e32 v6, v6, v8
	v_mul_f32_e32 v6, v6, v116
	v_mul_f32_e32 v13, 0x3e000000, v6
	v_mul_f32_e32 v6, 0x3c800000, v121
	v_mul_f32_e32 v8, 0xbfb8aa3b, v6
	v_exp_f32_e32 v8, v8
	s_nop 0
	v_add_f32_e32 v8, 1.0, v8
	v_rcp_f32_e32 v8, v8
	s_nop 0
	v_mul_f32_e32 v6, v6, v8
	v_mov_b32_e32 v8, v163
	v_cvt_pk_fp8_f32 v8, v5, v7
	v_med3_f32 v5, v9, s40, v189
	v_med3_f32 v7, v10, s40, v189
	v_mov_b32_e32 v9, v163
	v_cvt_pk_fp8_f32 v8, v5, v7 op_sel:[0,0,1]
	v_med3_f32 v5, v11, s40, v189
	v_med3_f32 v7, v12, s40, v189
	v_cvt_pk_fp8_f32 v9, v5, v7
	v_mul_f32_e32 v6, v6, v117
	v_mul_f32_e32 v14, 0x3e000000, v6
	v_add_u32_e32 v6, 32, v4
	v_med3_f32 v5, v13, s40, v189
	v_med3_f32 v7, v14, s40, v189
	v_cvt_pk_fp8_f32 v9, v5, v7 op_sel:[0,0,1]
	v_ashrrev_i32_e32 v7, 31, v6
	v_lshlrev_b64 v[6:7], 7, v[6:7]
	v_lshl_add_u64 v[6:7], s[10:11], 0, v[6:7]
	v_lshl_add_u64 v[6:7], v[6:7], 0, v[2:3]
	v_mul_f32_e32 v5, 0x3c800000, v110
	flat_store_dwordx2 v[6:7], v[8:9]
	v_mul_f32_e32 v6, 0xbfb8aa3b, v5
	v_exp_f32_e32 v6, v6
	s_nop 0
	v_add_f32_e32 v6, 1.0, v6
	v_rcp_f32_e32 v6, v6
	s_nop 0
	v_mul_f32_e32 v5, v5, v6
	v_mul_f32_e32 v6, 0x3c800000, v111
	v_mul_f32_e32 v7, 0xbfb8aa3b, v6
	v_exp_f32_e32 v7, v7
	v_mul_f32_e32 v5, v5, v106
	v_mul_f32_e32 v5, 0x3e000000, v5
	v_med3_f32 v5, v5, s40, v189
	v_add_f32_e32 v7, 1.0, v7
	v_rcp_f32_e32 v7, v7
	s_nop 0
	v_mul_f32_e32 v6, v6, v7
	v_mul_f32_e32 v6, v6, v107
	v_mul_f32_e32 v7, 0x3e000000, v6
	v_mul_f32_e32 v6, 0x3c800000, v112
	v_mul_f32_e32 v8, 0xbfb8aa3b, v6
	v_exp_f32_e32 v8, v8
	v_med3_f32 v7, v7, s40, v189
	v_add_f32_e32 v8, 1.0, v8
	v_rcp_f32_e32 v8, v8
	s_nop 0
	v_mul_f32_e32 v6, v6, v8
	v_mul_f32_e32 v6, v6, v108
	v_mul_f32_e32 v9, 0x3e000000, v6
	v_mul_f32_e32 v6, 0x3c800000, v113
	v_mul_f32_e32 v8, 0xbfb8aa3b, v6
	v_exp_f32_e32 v8, v8
	s_nop 0
	v_add_f32_e32 v8, 1.0, v8
	v_rcp_f32_e32 v8, v8
	s_nop 0
	v_mul_f32_e32 v6, v6, v8
	v_mul_f32_e32 v6, v6, v109
	v_mul_f32_e32 v10, 0x3e000000, v6
	v_mul_f32_e32 v6, 0x3c800000, v102
	v_mul_f32_e32 v8, 0xbfb8aa3b, v6
	v_exp_f32_e32 v8, v8
	s_nop 0
	v_add_f32_e32 v8, 1.0, v8
	v_rcp_f32_e32 v8, v8
	s_nop 0
	v_mul_f32_e32 v6, v6, v8
	v_mul_f32_e32 v6, v6, v98
	v_mul_f32_e32 v11, 0x3e000000, v6
	v_mul_f32_e32 v6, 0x3c800000, v103
	v_mul_f32_e32 v8, 0xbfb8aa3b, v6
	v_exp_f32_e32 v8, v8
	s_nop 0
	v_add_f32_e32 v8, 1.0, v8
	v_rcp_f32_e32 v8, v8
	s_nop 0
	v_mul_f32_e32 v6, v6, v8
	v_mul_f32_e32 v6, v6, v99
	v_mul_f32_e32 v12, 0x3e000000, v6
	v_mul_f32_e32 v6, 0x3c800000, v104
	v_mul_f32_e32 v8, 0xbfb8aa3b, v6
	v_exp_f32_e32 v8, v8
	s_nop 0
	v_add_f32_e32 v8, 1.0, v8
	v_rcp_f32_e32 v8, v8
	s_nop 0
	v_mul_f32_e32 v6, v6, v8
	v_mul_f32_e32 v6, v6, v100
	v_mul_f32_e32 v13, 0x3e000000, v6
	v_mul_f32_e32 v6, 0x3c800000, v105
	v_mul_f32_e32 v8, 0xbfb8aa3b, v6
	v_exp_f32_e32 v8, v8
	s_nop 0
	v_add_f32_e32 v8, 1.0, v8
	v_rcp_f32_e32 v8, v8
	s_nop 0
	v_mul_f32_e32 v6, v6, v8
	v_mov_b32_e32 v8, v163
	v_cvt_pk_fp8_f32 v8, v5, v7
	v_med3_f32 v5, v9, s40, v189
	v_med3_f32 v7, v10, s40, v189
	v_mov_b32_e32 v9, v163
	v_cvt_pk_fp8_f32 v8, v5, v7 op_sel:[0,0,1]
	v_med3_f32 v5, v11, s40, v189
	v_med3_f32 v7, v12, s40, v189
	v_cvt_pk_fp8_f32 v9, v5, v7
	v_mul_f32_e32 v6, v6, v101
	v_mul_f32_e32 v14, 0x3e000000, v6
	v_add_u32_e32 v6, 48, v4
	v_med3_f32 v5, v13, s40, v189
	v_med3_f32 v7, v14, s40, v189
	v_cvt_pk_fp8_f32 v9, v5, v7 op_sel:[0,0,1]
	v_ashrrev_i32_e32 v7, 31, v6
	v_lshlrev_b64 v[6:7], 7, v[6:7]
	v_lshl_add_u64 v[6:7], s[10:11], 0, v[6:7]
	v_lshl_add_u64 v[6:7], v[6:7], 0, v[2:3]
	v_mul_f32_e32 v5, 0x3c800000, v94
	flat_store_dwordx2 v[6:7], v[8:9]
	v_mul_f32_e32 v7, 0xbfb8aa3b, v5
	v_exp_f32_e32 v7, v7
	v_add_u32_e32 v6, 0x80, v4
	v_add_f32_e32 v7, 1.0, v7
	v_rcp_f32_e32 v7, v7
	s_nop 0
	v_mul_f32_e32 v5, v5, v7
	v_mul_f32_e32 v7, 0x3c800000, v95
	v_mul_f32_e32 v8, 0xbfb8aa3b, v7
	v_exp_f32_e32 v8, v8
	v_mul_f32_e32 v5, v5, v90
	v_mul_f32_e32 v5, 0x3e000000, v5
	v_med3_f32 v5, v5, s40, v189
	v_add_f32_e32 v8, 1.0, v8
	v_rcp_f32_e32 v8, v8
	s_nop 0
	v_mul_f32_e32 v7, v7, v8
	v_mul_f32_e32 v8, 0x3c800000, v96
	v_mul_f32_e32 v9, 0xbfb8aa3b, v8
	v_exp_f32_e32 v9, v9
	v_mul_f32_e32 v7, v7, v91
	v_mul_f32_e32 v7, 0x3e000000, v7
	v_med3_f32 v7, v7, s40, v189
	v_add_f32_e32 v9, 1.0, v9
	v_rcp_f32_e32 v9, v9
	s_nop 0
	v_mul_f32_e32 v8, v8, v9
	v_mul_f32_e32 v8, v8, v92
	v_mul_f32_e32 v9, 0x3e000000, v8
	v_mul_f32_e32 v8, 0x3c800000, v97
	v_mul_f32_e32 v10, 0xbfb8aa3b, v8
	v_exp_f32_e32 v10, v10
	s_nop 0
	v_add_f32_e32 v10, 1.0, v10
	v_rcp_f32_e32 v10, v10
	s_nop 0
	v_mul_f32_e32 v8, v8, v10
	v_mul_f32_e32 v8, v8, v93
	v_mul_f32_e32 v10, 0x3e000000, v8
	v_mul_f32_e32 v8, 0x3c800000, v86
	v_mul_f32_e32 v11, 0xbfb8aa3b, v8
	v_exp_f32_e32 v11, v11
	s_nop 0
	v_add_f32_e32 v11, 1.0, v11
	v_rcp_f32_e32 v11, v11
	s_nop 0
	v_mul_f32_e32 v8, v8, v11
	v_mul_f32_e32 v8, v8, v82
	v_mul_f32_e32 v11, 0x3e000000, v8
	v_mul_f32_e32 v8, 0x3c800000, v87
	v_mul_f32_e32 v12, 0xbfb8aa3b, v8
	v_exp_f32_e32 v12, v12
	s_nop 0
	v_add_f32_e32 v12, 1.0, v12
	v_rcp_f32_e32 v12, v12
	s_nop 0
	v_mul_f32_e32 v8, v8, v12
	v_mul_f32_e32 v8, v8, v83
	v_mul_f32_e32 v12, 0x3e000000, v8
	v_mul_f32_e32 v8, 0x3c800000, v88
	v_mul_f32_e32 v13, 0xbfb8aa3b, v8
	v_exp_f32_e32 v13, v13
	s_nop 0
	v_add_f32_e32 v13, 1.0, v13
	v_rcp_f32_e32 v13, v13
	s_nop 0
	v_mul_f32_e32 v8, v8, v13
	v_mul_f32_e32 v8, v8, v84
	v_mul_f32_e32 v13, 0x3e000000, v8
	v_mul_f32_e32 v8, 0x3c800000, v89
	v_mul_f32_e32 v14, 0xbfb8aa3b, v8
	v_exp_f32_e32 v14, v14
	s_nop 0
	v_add_f32_e32 v14, 1.0, v14
	v_rcp_f32_e32 v14, v14
	s_nop 0
	v_mul_f32_e32 v8, v8, v14
	v_mul_f32_e32 v8, v8, v85
	v_mul_f32_e32 v14, 0x3e000000, v8
	v_mov_b32_e32 v8, v163
	v_cvt_pk_fp8_f32 v8, v5, v7
	v_med3_f32 v5, v9, s40, v189
	v_med3_f32 v7, v10, s40, v189
	v_mov_b32_e32 v9, v163
	v_cvt_pk_fp8_f32 v8, v5, v7 op_sel:[0,0,1]
	v_med3_f32 v5, v11, s40, v189
	v_med3_f32 v7, v12, s40, v189
	v_cvt_pk_fp8_f32 v9, v5, v7
	v_med3_f32 v5, v13, s40, v189
	v_med3_f32 v7, v14, s40, v189
	v_cvt_pk_fp8_f32 v9, v5, v7 op_sel:[0,0,1]
	v_ashrrev_i32_e32 v7, 31, v6
	v_lshlrev_b64 v[6:7], 7, v[6:7]
	v_lshl_add_u64 v[6:7], s[10:11], 0, v[6:7]
	v_lshl_add_u64 v[6:7], v[6:7], 0, v[2:3]
	v_mul_f32_e32 v5, 0x3c800000, v78
	flat_store_dwordx2 v[6:7], v[8:9]
	v_mul_f32_e32 v6, 0xbfb8aa3b, v5
	v_exp_f32_e32 v6, v6
	s_nop 0
	v_add_f32_e32 v6, 1.0, v6
	v_rcp_f32_e32 v6, v6
	s_nop 0
	v_mul_f32_e32 v5, v5, v6
	v_mul_f32_e32 v6, 0x3c800000, v79
	v_mul_f32_e32 v7, 0xbfb8aa3b, v6
	v_exp_f32_e32 v7, v7
	v_mul_f32_e32 v5, v5, v74
	v_mul_f32_e32 v5, 0x3e000000, v5
	v_med3_f32 v5, v5, s40, v189
	v_add_f32_e32 v7, 1.0, v7
	v_rcp_f32_e32 v7, v7
	s_nop 0
	v_mul_f32_e32 v6, v6, v7
	v_mul_f32_e32 v6, v6, v75
	v_mul_f32_e32 v7, 0x3e000000, v6
	v_mul_f32_e32 v6, 0x3c800000, v80
	v_mul_f32_e32 v8, 0xbfb8aa3b, v6
	v_exp_f32_e32 v8, v8
	v_med3_f32 v7, v7, s40, v189
	v_add_f32_e32 v8, 1.0, v8
	v_rcp_f32_e32 v8, v8
	s_nop 0
	v_mul_f32_e32 v6, v6, v8
	v_mul_f32_e32 v6, v6, v76
	v_mul_f32_e32 v9, 0x3e000000, v6
	v_mul_f32_e32 v6, 0x3c800000, v81
	v_mul_f32_e32 v8, 0xbfb8aa3b, v6
	v_exp_f32_e32 v8, v8
	s_nop 0
	v_add_f32_e32 v8, 1.0, v8
	v_rcp_f32_e32 v8, v8
	s_nop 0
	v_mul_f32_e32 v6, v6, v8
	v_mul_f32_e32 v6, v6, v77
	v_mul_f32_e32 v10, 0x3e000000, v6
	v_mul_f32_e32 v6, 0x3c800000, v70
	v_mul_f32_e32 v8, 0xbfb8aa3b, v6
	v_exp_f32_e32 v8, v8
	s_nop 0
	v_add_f32_e32 v8, 1.0, v8
	v_rcp_f32_e32 v8, v8
	s_nop 0
	v_mul_f32_e32 v6, v6, v8
	v_mul_f32_e32 v6, v6, v66
	v_mul_f32_e32 v11, 0x3e000000, v6
	v_mul_f32_e32 v6, 0x3c800000, v71
	v_mul_f32_e32 v8, 0xbfb8aa3b, v6
	v_exp_f32_e32 v8, v8
	s_nop 0
	v_add_f32_e32 v8, 1.0, v8
	v_rcp_f32_e32 v8, v8
	s_nop 0
	v_mul_f32_e32 v6, v6, v8
	v_mul_f32_e32 v6, v6, v67
	v_mul_f32_e32 v12, 0x3e000000, v6
	v_mul_f32_e32 v6, 0x3c800000, v72
	v_mul_f32_e32 v8, 0xbfb8aa3b, v6
	v_exp_f32_e32 v8, v8
	s_nop 0
	v_add_f32_e32 v8, 1.0, v8
	v_rcp_f32_e32 v8, v8
	s_nop 0
	v_mul_f32_e32 v6, v6, v8
	v_mul_f32_e32 v6, v6, v68
	v_mul_f32_e32 v13, 0x3e000000, v6
	v_mul_f32_e32 v6, 0x3c800000, v73
	v_mul_f32_e32 v8, 0xbfb8aa3b, v6
	v_exp_f32_e32 v8, v8
	s_nop 0
	v_add_f32_e32 v8, 1.0, v8
	v_rcp_f32_e32 v8, v8
	s_nop 0
	v_mul_f32_e32 v6, v6, v8
	v_mov_b32_e32 v8, v163
	v_cvt_pk_fp8_f32 v8, v5, v7
	v_med3_f32 v5, v9, s40, v189
	v_med3_f32 v7, v10, s40, v189
	v_mov_b32_e32 v9, v163
	v_cvt_pk_fp8_f32 v8, v5, v7 op_sel:[0,0,1]
	v_med3_f32 v5, v11, s40, v189
	v_med3_f32 v7, v12, s40, v189
	v_cvt_pk_fp8_f32 v9, v5, v7
	v_mul_f32_e32 v6, v6, v69
	v_mul_f32_e32 v14, 0x3e000000, v6
	v_add_u32_e32 v6, 0x90, v4
	v_med3_f32 v5, v13, s40, v189
	v_med3_f32 v7, v14, s40, v189
	v_cvt_pk_fp8_f32 v9, v5, v7 op_sel:[0,0,1]
	v_ashrrev_i32_e32 v7, 31, v6
	v_lshlrev_b64 v[6:7], 7, v[6:7]
	v_lshl_add_u64 v[6:7], s[10:11], 0, v[6:7]
	v_lshl_add_u64 v[6:7], v[6:7], 0, v[2:3]
	v_mul_f32_e32 v5, 0x3c800000, v62
	flat_store_dwordx2 v[6:7], v[8:9]
	v_mul_f32_e32 v6, 0xbfb8aa3b, v5
	v_exp_f32_e32 v6, v6
	s_nop 0
	v_add_f32_e32 v6, 1.0, v6
	v_rcp_f32_e32 v6, v6
	s_nop 0
	v_mul_f32_e32 v5, v5, v6
	v_mul_f32_e32 v6, 0x3c800000, v63
	v_mul_f32_e32 v7, 0xbfb8aa3b, v6
	v_exp_f32_e32 v7, v7
	v_mul_f32_e32 v5, v5, v58
	v_mul_f32_e32 v5, 0x3e000000, v5
	v_med3_f32 v5, v5, s40, v189
	v_add_f32_e32 v7, 1.0, v7
	v_rcp_f32_e32 v7, v7
	s_nop 0
	v_mul_f32_e32 v6, v6, v7
	v_mul_f32_e32 v6, v6, v59
	v_mul_f32_e32 v7, 0x3e000000, v6
	v_mul_f32_e32 v6, 0x3c800000, v64
	v_mul_f32_e32 v8, 0xbfb8aa3b, v6
	v_exp_f32_e32 v8, v8
	v_med3_f32 v7, v7, s40, v189
	v_add_f32_e32 v8, 1.0, v8
	v_rcp_f32_e32 v8, v8
	s_nop 0
	v_mul_f32_e32 v6, v6, v8
	v_mul_f32_e32 v6, v6, v60
	v_mul_f32_e32 v9, 0x3e000000, v6
	v_mul_f32_e32 v6, 0x3c800000, v65
	v_mul_f32_e32 v8, 0xbfb8aa3b, v6
	v_exp_f32_e32 v8, v8
	s_nop 0
	v_add_f32_e32 v8, 1.0, v8
	v_rcp_f32_e32 v8, v8
	s_nop 0
	v_mul_f32_e32 v6, v6, v8
	v_mul_f32_e32 v6, v6, v61
	v_mul_f32_e32 v10, 0x3e000000, v6
	v_mul_f32_e32 v6, 0x3c800000, v54
	v_mul_f32_e32 v8, 0xbfb8aa3b, v6
	v_exp_f32_e32 v8, v8
	s_nop 0
	v_add_f32_e32 v8, 1.0, v8
	v_rcp_f32_e32 v8, v8
	s_nop 0
	v_mul_f32_e32 v6, v6, v8
	v_mul_f32_e32 v6, v6, v50
	v_mul_f32_e32 v11, 0x3e000000, v6
	v_mul_f32_e32 v6, 0x3c800000, v55
	v_mul_f32_e32 v8, 0xbfb8aa3b, v6
	v_exp_f32_e32 v8, v8
	s_nop 0
	v_add_f32_e32 v8, 1.0, v8
	v_rcp_f32_e32 v8, v8
	s_nop 0
	v_mul_f32_e32 v6, v6, v8
	v_mul_f32_e32 v6, v6, v51
	v_mul_f32_e32 v12, 0x3e000000, v6
	v_mul_f32_e32 v6, 0x3c800000, v56
	v_mul_f32_e32 v8, 0xbfb8aa3b, v6
	v_exp_f32_e32 v8, v8
	s_nop 0
	v_add_f32_e32 v8, 1.0, v8
	v_rcp_f32_e32 v8, v8
	s_nop 0
	v_mul_f32_e32 v6, v6, v8
	v_mul_f32_e32 v6, v6, v52
	v_mul_f32_e32 v13, 0x3e000000, v6
	v_mul_f32_e32 v6, 0x3c800000, v57
	v_mul_f32_e32 v8, 0xbfb8aa3b, v6
	v_exp_f32_e32 v8, v8
	s_nop 0
	v_add_f32_e32 v8, 1.0, v8
	v_rcp_f32_e32 v8, v8
	s_nop 0
	v_mul_f32_e32 v6, v6, v8
	v_mov_b32_e32 v8, v163
	v_cvt_pk_fp8_f32 v8, v5, v7
	v_med3_f32 v5, v9, s40, v189
	v_med3_f32 v7, v10, s40, v189
	v_mov_b32_e32 v9, v163
	v_cvt_pk_fp8_f32 v8, v5, v7 op_sel:[0,0,1]
	v_med3_f32 v5, v11, s40, v189
	v_med3_f32 v7, v12, s40, v189
	v_cvt_pk_fp8_f32 v9, v5, v7
	v_mul_f32_e32 v6, v6, v53
	v_mul_f32_e32 v14, 0x3e000000, v6
	v_add_u32_e32 v6, 0xa0, v4
	v_med3_f32 v5, v13, s40, v189
	v_med3_f32 v7, v14, s40, v189
	v_cvt_pk_fp8_f32 v9, v5, v7 op_sel:[0,0,1]
	v_ashrrev_i32_e32 v7, 31, v6
	v_lshlrev_b64 v[6:7], 7, v[6:7]
	v_lshl_add_u64 v[6:7], s[10:11], 0, v[6:7]
	v_lshl_add_u64 v[6:7], v[6:7], 0, v[2:3]
	v_mul_f32_e32 v5, 0x3c800000, v46
	flat_store_dwordx2 v[6:7], v[8:9]
	v_mul_f32_e32 v6, 0xbfb8aa3b, v5
	v_exp_f32_e32 v6, v6
	v_add_u32_e32 v4, 0xb0, v4
	v_add_f32_e32 v6, 1.0, v6
	v_rcp_f32_e32 v6, v6
	s_nop 0
	v_mul_f32_e32 v5, v5, v6
	v_mul_f32_e32 v6, 0x3c800000, v47
	v_mul_f32_e32 v7, 0xbfb8aa3b, v6
	v_exp_f32_e32 v7, v7
	v_mul_f32_e32 v5, v5, v42
	v_mul_f32_e32 v5, 0x3e000000, v5
	v_med3_f32 v5, v5, s40, v189
	v_add_f32_e32 v7, 1.0, v7
	v_rcp_f32_e32 v7, v7
	s_nop 0
	v_mul_f32_e32 v6, v6, v7
	v_mul_f32_e32 v7, 0x3c800000, v48
	v_mul_f32_e32 v8, 0xbfb8aa3b, v7
	v_exp_f32_e32 v8, v8
	v_mul_f32_e32 v6, v6, v43
	v_mul_f32_e32 v6, 0x3e000000, v6
	v_add_f32_e32 v8, 1.0, v8
	v_rcp_f32_e32 v8, v8
	s_nop 0
	v_mul_f32_e32 v7, v7, v8
	v_mul_f32_e32 v8, 0x3c800000, v49
	v_mul_f32_e32 v9, 0xbfb8aa3b, v8
	v_exp_f32_e32 v9, v9
	v_mul_f32_e32 v7, v7, v44
	v_mul_f32_e32 v7, 0x3e000000, v7
	v_add_f32_e32 v9, 1.0, v9
	v_rcp_f32_e32 v9, v9
	s_nop 0
	v_mul_f32_e32 v8, v8, v9
	v_mul_f32_e32 v9, 0x3c800000, v38
	v_mul_f32_e32 v10, 0xbfb8aa3b, v9
	v_exp_f32_e32 v10, v10
	v_mul_f32_e32 v8, v8, v45
	v_mul_f32_e32 v8, 0x3e000000, v8
	v_add_f32_e32 v10, 1.0, v10
	v_rcp_f32_e32 v10, v10
	s_nop 0
	v_mul_f32_e32 v9, v9, v10
	v_mul_f32_e32 v10, 0x3c800000, v39
	v_mul_f32_e32 v11, 0xbfb8aa3b, v10
	v_exp_f32_e32 v11, v11
	v_mul_f32_e32 v9, v9, v34
	v_mul_f32_e32 v9, 0x3e000000, v9
	v_add_f32_e32 v11, 1.0, v11
	v_rcp_f32_e32 v11, v11
	s_nop 0
	v_mul_f32_e32 v10, v10, v11
	v_mul_f32_e32 v11, 0x3c800000, v40
	v_mul_f32_e32 v12, 0xbfb8aa3b, v11
	v_exp_f32_e32 v12, v12
	v_mul_f32_e32 v10, v10, v35
	v_mul_f32_e32 v10, 0x3e000000, v10
	v_add_f32_e32 v12, 1.0, v12
	v_rcp_f32_e32 v12, v12
	s_nop 0
	v_mul_f32_e32 v11, v11, v12
	v_mul_f32_e32 v12, 0x3c800000, v41
	v_mul_f32_e32 v13, 0xbfb8aa3b, v12
	v_exp_f32_e32 v13, v13
	v_mul_f32_e32 v11, v11, v36
	v_mul_f32_e32 v11, 0x3e000000, v11
	v_add_f32_e32 v13, 1.0, v13
	v_rcp_f32_e32 v13, v13
	s_nop 0
	v_mul_f32_e32 v12, v12, v13
	v_med3_f32 v13, v6, s40, v189
	v_mov_b32_e32 v6, v163
	v_cvt_pk_fp8_f32 v6, v5, v13
	v_med3_f32 v5, v7, s40, v189
	v_med3_f32 v7, v8, s40, v189
	v_med3_f32 v8, v10, s40, v189
	v_cvt_pk_fp8_f32 v6, v5, v7 op_sel:[0,0,1]
	v_med3_f32 v5, v9, s40, v189
	v_mov_b32_e32 v7, v163
	v_cvt_pk_fp8_f32 v7, v5, v8
	v_mul_f32_e32 v12, v12, v37
	v_mul_f32_e32 v12, 0x3e000000, v12
	v_med3_f32 v5, v11, s40, v189
	v_med3_f32 v8, v12, s40, v189
	v_cvt_pk_fp8_f32 v7, v5, v8 op_sel:[0,0,1]
	v_ashrrev_i32_e32 v5, 31, v4
	v_lshlrev_b64 v[4:5], 7, v[4:5]
	v_lshl_add_u64 v[4:5], s[10:11], 0, v[4:5]
	v_lshl_add_u64 v[2:3], v[4:5], 0, v[2:3]
	flat_store_dwordx2 v[2:3], v[6:7]
	s_cbranch_vccz .LBB0_2738
	s_waitcnt vmcnt(0)
	s_cmpk_gt_u32 s42, 0xff
	s_cbranch_scc1 .LBB0_2684
	s_barrier
	s_branch .LBB0_2684

.LBB0_2816:
	ds_read_b128 v[2:5], v168
	ds_read_b128 v[6:9], v168 offset:1024
	ds_read_b128 v[10:13], v168 offset:2048
	ds_read_b128 v[14:17], v168 offset:3072
	s_add_u32 s0, s26, 0x4000
	s_addc_u32 s1, s27, 0
	s_cmp_eq_u32 s53, 4
	s_cselect_b32 s34, s49, s0
	s_cselect_b32 s35, s19, s1
	s_cselect_b32 s28, s50, s51
	s_cselect_b32 s29, s17, s52
	s_add_u32 s30, s34, 0x8000
	s_addc_u32 s31, s35, 0
	v_lshl_add_u64 v[162:163], s[26:27], 0, v[156:157]
	s_add_i32 m0, s25, 0xc000
	ds_read_b128 v[174:177], v169
	ds_read_b128 v[178:181], v169 offset:1024
	ds_read_b128 v[182:185], v169 offset:2048
	ds_read_b128 v[186:189], v169 offset:3072
	ds_read_b128 v[190:193], v169 offset:4096
	ds_read_b128 v[194:197], v169 offset:5120
	ds_read_b128 v[198:201], v169 offset:6144
	ds_read_b128 v[202:205], v169 offset:7168
	global_load_lds_dwordx4 v[162:163], off
	v_lshl_add_u64 v[162:163], s[26:27], 0, v[154:155]
	s_add_i32 m0, s25, 0xe000
	s_nop 0
	global_load_lds_dwordx4 v[162:163], off
	s_waitcnt lgkmcnt(8)
	s_waitcnt vmcnt(10)
	s_barrier
	s_waitcnt lgkmcnt(0)
	s_waitcnt lgkmcnt(0)
	v_mfma_scale_f32_16x16x128_f8f6f4 v[142:145], v[2:9], v[174:181], v[142:145], v170, v170 op_sel_hi:[0,0,0]
	v_mfma_scale_f32_16x16x128_f8f6f4 v[138:141], v[10:17], v[174:181], v[138:141], v170, v170 op_sel_hi:[0,0,0]
	v_mfma_scale_f32_16x16x128_f8f6f4 v[126:129], v[2:9], v[182:189], v[126:129], v170, v170 op_sel_hi:[0,0,0]
	v_mfma_scale_f32_16x16x128_f8f6f4 v[122:125], v[10:17], v[182:189], v[122:125], v170, v170 op_sel_hi:[0,0,0]
	v_mfma_scale_f32_16x16x128_f8f6f4 v[110:113], v[2:9], v[190:197], v[110:113], v170, v170 op_sel_hi:[0,0,0]
	v_mfma_scale_f32_16x16x128_f8f6f4 v[106:109], v[10:17], v[190:197], v[106:109], v170, v170 op_sel_hi:[0,0,0]
	v_mfma_scale_f32_16x16x128_f8f6f4 v[94:97], v[2:9], v[198:205], v[94:97], v170, v170 op_sel_hi:[0,0,0]
	v_mfma_scale_f32_16x16x128_f8f6f4 v[90:93], v[10:17], v[198:205], v[90:93], v170, v170 op_sel_hi:[0,0,0]
	s_barrier
	s_add_i32 s0, s45, s37
	v_lshl_add_u64 v[162:163], s[28:29], 0, v[150:151]
	s_mov_b32 m0, s0
	ds_read_b128 v[206:209], v171
	ds_read_b128 v[210:213], v171 offset:1024
	ds_read_b128 v[214:217], v171 offset:2048
	ds_read_b128 v[218:221], v171 offset:3072
	global_load_lds_dwordx4 v[162:163], off
	v_lshl_add_u64 v[164:165], s[28:29], 0, v[146:147]
	s_add_i32 m0, s0, 0x2000
	s_nop 0
	global_load_lds_dwordx4 v[164:165], off
	s_waitcnt vmcnt(10)
	s_barrier
	s_waitcnt lgkmcnt(0)
	s_waitcnt lgkmcnt(0)
	v_mfma_scale_f32_16x16x128_f8f6f4 v[134:137], v[206:213], v[174:181], v[134:137], v170, v170 op_sel_hi:[0,0,0]
	v_mfma_scale_f32_16x16x128_f8f6f4 v[130:133], v[214:221], v[174:181], v[130:133], v170, v170 op_sel_hi:[0,0,0]
	v_mfma_scale_f32_16x16x128_f8f6f4 v[118:121], v[206:213], v[182:189], v[118:121], v170, v170 op_sel_hi:[0,0,0]
	v_mfma_scale_f32_16x16x128_f8f6f4 v[114:117], v[214:221], v[182:189], v[114:117], v170, v170 op_sel_hi:[0,0,0]
	v_mfma_scale_f32_16x16x128_f8f6f4 v[102:105], v[206:213], v[190:197], v[102:105], v170, v170 op_sel_hi:[0,0,0]
	v_mfma_scale_f32_16x16x128_f8f6f4 v[98:101], v[214:221], v[190:197], v[98:101], v170, v170 op_sel_hi:[0,0,0]
	v_mfma_scale_f32_16x16x128_f8f6f4 v[86:89], v[206:213], v[198:205], v[86:89], v170, v170 op_sel_hi:[0,0,0]
	v_mfma_scale_f32_16x16x128_f8f6f4 v[82:85], v[214:221], v[198:205], v[82:85], v170, v170 op_sel_hi:[0,0,0]
	s_mov_b32 m0, s25
	v_lshl_add_u64 v[222:223], s[34:35], 0, v[152:153]
	s_barrier
	ds_read_b128 v[174:177], v169 offset:16384
	ds_read_b128 v[178:181], v169 offset:17408
	ds_read_b128 v[182:185], v169 offset:18432
	ds_read_b128 v[186:189], v169 offset:19456
	ds_read_b128 v[190:193], v169 offset:20480
	ds_read_b128 v[194:197], v169 offset:21504
	ds_read_b128 v[198:201], v169 offset:22528
	ds_read_b128 v[202:205], v169 offset:23552
	global_load_lds_dwordx4 v[222:223], off
	v_lshl_add_u64 v[222:223], s[34:35], 0, v[148:149]
	s_mov_b32 m0, s38
	s_nop 0
	global_load_lds_dwordx4 v[222:223], off
	s_waitcnt vmcnt(10)
	s_barrier
	s_waitcnt lgkmcnt(0)
	s_waitcnt lgkmcnt(0)
	v_mfma_scale_f32_16x16x128_f8f6f4 v[78:81], v[2:9], v[174:181], v[78:81], v170, v170 op_sel_hi:[0,0,0]
	v_mfma_scale_f32_16x16x128_f8f6f4 v[74:77], v[10:17], v[174:181], v[74:77], v170, v170 op_sel_hi:[0,0,0]
	v_mfma_scale_f32_16x16x128_f8f6f4 v[62:65], v[2:9], v[182:189], v[62:65], v170, v170 op_sel_hi:[0,0,0]
	v_mfma_scale_f32_16x16x128_f8f6f4 v[58:61], v[10:17], v[182:189], v[58:61], v170, v170 op_sel_hi:[0,0,0]
	v_mfma_scale_f32_16x16x128_f8f6f4 v[46:49], v[2:9], v[190:197], v[46:49], v170, v170 op_sel_hi:[0,0,0]
	v_mfma_scale_f32_16x16x128_f8f6f4 v[42:45], v[10:17], v[190:197], v[42:45], v170, v170 op_sel_hi:[0,0,0]
	v_mfma_scale_f32_16x16x128_f8f6f4 v[30:33], v[2:9], v[198:205], v[30:33], v170, v170 op_sel_hi:[0,0,0]
	v_mfma_scale_f32_16x16x128_f8f6f4 v[26:29], v[10:17], v[198:205], v[26:29], v170, v170 op_sel_hi:[0,0,0]
	s_barrier
	s_add_u32 s0, s28, 0x20000
	s_addc_u32 s1, s29, 0
	s_add_i32 s54, s46, s37
	v_lshl_add_u64 v[2:3], s[0:1], 0, v[150:151]
	s_mov_b32 m0, s54
	s_nop 0
	global_load_lds_dwordx4 v[2:3], off
	v_lshl_add_u64 v[2:3], s[0:1], 0, v[146:147]
	s_add_i32 m0, s54, 0x2000
	s_nop 0
	global_load_lds_dwordx4 v[2:3], off
	s_waitcnt vmcnt(10)
	s_barrier
	v_mfma_scale_f32_16x16x128_f8f6f4 v[70:73], v[206:213], v[174:181], v[70:73], v170, v170 op_sel_hi:[0,0,0]
	v_mfma_scale_f32_16x16x128_f8f6f4 v[66:69], v[214:221], v[174:181], v[66:69], v170, v170 op_sel_hi:[0,0,0]
	v_mfma_scale_f32_16x16x128_f8f6f4 v[54:57], v[206:213], v[182:189], v[54:57], v170, v170 op_sel_hi:[0,0,0]
	v_mfma_scale_f32_16x16x128_f8f6f4 v[50:53], v[214:221], v[182:189], v[50:53], v170, v170 op_sel_hi:[0,0,0]
	v_mfma_scale_f32_16x16x128_f8f6f4 v[38:41], v[206:213], v[190:197], v[38:41], v170, v170 op_sel_hi:[0,0,0]
	v_mfma_scale_f32_16x16x128_f8f6f4 v[34:37], v[214:221], v[190:197], v[34:37], v170, v170 op_sel_hi:[0,0,0]
	v_mfma_scale_f32_16x16x128_f8f6f4 v[22:25], v[206:213], v[198:205], v[22:25], v170, v170 op_sel_hi:[0,0,0]
	v_mfma_scale_f32_16x16x128_f8f6f4 v[18:21], v[214:221], v[198:205], v[18:21], v170, v170 op_sel_hi:[0,0,0]
	s_add_i32 s54, 0, 0x18000
	v_add_u32_e32 v14, s54, v167
	s_barrier
	ds_read_b128 v[2:5], v14
	ds_read_b128 v[6:9], v14 offset:1024
	ds_read_b128 v[10:13], v14 offset:2048
	ds_read_b128 v[14:17], v14 offset:3072
	s_add_u32 s0, s34, 0x4000
	s_addc_u32 s1, s35, 0
	s_mov_b32 m0, s39
	v_lshl_add_u64 v[206:207], s[0:1], 0, v[152:153]
	ds_read_b128 v[174:177], v169 offset:32768
	ds_read_b128 v[178:181], v169 offset:33792
	ds_read_b128 v[182:185], v169 offset:34816
	ds_read_b128 v[186:189], v169 offset:35840
	ds_read_b128 v[190:193], v169 offset:36864
	ds_read_b128 v[194:197], v169 offset:37888
	ds_read_b128 v[198:201], v169 offset:38912
	ds_read_b128 v[202:205], v169 offset:39936
	global_load_lds_dwordx4 v[206:207], off
	v_lshl_add_u64 v[206:207], s[0:1], 0, v[148:149]
	s_mov_b32 m0, s40
	s_nop 0
	global_load_lds_dwordx4 v[206:207], off
	s_waitcnt lgkmcnt(8)
	s_waitcnt vmcnt(10)
	s_barrier
	s_waitcnt lgkmcnt(0)
	s_waitcnt lgkmcnt(0)
	v_mfma_scale_f32_16x16x128_f8f6f4 v[142:145], v[2:9], v[174:181], v[142:145], v170, v170 op_sel_hi:[0,0,0]
	v_mfma_scale_f32_16x16x128_f8f6f4 v[138:141], v[10:17], v[174:181], v[138:141], v170, v170 op_sel_hi:[0,0,0]
	v_mfma_scale_f32_16x16x128_f8f6f4 v[126:129], v[2:9], v[182:189], v[126:129], v170, v170 op_sel_hi:[0,0,0]
	v_mfma_scale_f32_16x16x128_f8f6f4 v[122:125], v[10:17], v[182:189], v[122:125], v170, v170 op_sel_hi:[0,0,0]
	v_mfma_scale_f32_16x16x128_f8f6f4 v[110:113], v[2:9], v[190:197], v[110:113], v170, v170 op_sel_hi:[0,0,0]
	v_mfma_scale_f32_16x16x128_f8f6f4 v[106:109], v[10:17], v[190:197], v[106:109], v170, v170 op_sel_hi:[0,0,0]
	v_mfma_scale_f32_16x16x128_f8f6f4 v[94:97], v[2:9], v[198:205], v[94:97], v170, v170 op_sel_hi:[0,0,0]
	v_mfma_scale_f32_16x16x128_f8f6f4 v[90:93], v[10:17], v[198:205], v[90:93], v170, v170 op_sel_hi:[0,0,0]
	s_barrier
	s_add_i32 s34, 0, 0x1c000
	s_add_i32 s0, s54, s37
	v_add_u32_e32 v173, s34, v167
	v_lshl_add_u64 v[162:163], v[162:163], 0, s[12:13]
	s_mov_b32 m0, s0
	ds_read_b128 v[206:209], v173
	ds_read_b128 v[210:213], v173 offset:1024
	ds_read_b128 v[214:217], v173 offset:2048
	ds_read_b128 v[218:221], v173 offset:3072
	global_load_lds_dwordx4 v[162:163], off
	v_lshl_add_u64 v[162:163], v[164:165], 0, s[12:13]
	s_add_i32 m0, s0, 0x2000
	s_nop 0
	global_load_lds_dwordx4 v[162:163], off
	s_waitcnt vmcnt(10)
	s_barrier
	s_waitcnt lgkmcnt(0)
	s_waitcnt lgkmcnt(0)
	v_mfma_scale_f32_16x16x128_f8f6f4 v[134:137], v[206:213], v[174:181], v[134:137], v170, v170 op_sel_hi:[0,0,0]
	v_mfma_scale_f32_16x16x128_f8f6f4 v[130:133], v[214:221], v[174:181], v[130:133], v170, v170 op_sel_hi:[0,0,0]
	v_mfma_scale_f32_16x16x128_f8f6f4 v[118:121], v[206:213], v[182:189], v[118:121], v170, v170 op_sel_hi:[0,0,0]
	v_mfma_scale_f32_16x16x128_f8f6f4 v[114:117], v[214:221], v[182:189], v[114:117], v170, v170 op_sel_hi:[0,0,0]
	v_mfma_scale_f32_16x16x128_f8f6f4 v[102:105], v[206:213], v[190:197], v[102:105], v170, v170 op_sel_hi:[0,0,0]
	v_mfma_scale_f32_16x16x128_f8f6f4 v[98:101], v[214:221], v[190:197], v[98:101], v170, v170 op_sel_hi:[0,0,0]
	v_mfma_scale_f32_16x16x128_f8f6f4 v[86:89], v[206:213], v[198:205], v[86:89], v170, v170 op_sel_hi:[0,0,0]
	v_mfma_scale_f32_16x16x128_f8f6f4 v[82:85], v[214:221], v[198:205], v[82:85], v170, v170 op_sel_hi:[0,0,0]
	s_mov_b32 m0, s43
	v_lshl_add_u64 v[162:163], s[30:31], 0, v[152:153]
	s_barrier
	ds_read_b128 v[174:177], v169 offset:49152
	ds_read_b128 v[178:181], v169 offset:50176
	ds_read_b128 v[182:185], v169 offset:51200
	ds_read_b128 v[186:189], v169 offset:52224
	ds_read_b128 v[190:193], v169 offset:53248
	ds_read_b128 v[194:197], v169 offset:54272
	ds_read_b128 v[198:201], v169 offset:55296
	ds_read_b128 v[202:205], v169 offset:56320
	global_load_lds_dwordx4 v[162:163], off
	v_lshl_add_u64 v[162:163], s[30:31], 0, v[148:149]
	s_mov_b32 m0, s44
	s_nop 0
	global_load_lds_dwordx4 v[162:163], off
	s_waitcnt vmcnt(10)
	s_barrier
	s_waitcnt lgkmcnt(0)
	s_waitcnt lgkmcnt(0)
	v_mfma_scale_f32_16x16x128_f8f6f4 v[78:81], v[2:9], v[174:181], v[78:81], v170, v170 op_sel_hi:[0,0,0]
	v_mfma_scale_f32_16x16x128_f8f6f4 v[74:77], v[10:17], v[174:181], v[74:77], v170, v170 op_sel_hi:[0,0,0]
	v_mfma_scale_f32_16x16x128_f8f6f4 v[62:65], v[2:9], v[182:189], v[62:65], v170, v170 op_sel_hi:[0,0,0]
	v_mfma_scale_f32_16x16x128_f8f6f4 v[58:61], v[10:17], v[182:189], v[58:61], v170, v170 op_sel_hi:[0,0,0]
	v_mfma_scale_f32_16x16x128_f8f6f4 v[46:49], v[2:9], v[190:197], v[46:49], v170, v170 op_sel_hi:[0,0,0]
	v_mfma_scale_f32_16x16x128_f8f6f4 v[42:45], v[10:17], v[190:197], v[42:45], v170, v170 op_sel_hi:[0,0,0]
	v_mfma_scale_f32_16x16x128_f8f6f4 v[30:33], v[2:9], v[198:205], v[30:33], v170, v170 op_sel_hi:[0,0,0]
	v_mfma_scale_f32_16x16x128_f8f6f4 v[26:29], v[10:17], v[198:205], v[26:29], v170, v170 op_sel_hi:[0,0,0]
	s_barrier
	s_add_u32 s0, s28, 0x20080
	s_addc_u32 s1, s29, 0
	s_add_i32 s28, s34, s37
	v_lshl_add_u64 v[2:3], s[0:1], 0, v[150:151]
	s_mov_b32 m0, s28
	s_nop 0
	global_load_lds_dwordx4 v[2:3], off
	v_lshl_add_u64 v[2:3], s[0:1], 0, v[146:147]
	s_add_i32 m0, s28, 0x2000
	s_nop 0
	global_load_lds_dwordx4 v[2:3], off
	s_waitcnt vmcnt(10)
	s_barrier
	v_mfma_scale_f32_16x16x128_f8f6f4 v[70:73], v[206:213], v[174:181], v[70:73], v170, v170 op_sel_hi:[0,0,0]
	v_mfma_scale_f32_16x16x128_f8f6f4 v[66:69], v[214:221], v[174:181], v[66:69], v170, v170 op_sel_hi:[0,0,0]
	v_mfma_scale_f32_16x16x128_f8f6f4 v[54:57], v[206:213], v[182:189], v[54:57], v170, v170 op_sel_hi:[0,0,0]
	v_mfma_scale_f32_16x16x128_f8f6f4 v[50:53], v[214:221], v[182:189], v[50:53], v170, v170 op_sel_hi:[0,0,0]
	v_mfma_scale_f32_16x16x128_f8f6f4 v[38:41], v[206:213], v[190:197], v[38:41], v170, v170 op_sel_hi:[0,0,0]
	v_mfma_scale_f32_16x16x128_f8f6f4 v[34:37], v[214:221], v[190:197], v[34:37], v170, v170 op_sel_hi:[0,0,0]
	v_mfma_scale_f32_16x16x128_f8f6f4 v[22:25], v[206:213], v[198:205], v[22:25], v170, v170 op_sel_hi:[0,0,0]
	v_mfma_scale_f32_16x16x128_f8f6f4 v[18:21], v[214:221], v[198:205], v[18:21], v170, v170 op_sel_hi:[0,0,0]
	s_add_i32 s53, s53, 2
	s_add_u32 s51, s51, 0x100
	s_addc_u32 s52, s52, 0
	s_add_u32 s26, s26, 0x10000
	s_addc_u32 s27, s27, 0
	s_cmp_gt_u32 s53, 5
	s_barrier
	s_cbranch_scc0 .LBB0_2816
	v_pk_mul_f32 v[8:9], v[142:143], s[14:15] op_sel_hi:[1,0]
	v_pk_mul_f32 v[6:7], v[144:145], s[14:15] op_sel_hi:[1,0]
	v_med3_f32 v14, v8, s47, v172
	v_med3_f32 v9, v9, s47, v172
	v_mov_b32_e32 v8, 0
	v_cvt_pk_fp8_f32 v8, v14, v9
	v_pk_mul_f32 v[12:13], v[138:139], s[14:15] op_sel_hi:[1,0]
	v_pk_mul_f32 v[10:11], v[140:141], s[14:15] op_sel_hi:[1,0]
	v_med3_f32 v6, v6, s47, v172
	v_med3_f32 v7, v7, s47, v172
	v_med3_f32 v12, v12, s47, v172
	v_med3_f32 v13, v13, s47, v172
	v_mov_b32_e32 v9, 0
	v_mov_b32_e32 v3, v1
	v_mov_b32_e32 v2, v166
	s_lshl_b32 s0, s48, 8
	v_cvt_pk_fp8_f32 v9, v12, v13
	v_cvt_pk_fp8_f32 v8, v6, v7 op_sel:[0,0,1]
	v_med3_f32 v6, v10, s47, v172
	v_med3_f32 v7, v11, s47, v172
	v_pk_mul_f32 v[10:11], v[134:135], s[14:15] op_sel_hi:[1,0]
	s_nop 15
	s_nop 15
	s_or_b32 s0, s0, s42
	v_pk_mul_f32 v[14:15], v[130:131], s[14:15] op_sel_hi:[1,0]
	v_med3_f32 v17, v10, s47, v172
	v_med3_f32 v11, v11, s47, v172
	v_mov_b32_e32 v10, 0
	v_lshl_add_u32 v2, v2, 3, s0
	s_lshl_b32 s0, s24, 8
	v_cvt_pk_fp8_f32 v10, v17, v11
	v_med3_f32 v14, v14, s47, v172
	v_med3_f32 v15, v15, s47, v172
	v_mov_b32_e32 v11, 0
	s_add_i32 s0, s0, s15
	v_cvt_pk_fp8_f32 v11, v14, v15
	v_add_u32_e32 v16, s0, v3
	v_cvt_pk_fp8_f32 v9, v6, v7 op_sel:[0,0,1]
	v_pk_mul_f32 v[6:7], v[136:137], s[14:15] op_sel_hi:[1,0]
	v_mov_b32_e32 v4, v16
	v_pk_mul_f32 v[12:13], v[132:133], s[14:15] op_sel_hi:[1,0]
	v_med3_f32 v6, v6, s47, v172
	v_med3_f32 v7, v7, s47, v172
	v_cvt_pk_fp8_f32 v10, v6, v7 op_sel:[0,0,1]
	v_ashrrev_i32_e32 v5, 31, v4
	v_med3_f32 v6, v12, s47, v172
	v_med3_f32 v7, v13, s47, v172
	v_lshlrev_b64 v[4:5], 10, v[4:5]
	v_cvt_pk_fp8_f32 v11, v6, v7 op_sel:[0,0,1]
	v_ashrrev_i32_e32 v3, 31, v2
	v_lshl_add_u64 v[4:5], s[10:11], 0, v[4:5]
	v_lshl_add_u64 v[4:5], v[4:5], 0, v[2:3]
	flat_store_dwordx2 v[4:5], v[8:9]
	flat_store_dwordx2 v[4:5], v[10:11] offset:128
	v_pk_mul_f32 v[8:9], v[126:127], s[14:15] op_sel_hi:[1,0]
	v_pk_mul_f32 v[6:7], v[128:129], s[14:15] op_sel_hi:[1,0]
	v_med3_f32 v14, v8, s47, v172
	v_med3_f32 v9, v9, s47, v172
	v_mov_b32_e32 v8, 0
	v_cvt_pk_fp8_f32 v8, v14, v9
	v_pk_mul_f32 v[12:13], v[122:123], s[14:15] op_sel_hi:[1,0]
	v_pk_mul_f32 v[10:11], v[124:125], s[14:15] op_sel_hi:[1,0]
	v_med3_f32 v6, v6, s47, v172
	v_med3_f32 v7, v7, s47, v172
	v_med3_f32 v12, v12, s47, v172
	v_med3_f32 v13, v13, s47, v172
	v_mov_b32_e32 v9, 0
	v_cvt_pk_fp8_f32 v9, v12, v13
	v_cvt_pk_fp8_f32 v8, v6, v7 op_sel:[0,0,1]
	v_med3_f32 v6, v10, s47, v172
	v_med3_f32 v7, v11, s47, v172
	v_pk_mul_f32 v[10:11], v[118:119], s[14:15] op_sel_hi:[1,0]
	v_pk_mul_f32 v[14:15], v[114:115], s[14:15] op_sel_hi:[1,0]
	v_med3_f32 v17, v10, s47, v172
	v_med3_f32 v11, v11, s47, v172
	v_mov_b32_e32 v10, 0
	v_cvt_pk_fp8_f32 v10, v17, v11
	v_med3_f32 v14, v14, s47, v172
	v_med3_f32 v15, v15, s47, v172
	v_mov_b32_e32 v11, 0
	v_cvt_pk_fp8_f32 v11, v14, v15
	v_cvt_pk_fp8_f32 v9, v6, v7 op_sel:[0,0,1]
	v_pk_mul_f32 v[6:7], v[120:121], s[14:15] op_sel_hi:[1,0]
	v_add_u32_e32 v4, 16, v16
	v_pk_mul_f32 v[12:13], v[116:117], s[14:15] op_sel_hi:[1,0]
	v_med3_f32 v6, v6, s47, v172
	v_med3_f32 v7, v7, s47, v172
	v_cvt_pk_fp8_f32 v10, v6, v7 op_sel:[0,0,1]
	v_ashrrev_i32_e32 v5, 31, v4
	v_med3_f32 v6, v12, s47, v172
	v_med3_f32 v7, v13, s47, v172
	v_lshlrev_b64 v[4:5], 10, v[4:5]
	v_cvt_pk_fp8_f32 v11, v6, v7 op_sel:[0,0,1]
	v_lshl_add_u64 v[4:5], s[10:11], 0, v[4:5]
	v_lshl_add_u64 v[4:5], v[4:5], 0, v[2:3]
	flat_store_dwordx2 v[4:5], v[8:9]
	flat_store_dwordx2 v[4:5], v[10:11] offset:128
	v_pk_mul_f32 v[8:9], v[110:111], s[14:15] op_sel_hi:[1,0]
	v_pk_mul_f32 v[6:7], v[112:113], s[14:15] op_sel_hi:[1,0]
	v_med3_f32 v14, v8, s47, v172
	v_med3_f32 v9, v9, s47, v172
	v_mov_b32_e32 v8, 0
	v_cvt_pk_fp8_f32 v8, v14, v9
	v_pk_mul_f32 v[12:13], v[106:107], s[14:15] op_sel_hi:[1,0]
	v_pk_mul_f32 v[10:11], v[108:109], s[14:15] op_sel_hi:[1,0]
	v_med3_f32 v6, v6, s47, v172
	v_med3_f32 v7, v7, s47, v172
	v_med3_f32 v12, v12, s47, v172
	v_med3_f32 v13, v13, s47, v172
	v_mov_b32_e32 v9, 0
	v_cvt_pk_fp8_f32 v9, v12, v13
	v_cvt_pk_fp8_f32 v8, v6, v7 op_sel:[0,0,1]
	v_med3_f32 v6, v10, s47, v172
	v_med3_f32 v7, v11, s47, v172
	v_pk_mul_f32 v[10:11], v[102:103], s[14:15] op_sel_hi:[1,0]
	v_pk_mul_f32 v[14:15], v[98:99], s[14:15] op_sel_hi:[1,0]
	v_med3_f32 v17, v10, s47, v172
	v_med3_f32 v11, v11, s47, v172
	v_mov_b32_e32 v10, 0
	v_cvt_pk_fp8_f32 v10, v17, v11
	v_med3_f32 v14, v14, s47, v172
	v_med3_f32 v15, v15, s47, v172
	v_mov_b32_e32 v11, 0
	v_cvt_pk_fp8_f32 v11, v14, v15
	v_cvt_pk_fp8_f32 v9, v6, v7 op_sel:[0,0,1]
	v_pk_mul_f32 v[6:7], v[104:105], s[14:15] op_sel_hi:[1,0]
	v_add_u32_e32 v4, 32, v16
	v_pk_mul_f32 v[12:13], v[100:101], s[14:15] op_sel_hi:[1,0]
	v_med3_f32 v6, v6, s47, v172
	v_med3_f32 v7, v7, s47, v172
	v_cvt_pk_fp8_f32 v10, v6, v7 op_sel:[0,0,1]
	v_ashrrev_i32_e32 v5, 31, v4
	v_med3_f32 v6, v12, s47, v172
	v_med3_f32 v7, v13, s47, v172
	v_lshlrev_b64 v[4:5], 10, v[4:5]
	v_cvt_pk_fp8_f32 v11, v6, v7 op_sel:[0,0,1]
	v_lshl_add_u64 v[4:5], s[10:11], 0, v[4:5]
	v_lshl_add_u64 v[4:5], v[4:5], 0, v[2:3]
	flat_store_dwordx2 v[4:5], v[8:9]
	flat_store_dwordx2 v[4:5], v[10:11] offset:128
	v_pk_mul_f32 v[8:9], v[94:95], s[14:15] op_sel_hi:[1,0]
	v_pk_mul_f32 v[6:7], v[96:97], s[14:15] op_sel_hi:[1,0]
	v_med3_f32 v14, v8, s47, v172
	v_med3_f32 v9, v9, s47, v172
	v_mov_b32_e32 v8, 0
	v_cvt_pk_fp8_f32 v8, v14, v9
	v_pk_mul_f32 v[12:13], v[90:91], s[14:15] op_sel_hi:[1,0]
	v_pk_mul_f32 v[10:11], v[92:93], s[14:15] op_sel_hi:[1,0]
	v_med3_f32 v6, v6, s47, v172
	v_med3_f32 v7, v7, s47, v172
	v_med3_f32 v12, v12, s47, v172
	v_med3_f32 v13, v13, s47, v172
	v_mov_b32_e32 v9, 0
	v_cvt_pk_fp8_f32 v9, v12, v13
	v_cvt_pk_fp8_f32 v8, v6, v7 op_sel:[0,0,1]
	v_med3_f32 v6, v10, s47, v172
	v_med3_f32 v7, v11, s47, v172
	v_pk_mul_f32 v[10:11], v[86:87], s[14:15] op_sel_hi:[1,0]
	v_pk_mul_f32 v[14:15], v[82:83], s[14:15] op_sel_hi:[1,0]
	v_med3_f32 v17, v10, s47, v172
	v_med3_f32 v11, v11, s47, v172
	v_mov_b32_e32 v10, 0
	v_cvt_pk_fp8_f32 v10, v17, v11
	v_med3_f32 v14, v14, s47, v172
	v_med3_f32 v15, v15, s47, v172
	v_mov_b32_e32 v11, 0
	v_cvt_pk_fp8_f32 v11, v14, v15
	v_cvt_pk_fp8_f32 v9, v6, v7 op_sel:[0,0,1]
	v_pk_mul_f32 v[6:7], v[88:89], s[14:15] op_sel_hi:[1,0]
	v_add_u32_e32 v4, 48, v16
	v_pk_mul_f32 v[12:13], v[84:85], s[14:15] op_sel_hi:[1,0]
	v_med3_f32 v6, v6, s47, v172
	v_med3_f32 v7, v7, s47, v172
	v_cvt_pk_fp8_f32 v10, v6, v7 op_sel:[0,0,1]
	v_ashrrev_i32_e32 v5, 31, v4
	v_med3_f32 v6, v12, s47, v172
	v_med3_f32 v7, v13, s47, v172
	v_lshlrev_b64 v[4:5], 10, v[4:5]
	v_cvt_pk_fp8_f32 v11, v6, v7 op_sel:[0,0,1]
	v_lshl_add_u64 v[4:5], s[10:11], 0, v[4:5]
	v_lshl_add_u64 v[4:5], v[4:5], 0, v[2:3]
	flat_store_dwordx2 v[4:5], v[8:9]
	flat_store_dwordx2 v[4:5], v[10:11] offset:128
	v_pk_mul_f32 v[8:9], v[78:79], s[14:15] op_sel_hi:[1,0]
	v_pk_mul_f32 v[6:7], v[80:81], s[14:15] op_sel_hi:[1,0]
	v_med3_f32 v14, v8, s47, v172
	v_med3_f32 v9, v9, s47, v172
	v_mov_b32_e32 v8, 0
	v_cvt_pk_fp8_f32 v8, v14, v9
	v_pk_mul_f32 v[12:13], v[74:75], s[14:15] op_sel_hi:[1,0]
	v_pk_mul_f32 v[10:11], v[76:77], s[14:15] op_sel_hi:[1,0]
	v_med3_f32 v6, v6, s47, v172
	v_med3_f32 v7, v7, s47, v172
	v_med3_f32 v12, v12, s47, v172
	v_med3_f32 v13, v13, s47, v172
	v_mov_b32_e32 v9, 0
	v_cvt_pk_fp8_f32 v9, v12, v13
	v_cvt_pk_fp8_f32 v8, v6, v7 op_sel:[0,0,1]
	v_med3_f32 v6, v10, s47, v172
	v_med3_f32 v7, v11, s47, v172
	v_pk_mul_f32 v[10:11], v[70:71], s[14:15] op_sel_hi:[1,0]
	v_pk_mul_f32 v[14:15], v[66:67], s[14:15] op_sel_hi:[1,0]
	v_med3_f32 v17, v10, s47, v172
	v_med3_f32 v11, v11, s47, v172
	v_mov_b32_e32 v10, 0
	v_cvt_pk_fp8_f32 v10, v17, v11
	v_med3_f32 v14, v14, s47, v172
	v_med3_f32 v15, v15, s47, v172
	v_mov_b32_e32 v11, 0
	v_cvt_pk_fp8_f32 v11, v14, v15
	v_cvt_pk_fp8_f32 v9, v6, v7 op_sel:[0,0,1]
	v_pk_mul_f32 v[6:7], v[72:73], s[14:15] op_sel_hi:[1,0]
	v_add_u32_e32 v4, 0x80, v16
	v_pk_mul_f32 v[12:13], v[68:69], s[14:15] op_sel_hi:[1,0]
	v_med3_f32 v6, v6, s47, v172
	v_med3_f32 v7, v7, s47, v172
	v_cvt_pk_fp8_f32 v10, v6, v7 op_sel:[0,0,1]
	v_ashrrev_i32_e32 v5, 31, v4
	v_med3_f32 v6, v12, s47, v172
	v_med3_f32 v7, v13, s47, v172
	v_lshlrev_b64 v[4:5], 10, v[4:5]
	v_cvt_pk_fp8_f32 v11, v6, v7 op_sel:[0,0,1]
	v_lshl_add_u64 v[4:5], s[10:11], 0, v[4:5]
	v_lshl_add_u64 v[4:5], v[4:5], 0, v[2:3]
	flat_store_dwordx2 v[4:5], v[8:9]
	flat_store_dwordx2 v[4:5], v[10:11] offset:128
	v_pk_mul_f32 v[8:9], v[62:63], s[14:15] op_sel_hi:[1,0]
	v_pk_mul_f32 v[6:7], v[64:65], s[14:15] op_sel_hi:[1,0]
	v_med3_f32 v14, v8, s47, v172
	v_med3_f32 v9, v9, s47, v172
	v_mov_b32_e32 v8, 0
	v_cvt_pk_fp8_f32 v8, v14, v9
	v_pk_mul_f32 v[12:13], v[58:59], s[14:15] op_sel_hi:[1,0]
	v_pk_mul_f32 v[10:11], v[60:61], s[14:15] op_sel_hi:[1,0]
	v_med3_f32 v6, v6, s47, v172
	v_med3_f32 v7, v7, s47, v172
	v_med3_f32 v12, v12, s47, v172
	v_med3_f32 v13, v13, s47, v172
	v_mov_b32_e32 v9, 0
	v_cvt_pk_fp8_f32 v9, v12, v13
	v_cvt_pk_fp8_f32 v8, v6, v7 op_sel:[0,0,1]
	v_med3_f32 v6, v10, s47, v172
	v_med3_f32 v7, v11, s47, v172
	v_pk_mul_f32 v[10:11], v[54:55], s[14:15] op_sel_hi:[1,0]
	v_pk_mul_f32 v[14:15], v[50:51], s[14:15] op_sel_hi:[1,0]
	v_med3_f32 v17, v10, s47, v172
	v_med3_f32 v11, v11, s47, v172
	v_mov_b32_e32 v10, 0
	v_cvt_pk_fp8_f32 v10, v17, v11
	v_med3_f32 v14, v14, s47, v172
	v_med3_f32 v15, v15, s47, v172
	v_mov_b32_e32 v11, 0
	v_cvt_pk_fp8_f32 v11, v14, v15
	v_cvt_pk_fp8_f32 v9, v6, v7 op_sel:[0,0,1]
	v_pk_mul_f32 v[6:7], v[56:57], s[14:15] op_sel_hi:[1,0]
	v_add_u32_e32 v4, 0x90, v16
	v_pk_mul_f32 v[12:13], v[52:53], s[14:15] op_sel_hi:[1,0]
	v_med3_f32 v6, v6, s47, v172
	v_med3_f32 v7, v7, s47, v172
	v_cvt_pk_fp8_f32 v10, v6, v7 op_sel:[0,0,1]
	v_ashrrev_i32_e32 v5, 31, v4
	v_med3_f32 v6, v12, s47, v172
	v_med3_f32 v7, v13, s47, v172
	v_lshlrev_b64 v[4:5], 10, v[4:5]
	v_cvt_pk_fp8_f32 v11, v6, v7 op_sel:[0,0,1]
	v_lshl_add_u64 v[4:5], s[10:11], 0, v[4:5]
	v_lshl_add_u64 v[4:5], v[4:5], 0, v[2:3]
	flat_store_dwordx2 v[4:5], v[8:9]
	flat_store_dwordx2 v[4:5], v[10:11] offset:128
	v_pk_mul_f32 v[8:9], v[46:47], s[14:15] op_sel_hi:[1,0]
	v_pk_mul_f32 v[6:7], v[48:49], s[14:15] op_sel_hi:[1,0]
	v_med3_f32 v14, v8, s47, v172
	v_med3_f32 v9, v9, s47, v172
	v_mov_b32_e32 v8, 0
	v_cvt_pk_fp8_f32 v8, v14, v9
	v_pk_mul_f32 v[12:13], v[42:43], s[14:15] op_sel_hi:[1,0]
	v_pk_mul_f32 v[10:11], v[44:45], s[14:15] op_sel_hi:[1,0]
	v_med3_f32 v6, v6, s47, v172
	v_med3_f32 v7, v7, s47, v172
	v_med3_f32 v12, v12, s47, v172
	v_med3_f32 v13, v13, s47, v172
	v_mov_b32_e32 v9, 0
	v_cvt_pk_fp8_f32 v9, v12, v13
	v_cvt_pk_fp8_f32 v8, v6, v7 op_sel:[0,0,1]
	v_med3_f32 v6, v10, s47, v172
	v_med3_f32 v7, v11, s47, v172
	v_pk_mul_f32 v[10:11], v[38:39], s[14:15] op_sel_hi:[1,0]
	v_pk_mul_f32 v[14:15], v[34:35], s[14:15] op_sel_hi:[1,0]
	v_med3_f32 v17, v10, s47, v172
	v_med3_f32 v11, v11, s47, v172
	v_mov_b32_e32 v10, 0
	v_cvt_pk_fp8_f32 v10, v17, v11
	v_med3_f32 v14, v14, s47, v172
	v_med3_f32 v15, v15, s47, v172
	v_mov_b32_e32 v11, 0
	v_cvt_pk_fp8_f32 v11, v14, v15
	v_cvt_pk_fp8_f32 v9, v6, v7 op_sel:[0,0,1]
	v_pk_mul_f32 v[6:7], v[40:41], s[14:15] op_sel_hi:[1,0]
	v_add_u32_e32 v4, 0xa0, v16
	v_pk_mul_f32 v[12:13], v[36:37], s[14:15] op_sel_hi:[1,0]
	v_med3_f32 v6, v6, s47, v172
	v_med3_f32 v7, v7, s47, v172
	v_cvt_pk_fp8_f32 v10, v6, v7 op_sel:[0,0,1]
	v_ashrrev_i32_e32 v5, 31, v4
	v_med3_f32 v6, v12, s47, v172
	v_med3_f32 v7, v13, s47, v172
	v_lshlrev_b64 v[4:5], 10, v[4:5]
	v_cvt_pk_fp8_f32 v11, v6, v7 op_sel:[0,0,1]
	v_lshl_add_u64 v[4:5], s[10:11], 0, v[4:5]
	v_lshl_add_u64 v[4:5], v[4:5], 0, v[2:3]
	flat_store_dwordx2 v[4:5], v[8:9]
	flat_store_dwordx2 v[4:5], v[10:11] offset:128
	v_pk_mul_f32 v[8:9], v[30:31], s[14:15] op_sel_hi:[1,0]
	v_pk_mul_f32 v[6:7], v[32:33], s[14:15] op_sel_hi:[1,0]
	v_med3_f32 v14, v8, s47, v172
	v_med3_f32 v9, v9, s47, v172
	v_mov_b32_e32 v8, 0
	v_cvt_pk_fp8_f32 v8, v14, v9
	v_pk_mul_f32 v[12:13], v[26:27], s[14:15] op_sel_hi:[1,0]
	v_pk_mul_f32 v[10:11], v[28:29], s[14:15] op_sel_hi:[1,0]
	v_med3_f32 v6, v6, s47, v172
	v_med3_f32 v7, v7, s47, v172
	v_med3_f32 v12, v12, s47, v172
	v_med3_f32 v13, v13, s47, v172
	v_mov_b32_e32 v9, 0
	v_cvt_pk_fp8_f32 v9, v12, v13
	v_cvt_pk_fp8_f32 v8, v6, v7 op_sel:[0,0,1]
	v_med3_f32 v6, v10, s47, v172
	v_med3_f32 v7, v11, s47, v172
	v_pk_mul_f32 v[10:11], v[22:23], s[14:15] op_sel_hi:[1,0]
	v_add_u32_e32 v4, 0xb0, v16
	v_pk_mul_f32 v[14:15], v[18:19], s[14:15] op_sel_hi:[1,0]
	v_med3_f32 v16, v10, s47, v172
	v_med3_f32 v11, v11, s47, v172
	v_mov_b32_e32 v10, 0
	v_cvt_pk_fp8_f32 v10, v16, v11
	v_med3_f32 v14, v14, s47, v172
	v_med3_f32 v15, v15, s47, v172
	v_mov_b32_e32 v11, 0
	v_cvt_pk_fp8_f32 v11, v14, v15
	v_cvt_pk_fp8_f32 v9, v6, v7 op_sel:[0,0,1]
	v_pk_mul_f32 v[6:7], v[24:25], s[14:15] op_sel_hi:[1,0]
	v_pk_mul_f32 v[12:13], v[20:21], s[14:15] op_sel_hi:[1,0]
	v_med3_f32 v6, v6, s47, v172
	v_med3_f32 v7, v7, s47, v172
	v_cvt_pk_fp8_f32 v10, v6, v7 op_sel:[0,0,1]
	v_ashrrev_i32_e32 v5, 31, v4
	v_med3_f32 v6, v12, s47, v172
	v_med3_f32 v7, v13, s47, v172
	v_lshlrev_b64 v[4:5], 10, v[4:5]
	v_cvt_pk_fp8_f32 v11, v6, v7 op_sel:[0,0,1]
	v_lshl_add_u64 v[4:5], s[10:11], 0, v[4:5]
	v_lshl_add_u64 v[2:3], v[4:5], 0, v[2:3]
	s_and_b64 vcc, exec, s[6:7]
	s_mov_b32 s48, s16
	s_mov_b32 s24, s18
	s_mov_b64 s[26:27], s[22:23]
	s_mov_b64 s[28:29], s[20:21]
	flat_store_dwordx2 v[2:3], v[8:9]
	flat_store_dwordx2 v[2:3], v[10:11] offset:128
	s_cbranch_vccz .LBB0_2809
	s_waitcnt vmcnt(0)
	s_cmpk_gt_u32 s4, 0xff
	s_cbranch_scc1 .LBB0_2820
	s_barrier
